# flat_load/flat_store replaced by global_load/global_store everywhere (addresses are global; stops flat ops counting on lgkmcnt so LDS waits no longer stall on memory)
# baseline (speedup 1.0000x reference)
; __device__ __forceinline__ void zero_lora_pool(bf16* lora_t, bf16* pool_t, int gtid, int gthreads) {
;     for (int e = gtid; e < 3072 * 48; e += gthreads) { const int n = e / 48, c = e - n * 48, seg = n >> 10; const int lo = seg == 0 ? 0 : (seg == 1 ? 8 : 16), hi = seg == 0 ? 8 : (seg == 1 ? 16 : 40);
;         if (c < lo || c >= hi) *(u32x4*)(lora_t + (size_t)n * 384 + c * 8) = (u32x4){0u, 0u, 0u, 0u}; }
.LBB0_94:
	s_waitcnt lgkmcnt(0)
	v_mul_hi_i32 v1, v6, s19
	v_lshrrev_b32_e32 v3, 31, v1
	v_ashrrev_i32_e32 v1, 3, v1
	v_add_u32_e32 v1, v1, v3
	v_and_b32_e32 v3, 0xfffffc00, v1
	v_cmp_eq_u32_e64 s[38:39], s30, v3
	v_cmp_gt_u32_e64 s[40:41], s30, v1
	v_mad_u64_u32 v[8:9], s[6:7], v1, s28, v[6:7]
	v_cndmask_b32_e64 v3, 16, 8, s[38:39]
	v_cndmask_b32_e64 v5, 40, 16, s[38:39]
	v_cndmask_b32_e64 v3, v3, 0, s[40:41]
	v_cndmask_b32_e64 v5, v5, 8, s[40:41]
	v_cmp_lt_i32_e64 s[38:39], v8, v3
	v_cmp_ge_i32_e64 s[40:41], v8, v5
	s_or_b64 s[6:7], s[38:39], s[40:41]
	s_and_saveexec_b64 s[36:37], s[6:7]
	s_cbranch_execz .LBB0_93
	v_mov_b64_e32 v[8:9], s[34:35]
	v_mad_u64_u32 v[10:11], s[6:7], v1, s31, v[4:5]
	v_mad_i64_i32 v[8:9], s[6:7], v1, s60, v[8:9]
	v_ashrrev_i32_e32 v11, 31, v10
	v_lshl_add_u64 v[8:9], v[10:11], 1, v[8:9]
	global_store_dwordx4 v[8:9], v[238:241], off
	s_branch .LBB0_93

; __device__ __forceinline__ void zero_lora_pool(bf16* lora_t, bf16* pool_t, int gtid, int gthreads) {
;     ...
;     for (int e = gtid; e < 512 * 64; e += gthreads) { const int r = e >> 6, c = e & 63;
;         if ((c >> 4) != (r >> 7)) *(u32x4*)(pool_t + (size_t)r * 512 + c * 8) = (u32x4){0u, 0u, 0u, 0u}; }
.LBB0_100:
	v_ashrrev_i32_e32 v6, 13, v3
	v_cmp_ne_u32_e64 s[40:41], v1, v6
	s_and_saveexec_b64 s[36:37], s[40:41]
	s_cbranch_execz .LBB0_99
	v_ashrrev_i32_e32 v6, 6, v3
	v_ashrrev_i32_e32 v7, 31, v6
	v_lshlrev_b64 v[6:7], 10, v[6:7]
	v_lshl_add_u64 v[6:7], v[4:5], 0, v[6:7]
	global_store_dwordx4 v[6:7], v[238:241], off
	s_branch .LBB0_99

; __device__ __forceinline__ void zero_fill(void* p, size_t bytes, int gtid, int gthreads) {
;     u32x4* q = (u32x4*)p; const size_t n = bytes / 16;
;     for (size_t i = gtid; i < n; i += gthreads) q[i] = (u32x4){0u, 0u, 0u, 0u};
.LBB0_104:
	v_lshl_add_u64 v[10:11], v[10:11], 0, s[8:9]
	v_cmp_lt_u64_e64 s[42:43], s[44:45], v[10:11]
	global_store_dwordx4 v[8:9], v[238:241], off
	s_or_b64 s[4:5], s[42:43], s[4:5]
	v_lshl_add_u64 v[8:9], v[8:9], 0, s[6:7]
	s_andn2_b64 exec, exec, s[4:5]
	s_cbranch_execnz .LBB0_104

; __device__ __forceinline__ void zero_fill(void* p, size_t bytes, int gtid, int gthreads) {
;     u32x4* q = (u32x4*)p; const size_t n = bytes / 16;
;     for (size_t i = gtid; i < n; i += gthreads) q[i] = (u32x4){0u, 0u, 0u, 0u};
.LBB0_107:
	v_lshl_add_u64 v[10:11], v[10:11], 0, s[8:9]
	v_cmp_lt_u64_e64 s[44:45], s[36:37], v[10:11]
	v_readlane_b32 s8, v253, 35
	global_store_dwordx4 v[8:9], v[238:241], off
	s_or_b64 s[4:5], s[44:45], s[4:5]
	v_readlane_b32 s9, v253, 36
	v_lshl_add_u64 v[8:9], v[8:9], 0, s[6:7]
	s_andn2_b64 exec, exec, s[4:5]
	s_cbranch_execnz .LBB0_107

; __device__ __forceinline__ void zero_lora_pool(bf16* lora_t, bf16* pool_t, int gtid, int gthreads) {
;     for (int e = gtid; e < 3072 * 48; e += gthreads) { const int n = e / 48, c = e - n * 48, seg = n >> 10; const int lo = seg == 0 ? 0 : (seg == 1 ? 8 : 16), hi = seg == 0 ? 8 : (seg == 1 ? 16 : 40);
;         if (c < lo || c >= hi) *(u32x4*)(lora_t + (size_t)n * 384 + c * 8) = (u32x4){0u, 0u, 0u, 0u}; }
.LBB0_111:
	v_mul_hi_i32 v1, v8, s19
	v_lshrrev_b32_e32 v3, 31, v1
	v_ashrrev_i32_e32 v1, 3, v1
	v_add_u32_e32 v1, v1, v3
	v_and_b32_e32 v3, 0xfffffc00, v1
	v_cmp_eq_u32_e32 vcc, s30, v3
	v_mad_u64_u32 v[10:11], s[6:7], v1, s28, v[8:9]
	s_nop 0
	v_cndmask_b32_e64 v3, 16, 8, vcc
	v_cmp_gt_u32_e64 s[44:45], s30, v1
	v_cndmask_b32_e64 v9, 40, 16, vcc
	s_nop 0
	v_cndmask_b32_e64 v3, v3, 0, s[44:45]
	v_cndmask_b32_e64 v9, v9, 8, s[44:45]
	v_cmp_lt_i32_e32 vcc, v10, v3
	v_cmp_ge_i32_e64 s[44:45], v10, v9
	s_or_b64 s[6:7], vcc, s[44:45]
	s_and_saveexec_b64 s[44:45], s[6:7]
	s_cbranch_execz .LBB0_110
	v_mov_b64_e32 v[10:11], s[4:5]
	v_mad_u64_u32 v[12:13], s[6:7], v1, s31, v[2:3]
	v_mad_i64_i32 v[10:11], s[6:7], v1, s60, v[10:11]
	v_ashrrev_i32_e32 v13, 31, v12
	v_lshl_add_u64 v[10:11], v[12:13], 1, v[10:11]
	global_store_dwordx4 v[10:11], v[238:241], off
	s_branch .LBB0_110

; __device__ __forceinline__ void zero_lora_pool(bf16* lora_t, bf16* pool_t, int gtid, int gthreads) {
;     ...
;     for (int e = gtid; e < 512 * 64; e += gthreads) { const int r = e >> 6, c = e & 63;
;         if ((c >> 4) != (r >> 7)) *(u32x4*)(pool_t + (size_t)r * 512 + c * 8) = (u32x4){0u, 0u, 0u, 0u}; }
.LBB0_116:
	v_ashrrev_i32_e32 v9, 13, v8
	v_cmp_ne_u32_e32 vcc, v1, v9
	s_and_saveexec_b64 s[36:37], vcc
	s_cbranch_execz .LBB0_115
	v_ashrrev_i32_e32 v10, 6, v8
	v_ashrrev_i32_e32 v11, 31, v10
	v_lshlrev_b64 v[10:11], 10, v[10:11]
	v_lshl_add_u64 v[10:11], v[2:3], 0, v[10:11]
	global_store_dwordx4 v[10:11], v[238:241], off
	s_branch .LBB0_115

; __device__ __forceinline__ void zero_fill(void* p, size_t bytes, int gtid, int gthreads) {
;     u32x4* q = (u32x4*)p; const size_t n = bytes / 16;
;     for (size_t i = gtid; i < n; i += gthreads) q[i] = (u32x4){0u, 0u, 0u, 0u};
.LBB0_120:
	v_lshl_add_u64 v[8:9], v[8:9], 0, s[8:9]
	v_cmp_lt_u64_e32 vcc, s[44:45], v[8:9]
	global_store_dwordx4 v[2:3], v[238:241], off
	s_or_b64 s[4:5], vcc, s[4:5]
	v_lshl_add_u64 v[2:3], v[2:3], 0, s[30:31]
	s_andn2_b64 exec, exec, s[4:5]
	s_cbranch_execnz .LBB0_120

; __device__ __forceinline__ void zero_fill(void* p, size_t bytes, int gtid, int gthreads) {
;     u32x4* q = (u32x4*)p; const size_t n = bytes / 16;
;     for (size_t i = gtid; i < n; i += gthreads) q[i] = (u32x4){0u, 0u, 0u, 0u};
.LBB0_123:
	v_lshl_add_u64 v[4:5], v[4:5], 0, s[8:9]
	v_cmp_lt_u64_e32 vcc, s[6:7], v[4:5]
	global_store_dwordx4 v[2:3], v[238:241], off
	s_or_b64 s[4:5], vcc, s[4:5]
	v_lshl_add_u64 v[2:3], v[2:3], 0, s[30:31]
	s_andn2_b64 exec, exec, s[4:5]
	s_cbranch_execnz .LBB0_123

; __device__ __forceinline__ void rope_table(const int* pos, float* rope, int gtid, int gthreads) {
;     for (int e = gtid; e < T * 32; e += gthreads) { const int m = e >> 5, i = e & 31;
;         const float inv = exp2f(-(float)i * (13.287712379549449f / 32.0f));
;         const float ang = (float)pos[m] * inv;
;         const double rev = (double)ang * 0.15915494309189535; const double fr = rev - rint(rev);
;         const float a = (float)(fr * 6.283185307179586);
;         rope[2 * e] = __cosf(a); rope[2 * e + 1] = __sinf(a); }
; }
.LBB0_126:
	v_ashrrev_i32_e32 v4, 5, v0
	v_ashrrev_i32_e32 v5, 31, v4
	v_lshl_add_u64 v[4:5], v[4:5], 2, s[0:1]
	global_load_dword v4, v[4:5], off
	v_ashrrev_i32_e32 v3, 31, v2
	v_add_u32_e32 v0, s8, v0
	s_mov_b32 s2, 0x7ffff
	v_cmp_lt_i32_e32 vcc, s2, v0
	s_or_b64 s[36:37], vcc, s[36:37]
	s_waitcnt vmcnt(0) lgkmcnt(0)
	v_cvt_f32_i32_e32 v6, v4
	v_lshl_add_u64 v[4:5], v[2:3], 2, s[56:57]
	v_add_u32_e32 v2, s17, v2
	v_mul_f32_e32 v3, v1, v6
	v_cvt_f64_f32_e32 v[6:7], v3
	v_mul_f64 v[8:9], v[6:7], s[6:7]
	v_rndne_f64_e32 v[8:9], v[8:9]
	v_fma_f64 v[6:7], v[6:7], s[6:7], -v[8:9]
	v_mul_f64 v[6:7], v[6:7], s[14:15]
	v_cvt_f32_f64_e32 v3, v[6:7]
	v_mul_f32_e32 v3, 0.15915494, v3
	v_cos_f32_e32 v6, v3
	v_sin_f32_e32 v7, v3
	global_store_dwordx2 v[4:5], v[6:7], off
	s_andn2_b64 exec, exec, s[36:37]
	s_cbranch_execnz .LBB0_126
	s_or_b64 exec, exec, s[36:37]

; __device__ __forceinline__ void unpack8(const u32x4 w, float (&f)[8]) { f[0] = bflo(w.x); f[1] = bfhi(w.x); f[2] = bflo(w.y); f[3] = bfhi(w.y); f[4] = bflo(w.z); f[5] = bfhi(w.z); f[6] = bflo(w.w); f[7] = bfhi(w.w); }
; __device__ __forceinline__ u32x4 pack8(const float (&f)[8]) { u32x4 w; w.x = pk_bf16(f[0], f[1]); w.y = pk_bf16(f[2], f[3]); w.z = pk_bf16(f[4], f[5]); w.w = pk_bf16(f[6], f[7]); return w; }
; __device__ __forceinline__ float wave_sum(float v) {
; #pragma unroll
;     for (int o = 1; o < 64; o <<= 1) v += __shfl_xor(v, o);
;     return v;
; }
; __device__ __forceinline__ void init_rows(const float* x32, bf16* h16, float* ssp, int gw, int ngw, int lane) {
;     for (int m = gw; m < T; m += ngw) { float s = 0.f;
; #pragma unroll
;         for (int j = 0; j < 4; ++j) { float v[8]; ld8f(x32 + (size_t)m * D + (64 * j + lane) * 8, v); const u32x4 w = pack8(v); *(u32x4*)(h16 + (size_t)m * D + (64 * j + lane) * 8) = w; unpack8(w, v);
; #pragma unroll
;             for (int e = 0; e < 8; ++e) s += v[e] * v[e]; }
;         s = wave_sum(s);
;         if (lane < 32) ssp[(size_t)m * 32 + lane] = (lane == 0) ? s : 0.f; }
; }
.LBB0_131:
	v_add_co_u32_e32 v12, vcc, 0xfffff000, v4
	v_lshl_add_u64 v[20:21], s[88:89], 0, v[2:3]
	s_waitcnt lgkmcnt(0)
	v_addc_co_u32_e32 v13, vcc, -1, v5, vcc
	v_add_co_u32_e32 v16, vcc, 0xfffff010, v4
	global_load_dwordx4 v[12:15], v[12:13], off
	s_nop 0
	v_addc_co_u32_e32 v17, vcc, -1, v5, vcc
	global_load_dwordx4 v[16:19], v[16:17], off
	v_add_co_u32_e32 v22, vcc, s49, v4
	s_waitcnt vmcnt(0) lgkmcnt(0)
	v_cvt_pk_bf16_f32 v12, v12, v13
	v_addc_co_u32_e32 v23, vcc, -1, v5, vcc
	v_add_co_u32_e32 v32, vcc, s47, v20
	v_cvt_pk_bf16_f32 v13, v14, v15
	s_nop 0
	v_addc_co_u32_e32 v33, vcc, 0, v21, vcc
	v_cvt_pk_bf16_f32 v14, v16, v17
	v_cvt_pk_bf16_f32 v15, v18, v19
	v_add_co_u32_e32 v20, vcc, s52, v4
	global_store_dwordx4 v[32:33], v[12:15], off
	s_nop 0
	v_addc_co_u32_e32 v21, vcc, -1, v5, vcc
	global_load_dwordx4 v[16:19], v[22:23], off
	v_lshlrev_b32_e32 v34, 16, v12
	global_load_dwordx4 v[20:23], v[20:21], off
	v_and_b32_e32 v12, 0xffff0000, v12
	v_mul_f32_e32 v12, v12, v12
	v_lshlrev_b32_e32 v35, 16, v13
	v_fmac_f32_e32 v12, v34, v34
	v_and_b32_e32 v13, 0xffff0000, v13
	v_fmac_f32_e32 v12, v35, v35
	v_lshlrev_b32_e32 v36, 16, v14
	v_fmac_f32_e32 v12, v13, v13
	v_and_b32_e32 v14, 0xffff0000, v14
	v_fmac_f32_e32 v12, v36, v36
	v_lshlrev_b32_e32 v37, 16, v15
	v_fmac_f32_e32 v12, v14, v14
	v_and_b32_e32 v15, 0xffff0000, v15
	v_fmac_f32_e32 v12, v37, v37
	v_fmac_f32_e32 v12, v15, v15
	s_waitcnt vmcnt(0) lgkmcnt(0)
	v_cvt_pk_bf16_f32 v16, v16, v17
	v_cvt_pk_bf16_f32 v17, v18, v19
	v_cvt_pk_bf16_f32 v18, v20, v21
	v_cvt_pk_bf16_f32 v19, v22, v23
	global_store_dwordx4 v[32:33], v[16:19], off offset:1024
	global_load_dwordx4 v[20:23], v[4:5], off
	global_load_dwordx4 v[24:27], v[4:5], off offset:16
	v_lshlrev_b32_e32 v13, 16, v16
	v_and_b32_e32 v14, 0xffff0000, v16
	v_fmac_f32_e32 v12, v13, v13
	v_lshlrev_b32_e32 v15, 16, v17
	v_fmac_f32_e32 v12, v14, v14
	v_and_b32_e32 v16, 0xffff0000, v17
	v_fmac_f32_e32 v12, v15, v15
	v_lshlrev_b32_e32 v17, 16, v18
	v_fmac_f32_e32 v12, v16, v16
	v_and_b32_e32 v18, 0xffff0000, v18
	v_fmac_f32_e32 v12, v17, v17
	v_lshlrev_b32_e32 v34, 16, v19
	v_fmac_f32_e32 v12, v18, v18
	v_and_b32_e32 v19, 0xffff0000, v19
	v_fmac_f32_e32 v12, v34, v34
	v_fmac_f32_e32 v12, v19, v19
	s_waitcnt vmcnt(0) lgkmcnt(0)
	v_cvt_pk_bf16_f32 v20, v20, v21
	v_cvt_pk_bf16_f32 v21, v22, v23
	v_cvt_pk_bf16_f32 v22, v24, v25
	v_cvt_pk_bf16_f32 v23, v26, v27
	global_store_dwordx4 v[32:33], v[20:23], off offset:2048
	global_load_dwordx4 v[24:27], v[4:5], off offset:2048
	global_load_dwordx4 v[28:31], v[4:5], off offset:2064
	v_lshlrev_b32_e32 v13, 16, v20
	v_and_b32_e32 v14, 0xffff0000, v20
	v_fmac_f32_e32 v12, v13, v13
	v_lshlrev_b32_e32 v15, 16, v21
	v_fmac_f32_e32 v12, v14, v14
	v_and_b32_e32 v16, 0xffff0000, v21
	v_fmac_f32_e32 v12, v15, v15
	v_lshlrev_b32_e32 v17, 16, v22
	v_fmac_f32_e32 v12, v16, v16
	v_and_b32_e32 v18, 0xffff0000, v22
	v_fmac_f32_e32 v12, v17, v17
	v_lshlrev_b32_e32 v19, 16, v23
	v_fmac_f32_e32 v12, v18, v18
	v_and_b32_e32 v20, 0xffff0000, v23
	v_fmac_f32_e32 v12, v19, v19
	v_fmac_f32_e32 v12, v20, v20
	s_waitcnt vmcnt(0) lgkmcnt(0)
	v_cvt_pk_bf16_f32 v14, v24, v25
	v_lshlrev_b32_e32 v13, 16, v14
	v_cvt_pk_bf16_f32 v15, v26, v27
	v_and_b32_e32 v18, 0xffff0000, v14
	v_fmac_f32_e32 v12, v13, v13
	v_lshlrev_b32_e32 v19, 16, v15
	v_fmac_f32_e32 v12, v18, v18
	v_cvt_pk_bf16_f32 v16, v28, v29
	v_and_b32_e32 v20, 0xffff0000, v15
	v_fmac_f32_e32 v12, v19, v19
	v_lshlrev_b32_e32 v21, 16, v16
	v_fmac_f32_e32 v12, v20, v20
	v_cvt_pk_bf16_f32 v17, v30, v31
	v_and_b32_e32 v22, 0xffff0000, v16
	v_fmac_f32_e32 v12, v21, v21
	v_lshlrev_b32_e32 v23, 16, v17
	v_fmac_f32_e32 v12, v22, v22
	v_and_b32_e32 v24, 0xffff0000, v17
	v_fmac_f32_e32 v12, v23, v23
	v_fmac_f32_e32 v12, v24, v24
	ds_bpermute_b32 v13, v6, v12
	global_store_dwordx4 v[32:33], v[14:17], off offset:3072
	s_waitcnt lgkmcnt(0)
	v_add_f32_e32 v12, v12, v13
	ds_bpermute_b32 v13, v7, v12
	s_waitcnt lgkmcnt(0)
	v_add_f32_e32 v12, v12, v13
	ds_bpermute_b32 v13, v8, v12
	s_waitcnt lgkmcnt(0)
	v_add_f32_e32 v12, v12, v13
	ds_bpermute_b32 v13, v9, v12
	s_waitcnt lgkmcnt(0)
	v_add_f32_e32 v12, v12, v13
	ds_bpermute_b32 v13, v10, v12
	s_waitcnt lgkmcnt(0)
	v_add_f32_e32 v12, v12, v13
	ds_bpermute_b32 v13, v11, v12
	s_and_saveexec_b64 s[0:1], s[38:39]
	s_cbranch_execz .LBB0_130
	s_waitcnt lgkmcnt(0)
	v_add_f32_e32 v12, v12, v13
	v_cndmask_b32_e64 v14, 0, v12, s[40:41]
	v_lshl_add_u64 v[12:13], s[88:89], 0, v[0:1]
	global_store_dword v[12:13], v14, off
	s_branch .LBB0_130

; __device__ __forceinline__ unsigned pk_bf16(float lo, float hi) { f32x2e v = {lo, hi}; bf16x2e b = __builtin_convertvector(v, bf16x2e); return __builtin_bit_cast(unsigned, b); }
; #define LAS __attribute__((address_space(3)))
; __device__ __forceinline__ void tr_item(const float* W, int Ksrc, int N, int k0, int n0, bf16* dst, int ldt, int drow0, int dcol0, LAS float* scr, int lane, const float* nscale = nullptr, const float* kscale = nullptr) {
;     f32x4 tv[8]; const int kr_ = lane >> 3, nq_ = lane & 7;
; #pragma unroll
;     for (int i = 0; i < 8; ++i) { const int kk = 8 * i + kr_; const int kr = (k0 + kk < Ksrc) ? (k0 + kk) : (Ksrc - 1); tv[i] = __builtin_nontemporal_load((const f32x4*)(W + (size_t)kr * N + n0 + 4 * nq_)); }
; #pragma unroll
;     for (int i = 0; i < 8; ++i) { const int kk = 8 * i + kr_; const bool ok = (k0 + kk < Ksrc); LAS float* d_ = scr + kk * 33 + 4 * nq_;
;         const float ks_ = (ok && kscale) ? kscale[k0 + kk] : 1.0f;
;         d_[0] = ok ? tv[i].x * ks_ : 0.f; d_[1] = ok ? tv[i].y * ks_ : 0.f; d_[2] = ok ? tv[i].z * ks_ : 0.f; d_[3] = ok ? tv[i].w * ks_ : 0.f; }
;     asm volatile("s_waitcnt lgkmcnt(0)" ::: "memory");
;     const int c = lane & 7;
; #pragma unroll
;     for (int j = 0; j < 4; ++j) { const int n = (lane >> 3) + 8 * j; const LAS float* s = scr + (8 * c) * 33 + n;
;         const float sc = nscale ? nscale[n0 + n] : 1.0f;
;         u32x4 o; o.x = pk_bf16(s[0 * 33] * sc, s[1 * 33] * sc); o.y = pk_bf16(s[2 * 33] * sc, s[3 * 33] * sc); o.z = pk_bf16(s[4 * 33] * sc, s[5 * 33] * sc); o.w = pk_bf16(s[6 * 33] * sc, s[7 * 33] * sc);
;         *(u32x4*)(dst + (size_t)(drow0 + n) * ldt + dcol0 + k0 + 8 * c) = o; }
;     asm volatile("s_waitcnt lgkmcnt(0)" ::: "memory");
; }
.LBB0_139:
	s_or_b64 exec, exec, s[0:1]
	s_waitcnt vmcnt(0) lgkmcnt(0)
	v_mul_f32_e32 v0, v0, v6
	v_mul_f32_e32 v1, v1, v6
	v_cndmask_b32_e32 v0, 0, v0, vcc
	v_cndmask_b32_e32 v1, 0, v1, vcc
	v_add_u32_e32 v7, 0x840, v8
	ds_write2_b32 v7, v0, v1 offset1:1
	v_mul_f32_e32 v0, v2, v6
	v_mul_f32_e32 v1, v3, v6
	v_cndmask_b32_e32 v0, 0, v0, vcc
	v_cndmask_b32_e32 v1, 0, v1, vcc
	v_add_u32_e32 v2, 0x848, v8
	ds_write2_b32 v2, v0, v1 offset1:1
	s_waitcnt lgkmcnt(0)
	ds_read_b32 v0, v70
	ds_read_b32 v1, v70 offset:132
	ds_read_b32 v2, v70 offset:264
	ds_read_b32 v3, v70 offset:396
	ds_read_b32 v6, v70 offset:528
	ds_read_b32 v7, v70 offset:660
	ds_read_b32 v8, v70 offset:792
	ds_read_b32 v9, v70 offset:924
	s_waitcnt lgkmcnt(6)
	v_cvt_pk_bf16_f32 v0, v0, v1
	s_waitcnt lgkmcnt(4)
	v_cvt_pk_bf16_f32 v1, v2, v3
	s_waitcnt lgkmcnt(2)
	v_cvt_pk_bf16_f32 v2, v6, v7
	v_add_u32_e32 v6, s80, v32
	v_ashrrev_i32_e32 v7, 31, v6
	v_lshl_add_u64 v[4:5], v[4:5], 1, v[54:55]
	s_waitcnt lgkmcnt(0)
	v_cvt_pk_bf16_f32 v3, v8, v9
	v_lshlrev_b64 v[8:9], 12, v[6:7]
	v_lshl_add_u64 v[8:9], v[4:5], 0, v[8:9]
	global_store_dwordx4 v[8:9], v[0:3], off
	ds_read_b32 v0, v70 offset:32
	ds_read_b32 v1, v70 offset:164
	ds_read_b32 v2, v70 offset:296
	ds_read_b32 v3, v70 offset:428
	ds_read_b32 v7, v70 offset:560
	ds_read_b32 v8, v70 offset:692
	ds_read_b32 v9, v70 offset:824
	ds_read_b32 v10, v70 offset:956
	s_waitcnt lgkmcnt(0)
	v_cvt_pk_bf16_f32 v0, v0, v1
	v_cvt_pk_bf16_f32 v1, v2, v3
	v_cvt_pk_bf16_f32 v2, v7, v8
	v_add_u32_e32 v8, 8, v6
	v_cvt_pk_bf16_f32 v3, v9, v10
	v_ashrrev_i32_e32 v9, 31, v8
	v_lshlrev_b64 v[8:9], 12, v[8:9]
	v_lshl_add_u64 v[8:9], v[4:5], 0, v[8:9]
	global_store_dwordx4 v[8:9], v[0:3], off
	ds_read_b32 v0, v70 offset:64
	ds_read_b32 v1, v70 offset:196
	ds_read_b32 v2, v70 offset:328
	ds_read_b32 v3, v70 offset:460
	ds_read_b32 v7, v70 offset:592
	ds_read_b32 v8, v70 offset:724
	ds_read_b32 v9, v70 offset:856
	ds_read_b32 v10, v70 offset:988
	s_waitcnt lgkmcnt(0)
	v_cvt_pk_bf16_f32 v0, v0, v1
	v_cvt_pk_bf16_f32 v1, v2, v3
	v_cvt_pk_bf16_f32 v2, v7, v8
	v_add_u32_e32 v8, 16, v6
	v_cvt_pk_bf16_f32 v3, v9, v10
	v_ashrrev_i32_e32 v9, 31, v8
	v_lshlrev_b64 v[8:9], 12, v[8:9]
	v_lshl_add_u64 v[8:9], v[4:5], 0, v[8:9]
	global_store_dwordx4 v[8:9], v[0:3], off
	ds_read_b32 v0, v70 offset:96
	ds_read_b32 v1, v70 offset:228
	ds_read_b32 v2, v70 offset:360
	ds_read_b32 v3, v70 offset:492
	ds_read_b32 v7, v70 offset:624
	ds_read_b32 v8, v70 offset:756
	ds_read_b32 v9, v70 offset:888
	ds_read_b32 v10, v70 offset:1020
	v_add_u32_e32 v6, 24, v6
	s_waitcnt lgkmcnt(0)
	v_cvt_pk_bf16_f32 v0, v0, v1
	v_cvt_pk_bf16_f32 v1, v2, v3
	v_cvt_pk_bf16_f32 v2, v7, v8
	v_ashrrev_i32_e32 v7, 31, v6
	v_lshlrev_b64 v[6:7], 12, v[6:7]
	v_cvt_pk_bf16_f32 v3, v9, v10
	v_lshl_add_u64 v[4:5], v[4:5], 0, v[6:7]
	global_store_dwordx4 v[4:5], v[0:3], off
	s_waitcnt lgkmcnt(0)
	s_add_i32 s4, s4, s16
	s_add_i32 s2, s2, s27
	s_cmpk_lt_i32 s4, 0x1920
	s_cbranch_scc0 .LBB0_158
.LBB0_140:
	s_mul_hi_i32 s0, s4, 0x28c1979
	s_lshr_b32 s1, s0, 31
	s_ashr_i32 s0, s0, 1
	s_add_i32 s0, s0, s1
	s_mul_i32 s1, s0, 0xffffe6e0
	s_lshl_b32 s82, s0, 6
	s_add_i32 s80, s2, s1
	v_or_b32_e32 v56, s82, v32
	s_ashr_i32 s81, s80, 31
	v_or_b32_e32 v4, 8, v56
	v_lshl_add_u64 v[0:1], s[80:81], 2, v[52:53]
	v_min_i32_e32 v2, 0x7ff, v56
	v_min_i32_e32 v4, 0x7ff, v4
	v_mad_i64_i32 v[2:3], s[0:1], v2, s70, v[0:1]
	v_mad_i64_i32 v[4:5], s[0:1], v4, s70, v[0:1]
	global_load_dwordx4 v[28:31], v[2:3], off nt
	global_load_dwordx4 v[24:27], v[4:5], off nt
	v_or_b32_e32 v2, 16, v56
	v_or_b32_e32 v4, 24, v56
	v_min_i32_e32 v2, 0x7ff, v2
	v_min_i32_e32 v4, 0x7ff, v4
	v_mad_i64_i32 v[2:3], s[0:1], v2, s70, v[0:1]
	v_mad_i64_i32 v[4:5], s[0:1], v4, s70, v[0:1]
	global_load_dwordx4 v[20:23], v[2:3], off nt
	global_load_dwordx4 v[16:19], v[4:5], off nt
	v_or_b32_e32 v2, 32, v56
	v_or_b32_e32 v4, 40, v56
	v_min_i32_e32 v2, 0x7ff, v2
	v_min_i32_e32 v4, 0x7ff, v4
	v_mad_i64_i32 v[2:3], s[0:1], v2, s70, v[0:1]
	v_mad_i64_i32 v[4:5], s[0:1], v4, s70, v[0:1]
	global_load_dwordx4 v[12:15], v[2:3], off nt
	global_load_dwordx4 v[8:11], v[4:5], off nt
	v_or_b32_e32 v2, 48, v56
	v_or_b32_e32 v4, 56, v56
	v_min_i32_e32 v2, 0x7ff, v2
	v_min_i32_e32 v4, 0x7ff, v4
	v_mad_i64_i32 v[2:3], s[0:1], v2, s70, v[0:1]
	v_mad_i64_i32 v[0:1], s[0:1], v4, s70, v[0:1]
	global_load_dwordx4 v[4:7], v[2:3], off nt
	s_nop 0
	global_load_dwordx4 v[0:3], v[0:1], off nt
	v_cmp_gt_i32_e32 vcc, s61, v56
	s_and_b64 s[6:7], s[74:75], vcc
	v_mov_b32_e32 v71, 1.0
	v_mov_b32_e32 v57, 1.0
	s_and_saveexec_b64 s[0:1], s[6:7]
	s_cbranch_execz .LBB0_142
	v_ashrrev_i32_e32 v57, 31, v56
	v_lshl_add_u64 v[56:57], v[56:57], 2, s[40:41]
	global_load_dword v57, v[56:57], off
.LBB0_142:
	s_or_b64 exec, exec, s[0:1]
	s_waitcnt vmcnt(0) lgkmcnt(0)
	v_mul_f32_e32 v28, v28, v57
	v_mul_f32_e32 v29, v29, v57
	v_cndmask_b32_e32 v28, 0, v28, vcc
	v_cndmask_b32_e32 v29, 0, v29, vcc
	v_add_u32_e32 v56, v35, v37
	ds_write2_b32 v56, v28, v29 offset1:1
	v_mul_f32_e32 v28, v30, v57
	v_mul_f32_e32 v29, v31, v57
	v_cndmask_b32_e32 v28, 0, v28, vcc
	v_cndmask_b32_e32 v29, 0, v29, vcc
	ds_write2_b32 v56, v28, v29 offset0:2 offset1:3
	v_or_b32_e32 v28, s82, v58
	v_cmp_gt_i32_e32 vcc, s61, v28
	s_and_b64 s[6:7], s[74:75], vcc
	s_and_saveexec_b64 s[0:1], s[6:7]
	s_cbranch_execz .LBB0_144
	s_ashr_i32 s83, s82, 31
	v_lshl_add_u64 v[28:29], s[82:83], 0, v[32:33]
	v_lshl_add_u64 v[28:29], v[28:29], 2, s[40:41]
	global_load_dword v71, v[28:29], off offset:32
; #define LAS __attribute__((address_space(3)))
; __device__ __forceinline__ void tr_item(const float* W, int Ksrc, int N, int k0, int n0, bf16* dst, int ldt, int drow0, int dcol0, LAS float* scr, int lane, const float* nscale = nullptr, const float* kscale = nullptr) {
;     ...
;     for (int i = 0; i < 8; ++i) { const int kk = 8 * i + kr_; const int kr = (k0 + kk < Ksrc) ? (k0 + kk) : (Ksrc - 1); tv[i] = __builtin_nontemporal_load((const f32x4*)(W + (size_t)kr * N + n0 + 4 * nq_)); }
; #pragma unroll
;     for (int i = 0; i < 8; ++i) { const int kk = 8 * i + kr_; const bool ok = (k0 + kk < Ksrc); LAS float* d_ = scr + kk * 33 + 4 * nq_;
;         const float ks_ = (ok && kscale) ? kscale[k0 + kk] : 1.0f;
;         d_[0] = ok ? tv[i].x * ks_ : 0.f; d_[1] = ok ? tv[i].y * ks_ : 0.f; d_[2] = ok ? tv[i].z * ks_ : 0.f; d_[3] = ok ? tv[i].w * ks_ : 0.f; }
.LBB0_144:
	s_or_b64 exec, exec, s[0:1]
	s_waitcnt vmcnt(0) lgkmcnt(0)
	v_mul_f32_e32 v24, v24, v71
	v_mul_f32_e32 v25, v25, v71
	v_cndmask_b32_e32 v24, 0, v24, vcc
	v_cndmask_b32_e32 v25, 0, v25, vcc
	v_add_u32_e32 v28, v35, v59
	ds_write2_b32 v28, v24, v25 offset1:1
	v_mul_f32_e32 v24, v26, v71
	v_mul_f32_e32 v25, v27, v71
	v_cndmask_b32_e32 v24, 0, v24, vcc
	v_cndmask_b32_e32 v25, 0, v25, vcc
	ds_write2_b32 v28, v24, v25 offset0:2 offset1:3
	v_or_b32_e32 v24, s82, v60
	v_cmp_gt_i32_e32 vcc, s61, v24
	s_and_b64 s[6:7], s[74:75], vcc
	v_mov_b32_e32 v24, 1.0
	v_mov_b32_e32 v25, 1.0
	s_and_saveexec_b64 s[0:1], s[6:7]
	s_cbranch_execz .LBB0_146
	s_ashr_i32 s83, s82, 31
	v_lshl_add_u64 v[26:27], s[82:83], 0, v[32:33]
	v_lshl_add_u64 v[26:27], v[26:27], 2, s[40:41]
	global_load_dword v25, v[26:27], off offset:64
.LBB0_146:
	s_or_b64 exec, exec, s[0:1]
	s_waitcnt vmcnt(0) lgkmcnt(0)
	v_mul_f32_e32 v20, v20, v25
	v_mul_f32_e32 v21, v21, v25
	v_cndmask_b32_e32 v20, 0, v20, vcc
	v_cndmask_b32_e32 v21, 0, v21, vcc
	v_add_u32_e32 v26, v35, v61
	ds_write2_b32 v26, v20, v21 offset1:1
	v_mul_f32_e32 v20, v22, v25
	v_mul_f32_e32 v21, v23, v25
	v_cndmask_b32_e32 v20, 0, v20, vcc
	v_cndmask_b32_e32 v21, 0, v21, vcc
	ds_write2_b32 v26, v20, v21 offset0:2 offset1:3
	v_or_b32_e32 v20, s82, v62
	v_cmp_gt_i32_e32 vcc, s61, v20
	s_and_b64 s[6:7], s[74:75], vcc
	s_and_saveexec_b64 s[0:1], s[6:7]
	s_cbranch_execz .LBB0_148
	s_ashr_i32 s83, s82, 31
	v_lshl_add_u64 v[20:21], s[82:83], 0, v[32:33]
	v_lshl_add_u64 v[20:21], v[20:21], 2, s[40:41]
	global_load_dword v24, v[20:21], off offset:96
.LBB0_148:
	s_or_b64 exec, exec, s[0:1]
	s_waitcnt vmcnt(0) lgkmcnt(0)
	v_mul_f32_e32 v16, v16, v24
	v_mul_f32_e32 v17, v17, v24
	v_cndmask_b32_e32 v16, 0, v16, vcc
	v_cndmask_b32_e32 v17, 0, v17, vcc
	v_add_u32_e32 v20, v35, v63
	ds_write2_b32 v20, v16, v17 offset1:1
	v_mul_f32_e32 v16, v18, v24
	v_mul_f32_e32 v17, v19, v24
	v_cndmask_b32_e32 v16, 0, v16, vcc
	v_cndmask_b32_e32 v17, 0, v17, vcc
	ds_write2_b32 v20, v16, v17 offset0:2 offset1:3
	v_or_b32_e32 v16, s82, v64
	v_cmp_gt_i32_e32 vcc, s61, v16
	s_and_b64 s[6:7], s[74:75], vcc
	v_mov_b32_e32 v16, 1.0
	v_mov_b32_e32 v17, 1.0
	s_and_saveexec_b64 s[0:1], s[6:7]
	s_cbranch_execz .LBB0_150
	s_ashr_i32 s83, s82, 31
	v_lshl_add_u64 v[18:19], s[82:83], 0, v[32:33]
	v_lshl_add_u64 v[18:19], v[18:19], 2, s[40:41]
	global_load_dword v17, v[18:19], off offset:128
.LBB0_150:
	s_or_b64 exec, exec, s[0:1]
	s_waitcnt vmcnt(0) lgkmcnt(0)
	v_mul_f32_e32 v12, v12, v17
	v_mul_f32_e32 v13, v13, v17
	v_cndmask_b32_e32 v12, 0, v12, vcc
	v_cndmask_b32_e32 v13, 0, v13, vcc
	v_add_u32_e32 v18, v35, v65
	ds_write2_b32 v18, v12, v13 offset1:1
	v_mul_f32_e32 v12, v14, v17
	v_mul_f32_e32 v13, v15, v17
	v_cndmask_b32_e32 v12, 0, v12, vcc
	v_cndmask_b32_e32 v13, 0, v13, vcc
	ds_write2_b32 v18, v12, v13 offset0:2 offset1:3
	v_or_b32_e32 v12, s82, v66
	v_cmp_gt_i32_e32 vcc, s61, v12
	s_and_b64 s[6:7], s[74:75], vcc
	s_and_saveexec_b64 s[0:1], s[6:7]
	s_cbranch_execz .LBB0_152
	s_ashr_i32 s83, s82, 31
	v_lshl_add_u64 v[12:13], s[82:83], 0, v[32:33]
	v_lshl_add_u64 v[12:13], v[12:13], 2, s[40:41]
	global_load_dword v16, v[12:13], off offset:160
.LBB0_152:
	s_or_b64 exec, exec, s[0:1]
	s_waitcnt vmcnt(0) lgkmcnt(0)
	v_mul_f32_e32 v8, v8, v16
	v_mul_f32_e32 v9, v9, v16
	v_cndmask_b32_e32 v12, 0, v8, vcc
	v_cndmask_b32_e32 v9, 0, v9, vcc
	v_add_u32_e32 v8, v35, v67
	ds_write2_b32 v8, v12, v9 offset1:1
	v_mul_f32_e32 v9, v10, v16
	v_mul_f32_e32 v10, v11, v16
	v_cndmask_b32_e32 v9, 0, v9, vcc
	v_cndmask_b32_e32 v10, 0, v10, vcc
	ds_write2_b32 v8, v9, v10 offset0:2 offset1:3
	v_or_b32_e32 v9, s82, v68
	v_cmp_gt_i32_e32 vcc, s61, v9
	s_and_b64 s[6:7], s[74:75], vcc
	v_mov_b32_e32 v9, 1.0
	s_and_saveexec_b64 s[0:1], s[6:7]
	s_cbranch_execz .LBB0_154
	s_ashr_i32 s83, s82, 31
	v_lshl_add_u64 v[10:11], s[82:83], 0, v[32:33]
	v_lshl_add_u64 v[10:11], v[10:11], 2, s[40:41]
	global_load_dword v9, v[10:11], off offset:192
.LBB0_154:
	s_or_b64 exec, exec, s[0:1]
	s_waitcnt vmcnt(0) lgkmcnt(0)
	v_mul_f32_e32 v4, v4, v9
	v_mul_f32_e32 v5, v5, v9
	v_cndmask_b32_e32 v4, 0, v4, vcc
	v_cndmask_b32_e32 v5, 0, v5, vcc
	v_add_u32_e32 v10, 0x420, v8
	ds_write2_b32 v10, v4, v5 offset1:1
	v_mul_f32_e32 v4, v6, v9
	v_mul_f32_e32 v5, v7, v9
	v_cndmask_b32_e32 v4, 0, v4, vcc
	v_cndmask_b32_e32 v5, 0, v5, vcc
	v_add_u32_e32 v6, 0x428, v8
	ds_write2_b32 v6, v4, v5 offset1:1
	v_or_b32_e32 v4, s82, v69
	v_cmp_gt_i32_e32 vcc, s61, v4
	s_and_b64 s[0:1], s[74:75], vcc
	s_xor_b64 s[0:1], s[0:1], -1
	s_and_saveexec_b64 s[6:7], s[0:1]
	s_xor_b64 s[0:1], exec, s[6:7]
	s_ashr_i32 s83, s82, 31
	s_or_saveexec_b64 s[0:1], s[0:1]
	v_mov_b32_e32 v6, 1.0
	v_mov_b64_e32 v[4:5], s[82:83]
	s_xor_b64 exec, exec, s[0:1]
	s_cbranch_execz .LBB0_139
	s_ashr_i32 s83, s82, 31
	v_lshl_add_u64 v[4:5], s[82:83], 0, v[32:33]
	v_lshl_add_u64 v[4:5], v[4:5], 2, s[40:41]
	global_load_dword v6, v[4:5], off offset:224
	v_mov_b64_e32 v[4:5], s[82:83]
	s_branch .LBB0_139

; #define LAS __attribute__((address_space(3)))
; __device__ __forceinline__ void tr_item(const float* W, int Ksrc, int N, int k0, int n0, bf16* dst, int ldt, int drow0, int dcol0, LAS float* scr, int lane, const float* nscale = nullptr, const float* kscale = nullptr) {
;     ...
;     for (int i = 0; i < 8; ++i) { const int kk = 8 * i + kr_; const int kr = (k0 + kk < Ksrc) ? (k0 + kk) : (Ksrc - 1); tv[i] = __builtin_nontemporal_load((const f32x4*)(W + (size_t)kr * N + n0 + 4 * nq_)); }
; #pragma unroll
;     for (int i = 0; i < 8; ++i) { const int kk = 8 * i + kr_; const bool ok = (k0 + kk < Ksrc); LAS float* d_ = scr + kk * 33 + 4 * nq_;
;         const float ks_ = (ok && kscale) ? kscale[k0 + kk] : 1.0f;
;         d_[0] = ok ? tv[i].x * ks_ : 0.f; d_[1] = ok ? tv[i].y * ks_ : 0.f; d_[2] = ok ? tv[i].z * ks_ : 0.f; d_[3] = ok ? tv[i].w * ks_ : 0.f; }
;     asm volatile("s_waitcnt lgkmcnt(0)" ::: "memory");
.LBB0_160:
	s_ashr_i32 s2, s1, 31
	s_lshr_b32 s2, s2, 27
	s_add_i32 s2, s1, s2
	s_ashr_i32 s2, s2, 5
	s_lshl_b32 s86, s2, 6
	s_lshl_b32 s4, s2, 10
	v_or_b32_e32 v53, s86, v32
	s_sub_i32 s84, s0, s4
	v_min_i32_e32 v2, 63, v53
	s_ashr_i32 s85, s84, 31
	v_ashrrev_i32_e32 v3, 31, v2
	v_lshl_add_u64 v[0:1], s[84:85], 2, v[54:55]
	v_lshlrev_b64 v[2:3], 12, v[2:3]
	v_lshl_add_u64 v[2:3], v[0:1], 0, v[2:3]
	global_load_dwordx4 v[28:31], v[2:3], off nt
	v_or_b32_e32 v2, 8, v53
	v_min_i32_e32 v2, 63, v2
	v_ashrrev_i32_e32 v3, 31, v2
	v_lshlrev_b64 v[2:3], 12, v[2:3]
	v_lshl_add_u64 v[2:3], v[0:1], 0, v[2:3]
	global_load_dwordx4 v[24:27], v[2:3], off nt
	v_or_b32_e32 v2, 16, v53
	v_min_i32_e32 v2, 63, v2
	v_ashrrev_i32_e32 v3, 31, v2
	v_lshlrev_b64 v[2:3], 12, v[2:3]
	v_lshl_add_u64 v[2:3], v[0:1], 0, v[2:3]
	global_load_dwordx4 v[20:23], v[2:3], off nt
	v_or_b32_e32 v2, 24, v53
	v_min_i32_e32 v2, 63, v2
	v_ashrrev_i32_e32 v3, 31, v2
	v_lshlrev_b64 v[2:3], 12, v[2:3]
	v_lshl_add_u64 v[2:3], v[0:1], 0, v[2:3]
	global_load_dwordx4 v[16:19], v[2:3], off nt
	v_or_b32_e32 v2, 32, v53
	v_min_i32_e32 v2, 63, v2
	v_ashrrev_i32_e32 v3, 31, v2
	v_lshlrev_b64 v[2:3], 12, v[2:3]
	v_lshl_add_u64 v[2:3], v[0:1], 0, v[2:3]
	global_load_dwordx4 v[12:15], v[2:3], off nt
	v_or_b32_e32 v2, 40, v53
	v_min_i32_e32 v2, 63, v2
	v_ashrrev_i32_e32 v3, 31, v2
	v_lshlrev_b64 v[2:3], 12, v[2:3]
	v_lshl_add_u64 v[2:3], v[0:1], 0, v[2:3]
	global_load_dwordx4 v[8:11], v[2:3], off nt
	v_or_b32_e32 v2, 48, v53
	v_min_i32_e32 v2, 63, v2
	v_ashrrev_i32_e32 v3, 31, v2
	v_lshlrev_b64 v[2:3], 12, v[2:3]
	v_lshl_add_u64 v[2:3], v[0:1], 0, v[2:3]
	global_load_dwordx4 v[4:7], v[2:3], off nt
	v_or_b32_e32 v2, 56, v53
	v_min_i32_e32 v2, 63, v2
	v_ashrrev_i32_e32 v3, 31, v2
	v_lshlrev_b64 v[2:3], 12, v[2:3]
	v_lshl_add_u64 v[0:1], v[0:1], 0, v[2:3]
	global_load_dwordx4 v[0:3], v[0:1], off nt
	v_cmp_gt_i32_e32 vcc, 64, v53
	v_add_u32_e32 v53, v35, v37
	s_ashr_i32 s87, s86, 31
	s_add_i32 s1, s1, s16
	s_add_i32 s0, s0, s27
	s_cmp_lt_i32 s1, 32
	s_waitcnt vmcnt(0) lgkmcnt(0)
	v_cndmask_b32_e32 v28, 0, v28, vcc
	v_cndmask_b32_e32 v29, 0, v29, vcc
	ds_write2_b32 v53, v28, v29 offset1:1
	v_cndmask_b32_e32 v28, 0, v30, vcc
	v_cndmask_b32_e32 v29, 0, v31, vcc
	ds_write2_b32 v53, v28, v29 offset0:2 offset1:3
	v_or_b32_e32 v28, s86, v58
	v_cmp_gt_i32_e32 vcc, 64, v28
	v_add_u32_e32 v28, 0x420, v53
	s_nop 0
	v_cndmask_b32_e32 v24, 0, v24, vcc
	v_cndmask_b32_e32 v25, 0, v25, vcc
	ds_write2_b32 v28, v24, v25 offset1:1
	v_cndmask_b32_e32 v24, 0, v26, vcc
	v_cndmask_b32_e32 v25, 0, v27, vcc
	v_add_u32_e32 v26, 0x428, v53
	ds_write2_b32 v26, v24, v25 offset1:1
	v_or_b32_e32 v24, s86, v60
	v_cmp_gt_i32_e32 vcc, 64, v24
	v_add_u32_e32 v24, 0x840, v53
	s_nop 0
	v_cndmask_b32_e32 v20, 0, v20, vcc
	v_cndmask_b32_e32 v21, 0, v21, vcc
	ds_write2_b32 v24, v20, v21 offset1:1
	v_cndmask_b32_e32 v20, 0, v22, vcc
	v_cndmask_b32_e32 v21, 0, v23, vcc
	v_add_u32_e32 v22, 0x848, v53
	ds_write2_b32 v22, v20, v21 offset1:1
	v_or_b32_e32 v20, s86, v62
	v_cmp_gt_i32_e32 vcc, 64, v20
	v_add_u32_e32 v20, 0xc60, v53
	s_nop 0
	v_cndmask_b32_e32 v16, 0, v16, vcc
	v_cndmask_b32_e32 v17, 0, v17, vcc
	ds_write2_b32 v20, v16, v17 offset1:1
	v_cndmask_b32_e32 v16, 0, v18, vcc
	v_cndmask_b32_e32 v17, 0, v19, vcc
	v_add_u32_e32 v18, 0xc68, v53
	ds_write2_b32 v18, v16, v17 offset1:1
	v_or_b32_e32 v16, s86, v64
	v_cmp_gt_i32_e32 vcc, 64, v16
	v_add_u32_e32 v16, 0x1080, v53
	s_nop 0
	v_cndmask_b32_e32 v12, 0, v12, vcc
	v_cndmask_b32_e32 v13, 0, v13, vcc
	ds_write2_b32 v16, v12, v13 offset1:1
	v_cndmask_b32_e32 v12, 0, v14, vcc
	v_cndmask_b32_e32 v13, 0, v15, vcc
	v_add_u32_e32 v14, 0x1088, v53
	ds_write2_b32 v14, v12, v13 offset1:1
	v_or_b32_e32 v12, s86, v66
	v_cmp_gt_i32_e32 vcc, 64, v12
	v_add_u32_e32 v12, 0x14a0, v53
	s_nop 0
	v_cndmask_b32_e32 v8, 0, v8, vcc
	v_cndmask_b32_e32 v9, 0, v9, vcc
	ds_write2_b32 v12, v8, v9 offset1:1
	v_cndmask_b32_e32 v8, 0, v10, vcc
	v_cndmask_b32_e32 v9, 0, v11, vcc
	v_add_u32_e32 v10, v35, v67
	ds_write2_b32 v10, v8, v9 offset0:2 offset1:3
	v_or_b32_e32 v8, s86, v68
	v_cmp_gt_i32_e32 vcc, 64, v8
	v_add_u32_e32 v8, 0x420, v10
	s_nop 0
	v_cndmask_b32_e32 v4, 0, v4, vcc
	v_cndmask_b32_e32 v5, 0, v5, vcc
	ds_write2_b32 v8, v4, v5 offset1:1
	v_cndmask_b32_e32 v4, 0, v6, vcc
	v_cndmask_b32_e32 v5, 0, v7, vcc
	v_add_u32_e32 v6, 0x428, v10
	ds_write2_b32 v6, v4, v5 offset1:1
	v_or_b32_e32 v4, s86, v69
	v_cmp_gt_i32_e32 vcc, 64, v4
	v_add_u32_e32 v4, 0x840, v10
	v_add_u32_e32 v8, s84, v32
	v_cndmask_b32_e32 v0, 0, v0, vcc
	v_cndmask_b32_e32 v1, 0, v1, vcc
	ds_write2_b32 v4, v0, v1 offset1:1
	v_cndmask_b32_e32 v0, 0, v2, vcc
	v_cndmask_b32_e32 v1, 0, v3, vcc
	v_add_u32_e32 v2, 0x848, v10
	ds_write2_b32 v2, v0, v1 offset1:1
	s_waitcnt lgkmcnt(0)
; __device__ __forceinline__ unsigned pk_bf16(float lo, float hi) { f32x2e v = {lo, hi}; bf16x2e b = __builtin_convertvector(v, bf16x2e); return __builtin_bit_cast(unsigned, b); }
; #define LAS __attribute__((address_space(3)))
; __device__ __forceinline__ void tr_item(const float* W, int Ksrc, int N, int k0, int n0, bf16* dst, int ldt, int drow0, int dcol0, LAS float* scr, int lane, const float* nscale = nullptr, const float* kscale = nullptr) {
;     ...
;     const int c = lane & 7;
; #pragma unroll
;     for (int j = 0; j < 4; ++j) { const int n = (lane >> 3) + 8 * j; const LAS float* s = scr + (8 * c) * 33 + n;
;         const float sc = nscale ? nscale[n0 + n] : 1.0f;
;         u32x4 o; o.x = pk_bf16(s[0 * 33] * sc, s[1 * 33] * sc); o.y = pk_bf16(s[2 * 33] * sc, s[3 * 33] * sc); o.z = pk_bf16(s[4 * 33] * sc, s[5 * 33] * sc); o.w = pk_bf16(s[6 * 33] * sc, s[7 * 33] * sc);
;         *(u32x4*)(dst + (size_t)(drow0 + n) * ldt + dcol0 + k0 + 8 * c) = o; }
;     asm volatile("s_waitcnt lgkmcnt(0)" ::: "memory");
	ds_read_b32 v0, v70
	ds_read_b32 v1, v70 offset:132
	v_lshl_add_u64 v[4:5], s[86:87], 1, v[56:57]
	s_waitcnt lgkmcnt(0)
	v_cvt_pk_bf16_f32 v0, v0, v1
	ds_read_b32 v1, v70 offset:264
	ds_read_b32 v2, v70 offset:396
	s_waitcnt lgkmcnt(0)
	v_cvt_pk_bf16_f32 v1, v1, v2
	ds_read_b32 v2, v70 offset:528
	ds_read_b32 v3, v70 offset:660
	s_waitcnt lgkmcnt(0)
	v_cvt_pk_bf16_f32 v2, v2, v3
	ds_read_b32 v3, v70 offset:792
	ds_read_b32 v6, v70 offset:924
	s_waitcnt lgkmcnt(0)
	v_cvt_pk_bf16_f32 v3, v3, v6
	v_mad_i64_i32 v[6:7], s[4:5], v8, s60, v[4:5]
	global_store_dwordx4 v[6:7], v[0:3], off
	ds_read_b32 v0, v70 offset:32
	ds_read_b32 v1, v70 offset:164
	s_waitcnt lgkmcnt(0)
	v_cvt_pk_bf16_f32 v0, v0, v1
	ds_read_b32 v1, v70 offset:296
	ds_read_b32 v2, v70 offset:428
	s_waitcnt lgkmcnt(0)
	v_cvt_pk_bf16_f32 v1, v1, v2
	ds_read_b32 v2, v70 offset:560
	ds_read_b32 v3, v70 offset:692
	s_waitcnt lgkmcnt(0)
	v_cvt_pk_bf16_f32 v2, v2, v3
	ds_read_b32 v3, v70 offset:824
	ds_read_b32 v6, v70 offset:956
	s_waitcnt lgkmcnt(0)
	v_cvt_pk_bf16_f32 v3, v3, v6
	v_add_u32_e32 v6, 8, v8
	v_mad_i64_i32 v[6:7], s[4:5], v6, s60, v[4:5]
	global_store_dwordx4 v[6:7], v[0:3], off
	ds_read_b32 v0, v70 offset:64
	ds_read_b32 v1, v70 offset:196
	s_waitcnt lgkmcnt(0)
	v_cvt_pk_bf16_f32 v0, v0, v1
	ds_read_b32 v1, v70 offset:328
	ds_read_b32 v2, v70 offset:460
	s_waitcnt lgkmcnt(0)
	v_cvt_pk_bf16_f32 v1, v1, v2
	ds_read_b32 v2, v70 offset:592
	ds_read_b32 v3, v70 offset:724
	s_waitcnt lgkmcnt(0)
	v_cvt_pk_bf16_f32 v2, v2, v3
	ds_read_b32 v3, v70 offset:856
	ds_read_b32 v6, v70 offset:988
	s_waitcnt lgkmcnt(0)
	v_cvt_pk_bf16_f32 v3, v3, v6
	v_add_u32_e32 v6, 16, v8
	v_mad_i64_i32 v[6:7], s[4:5], v6, s60, v[4:5]
	global_store_dwordx4 v[6:7], v[0:3], off
	ds_read_b32 v0, v70 offset:96
	ds_read_b32 v1, v70 offset:228
	s_waitcnt lgkmcnt(0)
	v_cvt_pk_bf16_f32 v0, v0, v1
	ds_read_b32 v1, v70 offset:360
	ds_read_b32 v2, v70 offset:492
	s_waitcnt lgkmcnt(0)
	v_cvt_pk_bf16_f32 v1, v1, v2
	ds_read_b32 v2, v70 offset:624
	ds_read_b32 v3, v70 offset:756
	s_waitcnt lgkmcnt(0)
	v_cvt_pk_bf16_f32 v2, v2, v3
	ds_read_b32 v3, v70 offset:888
	ds_read_b32 v6, v70 offset:1020
	s_waitcnt lgkmcnt(0)
	v_cvt_pk_bf16_f32 v3, v3, v6
	v_add_u32_e32 v6, 24, v8
	v_mad_i64_i32 v[4:5], s[4:5], v6, s60, v[4:5]
	global_store_dwordx4 v[4:5], v[0:3], off
	s_waitcnt lgkmcnt(0)
	s_cbranch_scc1 .LBB0_160

; #define LAS __attribute__((address_space(3)))
; __device__ __forceinline__ void tr_item(const float* W, int Ksrc, int N, int k0, int n0, bf16* dst, int ldt, int drow0, int dcol0, LAS float* scr, int lane, const float* nscale = nullptr, const float* kscale = nullptr) {
;     ...
;     for (int i = 0; i < 8; ++i) { const int kk = 8 * i + kr_; const int kr = (k0 + kk < Ksrc) ? (k0 + kk) : (Ksrc - 1); tv[i] = __builtin_nontemporal_load((const f32x4*)(W + (size_t)kr * N + n0 + 4 * nq_)); }
; #pragma unroll
;     for (int i = 0; i < 8; ++i) { const int kk = 8 * i + kr_; const bool ok = (k0 + kk < Ksrc); LAS float* d_ = scr + kk * 33 + 4 * nq_;
;         const float ks_ = (ok && kscale) ? kscale[k0 + kk] : 1.0f;
;         d_[0] = ok ? tv[i].x * ks_ : 0.f; d_[1] = ok ? tv[i].y * ks_ : 0.f; d_[2] = ok ? tv[i].z * ks_ : 0.f; d_[3] = ok ? tv[i].w * ks_ : 0.f; }
;     asm volatile("s_waitcnt lgkmcnt(0)" ::: "memory");
.LBB0_163:
	s_ashr_i32 s2, s1, 31
	s_lshr_b32 s2, s2, 27
	s_add_i32 s2, s1, s2
	s_ashr_i32 s2, s2, 5
	s_lshl_b32 s82, s2, 6
	s_lshl_b32 s4, s2, 10
	v_or_b32_e32 v53, s82, v32
	s_sub_i32 s38, s0, s4
	v_min_i32_e32 v2, 63, v53
	s_ashr_i32 s39, s38, 31
	v_ashrrev_i32_e32 v3, 31, v2
	v_lshl_add_u64 v[0:1], s[38:39], 2, v[54:55]
	v_lshlrev_b64 v[2:3], 12, v[2:3]
	v_lshl_add_u64 v[2:3], v[0:1], 0, v[2:3]
	global_load_dwordx4 v[28:31], v[2:3], off nt
	v_or_b32_e32 v2, 8, v53
	v_min_i32_e32 v2, 63, v2
	v_ashrrev_i32_e32 v3, 31, v2
	v_lshlrev_b64 v[2:3], 12, v[2:3]
	v_lshl_add_u64 v[2:3], v[0:1], 0, v[2:3]
	global_load_dwordx4 v[24:27], v[2:3], off nt
	v_or_b32_e32 v2, 16, v53
	v_min_i32_e32 v2, 63, v2
	v_ashrrev_i32_e32 v3, 31, v2
	v_lshlrev_b64 v[2:3], 12, v[2:3]
	v_lshl_add_u64 v[2:3], v[0:1], 0, v[2:3]
	global_load_dwordx4 v[20:23], v[2:3], off nt
	v_or_b32_e32 v2, 24, v53
	v_min_i32_e32 v2, 63, v2
	v_ashrrev_i32_e32 v3, 31, v2
	v_lshlrev_b64 v[2:3], 12, v[2:3]
	v_lshl_add_u64 v[2:3], v[0:1], 0, v[2:3]
	global_load_dwordx4 v[16:19], v[2:3], off nt
	v_or_b32_e32 v2, 32, v53
	v_min_i32_e32 v2, 63, v2
	v_ashrrev_i32_e32 v3, 31, v2
	v_lshlrev_b64 v[2:3], 12, v[2:3]
	v_lshl_add_u64 v[2:3], v[0:1], 0, v[2:3]
	global_load_dwordx4 v[12:15], v[2:3], off nt
	v_or_b32_e32 v2, 40, v53
	v_min_i32_e32 v2, 63, v2
	v_ashrrev_i32_e32 v3, 31, v2
	v_lshlrev_b64 v[2:3], 12, v[2:3]
	v_lshl_add_u64 v[2:3], v[0:1], 0, v[2:3]
	global_load_dwordx4 v[8:11], v[2:3], off nt
	v_or_b32_e32 v2, 48, v53
	v_min_i32_e32 v2, 63, v2
	v_ashrrev_i32_e32 v3, 31, v2
	v_lshlrev_b64 v[2:3], 12, v[2:3]
	v_lshl_add_u64 v[2:3], v[0:1], 0, v[2:3]
	global_load_dwordx4 v[4:7], v[2:3], off nt
	v_or_b32_e32 v2, 56, v53
	v_min_i32_e32 v2, 63, v2
	v_ashrrev_i32_e32 v3, 31, v2
	v_lshlrev_b64 v[2:3], 12, v[2:3]
	v_lshl_add_u64 v[0:1], v[0:1], 0, v[2:3]
	global_load_dwordx4 v[0:3], v[0:1], off nt
	v_cmp_gt_i32_e32 vcc, 64, v53
	v_add_u32_e32 v53, v35, v37
	s_ashr_i32 s83, s82, 31
	s_add_i32 s1, s1, s16
	s_add_i32 s0, s0, s27
	s_cmp_lt_i32 s1, 32
	s_waitcnt vmcnt(0) lgkmcnt(0)
	v_cndmask_b32_e32 v28, 0, v28, vcc
	v_cndmask_b32_e32 v29, 0, v29, vcc
	ds_write2_b32 v53, v28, v29 offset1:1
	v_cndmask_b32_e32 v28, 0, v30, vcc
	v_cndmask_b32_e32 v29, 0, v31, vcc
	ds_write2_b32 v53, v28, v29 offset0:2 offset1:3
	v_or_b32_e32 v28, s82, v58
	v_cmp_gt_i32_e32 vcc, 64, v28
	v_add_u32_e32 v28, 0x420, v53
	s_nop 0
	v_cndmask_b32_e32 v24, 0, v24, vcc
	v_cndmask_b32_e32 v25, 0, v25, vcc
	ds_write2_b32 v28, v24, v25 offset1:1
	v_cndmask_b32_e32 v24, 0, v26, vcc
	v_cndmask_b32_e32 v25, 0, v27, vcc
	v_add_u32_e32 v26, 0x428, v53
	ds_write2_b32 v26, v24, v25 offset1:1
	v_or_b32_e32 v24, s82, v60
	v_cmp_gt_i32_e32 vcc, 64, v24
	v_add_u32_e32 v24, 0x840, v53
	s_nop 0
	v_cndmask_b32_e32 v20, 0, v20, vcc
	v_cndmask_b32_e32 v21, 0, v21, vcc
	ds_write2_b32 v24, v20, v21 offset1:1
	v_cndmask_b32_e32 v20, 0, v22, vcc
	v_cndmask_b32_e32 v21, 0, v23, vcc
	v_add_u32_e32 v22, 0x848, v53
	ds_write2_b32 v22, v20, v21 offset1:1
	v_or_b32_e32 v20, s82, v62
	v_cmp_gt_i32_e32 vcc, 64, v20
	v_add_u32_e32 v20, 0xc60, v53
	s_nop 0
	v_cndmask_b32_e32 v16, 0, v16, vcc
	v_cndmask_b32_e32 v17, 0, v17, vcc
	ds_write2_b32 v20, v16, v17 offset1:1
	v_cndmask_b32_e32 v16, 0, v18, vcc
	v_cndmask_b32_e32 v17, 0, v19, vcc
	v_add_u32_e32 v18, 0xc68, v53
	ds_write2_b32 v18, v16, v17 offset1:1
	v_or_b32_e32 v16, s82, v64
	v_cmp_gt_i32_e32 vcc, 64, v16
	v_add_u32_e32 v16, 0x1080, v53
	s_nop 0
	v_cndmask_b32_e32 v12, 0, v12, vcc
	v_cndmask_b32_e32 v13, 0, v13, vcc
	ds_write2_b32 v16, v12, v13 offset1:1
	v_cndmask_b32_e32 v12, 0, v14, vcc
	v_cndmask_b32_e32 v13, 0, v15, vcc
	v_add_u32_e32 v14, 0x1088, v53
	ds_write2_b32 v14, v12, v13 offset1:1
	v_or_b32_e32 v12, s82, v66
	v_cmp_gt_i32_e32 vcc, 64, v12
	v_add_u32_e32 v12, 0x14a0, v53
	s_nop 0
	v_cndmask_b32_e32 v8, 0, v8, vcc
	v_cndmask_b32_e32 v9, 0, v9, vcc
	ds_write2_b32 v12, v8, v9 offset1:1
	v_cndmask_b32_e32 v8, 0, v10, vcc
	v_cndmask_b32_e32 v9, 0, v11, vcc
	v_add_u32_e32 v10, v35, v67
	ds_write2_b32 v10, v8, v9 offset0:2 offset1:3
	v_or_b32_e32 v8, s82, v68
	v_cmp_gt_i32_e32 vcc, 64, v8
	v_add_u32_e32 v8, 0x420, v10
	s_nop 0
	v_cndmask_b32_e32 v4, 0, v4, vcc
	v_cndmask_b32_e32 v5, 0, v5, vcc
	ds_write2_b32 v8, v4, v5 offset1:1
	v_cndmask_b32_e32 v4, 0, v6, vcc
	v_cndmask_b32_e32 v5, 0, v7, vcc
	v_add_u32_e32 v6, 0x428, v10
	ds_write2_b32 v6, v4, v5 offset1:1
	v_or_b32_e32 v4, s82, v69
	v_cmp_gt_i32_e32 vcc, 64, v4
	v_add_u32_e32 v4, 0x840, v10
	v_add_u32_e32 v8, s38, v32
	v_cndmask_b32_e32 v0, 0, v0, vcc
	v_cndmask_b32_e32 v1, 0, v1, vcc
	ds_write2_b32 v4, v0, v1 offset1:1
	v_cndmask_b32_e32 v0, 0, v2, vcc
	v_cndmask_b32_e32 v1, 0, v3, vcc
	v_add_u32_e32 v2, 0x848, v10
	ds_write2_b32 v2, v0, v1 offset1:1
	s_waitcnt lgkmcnt(0)
; __device__ __forceinline__ unsigned pk_bf16(float lo, float hi) { f32x2e v = {lo, hi}; bf16x2e b = __builtin_convertvector(v, bf16x2e); return __builtin_bit_cast(unsigned, b); }
; #define LAS __attribute__((address_space(3)))
; __device__ __forceinline__ void tr_item(const float* W, int Ksrc, int N, int k0, int n0, bf16* dst, int ldt, int drow0, int dcol0, LAS float* scr, int lane, const float* nscale = nullptr, const float* kscale = nullptr) {
;     ...
;     const int c = lane & 7;
; #pragma unroll
;     for (int j = 0; j < 4; ++j) { const int n = (lane >> 3) + 8 * j; const LAS float* s = scr + (8 * c) * 33 + n;
;         const float sc = nscale ? nscale[n0 + n] : 1.0f;
;         u32x4 o; o.x = pk_bf16(s[0 * 33] * sc, s[1 * 33] * sc); o.y = pk_bf16(s[2 * 33] * sc, s[3 * 33] * sc); o.z = pk_bf16(s[4 * 33] * sc, s[5 * 33] * sc); o.w = pk_bf16(s[6 * 33] * sc, s[7 * 33] * sc);
;         *(u32x4*)(dst + (size_t)(drow0 + n) * ldt + dcol0 + k0 + 8 * c) = o; }
;     asm volatile("s_waitcnt lgkmcnt(0)" ::: "memory");
	ds_read_b32 v0, v70
	ds_read_b32 v1, v70 offset:132
	v_lshl_add_u64 v[4:5], s[82:83], 1, v[56:57]
	s_waitcnt lgkmcnt(0)
	v_cvt_pk_bf16_f32 v0, v0, v1
	ds_read_b32 v1, v70 offset:264
	ds_read_b32 v2, v70 offset:396
	s_waitcnt lgkmcnt(0)
	v_cvt_pk_bf16_f32 v1, v1, v2
	ds_read_b32 v2, v70 offset:528
	ds_read_b32 v3, v70 offset:660
	s_waitcnt lgkmcnt(0)
	v_cvt_pk_bf16_f32 v2, v2, v3
	ds_read_b32 v3, v70 offset:792
	ds_read_b32 v6, v70 offset:924
	s_waitcnt lgkmcnt(0)
	v_cvt_pk_bf16_f32 v3, v3, v6
	v_add_u32_e32 v6, 0x400, v8
	v_mad_i64_i32 v[6:7], s[4:5], v6, s60, v[4:5]
	global_store_dwordx4 v[6:7], v[0:3], off offset:128
	ds_read_b32 v0, v70 offset:32
	ds_read_b32 v1, v70 offset:164
	s_waitcnt lgkmcnt(0)
	v_cvt_pk_bf16_f32 v0, v0, v1
	ds_read_b32 v1, v70 offset:296
	ds_read_b32 v2, v70 offset:428
	s_waitcnt lgkmcnt(0)
	v_cvt_pk_bf16_f32 v1, v1, v2
	ds_read_b32 v2, v70 offset:560
	ds_read_b32 v3, v70 offset:692
	s_waitcnt lgkmcnt(0)
	v_cvt_pk_bf16_f32 v2, v2, v3
	ds_read_b32 v3, v70 offset:824
	ds_read_b32 v6, v70 offset:956
	s_waitcnt lgkmcnt(0)
	v_cvt_pk_bf16_f32 v3, v3, v6
	v_add_u32_e32 v6, 0x408, v8
	v_mad_i64_i32 v[6:7], s[4:5], v6, s60, v[4:5]
	global_store_dwordx4 v[6:7], v[0:3], off offset:128
	ds_read_b32 v0, v70 offset:64
	ds_read_b32 v1, v70 offset:196
	s_waitcnt lgkmcnt(0)
	v_cvt_pk_bf16_f32 v0, v0, v1
	ds_read_b32 v1, v70 offset:328
	ds_read_b32 v2, v70 offset:460
	s_waitcnt lgkmcnt(0)
	v_cvt_pk_bf16_f32 v1, v1, v2
	ds_read_b32 v2, v70 offset:592
	ds_read_b32 v3, v70 offset:724
	s_waitcnt lgkmcnt(0)
	v_cvt_pk_bf16_f32 v2, v2, v3
	ds_read_b32 v3, v70 offset:856
	ds_read_b32 v6, v70 offset:988
	s_waitcnt lgkmcnt(0)
	v_cvt_pk_bf16_f32 v3, v3, v6
	v_add_u32_e32 v6, 0x410, v8
	v_mad_i64_i32 v[6:7], s[4:5], v6, s60, v[4:5]
	global_store_dwordx4 v[6:7], v[0:3], off offset:128
	ds_read_b32 v0, v70 offset:96
	ds_read_b32 v1, v70 offset:228
	s_waitcnt lgkmcnt(0)
	v_cvt_pk_bf16_f32 v0, v0, v1
	ds_read_b32 v1, v70 offset:360
	ds_read_b32 v2, v70 offset:492
	s_waitcnt lgkmcnt(0)
	v_cvt_pk_bf16_f32 v1, v1, v2
	ds_read_b32 v2, v70 offset:624
	ds_read_b32 v3, v70 offset:756
	s_waitcnt lgkmcnt(0)
	v_cvt_pk_bf16_f32 v2, v2, v3
	ds_read_b32 v3, v70 offset:888
	ds_read_b32 v6, v70 offset:1020
	s_waitcnt lgkmcnt(0)
	v_cvt_pk_bf16_f32 v3, v3, v6
	v_add_u32_e32 v6, 0x418, v8
	v_mad_i64_i32 v[4:5], s[4:5], v6, s60, v[4:5]
	global_store_dwordx4 v[4:5], v[0:3], off offset:128
	s_waitcnt lgkmcnt(0)
	s_cbranch_scc1 .LBB0_163

; #define LAS __attribute__((address_space(3)))
; __device__ __forceinline__ void tr_item(const float* W, int Ksrc, int N, int k0, int n0, bf16* dst, int ldt, int drow0, int dcol0, LAS float* scr, int lane, const float* nscale = nullptr, const float* kscale = nullptr) {
;     ...
;     for (int i = 0; i < 8; ++i) { const int kk = 8 * i + kr_; const int kr = (k0 + kk < Ksrc) ? (k0 + kk) : (Ksrc - 1); tv[i] = __builtin_nontemporal_load((const f32x4*)(W + (size_t)kr * N + n0 + 4 * nq_)); }
; #pragma unroll
;     for (int i = 0; i < 8; ++i) { const int kk = 8 * i + kr_; const bool ok = (k0 + kk < Ksrc); LAS float* d_ = scr + kk * 33 + 4 * nq_;
;         const float ks_ = (ok && kscale) ? kscale[k0 + kk] : 1.0f;
;         d_[0] = ok ? tv[i].x * ks_ : 0.f; d_[1] = ok ? tv[i].y * ks_ : 0.f; d_[2] = ok ? tv[i].z * ks_ : 0.f; d_[3] = ok ? tv[i].w * ks_ : 0.f; }
;     asm volatile("s_waitcnt lgkmcnt(0)" ::: "memory");
.LBB0_166:
	s_ashr_i32 s2, s1, 31
	s_lshr_b32 s2, s2, 27
	s_add_i32 s2, s1, s2
	s_ashr_i32 s2, s2, 5
	s_lshl_b32 s40, s2, 6
	s_lshl_b32 s4, s2, 10
	v_or_b32_e32 v56, s40, v32
	s_sub_i32 s38, s0, s4
	v_min_i32_e32 v2, 0x9f, v56
	s_ashr_i32 s39, s38, 31
	v_ashrrev_i32_e32 v3, 31, v2
	v_lshl_add_u64 v[0:1], s[38:39], 2, v[54:55]
	v_lshlrev_b64 v[2:3], 12, v[2:3]
	v_lshl_add_u64 v[2:3], v[0:1], 0, v[2:3]
	global_load_dwordx4 v[28:31], v[2:3], off nt
	v_or_b32_e32 v2, 8, v56
	v_min_i32_e32 v2, 0x9f, v2
	v_ashrrev_i32_e32 v3, 31, v2
	v_lshlrev_b64 v[2:3], 12, v[2:3]
	v_lshl_add_u64 v[2:3], v[0:1], 0, v[2:3]
	global_load_dwordx4 v[24:27], v[2:3], off nt
	v_or_b32_e32 v2, 16, v56
	v_min_i32_e32 v2, 0x9f, v2
	v_ashrrev_i32_e32 v3, 31, v2
	v_lshlrev_b64 v[2:3], 12, v[2:3]
	v_lshl_add_u64 v[2:3], v[0:1], 0, v[2:3]
	global_load_dwordx4 v[20:23], v[2:3], off nt
	v_or_b32_e32 v2, 24, v56
	v_min_i32_e32 v2, 0x9f, v2
	v_ashrrev_i32_e32 v3, 31, v2
	v_lshlrev_b64 v[2:3], 12, v[2:3]
	v_lshl_add_u64 v[2:3], v[0:1], 0, v[2:3]
	global_load_dwordx4 v[16:19], v[2:3], off nt
	v_or_b32_e32 v2, 32, v56
	v_min_i32_e32 v2, 0x9f, v2
	v_ashrrev_i32_e32 v3, 31, v2
	v_lshlrev_b64 v[2:3], 12, v[2:3]
	v_lshl_add_u64 v[2:3], v[0:1], 0, v[2:3]
	global_load_dwordx4 v[12:15], v[2:3], off nt
	v_or_b32_e32 v2, 40, v56
	v_min_i32_e32 v2, 0x9f, v2
	v_ashrrev_i32_e32 v3, 31, v2
	v_lshlrev_b64 v[2:3], 12, v[2:3]
	v_lshl_add_u64 v[2:3], v[0:1], 0, v[2:3]
	global_load_dwordx4 v[8:11], v[2:3], off nt
	v_or_b32_e32 v2, 48, v56
	v_min_i32_e32 v2, 0x9f, v2
	v_ashrrev_i32_e32 v3, 31, v2
	v_lshlrev_b64 v[2:3], 12, v[2:3]
	v_lshl_add_u64 v[2:3], v[0:1], 0, v[2:3]
	global_load_dwordx4 v[4:7], v[2:3], off nt
	v_or_b32_e32 v2, 56, v56
	v_min_i32_e32 v2, 0x9f, v2
	v_ashrrev_i32_e32 v3, 31, v2
	v_lshlrev_b64 v[2:3], 12, v[2:3]
	v_lshl_add_u64 v[0:1], v[0:1], 0, v[2:3]
	global_load_dwordx4 v[0:3], v[0:1], off nt
	v_cmp_gt_i32_e32 vcc, s71, v56
	v_add_u32_e32 v56, v35, v37
	s_ashr_i32 s41, s40, 31
	s_add_i32 s1, s1, s16
	s_add_i32 s0, s0, s27
	s_cmpk_lt_i32 s1, 0x60
	s_waitcnt vmcnt(0) lgkmcnt(0)
	v_cndmask_b32_e32 v28, 0, v28, vcc
	v_cndmask_b32_e32 v29, 0, v29, vcc
	ds_write2_b32 v56, v28, v29 offset1:1
	v_cndmask_b32_e32 v28, 0, v30, vcc
	v_cndmask_b32_e32 v29, 0, v31, vcc
	ds_write2_b32 v56, v28, v29 offset0:2 offset1:3
	v_or_b32_e32 v28, s40, v58
	v_cmp_gt_i32_e32 vcc, s71, v28
	v_add_u32_e32 v28, 0x420, v56
	s_nop 0
	v_cndmask_b32_e32 v24, 0, v24, vcc
	v_cndmask_b32_e32 v25, 0, v25, vcc
	ds_write2_b32 v28, v24, v25 offset1:1
	v_cndmask_b32_e32 v24, 0, v26, vcc
	v_cndmask_b32_e32 v25, 0, v27, vcc
	v_add_u32_e32 v26, 0x428, v56
	ds_write2_b32 v26, v24, v25 offset1:1
	v_or_b32_e32 v24, s40, v60
	v_cmp_gt_i32_e32 vcc, s71, v24
	v_add_u32_e32 v24, 0x840, v56
	s_nop 0
	v_cndmask_b32_e32 v20, 0, v20, vcc
	v_cndmask_b32_e32 v21, 0, v21, vcc
	ds_write2_b32 v24, v20, v21 offset1:1
	v_cndmask_b32_e32 v20, 0, v22, vcc
	v_cndmask_b32_e32 v21, 0, v23, vcc
	v_add_u32_e32 v22, 0x848, v56
	ds_write2_b32 v22, v20, v21 offset1:1
	v_or_b32_e32 v20, s40, v62
	v_cmp_gt_i32_e32 vcc, s71, v20
	v_add_u32_e32 v20, 0xc60, v56
	s_nop 0
	v_cndmask_b32_e32 v16, 0, v16, vcc
	v_cndmask_b32_e32 v17, 0, v17, vcc
	ds_write2_b32 v20, v16, v17 offset1:1
	v_cndmask_b32_e32 v16, 0, v18, vcc
	v_cndmask_b32_e32 v17, 0, v19, vcc
	v_add_u32_e32 v18, 0xc68, v56
	ds_write2_b32 v18, v16, v17 offset1:1
	v_or_b32_e32 v16, s40, v64
	v_cmp_gt_i32_e32 vcc, s71, v16
	v_add_u32_e32 v16, 0x1080, v56
	s_nop 0
	v_cndmask_b32_e32 v12, 0, v12, vcc
	v_cndmask_b32_e32 v13, 0, v13, vcc
	ds_write2_b32 v16, v12, v13 offset1:1
	v_cndmask_b32_e32 v12, 0, v14, vcc
	v_cndmask_b32_e32 v13, 0, v15, vcc
	v_add_u32_e32 v14, 0x1088, v56
	ds_write2_b32 v14, v12, v13 offset1:1
	v_or_b32_e32 v12, s40, v66
	v_cmp_gt_i32_e32 vcc, s71, v12
	v_add_u32_e32 v12, 0x14a0, v56
	s_nop 0
	v_cndmask_b32_e32 v8, 0, v8, vcc
	v_cndmask_b32_e32 v9, 0, v9, vcc
	ds_write2_b32 v12, v8, v9 offset1:1
	v_cndmask_b32_e32 v8, 0, v10, vcc
	v_cndmask_b32_e32 v9, 0, v11, vcc
	v_add_u32_e32 v10, v35, v67
	ds_write2_b32 v10, v8, v9 offset0:2 offset1:3
	v_or_b32_e32 v8, s40, v68
	v_cmp_gt_i32_e32 vcc, s71, v8
	v_add_u32_e32 v8, 0x420, v10
	s_nop 0
	v_cndmask_b32_e32 v4, 0, v4, vcc
	v_cndmask_b32_e32 v5, 0, v5, vcc
	ds_write2_b32 v8, v4, v5 offset1:1
	v_cndmask_b32_e32 v4, 0, v6, vcc
	v_cndmask_b32_e32 v5, 0, v7, vcc
	v_add_u32_e32 v6, 0x428, v10
	ds_write2_b32 v6, v4, v5 offset1:1
	v_or_b32_e32 v4, s40, v69
	v_cmp_gt_i32_e32 vcc, s71, v4
	v_add_u32_e32 v4, 0x840, v10
	v_add_u32_e32 v8, s38, v32
	v_cndmask_b32_e32 v0, 0, v0, vcc
	v_cndmask_b32_e32 v1, 0, v1, vcc
	ds_write2_b32 v4, v0, v1 offset1:1
	v_cndmask_b32_e32 v0, 0, v2, vcc
	v_cndmask_b32_e32 v1, 0, v3, vcc
	v_add_u32_e32 v2, 0x848, v10
	ds_write2_b32 v2, v0, v1 offset1:1
	s_waitcnt lgkmcnt(0)
; __device__ __forceinline__ unsigned pk_bf16(float lo, float hi) { f32x2e v = {lo, hi}; bf16x2e b = __builtin_convertvector(v, bf16x2e); return __builtin_bit_cast(unsigned, b); }
; #define LAS __attribute__((address_space(3)))
; __device__ __forceinline__ void tr_item(const float* W, int Ksrc, int N, int k0, int n0, bf16* dst, int ldt, int drow0, int dcol0, LAS float* scr, int lane, const float* nscale = nullptr, const float* kscale = nullptr) {
;     ...
;     const int c = lane & 7;
; #pragma unroll
;     for (int j = 0; j < 4; ++j) { const int n = (lane >> 3) + 8 * j; const LAS float* s = scr + (8 * c) * 33 + n;
;         const float sc = nscale ? nscale[n0 + n] : 1.0f;
;         u32x4 o; o.x = pk_bf16(s[0 * 33] * sc, s[1 * 33] * sc); o.y = pk_bf16(s[2 * 33] * sc, s[3 * 33] * sc); o.z = pk_bf16(s[4 * 33] * sc, s[5 * 33] * sc); o.w = pk_bf16(s[6 * 33] * sc, s[7 * 33] * sc);
;         *(u32x4*)(dst + (size_t)(drow0 + n) * ldt + dcol0 + k0 + 8 * c) = o; }
;     asm volatile("s_waitcnt lgkmcnt(0)" ::: "memory");
	ds_read_b32 v0, v70
	ds_read_b32 v1, v70 offset:132
	v_lshl_add_u64 v[4:5], s[40:41], 1, v[52:53]
	s_waitcnt lgkmcnt(0)
	v_cvt_pk_bf16_f32 v0, v0, v1
	ds_read_b32 v1, v70 offset:264
	ds_read_b32 v2, v70 offset:396
	s_waitcnt lgkmcnt(0)
	v_cvt_pk_bf16_f32 v1, v1, v2
	ds_read_b32 v2, v70 offset:528
	ds_read_b32 v3, v70 offset:660
	s_waitcnt lgkmcnt(0)
	v_cvt_pk_bf16_f32 v2, v2, v3
	ds_read_b32 v3, v70 offset:792
	ds_read_b32 v6, v70 offset:924
	s_waitcnt lgkmcnt(0)
	v_cvt_pk_bf16_f32 v3, v3, v6
	v_add_u32_e32 v6, 0x800, v8
	v_mad_i64_i32 v[6:7], s[4:5], v6, s60, v[4:5]
	global_store_dwordx4 v[6:7], v[0:3], off offset:256
	ds_read_b32 v0, v70 offset:32
	ds_read_b32 v1, v70 offset:164
	s_waitcnt lgkmcnt(0)
	v_cvt_pk_bf16_f32 v0, v0, v1
	ds_read_b32 v1, v70 offset:296
	ds_read_b32 v2, v70 offset:428
	s_waitcnt lgkmcnt(0)
	v_cvt_pk_bf16_f32 v1, v1, v2
	ds_read_b32 v2, v70 offset:560
	ds_read_b32 v3, v70 offset:692
	s_waitcnt lgkmcnt(0)
	v_cvt_pk_bf16_f32 v2, v2, v3
	ds_read_b32 v3, v70 offset:824
	ds_read_b32 v6, v70 offset:956
	s_waitcnt lgkmcnt(0)
	v_cvt_pk_bf16_f32 v3, v3, v6
	v_add_u32_e32 v6, 0x808, v8
	v_mad_i64_i32 v[6:7], s[4:5], v6, s60, v[4:5]
	global_store_dwordx4 v[6:7], v[0:3], off offset:256
	ds_read_b32 v0, v70 offset:64
	ds_read_b32 v1, v70 offset:196
	s_waitcnt lgkmcnt(0)
	v_cvt_pk_bf16_f32 v0, v0, v1
	ds_read_b32 v1, v70 offset:328
	ds_read_b32 v2, v70 offset:460
	s_waitcnt lgkmcnt(0)
	v_cvt_pk_bf16_f32 v1, v1, v2
	ds_read_b32 v2, v70 offset:592
	ds_read_b32 v3, v70 offset:724
	s_waitcnt lgkmcnt(0)
	v_cvt_pk_bf16_f32 v2, v2, v3
	ds_read_b32 v3, v70 offset:856
	ds_read_b32 v6, v70 offset:988
	s_waitcnt lgkmcnt(0)
	v_cvt_pk_bf16_f32 v3, v3, v6
	v_add_u32_e32 v6, 0x810, v8
	v_mad_i64_i32 v[6:7], s[4:5], v6, s60, v[4:5]
	global_store_dwordx4 v[6:7], v[0:3], off offset:256
	ds_read_b32 v0, v70 offset:96
	ds_read_b32 v1, v70 offset:228
	s_waitcnt lgkmcnt(0)
	v_cvt_pk_bf16_f32 v0, v0, v1
	ds_read_b32 v1, v70 offset:360
	ds_read_b32 v2, v70 offset:492
	s_waitcnt lgkmcnt(0)
	v_cvt_pk_bf16_f32 v1, v1, v2
	ds_read_b32 v2, v70 offset:624
	ds_read_b32 v3, v70 offset:756
	s_waitcnt lgkmcnt(0)
	v_cvt_pk_bf16_f32 v2, v2, v3
	ds_read_b32 v3, v70 offset:888
	ds_read_b32 v6, v70 offset:1020
	s_waitcnt lgkmcnt(0)
	v_cvt_pk_bf16_f32 v3, v3, v6
	v_add_u32_e32 v6, 0x818, v8
	v_mad_i64_i32 v[4:5], s[4:5], v6, s60, v[4:5]
	global_store_dwordx4 v[4:5], v[0:3], off offset:256
	s_waitcnt lgkmcnt(0)
	s_cbranch_scc1 .LBB0_166

; #define LAS __attribute__((address_space(3)))
; __device__ __forceinline__ void tr_item(const float* W, int Ksrc, int N, int k0, int n0, bf16* dst, int ldt, int drow0, int dcol0, LAS float* scr, int lane, const float* nscale = nullptr, const float* kscale = nullptr) {
;     ...
;     for (int i = 0; i < 8; ++i) { const int kk = 8 * i + kr_; const int kr = (k0 + kk < Ksrc) ? (k0 + kk) : (Ksrc - 1); tv[i] = __builtin_nontemporal_load((const f32x4*)(W + (size_t)kr * N + n0 + 4 * nq_)); }
; #pragma unroll
;     for (int i = 0; i < 8; ++i) { const int kk = 8 * i + kr_; const bool ok = (k0 + kk < Ksrc); LAS float* d_ = scr + kk * 33 + 4 * nq_;
;         const float ks_ = (ok && kscale) ? kscale[k0 + kk] : 1.0f;
;         d_[0] = ok ? tv[i].x * ks_ : 0.f; d_[1] = ok ? tv[i].y * ks_ : 0.f; d_[2] = ok ? tv[i].z * ks_ : 0.f; d_[3] = ok ? tv[i].w * ks_ : 0.f; }
;     asm volatile("s_waitcnt lgkmcnt(0)" ::: "memory");
.LBB0_169:
	s_ashr_i32 s2, s1, 31
	s_lshr_b32 s2, s2, 26
	s_add_i32 s2, s1, s2
	s_lshl_b32 s4, s2, 5
	s_and_b32 s86, s2, 0xffffffc0
	s_and_b32 s4, s4, 0xfffff800
	v_or_b32_e32 v56, s86, v32
	s_sub_i32 s40, s0, s4
	v_min_i32_e32 v2, 0x7ff, v56
	s_ashr_i32 s41, s40, 31
	v_ashrrev_i32_e32 v3, 31, v2
	v_lshl_add_u64 v[0:1], s[40:41], 2, v[52:53]
	v_lshlrev_b64 v[2:3], 13, v[2:3]
	v_lshl_add_u64 v[2:3], v[0:1], 0, v[2:3]
	global_load_dwordx4 v[28:31], v[2:3], off nt
	v_or_b32_e32 v2, 8, v56
	v_min_i32_e32 v2, 0x7ff, v2
	v_ashrrev_i32_e32 v3, 31, v2
	v_lshlrev_b64 v[2:3], 13, v[2:3]
	v_lshl_add_u64 v[2:3], v[0:1], 0, v[2:3]
	global_load_dwordx4 v[24:27], v[2:3], off nt
	v_or_b32_e32 v2, 16, v56
	v_min_i32_e32 v2, 0x7ff, v2
	v_ashrrev_i32_e32 v3, 31, v2
	v_lshlrev_b64 v[2:3], 13, v[2:3]
	v_lshl_add_u64 v[2:3], v[0:1], 0, v[2:3]
	global_load_dwordx4 v[20:23], v[2:3], off nt
	v_or_b32_e32 v2, 24, v56
	v_min_i32_e32 v2, 0x7ff, v2
	v_ashrrev_i32_e32 v3, 31, v2
	v_lshlrev_b64 v[2:3], 13, v[2:3]
	v_lshl_add_u64 v[2:3], v[0:1], 0, v[2:3]
	global_load_dwordx4 v[16:19], v[2:3], off nt
	v_or_b32_e32 v2, 32, v56
	v_min_i32_e32 v2, 0x7ff, v2
	v_ashrrev_i32_e32 v3, 31, v2
	v_lshlrev_b64 v[2:3], 13, v[2:3]
	v_lshl_add_u64 v[2:3], v[0:1], 0, v[2:3]
	global_load_dwordx4 v[12:15], v[2:3], off nt
	v_or_b32_e32 v2, 40, v56
	v_min_i32_e32 v2, 0x7ff, v2
	v_ashrrev_i32_e32 v3, 31, v2
	v_lshlrev_b64 v[2:3], 13, v[2:3]
	v_lshl_add_u64 v[2:3], v[0:1], 0, v[2:3]
	global_load_dwordx4 v[8:11], v[2:3], off nt
	v_or_b32_e32 v2, 48, v56
	v_min_i32_e32 v2, 0x7ff, v2
	v_ashrrev_i32_e32 v3, 31, v2
	v_lshlrev_b64 v[2:3], 13, v[2:3]
	v_lshl_add_u64 v[2:3], v[0:1], 0, v[2:3]
	global_load_dwordx4 v[4:7], v[2:3], off nt
	v_or_b32_e32 v2, 56, v56
	v_min_i32_e32 v2, 0x7ff, v2
	v_ashrrev_i32_e32 v3, 31, v2
	v_lshlrev_b64 v[2:3], 13, v[2:3]
	v_lshl_add_u64 v[0:1], v[0:1], 0, v[2:3]
	global_load_dwordx4 v[0:3], v[0:1], off nt
	v_cmp_gt_i32_e32 vcc, s61, v56
	v_add_u32_e32 v56, v35, v37
	s_ashr_i32 s87, s86, 31
	s_add_i32 s1, s1, s16
	s_add_i32 s0, s0, s27
	s_cmpk_lt_i32 s1, 0x800
	s_waitcnt vmcnt(0) lgkmcnt(0)
	v_cndmask_b32_e32 v28, 0, v28, vcc
	v_cndmask_b32_e32 v29, 0, v29, vcc
	ds_write2_b32 v56, v28, v29 offset1:1
	v_cndmask_b32_e32 v28, 0, v30, vcc
	v_cndmask_b32_e32 v29, 0, v31, vcc
	ds_write2_b32 v56, v28, v29 offset0:2 offset1:3
	v_or_b32_e32 v28, s86, v58
	v_cmp_gt_i32_e32 vcc, s61, v28
	v_add_u32_e32 v28, 0x420, v56
	s_nop 0
	v_cndmask_b32_e32 v24, 0, v24, vcc
	v_cndmask_b32_e32 v25, 0, v25, vcc
	ds_write2_b32 v28, v24, v25 offset1:1
	v_cndmask_b32_e32 v24, 0, v26, vcc
	v_cndmask_b32_e32 v25, 0, v27, vcc
	v_add_u32_e32 v26, 0x428, v56
	ds_write2_b32 v26, v24, v25 offset1:1
	v_or_b32_e32 v24, s86, v60
	v_cmp_gt_i32_e32 vcc, s61, v24
	v_add_u32_e32 v24, 0x840, v56
	s_nop 0
	v_cndmask_b32_e32 v20, 0, v20, vcc
	v_cndmask_b32_e32 v21, 0, v21, vcc
	ds_write2_b32 v24, v20, v21 offset1:1
	v_cndmask_b32_e32 v20, 0, v22, vcc
	v_cndmask_b32_e32 v21, 0, v23, vcc
	v_add_u32_e32 v22, 0x848, v56
	ds_write2_b32 v22, v20, v21 offset1:1
	v_or_b32_e32 v20, s86, v62
	v_cmp_gt_i32_e32 vcc, s61, v20
	v_add_u32_e32 v20, 0xc60, v56
	s_nop 0
	v_cndmask_b32_e32 v16, 0, v16, vcc
	v_cndmask_b32_e32 v17, 0, v17, vcc
	ds_write2_b32 v20, v16, v17 offset1:1
	v_cndmask_b32_e32 v16, 0, v18, vcc
	v_cndmask_b32_e32 v17, 0, v19, vcc
	v_add_u32_e32 v18, 0xc68, v56
	ds_write2_b32 v18, v16, v17 offset1:1
	v_or_b32_e32 v16, s86, v64
	v_cmp_gt_i32_e32 vcc, s61, v16
	v_add_u32_e32 v16, 0x1080, v56
	s_nop 0
	v_cndmask_b32_e32 v12, 0, v12, vcc
	v_cndmask_b32_e32 v13, 0, v13, vcc
	ds_write2_b32 v16, v12, v13 offset1:1
	v_cndmask_b32_e32 v12, 0, v14, vcc
	v_cndmask_b32_e32 v13, 0, v15, vcc
	v_add_u32_e32 v14, 0x1088, v56
	ds_write2_b32 v14, v12, v13 offset1:1
	v_or_b32_e32 v12, s86, v66
	v_cmp_gt_i32_e32 vcc, s61, v12
	v_add_u32_e32 v12, 0x14a0, v56
	s_nop 0
	v_cndmask_b32_e32 v8, 0, v8, vcc
	v_cndmask_b32_e32 v9, 0, v9, vcc
	ds_write2_b32 v12, v8, v9 offset1:1
	v_cndmask_b32_e32 v8, 0, v10, vcc
	v_cndmask_b32_e32 v9, 0, v11, vcc
	v_add_u32_e32 v10, v35, v67
	ds_write2_b32 v10, v8, v9 offset0:2 offset1:3
	v_or_b32_e32 v8, s86, v68
	v_cmp_gt_i32_e32 vcc, s61, v8
	v_add_u32_e32 v8, 0x420, v10
	s_nop 0
	v_cndmask_b32_e32 v4, 0, v4, vcc
	v_cndmask_b32_e32 v5, 0, v5, vcc
	ds_write2_b32 v8, v4, v5 offset1:1
	v_cndmask_b32_e32 v4, 0, v6, vcc
	v_cndmask_b32_e32 v5, 0, v7, vcc
	v_add_u32_e32 v6, 0x428, v10
	ds_write2_b32 v6, v4, v5 offset1:1
	v_or_b32_e32 v4, s86, v69
	v_cmp_gt_i32_e32 vcc, s61, v4
	v_add_u32_e32 v4, 0x840, v10
	s_nop 0
	v_cndmask_b32_e32 v0, 0, v0, vcc
	v_cndmask_b32_e32 v1, 0, v1, vcc
	ds_write2_b32 v4, v0, v1 offset1:1
	v_cndmask_b32_e32 v0, 0, v2, vcc
	v_cndmask_b32_e32 v1, 0, v3, vcc
	v_add_u32_e32 v2, 0x848, v10
	ds_write2_b32 v2, v0, v1 offset1:1
	s_waitcnt lgkmcnt(0)
; __device__ __forceinline__ unsigned pk_bf16(float lo, float hi) { f32x2e v = {lo, hi}; bf16x2e b = __builtin_convertvector(v, bf16x2e); return __builtin_bit_cast(unsigned, b); }
; #define LAS __attribute__((address_space(3)))
; __device__ __forceinline__ void tr_item(const float* W, int Ksrc, int N, int k0, int n0, bf16* dst, int ldt, int drow0, int dcol0, LAS float* scr, int lane, const float* nscale = nullptr, const float* kscale = nullptr) {
;     ...
;     const int c = lane & 7;
; #pragma unroll
;     for (int j = 0; j < 4; ++j) { const int n = (lane >> 3) + 8 * j; const LAS float* s = scr + (8 * c) * 33 + n;
;         const float sc = nscale ? nscale[n0 + n] : 1.0f;
;         u32x4 o; o.x = pk_bf16(s[0 * 33] * sc, s[1 * 33] * sc); o.y = pk_bf16(s[2 * 33] * sc, s[3 * 33] * sc); o.z = pk_bf16(s[4 * 33] * sc, s[5 * 33] * sc); o.w = pk_bf16(s[6 * 33] * sc, s[7 * 33] * sc);
;         *(u32x4*)(dst + (size_t)(drow0 + n) * ldt + dcol0 + k0 + 8 * c) = o; }
;     asm volatile("s_waitcnt lgkmcnt(0)" ::: "memory");
	ds_read_b32 v0, v70
	ds_read_b32 v1, v70 offset:132
	v_lshl_add_u64 v[4:5], s[86:87], 1, v[54:55]
	s_waitcnt lgkmcnt(0)
	v_cvt_pk_bf16_f32 v0, v0, v1
	ds_read_b32 v1, v70 offset:264
	ds_read_b32 v2, v70 offset:396
	s_waitcnt lgkmcnt(0)
	v_cvt_pk_bf16_f32 v1, v1, v2
	ds_read_b32 v2, v70 offset:528
	ds_read_b32 v3, v70 offset:660
	s_waitcnt lgkmcnt(0)
	v_cvt_pk_bf16_f32 v2, v2, v3
	ds_read_b32 v3, v70 offset:792
	ds_read_b32 v6, v70 offset:924
	s_waitcnt lgkmcnt(0)
	v_cvt_pk_bf16_f32 v3, v3, v6
	v_add_u32_e32 v6, s40, v32
	v_ashrrev_i32_e32 v7, 31, v6
	v_lshlrev_b64 v[8:9], 12, v[6:7]
	v_lshl_add_u64 v[8:9], v[4:5], 0, v[8:9]
	global_store_dwordx4 v[8:9], v[0:3], off
	ds_read_b32 v0, v70 offset:32
	ds_read_b32 v1, v70 offset:164
	v_add_u32_e32 v8, 8, v6
	v_ashrrev_i32_e32 v9, 31, v8
	v_lshlrev_b64 v[8:9], 12, v[8:9]
	v_lshl_add_u64 v[8:9], v[4:5], 0, v[8:9]
	s_waitcnt lgkmcnt(0)
	v_cvt_pk_bf16_f32 v0, v0, v1
	ds_read_b32 v1, v70 offset:296
	ds_read_b32 v2, v70 offset:428
	s_waitcnt lgkmcnt(0)
	v_cvt_pk_bf16_f32 v1, v1, v2
	ds_read_b32 v2, v70 offset:560
	ds_read_b32 v3, v70 offset:692
	s_waitcnt lgkmcnt(0)
	v_cvt_pk_bf16_f32 v2, v2, v3
	ds_read_b32 v3, v70 offset:824
	ds_read_b32 v7, v70 offset:956
	s_waitcnt lgkmcnt(0)
	v_cvt_pk_bf16_f32 v3, v3, v7
	global_store_dwordx4 v[8:9], v[0:3], off
	ds_read_b32 v0, v70 offset:64
	ds_read_b32 v1, v70 offset:196
	v_add_u32_e32 v8, 16, v6
	v_ashrrev_i32_e32 v9, 31, v8
	v_lshlrev_b64 v[8:9], 12, v[8:9]
	v_lshl_add_u64 v[8:9], v[4:5], 0, v[8:9]
	s_waitcnt lgkmcnt(0)
	v_cvt_pk_bf16_f32 v0, v0, v1
	ds_read_b32 v1, v70 offset:328
	ds_read_b32 v2, v70 offset:460
	v_add_u32_e32 v6, 24, v6
	s_waitcnt lgkmcnt(0)
	v_cvt_pk_bf16_f32 v1, v1, v2
	ds_read_b32 v2, v70 offset:592
	ds_read_b32 v3, v70 offset:724
	s_waitcnt lgkmcnt(0)
	v_cvt_pk_bf16_f32 v2, v2, v3
	ds_read_b32 v3, v70 offset:856
	ds_read_b32 v7, v70 offset:988
	s_waitcnt lgkmcnt(0)
	v_cvt_pk_bf16_f32 v3, v3, v7
	global_store_dwordx4 v[8:9], v[0:3], off
	ds_read_b32 v0, v70 offset:96
	ds_read_b32 v1, v70 offset:228
	s_waitcnt lgkmcnt(0)
	v_cvt_pk_bf16_f32 v0, v0, v1
	ds_read_b32 v1, v70 offset:360
	ds_read_b32 v2, v70 offset:492
	s_waitcnt lgkmcnt(0)
	v_cvt_pk_bf16_f32 v1, v1, v2
	ds_read_b32 v2, v70 offset:624
	ds_read_b32 v3, v70 offset:756
	s_waitcnt lgkmcnt(0)
	v_cvt_pk_bf16_f32 v2, v2, v3
	ds_read_b32 v3, v70 offset:888
	ds_read_b32 v7, v70 offset:1020
	s_waitcnt lgkmcnt(0)
	v_cvt_pk_bf16_f32 v3, v3, v7
	v_ashrrev_i32_e32 v7, 31, v6
	v_lshlrev_b64 v[6:7], 12, v[6:7]
	v_lshl_add_u64 v[4:5], v[4:5], 0, v[6:7]
	global_store_dwordx4 v[4:5], v[0:3], off
	s_waitcnt lgkmcnt(0)
	s_cbranch_scc1 .LBB0_169

; __device__ __forceinline__ unsigned pk_bf16(float lo, float hi) { f32x2e v = {lo, hi}; bf16x2e b = __builtin_convertvector(v, bf16x2e); return __builtin_bit_cast(unsigned, b); }
; #define LAS __attribute__((address_space(3)))
; __device__ __forceinline__ void tr_item(const float* W, int Ksrc, int N, int k0, int n0, bf16* dst, int ldt, int drow0, int dcol0, LAS float* scr, int lane, const float* nscale = nullptr, const float* kscale = nullptr) {
;     f32x4 tv[8]; const int kr_ = lane >> 3, nq_ = lane & 7;
; #pragma unroll
;     for (int i = 0; i < 8; ++i) { const int kk = 8 * i + kr_; const int kr = (k0 + kk < Ksrc) ? (k0 + kk) : (Ksrc - 1); tv[i] = __builtin_nontemporal_load((const f32x4*)(W + (size_t)kr * N + n0 + 4 * nq_)); }
; #pragma unroll
;     for (int i = 0; i < 8; ++i) { const int kk = 8 * i + kr_; const bool ok = (k0 + kk < Ksrc); LAS float* d_ = scr + kk * 33 + 4 * nq_;
;         const float ks_ = (ok && kscale) ? kscale[k0 + kk] : 1.0f;
;         d_[0] = ok ? tv[i].x * ks_ : 0.f; d_[1] = ok ? tv[i].y * ks_ : 0.f; d_[2] = ok ? tv[i].z * ks_ : 0.f; d_[3] = ok ? tv[i].w * ks_ : 0.f; }
;     asm volatile("s_waitcnt lgkmcnt(0)" ::: "memory");
;     const int c = lane & 7;
; #pragma unroll
;     for (int j = 0; j < 4; ++j) { const int n = (lane >> 3) + 8 * j; const LAS float* s = scr + (8 * c) * 33 + n;
;         const float sc = nscale ? nscale[n0 + n] : 1.0f;
;         u32x4 o; o.x = pk_bf16(s[0 * 33] * sc, s[1 * 33] * sc); o.y = pk_bf16(s[2 * 33] * sc, s[3 * 33] * sc); o.z = pk_bf16(s[4 * 33] * sc, s[5 * 33] * sc); o.w = pk_bf16(s[6 * 33] * sc, s[7 * 33] * sc);
;         *(u32x4*)(dst + (size_t)(drow0 + n) * ldt + dcol0 + k0 + 8 * c) = o; }
;     asm volatile("s_waitcnt lgkmcnt(0)" ::: "memory");
; }
.LBB0_172:
	s_or_b64 exec, exec, s[0:1]
	s_waitcnt vmcnt(0) lgkmcnt(0)
	v_mul_f32_e32 v0, v0, v6
	v_mul_f32_e32 v1, v1, v6
	v_cndmask_b32_e32 v0, 0, v0, vcc
	v_cndmask_b32_e32 v1, 0, v1, vcc
	v_add_u32_e32 v7, 0x840, v8
	ds_write2_b32 v7, v0, v1 offset1:1
	v_mul_f32_e32 v0, v2, v6
	v_mul_f32_e32 v1, v3, v6
	v_cndmask_b32_e32 v0, 0, v0, vcc
	v_cndmask_b32_e32 v1, 0, v1, vcc
	v_add_u32_e32 v2, 0x848, v8
	ds_write2_b32 v2, v0, v1 offset1:1
	s_waitcnt lgkmcnt(0)
	ds_read_b32 v0, v70
	ds_read_b32 v1, v70 offset:132
	ds_read_b32 v2, v70 offset:264
	ds_read_b32 v3, v70 offset:396
	ds_read_b32 v6, v70 offset:528
	ds_read_b32 v7, v70 offset:660
	ds_read_b32 v8, v70 offset:792
	ds_read_b32 v9, v70 offset:924
	s_waitcnt lgkmcnt(6)
	v_cvt_pk_bf16_f32 v0, v0, v1
	s_waitcnt lgkmcnt(4)
	v_cvt_pk_bf16_f32 v1, v2, v3
	s_waitcnt lgkmcnt(2)
	v_cvt_pk_bf16_f32 v2, v6, v7
	v_add_u32_e32 v6, s94, v32
	v_ashrrev_i32_e32 v7, 31, v6
	v_lshl_add_u64 v[4:5], v[4:5], 1, v[54:55]
	s_waitcnt lgkmcnt(0)
	v_cvt_pk_bf16_f32 v3, v8, v9
	v_lshlrev_b64 v[8:9], 12, v[6:7]
	v_lshl_add_u64 v[8:9], v[4:5], 0, v[8:9]
	global_store_dwordx4 v[8:9], v[0:3], off
	ds_read_b32 v0, v70 offset:32
	ds_read_b32 v1, v70 offset:164
	ds_read_b32 v2, v70 offset:296
	ds_read_b32 v3, v70 offset:428
	ds_read_b32 v7, v70 offset:560
	ds_read_b32 v8, v70 offset:692
	ds_read_b32 v9, v70 offset:824
	ds_read_b32 v10, v70 offset:956
	s_waitcnt lgkmcnt(0)
	v_cvt_pk_bf16_f32 v0, v0, v1
	v_cvt_pk_bf16_f32 v1, v2, v3
	v_cvt_pk_bf16_f32 v2, v7, v8
	v_add_u32_e32 v8, 8, v6
	v_cvt_pk_bf16_f32 v3, v9, v10
	v_ashrrev_i32_e32 v9, 31, v8
	v_lshlrev_b64 v[8:9], 12, v[8:9]
	v_lshl_add_u64 v[8:9], v[4:5], 0, v[8:9]
	global_store_dwordx4 v[8:9], v[0:3], off
	ds_read_b32 v0, v70 offset:64
	ds_read_b32 v1, v70 offset:196
	ds_read_b32 v2, v70 offset:328
	ds_read_b32 v3, v70 offset:460
	ds_read_b32 v7, v70 offset:592
	ds_read_b32 v8, v70 offset:724
	ds_read_b32 v9, v70 offset:856
	ds_read_b32 v10, v70 offset:988
	s_waitcnt lgkmcnt(0)
	v_cvt_pk_bf16_f32 v0, v0, v1
	v_cvt_pk_bf16_f32 v1, v2, v3
	v_cvt_pk_bf16_f32 v2, v7, v8
	v_add_u32_e32 v8, 16, v6
	v_cvt_pk_bf16_f32 v3, v9, v10
	v_ashrrev_i32_e32 v9, 31, v8
	v_lshlrev_b64 v[8:9], 12, v[8:9]
	v_lshl_add_u64 v[8:9], v[4:5], 0, v[8:9]
	global_store_dwordx4 v[8:9], v[0:3], off
	ds_read_b32 v0, v70 offset:96
	ds_read_b32 v1, v70 offset:228
	ds_read_b32 v2, v70 offset:360
	ds_read_b32 v3, v70 offset:492
	ds_read_b32 v7, v70 offset:624
	ds_read_b32 v8, v70 offset:756
	ds_read_b32 v9, v70 offset:888
	ds_read_b32 v10, v70 offset:1020
	v_add_u32_e32 v6, 24, v6
	s_waitcnt lgkmcnt(0)
	v_cvt_pk_bf16_f32 v0, v0, v1
	v_cvt_pk_bf16_f32 v1, v2, v3
	v_cvt_pk_bf16_f32 v2, v7, v8
	v_ashrrev_i32_e32 v7, 31, v6
	v_lshlrev_b64 v[6:7], 12, v[6:7]
	v_cvt_pk_bf16_f32 v3, v9, v10
	v_lshl_add_u64 v[4:5], v[4:5], 0, v[6:7]
	global_store_dwordx4 v[4:5], v[0:3], off
	s_waitcnt lgkmcnt(0)
	s_add_i32 s4, s4, s16
	s_add_i32 s2, s2, s27
	s_cmpk_lt_i32 s4, 0x640
	s_cbranch_scc0 .LBB0_191
.LBB0_173:
	s_mul_hi_i32 s0, s4, 0x51eb851f
	s_lshr_b32 s1, s0, 31
	s_ashr_i32 s0, s0, 4
	s_add_i32 s0, s0, s1
	s_mul_i32 s1, s0, 0xfffff9c0
	s_lshl_b32 s96, s0, 6
	s_add_i32 s94, s2, s1
	v_or_b32_e32 v56, s96, v32
	s_ashr_i32 s95, s94, 31
	v_or_b32_e32 v4, 8, v56
	v_lshl_add_u64 v[0:1], s[94:95], 2, v[52:53]
	v_min_i32_e32 v2, 0x7ff, v56
	v_min_i32_e32 v4, 0x7ff, v4
	v_mad_i64_i32 v[2:3], s[0:1], v2, s50, v[0:1]
	v_mad_i64_i32 v[4:5], s[0:1], v4, s50, v[0:1]
	global_load_dwordx4 v[28:31], v[2:3], off nt
	global_load_dwordx4 v[24:27], v[4:5], off nt
	v_or_b32_e32 v2, 16, v56
	v_or_b32_e32 v4, 24, v56
	v_min_i32_e32 v2, 0x7ff, v2
	v_min_i32_e32 v4, 0x7ff, v4
	v_mad_i64_i32 v[2:3], s[0:1], v2, s50, v[0:1]
	v_mad_i64_i32 v[4:5], s[0:1], v4, s50, v[0:1]
	global_load_dwordx4 v[20:23], v[2:3], off nt
	global_load_dwordx4 v[16:19], v[4:5], off nt
	v_or_b32_e32 v2, 32, v56
	v_or_b32_e32 v4, 40, v56
	v_min_i32_e32 v2, 0x7ff, v2
	v_min_i32_e32 v4, 0x7ff, v4
	v_mad_i64_i32 v[2:3], s[0:1], v2, s50, v[0:1]
	v_mad_i64_i32 v[4:5], s[0:1], v4, s50, v[0:1]
	global_load_dwordx4 v[12:15], v[2:3], off nt
	global_load_dwordx4 v[8:11], v[4:5], off nt
	v_or_b32_e32 v2, 48, v56
	v_or_b32_e32 v4, 56, v56
	v_min_i32_e32 v2, 0x7ff, v2
	v_min_i32_e32 v4, 0x7ff, v4
	v_mad_i64_i32 v[2:3], s[0:1], v2, s50, v[0:1]
	v_mad_i64_i32 v[0:1], s[0:1], v4, s50, v[0:1]
	global_load_dwordx4 v[4:7], v[2:3], off nt
	s_nop 0
	global_load_dwordx4 v[0:3], v[0:1], off nt
	v_cmp_gt_i32_e32 vcc, s61, v56
	s_and_b64 s[6:7], s[86:87], vcc
	v_mov_b32_e32 v71, 1.0
	v_mov_b32_e32 v57, 1.0
	s_and_saveexec_b64 s[0:1], s[6:7]
	s_cbranch_execz .LBB0_175
	v_ashrrev_i32_e32 v57, 31, v56
	v_lshl_add_u64 v[56:57], v[56:57], 2, s[40:41]
	global_load_dword v57, v[56:57], off
.LBB0_175:
	s_or_b64 exec, exec, s[0:1]
	s_waitcnt vmcnt(0) lgkmcnt(0)
	v_mul_f32_e32 v28, v28, v57
	v_mul_f32_e32 v29, v29, v57
	v_cndmask_b32_e32 v28, 0, v28, vcc
	v_cndmask_b32_e32 v29, 0, v29, vcc
	v_add_u32_e32 v56, v35, v37
	ds_write2_b32 v56, v28, v29 offset1:1
	v_mul_f32_e32 v28, v30, v57
	v_mul_f32_e32 v29, v31, v57
	v_cndmask_b32_e32 v28, 0, v28, vcc
	v_cndmask_b32_e32 v29, 0, v29, vcc
	ds_write2_b32 v56, v28, v29 offset0:2 offset1:3
	v_or_b32_e32 v28, s96, v58
	v_cmp_gt_i32_e32 vcc, s61, v28
	s_and_b64 s[6:7], s[86:87], vcc
	s_and_saveexec_b64 s[0:1], s[6:7]
	s_cbranch_execz .LBB0_177
	s_ashr_i32 s97, s96, 31
	v_lshl_add_u64 v[28:29], s[96:97], 0, v[32:33]
	v_lshl_add_u64 v[28:29], v[28:29], 2, s[40:41]
	global_load_dword v71, v[28:29], off offset:32
; #define LAS __attribute__((address_space(3)))
; __device__ __forceinline__ void tr_item(const float* W, int Ksrc, int N, int k0, int n0, bf16* dst, int ldt, int drow0, int dcol0, LAS float* scr, int lane, const float* nscale = nullptr, const float* kscale = nullptr) {
;     ...
;     for (int i = 0; i < 8; ++i) { const int kk = 8 * i + kr_; const int kr = (k0 + kk < Ksrc) ? (k0 + kk) : (Ksrc - 1); tv[i] = __builtin_nontemporal_load((const f32x4*)(W + (size_t)kr * N + n0 + 4 * nq_)); }
; #pragma unroll
;     for (int i = 0; i < 8; ++i) { const int kk = 8 * i + kr_; const bool ok = (k0 + kk < Ksrc); LAS float* d_ = scr + kk * 33 + 4 * nq_;
;         const float ks_ = (ok && kscale) ? kscale[k0 + kk] : 1.0f;
;         d_[0] = ok ? tv[i].x * ks_ : 0.f; d_[1] = ok ? tv[i].y * ks_ : 0.f; d_[2] = ok ? tv[i].z * ks_ : 0.f; d_[3] = ok ? tv[i].w * ks_ : 0.f; }
.LBB0_177:
	s_or_b64 exec, exec, s[0:1]
	s_waitcnt vmcnt(0) lgkmcnt(0)
	v_mul_f32_e32 v24, v24, v71
	v_mul_f32_e32 v25, v25, v71
	v_cndmask_b32_e32 v24, 0, v24, vcc
	v_cndmask_b32_e32 v25, 0, v25, vcc
	v_add_u32_e32 v28, v35, v59
	ds_write2_b32 v28, v24, v25 offset1:1
	v_mul_f32_e32 v24, v26, v71
	v_mul_f32_e32 v25, v27, v71
	v_cndmask_b32_e32 v24, 0, v24, vcc
	v_cndmask_b32_e32 v25, 0, v25, vcc
	ds_write2_b32 v28, v24, v25 offset0:2 offset1:3
	v_or_b32_e32 v24, s96, v60
	v_cmp_gt_i32_e32 vcc, s61, v24
	s_and_b64 s[6:7], s[86:87], vcc
	v_mov_b32_e32 v24, 1.0
	v_mov_b32_e32 v25, 1.0
	s_and_saveexec_b64 s[0:1], s[6:7]
	s_cbranch_execz .LBB0_179
	s_ashr_i32 s97, s96, 31
	v_lshl_add_u64 v[26:27], s[96:97], 0, v[32:33]
	v_lshl_add_u64 v[26:27], v[26:27], 2, s[40:41]
	global_load_dword v25, v[26:27], off offset:64
.LBB0_179:
	s_or_b64 exec, exec, s[0:1]
	s_waitcnt vmcnt(0) lgkmcnt(0)
	v_mul_f32_e32 v20, v20, v25
	v_mul_f32_e32 v21, v21, v25
	v_cndmask_b32_e32 v20, 0, v20, vcc
	v_cndmask_b32_e32 v21, 0, v21, vcc
	v_add_u32_e32 v26, v35, v61
	ds_write2_b32 v26, v20, v21 offset1:1
	v_mul_f32_e32 v20, v22, v25
	v_mul_f32_e32 v21, v23, v25
	v_cndmask_b32_e32 v20, 0, v20, vcc
	v_cndmask_b32_e32 v21, 0, v21, vcc
	ds_write2_b32 v26, v20, v21 offset0:2 offset1:3
	v_or_b32_e32 v20, s96, v62
	v_cmp_gt_i32_e32 vcc, s61, v20
	s_and_b64 s[6:7], s[86:87], vcc
	s_and_saveexec_b64 s[0:1], s[6:7]
	s_cbranch_execz .LBB0_181
	s_ashr_i32 s97, s96, 31
	v_lshl_add_u64 v[20:21], s[96:97], 0, v[32:33]
	v_lshl_add_u64 v[20:21], v[20:21], 2, s[40:41]
	global_load_dword v24, v[20:21], off offset:96
.LBB0_181:
	s_or_b64 exec, exec, s[0:1]
	s_waitcnt vmcnt(0) lgkmcnt(0)
	v_mul_f32_e32 v16, v16, v24
	v_mul_f32_e32 v17, v17, v24
	v_cndmask_b32_e32 v16, 0, v16, vcc
	v_cndmask_b32_e32 v17, 0, v17, vcc
	v_add_u32_e32 v20, v35, v63
	ds_write2_b32 v20, v16, v17 offset1:1
	v_mul_f32_e32 v16, v18, v24
	v_mul_f32_e32 v17, v19, v24
	v_cndmask_b32_e32 v16, 0, v16, vcc
	v_cndmask_b32_e32 v17, 0, v17, vcc
	ds_write2_b32 v20, v16, v17 offset0:2 offset1:3
	v_or_b32_e32 v16, s96, v64
	v_cmp_gt_i32_e32 vcc, s61, v16
	s_and_b64 s[6:7], s[86:87], vcc
	v_mov_b32_e32 v16, 1.0
	v_mov_b32_e32 v17, 1.0
	s_and_saveexec_b64 s[0:1], s[6:7]
	s_cbranch_execz .LBB0_183
	s_ashr_i32 s97, s96, 31
	v_lshl_add_u64 v[18:19], s[96:97], 0, v[32:33]
	v_lshl_add_u64 v[18:19], v[18:19], 2, s[40:41]
	global_load_dword v17, v[18:19], off offset:128
.LBB0_183:
	s_or_b64 exec, exec, s[0:1]
	s_waitcnt vmcnt(0) lgkmcnt(0)
	v_mul_f32_e32 v12, v12, v17
	v_mul_f32_e32 v13, v13, v17
	v_cndmask_b32_e32 v12, 0, v12, vcc
	v_cndmask_b32_e32 v13, 0, v13, vcc
	v_add_u32_e32 v18, v35, v65
	ds_write2_b32 v18, v12, v13 offset1:1
	v_mul_f32_e32 v12, v14, v17
	v_mul_f32_e32 v13, v15, v17
	v_cndmask_b32_e32 v12, 0, v12, vcc
	v_cndmask_b32_e32 v13, 0, v13, vcc
	ds_write2_b32 v18, v12, v13 offset0:2 offset1:3
	v_or_b32_e32 v12, s96, v66
	v_cmp_gt_i32_e32 vcc, s61, v12
	s_and_b64 s[6:7], s[86:87], vcc
	s_and_saveexec_b64 s[0:1], s[6:7]
	s_cbranch_execz .LBB0_185
	s_ashr_i32 s97, s96, 31
	v_lshl_add_u64 v[12:13], s[96:97], 0, v[32:33]
	v_lshl_add_u64 v[12:13], v[12:13], 2, s[40:41]
	global_load_dword v16, v[12:13], off offset:160
.LBB0_185:
	s_or_b64 exec, exec, s[0:1]
	s_waitcnt vmcnt(0) lgkmcnt(0)
	v_mul_f32_e32 v8, v8, v16
	v_mul_f32_e32 v9, v9, v16
	v_cndmask_b32_e32 v12, 0, v8, vcc
	v_cndmask_b32_e32 v9, 0, v9, vcc
	v_add_u32_e32 v8, v35, v67
	ds_write2_b32 v8, v12, v9 offset1:1
	v_mul_f32_e32 v9, v10, v16
	v_mul_f32_e32 v10, v11, v16
	v_cndmask_b32_e32 v9, 0, v9, vcc
	v_cndmask_b32_e32 v10, 0, v10, vcc
	ds_write2_b32 v8, v9, v10 offset0:2 offset1:3
	v_or_b32_e32 v9, s96, v68
	v_cmp_gt_i32_e32 vcc, s61, v9
	s_and_b64 s[6:7], s[86:87], vcc
	v_mov_b32_e32 v9, 1.0
	s_and_saveexec_b64 s[0:1], s[6:7]
	s_cbranch_execz .LBB0_187
	s_ashr_i32 s97, s96, 31
	v_lshl_add_u64 v[10:11], s[96:97], 0, v[32:33]
	v_lshl_add_u64 v[10:11], v[10:11], 2, s[40:41]
	global_load_dword v9, v[10:11], off offset:192
.LBB0_187:
	s_or_b64 exec, exec, s[0:1]
	s_waitcnt vmcnt(0) lgkmcnt(0)
	v_mul_f32_e32 v4, v4, v9
	v_mul_f32_e32 v5, v5, v9
	v_cndmask_b32_e32 v4, 0, v4, vcc
	v_cndmask_b32_e32 v5, 0, v5, vcc
	v_add_u32_e32 v10, 0x420, v8
	ds_write2_b32 v10, v4, v5 offset1:1
	v_mul_f32_e32 v4, v6, v9
	v_mul_f32_e32 v5, v7, v9
	v_cndmask_b32_e32 v4, 0, v4, vcc
	v_cndmask_b32_e32 v5, 0, v5, vcc
	v_add_u32_e32 v6, 0x428, v8
	ds_write2_b32 v6, v4, v5 offset1:1
	v_or_b32_e32 v4, s96, v69
	v_cmp_gt_i32_e32 vcc, s61, v4
	s_and_b64 s[0:1], s[86:87], vcc
	s_xor_b64 s[0:1], s[0:1], -1
	s_and_saveexec_b64 s[6:7], s[0:1]
	s_xor_b64 s[0:1], exec, s[6:7]
	s_ashr_i32 s97, s96, 31
	s_or_saveexec_b64 s[0:1], s[0:1]
	v_mov_b32_e32 v6, 1.0
	v_mov_b64_e32 v[4:5], s[96:97]
	s_xor_b64 exec, exec, s[0:1]
	s_cbranch_execz .LBB0_172
	s_ashr_i32 s97, s96, 31
	v_lshl_add_u64 v[4:5], s[96:97], 0, v[32:33]
	v_lshl_add_u64 v[4:5], v[4:5], 2, s[40:41]
	global_load_dword v6, v[4:5], off offset:224
	v_mov_b64_e32 v[4:5], s[96:97]
	s_branch .LBB0_172

; __device__ __forceinline__ unsigned pk_bf16(float lo, float hi) { f32x2e v = {lo, hi}; bf16x2e b = __builtin_convertvector(v, bf16x2e); return __builtin_bit_cast(unsigned, b); }
; #define LAS __attribute__((address_space(3)))
; __device__ __forceinline__ void tr_item(const float* W, int Ksrc, int N, int k0, int n0, bf16* dst, int ldt, int drow0, int dcol0, LAS float* scr, int lane, const float* nscale = nullptr, const float* kscale = nullptr) {
;     f32x4 tv[8]; const int kr_ = lane >> 3, nq_ = lane & 7;
; #pragma unroll
;     for (int i = 0; i < 8; ++i) { const int kk = 8 * i + kr_; const int kr = (k0 + kk < Ksrc) ? (k0 + kk) : (Ksrc - 1); tv[i] = __builtin_nontemporal_load((const f32x4*)(W + (size_t)kr * N + n0 + 4 * nq_)); }
; #pragma unroll
;     for (int i = 0; i < 8; ++i) { const int kk = 8 * i + kr_; const bool ok = (k0 + kk < Ksrc); LAS float* d_ = scr + kk * 33 + 4 * nq_;
;         const float ks_ = (ok && kscale) ? kscale[k0 + kk] : 1.0f;
;         d_[0] = ok ? tv[i].x * ks_ : 0.f; d_[1] = ok ? tv[i].y * ks_ : 0.f; d_[2] = ok ? tv[i].z * ks_ : 0.f; d_[3] = ok ? tv[i].w * ks_ : 0.f; }
;     asm volatile("s_waitcnt lgkmcnt(0)" ::: "memory");
;     const int c = lane & 7;
; #pragma unroll
;     for (int j = 0; j < 4; ++j) { const int n = (lane >> 3) + 8 * j; const LAS float* s = scr + (8 * c) * 33 + n;
;         const float sc = nscale ? nscale[n0 + n] : 1.0f;
;         u32x4 o; o.x = pk_bf16(s[0 * 33] * sc, s[1 * 33] * sc); o.y = pk_bf16(s[2 * 33] * sc, s[3 * 33] * sc); o.z = pk_bf16(s[4 * 33] * sc, s[5 * 33] * sc); o.w = pk_bf16(s[6 * 33] * sc, s[7 * 33] * sc);
;         *(u32x4*)(dst + (size_t)(drow0 + n) * ldt + dcol0 + k0 + 8 * c) = o; }
.LBB0_195:
	ds_read2_b32 v[10:11], v70 offset0:24 offset1:57
	ds_read2_b32 v[14:15], v70 offset0:90 offset1:123
	ds_read2_b32 v[16:17], v70 offset0:156 offset1:189
	ds_read2_b32 v[18:19], v70 offset0:222 offset1:255
	v_add_u32_e32 v8, 24, v8
	s_waitcnt vmcnt(0) lgkmcnt(0)
	v_pk_mul_f32 v[10:11], v[12:13], v[10:11] op_sel_hi:[0,1]
	v_pk_mul_f32 v[20:21], v[12:13], v[14:15] op_sel_hi:[0,1]
	v_cvt_pk_bf16_f32 v14, v10, v11
	v_pk_mul_f32 v[10:11], v[12:13], v[16:17] op_sel_hi:[0,1]
	v_ashrrev_i32_e32 v9, 31, v8
	v_cvt_pk_bf16_f32 v16, v10, v11
	v_pk_mul_f32 v[10:11], v[12:13], v[18:19] op_sel_hi:[0,1]
	v_lshlrev_b64 v[8:9], 10, v[8:9]
	v_cvt_pk_bf16_f32 v15, v20, v21
	v_cvt_pk_bf16_f32 v17, v10, v11
	v_lshl_add_u64 v[6:7], v[6:7], 0, v[8:9]
	global_store_dwordx4 v[6:7], v[14:17], off
	s_waitcnt lgkmcnt(0)
	s_add_i32 s7, s7, s16
	s_add_i32 s6, s6, s27
	s_cmp_lt_i32 s7, 8
	s_cbranch_scc0 .LBB0_192
.LBB0_196:
	s_ashr_i32 s0, s7, 31
	s_lshr_b32 s0, s0, 30
	s_add_i32 s0, s7, s0
	s_ashr_i32 s1, s0, 2
	s_lshl_b32 s4, s1, 6
	s_lshl_b32 s5, s1, 7
	v_or_b32_e32 v12, s4, v32
	s_sub_i32 s0, s6, s5
	v_min_i32_e32 v6, 0x7f, v12
	v_or_b32_e32 v14, 8, v12
	s_ashr_i32 s1, s0, 31
	v_ashrrev_i32_e32 v7, 31, v6
	v_min_i32_e32 v14, 0x7f, v14
	v_or_b32_e32 v18, 16, v12
	v_lshl_add_u64 v[10:11], s[0:1], 2, v[2:3]
	v_lshlrev_b64 v[6:7], 9, v[6:7]
	v_ashrrev_i32_e32 v15, 31, v14
	v_min_i32_e32 v18, 0x7f, v18
	v_or_b32_e32 v22, 24, v12
	v_lshl_add_u64 v[6:7], v[10:11], 0, v[6:7]
	v_lshlrev_b64 v[14:15], 9, v[14:15]
	v_ashrrev_i32_e32 v19, 31, v18
	v_min_i32_e32 v22, 0x7f, v22
	global_load_dwordx4 v[6:9], v[6:7], off nt
	v_lshl_add_u64 v[14:15], v[10:11], 0, v[14:15]
	v_lshlrev_b64 v[18:19], 9, v[18:19]
	v_ashrrev_i32_e32 v23, 31, v22
	global_load_dwordx4 v[14:17], v[14:15], off nt
	v_lshl_add_u64 v[18:19], v[10:11], 0, v[18:19]
	v_lshlrev_b64 v[22:23], 9, v[22:23]
	v_or_b32_e32 v26, 32, v12
	global_load_dwordx4 v[18:21], v[18:19], off nt
	v_lshl_add_u64 v[22:23], v[10:11], 0, v[22:23]
	v_min_i32_e32 v26, 0x7f, v26
	global_load_dwordx4 v[22:25], v[22:23], off nt
	v_ashrrev_i32_e32 v27, 31, v26
	v_or_b32_e32 v30, 40, v12
	v_lshlrev_b64 v[26:27], 9, v[26:27]
	v_min_i32_e32 v30, 0x7f, v30
	v_lshl_add_u64 v[26:27], v[10:11], 0, v[26:27]
	v_ashrrev_i32_e32 v31, 31, v30
	global_load_dwordx4 v[26:29], v[26:27], off nt
	v_lshlrev_b64 v[30:31], 9, v[30:31]
	v_lshl_add_u64 v[30:31], v[10:11], 0, v[30:31]
	global_load_dwordx4 v[52:55], v[30:31], off nt
	v_or_b32_e32 v30, 48, v12
	v_min_i32_e32 v30, 0x7f, v30
	v_ashrrev_i32_e32 v31, 31, v30
	v_lshlrev_b64 v[30:31], 9, v[30:31]
	v_lshl_add_u64 v[30:31], v[10:11], 0, v[30:31]
	global_load_dwordx4 v[72:75], v[30:31], off nt
	v_or_b32_e32 v30, 56, v12
	v_min_i32_e32 v30, 0x7f, v30
	v_ashrrev_i32_e32 v31, 31, v30
	v_lshlrev_b64 v[30:31], 9, v[30:31]
	v_lshl_add_u64 v[10:11], v[10:11], 0, v[30:31]
	global_load_dwordx4 v[76:79], v[10:11], off nt
	v_or_b32_e32 v71, s4, v58
	v_cmp_gt_i32_e32 vcc, s51, v12
	v_add_u32_e32 v10, v35, v37
	v_or_b32_e32 v80, s4, v60
	v_or_b32_e32 v81, s4, v62
	v_add_u32_e32 v11, 0x420, v10
	v_add_u32_e32 v30, 0x428, v10
	v_add_u32_e32 v31, 0x840, v10
	v_add_u32_e32 v56, 0x848, v10
	v_add_u32_e32 v57, 0xc60, v10
	s_sub_i32 s8, 0, s5
	s_waitcnt vmcnt(0) lgkmcnt(0)
	v_cndmask_b32_e32 v6, 0, v6, vcc
	v_cndmask_b32_e32 v7, 0, v7, vcc
	v_cndmask_b32_e32 v8, 0, v8, vcc
	v_cndmask_b32_e32 v9, 0, v9, vcc
	v_cmp_gt_i32_e32 vcc, s51, v71
	ds_write2_b32 v10, v6, v7 offset1:1
	ds_write2_b32 v10, v8, v9 offset0:2 offset1:3
	v_cndmask_b32_e32 v6, 0, v14, vcc
	v_cndmask_b32_e32 v7, 0, v15, vcc
	v_cndmask_b32_e32 v8, 0, v16, vcc
	v_cndmask_b32_e32 v9, 0, v17, vcc
	v_cmp_gt_i32_e32 vcc, s51, v80
	s_nop 1
	v_cndmask_b32_e32 v12, 0, v18, vcc
	v_cndmask_b32_e32 v14, 0, v19, vcc
	v_cndmask_b32_e32 v15, 0, v20, vcc
	v_cndmask_b32_e32 v16, 0, v21, vcc
	v_cmp_gt_i32_e32 vcc, s51, v81
	s_nop 1
	v_cndmask_b32_e32 v17, 0, v22, vcc
	v_cndmask_b32_e32 v18, 0, v23, vcc
	v_cndmask_b32_e32 v19, 0, v24, vcc
	ds_write2_b32 v11, v6, v7 offset1:1
	ds_write2_b32 v30, v8, v9 offset1:1
	ds_write2_b32 v31, v12, v14 offset1:1
	ds_write2_b32 v56, v15, v16 offset1:1
	ds_write2_b32 v57, v17, v18 offset1:1
	v_cndmask_b32_e32 v6, 0, v25, vcc
	v_add_u32_e32 v7, 0xc68, v10
	ds_write2_b32 v7, v19, v6 offset1:1
	v_or_b32_e32 v6, s4, v64
	v_cmp_gt_i32_e32 vcc, s51, v6
	v_add_u32_e32 v8, 0x1080, v10
	v_mov_b32_e32 v12, 1.0
	v_cndmask_b32_e32 v6, 0, v26, vcc
	v_cndmask_b32_e32 v7, 0, v27, vcc
	ds_write2_b32 v8, v6, v7 offset1:1
	v_cndmask_b32_e32 v6, 0, v28, vcc
	v_cndmask_b32_e32 v7, 0, v29, vcc
	v_add_u32_e32 v8, 0x1088, v10
	ds_write2_b32 v8, v6, v7 offset1:1
	v_or_b32_e32 v6, s4, v66
	v_cmp_gt_i32_e32 vcc, s51, v6
	v_add_u32_e32 v8, 0x14a0, v10
	s_nop 0
	v_cndmask_b32_e32 v6, 0, v52, vcc
	v_cndmask_b32_e32 v7, 0, v53, vcc
	ds_write2_b32 v8, v6, v7 offset1:1
	v_cndmask_b32_e32 v6, 0, v54, vcc
	v_cndmask_b32_e32 v7, 0, v55, vcc
	v_add_u32_e32 v8, v35, v67
	ds_write2_b32 v8, v6, v7 offset0:2 offset1:3
	v_or_b32_e32 v6, s4, v68
	v_cmp_gt_i32_e32 vcc, s51, v6
	v_add_u32_e32 v9, 0x420, v8
	s_nop 0
	v_cndmask_b32_e32 v6, 0, v72, vcc
	v_cndmask_b32_e32 v7, 0, v73, vcc
	ds_write2_b32 v9, v6, v7 offset1:1
	v_cndmask_b32_e32 v6, 0, v74, vcc
	v_cndmask_b32_e32 v7, 0, v75, vcc
	v_add_u32_e32 v9, 0x428, v8
	ds_write2_b32 v9, v6, v7 offset1:1
	v_or_b32_e32 v6, s4, v69
	v_cmp_gt_i32_e32 vcc, s51, v6
	v_add_u32_e32 v9, 0x840, v8
	v_add_u32_e32 v8, 0x848, v8
	v_cndmask_b32_e32 v6, 0, v76, vcc
	v_cndmask_b32_e32 v7, 0, v77, vcc
	ds_write2_b32 v9, v6, v7 offset1:1
	v_cndmask_b32_e32 v6, 0, v78, vcc
	v_cndmask_b32_e32 v7, 0, v79, vcc
	ds_write2_b32 v8, v6, v7 offset1:1
	s_waitcnt lgkmcnt(0)
	v_cndmask_b32_e64 v6, 0, 1, s[96:97]
	v_cmp_ne_u32_e64 s[40:41], 1, v6
	s_andn2_b64 vcc, exec, s[96:97]
	v_mov_b32_e32 v8, 1.0
	s_cbranch_vccnz .LBB0_198
	s_add_i32 s5, s8, s6
	v_add_u32_e32 v6, s5, v32
	v_ashrrev_i32_e32 v7, 31, v6
	v_lshl_add_u64 v[6:7], v[6:7], 2, s[94:95]
	global_load_dword v8, v[6:7], off
; __device__ __forceinline__ unsigned pk_bf16(float lo, float hi) { f32x2e v = {lo, hi}; bf16x2e b = __builtin_convertvector(v, bf16x2e); return __builtin_bit_cast(unsigned, b); }
; #define LAS __attribute__((address_space(3)))
; __device__ __forceinline__ void tr_item(const float* W, int Ksrc, int N, int k0, int n0, bf16* dst, int ldt, int drow0, int dcol0, LAS float* scr, int lane, const float* nscale = nullptr, const float* kscale = nullptr) {
;     ...
;     const int c = lane & 7;
; #pragma unroll
;     for (int j = 0; j < 4; ++j) { const int n = (lane >> 3) + 8 * j; const LAS float* s = scr + (8 * c) * 33 + n;
;         const float sc = nscale ? nscale[n0 + n] : 1.0f;
;         u32x4 o; o.x = pk_bf16(s[0 * 33] * sc, s[1 * 33] * sc); o.y = pk_bf16(s[2 * 33] * sc, s[3 * 33] * sc); o.z = pk_bf16(s[4 * 33] * sc, s[5 * 33] * sc); o.w = pk_bf16(s[6 * 33] * sc, s[7 * 33] * sc);
;         *(u32x4*)(dst + (size_t)(drow0 + n) * ldt + dcol0 + k0 + 8 * c) = o; }
;     asm volatile("s_waitcnt lgkmcnt(0)" ::: "memory");
.LBB0_198:
	ds_read2_b32 v[10:11], v70 offset1:33
	ds_read2_b32 v[16:17], v70 offset0:66 offset1:99
	ds_read2_b32 v[18:19], v70 offset0:132 offset1:165
	s_add_i32 s8, s8, s6
	s_ashr_i32 s5, s4, 31
	v_lshl_add_u64 v[6:7], s[4:5], 1, v[4:5]
	s_waitcnt vmcnt(0) lgkmcnt(0)
	v_pk_mul_f32 v[10:11], v[8:9], v[10:11] op_sel_hi:[0,1]
	v_cvt_pk_bf16_f32 v14, v10, v11
	ds_read2_b32 v[10:11], v70 offset0:198 offset1:231
	v_pk_mul_f32 v[16:17], v[8:9], v[16:17] op_sel_hi:[0,1]
	v_cvt_pk_bf16_f32 v15, v16, v17
	v_pk_mul_f32 v[16:17], v[8:9], v[18:19] op_sel_hi:[0,1]
	v_cvt_pk_bf16_f32 v16, v16, v17
	s_waitcnt lgkmcnt(0)
	v_pk_mul_f32 v[8:9], v[8:9], v[10:11] op_sel_hi:[0,1]
	v_cvt_pk_bf16_f32 v17, v8, v9
	v_add_u32_e32 v8, s8, v13
	v_ashrrev_i32_e32 v9, 31, v8
	v_lshlrev_b64 v[10:11], 10, v[8:9]
	v_lshl_add_u64 v[10:11], v[6:7], 0, v[10:11]
	global_store_dwordx4 v[10:11], v[14:17], off
	v_lshl_add_u64 v[10:11], s[0:1], 0, v[32:33]
	s_and_b64 vcc, exec, s[40:41]
	v_lshl_add_u64 v[10:11], v[10:11], 2, s[94:95]
	s_cbranch_vccnz .LBB0_200
	global_load_dword v12, v[10:11], off offset:32
.LBB0_200:
	ds_read2_b32 v[14:15], v70 offset0:8 offset1:41
	ds_read2_b32 v[16:17], v70 offset0:74 offset1:107
	ds_read2_b32 v[18:19], v70 offset0:140 offset1:173
	ds_read2_b32 v[20:21], v70 offset0:206 offset1:239
	s_and_b64 vcc, exec, s[40:41]
	s_waitcnt vmcnt(0) lgkmcnt(0)
	v_pk_mul_f32 v[14:15], v[12:13], v[14:15] op_sel_hi:[0,1]
	v_pk_mul_f32 v[16:17], v[12:13], v[16:17] op_sel_hi:[0,1]
	v_cvt_pk_bf16_f32 v14, v14, v15
	v_cvt_pk_bf16_f32 v15, v16, v17
	v_pk_mul_f32 v[16:17], v[12:13], v[18:19] op_sel_hi:[0,1]
	v_pk_mul_f32 v[18:19], v[12:13], v[20:21] op_sel_hi:[0,1]
	v_cvt_pk_bf16_f32 v16, v16, v17
	v_cvt_pk_bf16_f32 v17, v18, v19
	v_add_u32_e32 v18, 8, v8
	v_ashrrev_i32_e32 v19, 31, v18
	v_lshlrev_b64 v[18:19], 10, v[18:19]
	v_lshl_add_u64 v[18:19], v[6:7], 0, v[18:19]
	global_store_dwordx4 v[18:19], v[14:17], off
	v_mov_b32_e32 v12, 1.0
	s_nop 0
	v_mov_b32_e32 v14, 1.0
	s_cbranch_vccnz .LBB0_202
	global_load_dword v14, v[10:11], off offset:64
.LBB0_202:
	ds_read2_b32 v[16:17], v70 offset0:16 offset1:49
	ds_read2_b32 v[18:19], v70 offset0:82 offset1:115
	ds_read2_b32 v[20:21], v70 offset0:148 offset1:181
	ds_read2_b32 v[22:23], v70 offset0:214 offset1:247
	s_and_b64 vcc, exec, s[40:41]
	s_waitcnt vmcnt(0) lgkmcnt(0)
	v_pk_mul_f32 v[16:17], v[14:15], v[16:17] op_sel_hi:[0,1]
	v_pk_mul_f32 v[18:19], v[14:15], v[18:19] op_sel_hi:[0,1]
	v_cvt_pk_bf16_f32 v16, v16, v17
	v_cvt_pk_bf16_f32 v17, v18, v19
	v_pk_mul_f32 v[18:19], v[14:15], v[20:21] op_sel_hi:[0,1]
	v_pk_mul_f32 v[14:15], v[14:15], v[22:23] op_sel_hi:[0,1]
	v_cvt_pk_bf16_f32 v18, v18, v19
	v_cvt_pk_bf16_f32 v19, v14, v15
	v_add_u32_e32 v14, 16, v8
	v_ashrrev_i32_e32 v15, 31, v14
	v_lshlrev_b64 v[14:15], 10, v[14:15]
	v_lshl_add_u64 v[14:15], v[6:7], 0, v[14:15]
	global_store_dwordx4 v[14:15], v[16:19], off
	s_cbranch_vccnz .LBB0_195
	global_load_dword v12, v[10:11], off offset:96
	s_branch .LBB0_195

; __device__ __forceinline__ unsigned pk_bf16(float lo, float hi) { f32x2e v = {lo, hi}; bf16x2e b = __builtin_convertvector(v, bf16x2e); return __builtin_bit_cast(unsigned, b); }
; #define LAS __attribute__((address_space(3)))
; __device__ __forceinline__ void tr_item(const float* W, int Ksrc, int N, int k0, int n0, bf16* dst, int ldt, int drow0, int dcol0, LAS float* scr, int lane, const float* nscale = nullptr, const float* kscale = nullptr) {
;     f32x4 tv[8]; const int kr_ = lane >> 3, nq_ = lane & 7;
; #pragma unroll
;     for (int i = 0; i < 8; ++i) { const int kk = 8 * i + kr_; const int kr = (k0 + kk < Ksrc) ? (k0 + kk) : (Ksrc - 1); tv[i] = __builtin_nontemporal_load((const f32x4*)(W + (size_t)kr * N + n0 + 4 * nq_)); }
; #pragma unroll
;     for (int i = 0; i < 8; ++i) { const int kk = 8 * i + kr_; const bool ok = (k0 + kk < Ksrc); LAS float* d_ = scr + kk * 33 + 4 * nq_;
;         const float ks_ = (ok && kscale) ? kscale[k0 + kk] : 1.0f;
;         d_[0] = ok ? tv[i].x * ks_ : 0.f; d_[1] = ok ? tv[i].y * ks_ : 0.f; d_[2] = ok ? tv[i].z * ks_ : 0.f; d_[3] = ok ? tv[i].w * ks_ : 0.f; }
;     asm volatile("s_waitcnt lgkmcnt(0)" ::: "memory");
;     const int c = lane & 7;
; #pragma unroll
;     for (int j = 0; j < 4; ++j) { const int n = (lane >> 3) + 8 * j; const LAS float* s = scr + (8 * c) * 33 + n;
;         const float sc = nscale ? nscale[n0 + n] : 1.0f;
;         u32x4 o; o.x = pk_bf16(s[0 * 33] * sc, s[1 * 33] * sc); o.y = pk_bf16(s[2 * 33] * sc, s[3 * 33] * sc); o.z = pk_bf16(s[4 * 33] * sc, s[5 * 33] * sc); o.w = pk_bf16(s[6 * 33] * sc, s[7 * 33] * sc);
;         *(u32x4*)(dst + (size_t)(drow0 + n) * ldt + dcol0 + k0 + 8 * c) = o; }
;     asm volatile("s_waitcnt lgkmcnt(0)" ::: "memory");
.LBB0_206:
	s_mul_hi_i32 s2, s1, 0x38e38e39
	s_lshr_b32 s4, s2, 31
	s_ashr_i32 s2, s2, 4
	s_add_i32 s2, s2, s4
	s_mul_i32 s4, s2, 0xfffff700
	s_add_i32 s40, s0, s4
	s_lshl_b32 s78, s2, 6
	v_or_b32_e32 v56, s78, v32
	s_ashr_i32 s41, s40, 31
	v_lshl_add_u64 v[0:1], s[40:41], 2, v[8:9]
	v_min_i32_e32 v2, 0x1ff, v56
	v_mad_i64_i32 v[2:3], s[4:5], v2, s3, v[0:1]
	global_load_dwordx4 v[12:15], v[2:3], off nt
	v_or_b32_e32 v2, 8, v56
	v_min_i32_e32 v2, 0x1ff, v2
	v_mad_i64_i32 v[2:3], s[4:5], v2, s3, v[0:1]
	global_load_dwordx4 v[16:19], v[2:3], off nt
	v_or_b32_e32 v2, 16, v56
	v_min_i32_e32 v2, 0x1ff, v2
	v_mad_i64_i32 v[2:3], s[4:5], v2, s3, v[0:1]
	global_load_dwordx4 v[20:23], v[2:3], off nt
	v_or_b32_e32 v2, 24, v56
	v_min_i32_e32 v2, 0x1ff, v2
	v_mad_i64_i32 v[2:3], s[4:5], v2, s3, v[0:1]
	global_load_dwordx4 v[24:27], v[2:3], off nt
	v_or_b32_e32 v2, 32, v56
	v_min_i32_e32 v2, 0x1ff, v2
	v_mad_i64_i32 v[2:3], s[4:5], v2, s3, v[0:1]
	global_load_dwordx4 v[28:31], v[2:3], off nt
	v_or_b32_e32 v2, 40, v56
	v_min_i32_e32 v2, 0x1ff, v2
	v_mad_i64_i32 v[2:3], s[4:5], v2, s3, v[0:1]
	global_load_dwordx4 v[52:55], v[2:3], off nt
	v_or_b32_e32 v2, 48, v56
	v_min_i32_e32 v2, 0x1ff, v2
	v_mad_i64_i32 v[2:3], s[4:5], v2, s3, v[0:1]
	global_load_dwordx4 v[4:7], v[2:3], off nt
	v_or_b32_e32 v2, 56, v56
	v_min_i32_e32 v2, 0x1ff, v2
	v_mad_i64_i32 v[0:1], s[4:5], v2, s3, v[0:1]
	global_load_dwordx4 v[0:3], v[0:1], off nt
	v_cmp_gt_i32_e32 vcc, s26, v56
	v_add_u32_e32 v56, v35, v37
	s_ashr_i32 s79, s78, 31
	s_add_i32 s1, s1, s16
	s_add_i32 s0, s0, s27
	s_cmpk_lt_i32 s1, 0x240
	s_waitcnt vmcnt(0) lgkmcnt(0)
	v_cndmask_b32_e32 v12, 0, v12, vcc
	v_cndmask_b32_e32 v13, 0, v13, vcc
	ds_write2_b32 v56, v12, v13 offset1:1
	v_cndmask_b32_e32 v12, 0, v14, vcc
	v_cndmask_b32_e32 v13, 0, v15, vcc
	ds_write2_b32 v56, v12, v13 offset0:2 offset1:3
	v_or_b32_e32 v12, s78, v58
	v_cmp_gt_i32_e32 vcc, s26, v12
	v_add_u32_e32 v14, 0x420, v56
	s_nop 0
	v_cndmask_b32_e32 v12, 0, v16, vcc
	v_cndmask_b32_e32 v13, 0, v17, vcc
	ds_write2_b32 v14, v12, v13 offset1:1
	v_cndmask_b32_e32 v12, 0, v18, vcc
	v_cndmask_b32_e32 v13, 0, v19, vcc
	v_add_u32_e32 v14, 0x428, v56
	ds_write2_b32 v14, v12, v13 offset1:1
	v_or_b32_e32 v12, s78, v60
	v_cmp_gt_i32_e32 vcc, s26, v12
	v_add_u32_e32 v14, 0x840, v56
	s_nop 0
	v_cndmask_b32_e32 v12, 0, v20, vcc
	v_cndmask_b32_e32 v13, 0, v21, vcc
	ds_write2_b32 v14, v12, v13 offset1:1
	v_cndmask_b32_e32 v12, 0, v22, vcc
	v_cndmask_b32_e32 v13, 0, v23, vcc
	v_add_u32_e32 v14, 0x848, v56
	ds_write2_b32 v14, v12, v13 offset1:1
	v_or_b32_e32 v12, s78, v62
	v_cmp_gt_i32_e32 vcc, s26, v12
	v_add_u32_e32 v14, 0xc60, v56
	s_nop 0
	v_cndmask_b32_e32 v12, 0, v24, vcc
	v_cndmask_b32_e32 v13, 0, v25, vcc
	ds_write2_b32 v14, v12, v13 offset1:1
	v_cndmask_b32_e32 v12, 0, v26, vcc
	v_cndmask_b32_e32 v13, 0, v27, vcc
	v_add_u32_e32 v14, 0xc68, v56
	ds_write2_b32 v14, v12, v13 offset1:1
	v_or_b32_e32 v12, s78, v64
	v_cmp_gt_i32_e32 vcc, s26, v12
	v_add_u32_e32 v14, 0x1080, v56
	s_nop 0
	v_cndmask_b32_e32 v12, 0, v28, vcc
	v_cndmask_b32_e32 v13, 0, v29, vcc
	ds_write2_b32 v14, v12, v13 offset1:1
	v_cndmask_b32_e32 v12, 0, v30, vcc
	v_cndmask_b32_e32 v13, 0, v31, vcc
	v_add_u32_e32 v14, 0x1088, v56
	ds_write2_b32 v14, v12, v13 offset1:1
	v_or_b32_e32 v12, s78, v66
	v_cmp_gt_i32_e32 vcc, s26, v12
	v_add_u32_e32 v14, 0x14a0, v56
	s_nop 0
	v_cndmask_b32_e32 v12, 0, v52, vcc
	v_cndmask_b32_e32 v13, 0, v53, vcc
	ds_write2_b32 v14, v12, v13 offset1:1
	v_cndmask_b32_e32 v12, 0, v54, vcc
	v_cndmask_b32_e32 v13, 0, v55, vcc
	v_add_u32_e32 v14, v35, v67
	ds_write2_b32 v14, v12, v13 offset0:2 offset1:3
	v_or_b32_e32 v12, s78, v68
	v_cmp_gt_i32_e32 vcc, s26, v12
	v_add_u32_e32 v12, 0x420, v14
	s_nop 0
	v_cndmask_b32_e32 v4, 0, v4, vcc
	v_cndmask_b32_e32 v5, 0, v5, vcc
	ds_write2_b32 v12, v4, v5 offset1:1
	v_cndmask_b32_e32 v4, 0, v6, vcc
	v_cndmask_b32_e32 v5, 0, v7, vcc
	v_add_u32_e32 v6, 0x428, v14
	ds_write2_b32 v6, v4, v5 offset1:1
	v_or_b32_e32 v4, s78, v69
	v_cmp_gt_i32_e32 vcc, s26, v4
	v_add_u32_e32 v4, 0x840, v14
	s_nop 0
	v_cndmask_b32_e32 v0, 0, v0, vcc
	v_cndmask_b32_e32 v1, 0, v1, vcc
	ds_write2_b32 v4, v0, v1 offset1:1
	v_cndmask_b32_e32 v0, 0, v2, vcc
	v_cndmask_b32_e32 v1, 0, v3, vcc
	v_add_u32_e32 v2, 0x848, v14
	ds_write2_b32 v2, v0, v1 offset1:1
	s_waitcnt lgkmcnt(0)
	ds_read_b32 v0, v70
	ds_read_b32 v1, v70 offset:132
	v_lshl_add_u64 v[4:5], s[78:79], 1, v[10:11]
	s_waitcnt lgkmcnt(0)
	v_cvt_pk_bf16_f32 v0, v0, v1
	ds_read_b32 v1, v70 offset:264
	ds_read_b32 v2, v70 offset:396
	s_waitcnt lgkmcnt(0)
	v_cvt_pk_bf16_f32 v1, v1, v2
	ds_read_b32 v2, v70 offset:528
	ds_read_b32 v3, v70 offset:660
	s_waitcnt lgkmcnt(0)
	v_cvt_pk_bf16_f32 v2, v2, v3
	ds_read_b32 v3, v70 offset:792
	ds_read_b32 v6, v70 offset:924
	s_waitcnt lgkmcnt(0)
	v_cvt_pk_bf16_f32 v3, v3, v6
	v_add_u32_e32 v6, s40, v32
	v_ashrrev_i32_e32 v7, 31, v6
	v_lshlrev_b64 v[12:13], 10, v[6:7]
	v_lshl_add_u64 v[12:13], v[4:5], 0, v[12:13]
	global_store_dwordx4 v[12:13], v[0:3], off
	ds_read_b32 v0, v70 offset:32
	ds_read_b32 v1, v70 offset:164
	v_add_u32_e32 v12, 8, v6
	v_ashrrev_i32_e32 v13, 31, v12
	v_lshlrev_b64 v[12:13], 10, v[12:13]
	v_lshl_add_u64 v[12:13], v[4:5], 0, v[12:13]
	s_waitcnt lgkmcnt(0)
	v_cvt_pk_bf16_f32 v0, v0, v1
	ds_read_b32 v1, v70 offset:296
	ds_read_b32 v2, v70 offset:428
	s_waitcnt lgkmcnt(0)
	v_cvt_pk_bf16_f32 v1, v1, v2
	ds_read_b32 v2, v70 offset:560
	ds_read_b32 v3, v70 offset:692
	s_waitcnt lgkmcnt(0)
	v_cvt_pk_bf16_f32 v2, v2, v3
	ds_read_b32 v3, v70 offset:824
	ds_read_b32 v7, v70 offset:956
	s_waitcnt lgkmcnt(0)
	v_cvt_pk_bf16_f32 v3, v3, v7
	global_store_dwordx4 v[12:13], v[0:3], off
	ds_read_b32 v0, v70 offset:64
	ds_read_b32 v1, v70 offset:196
	v_add_u32_e32 v12, 16, v6
	v_ashrrev_i32_e32 v13, 31, v12
	v_lshlrev_b64 v[12:13], 10, v[12:13]
	v_lshl_add_u64 v[12:13], v[4:5], 0, v[12:13]
	s_waitcnt lgkmcnt(0)
	v_cvt_pk_bf16_f32 v0, v0, v1
	ds_read_b32 v1, v70 offset:328
	ds_read_b32 v2, v70 offset:460
	v_add_u32_e32 v6, 24, v6
	s_waitcnt lgkmcnt(0)
	v_cvt_pk_bf16_f32 v1, v1, v2
	ds_read_b32 v2, v70 offset:592
	ds_read_b32 v3, v70 offset:724
	s_waitcnt lgkmcnt(0)
	v_cvt_pk_bf16_f32 v2, v2, v3
	ds_read_b32 v3, v70 offset:856
	ds_read_b32 v7, v70 offset:988
	s_waitcnt lgkmcnt(0)
	v_cvt_pk_bf16_f32 v3, v3, v7
	global_store_dwordx4 v[12:13], v[0:3], off
	ds_read_b32 v0, v70 offset:96
	ds_read_b32 v1, v70 offset:228
	s_waitcnt lgkmcnt(0)
	v_cvt_pk_bf16_f32 v0, v0, v1
	ds_read_b32 v1, v70 offset:360
	ds_read_b32 v2, v70 offset:492
	s_waitcnt lgkmcnt(0)
	v_cvt_pk_bf16_f32 v1, v1, v2
	ds_read_b32 v2, v70 offset:624
	ds_read_b32 v3, v70 offset:756
	s_waitcnt lgkmcnt(0)
	v_cvt_pk_bf16_f32 v2, v2, v3
	ds_read_b32 v3, v70 offset:888
	ds_read_b32 v7, v70 offset:1020
	s_waitcnt lgkmcnt(0)
	v_cvt_pk_bf16_f32 v3, v3, v7
	v_ashrrev_i32_e32 v7, 31, v6
	v_lshlrev_b64 v[6:7], 10, v[6:7]
	v_lshl_add_u64 v[4:5], v[4:5], 0, v[6:7]
	global_store_dwordx4 v[4:5], v[0:3], off
	s_waitcnt lgkmcnt(0)
	s_cbranch_scc1 .LBB0_206

; __device__ __forceinline__ unsigned pk_bf16(float lo, float hi) { f32x2e v = {lo, hi}; bf16x2e b = __builtin_convertvector(v, bf16x2e); return __builtin_bit_cast(unsigned, b); }
; #define LAS __attribute__((address_space(3)))
; __device__ __forceinline__ void tr_item(const float* W, int Ksrc, int N, int k0, int n0, bf16* dst, int ldt, int drow0, int dcol0, LAS float* scr, int lane, const float* nscale = nullptr, const float* kscale = nullptr) {
;     f32x4 tv[8]; const int kr_ = lane >> 3, nq_ = lane & 7;
; #pragma unroll
;     for (int i = 0; i < 8; ++i) { const int kk = 8 * i + kr_; const int kr = (k0 + kk < Ksrc) ? (k0 + kk) : (Ksrc - 1); tv[i] = __builtin_nontemporal_load((const f32x4*)(W + (size_t)kr * N + n0 + 4 * nq_)); }
; #pragma unroll
;     for (int i = 0; i < 8; ++i) { const int kk = 8 * i + kr_; const bool ok = (k0 + kk < Ksrc); LAS float* d_ = scr + kk * 33 + 4 * nq_;
;         const float ks_ = (ok && kscale) ? kscale[k0 + kk] : 1.0f;
;         d_[0] = ok ? tv[i].x * ks_ : 0.f; d_[1] = ok ? tv[i].y * ks_ : 0.f; d_[2] = ok ? tv[i].z * ks_ : 0.f; d_[3] = ok ? tv[i].w * ks_ : 0.f; }
;     asm volatile("s_waitcnt lgkmcnt(0)" ::: "memory");
;     const int c = lane & 7;
; #pragma unroll
;     for (int j = 0; j < 4; ++j) { const int n = (lane >> 3) + 8 * j; const LAS float* s = scr + (8 * c) * 33 + n;
;         const float sc = nscale ? nscale[n0 + n] : 1.0f;
;         u32x4 o; o.x = pk_bf16(s[0 * 33] * sc, s[1 * 33] * sc); o.y = pk_bf16(s[2 * 33] * sc, s[3 * 33] * sc); o.z = pk_bf16(s[4 * 33] * sc, s[5 * 33] * sc); o.w = pk_bf16(s[6 * 33] * sc, s[7 * 33] * sc);
;         *(u32x4*)(dst + (size_t)(drow0 + n) * ldt + dcol0 + k0 + 8 * c) = o; }
;     asm volatile("s_waitcnt lgkmcnt(0)" ::: "memory");
.LBB0_209:
	s_mul_hi_i32 s2, s1, 0x2aaaaaab
	s_lshr_b32 s4, s2, 31
	s_ashr_i32 s2, s2, 4
	s_add_i32 s2, s2, s4
	s_mul_i32 s4, s2, 0xfffff400
	s_add_i32 s40, s0, s4
	s_lshl_b32 s76, s2, 6
	v_or_b32_e32 v56, s76, v32
	s_ashr_i32 s41, s40, 31
	v_lshl_add_u64 v[0:1], s[40:41], 2, v[8:9]
	v_min_i32_e32 v2, 0x1ff, v56
	v_mad_i64_i32 v[2:3], s[4:5], v2, s54, v[0:1]
	global_load_dwordx4 v[12:15], v[2:3], off nt
	v_or_b32_e32 v2, 8, v56
	v_min_i32_e32 v2, 0x1ff, v2
	v_mad_i64_i32 v[2:3], s[4:5], v2, s54, v[0:1]
	global_load_dwordx4 v[16:19], v[2:3], off nt
	v_or_b32_e32 v2, 16, v56
	v_min_i32_e32 v2, 0x1ff, v2
	v_mad_i64_i32 v[2:3], s[4:5], v2, s54, v[0:1]
	global_load_dwordx4 v[20:23], v[2:3], off nt
	v_or_b32_e32 v2, 24, v56
	v_min_i32_e32 v2, 0x1ff, v2
	v_mad_i64_i32 v[2:3], s[4:5], v2, s54, v[0:1]
	global_load_dwordx4 v[24:27], v[2:3], off nt
	v_or_b32_e32 v2, 32, v56
	v_min_i32_e32 v2, 0x1ff, v2
	v_mad_i64_i32 v[2:3], s[4:5], v2, s54, v[0:1]
	global_load_dwordx4 v[28:31], v[2:3], off nt
	v_or_b32_e32 v2, 40, v56
	v_min_i32_e32 v2, 0x1ff, v2
	v_mad_i64_i32 v[2:3], s[4:5], v2, s54, v[0:1]
	global_load_dwordx4 v[52:55], v[2:3], off nt
	v_or_b32_e32 v2, 48, v56
	v_min_i32_e32 v2, 0x1ff, v2
	v_mad_i64_i32 v[2:3], s[4:5], v2, s54, v[0:1]
	global_load_dwordx4 v[4:7], v[2:3], off nt
	v_or_b32_e32 v2, 56, v56
	v_min_i32_e32 v2, 0x1ff, v2
	v_mad_i64_i32 v[0:1], s[4:5], v2, s54, v[0:1]
	global_load_dwordx4 v[0:3], v[0:1], off nt
	v_cmp_gt_i32_e32 vcc, s26, v56
	v_add_u32_e32 v56, v35, v37
	s_ashr_i32 s77, s76, 31
	s_add_i32 s1, s1, s16
	s_add_i32 s0, s0, s27
	s_cmpk_lt_i32 s1, 0x300
	s_waitcnt vmcnt(0) lgkmcnt(0)
	v_cndmask_b32_e32 v12, 0, v12, vcc
	v_cndmask_b32_e32 v13, 0, v13, vcc
	ds_write2_b32 v56, v12, v13 offset1:1
	v_cndmask_b32_e32 v12, 0, v14, vcc
	v_cndmask_b32_e32 v13, 0, v15, vcc
	ds_write2_b32 v56, v12, v13 offset0:2 offset1:3
	v_or_b32_e32 v12, s76, v58
	v_cmp_gt_i32_e32 vcc, s26, v12
	v_add_u32_e32 v14, 0x420, v56
	s_nop 0
	v_cndmask_b32_e32 v12, 0, v16, vcc
	v_cndmask_b32_e32 v13, 0, v17, vcc
	ds_write2_b32 v14, v12, v13 offset1:1
	v_cndmask_b32_e32 v12, 0, v18, vcc
	v_cndmask_b32_e32 v13, 0, v19, vcc
	v_add_u32_e32 v14, 0x428, v56
	ds_write2_b32 v14, v12, v13 offset1:1
	v_or_b32_e32 v12, s76, v60
	v_cmp_gt_i32_e32 vcc, s26, v12
	v_add_u32_e32 v14, 0x840, v56
	s_nop 0
	v_cndmask_b32_e32 v12, 0, v20, vcc
	v_cndmask_b32_e32 v13, 0, v21, vcc
	ds_write2_b32 v14, v12, v13 offset1:1
	v_cndmask_b32_e32 v12, 0, v22, vcc
	v_cndmask_b32_e32 v13, 0, v23, vcc
	v_add_u32_e32 v14, 0x848, v56
	ds_write2_b32 v14, v12, v13 offset1:1
	v_or_b32_e32 v12, s76, v62
	v_cmp_gt_i32_e32 vcc, s26, v12
	v_add_u32_e32 v14, 0xc60, v56
	s_nop 0
	v_cndmask_b32_e32 v12, 0, v24, vcc
	v_cndmask_b32_e32 v13, 0, v25, vcc
	ds_write2_b32 v14, v12, v13 offset1:1
	v_cndmask_b32_e32 v12, 0, v26, vcc
	v_cndmask_b32_e32 v13, 0, v27, vcc
	v_add_u32_e32 v14, 0xc68, v56
	ds_write2_b32 v14, v12, v13 offset1:1
	v_or_b32_e32 v12, s76, v64
	v_cmp_gt_i32_e32 vcc, s26, v12
	v_add_u32_e32 v14, 0x1080, v56
	s_nop 0
	v_cndmask_b32_e32 v12, 0, v28, vcc
	v_cndmask_b32_e32 v13, 0, v29, vcc
	ds_write2_b32 v14, v12, v13 offset1:1
	v_cndmask_b32_e32 v12, 0, v30, vcc
	v_cndmask_b32_e32 v13, 0, v31, vcc
	v_add_u32_e32 v14, 0x1088, v56
	ds_write2_b32 v14, v12, v13 offset1:1
	v_or_b32_e32 v12, s76, v66
	v_cmp_gt_i32_e32 vcc, s26, v12
	v_add_u32_e32 v14, 0x14a0, v56
	s_nop 0
	v_cndmask_b32_e32 v12, 0, v52, vcc
	v_cndmask_b32_e32 v13, 0, v53, vcc
	ds_write2_b32 v14, v12, v13 offset1:1
	v_cndmask_b32_e32 v12, 0, v54, vcc
	v_cndmask_b32_e32 v13, 0, v55, vcc
	v_add_u32_e32 v14, v35, v67
	ds_write2_b32 v14, v12, v13 offset0:2 offset1:3
	v_or_b32_e32 v12, s76, v68
	v_cmp_gt_i32_e32 vcc, s26, v12
	v_add_u32_e32 v12, 0x420, v14
	s_nop 0
	v_cndmask_b32_e32 v4, 0, v4, vcc
	v_cndmask_b32_e32 v5, 0, v5, vcc
	ds_write2_b32 v12, v4, v5 offset1:1
	v_cndmask_b32_e32 v4, 0, v6, vcc
	v_cndmask_b32_e32 v5, 0, v7, vcc
	v_add_u32_e32 v6, 0x428, v14
	ds_write2_b32 v6, v4, v5 offset1:1
	v_or_b32_e32 v4, s76, v69
	v_cmp_gt_i32_e32 vcc, s26, v4
	v_add_u32_e32 v4, 0x840, v14
	s_nop 0
	v_cndmask_b32_e32 v0, 0, v0, vcc
	v_cndmask_b32_e32 v1, 0, v1, vcc
	ds_write2_b32 v4, v0, v1 offset1:1
	v_cndmask_b32_e32 v0, 0, v2, vcc
	v_cndmask_b32_e32 v1, 0, v3, vcc
	v_add_u32_e32 v2, 0x848, v14
	ds_write2_b32 v2, v0, v1 offset1:1
	s_waitcnt lgkmcnt(0)
	ds_read_b32 v0, v70
	ds_read_b32 v1, v70 offset:132
	v_lshl_add_u64 v[4:5], s[76:77], 1, v[10:11]
	s_waitcnt lgkmcnt(0)
	v_cvt_pk_bf16_f32 v0, v0, v1
	ds_read_b32 v1, v70 offset:264
	ds_read_b32 v2, v70 offset:396
	s_waitcnt lgkmcnt(0)
	v_cvt_pk_bf16_f32 v1, v1, v2
	ds_read_b32 v2, v70 offset:528
	ds_read_b32 v3, v70 offset:660
	s_waitcnt lgkmcnt(0)
	v_cvt_pk_bf16_f32 v2, v2, v3
	ds_read_b32 v3, v70 offset:792
	ds_read_b32 v6, v70 offset:924
	s_waitcnt lgkmcnt(0)
	v_cvt_pk_bf16_f32 v3, v3, v6
	v_add_u32_e32 v6, s40, v32
	v_ashrrev_i32_e32 v7, 31, v6
	v_lshlrev_b64 v[12:13], 10, v[6:7]
	v_lshl_add_u64 v[12:13], v[4:5], 0, v[12:13]
	global_store_dwordx4 v[12:13], v[0:3], off
	ds_read_b32 v0, v70 offset:32
	ds_read_b32 v1, v70 offset:164
	v_add_u32_e32 v12, 8, v6
	v_ashrrev_i32_e32 v13, 31, v12
	v_lshlrev_b64 v[12:13], 10, v[12:13]
	v_lshl_add_u64 v[12:13], v[4:5], 0, v[12:13]
	s_waitcnt lgkmcnt(0)
	v_cvt_pk_bf16_f32 v0, v0, v1
	ds_read_b32 v1, v70 offset:296
	ds_read_b32 v2, v70 offset:428
	s_waitcnt lgkmcnt(0)
	v_cvt_pk_bf16_f32 v1, v1, v2
	ds_read_b32 v2, v70 offset:560
	ds_read_b32 v3, v70 offset:692
	s_waitcnt lgkmcnt(0)
	v_cvt_pk_bf16_f32 v2, v2, v3
	ds_read_b32 v3, v70 offset:824
	ds_read_b32 v7, v70 offset:956
	s_waitcnt lgkmcnt(0)
	v_cvt_pk_bf16_f32 v3, v3, v7
	global_store_dwordx4 v[12:13], v[0:3], off
	ds_read_b32 v0, v70 offset:64
	ds_read_b32 v1, v70 offset:196
	v_add_u32_e32 v12, 16, v6
	v_ashrrev_i32_e32 v13, 31, v12
	v_lshlrev_b64 v[12:13], 10, v[12:13]
	v_lshl_add_u64 v[12:13], v[4:5], 0, v[12:13]
	s_waitcnt lgkmcnt(0)
	v_cvt_pk_bf16_f32 v0, v0, v1
	ds_read_b32 v1, v70 offset:328
	ds_read_b32 v2, v70 offset:460
	v_add_u32_e32 v6, 24, v6
	s_waitcnt lgkmcnt(0)
	v_cvt_pk_bf16_f32 v1, v1, v2
	ds_read_b32 v2, v70 offset:592
	ds_read_b32 v3, v70 offset:724
	s_waitcnt lgkmcnt(0)
	v_cvt_pk_bf16_f32 v2, v2, v3
	ds_read_b32 v3, v70 offset:856
	ds_read_b32 v7, v70 offset:988
	s_waitcnt lgkmcnt(0)
	v_cvt_pk_bf16_f32 v3, v3, v7
	global_store_dwordx4 v[12:13], v[0:3], off
	ds_read_b32 v0, v70 offset:96
	ds_read_b32 v1, v70 offset:228
	s_waitcnt lgkmcnt(0)
	v_cvt_pk_bf16_f32 v0, v0, v1
	ds_read_b32 v1, v70 offset:360
	ds_read_b32 v2, v70 offset:492
	s_waitcnt lgkmcnt(0)
	v_cvt_pk_bf16_f32 v1, v1, v2
	ds_read_b32 v2, v70 offset:624
	ds_read_b32 v3, v70 offset:756
	s_waitcnt lgkmcnt(0)
	v_cvt_pk_bf16_f32 v2, v2, v3
	ds_read_b32 v3, v70 offset:888
	ds_read_b32 v7, v70 offset:1020
	s_waitcnt lgkmcnt(0)
	v_cvt_pk_bf16_f32 v3, v3, v7
	v_ashrrev_i32_e32 v7, 31, v6
	v_lshlrev_b64 v[6:7], 10, v[6:7]
	v_lshl_add_u64 v[4:5], v[4:5], 0, v[6:7]
	global_store_dwordx4 v[4:5], v[0:3], off
	s_waitcnt lgkmcnt(0)
	s_cbranch_scc1 .LBB0_209

; #define LAS __attribute__((address_space(3)))
; __device__ __forceinline__ void tr_item(const float* W, int Ksrc, int N, int k0, int n0, bf16* dst, int ldt, int drow0, int dcol0, LAS float* scr, int lane, const float* nscale = nullptr, const float* kscale = nullptr) {
;     ...
;     for (int i = 0; i < 8; ++i) { const int kk = 8 * i + kr_; const int kr = (k0 + kk < Ksrc) ? (k0 + kk) : (Ksrc - 1); tv[i] = __builtin_nontemporal_load((const f32x4*)(W + (size_t)kr * N + n0 + 4 * nq_)); }
; #pragma unroll
;     for (int i = 0; i < 8; ++i) { const int kk = 8 * i + kr_; const bool ok = (k0 + kk < Ksrc); LAS float* d_ = scr + kk * 33 + 4 * nq_;
;         const float ks_ = (ok && kscale) ? kscale[k0 + kk] : 1.0f;
;         d_[0] = ok ? tv[i].x * ks_ : 0.f; d_[1] = ok ? tv[i].y * ks_ : 0.f; d_[2] = ok ? tv[i].z * ks_ : 0.f; d_[3] = ok ? tv[i].w * ks_ : 0.f; }
;     asm volatile("s_waitcnt lgkmcnt(0)" ::: "memory");
.LBB0_212:
	s_ashr_i32 s2, s1, 31
	s_lshr_b32 s2, s2, 26
	s_add_i32 s2, s1, s2
	s_lshl_b32 s4, s2, 5
	s_and_b32 s40, s2, 0xffffffc0
	s_and_b32 s4, s4, 0xfffff800
	v_or_b32_e32 v56, s40, v32
	s_sub_i32 s38, s0, s4
	v_min_i32_e32 v2, 0x7ff, v56
	s_ashr_i32 s39, s38, 31
	v_ashrrev_i32_e32 v3, 31, v2
	v_lshl_add_u64 v[0:1], s[38:39], 2, v[52:53]
	v_lshlrev_b64 v[2:3], 13, v[2:3]
	v_lshl_add_u64 v[2:3], v[0:1], 0, v[2:3]
	global_load_dwordx4 v[28:31], v[2:3], off nt
	v_or_b32_e32 v2, 8, v56
	v_min_i32_e32 v2, 0x7ff, v2
	v_ashrrev_i32_e32 v3, 31, v2
	v_lshlrev_b64 v[2:3], 13, v[2:3]
	v_lshl_add_u64 v[2:3], v[0:1], 0, v[2:3]
	global_load_dwordx4 v[24:27], v[2:3], off nt
	v_or_b32_e32 v2, 16, v56
	v_min_i32_e32 v2, 0x7ff, v2
	v_ashrrev_i32_e32 v3, 31, v2
	v_lshlrev_b64 v[2:3], 13, v[2:3]
	v_lshl_add_u64 v[2:3], v[0:1], 0, v[2:3]
	global_load_dwordx4 v[20:23], v[2:3], off nt
	v_or_b32_e32 v2, 24, v56
	v_min_i32_e32 v2, 0x7ff, v2
	v_ashrrev_i32_e32 v3, 31, v2
	v_lshlrev_b64 v[2:3], 13, v[2:3]
	v_lshl_add_u64 v[2:3], v[0:1], 0, v[2:3]
	global_load_dwordx4 v[16:19], v[2:3], off nt
	v_or_b32_e32 v2, 32, v56
	v_min_i32_e32 v2, 0x7ff, v2
	v_ashrrev_i32_e32 v3, 31, v2
	v_lshlrev_b64 v[2:3], 13, v[2:3]
	v_lshl_add_u64 v[2:3], v[0:1], 0, v[2:3]
	global_load_dwordx4 v[12:15], v[2:3], off nt
	v_or_b32_e32 v2, 40, v56
	v_min_i32_e32 v2, 0x7ff, v2
	v_ashrrev_i32_e32 v3, 31, v2
	v_lshlrev_b64 v[2:3], 13, v[2:3]
	v_lshl_add_u64 v[2:3], v[0:1], 0, v[2:3]
	global_load_dwordx4 v[8:11], v[2:3], off nt
	v_or_b32_e32 v2, 48, v56
	v_min_i32_e32 v2, 0x7ff, v2
	v_ashrrev_i32_e32 v3, 31, v2
	v_lshlrev_b64 v[2:3], 13, v[2:3]
	v_lshl_add_u64 v[2:3], v[0:1], 0, v[2:3]
	global_load_dwordx4 v[4:7], v[2:3], off nt
	v_or_b32_e32 v2, 56, v56
	v_min_i32_e32 v2, 0x7ff, v2
	v_ashrrev_i32_e32 v3, 31, v2
	v_lshlrev_b64 v[2:3], 13, v[2:3]
	v_lshl_add_u64 v[0:1], v[0:1], 0, v[2:3]
	global_load_dwordx4 v[0:3], v[0:1], off nt
	v_cmp_gt_i32_e32 vcc, s61, v56
	v_add_u32_e32 v56, v35, v37
	s_ashr_i32 s41, s40, 31
	s_add_i32 s1, s1, s16
	s_add_i32 s0, s0, s27
	s_cmpk_lt_i32 s1, 0x800
	s_waitcnt vmcnt(0) lgkmcnt(0)
	v_cndmask_b32_e32 v28, 0, v28, vcc
	v_cndmask_b32_e32 v29, 0, v29, vcc
	ds_write2_b32 v56, v28, v29 offset1:1
	v_cndmask_b32_e32 v28, 0, v30, vcc
	v_cndmask_b32_e32 v29, 0, v31, vcc
	ds_write2_b32 v56, v28, v29 offset0:2 offset1:3
	v_or_b32_e32 v28, s40, v58
	v_cmp_gt_i32_e32 vcc, s61, v28
	v_add_u32_e32 v28, 0x420, v56
	s_nop 0
	v_cndmask_b32_e32 v24, 0, v24, vcc
	v_cndmask_b32_e32 v25, 0, v25, vcc
	ds_write2_b32 v28, v24, v25 offset1:1
	v_cndmask_b32_e32 v24, 0, v26, vcc
	v_cndmask_b32_e32 v25, 0, v27, vcc
	v_add_u32_e32 v26, 0x428, v56
	ds_write2_b32 v26, v24, v25 offset1:1
	v_or_b32_e32 v24, s40, v60
	v_cmp_gt_i32_e32 vcc, s61, v24
	v_add_u32_e32 v24, 0x840, v56
	s_nop 0
	v_cndmask_b32_e32 v20, 0, v20, vcc
	v_cndmask_b32_e32 v21, 0, v21, vcc
	ds_write2_b32 v24, v20, v21 offset1:1
	v_cndmask_b32_e32 v20, 0, v22, vcc
	v_cndmask_b32_e32 v21, 0, v23, vcc
	v_add_u32_e32 v22, 0x848, v56
	ds_write2_b32 v22, v20, v21 offset1:1
	v_or_b32_e32 v20, s40, v62
	v_cmp_gt_i32_e32 vcc, s61, v20
	v_add_u32_e32 v20, 0xc60, v56
	s_nop 0
	v_cndmask_b32_e32 v16, 0, v16, vcc
	v_cndmask_b32_e32 v17, 0, v17, vcc
	ds_write2_b32 v20, v16, v17 offset1:1
	v_cndmask_b32_e32 v16, 0, v18, vcc
	v_cndmask_b32_e32 v17, 0, v19, vcc
	v_add_u32_e32 v18, 0xc68, v56
	ds_write2_b32 v18, v16, v17 offset1:1
	v_or_b32_e32 v16, s40, v64
	v_cmp_gt_i32_e32 vcc, s61, v16
	v_add_u32_e32 v16, 0x1080, v56
	s_nop 0
	v_cndmask_b32_e32 v12, 0, v12, vcc
	v_cndmask_b32_e32 v13, 0, v13, vcc
	ds_write2_b32 v16, v12, v13 offset1:1
	v_cndmask_b32_e32 v12, 0, v14, vcc
	v_cndmask_b32_e32 v13, 0, v15, vcc
	v_add_u32_e32 v14, 0x1088, v56
	ds_write2_b32 v14, v12, v13 offset1:1
	v_or_b32_e32 v12, s40, v66
	v_cmp_gt_i32_e32 vcc, s61, v12
	v_add_u32_e32 v12, 0x14a0, v56
	s_nop 0
	v_cndmask_b32_e32 v8, 0, v8, vcc
	v_cndmask_b32_e32 v9, 0, v9, vcc
	ds_write2_b32 v12, v8, v9 offset1:1
	v_cndmask_b32_e32 v8, 0, v10, vcc
	v_cndmask_b32_e32 v9, 0, v11, vcc
	v_add_u32_e32 v10, v35, v67
	ds_write2_b32 v10, v8, v9 offset0:2 offset1:3
	v_or_b32_e32 v8, s40, v68
	v_cmp_gt_i32_e32 vcc, s61, v8
	v_add_u32_e32 v8, 0x420, v10
	s_nop 0
	v_cndmask_b32_e32 v4, 0, v4, vcc
	v_cndmask_b32_e32 v5, 0, v5, vcc
	ds_write2_b32 v8, v4, v5 offset1:1
	v_cndmask_b32_e32 v4, 0, v6, vcc
	v_cndmask_b32_e32 v5, 0, v7, vcc
	v_add_u32_e32 v6, 0x428, v10
	ds_write2_b32 v6, v4, v5 offset1:1
	v_or_b32_e32 v4, s40, v69
	v_cmp_gt_i32_e32 vcc, s61, v4
	v_add_u32_e32 v4, 0x840, v10
	s_nop 0
	v_cndmask_b32_e32 v0, 0, v0, vcc
	v_cndmask_b32_e32 v1, 0, v1, vcc
	ds_write2_b32 v4, v0, v1 offset1:1
	v_cndmask_b32_e32 v0, 0, v2, vcc
	v_cndmask_b32_e32 v1, 0, v3, vcc
	v_add_u32_e32 v2, 0x848, v10
	ds_write2_b32 v2, v0, v1 offset1:1
	s_waitcnt lgkmcnt(0)
; __device__ __forceinline__ unsigned pk_bf16(float lo, float hi) { f32x2e v = {lo, hi}; bf16x2e b = __builtin_convertvector(v, bf16x2e); return __builtin_bit_cast(unsigned, b); }
; #define LAS __attribute__((address_space(3)))
; __device__ __forceinline__ void tr_item(const float* W, int Ksrc, int N, int k0, int n0, bf16* dst, int ldt, int drow0, int dcol0, LAS float* scr, int lane, const float* nscale = nullptr, const float* kscale = nullptr) {
;     ...
;     const int c = lane & 7;
; #pragma unroll
;     for (int j = 0; j < 4; ++j) { const int n = (lane >> 3) + 8 * j; const LAS float* s = scr + (8 * c) * 33 + n;
;         const float sc = nscale ? nscale[n0 + n] : 1.0f;
;         u32x4 o; o.x = pk_bf16(s[0 * 33] * sc, s[1 * 33] * sc); o.y = pk_bf16(s[2 * 33] * sc, s[3 * 33] * sc); o.z = pk_bf16(s[4 * 33] * sc, s[5 * 33] * sc); o.w = pk_bf16(s[6 * 33] * sc, s[7 * 33] * sc);
;         *(u32x4*)(dst + (size_t)(drow0 + n) * ldt + dcol0 + k0 + 8 * c) = o; }
;     asm volatile("s_waitcnt lgkmcnt(0)" ::: "memory");
	ds_read_b32 v0, v70
	ds_read_b32 v1, v70 offset:132
	v_lshl_add_u64 v[4:5], s[40:41], 1, v[54:55]
	s_waitcnt lgkmcnt(0)
	v_cvt_pk_bf16_f32 v0, v0, v1
	ds_read_b32 v1, v70 offset:264
	ds_read_b32 v2, v70 offset:396
	s_waitcnt lgkmcnt(0)
	v_cvt_pk_bf16_f32 v1, v1, v2
	ds_read_b32 v2, v70 offset:528
	ds_read_b32 v3, v70 offset:660
	s_waitcnt lgkmcnt(0)
	v_cvt_pk_bf16_f32 v2, v2, v3
	ds_read_b32 v3, v70 offset:792
	ds_read_b32 v6, v70 offset:924
	s_waitcnt lgkmcnt(0)
	v_cvt_pk_bf16_f32 v3, v3, v6
	v_add_u32_e32 v6, s38, v32
	v_ashrrev_i32_e32 v7, 31, v6
	v_lshlrev_b64 v[8:9], 12, v[6:7]
	v_lshl_add_u64 v[8:9], v[4:5], 0, v[8:9]
	global_store_dwordx4 v[8:9], v[0:3], off
	ds_read_b32 v0, v70 offset:32
	ds_read_b32 v1, v70 offset:164
	v_add_u32_e32 v8, 8, v6
	v_ashrrev_i32_e32 v9, 31, v8
	v_lshlrev_b64 v[8:9], 12, v[8:9]
	v_lshl_add_u64 v[8:9], v[4:5], 0, v[8:9]
	s_waitcnt lgkmcnt(0)
	v_cvt_pk_bf16_f32 v0, v0, v1
	ds_read_b32 v1, v70 offset:296
	ds_read_b32 v2, v70 offset:428
	s_waitcnt lgkmcnt(0)
	v_cvt_pk_bf16_f32 v1, v1, v2
	ds_read_b32 v2, v70 offset:560
	ds_read_b32 v3, v70 offset:692
	s_waitcnt lgkmcnt(0)
	v_cvt_pk_bf16_f32 v2, v2, v3
	ds_read_b32 v3, v70 offset:824
	ds_read_b32 v7, v70 offset:956
	s_waitcnt lgkmcnt(0)
	v_cvt_pk_bf16_f32 v3, v3, v7
	global_store_dwordx4 v[8:9], v[0:3], off
	ds_read_b32 v0, v70 offset:64
	ds_read_b32 v1, v70 offset:196
	v_add_u32_e32 v8, 16, v6
	v_ashrrev_i32_e32 v9, 31, v8
	v_lshlrev_b64 v[8:9], 12, v[8:9]
	v_lshl_add_u64 v[8:9], v[4:5], 0, v[8:9]
	s_waitcnt lgkmcnt(0)
	v_cvt_pk_bf16_f32 v0, v0, v1
	ds_read_b32 v1, v70 offset:328
	ds_read_b32 v2, v70 offset:460
	v_add_u32_e32 v6, 24, v6
	s_waitcnt lgkmcnt(0)
	v_cvt_pk_bf16_f32 v1, v1, v2
	ds_read_b32 v2, v70 offset:592
	ds_read_b32 v3, v70 offset:724
	s_waitcnt lgkmcnt(0)
	v_cvt_pk_bf16_f32 v2, v2, v3
	ds_read_b32 v3, v70 offset:856
	ds_read_b32 v7, v70 offset:988
	s_waitcnt lgkmcnt(0)
	v_cvt_pk_bf16_f32 v3, v3, v7
	global_store_dwordx4 v[8:9], v[0:3], off
	ds_read_b32 v0, v70 offset:96
	ds_read_b32 v1, v70 offset:228
	s_waitcnt lgkmcnt(0)
	v_cvt_pk_bf16_f32 v0, v0, v1
	ds_read_b32 v1, v70 offset:360
	ds_read_b32 v2, v70 offset:492
	s_waitcnt lgkmcnt(0)
	v_cvt_pk_bf16_f32 v1, v1, v2
	ds_read_b32 v2, v70 offset:624
	ds_read_b32 v3, v70 offset:756
	s_waitcnt lgkmcnt(0)
	v_cvt_pk_bf16_f32 v2, v2, v3
	ds_read_b32 v3, v70 offset:888
	ds_read_b32 v7, v70 offset:1020
	s_waitcnt lgkmcnt(0)
	v_cvt_pk_bf16_f32 v3, v3, v7
	v_ashrrev_i32_e32 v7, 31, v6
	v_lshlrev_b64 v[6:7], 12, v[6:7]
	v_lshl_add_u64 v[4:5], v[4:5], 0, v[6:7]
	global_store_dwordx4 v[4:5], v[0:3], off
	s_waitcnt lgkmcnt(0)
	s_cbranch_scc1 .LBB0_212
	s_branch .LBB0_134

; __device__ __forceinline__ void unpack8(const u32x4 w, float (&f)[8]) { f[0] = bflo(w.x); f[1] = bfhi(w.x); f[2] = bflo(w.y); f[3] = bfhi(w.y); f[4] = bflo(w.z); f[5] = bfhi(w.z); f[6] = bflo(w.w); f[7] = bfhi(w.w); }
; __device__ __forceinline__ void final_rows(const bf16* h16, const float* ssp, const float* g, float* out, int gw, int ngw, int lane) {
;     for (int m = gw; m < T; m += ngw) { float t = 0.f;
; #pragma unroll
;         for (int i = 0; i < 8; ++i) { const f32x4 q = *(const f32x4*)(ssp + (size_t)m * 32 + 4 * i); t += (q.x + q.y) + (q.z + q.w); }
;         const float sc = rsqrtf(t * (1.0f / D) + NORM_EPS);
; #pragma unroll
;         for (int j = 0; j < 4; ++j) { float v[8], gg[8]; unpack8(*(const u32x4*)(h16 + (size_t)m * D + (64 * j + lane) * 8), v); ld8f(g + (64 * j + lane) * 8, gg);
;             float* fp = out + (size_t)m * D + (64 * j + lane) * 8;
;             *(f32x4*)fp = (f32x4){v[0] * sc * gg[0], v[1] * sc * gg[1], v[2] * sc * gg[2], v[3] * sc * gg[3]}; *(f32x4*)(fp + 4) = (f32x4){v[4] * sc * gg[4], v[5] * sc * gg[5], v[6] * sc * gg[6], v[7] * sc * gg[7]}; } }
; }
.LBB0_218:
	s_movk_i32 s2, 0xf000
	v_add_co_u32_e32 v54, vcc, s2, v8
	s_movk_i32 s2, 0xf010
	s_nop 0
	v_addc_co_u32_e32 v55, vcc, -1, v9, vcc
	v_add_co_u32_e32 v56, vcc, s2, v8
	v_lshl_add_u64 v[18:19], s[88:89], 0, v[6:7]
	s_nop 0
	v_addc_co_u32_e32 v57, vcc, -1, v9, vcc
	s_add_u32 s1, s88, s34
	v_add_co_u32_e32 v58, vcc, s4, v18
	s_addc_u32 s2, s89, s35
	v_mov_b32_e32 v22, s1
	v_addc_co_u32_e32 v59, vcc, 0, v19, vcc
	v_add_co_u32_e32 v50, vcc, 0x35810000, v22
	v_mov_b32_e32 v22, s2
	s_nop 0
	v_addc_co_u32_e32 v51, vcc, 0, v22, vcc
	global_load_dwordx4 v[10:13], v[0:1], off
	global_load_dwordx4 v[14:17], v[0:1], off offset:16
	global_load_dwordx4 v[18:21], v[58:59], off
	global_load_dwordx4 v[22:25], v[50:51], off
	global_load_dwordx4 v[26:29], v[50:51], off offset:16
	global_load_dwordx4 v[30:33], v[50:51], off offset:32
	global_load_dwordx4 v[34:37], v[50:51], off offset:48
	global_load_dwordx4 v[38:41], v[50:51], off offset:64
	global_load_dwordx4 v[42:45], v[50:51], off offset:80
	global_load_dwordx4 v[46:49], v[50:51], off offset:96
	s_nop 0
	global_load_dwordx4 v[50:53], v[50:51], off offset:112
	s_add_i32 s0, s0, s16
	s_add_u32 s34, s34, s14
	s_addc_u32 s35, s35, s15
	v_lshl_add_u64 v[6:7], v[6:7], 0, s[8:9]
	s_cmpk_gt_i32 s0, 0x3fff
	s_waitcnt vmcnt(0) lgkmcnt(0)
	v_mov_b32_e32 v64, v22
	v_mov_b32_e32 v65, v26
	v_mov_b32_e32 v26, v23
	v_mov_b32_e32 v22, v24
	v_mov_b32_e32 v23, v28
	v_mov_b32_e32 v28, v25
	v_mov_b32_e32 v24, v31
	v_mov_b32_e32 v25, v32
	v_mov_b32_e32 v31, v33
	v_pk_add_f32 v[26:27], v[64:65], v[26:27]
	v_pk_add_f32 v[22:23], v[22:23], v[28:29]
	v_pk_add_f32 v[24:25], v[24:25], v[30:31]
	v_pk_add_f32 v[22:23], v[26:27], v[22:23]
	v_pk_add_f32 v[24:25], v[24:25], v[24:25] op_sel:[0,1] op_sel_hi:[1,0]
	v_add_f32_e32 v22, 0, v22
	v_add_f32_e32 v32, v34, v35
	v_add_f32_e32 v34, v36, v37
	v_mov_b32_e32 v37, v38
	v_mov_b32_e32 v33, v40
	v_mov_b32_e32 v35, v41
	v_mov_b32_e32 v25, v39
	v_add_f32_e32 v36, v22, v23
	v_mov_b32_e32 v40, v43
	v_mov_b32_e32 v41, v44
	v_mov_b32_e32 v43, v45
	v_pk_add_f32 v[28:29], v[32:33], v[34:35]
	v_pk_add_f32 v[22:23], v[36:37], v[24:25]
	v_pk_add_f32 v[30:31], v[40:41], v[42:43]
	v_pk_add_f32 v[22:23], v[22:23], v[28:29]
	v_pk_add_f32 v[26:27], v[30:31], v[30:31] op_sel:[0,1] op_sel_hi:[1,0]
	v_pk_add_f32 v[22:23], v[22:23], v[22:23] op_sel:[0,1] op_sel_hi:[1,0]
	v_add_f32_e32 v44, v46, v47
	v_add_f32_e32 v46, v48, v49
	v_mov_b32_e32 v45, v52
	v_mov_b32_e32 v47, v53
	v_mov_b32_e32 v27, v51
	v_mov_b32_e32 v23, v50
	v_pk_add_f32 v[32:33], v[44:45], v[46:47]
	v_pk_add_f32 v[22:23], v[22:23], v[26:27]
	v_lshlrev_b32_e32 v60, 16, v18
	v_pk_add_f32 v[22:23], v[22:23], v[32:33]
	v_and_b32_e32 v61, 0xffff0000, v18
	v_add_f32_e32 v22, v22, v23
	v_fmamk_f32 v22, v22, 0x3a000000, v218
	v_mul_f32_e32 v23, 0x4b800000, v22
	v_cmp_gt_f32_e32 vcc, s12, v22
	v_lshlrev_b32_e32 v18, 16, v19
	v_and_b32_e32 v19, 0xffff0000, v19
	v_cndmask_b32_e32 v22, v22, v23, vcc
	v_rsq_f32_e32 v22, v22
	v_lshlrev_b32_e32 v62, 16, v20
	v_and_b32_e32 v63, 0xffff0000, v20
	v_lshlrev_b32_e32 v20, 16, v21
	v_mul_f32_e32 v23, 0x45800000, v22
	v_cndmask_b32_e32 v22, v22, v23, vcc
	v_and_b32_e32 v21, 0xffff0000, v21
	v_pk_mul_f32 v[24:25], v[22:23], v[60:61] op_sel_hi:[0,1]
	v_pk_mul_f32 v[18:19], v[22:23], v[18:19] op_sel_hi:[0,1]
	v_pk_mul_f32 v[26:27], v[22:23], v[62:63] op_sel_hi:[0,1]
	v_pk_mul_f32 v[20:21], v[22:23], v[20:21] op_sel_hi:[0,1]
	v_pk_mul_f32 v[10:11], v[10:11], v[24:25]
	v_pk_mul_f32 v[12:13], v[12:13], v[18:19]
	v_pk_mul_f32 v[14:15], v[14:15], v[26:27]
	v_pk_mul_f32 v[16:17], v[16:17], v[20:21]
	global_store_dwordx4 v[54:55], v[10:13], off
	global_store_dwordx4 v[56:57], v[14:17], off
	global_load_dwordx4 v[10:13], v[58:59], off offset:1024
	s_nop 0
	global_load_dwordx4 v[14:17], v[0:1], off offset:2048
	global_load_dwordx4 v[18:21], v[0:1], off offset:2064
	v_add_co_u32_e32 v24, vcc, s5, v8
	s_waitcnt vmcnt(0) lgkmcnt(0)
	v_lshlrev_b32_e32 v28, 16, v10
	v_and_b32_e32 v29, 0xffff0000, v10
	v_lshlrev_b32_e32 v10, 16, v11
	v_and_b32_e32 v11, 0xffff0000, v11
	v_addc_co_u32_e32 v25, vcc, -1, v9, vcc
	v_lshlrev_b32_e32 v30, 16, v12
	v_and_b32_e32 v31, 0xffff0000, v12
	v_lshlrev_b32_e32 v12, 16, v13
	v_and_b32_e32 v13, 0xffff0000, v13
	v_pk_mul_f32 v[28:29], v[22:23], v[28:29] op_sel_hi:[0,1]
	v_pk_mul_f32 v[32:33], v[22:23], v[10:11] op_sel_hi:[0,1]
	v_add_co_u32_e32 v26, vcc, s6, v8
	v_pk_mul_f32 v[30:31], v[22:23], v[30:31] op_sel_hi:[0,1]
	v_pk_mul_f32 v[34:35], v[22:23], v[12:13] op_sel_hi:[0,1]
	v_pk_mul_f32 v[10:11], v[14:15], v[28:29]
	v_pk_mul_f32 v[12:13], v[16:17], v[32:33]
	v_addc_co_u32_e32 v27, vcc, -1, v9, vcc
	v_pk_mul_f32 v[14:15], v[18:19], v[30:31]
	v_pk_mul_f32 v[16:17], v[20:21], v[34:35]
	global_store_dwordx4 v[24:25], v[10:13], off
	global_store_dwordx4 v[26:27], v[14:17], off
	global_load_dwordx4 v[10:13], v[58:59], off offset:2048
	s_nop 0
	global_load_dwordx4 v[14:17], v[2:3], off
	global_load_dwordx4 v[18:21], v[2:3], off offset:16
	s_waitcnt vmcnt(0) lgkmcnt(0)
	v_lshlrev_b32_e32 v24, 16, v10
	v_and_b32_e32 v25, 0xffff0000, v10
	v_lshlrev_b32_e32 v10, 16, v11
	v_and_b32_e32 v11, 0xffff0000, v11
	v_lshlrev_b32_e32 v26, 16, v12
	v_and_b32_e32 v27, 0xffff0000, v12
	v_lshlrev_b32_e32 v12, 16, v13
	v_and_b32_e32 v13, 0xffff0000, v13
	v_pk_mul_f32 v[24:25], v[22:23], v[24:25] op_sel_hi:[0,1]
	v_pk_mul_f32 v[28:29], v[22:23], v[10:11] op_sel_hi:[0,1]
	v_pk_mul_f32 v[26:27], v[22:23], v[26:27] op_sel_hi:[0,1]
	v_pk_mul_f32 v[30:31], v[22:23], v[12:13] op_sel_hi:[0,1]
	v_pk_mul_f32 v[10:11], v[14:15], v[24:25]
	v_pk_mul_f32 v[12:13], v[16:17], v[28:29]
	v_pk_mul_f32 v[14:15], v[18:19], v[26:27]
	v_pk_mul_f32 v[16:17], v[20:21], v[30:31]
	global_store_dwordx4 v[8:9], v[10:13], off
	global_store_dwordx4 v[8:9], v[14:17], off offset:16
	global_load_dwordx4 v[10:13], v[58:59], off offset:3072
	s_nop 0
	global_load_dwordx4 v[14:17], v[4:5], off
	global_load_dwordx4 v[18:21], v[4:5], off offset:16
	s_waitcnt vmcnt(0) lgkmcnt(0)
	v_lshlrev_b32_e32 v24, 16, v10
	v_and_b32_e32 v25, 0xffff0000, v10
	v_lshlrev_b32_e32 v10, 16, v11
	v_and_b32_e32 v11, 0xffff0000, v11
	v_lshlrev_b32_e32 v26, 16, v12
	v_and_b32_e32 v27, 0xffff0000, v12
	v_lshlrev_b32_e32 v12, 16, v13
	v_and_b32_e32 v13, 0xffff0000, v13
	v_pk_mul_f32 v[24:25], v[22:23], v[24:25] op_sel_hi:[0,1]
	v_pk_mul_f32 v[28:29], v[22:23], v[10:11] op_sel_hi:[0,1]
	v_pk_mul_f32 v[26:27], v[22:23], v[26:27] op_sel_hi:[0,1]
	v_pk_mul_f32 v[22:23], v[22:23], v[12:13] op_sel_hi:[0,1]
	v_pk_mul_f32 v[10:11], v[14:15], v[24:25]
	v_pk_mul_f32 v[12:13], v[16:17], v[28:29]
	v_pk_mul_f32 v[14:15], v[18:19], v[26:27]
	v_pk_mul_f32 v[16:17], v[20:21], v[22:23]
	global_store_dwordx4 v[8:9], v[10:13], off offset:2048
	global_store_dwordx4 v[8:9], v[14:17], off offset:2064
	v_lshl_add_u64 v[8:9], v[8:9], 0, s[44:45]
	s_cbranch_scc0 .LBB0_218

; __device__ __forceinline__ unsigned pk_bf16(float lo, float hi) { f32x2e v = {lo, hi}; bf16x2e b = __builtin_convertvector(v, bf16x2e); return __builtin_bit_cast(unsigned, b); }
; __device__ __forceinline__ void attn_phase(LAS unsigned char* lds, const bf16* Q, const bf16* KV, const bf16* KPE, const float* rope, bf16* mix, int bid, int G, int tid) {
;     ...
;         const float ltot = lrun + __shfl_xor(lrun, 32); const float inv = 1.0f / ltot;
;         bf16* op = mix + (size_t)qrow * D + 512 + h * 128 + 4 * hh;
; #pragma unroll
;         for (int dvt = 0; dvt < 4; ++dvt)
; #pragma unroll
;             for (int g4 = 0; g4 < 4; ++g4) { u32x2 w; w.x = pk_bf16(O[dvt][4 * g4] * inv, O[dvt][4 * g4 + 1] * inv); w.y = pk_bf16(O[dvt][4 * g4 + 2] * inv, O[dvt][4 * g4 + 3] * inv);
;                 *(u32x2*)(op + dvt * 32 + 8 * g4) = w; }
.LBB0_239:
	v_and_b32_e32 v65, 64, v220
	v_xor_b32_e32 v64, 32, v220
	v_add_u32_e32 v65, 64, v65
	v_cmp_lt_i32_e32 vcc, v64, v65
	v_lshlrev_b32_e32 v96, 1, v189
	s_nop 0
	v_cndmask_b32_e32 v64, v220, v64, vcc
	v_lshlrev_b32_e32 v64, 2, v64
	ds_bpermute_b32 v64, v64, v207
	s_waitcnt lgkmcnt(0)
	v_add_f32_e32 v66, v207, v64
	v_div_scale_f32 v67, s[0:1], v66, v66, 1.0
	v_rcp_f32_e32 v68, v67
	v_div_scale_f32 v69, vcc, 1.0, v66, 1.0
	v_readlane_b32 s0, v254, 57
	v_fma_f32 v70, -v67, v68, 1.0
	v_fmac_f32_e32 v68, v70, v68
	v_mul_f32_e32 v70, v69, v68
	v_fma_f32 v71, -v67, v70, v69
	v_fmac_f32_e32 v70, v71, v68
	v_lshlrev_b64 v[64:65], 12, v[174:175]
	v_fma_f32 v67, -v67, v70, v69
	v_readlane_b32 s1, v254, 58
	v_div_fmas_f32 v67, v67, v68, v70
	v_div_fixup_f32 v66, v67, v66, 1.0
	v_lshl_add_u64 v[64:65], s[0:1], 0, v[64:65]
	s_lshl_b32 s0, s7, 7
	s_ashr_i32 s1, s0, 31
	v_lshl_add_u64 v[64:65], s[0:1], 1, v[64:65]
	v_pk_mul_f32 v[48:49], v[48:49], v[66:67] op_sel_hi:[1,0]
	v_pk_mul_f32 v[50:51], v[50:51], v[66:67] op_sel_hi:[1,0]
	v_pk_mul_f32 v[32:33], v[32:33], v[66:67] op_sel_hi:[1,0]
	v_pk_mul_f32 v[34:35], v[34:35], v[66:67] op_sel_hi:[1,0]
	v_pk_mul_f32 v[16:17], v[16:17], v[66:67] op_sel_hi:[1,0]
	v_pk_mul_f32 v[18:19], v[18:19], v[66:67] op_sel_hi:[1,0]
	v_pk_mul_f32 v[0:1], v[0:1], v[66:67] op_sel_hi:[1,0]
	v_pk_mul_f32 v[2:3], v[2:3], v[66:67] op_sel_hi:[1,0]
	v_lshl_add_u64 v[64:65], v[64:65], 0, v[96:97]
	v_cvt_pk_bf16_f32 v48, v48, v49
	v_cvt_pk_bf16_f32 v49, v50, v51
	v_cvt_pk_bf16_f32 v32, v32, v33
	v_cvt_pk_bf16_f32 v33, v34, v35
	v_cvt_pk_bf16_f32 v16, v16, v17
	v_cvt_pk_bf16_f32 v17, v18, v19
	v_cvt_pk_bf16_f32 v0, v0, v1
	v_cvt_pk_bf16_f32 v1, v2, v3
	global_store_dwordx2 v[64:65], v[48:49], off offset:1024
	v_pk_mul_f32 v[48:49], v[52:53], v[66:67] op_sel_hi:[1,0]
	v_pk_mul_f32 v[50:51], v[54:55], v[66:67] op_sel_hi:[1,0]
	global_store_dwordx2 v[64:65], v[32:33], off offset:1088
	v_pk_mul_f32 v[32:33], v[36:37], v[66:67] op_sel_hi:[1,0]
	v_pk_mul_f32 v[34:35], v[38:39], v[66:67] op_sel_hi:[1,0]
	global_store_dwordx2 v[64:65], v[16:17], off offset:1152
	v_pk_mul_f32 v[16:17], v[20:21], v[66:67] op_sel_hi:[1,0]
	v_pk_mul_f32 v[18:19], v[22:23], v[66:67] op_sel_hi:[1,0]
	global_store_dwordx2 v[64:65], v[0:1], off offset:1216
	v_pk_mul_f32 v[0:1], v[4:5], v[66:67] op_sel_hi:[1,0]
	v_pk_mul_f32 v[2:3], v[6:7], v[66:67] op_sel_hi:[1,0]
	v_cvt_pk_bf16_f32 v48, v48, v49
	v_cvt_pk_bf16_f32 v49, v50, v51
	v_cvt_pk_bf16_f32 v32, v32, v33
	v_cvt_pk_bf16_f32 v33, v34, v35
	v_cvt_pk_bf16_f32 v16, v16, v17
	v_cvt_pk_bf16_f32 v17, v18, v19
	v_cvt_pk_bf16_f32 v0, v0, v1
	v_cvt_pk_bf16_f32 v1, v2, v3
	global_store_dwordx2 v[64:65], v[48:49], off offset:1040
	v_pk_mul_f32 v[48:49], v[56:57], v[66:67] op_sel_hi:[1,0]
	v_pk_mul_f32 v[50:51], v[58:59], v[66:67] op_sel_hi:[1,0]
	global_store_dwordx2 v[64:65], v[32:33], off offset:1104
	v_pk_mul_f32 v[32:33], v[40:41], v[66:67] op_sel_hi:[1,0]
	v_pk_mul_f32 v[34:35], v[42:43], v[66:67] op_sel_hi:[1,0]
	global_store_dwordx2 v[64:65], v[16:17], off offset:1168
	v_pk_mul_f32 v[16:17], v[24:25], v[66:67] op_sel_hi:[1,0]
	v_pk_mul_f32 v[18:19], v[26:27], v[66:67] op_sel_hi:[1,0]
	global_store_dwordx2 v[64:65], v[0:1], off offset:1232
	v_pk_mul_f32 v[0:1], v[8:9], v[66:67] op_sel_hi:[1,0]
	v_pk_mul_f32 v[2:3], v[10:11], v[66:67] op_sel_hi:[1,0]
	v_cvt_pk_bf16_f32 v48, v48, v49
	v_cvt_pk_bf16_f32 v49, v50, v51
	v_cvt_pk_bf16_f32 v32, v32, v33
	v_cvt_pk_bf16_f32 v33, v34, v35
	v_cvt_pk_bf16_f32 v16, v16, v17
	v_cvt_pk_bf16_f32 v17, v18, v19
	v_cvt_pk_bf16_f32 v0, v0, v1
	v_cvt_pk_bf16_f32 v1, v2, v3
	global_store_dwordx2 v[64:65], v[48:49], off offset:1056
	v_pk_mul_f32 v[48:49], v[60:61], v[66:67] op_sel_hi:[1,0]
	v_pk_mul_f32 v[50:51], v[62:63], v[66:67] op_sel_hi:[1,0]
	global_store_dwordx2 v[64:65], v[32:33], off offset:1120
	v_pk_mul_f32 v[32:33], v[44:45], v[66:67] op_sel_hi:[1,0]
	v_pk_mul_f32 v[34:35], v[46:47], v[66:67] op_sel_hi:[1,0]
	global_store_dwordx2 v[64:65], v[16:17], off offset:1184
	v_pk_mul_f32 v[16:17], v[28:29], v[66:67] op_sel_hi:[1,0]
	v_pk_mul_f32 v[18:19], v[30:31], v[66:67] op_sel_hi:[1,0]
	global_store_dwordx2 v[64:65], v[0:1], off offset:1248
	v_pk_mul_f32 v[0:1], v[12:13], v[66:67] op_sel_hi:[1,0]
	v_pk_mul_f32 v[2:3], v[14:15], v[66:67] op_sel_hi:[1,0]
	v_cvt_pk_bf16_f32 v48, v48, v49
	v_cvt_pk_bf16_f32 v49, v50, v51
	v_cvt_pk_bf16_f32 v32, v32, v33
	v_cvt_pk_bf16_f32 v33, v34, v35
	v_cvt_pk_bf16_f32 v16, v16, v17
	v_cvt_pk_bf16_f32 v17, v18, v19
	v_cvt_pk_bf16_f32 v0, v0, v1
	v_cvt_pk_bf16_f32 v1, v2, v3
	global_store_dwordx2 v[64:65], v[48:49], off offset:1072
	global_store_dwordx2 v[64:65], v[32:33], off offset:1136
	global_store_dwordx2 v[64:65], v[16:17], off offset:1200
	global_store_dwordx2 v[64:65], v[0:1], off offset:1264

; __device__ __forceinline__ void unpack8(const u32x4 w, float (&f)[8]) { f[0] = bflo(w.x); f[1] = bfhi(w.x); f[2] = bflo(w.y); f[3] = bfhi(w.y); f[4] = bflo(w.z); f[5] = bfhi(w.z); f[6] = bflo(w.w); f[7] = bfhi(w.w); }
; __device__ __forceinline__ void attn_phase(LAS unsigned char* lds, const bf16* Q, const bf16* KV, const bf16* KPE, const float* rope, bf16* mix, int bid, int G, int tid) {
;     ...
;     for (int round = 0; round * G < AT_UNITS; ++round) {
;         int idx;
;         if (G == 256) { const int i2 = bid >> 1, od = bid & 1;
;             idx = (round == 0) ? bid : (round == 1 ? 256 + (od ? 127 - i2 : 255 - i2) : 512 + (od ? 255 - i2 : 127 - i2)); }
;         else idx = (round & 1) ? (round * G + (G - 1 - bid)) : (round * G + bid);
;         if (idx >= AT_UNITS) continue;
;         int tid_r = tid; asm volatile("" : "+v"(tid_r));
;         const int lane = tid_r & 63, l32 = lane & 31, hh = lane >> 5;
;         const int sr16 = tid_r >> 4, sc16 = tid_r & 15, sr8 = tid_r >> 3, sc8 = tid_r & 7;
;         const int qb = 15 - idx / 48, bh = idx % 48, b = bh / 12, h = bh - b * 12;
;         const int q0 = qb * 256, mrow0 = b * SEQ, ntiles = (qb + 1) * 4;
;         const int qrow = mrow0 + q0 + wid * 32 + l32;
;         bf16x8 qf[12];
;         { const bf16* qp = Q + (size_t)qrow * 2304 + h * 192 + hh * 8; const float* rp = rope + (size_t)qrow * 64;
; #pragma unroll
;           for (int ks = 0; ks < 8; ++ks) { float f[8]; unpack8(*(const u32x4*)(qp + ks * 16), f);
; #pragma unroll
;               for (int e = 0; e < 8; ++e) f[e] *= qs;
;               qf[ks] = __builtin_bit_cast(bf16x8, pack8(f)); if (ks & 1) asm volatile("" ::: "memory"); }
; #pragma unroll
;           for (int ks = 8; ks < 10; ++ks) { float f1[8], f2[8], o1[8], o2[8]; unpack8(*(const u32x4*)(qp + ks * 16), f1); unpack8(*(const u32x4*)(qp + (ks + 2) * 16), f2);
; #pragma unroll
;               for (int e = 0; e < 8; ++e) { const int i = (ks - 8) * 16 + hh * 8 + e; const float cs = rp[2 * i], sn = rp[2 * i + 1];
;                   o1[e] = (f1[e] * cs - f2[e] * sn) * qs; o2[e] = (f1[e] * sn + f2[e] * cs) * qs; }
;               qf[ks] = __builtin_bit_cast(bf16x8, pack8(o1)); qf[ks + 2] = __builtin_bit_cast(bf16x8, pack8(o2)); asm volatile("" ::: "memory"); } }
.LBB0_249:
	s_cmpk_gt_i32 s4, 0x2ff
	s_cbranch_scc1 .LBB0_240
	s_mul_hi_i32 s0, s4, 0xd5555555
	s_lshr_b32 s1, s0, 31
	s_ashr_i32 s0, s0, 3
	s_add_i32 s1, s0, s1
	s_mul_hi_i32 s0, s4, 0x2aaaaaab
	s_lshr_b32 s5, s0, 31
	s_lshr_b32 s0, s0, 3
	s_add_i32 s0, s0, s5
	s_mul_i32 s0, s0, 48
	s_sub_i32 s4, s4, s0
	s_mul_i32 s0, s4, 43
	s_sext_i32_i16 s5, s0
	s_lshr_b32 s5, s5, 9
	s_bfe_u32 s0, s0, 0x1000f
	s_add_i32 s5, s5, s0
	s_sext_i32_i16 s0, s5
	s_mul_i32 s7, s0, -12
	s_add_i32 s7, s7, s4
	s_lshl_b32 s4, s1, 8
	s_waitcnt vmcnt(0)
	v_mov_b32_e32 v23, v186
	s_lshl_b32 s34, s0, 12
	s_add_i32 s8, s2, s4
	s_add_i32 s4, s34, s8
	v_and_b32_e32 v22, 31, v23
	v_or_b32_e32 v174, s4, v22
	v_readlane_b32 s4, v255, 1
	v_readlane_b32 s5, v255, 2
	v_bfe_u32 v24, v23, 5, 1
	v_lshlrev_b32_e32 v96, 4, v24
	s_waitcnt lgkmcnt(0)
	v_mov_b64_e32 v[0:1], s[4:5]
	s_movk_i32 s4, 0x1200
	v_mad_i64_i32 v[0:1], s[4:5], v174, s4, v[0:1]
	s_mul_i32 s4, s7, 0xc0
	s_ashr_i32 s5, s4, 31
	v_lshl_add_u64 v[0:1], s[4:5], 1, v[0:1]
	v_lshl_add_u64 v[4:5], v[0:1], 0, v[96:97]
	global_load_dwordx4 v[6:9], v[4:5], off
	global_load_dwordx4 v[10:13], v[4:5], off offset:32
	global_load_dwordx4 v[14:17], v[4:5], off offset:64
	global_load_dwordx4 v[26:29], v[4:5], off offset:96
	global_load_dwordx4 v[30:33], v[4:5], off offset:128
	global_load_dwordx4 v[34:37], v[4:5], off offset:160
	s_mov_b32 s28, 0x3dd53b94
	v_ashrrev_i32_e32 v175, 31, v174
	v_lshlrev_b64 v[18:19], 8, v[174:175]
	global_load_dwordx4 v[38:41], v[4:5], off offset:192
	global_load_dwordx4 v[0:3], v[4:5], off offset:224
	s_lshl_b32 s9, s1, 2
	s_add_i32 s9, s9, 64
	s_ashr_i32 s35, s34, 31
	s_mul_i32 s17, s0, 0x1800000
	v_readlane_b32 s0, v255, 5
	s_mul_hi_i32 s19, s34, 0x1800
	v_readlane_b32 s1, v255, 6
	s_add_u32 s4, s0, s17
	s_addc_u32 s5, s1, s19
	s_lshl_b32 s0, s7, 8
	s_ashr_i32 s1, s0, 31
	v_ashrrev_i32_e32 v25, 4, v23
	s_lshl_b64 s[0:1], s[0:1], 1
	s_movk_i32 s11, 0x1800
	s_add_u32 s14, s4, s0
	s_addc_u32 s15, s5, s1
	s_lshl_b64 s[4:5], s[34:35], 7
	v_readlane_b32 s30, v255, 3
	v_readlane_b32 s31, v255, 4
	s_add_u32 s30, s30, s4
	s_addc_u32 s31, s31, s5
	v_lshlrev_b32_e32 v189, 2, v24
	v_mul_u32_u24_e32 v203, 0x190, v22
	v_or_b32_e32 v206, s8, v22
	v_mov_b32_e32 v184, 0xf149f2ca
	v_mov_b32_e32 v207, 0
	s_waitcnt vmcnt(0) lgkmcnt(0)
	v_lshlrev_b32_e32 v42, 16, v8
	v_and_b32_e32 v43, 0xffff0000, v8
	v_lshlrev_b32_e32 v8, 16, v9
	v_and_b32_e32 v9, 0xffff0000, v9
	v_lshlrev_b32_e32 v44, 16, v10
	v_and_b32_e32 v45, 0xffff0000, v10
	v_lshlrev_b32_e32 v10, 16, v11
	v_and_b32_e32 v11, 0xffff0000, v11
	v_pk_mul_f32 v[8:9], v[8:9], s[28:29] op_sel_hi:[1,0]
	v_lshlrev_b32_e32 v48, 16, v14
	v_and_b32_e32 v49, 0xffff0000, v14
	v_lshlrev_b32_e32 v14, 16, v15
	v_and_b32_e32 v15, 0xffff0000, v15
	v_pk_mul_f32 v[10:11], v[10:11], s[28:29] op_sel_hi:[1,0]
	v_lshlrev_b32_e32 v50, 16, v16
	v_and_b32_e32 v51, 0xffff0000, v16
	v_cvt_pk_bf16_f32 v101, v8, v9
	v_pk_mul_f32 v[8:9], v[14:15], s[28:29] op_sel_hi:[1,0]
	v_lshlrev_b32_e32 v20, 16, v6
	v_and_b32_e32 v21, 0xffff0000, v6
	v_lshlrev_b32_e32 v46, 16, v12
	v_and_b32_e32 v47, 0xffff0000, v12
	v_lshlrev_b32_e32 v12, 16, v13
	v_and_b32_e32 v13, 0xffff0000, v13
	v_cvt_pk_bf16_f32 v103, v10, v11
	v_pk_mul_f32 v[10:11], v[50:51], s[28:29] op_sel_hi:[1,0]
	v_cvt_pk_bf16_f32 v107, v8, v9
	v_lshlrev_b32_e32 v8, 16, v27
	v_and_b32_e32 v9, 0xffff0000, v27
	v_pk_mul_f32 v[20:21], v[20:21], s[28:29] op_sel_hi:[1,0]
	v_pk_mul_f32 v[12:13], v[12:13], s[28:29] op_sel_hi:[1,0]
	v_lshlrev_b32_e32 v16, 16, v17
	v_and_b32_e32 v17, 0xffff0000, v17
	v_lshlrev_b32_e32 v52, 16, v26
	v_and_b32_e32 v53, 0xffff0000, v26
	v_cvt_pk_bf16_f32 v108, v10, v11
	v_pk_mul_f32 v[26:27], v[8:9], s[28:29] op_sel_hi:[1,0]
	v_lshl_add_u64 v[8:9], s[56:57], 0, v[18:19]
	v_lshlrev_b32_e32 v10, 6, v24
	v_mov_b32_e32 v11, v97
	v_cvt_pk_bf16_f32 v98, v20, v21
	v_cvt_pk_bf16_f32 v105, v12, v13
	v_pk_mul_f32 v[12:13], v[16:17], s[28:29] op_sel_hi:[1,0]
	v_lshl_add_u64 v[20:21], v[8:9], 0, v[10:11]
	v_cvt_pk_bf16_f32 v109, v12, v13
	global_load_dwordx4 v[16:19], v[20:21], off
	global_load_dwordx4 v[8:11], v[4:5], off offset:256
	global_load_dwordx4 v[12:15], v[4:5], off offset:320
	v_lshlrev_b32_e32 v6, 16, v7
	v_and_b32_e32 v7, 0xffff0000, v7
	v_pk_mul_f32 v[6:7], v[6:7], s[28:29] op_sel_hi:[1,0]
	v_pk_mul_f32 v[42:43], v[42:43], s[28:29] op_sel_hi:[1,0]
	v_cvt_pk_bf16_f32 v99, v6, v7
	v_pk_mul_f32 v[6:7], v[48:49], s[28:29] op_sel_hi:[1,0]
	v_cvt_pk_bf16_f32 v100, v42, v43
	v_cvt_pk_bf16_f32 v106, v6, v7
	v_pk_mul_f32 v[6:7], v[52:53], s[28:29] op_sel_hi:[1,0]
	v_lshlrev_b32_e32 v42, 16, v28
	v_and_b32_e32 v43, 0xffff0000, v28
	v_cvt_pk_bf16_f32 v111, v26, v27
	v_lshlrev_b32_e32 v26, 16, v31
	v_and_b32_e32 v27, 0xffff0000, v31
	v_pk_mul_f32 v[42:43], v[42:43], s[28:29] op_sel_hi:[1,0]
	v_lshlrev_b32_e32 v28, 16, v29
	v_and_b32_e32 v29, 0xffff0000, v29
	v_cvt_pk_bf16_f32 v110, v6, v7
	v_lshlrev_b32_e32 v6, 16, v30
	v_and_b32_e32 v7, 0xffff0000, v30
	v_pk_mul_f32 v[30:31], v[26:27], s[28:29] op_sel_hi:[1,0]
	v_lshlrev_b32_e32 v26, 16, v32
	v_and_b32_e32 v27, 0xffff0000, v32
	v_pk_mul_f32 v[28:29], v[28:29], s[28:29] op_sel_hi:[1,0]
	v_cvt_pk_bf16_f32 v112, v42, v43
	v_pk_mul_f32 v[6:7], v[6:7], s[28:29] op_sel_hi:[1,0]
	v_pk_mul_f32 v[42:43], v[26:27], s[28:29] op_sel_hi:[1,0]
	v_lshlrev_b32_e32 v26, 16, v33
	v_and_b32_e32 v27, 0xffff0000, v33
	v_cvt_pk_bf16_f32 v113, v28, v29
	v_pk_mul_f32 v[32:33], v[26:27], s[28:29] op_sel_hi:[1,0]
	global_load_dwordx4 v[26:29], v[20:21], off offset:16
	v_cvt_pk_bf16_f32 v114, v6, v7
	v_cvt_pk_bf16_f32 v115, v30, v31
	v_lshlrev_b32_e32 v6, 16, v34
	v_and_b32_e32 v7, 0xffff0000, v34
; __device__ __forceinline__ void unpack8(const u32x4 w, float (&f)[8]) { f[0] = bflo(w.x); f[1] = bfhi(w.x); f[2] = bflo(w.y); f[3] = bfhi(w.y); f[4] = bflo(w.z); f[5] = bfhi(w.z); f[6] = bflo(w.w); f[7] = bfhi(w.w); }
; __device__ __forceinline__ u32x4 pack8(const float (&f)[8]) { u32x4 w; w.x = pk_bf16(f[0], f[1]); w.y = pk_bf16(f[2], f[3]); w.z = pk_bf16(f[4], f[5]); w.w = pk_bf16(f[6], f[7]); return w; }
; __device__ __forceinline__ void attn_phase(LAS unsigned char* lds, const bf16* Q, const bf16* KV, const bf16* KPE, const float* rope, bf16* mix, int bid, int G, int tid) {
;     ...
;         { const bf16* qp = Q + (size_t)qrow * 2304 + h * 192 + hh * 8; const float* rp = rope + (size_t)qrow * 64;
; #pragma unroll
;           for (int ks = 0; ks < 8; ++ks) { float f[8]; unpack8(*(const u32x4*)(qp + ks * 16), f);
; #pragma unroll
;               for (int e = 0; e < 8; ++e) f[e] *= qs;
;               qf[ks] = __builtin_bit_cast(bf16x8, pack8(f)); if (ks & 1) asm volatile("" ::: "memory"); }
; #pragma unroll
;           for (int ks = 8; ks < 10; ++ks) { float f1[8], f2[8], o1[8], o2[8]; unpack8(*(const u32x4*)(qp + ks * 16), f1); unpack8(*(const u32x4*)(qp + (ks + 2) * 16), f2);
; #pragma unroll
;               for (int e = 0; e < 8; ++e) { const int i = (ks - 8) * 16 + hh * 8 + e; const float cs = rp[2 * i], sn = rp[2 * i + 1];
;                   o1[e] = (f1[e] * cs - f2[e] * sn) * qs; o2[e] = (f1[e] * sn + f2[e] * cs) * qs; }
;               qf[ks] = __builtin_bit_cast(bf16x8, pack8(o1)); qf[ks + 2] = __builtin_bit_cast(bf16x8, pack8(o2)); asm volatile("" ::: "memory"); } }
	v_lshlrev_b32_e32 v30, 16, v35
	v_and_b32_e32 v31, 0xffff0000, v35
	v_lshlrev_b32_e32 v34, 16, v37
	v_and_b32_e32 v35, 0xffff0000, v37
	v_cvt_pk_bf16_f32 v117, v32, v33
	v_pk_mul_f32 v[6:7], v[6:7], s[28:29] op_sel_hi:[1,0]
	v_lshlrev_b32_e32 v32, 16, v36
	v_and_b32_e32 v33, 0xffff0000, v36
	v_pk_mul_f32 v[34:35], v[34:35], s[28:29] op_sel_hi:[1,0]
	v_pk_mul_f32 v[30:31], v[30:31], s[28:29] op_sel_hi:[1,0]
	v_pk_mul_f32 v[32:33], v[32:33], s[28:29] op_sel_hi:[1,0]
	v_cvt_pk_bf16_f32 v118, v6, v7
	v_cvt_pk_bf16_f32 v121, v34, v35
	v_lshlrev_b32_e32 v6, 16, v38
	v_and_b32_e32 v7, 0xffff0000, v38
	v_lshlrev_b32_e32 v34, 16, v39
	v_and_b32_e32 v35, 0xffff0000, v39
	v_lshlrev_b32_e32 v38, 16, v41
	v_and_b32_e32 v39, 0xffff0000, v41
	v_cvt_pk_bf16_f32 v119, v30, v31
	v_cvt_pk_bf16_f32 v120, v32, v33
	global_load_dwordx4 v[30:33], v[20:21], off offset:32
	v_pk_mul_f32 v[38:39], v[38:39], s[28:29] op_sel_hi:[1,0]
	v_pk_mul_f32 v[6:7], v[6:7], s[28:29] op_sel_hi:[1,0]
	v_lshlrev_b32_e32 v36, 16, v40
	v_and_b32_e32 v37, 0xffff0000, v40
	v_cvt_pk_bf16_f32 v125, v38, v39
	v_lshlrev_b32_e32 v38, 16, v2
	v_and_b32_e32 v39, 0xffff0000, v2
	v_lshlrev_b32_e32 v2, 16, v3
	v_and_b32_e32 v3, 0xffff0000, v3
	v_pk_mul_f32 v[34:35], v[34:35], s[28:29] op_sel_hi:[1,0]
	v_pk_mul_f32 v[36:37], v[36:37], s[28:29] op_sel_hi:[1,0]
	v_cvt_pk_bf16_f32 v122, v6, v7
	v_lshlrev_b32_e32 v6, 16, v0
	v_and_b32_e32 v7, 0xffff0000, v0
	v_lshlrev_b32_e32 v0, 16, v1
	v_and_b32_e32 v1, 0xffff0000, v1
	v_pk_mul_f32 v[2:3], v[2:3], s[28:29] op_sel_hi:[1,0]
	v_pk_mul_f32 v[44:45], v[44:45], s[28:29] op_sel_hi:[1,0]
	v_cvt_pk_bf16_f32 v116, v42, v43
	v_cvt_pk_bf16_f32 v123, v34, v35
	v_cvt_pk_bf16_f32 v124, v36, v37
	global_load_dwordx4 v[34:37], v[20:21], off offset:48
	v_pk_mul_f32 v[0:1], v[0:1], s[28:29] op_sel_hi:[1,0]
	v_cvt_pk_bf16_f32 v129, v2, v3
	s_waitcnt vmcnt(0) lgkmcnt(0)
	v_lshlrev_b32_e32 v42, 16, v12
	v_and_b32_e32 v43, 0xffff0000, v8
	v_mov_b32_e32 v2, v16
	v_mov_b32_e32 v3, v19
	v_cvt_pk_bf16_f32 v102, v44, v45
	v_cvt_pk_bf16_f32 v127, v0, v1
	v_mov_b32_e32 v0, v17
	v_mov_b32_e32 v1, v18
	v_lshlrev_b32_e32 v44, 16, v8
	v_and_b32_e32 v45, 0xffff0000, v12
	v_pk_mul_f32 v[2:3], v[2:3], v[42:43]
	v_pk_mul_f32 v[46:47], v[46:47], s[28:29] op_sel_hi:[1,0]
	v_pk_mul_f32 v[6:7], v[6:7], s[28:29] op_sel_hi:[1,0]
	v_pk_mul_f32 v[38:39], v[38:39], s[28:29] op_sel_hi:[1,0]
	v_pk_fma_f32 v[0:1], v[0:1], v[44:45], v[2:3]
	v_cvt_pk_bf16_f32 v104, v46, v47
	v_cvt_pk_bf16_f32 v126, v6, v7
	v_cvt_pk_bf16_f32 v128, v38, v39
	v_pk_mul_f32 v[46:47], v[0:1], s[28:29] op_sel_hi:[1,0]
	global_load_dwordx4 v[38:41], v[20:21], off offset:128
	global_load_dwordx4 v[0:3], v[4:5], off offset:288
	s_nop 0
	global_load_dwordx4 v[4:7], v[4:5], off offset:352
	v_mov_b32_e32 v49, v18
	v_mov_b32_e32 v51, v43
	v_mov_b32_e32 v18, v17
	v_mov_b32_e32 v43, v45
	v_mov_b32_e32 v48, v16
	v_mov_b32_e32 v50, v44
	v_pk_mul_f32 v[16:17], v[18:19], v[42:43]
	v_lshlrev_b32_e32 v44, 16, v13
	v_pk_fma_f32 v[16:17], v[48:49], v[50:51], v[16:17] neg_lo:[0,0,1] neg_hi:[0,0,1]
	v_and_b32_e32 v45, 0xffff0000, v9
	v_lshlrev_b32_e32 v8, 16, v9
	v_and_b32_e32 v9, 0xffff0000, v13
	v_mov_b32_e32 v12, v26
	v_mov_b32_e32 v13, v29
	v_pk_mul_f32 v[42:43], v[16:17], s[28:29] op_sel_hi:[1,0]
	v_mov_b32_e32 v16, v27
	v_mov_b32_e32 v17, v28
	v_pk_mul_f32 v[12:13], v[12:13], v[44:45]
	v_mov_b32_e32 v49, v28
	v_mov_b32_e32 v51, v45
	v_mov_b32_e32 v28, v27
	v_mov_b32_e32 v45, v9
	v_pk_fma_f32 v[12:13], v[16:17], v[8:9], v[12:13]
	v_mov_b32_e32 v48, v26
	v_mov_b32_e32 v50, v8
	v_pk_mul_f32 v[8:9], v[28:29], v[44:45]
	v_lshlrev_b32_e32 v28, 16, v14
	v_pk_fma_f32 v[8:9], v[48:49], v[50:51], v[8:9] neg_lo:[0,0,1] neg_hi:[0,0,1]
	v_and_b32_e32 v29, 0xffff0000, v10
	v_lshlrev_b32_e32 v44, 16, v10
	v_and_b32_e32 v45, 0xffff0000, v14
	v_mov_b32_e32 v51, v29
	v_mov_b32_e32 v50, v44
	v_lshlrev_b32_e32 v10, 16, v11
	v_mov_b32_e32 v48, v30
	v_mov_b32_e32 v49, v33
	v_mov_b32_e32 v26, v31
	v_mov_b32_e32 v27, v32
	v_pk_mul_f32 v[48:49], v[48:49], v[28:29]
	v_mov_b32_e32 v29, v45
	v_pk_fma_f32 v[26:27], v[26:27], v[44:45], v[48:49]
	v_mov_b32_e32 v49, v32
	v_mov_b32_e32 v32, v31
	v_mov_b32_e32 v48, v30
	v_pk_mul_f32 v[28:29], v[32:33], v[28:29]
	v_lshlrev_b32_e32 v32, 16, v15
	v_and_b32_e32 v33, 0xffff0000, v11
	v_and_b32_e32 v11, 0xffff0000, v15
	v_pk_fma_f32 v[28:29], v[48:49], v[50:51], v[28:29] neg_lo:[0,0,1] neg_hi:[0,0,1]
	v_mov_b32_e32 v45, v33
	v_pk_mul_f32 v[26:27], v[26:27], s[28:29] op_sel_hi:[1,0]
	v_pk_mul_f32 v[28:29], v[28:29], s[28:29] op_sel_hi:[1,0]
	v_mov_b32_e32 v44, v10
	v_pk_mul_f32 v[12:13], v[12:13], s[28:29] op_sel_hi:[1,0]
	global_load_dwordx4 v[16:19], v[20:21], off offset:144
	v_cvt_pk_bf16_f32 v132, v28, v29
	v_mov_b32_e32 v14, v34
	v_mov_b32_e32 v15, v37
	v_mov_b32_e32 v30, v35
	v_mov_b32_e32 v31, v36
	v_pk_mul_f32 v[14:15], v[14:15], v[32:33]
	v_mov_b32_e32 v36, v35
	v_mov_b32_e32 v33, v11
	v_pk_fma_f32 v[14:15], v[30:31], v[10:11], v[14:15]
	v_mov_b32_e32 v30, v34
	v_pk_mul_f32 v[10:11], v[36:37], v[32:33]
	v_pk_mul_f32 v[14:15], v[14:15], s[28:29] op_sel_hi:[1,0]
	v_pk_fma_f32 v[10:11], v[30:31], v[44:45], v[10:11] neg_lo:[0,0,1] neg_hi:[0,0,1]
	v_cvt_pk_bf16_f32 v136, v26, v27
	v_pk_mul_f32 v[8:9], v[8:9], s[28:29] op_sel_hi:[1,0]
	v_pk_mul_f32 v[10:11], v[10:11], s[28:29] op_sel_hi:[1,0]
	v_cvt_pk_bf16_f32 v135, v12, v13
	v_cvt_pk_bf16_f32 v137, v14, v15
	v_cvt_pk_bf16_f32 v131, v8, v9
	v_cvt_pk_bf16_f32 v133, v10, v11
	global_load_dwordx4 v[8:11], v[20:21], off offset:160
	v_ashrrev_i32_e32 v52, 3, v23
	s_waitcnt vmcnt(0) lgkmcnt(0)
; __device__ __forceinline__ void unpack8(const u32x4 w, float (&f)[8]) { f[0] = bflo(w.x); f[1] = bfhi(w.x); f[2] = bflo(w.y); f[3] = bfhi(w.y); f[4] = bflo(w.z); f[5] = bfhi(w.z); f[6] = bflo(w.w); f[7] = bfhi(w.w); }
; __device__ __forceinline__ u32x4 pack8(const float (&f)[8]) { u32x4 w; w.x = pk_bf16(f[0], f[1]); w.y = pk_bf16(f[2], f[3]); w.z = pk_bf16(f[4], f[5]); w.w = pk_bf16(f[6], f[7]); return w; }
; #define AT_ISSUE(kt) do { const char* p_ = kvb + (size_t)(kt) * (64 * 3072 * 2); const char* q_ = kpb + (size_t)(kt) * (64 * 64 * 2); \
;         sk[0] = *(const u32x4*)(p_ + kvo); sk[1] = *(const u32x4*)(p_ + (kvo + 32u * 3072u * 2u)); sv[0] = *(const u32x4*)(p_ + (kvo + 256u)); sv[1] = *(const u32x4*)(p_ + (kvo + 32u * 3072u * 2u + 256u)); \
;         sk[2] = *(const u32x4*)(q_ + kpo); } while (0)
; __device__ __forceinline__ void attn_phase(LAS unsigned char* lds, const bf16* Q, const bf16* KV, const bf16* KPE, const float* rope, bf16* mix, int bid, int G, int tid) {
;     ...
;           for (int ks = 8; ks < 10; ++ks) { float f1[8], f2[8], o1[8], o2[8]; unpack8(*(const u32x4*)(qp + ks * 16), f1); unpack8(*(const u32x4*)(qp + (ks + 2) * 16), f2);
; #pragma unroll
;               for (int e = 0; e < 8; ++e) { const int i = (ks - 8) * 16 + hh * 8 + e; const float cs = rp[2 * i], sn = rp[2 * i + 1];
;                   o1[e] = (f1[e] * cs - f2[e] * sn) * qs; o2[e] = (f1[e] * sn + f2[e] * cs) * qs; }
;               qf[ks] = __builtin_bit_cast(bf16x8, pack8(o1)); qf[ks + 2] = __builtin_bit_cast(bf16x8, pack8(o2)); asm volatile("" ::: "memory"); } }
;         f32x16 O[4];
; #pragma unroll
;         for (int i = 0; i < 4; ++i)
; #pragma unroll
;             for (int e = 0; e < 16; ++e) O[i][e] = 0.f;
;         float mrun = -1e30f, lrun = 0.f;
;         u32x4 sk[3], sv[2];
;         const char* kvb = (const char*)(KV + (size_t)mrow0 * 3072 + h * 256); const char* kpb = (const char*)(KPE + (size_t)mrow0 * 64);
;         const unsigned kvo = (unsigned)(sr16 * 3072 + sc16 * 8) * 2u, kpo = (unsigned)(sr8 * 64 + sc8 * 8) * 2u;
;     ...
;         AT_ISSUE(0); AT_COMMIT(lds);
;         __syncthreads();
;         const int qlo = q0 + wid * 32;
;         for (int kt = 0; kt < ntiles; ++kt) {
;             if (kt + 1 < ntiles) AT_ISSUE(kt + 1);
	v_mov_b32_e32 v28, v38
	v_and_b32_e32 v27, 0xffff0000, v0
	v_lshlrev_b32_e32 v26, 16, v4
	v_mov_b32_e32 v29, v41
	v_mov_b32_e32 v12, v39
	v_mov_b32_e32 v13, v40
	v_lshlrev_b32_e32 v14, 16, v0
	v_and_b32_e32 v15, 0xffff0000, v4
	v_pk_mul_f32 v[28:29], v[28:29], v[26:27]
	v_mov_b32_e32 v31, v40
	v_pk_fma_f32 v[12:13], v[12:13], v[14:15], v[28:29]
	v_mov_b32_e32 v33, v27
	v_mov_b32_e32 v40, v39
	v_mov_b32_e32 v27, v15
	v_lshlrev_b32_e32 v0, 4, v23
	v_pk_mul_f32 v[28:29], v[12:13], s[28:29] op_sel_hi:[1,0]
	v_mov_b32_e32 v30, v38
	v_mov_b32_e32 v32, v14
	global_load_dwordx4 v[12:15], v[20:21], off offset:176
	v_pk_mul_f32 v[20:21], v[40:41], v[26:27]
	v_and_b32_e32 v187, 0xf0, v0
	v_mul_lo_u32 v4, v25, s11
	v_pk_fma_f32 v[20:21], v[30:31], v[32:33], v[20:21] neg_lo:[0,0,1] neg_hi:[0,0,1]
	v_or_b32_e32 v30, v187, v4
	v_mov_b32_e32 v31, v97
	v_lshl_add_u64 v[34:35], s[14:15], 0, v[30:31]
	v_and_b32_e32 v188, 0x70, v0
	global_load_dwordx4 v[138:141], v[34:35], off
	global_load_dwordx4 v[146:149], v[34:35], off offset:256
	v_add_u32_e32 v36, 0x30000, v30
	v_mov_b32_e32 v37, v97
	v_add_u32_e32 v34, 0x30100, v30
	v_mov_b32_e32 v35, v97
	v_lshl_or_b32 v32, v52, 7, v188
	v_lshl_add_u64 v[38:39], s[14:15], 0, v[36:37]
	v_mov_b32_e32 v33, v97
	v_lshl_add_u64 v[40:41], s[14:15], 0, v[34:35]
	global_load_dwordx4 v[142:145], v[38:39], off
	global_load_dwordx4 v[154:157], v[40:41], off
	v_lshl_add_u64 v[38:39], s[30:31], 0, v[32:33]
	global_load_dwordx4 v[150:153], v[38:39], off
	v_lshlrev_b32_e32 v38, 16, v5
	v_and_b32_e32 v39, 0xffff0000, v1
	v_lshlrev_b32_e32 v0, 16, v1
	v_and_b32_e32 v1, 0xffff0000, v5
	v_mov_b32_e32 v41, v39
	v_mov_b32_e32 v40, v0
	s_movk_i32 s11, 0x190
	v_mul_lo_u32 v190, v25, s11
	v_mul_lo_u32 v192, v52, s11
	s_movk_i32 s11, 0x140
	v_mul_lo_u32 v193, v25, s11
	s_movk_i32 s11, 0xffb0
	v_pk_mul_f32 v[20:21], v[20:21], s[28:29] op_sel_hi:[1,0]
	v_cvt_pk_bf16_f32 v130, v42, v43
	v_cvt_pk_bf16_f32 v134, v46, v47
	v_mov_b32_e32 v4, v16
	v_mov_b32_e32 v5, v19
	v_mov_b32_e32 v26, v17
	v_mov_b32_e32 v27, v18
	v_pk_mul_f32 v[4:5], v[4:5], v[38:39]
	v_mov_b32_e32 v18, v17
	v_mov_b32_e32 v39, v1
	v_pk_fma_f32 v[4:5], v[26:27], v[0:1], v[4:5]
	v_mov_b32_e32 v26, v16
	v_pk_mul_f32 v[0:1], v[18:19], v[38:39]
	v_lshlrev_b32_e32 v18, 16, v6
	v_and_b32_e32 v19, 0xffff0000, v2
	v_pk_fma_f32 v[0:1], v[26:27], v[40:41], v[0:1] neg_lo:[0,0,1] neg_hi:[0,0,1]
	v_lshlrev_b32_e32 v26, 16, v2
	v_and_b32_e32 v27, 0xffff0000, v6
	v_mov_b32_e32 v41, v19
	v_lshlrev_b32_e32 v2, 16, v3
	v_pk_mul_f32 v[0:1], v[0:1], s[28:29] op_sel_hi:[1,0]
	v_mov_b32_e32 v40, v26
	v_cvt_pk_bf16_f32 v159, v0, v1
	v_add3_u32 v0, 0, v190, v187
	v_mov_b32_e32 v38, v8
	v_mov_b32_e32 v39, v11
	v_mov_b32_e32 v16, v9
	v_mov_b32_e32 v17, v10
	v_pk_mul_f32 v[38:39], v[38:39], v[18:19]
	v_mov_b32_e32 v19, v27
	v_pk_fma_f32 v[16:17], v[16:17], v[26:27], v[38:39]
	v_mov_b32_e32 v39, v10
	v_mov_b32_e32 v10, v9
	v_mov_b32_e32 v38, v8
	v_pk_mul_f32 v[8:9], v[10:11], v[18:19]
	v_lshlrev_b32_e32 v18, 16, v7
	v_and_b32_e32 v19, 0xffff0000, v3
	v_and_b32_e32 v3, 0xffff0000, v7
	v_mov_b32_e32 v27, v19
	v_mov_b32_e32 v26, v2
	v_add3_u32 v1, 0, v192, v188
	v_pk_fma_f32 v[8:9], v[38:39], v[40:41], v[8:9] neg_lo:[0,0,1] neg_hi:[0,0,1]
	v_pk_mul_f32 v[4:5], v[4:5], s[28:29] op_sel_hi:[1,0]
	v_pk_mul_f32 v[16:17], v[16:17], s[28:29] op_sel_hi:[1,0]
	s_waitcnt vmcnt(0) lgkmcnt(0)
	v_mov_b32_e32 v6, v12
	v_mov_b32_e32 v7, v15
	v_mov_b32_e32 v10, v13
	v_mov_b32_e32 v11, v14
	v_pk_mul_f32 v[6:7], v[6:7], v[18:19]
	v_mov_b32_e32 v14, v13
	v_mov_b32_e32 v19, v3
	v_pk_fma_f32 v[6:7], v[10:11], v[2:3], v[6:7]
	v_mov_b32_e32 v10, v12
	v_pk_mul_f32 v[2:3], v[14:15], v[18:19]
	ds_write_b128 v0, v[138:141]
	v_pk_fma_f32 v[2:3], v[10:11], v[26:27], v[2:3] neg_lo:[0,0,1] neg_hi:[0,0,1]
	v_pk_mul_f32 v[8:9], v[8:9], s[28:29] op_sel_hi:[1,0]
	v_pk_mul_f32 v[2:3], v[2:3], s[28:29] op_sel_hi:[1,0]
	v_pk_mul_f32 v[6:7], v[6:7], s[28:29] op_sel_hi:[1,0]
	v_cvt_pk_bf16_f32 v161, v2, v3
	v_mov_b32_e32 v14, v97
	v_mov_b32_e32 v15, v97
	v_cvt_pk_bf16_f32 v158, v20, v21
	v_cvt_pk_bf16_f32 v160, v8, v9
	ds_write_b128 v0, v[142:145] offset:12800
	v_cvt_pk_bf16_f32 v162, v28, v29
	v_cvt_pk_bf16_f32 v163, v4, v5
	ds_write_b128 v1, v[150:153] offset:256
	v_mul_lo_u32 v1, v25, s11
	s_movk_i32 s11, 0x3200
	v_add_u32_e32 v2, v0, v1
	v_add3_u32 v0, v0, s11, v1
	s_or_b32 s11, s8, 31
	s_add_u32 s4, s4, 0x26a02000
	s_addc_u32 s5, s5, 0
	ds_write_b128 v0, v[154:157] offset:23040
	v_lshrrev_b32_e32 v0, 2, v23
	s_add_u32 s0, s17, s0
	v_and_or_b32 v0, v0, 3, v189
	s_addc_u32 s1, s19, s1
	v_mul_u32_u24_e32 v204, 0x140, v0
	v_and_b32_e32 v0, 16, v23
	v_lshlrev_b32_e32 v1, 2, v23
	v_lshl_add_u64 v[176:177], s[4:5], 0, v[32:33]
	s_add_u32 s4, s0, 0x27660000
	v_and_or_b32 v0, v1, 12, v0
	s_addc_u32 s5, s1, 0
	v_cvt_pk_bf16_f32 v164, v16, v17
	v_cvt_pk_bf16_f32 v165, v6, v7
	ds_write_b128 v2, v[146:149] offset:25600
	v_lshlrev_b32_e32 v205, 1, v0
	v_lshl_add_u64 v[178:179], s[4:5], 0, v[34:35]
	v_lshl_add_u64 v[180:181], s[4:5], 0, v[36:37]
	v_lshl_add_u64 v[182:183], s[0:1], 0, v[30:31]
	v_mov_b32_e32 v0, v97
	v_mov_b32_e32 v1, v97
	v_mov_b32_e32 v2, v97
	v_mov_b32_e32 v3, v97
	v_mov_b32_e32 v4, v97
	v_mov_b32_e32 v5, v97
	v_mov_b32_e32 v6, v97
	v_mov_b32_e32 v7, v97
	v_mov_b32_e32 v8, v97
	v_mov_b32_e32 v9, v97
	v_mov_b32_e32 v10, v97
	v_mov_b32_e32 v11, v97
	v_mov_b32_e32 v12, v97
	v_mov_b32_e32 v13, v97
	v_mov_b64_e32 v[30:31], v[14:15]
	v_mov_b64_e32 v[46:47], v[14:15]
	v_mov_b64_e32 v[62:63], v[14:15]
	v_add_u32_e32 v191, 0x3200, v190
	v_add_u32_e32 v202, 0x2800, v193
	s_mov_b32 s4, 0
	s_mov_b32 s0, 63
	v_mov_b64_e32 v[28:29], v[12:13]
	v_mov_b64_e32 v[26:27], v[10:11]
	v_mov_b64_e32 v[24:25], v[8:9]
	v_mov_b64_e32 v[22:23], v[6:7]
	v_mov_b64_e32 v[20:21], v[4:5]
	v_mov_b64_e32 v[18:19], v[2:3]
	v_mov_b64_e32 v[16:17], v[0:1]
	v_mov_b64_e32 v[44:45], v[12:13]
	v_mov_b64_e32 v[42:43], v[10:11]
	v_mov_b64_e32 v[40:41], v[8:9]
	v_mov_b64_e32 v[38:39], v[6:7]
	v_mov_b64_e32 v[36:37], v[4:5]
	v_mov_b64_e32 v[34:35], v[2:3]
	v_mov_b64_e32 v[32:33], v[0:1]
	v_mov_b64_e32 v[60:61], v[12:13]
	v_mov_b64_e32 v[58:59], v[10:11]
	v_mov_b64_e32 v[56:57], v[8:9]
	v_mov_b64_e32 v[54:55], v[6:7]
	v_mov_b64_e32 v[52:53], v[4:5]
	v_mov_b64_e32 v[50:51], v[2:3]
	v_mov_b64_e32 v[48:49], v[0:1]
	s_waitcnt lgkmcnt(0)
	s_barrier
.LBB0_251:
	s_add_i32 s1, s4, 1
	s_cmp_lt_i32 s1, s9
	s_cselect_b64 s[34:35], -1, 0
	s_cmp_ge_i32 s1, s9
	s_cbranch_scc1 .LBB0_253
	v_lshl_add_u64 v[64:65], s[88:89], 0, v[182:183]
	v_add_co_u32_e32 v64, vcc, 0x27660000, v64
	v_lshl_add_u64 v[66:67], s[88:89], 0, v[180:181]
	s_nop 0
	v_addc_co_u32_e32 v65, vcc, 0, v65, vcc
	s_waitcnt vmcnt(0)
	global_load_dwordx4 v[138:141], v[64:65], off
	global_load_dwordx4 v[146:149], v[64:65], off offset:256
	v_lshl_add_u64 v[64:65], s[88:89], 0, v[178:179]
	global_load_dwordx4 v[142:145], v[66:67], off
	global_load_dwordx4 v[154:157], v[64:65], off
	v_lshl_add_u64 v[64:65], s[88:89], 0, v[176:177]
	global_load_dwordx4 v[150:153], v[64:65], off

; #define INF(i) uniform_ptr((const float*)tab[i])
; __device__ __forceinline__ void o2_phase(const bf16* P, const float* qnorm, const float* kvnorm, const float* rope, bf16* PD, bf16* QN, bf16* KVN, bf16* KPE, int gw, int ngw, int lane) {
;     float qg[8], kg[8];
; #pragma unroll
;     for (int e = 0; e < 8; ++e) { qg[e] = qnorm[lane * 8 + e]; kg[e] = kvnorm[lane * 8 + e]; }
;     const int win = 2 << (lane >> 4);
;     for (int m = gw; m < T; m += ngw) { const int t = m & (SEQ - 1); const bf16* pr = P + (size_t)m * OD_IN_P;
; __global__ void __launch_bounds__(NTHREADS, 2) trunk_fwd(Args a) {
;     ...
;         } else if (kind == 21) {
;             o2_phase(P, INF(21) + (size_t)j * 512, INF(23) + (size_t)j * 512, ROPE, PD, QN, KVN, KPE, gw, ngw, lane);
.LBB0_264:
	s_andn2_b64 vcc, exec, s[0:1]
	s_cbranch_vccnz .LBB0_274
	s_cmp_eq_u32 s77, 21
	s_cbranch_scc0 .LBB0_274
	s_add_i32 s0, s92, 0
	s_waitcnt vmcnt(0)
	v_mov_b32_e32 v2, s0
	s_waitcnt lgkmcnt(0)
	ds_read_b64 v[0:1], v2 offset:168
	s_cmpk_gt_i32 s10, 0x3fff
	s_waitcnt lgkmcnt(0)
	v_readfirstlane_b32 s0, v1
	v_readfirstlane_b32 s1, v0
	ds_read_b64 v[0:1], v2 offset:184
	s_waitcnt lgkmcnt(0)
	v_readfirstlane_b32 s2, v1
	v_readfirstlane_b32 s4, v0
	s_cbranch_scc1 .LBB0_274
	s_lshl_b32 s5, s96, 11
	s_add_u32 s6, s1, s5
	s_addc_u32 s7, s0, 0
	s_add_u32 s0, s4, s5
	s_addc_u32 s1, s2, 0
	v_lshlrev_b32_e32 v96, 5, v185
	v_lshl_add_u64 v[4:5], s[6:7], 0, v[96:97]
	v_lshl_add_u64 v[12:13], s[0:1], 0, v[96:97]
	global_load_dwordx4 v[0:3], v[4:5], off
	s_nop 0
	global_load_dwordx4 v[4:7], v[4:5], off offset:16
	s_nop 0
	global_load_dwordx4 v[8:11], v[12:13], off
	s_nop 0
	global_load_dwordx4 v[12:15], v[12:13], off offset:16
	v_and_b32_e32 v18, 64, v220
	v_add_u32_e32 v18, 64, v18
	v_xor_b32_e32 v19, 1, v220
	v_cmp_lt_i32_e32 vcc, v19, v18
	v_readlane_b32 s0, v255, 7
	v_lshrrev_b32_e32 v16, 4, v185
	v_cndmask_b32_e32 v19, v220, v19, vcc
	v_lshlrev_b32_e32 v53, 2, v19
	v_xor_b32_e32 v19, 2, v220
	v_cmp_lt_i32_e32 vcc, v19, v18
	v_lshlrev_b32_e32 v96, 4, v185
	v_readlane_b32 s1, v255, 8
	v_cndmask_b32_e32 v19, v220, v19, vcc
	v_lshlrev_b32_e32 v54, 2, v19
	v_xor_b32_e32 v19, 4, v220
	v_cmp_lt_i32_e32 vcc, v19, v18
	v_lshlrev_b32_e64 v52, v16, 2
	v_lshl_add_u64 v[16:17], s[0:1], 0, v[96:97]
	v_cndmask_b32_e32 v19, v220, v19, vcc
	v_lshlrev_b32_e32 v55, 2, v19
	v_xor_b32_e32 v19, 8, v220
	v_cmp_lt_i32_e32 vcc, v19, v18
	v_readlane_b32 s0, v255, 9
	v_readlane_b32 s1, v255, 10
	v_cndmask_b32_e32 v19, v220, v19, vcc
	v_lshlrev_b32_e32 v56, 2, v19
	v_xor_b32_e32 v19, 16, v220
	v_cmp_lt_i32_e32 vcc, v19, v18
	v_lshlrev_b32_e32 v24, 1, v185
	v_mov_b32_e32 v25, v97
	v_cndmask_b32_e32 v19, v220, v19, vcc
	v_lshlrev_b32_e32 v57, 2, v19
	v_xor_b32_e32 v19, 32, v220
	v_cmp_lt_i32_e32 vcc, v19, v18
	v_and_b32_e32 v30, 31, v186
	v_lshlrev_b32_e32 v28, 3, v185
	v_cndmask_b32_e32 v18, v220, v19, vcc
	v_lshlrev_b32_e32 v58, 2, v18
	v_lshl_add_u64 v[18:19], s[0:1], 0, v[96:97]
	v_readlane_b32 s0, v255, 11
	v_readlane_b32 s1, v255, 12
	v_or_b32_e32 v32, 0x620, v185
	v_lshlrev_b32_e32 v22, 3, v30
	v_lshl_add_u64 v[20:21], s[0:1], 0, v[96:97]
	v_readlane_b32 s0, v255, 3
	v_readlane_b32 s1, v255, 4
	v_mov_b32_e32 v23, v97
	v_lshl_add_u64 v[22:23], s[56:57], 0, v[22:23]
	v_lshl_add_u64 v[24:25], s[0:1], 0, v[24:25]
	s_mul_i32 s0, s10, 0xe00
	s_mul_hi_i32 s1, s10, 0xe00
	s_add_u32 s0, s88, s0
	s_addc_u32 s1, s89, s1
	v_lshl_add_u64 v[26:27], s[0:1], 0, v[96:97]
	s_mov_b64 s[0:1], 0x139ff200
	v_cmp_gt_u32_e64 s[38:39], 32, v185
	v_lshl_add_u64 v[26:27], v[26:27], 0, s[0:1]
	v_lshlrev_b32_e32 v96, 1, v28
	v_lshlrev_b32_e32 v28, 1, v30
	v_lshlrev_b32_e32 v30, 1, v32
	s_mov_b32 s2, s10
	s_mov_b32 s34, s10
	s_branch .LBB0_270

; __device__ __forceinline__ float bf2f(bf16 b) { return __uint_as_float((unsigned)b << 16); }
; __device__ __forceinline__ bf16 f2bf(float f) { return (bf16)(pk_bf16(f, 0.f) & 0xffffu); }
; __device__ __forceinline__ void unpack8(const u32x4 w, float (&f)[8]) { f[0] = bflo(w.x); f[1] = bfhi(w.x); f[2] = bflo(w.y); f[3] = bfhi(w.y); f[4] = bflo(w.z); f[5] = bfhi(w.z); f[6] = bflo(w.w); f[7] = bfhi(w.w); }
; __device__ __forceinline__ u32x4 pack8(const float (&f)[8]) { u32x4 w; w.x = pk_bf16(f[0], f[1]); w.y = pk_bf16(f[2], f[3]); w.z = pk_bf16(f[4], f[5]); w.w = pk_bf16(f[6], f[7]); return w; }
; __device__ __forceinline__ void o2_phase(const bf16* P, const float* qnorm, const float* kvnorm, const float* rope, bf16* PD, bf16* QN, bf16* KVN, bf16* KPE, int gw, int ngw, int lane) {
;     ...
;           const float ic = 1.0f / (float)cnt;
; #pragma unroll
;           for (int e = 0; e < 8; ++e) acc[e] = acc[e] * ic - u[e];
;           *(u32x4*)(PD + (size_t)m * 512 + lane * 8) = pack8(acc); }
;         { float q[8]; unpack8(*(const u32x4*)(pr + 512 + lane * 8), q); float s = 0.f;
; #pragma unroll
;           for (int e = 0; e < 8; ++e) s += q[e] * q[e];
;           s = wave_sum(s); const float sc = rsqrtf(s * (1.0f / 512.0f) + NORM_EPS);
; #pragma unroll
;           for (int e = 0; e < 8; ++e) q[e] = q[e] * sc * qg[e];
;           *(u32x4*)(QN + (size_t)m * 512 + lane * 8) = pack8(q); }
;         { float q[8]; unpack8(*(const u32x4*)(pr + 1024 + lane * 8), q); float s = 0.f;
; #pragma unroll
;           for (int e = 0; e < 8; ++e) s += q[e] * q[e];
;           s = wave_sum(s); const float sc = rsqrtf(s * (1.0f / 512.0f) + NORM_EPS);
; #pragma unroll
;           for (int e = 0; e < 8; ++e) q[e] = q[e] * sc * kg[e];
;           *(u32x4*)(KVN + (size_t)m * 512 + lane * 8) = pack8(q); }
;         { const int i = lane & 31; const float t1 = bf2f(pr[1536 + i]), t2 = bf2f(pr[1568 + i]); const float cs = rope[(size_t)m * 64 + 2 * i], sn = rope[(size_t)m * 64 + 2 * i + 1];
;           const float o = (lane < 32) ? (t1 * cs - t2 * sn) : (t1 * sn + t2 * cs);
;           KPE[(size_t)m * 64 + lane] = f2bf(o); }
.LBB0_269:
	s_add_i32 s4, s4, 1
	v_min_u32_e32 v29, s4, v52
	v_cvt_f32_ubyte0_e32 v29, v29
	v_div_scale_f32 v31, s[0:1], v29, v29, 1.0
	v_rcp_f32_e32 v50, v31
	v_div_scale_f32 v51, vcc, 1.0, v29, 1.0
	s_ashr_i32 s35, s34, 31
	v_fma_f32 v59, -v31, v50, 1.0
	v_fmac_f32_e32 v50, v59, v50
	v_mul_f32_e32 v59, v51, v50
	v_fma_f32 v60, -v31, v59, v51
	v_fmac_f32_e32 v59, v60, v50
	v_fma_f32 v31, -v31, v59, v51
	v_div_fmas_f32 v31, v31, v50, v59
	v_div_fixup_f32 v50, v31, v29, 1.0
	v_pk_fma_f32 v[42:43], v[50:51], v[44:45], v[42:43] op_sel_hi:[0,1,1] neg_lo:[0,0,1] neg_hi:[0,0,1]
	v_pk_fma_f32 v[38:39], v[50:51], v[40:41], v[38:39] op_sel_hi:[0,1,1] neg_lo:[0,0,1] neg_hi:[0,0,1]
	v_pk_fma_f32 v[40:41], v[50:51], v[46:47], v[34:35] op_sel_hi:[0,1,1] neg_lo:[0,0,1] neg_hi:[0,0,1]
	v_pk_fma_f32 v[44:45], v[50:51], v[48:49], v[36:37] op_sel_hi:[0,1,1] neg_lo:[0,0,1] neg_hi:[0,0,1]
	s_lshl_b64 s[0:1], s[34:35], 10
	v_cvt_pk_bf16_f32 v34, v42, v43
	v_cvt_pk_bf16_f32 v35, v38, v39
	v_cvt_pk_bf16_f32 v36, v40, v41
	v_cvt_pk_bf16_f32 v37, v44, v45
	v_lshl_add_u64 v[38:39], v[16:17], 0, s[0:1]
	global_store_dwordx4 v[38:39], v[34:37], off
	global_load_dwordx4 v[34:37], v[32:33], off offset:1024
	s_lshl_b64 s[4:5], s[34:35], 8
	s_add_i32 s2, s2, s16
	s_waitcnt vmcnt(0) lgkmcnt(0)
	v_lshlrev_b32_e32 v42, 16, v34
	v_and_b32_e32 v43, 0xffff0000, v34
	v_lshlrev_b32_e32 v38, 16, v37
	v_and_b32_e32 v39, 0xffff0000, v37
	v_lshlrev_b32_e32 v40, 16, v36
	v_and_b32_e32 v41, 0xffff0000, v36
	v_lshlrev_b32_e32 v36, 16, v35
	v_and_b32_e32 v37, 0xffff0000, v35
	v_pk_mul_f32 v[48:49], v[42:43], v[42:43]
	v_pk_mul_f32 v[46:47], v[36:37], v[36:37]
	v_add_f32_e32 v29, v48, v49
	v_add_f32_e32 v29, v46, v29
	v_pk_mul_f32 v[44:45], v[40:41], v[40:41]
	v_add_f32_e32 v29, v47, v29
	v_add_f32_e32 v29, v44, v29
	v_pk_mul_f32 v[34:35], v[38:39], v[38:39]
	v_add_f32_e32 v29, v45, v29
	v_add_f32_e32 v29, v34, v29
	v_add_f32_e32 v29, v35, v29
	ds_bpermute_b32 v31, v53, v29
	v_lshl_add_u64 v[44:45], v[18:19], 0, s[0:1]
	v_lshl_add_u64 v[48:49], v[22:23], 0, s[4:5]
	s_waitcnt lgkmcnt(0)
	v_add_f32_e32 v29, v29, v31
	ds_bpermute_b32 v31, v54, v29
	s_waitcnt lgkmcnt(0)
	v_add_f32_e32 v29, v29, v31
	ds_bpermute_b32 v31, v55, v29
	s_waitcnt lgkmcnt(0)
	v_add_f32_e32 v29, v29, v31
	ds_bpermute_b32 v31, v56, v29
	s_waitcnt lgkmcnt(0)
	v_add_f32_e32 v29, v29, v31
	ds_bpermute_b32 v31, v57, v29
	s_waitcnt lgkmcnt(0)
	v_add_f32_e32 v29, v29, v31
	ds_bpermute_b32 v31, v58, v29
	s_waitcnt lgkmcnt(0)
	v_add_f32_e32 v29, v29, v31
	v_fmamk_f32 v29, v29, 0x3b000000, v218
	v_mul_f32_e32 v31, 0x4b800000, v29
	v_cmp_gt_f32_e32 vcc, s12, v29
	s_nop 1
	v_cndmask_b32_e32 v29, v29, v31, vcc
	v_rsq_f32_e32 v29, v29
	s_nop 0
	v_mul_f32_e32 v31, 0x45800000, v29
	v_cndmask_b32_e32 v34, v29, v31, vcc
	v_pk_mul_f32 v[42:43], v[34:35], v[42:43] op_sel_hi:[0,1]
	v_pk_mul_f32 v[36:37], v[34:35], v[36:37] op_sel_hi:[0,1]
	v_pk_mul_f32 v[40:41], v[34:35], v[40:41] op_sel_hi:[0,1]
	v_pk_mul_f32 v[34:35], v[34:35], v[38:39] op_sel_hi:[0,1]
	v_pk_mul_f32 v[38:39], v[0:1], v[42:43]
	v_pk_mul_f32 v[36:37], v[2:3], v[36:37]
	v_pk_mul_f32 v[40:41], v[4:5], v[40:41]
	v_pk_mul_f32 v[42:43], v[6:7], v[34:35]
	v_cvt_pk_bf16_f32 v34, v38, v39
	v_cvt_pk_bf16_f32 v35, v36, v37
	v_cvt_pk_bf16_f32 v36, v40, v41
	v_cvt_pk_bf16_f32 v37, v42, v43
	global_store_dwordx4 v[44:45], v[34:37], off
	global_load_dwordx4 v[32:35], v[32:33], off offset:2048
	s_waitcnt vmcnt(0) lgkmcnt(0)
	v_lshlrev_b32_e32 v40, 16, v32
	v_and_b32_e32 v41, 0xffff0000, v32
	v_lshlrev_b32_e32 v36, 16, v35
	v_and_b32_e32 v37, 0xffff0000, v35
	v_lshlrev_b32_e32 v38, 16, v34
	v_and_b32_e32 v39, 0xffff0000, v34
	v_lshlrev_b32_e32 v34, 16, v33
	v_and_b32_e32 v35, 0xffff0000, v33
	v_pk_mul_f32 v[46:47], v[40:41], v[40:41]
	v_pk_mul_f32 v[44:45], v[34:35], v[34:35]
	v_add_f32_e32 v29, v46, v47
	v_add_f32_e32 v29, v44, v29
	v_pk_mul_f32 v[42:43], v[38:39], v[38:39]
	v_add_f32_e32 v29, v45, v29
	v_add_f32_e32 v29, v42, v29
	v_pk_mul_f32 v[32:33], v[36:37], v[36:37]
	v_add_f32_e32 v29, v43, v29
	v_add_f32_e32 v29, v32, v29
	v_add_f32_e32 v29, v33, v29
	ds_bpermute_b32 v31, v53, v29
	v_lshl_add_u64 v[42:43], v[20:21], 0, s[0:1]
	s_lshl_b64 s[0:1], s[34:35], 7
	s_add_i32 s34, s34, s16
	s_cmpk_gt_i32 s34, 0x3fff
	s_waitcnt lgkmcnt(0)
	v_add_f32_e32 v29, v29, v31
	ds_bpermute_b32 v31, v54, v29
	s_waitcnt lgkmcnt(0)
	v_add_f32_e32 v29, v29, v31
	ds_bpermute_b32 v31, v55, v29
	s_waitcnt lgkmcnt(0)
	v_add_f32_e32 v29, v29, v31
	ds_bpermute_b32 v31, v56, v29
	s_waitcnt lgkmcnt(0)
	v_add_f32_e32 v29, v29, v31
	ds_bpermute_b32 v31, v57, v29
	s_waitcnt lgkmcnt(0)
	v_add_f32_e32 v32, v29, v31
	ds_bpermute_b32 v33, v58, v32
	v_mov_b32_e32 v29, v97
	v_lshl_add_u64 v[44:45], s[36:37], 0, v[28:29]
	v_mov_b32_e32 v31, v97
	v_lshl_add_u64 v[46:47], s[36:37], 0, v[30:31]
	s_waitcnt lgkmcnt(0)
	v_add_f32_e32 v32, v32, v33
	v_fmamk_f32 v32, v32, 0x3b000000, v218
	v_mul_f32_e32 v33, 0x4b800000, v32
	v_cmp_gt_f32_e32 vcc, s12, v32
	s_nop 1
	v_cndmask_b32_e32 v32, v32, v33, vcc
	v_rsq_f32_e32 v32, v32
	s_nop 0
	v_mul_f32_e32 v29, 0x45800000, v32
	v_cndmask_b32_e32 v32, v32, v29, vcc
	v_pk_mul_f32 v[40:41], v[32:33], v[40:41] op_sel_hi:[0,1]
	v_pk_mul_f32 v[34:35], v[32:33], v[34:35] op_sel_hi:[0,1]
	v_pk_mul_f32 v[38:39], v[32:33], v[38:39] op_sel_hi:[0,1]
	v_pk_mul_f32 v[32:33], v[32:33], v[36:37] op_sel_hi:[0,1]
	v_pk_mul_f32 v[36:37], v[8:9], v[40:41]
	v_pk_mul_f32 v[34:35], v[10:11], v[34:35]
	v_pk_mul_f32 v[38:39], v[12:13], v[38:39]
	v_pk_mul_f32 v[40:41], v[14:15], v[32:33]
	v_cvt_pk_bf16_f32 v32, v36, v37
	v_cvt_pk_bf16_f32 v33, v34, v35
	v_cvt_pk_bf16_f32 v34, v38, v39
	v_cvt_pk_bf16_f32 v35, v40, v41
	global_store_dwordx4 v[42:43], v[32:35], off
	global_load_ushort v29, v[46:47], off
	s_nop 0
	global_load_dwordx2 v[32:33], v[48:49], off
	global_load_ushort v31, v[44:45], off offset:3072
	v_lshl_add_u64 v[34:35], v[24:25], 0, s[0:1]
	s_waitcnt vmcnt(0) lgkmcnt(0)
	v_lshlrev_b32_e32 v37, 16, v29
	v_lshlrev_b32_e32 v36, 16, v31
	v_pk_mul_f32 v[38:39], v[32:33], v[36:37]
	v_pk_mul_f32 v[32:33], v[32:33], v[36:37] op_sel:[1,0] op_sel_hi:[0,1]
	v_sub_f32_e32 v29, v38, v39
	v_add_f32_e32 v31, v32, v33
	v_cndmask_b32_e64 v29, v31, v29, s[38:39]
	v_cvt_pk_bf16_f32 v29, v29, s0
	v_readlane_b32 s0, v254, 1
	v_readlane_b32 s1, v254, 2
	global_store_short v[34:35], v29, off
	s_nop 0
	v_lshl_add_u64 v[26:27], v[26:27], 0, s[0:1]
	s_cbranch_scc1 .LBB0_274
; __device__ __forceinline__ void unpack8(const u32x4 w, float (&f)[8]) { f[0] = bflo(w.x); f[1] = bfhi(w.x); f[2] = bflo(w.y); f[3] = bfhi(w.y); f[4] = bflo(w.z); f[5] = bfhi(w.z); f[6] = bflo(w.w); f[7] = bfhi(w.w); }
; __device__ __forceinline__ void o2_phase(const bf16* P, const float* qnorm, const float* kvnorm, const float* rope, bf16* PD, bf16* QN, bf16* KVN, bf16* KPE, int gw, int ngw, int lane) {
;     ...
;     for (int m = gw; m < T; m += ngw) { const int t = m & (SEQ - 1); const bf16* pr = P + (size_t)m * OD_IN_P;
;         { float u[8], acc[8], tmp[8]; unpack8(*(const u32x4*)(pr + lane * 8), u);
; #pragma unroll
;           for (int e = 0; e < 8; ++e) acc[e] = u[e];
;           const int cnt = (t + 1 < win) ? (t + 1) : win;
;           for (int j = 1; j < cnt; ++j) { unpack8(*(const u32x4*)(pr - (size_t)j * OD_IN_P + lane * 8), tmp);
; #pragma unroll
;               for (int e = 0; e < 8; ++e) acc[e] += tmp[e]; }
.LBB0_270:
	s_mul_i32 s1, s34, 0xe00
	v_readlane_b32 s4, v254, 63
	s_mul_hi_i32 s0, s34, 0xe00
	v_readlane_b32 s5, v255, 0
	s_add_u32 s36, s4, s1
	s_addc_u32 s37, s5, s0
	v_lshl_add_u64 v[32:33], s[36:37], 0, v[96:97]
	global_load_dwordx4 v[34:37], v[32:33], off
	s_and_b32 s4, s34, 0xfff
	s_cmp_eq_u32 s4, 0
	s_waitcnt vmcnt(0) lgkmcnt(0)
	v_lshlrev_b32_e32 v42, 16, v34
	v_and_b32_e32 v45, 0xffff0000, v34
	v_lshlrev_b32_e32 v38, 16, v35
	v_and_b32_e32 v41, 0xffff0000, v35
	v_lshlrev_b32_e32 v34, 16, v36
	v_and_b32_e32 v35, 0xffff0000, v36
	v_lshlrev_b32_e32 v36, 16, v37
	v_and_b32_e32 v37, 0xffff0000, v37
	v_mov_b32_e32 v43, v45
	v_mov_b32_e32 v44, v42
	v_mov_b32_e32 v39, v41
	v_mov_b32_e32 v40, v38
	v_mov_b32_e32 v46, v34
	v_mov_b32_e32 v47, v35
	s_cbranch_scc1 .LBB0_268
	s_and_b32 s0, s2, 0xfff
	s_add_i32 s0, s0, 1
	v_min_u32_e32 v29, s0, v52
	v_max_u32_e32 v29, 2, v29
	v_add_u32_e32 v29, -1, v29
	s_mov_b64 s[0:1], 0
	v_mov_b64_e32 v[50:51], v[26:27]
	v_mov_b64_e32 v[48:49], v[36:37]
.LBB0_272:
	global_load_dwordx4 v[60:63], v[50:51], off
	v_add_u32_e32 v29, -1, v29
	s_movk_i32 s6, 0xf200
	s_mov_b32 s7, -1
	v_cmp_eq_u32_e32 vcc, 0, v29
	v_lshl_add_u64 v[50:51], v[50:51], 0, s[6:7]
	s_or_b64 s[0:1], vcc, s[0:1]
	s_waitcnt vmcnt(0) lgkmcnt(0)
	v_lshlrev_b32_e32 v64, 16, v60
	v_and_b32_e32 v65, 0xffff0000, v60
	v_lshlrev_b32_e32 v60, 16, v61
	v_and_b32_e32 v61, 0xffff0000, v61
	v_pk_add_f32 v[40:41], v[40:41], v[60:61]
	v_lshlrev_b32_e32 v60, 16, v62
	v_and_b32_e32 v61, 0xffff0000, v62
	v_pk_add_f32 v[46:47], v[46:47], v[60:61]
	v_lshlrev_b32_e32 v60, 16, v63
	v_and_b32_e32 v61, 0xffff0000, v63
	v_pk_add_f32 v[44:45], v[44:45], v[64:65]
	v_pk_add_f32 v[48:49], v[48:49], v[60:61]
	s_andn2_b64 exec, exec, s[0:1]
	s_cbranch_execnz .LBB0_272
	s_or_b64 exec, exec, s[0:1]
	s_branch .LBB0_269

; #define LAS __attribute__((address_space(3)))
; __device__ __forceinline__ void pc_phase(LAS unsigned char* lds, const bf16* Pp_, const bf16* LO, const float* mu, const float* w0, const float* a0, const float* k_k, const float* k_a, const float* r_k, ...
;     ...
;             const float z = -(w0c + bf2f(slw[t])); const float sp = fmaxf(z, 0.f) + flog(1.0f + fexp(-fabsf(z))); const float w = -sp - 0.5f;
;             const float dec = fexp(-fexp(w)); const float a = fsigmoid(a0c + bf2f(sla[t]));
;             float kk = k * kkc; const float n2 = wsum_dpp(kk * kk); kk = kk / fmaxf(sqrtf(n2), 1e-12f);
;             const float kp = bf2f(f2bf(k * (1.0f + (a - 1.0f) * kac))), bb = bf2f(f2bf(kk * a)), rr = bf2f(f2bf(r)); kk = bf2f(f2bf(kk));
;             const float coef = wsum_dpp(rr * kp * rkc);
;             SV[(ib + t) * 64 + lane] = f2bf(v);
;             if (lane == 0) COEF[(size_t)(m0 + t) * 16 + h] = coef;
;             const float Pp = P; P *= dec; const float inv = 1.0f / P;
;             XKK[t * 72 + lane] = f2bf(kk * Pp); XR[t * 72 + lane] = f2bf(rr * P); XK[t * 72 + lane] = f2bf(kp * inv); XB[t * 72 + lane] = f2bf(bb * inv); }
;         PCL[lane] = P;
;         PC_FENCE();
;         { f32x4 akb = zero, akk = zero, ark = zero, arb = zero;
; #pragma unroll
;           for (int ks = 0; ks < 2; ++ks) { const int o = m * 72 + 32 * ks + 8 * g;
;               const bf16x8 fkk = *(const LAS bf16x8*)(XKK + o), fr = *(const LAS bf16x8*)(XR + o), fk = *(const LAS bf16x8*)(XK + o), fb = *(const LAS bf16x8*)(XB + o);
;               akb = __builtin_amdgcn_mfma_f32_16x16x32_bf16(fkk, fb, akb, 0, 0, 0); akk = __builtin_amdgcn_mfma_f32_16x16x32_bf16(fkk, fk, akk, 0, 0, 0);
;               ark = __builtin_amdgcn_mfma_f32_16x16x32_bf16(fr, fk, ark, 0, 0, 0); arb = __builtin_amdgcn_mfma_f32_16x16x32_bf16(fr, fb, arb, 0, 0, 0); }
; #pragma unroll
;           for (int r = 0; r < 4; ++r) { const int i = 4 * g + r, j = m;
;               AKB[i * 20 + j] = (j < i) ? akb[r] : 0.f; AKK[i * 17 + j] = (j < i) ? akk[r] : 0.f; ARK[i * 17 + j] = (j <= i) ? ark[r] : 0.f; ARB[i * 17 + j] = (j <= i) ? arb[r] : 0.f; } }
;         PC_FENCE();
;         { const int j = m; float Tc[16]; f32x4 Lc[4], Ln[4];
; #pragma unroll
;           for (int c4 = 0; c4 < 4; ++c4) Lc[c4] = *(const LAS f32x4*)(AKB + 20 + 4 * c4);
;           Tc[0] = (j == 0) ? 1.0f : 0.0f;
.LBB0_280:
	s_or_b64 exec, exec, s[4:5]
	v_lshlrev_b32_e32 v6, 16, v16
	v_add_f32_e32 v6, v8, v6
	v_mul_f32_e64 v7, |v6|, s19
	v_exp_f32_e32 v7, v7
	v_mov_b32_e32 v8, s9
	v_mov_b32_e32 v11, s8
	v_add_f32_e32 v8, s7, v8
	v_add_f32_e32 v7, 1.0, v7
	v_log_f32_e32 v7, v7
	v_add_f32_e32 v11, s6, v11
	v_max_f32_e64 v6, -v6, 0
	v_add_f32_e32 v8, v8, v11
	v_fmac_f32_e32 v6, 0x3f317218, v7
	v_cmp_gt_f32_e32 vcc, s33, v8
	v_mul_f32_e32 v7, 0x4f800000, v8
	v_sub_f32_e32 v6, -0.5, v6
	v_cndmask_b32_e32 v7, v8, v7, vcc
	v_sqrt_f32_e32 v8, v7
	v_mul_f32_e32 v6, 0x3fb8aa3b, v6
	v_exp_f32_e32 v6, v6
	v_mov_b32_e32 v76, s28
	v_add_u32_e32 v11, -1, v8
	v_fma_f32 v13, -v11, v8, v7
	v_cmp_ge_f32_e64 s[56:57], 0, v13
	v_add_u32_e32 v13, 1, v8
	v_mul_f32_e32 v6, 0xbfb8aa3b, v6
	v_cndmask_b32_e64 v11, v8, v11, s[56:57]
	v_fma_f32 v8, -v13, v8, v7
	v_cmp_lt_f32_e64 s[56:57], 0, v8
	v_exp_f32_e32 v6, v6
	s_add_i32 s11, s11, s16
	v_cndmask_b32_e64 v8, v11, v13, s[56:57]
	v_mul_f32_e32 v11, 0x37800000, v8
	v_cndmask_b32_e32 v8, v8, v11, vcc
	v_cmp_class_f32_e32 vcc, v7, v219
	v_mul_f32_e32 v61, v21, v6
	s_cmpk_gt_i32 s11, 0x3fff
	v_cndmask_b32_e32 v7, v8, v7, vcc
	v_max_f32_e32 v7, 0x2b8cbccc, v7
	v_div_scale_f32 v8, s[0:1], v7, v7, v14
	v_rcp_f32_e32 v11, v8
	s_nop 0
	v_fma_f32 v13, -v8, v11, 1.0
	v_fmac_f32_e32 v11, v13, v11
	v_div_scale_f32 v13, vcc, v14, v7, v14
	v_mul_f32_e32 v15, v13, v11
	v_fma_f32 v16, -v8, v15, v13
	v_fmac_f32_e32 v15, v16, v11
	v_fma_f32 v8, -v8, v15, v13
	v_div_fmas_f32 v8, v8, v11, v15
	v_div_fixup_f32 v7, v8, v7, v14
	v_mul_f32_e32 v8, v12, v7
	v_cvt_pk_bf16_f32 v8, v8, s0
	v_div_scale_f32 v6, s[0:1], v61, v61, 1.0
	v_rcp_f32_e32 v11, v6
	s_nop 0
	v_cvt_pk_bf16_f32 v7, v7, s0
	v_lshlrev_b32_e32 v7, 16, v7
	v_mul_f32_e32 v7, v21, v7
	v_fma_f32 v12, -v6, v11, 1.0
	v_fmac_f32_e32 v11, v12, v11
	v_div_scale_f32 v12, vcc, 1.0, v61, 1.0
	v_mul_f32_e32 v13, v12, v11
	v_fma_f32 v14, -v6, v13, v12
	v_fmac_f32_e32 v13, v14, v11
	v_fma_f32 v6, -v6, v13, v12
	v_cvt_pk_bf16_f32 v7, v7, s0
	v_div_fmas_f32 v6, v6, v11, v13
	ds_write_b16 v27, v7 offset:2160
	v_mul_f32_e32 v7, v61, v10
	v_lshlrev_b32_e32 v8, 16, v8
	v_div_fixup_f32 v6, v6, v61, 1.0
	v_cvt_pk_bf16_f32 v7, v7, s0
	ds_write_b16 v27, v7 offset:4464
	v_mul_f32_e32 v7, v6, v9
	v_mul_f32_e32 v6, v6, v8
	v_cvt_pk_bf16_f32 v7, v7, s0
	v_cvt_pk_bf16_f32 v6, v6, s0
	ds_write_b16 v27, v7 offset:6768
	ds_write_b16 v27, v6 offset:9072
	ds_write_b32 v22, v61 offset:15936
	s_waitcnt lgkmcnt(0)
	ds_read_b128 v[6:9], v28
	ds_read_b128 v[10:13], v28 offset:6912
	ds_read_b128 v[62:65], v28 offset:2304
	ds_read_b128 v[66:69], v28 offset:64
	ds_read_b128 v[18:21], v28 offset:4608
	ds_read_b128 v[70:73], v28 offset:4672
	s_waitcnt lgkmcnt(0)
	v_mfma_f32_16x16x32_bf16 v[14:17], v[6:9], v[10:13], 0
	v_readlane_b32 s0, v255, 28
	v_readlane_b32 s1, v255, 29
	v_mfma_f32_16x16x32_bf16 v[6:9], v[6:9], v[18:21], 0
	v_mfma_f32_16x16x32_bf16 v[18:21], v[62:65], v[18:21], 0
	v_mfma_f32_16x16x32_bf16 v[10:13], v[62:65], v[10:13], 0
	ds_read_b128 v[62:65], v28 offset:6976
	s_waitcnt lgkmcnt(0)
	v_mfma_f32_16x16x32_bf16 v[14:17], v[66:69], v[62:65], v[14:17]
	v_mfma_f32_16x16x32_bf16 v[6:9], v[66:69], v[70:73], v[6:9]
	ds_read_b128 v[66:69], v28 offset:2368
	s_nop 5
	v_cndmask_b32_e64 v14, 0, v14, s[0:1]
	ds_write_b32 v59, v14 offset:9216
	s_waitcnt lgkmcnt(0)
	v_mfma_f32_16x16x32_bf16 v[18:21], v[66:69], v[70:73], v[18:21]
	v_cndmask_b32_e64 v6, 0, v6, s[0:1]
	ds_write_b32 v30, v6 offset:10496
	v_readlane_b32 s0, v255, 30
	v_mfma_f32_16x16x32_bf16 v[10:13], v[66:69], v[62:65], v[10:13]
	s_nop 3
	v_cndmask_b32_e64 v6, v18, 0, s[42:43]
	ds_write_b32 v30, v6 offset:11584
	v_readlane_b32 s1, v255, 31
	s_nop 0
	v_cndmask_b32_e64 v6, v10, 0, s[42:43]
	ds_write_b32 v30, v6 offset:12672
	v_cndmask_b32_e64 v6, v15, 0, s[42:43]
	ds_write_b32 v60, v6 offset:9216
	v_cndmask_b32_e64 v6, v7, 0, s[42:43]
	ds_write_b32 v31, v6 offset:10496
	v_cndmask_b32_e64 v6, v19, 0, s[0:1]
	ds_write_b32 v31, v6 offset:11584
	v_cndmask_b32_e64 v6, v11, 0, s[0:1]
	v_readlane_b32 s0, v255, 32
	v_readlane_b32 s1, v255, 33
	ds_write_b32 v31, v6 offset:12672
	s_nop 0
	v_cndmask_b32_e64 v6, 0, v16, s[0:1]
	ds_write_b32 v60, v6 offset:9296
	v_cndmask_b32_e64 v6, 0, v8, s[0:1]
	v_readlane_b32 s0, v255, 34
	v_readlane_b32 s1, v255, 35
	ds_write_b32 v32, v6 offset:10496
	s_nop 0
	v_cndmask_b32_e64 v6, v20, 0, s[0:1]
	ds_write_b32 v32, v6 offset:11584
	v_cndmask_b32_e64 v6, v12, 0, s[0:1]
	v_readlane_b32 s0, v255, 36
	v_readlane_b32 s1, v255, 37
	ds_write_b32 v32, v6 offset:12672
	s_nop 0
	v_cndmask_b32_e64 v6, 0, v17, s[0:1]
	ds_write_b32 v60, v6 offset:9376
	v_cndmask_b32_e64 v6, 0, v9, s[0:1]
	s_mov_b64 s[0:1], s[46:47]
	ds_write_b32 v33, v6 offset:10496
	v_cndmask_b32_e64 v6, v21, 0, s[0:1]
	ds_write_b32 v33, v6 offset:11584
	v_cndmask_b32_e64 v6, v13, 0, s[0:1]
	ds_write_b32 v33, v6 offset:12672
	s_waitcnt lgkmcnt(0)
	ds_read_b128 v[6:9], v76 offset:9296
	s_waitcnt lgkmcnt(0)
	ds_read_b128 v[8:11], v76 offset:9376
	s_waitcnt lgkmcnt(0)
	ds_read_b128 v[10:13], v76 offset:9456
	s_mov_b32 s0, 0x27600000
	v_fma_f32 v6, v24, v6, 0
	v_sub_f32_e32 v78, v34, v6
	v_fma_f32 v6, v24, v8, 0
	v_fma_f32 v7, v9, v78, 0
	v_add_f32_e32 v6, v6, v7
	v_sub_f32_e32 v79, v35, v6
	ds_read_b128 v[6:9], v76 offset:9536
	s_waitcnt lgkmcnt(0)
	v_fma_f32 v10, v24, v10, 0
	v_fma_f32 v11, v11, v78, 0
	v_fma_f32 v12, v12, v79, 0
	v_add_f32_e32 v10, v10, v11
	v_add_f32_e32 v10, v10, v12
	v_sub_f32_e32 v80, v36, v10
	ds_read_b128 v[10:13], v76 offset:9616
	ds_read_b128 v[14:17], v76 offset:9632
	v_fma_f32 v6, v24, v6, 0
	v_fma_f32 v7, v78, v7, 0
	v_fma_f32 v8, v8, v79, 0
	v_fma_f32 v9, v9, v80, 0
	v_add_f32_e32 v6, v6, v7
	v_add_f32_e32 v7, v8, v9
	v_add_f32_e32 v6, v6, v7
	v_sub_f32_e32 v81, v37, v6
	ds_read_b128 v[6:9], v76 offset:9696
	s_waitcnt lgkmcnt(0)
; #define LAS __attribute__((address_space(3)))
; __device__ __forceinline__ void pc_phase(LAS unsigned char* lds, const bf16* Pp_, const bf16* LO, const float* mu, const float* w0, const float* a0, const float* k_k, const float* k_a, const float* r_k, ...
;     ...
;           for (int i = 1; i < 16; ++i) {
;               if (i + 1 < 16) {
; #pragma unroll
;                   for (int c4 = 0; c4 < 4; ++c4) Ln[c4] = *(const LAS f32x4*)(AKB + (i + 1) * 20 + 4 * c4); }
;               float a4[4] = {0.f, 0.f, 0.f, 0.f};
; #pragma unroll
;               for (int mm = 0; mm < i; ++mm) a4[mm & 3] += Lc[mm >> 2][mm & 3] * Tc[mm];
;               Tc[i] = ((i == j) ? 1.0f : 0.0f) - ((a4[0] + a4[1]) + (a4[2] + a4[3]));
; #pragma unroll
;               for (int c4 = 0; c4 < 4; ++c4) Lc[c4] = Ln[c4]; }
	ds_read_b128 v[16:19], v76 offset:9712
	v_fma_f32 v10, v24, v10, 0
	v_fma_f32 v11, v78, v11, 0
	v_fma_f32 v12, v12, v79, 0
	v_fma_f32 v13, v13, v80, 0
	v_fmac_f32_e32 v10, v14, v81
	v_add_f32_e32 v10, v11, v10
	v_add_f32_e32 v11, v12, v13
	v_add_f32_e32 v10, v11, v10
	v_sub_f32_e32 v82, v38, v10
	ds_read_b128 v[10:13], v76 offset:9776
	s_waitcnt lgkmcnt(0)
	ds_read_b128 v[18:21], v76 offset:9792
	v_fma_f32 v6, v24, v6, 0
	v_fma_f32 v7, v78, v7, 0
	v_fma_f32 v8, v8, v79, 0
	v_fma_f32 v9, v9, v80, 0
	v_fmac_f32_e32 v6, v16, v81
	v_fmac_f32_e32 v7, v17, v82
	v_add_f32_e32 v6, v6, v7
	v_add_f32_e32 v7, v8, v9
	v_add_f32_e32 v6, v7, v6
	v_sub_f32_e32 v83, v39, v6
	ds_read_b128 v[6:9], v76 offset:9856
	ds_read_b128 v[14:17], v76 offset:9872
	v_fma_f32 v10, v24, v10, 0
	v_fma_f32 v11, v78, v11, 0
	v_fma_f32 v12, v79, v12, 0
	v_fma_f32 v13, v13, v80, 0
	s_waitcnt lgkmcnt(0)
	v_fmac_f32_e32 v10, v18, v81
	v_fmac_f32_e32 v11, v19, v82
	v_fmac_f32_e32 v12, v20, v83
	v_add_f32_e32 v10, v10, v11
	v_add_f32_e32 v11, v13, v12
	v_add_f32_e32 v10, v10, v11
	v_sub_f32_e32 v84, v40, v10
	ds_read_b128 v[10:13], v76 offset:9936
	ds_read_b128 v[18:21], v76 offset:9952
	ds_read_b128 v[62:65], v76 offset:9968
	v_fma_f32 v6, v24, v6, 0
	v_fma_f32 v7, v78, v7, 0
	v_fma_f32 v8, v79, v8, 0
	v_fma_f32 v9, v9, v80, 0
	v_fmac_f32_e32 v6, v14, v81
	v_fmac_f32_e32 v7, v15, v82
	v_fmac_f32_e32 v8, v16, v83
	v_fmac_f32_e32 v9, v17, v84
	v_add_f32_e32 v6, v6, v7
	v_add_f32_e32 v7, v8, v9
	v_add_f32_e32 v6, v6, v7
	s_waitcnt lgkmcnt(0)
	v_fma_f32 v10, v24, v10, 0
	v_sub_f32_e32 v85, v41, v6
	ds_read_b128 v[6:9], v76 offset:10016
	ds_read_b128 v[14:17], v76 offset:10032
	ds_read_b128 v[64:67], v76 offset:10048
	v_fma_f32 v11, v78, v11, 0
	v_fma_f32 v12, v79, v12, 0
	v_fma_f32 v13, v80, v13, 0
	v_fmac_f32_e32 v10, v18, v81
	v_fmac_f32_e32 v11, v19, v82
	v_fmac_f32_e32 v12, v20, v83
	v_fmac_f32_e32 v13, v21, v84
	v_fmac_f32_e32 v10, v62, v85
	v_add_f32_e32 v10, v11, v10
	v_add_f32_e32 v11, v12, v13
	v_add_f32_e32 v10, v11, v10
	s_waitcnt lgkmcnt(0)
	v_fma_f32 v6, v24, v6, 0
	v_fma_f32 v7, v78, v7, 0
	v_sub_f32_e32 v86, v42, v10
	ds_read_b128 v[10:13], v76 offset:10096
	ds_read_b128 v[18:21], v76 offset:10112
	ds_read_b128 v[66:69], v76 offset:10128
	v_fma_f32 v8, v79, v8, 0
	v_fma_f32 v9, v80, v9, 0
	v_fmac_f32_e32 v6, v81, v14
	v_fmac_f32_e32 v7, v15, v82
	v_fmac_f32_e32 v8, v16, v83
	v_fmac_f32_e32 v9, v17, v84
	v_fmac_f32_e32 v6, v64, v85
	v_fmac_f32_e32 v7, v65, v86
	v_add_f32_e32 v6, v6, v7
	v_add_f32_e32 v7, v8, v9
	v_add_f32_e32 v6, v7, v6
	s_waitcnt lgkmcnt(0)
	v_fma_f32 v10, v24, v10, 0
	v_fma_f32 v11, v78, v11, 0
	v_fma_f32 v12, v79, v12, 0
	v_sub_f32_e32 v87, v43, v6
	ds_read_b128 v[6:9], v76 offset:10176
	ds_read_b128 v[14:17], v76 offset:10192
	ds_read_b128 v[62:65], v76 offset:10208
	v_fma_f32 v13, v80, v13, 0
	v_fmac_f32_e32 v10, v81, v18
	v_fmac_f32_e32 v11, v19, v82
	v_fmac_f32_e32 v12, v20, v83
	v_fmac_f32_e32 v13, v21, v84
	v_fmac_f32_e32 v10, v66, v85
	v_fmac_f32_e32 v11, v67, v86
	v_fmac_f32_e32 v12, v68, v87
	v_add_f32_e32 v10, v10, v11
	v_add_f32_e32 v11, v13, v12
	v_add_f32_e32 v10, v10, v11
	s_waitcnt lgkmcnt(0)
	v_fma_f32 v6, v24, v6, 0
	v_fma_f32 v7, v78, v7, 0
	v_fma_f32 v8, v79, v8, 0
	v_fma_f32 v9, v80, v9, 0
	v_sub_f32_e32 v88, v44, v10
	ds_read_b128 v[10:13], v76 offset:10256
	ds_read_b128 v[18:21], v76 offset:10272
	ds_read_b128 v[66:69], v76 offset:10288
	ds_read_b128 v[70:73], v76 offset:10304
	v_fmac_f32_e32 v6, v81, v14
	v_fmac_f32_e32 v7, v82, v15
	v_fmac_f32_e32 v8, v16, v83
	v_fmac_f32_e32 v9, v17, v84
	v_fmac_f32_e32 v6, v62, v85
	v_fmac_f32_e32 v7, v63, v86
	v_fmac_f32_e32 v8, v64, v87
	v_fmac_f32_e32 v9, v65, v88
	v_add_f32_e32 v6, v6, v7
	v_add_f32_e32 v7, v8, v9
	s_waitcnt lgkmcnt(0)
	v_fma_f32 v10, v24, v10, 0
	v_add_f32_e32 v6, v6, v7
	v_fma_f32 v11, v78, v11, 0
	v_fma_f32 v12, v79, v12, 0
	v_fma_f32 v13, v80, v13, 0
	v_fmac_f32_e32 v10, v81, v18
	v_sub_f32_e32 v71, v45, v6
	ds_read_b128 v[6:9], v76 offset:10336
	ds_read_b128 v[14:17], v76 offset:10352
	ds_read_b128 v[62:65], v76 offset:10368
	ds_read_b128 v[72:75], v76 offset:10384
	v_fmac_f32_e32 v11, v82, v19
	v_fmac_f32_e32 v12, v20, v83
	v_fmac_f32_e32 v13, v21, v84
	v_fmac_f32_e32 v10, v66, v85
	v_fmac_f32_e32 v11, v67, v86
	v_fmac_f32_e32 v12, v68, v87
	v_fmac_f32_e32 v13, v69, v88
	v_fmac_f32_e32 v10, v70, v71
	v_add_f32_e32 v10, v11, v10
	v_add_f32_e32 v11, v12, v13
	s_waitcnt lgkmcnt(0)
	v_fma_f32 v6, v24, v6, 0
	v_fma_f32 v7, v78, v7, 0
	v_add_f32_e32 v10, v11, v10
	v_fmac_f32_e32 v6, v81, v14
	v_fmac_f32_e32 v7, v82, v15
	v_sub_f32_e32 v70, v46, v10
	v_fmac_f32_e32 v6, v62, v85
	v_fmac_f32_e32 v7, v63, v86
	v_fmac_f32_e32 v6, v72, v71
	v_fmac_f32_e32 v7, v73, v70
	v_add_f32_e32 v6, v6, v7
	v_fma_f32 v7, v79, v8, 0
	v_fma_f32 v8, v80, v9, 0
	v_fmac_f32_e32 v7, v83, v16
	v_fmac_f32_e32 v8, v17, v84
	ds_read_b128 v[10:13], v76 offset:10416
	ds_read_b128 v[18:21], v76 offset:10432
	ds_read_b128 v[66:69], v76 offset:10448
	ds_read_b128 v[74:77], v76 offset:10464
	v_fmac_f32_e32 v7, v64, v87
	v_fmac_f32_e32 v8, v65, v88
	v_add_f32_e32 v7, v7, v8
	v_add_f32_e32 v6, v7, v6
	s_waitcnt lgkmcnt(0)
; #define LAS __attribute__((address_space(3)))
; #define PC_FENCE() asm volatile("s_waitcnt lgkmcnt(0)" ::: "memory")
; __device__ __forceinline__ void pc_phase(LAS unsigned char* lds, const bf16* Pp_, const bf16* LO, const float* mu, const float* w0, const float* a0, const float* k_k, const float* k_a, const float* r_k, ...
;     ...
;           for (int i = 1; i < 16; ++i) {
;               if (i + 1 < 16) {
; #pragma unroll
;                   for (int c4 = 0; c4 < 4; ++c4) Ln[c4] = *(const LAS f32x4*)(AKB + (i + 1) * 20 + 4 * c4); }
;               float a4[4] = {0.f, 0.f, 0.f, 0.f};
; #pragma unroll
;               for (int mm = 0; mm < i; ++mm) a4[mm & 3] += Lc[mm >> 2][mm & 3] * Tc[mm];
;               Tc[i] = ((i == j) ? 1.0f : 0.0f) - ((a4[0] + a4[1]) + (a4[2] + a4[3]));
; #pragma unroll
;               for (int c4 = 0; c4 < 4; ++c4) Lc[c4] = Ln[c4]; }
; #pragma unroll
;           for (int i = 0; i < 16; ++i) TT[i * 17 + j] = Tc[i]; }
;         PC_FENCE();
; #pragma unroll
;         for (int q = 0; q < 4; ++q) { const int i = g + 4 * q, j = m; float acc = 0.f;
; #pragma unroll
;             for (int mm = 0; mm < 16; ++mm) acc += TT[i * 17 + mm] * AKK[mm * 17 + j];
;             M1[i * 17 + j] = acc; }
	v_fma_f32 v7, v24, v10, 0
	v_fma_f32 v8, v78, v11, 0
	v_fma_f32 v9, v79, v12, 0
	v_fma_f32 v10, v80, v13, 0
	v_fmac_f32_e32 v7, v81, v18
	v_fmac_f32_e32 v8, v82, v19
	v_fmac_f32_e32 v9, v83, v20
	v_sub_f32_e32 v6, v26, v6
	v_fmac_f32_e32 v10, v84, v21
	v_fmac_f32_e32 v7, v66, v85
	v_fmac_f32_e32 v8, v67, v86
	v_fmac_f32_e32 v9, v68, v87
	v_fmac_f32_e32 v10, v69, v88
	v_fmac_f32_e32 v7, v74, v71
	v_fmac_f32_e32 v8, v75, v70
	v_fmac_f32_e32 v9, v76, v6
	v_add_f32_e32 v7, v7, v8
	v_add_f32_e32 v8, v10, v9
	v_add_f32_e32 v7, v7, v8
	v_add_u32_e32 v8, 0x3400, v23
	ds_write2_b32 v8, v24, v78 offset0:112 offset1:129
	ds_write2_b32 v8, v79, v80 offset0:146 offset1:163
	ds_write2_b32 v8, v81, v82 offset0:180 offset1:197
	ds_write2_b32 v8, v83, v84 offset0:214 offset1:231
	v_add_u32_e32 v8, 0x3600, v23
	ds_write2_b32 v8, v85, v86 offset0:120 offset1:137
	v_add_u32_e32 v8, 0x3800, v23
	v_sub_f32_e32 v7, v47, v7
	ds_write2_b32 v8, v87, v88 offset0:26 offset1:43
	ds_write2_b32 v8, v71, v70 offset0:60 offset1:77
	ds_write2_b32 v8, v6, v7 offset0:94 offset1:111
	v_add_u32_e32 v62, s28, v29
	s_waitcnt lgkmcnt(0)
	v_add_u32_e32 v6, 0x35c0, v62
	v_add_u32_e32 v63, 0x2800, v23
	ds_read2_b32 v[6:7], v6 offset1:1
	ds_read2_b32 v[10:11], v63 offset0:64 offset1:81
	v_add_u32_e32 v8, 0x35c8, v62
	ds_read2_b32 v[8:9], v8 offset1:1
	ds_read2_b32 v[16:17], v63 offset0:98 offset1:115
	v_add_u32_e32 v12, 0x35d8, v62
	v_add_u32_e32 v18, 0x35e0, v62
	s_waitcnt lgkmcnt(0)
	v_fma_f32 v70, v6, v10, 0
	v_fmac_f32_e32 v70, v7, v11
	v_fmac_f32_e32 v70, v8, v16
	v_add_u32_e32 v6, 0x35d0, v62
	v_fmac_f32_e32 v70, v9, v17
	ds_read2_b32 v[8:9], v6 offset1:1
	ds_read2_b32 v[6:7], v63 offset0:132 offset1:149
	ds_read2_b32 v[12:13], v12 offset1:1
	ds_read2_b32 v[14:15], v63 offset0:166 offset1:183
	ds_read2_b32 v[20:21], v18 offset1:1
	ds_read2_b32 v[18:19], v63 offset0:200 offset1:217
	s_waitcnt lgkmcnt(0)
	v_fmac_f32_e32 v70, v8, v6
	v_fmac_f32_e32 v70, v9, v7
	v_add_u32_e32 v8, 0x35e8, v62
	v_fmac_f32_e32 v70, v12, v14
	ds_read2_b32 v[64:65], v8 offset1:1
	ds_read2_b32 v[8:9], v63 offset0:234 offset1:251
	v_fmac_f32_e32 v70, v13, v15
	v_fmac_f32_e32 v70, v20, v18
	v_add_u32_e32 v12, 0x35f0, v62
	v_add_u32_e32 v20, 0x2c00, v23
	ds_read2_b32 v[66:67], v12 offset1:1
	ds_read2_b32 v[12:13], v20 offset0:12 offset1:29
	v_fmac_f32_e32 v70, v21, v19
	v_add_u32_e32 v21, 0x35f8, v62
	s_waitcnt lgkmcnt(0)
	v_fmac_f32_e32 v70, v64, v8
	v_add_u32_e32 v63, 0x36d0, v62
	ds_read2_b32 v[68:69], v21 offset1:1
	ds_read2_b32 v[20:21], v20 offset0:46 offset1:63
	v_fmac_f32_e32 v70, v65, v9
	ds_read2_b32 v[64:65], v63 offset1:1
	v_fmac_f32_e32 v70, v66, v12
	v_add_u32_e32 v66, 0x36d8, v62
	v_fmac_f32_e32 v70, v67, v13
	ds_read2_b32 v[66:67], v66 offset1:1
	s_waitcnt lgkmcnt(0)
	v_fmac_f32_e32 v70, v68, v20
	v_fma_f32 v68, v10, v64, 0
	v_add_u32_e32 v64, 0x36e0, v62
	v_fmac_f32_e32 v68, v11, v65
	ds_read2_b32 v[64:65], v64 offset1:1
	v_fmac_f32_e32 v68, v16, v66
	v_add_u32_e32 v66, 0x36e8, v62
	v_fmac_f32_e32 v68, v17, v67
	ds_read2_b32 v[66:67], v66 offset1:1
	s_waitcnt lgkmcnt(0)
	v_fmac_f32_e32 v68, v6, v64
	v_add_u32_e32 v64, 0x36f0, v62
	v_fmac_f32_e32 v68, v7, v65
	ds_read2_b32 v[64:65], v64 offset1:1
	v_fmac_f32_e32 v68, v14, v66
	v_add_u32_e32 v66, 0x36f8, v62
	v_fmac_f32_e32 v68, v15, v67
	ds_read2_b32 v[66:67], v66 offset1:1
	s_waitcnt lgkmcnt(0)
	v_fmac_f32_e32 v68, v18, v64
	v_add_u32_e32 v64, 0x3700, v62
	v_fmac_f32_e32 v68, v19, v65
	ds_read2_b32 v[64:65], v64 offset1:1
	v_fmac_f32_e32 v68, v8, v66
	v_add_u32_e32 v66, 0x3708, v62
	v_fmac_f32_e32 v68, v9, v67
	ds_read2_b32 v[66:67], v66 offset1:1
	s_waitcnt lgkmcnt(0)
	v_fmac_f32_e32 v68, v12, v64
	v_add_u32_e32 v64, 0x37e0, v62
	v_fmac_f32_e32 v68, v13, v65
	ds_read2_b32 v[64:65], v64 offset1:1
	v_add_u32_e32 v63, v23, v29
	v_fmac_f32_e32 v68, v20, v66
	v_fmac_f32_e32 v70, v69, v21
	v_fmac_f32_e32 v68, v21, v67
	v_add_u32_e32 v66, 0x3800, v63
	ds_write2_b32 v66, v70, v68 offset0:128 offset1:196
	v_add_u32_e32 v66, 0x37f0, v62
	ds_read2_b32 v[66:67], v66 offset1:1
	s_waitcnt lgkmcnt(0)
	v_fma_f32 v70, v10, v64, 0
	v_add_u32_e32 v64, 0x37e8, v62
	v_fmac_f32_e32 v70, v11, v65
	ds_read2_b32 v[64:65], v64 offset1:1
	v_add_u32_e32 v68, 0x37f8, v62
	ds_read2_b32 v[68:69], v68 offset1:1
	s_waitcnt lgkmcnt(0)
	v_fmac_f32_e32 v70, v16, v64
	v_add_u32_e32 v64, 0x3800, v62
	v_fmac_f32_e32 v70, v17, v65
	ds_read2_b32 v[64:65], v64 offset1:1
	v_fmac_f32_e32 v70, v6, v66
	v_add_u32_e32 v66, 0x3808, v62
	v_fmac_f32_e32 v70, v7, v67
	ds_read2_b32 v[66:67], v66 offset1:1
	v_fmac_f32_e32 v70, v14, v68
	v_add_u32_e32 v68, 0x3810, v62
	v_fmac_f32_e32 v70, v15, v69
	ds_read2_b32 v[68:69], v68 offset1:1
	s_waitcnt lgkmcnt(0)
	v_fmac_f32_e32 v70, v18, v64
	v_fmac_f32_e32 v70, v19, v65
	v_fmac_f32_e32 v70, v8, v66
	v_add_u32_e32 v66, 0x38f0, v62
	v_fmac_f32_e32 v70, v9, v67
	ds_read2_b32 v[66:67], v66 offset1:1
	v_fmac_f32_e32 v70, v12, v68
	v_add_u32_e32 v68, 0x38f8, v62
	v_fmac_f32_e32 v70, v13, v69
	ds_read2_b32 v[68:69], v68 offset1:1
	s_waitcnt lgkmcnt(0)
	v_fma_f32 v66, v10, v66, 0
	v_add_u32_e32 v10, 0x3900, v62
	v_fmac_f32_e32 v66, v11, v67
	ds_read2_b32 v[10:11], v10 offset1:1
	v_fmac_f32_e32 v66, v16, v68
	v_add_u32_e32 v16, 0x3908, v62
	v_add_u32_e32 v64, 0x3818, v62
	v_fmac_f32_e32 v66, v17, v69
	ds_read2_b32 v[16:17], v16 offset1:1
	ds_read2_b32 v[64:65], v64 offset1:1
	s_waitcnt lgkmcnt(0)
	v_fmac_f32_e32 v66, v6, v10
	v_fmac_f32_e32 v66, v7, v11
	v_add_u32_e32 v6, 0x3918, v62
	v_fmac_f32_e32 v66, v14, v16
	v_add_u32_e32 v10, 0x3920, v62
	v_add_u32_e32 v14, 0x3928, v62
	v_fmac_f32_e32 v66, v15, v17
	ds_read2_b32 v[6:7], v6 offset1:1
	ds_read2_b32 v[10:11], v10 offset1:1
	ds_read2_b32 v[14:15], v14 offset1:1
	v_fmac_f32_e32 v70, v20, v64
	v_add_u32_e32 v64, 0x3910, v62
	v_fmac_f32_e32 v70, v21, v65
	ds_read2_b32 v[64:65], v64 offset1:1
	v_add_u32_e32 v16, 0x3188, v49
	s_waitcnt lgkmcnt(0)
; #define LAS __attribute__((address_space(3)))
; __device__ __forceinline__ float bf2f(bf16 b) { return __uint_as_float((unsigned)b << 16); }
; __device__ __forceinline__ u32x4 pack8v(f32x4 lo, f32x4 hi) { u32x4 w; w.x = pk_bf16(lo.x, lo.y); w.y = pk_bf16(lo.z, lo.w); w.z = pk_bf16(hi.x, hi.y); w.w = pk_bf16(hi.z, hi.w); return w; }
; __device__ __forceinline__ void pc_phase(LAS unsigned char* lds, const bf16* Pp_, const bf16* LO, const float* mu, const float* w0, const float* a0, const float* k_k, const float* k_a, const float* r_k, ...
;     ...
;         for (int q = 0; q < 4; ++q) { const int i = g + 4 * q, j = m; float acc = 0.f;
; #pragma unroll
;             for (int mm = 0; mm < 16; ++mm) acc += TT[i * 17 + mm] * AKK[mm * 17 + j];
;             M1[i * 17 + j] = acc; }
;         PC_FENCE();
;         { unsigned char* ob = OPS + (size_t)item * PCI_BYTES;
; #pragma unroll
;           for (int ks = 0; ks < 2; ++ks) { u32x4 w; const LAS u32x2* p0 = (const LAS u32x2*)(XKK + m * 72 + 32 * ks + 4 * g); const LAS u32x2* p1 = (const LAS u32x2*)(XKK + m * 72 + 32 * ks + 16 + 4 * g);
;               u32x2 a = *p0, b = *p1; w.x = a.x; w.y = a.y; w.z = b.x; w.w = b.y; *(u32x4*)(ob + ks * 1024 + lane * 16) = w;
;               p0 = (const LAS u32x2*)(XR + m * 72 + 32 * ks + 4 * g); p1 = (const LAS u32x2*)(XR + m * 72 + 32 * ks + 16 + 4 * g);
;               a = *p0; b = *p1; w.x = a.x; w.y = a.y; w.z = b.x; w.w = b.y; *(u32x4*)(ob + (2 + ks) * 1024 + lane * 16) = w; }
;           { f32x4 lo, hi;
; #pragma unroll
;             for (int j = 0; j < 4; ++j) { lo[j] = TT[m * 17 + 4 * g + j]; hi[j] = M1[m * 17 + 4 * g + j]; }
;             *(u32x4*)(ob + 4 * 1024 + lane * 16) = pack8v(lo, hi);
; #pragma unroll
;             for (int j = 0; j < 4; ++j) { lo[j] = ARK[m * 17 + 4 * g + j]; hi[j] = -ARB[m * 17 + 4 * g + j]; }
;             *(u32x4*)(ob + 5 * 1024 + lane * 16) = pack8v(lo, hi); }
; #pragma unroll
;           for (int kt = 0; kt < 4; ++kt) { const int kcol = 16 * kt + m; const float pc = PCL[kcol]; f32x4 lo, hi;
; #pragma unroll
;               for (int j = 0; j < 4; ++j) { lo[j] = bf2f(XK[(4 * g + j) * 72 + kcol]) * pc; hi[j] = -bf2f(XB[(4 * g + j) * 72 + kcol]) * pc; }
;               *(u32x4*)(ob + (6 + kt) * 1024 + lane * 16) = pack8v(lo, hi); }
;           *(float*)(ob + 10240 + lane * 4) = P; }
	v_fmac_f32_e32 v66, v18, v64
	v_fmac_f32_e32 v66, v19, v65
	v_fmac_f32_e32 v66, v8, v6
	v_fmac_f32_e32 v66, v9, v7
	v_fmac_f32_e32 v66, v12, v10
	v_fmac_f32_e32 v66, v13, v11
	v_fmac_f32_e32 v66, v20, v14
	v_fmac_f32_e32 v66, v21, v15
	v_add_u32_e32 v6, 0x3c00, v63
	ds_write2_b32 v6, v70, v66 offset0:8 offset1:76
	s_waitcnt lgkmcnt(0)
	ds_read2_b64 v[8:11], v48 offset1:4
	v_lshl_add_u64 v[6:7], s[88:89], 0, v[2:3]
	v_add_co_u32_e32 v12, vcc, s0, v6
	v_add_u32_e32 v14, 0x800, v48
	s_nop 0
	v_addc_co_u32_e32 v13, vcc, 0, v7, vcc
	s_waitcnt lgkmcnt(0)
	global_store_dwordx4 v[12:13], v[8:11], off
	ds_read2_b64 v[8:11], v14 offset0:32 offset1:36
	s_mov_b32 s0, 0x27601000
	s_waitcnt lgkmcnt(0)
	global_store_dwordx4 v[12:13], v[8:11], off offset:2048
	ds_read2_b64 v[8:11], v48 offset0:8 offset1:12
	s_waitcnt lgkmcnt(0)
	global_store_dwordx4 v[12:13], v[8:11], off offset:1024
	ds_read2_b64 v[8:11], v14 offset0:40 offset1:44
	v_add_u32_e32 v14, 0x3a08, v49
	s_waitcnt lgkmcnt(0)
	global_store_dwordx4 v[12:13], v[8:11], off offset:3072
	s_nop 1
	v_add_u32_e32 v8, 0x35c0, v49
	v_add_u32_e32 v10, 0x3a00, v49
	v_add_u32_e32 v12, 0x35c8, v49
	ds_read2_b32 v[8:9], v8 offset1:1
	ds_read2_b32 v[10:11], v10 offset1:1
	ds_read2_b32 v[12:13], v12 offset1:1
	ds_read2_b32 v[14:15], v14 offset1:1
	s_waitcnt lgkmcnt(0)
	v_cvt_pk_bf16_f32 v8, v8, v9
	v_cvt_pk_bf16_f32 v10, v10, v11
	v_cvt_pk_bf16_f32 v9, v12, v13
	v_add_co_u32_e32 v12, vcc, s0, v6
	v_cvt_pk_bf16_f32 v11, v14, v15
	s_nop 0
	v_addc_co_u32_e32 v13, vcc, 0, v7, vcc
	global_store_dwordx4 v[12:13], v[8:11], off
	v_add_u32_e32 v14, 0x3180, v49
	s_mov_b32 s0, 0x27602000
	v_add_u32_e32 v8, 0x2d40, v49
	v_add_u32_e32 v10, 0x2d48, v49
	ds_read2_b32 v[8:9], v8 offset1:1
	ds_read2_b32 v[10:11], v10 offset1:1
	ds_read2_b32 v[14:15], v14 offset1:1
	ds_read2_b32 v[16:17], v16 offset1:1
	s_waitcnt lgkmcnt(0)
	v_cvt_pk_bf16_f32 v8, v8, v9
	v_cvt_pk_bf16_f32 v9, v10, v11
	v_pk_add_f32 v[10:11], v[14:15], 0 neg_lo:[1,1] neg_hi:[1,1]
	v_pk_add_f32 v[14:15], v[16:17], 0 neg_lo:[1,1] neg_hi:[1,1]
	v_cvt_pk_bf16_f32 v10, v10, v11
	v_cvt_pk_bf16_f32 v11, v14, v15
	global_store_dwordx4 v[12:13], v[8:11], off offset:1024
	ds_read_u16 v9, v51 offset:4608
	ds_read_u16 v10, v50 offset:4608
	ds_read_b32 v8, v23 offset:15936
	ds_read_u16 v14, v51 offset:6912
	ds_read_u16 v16, v50 offset:6912
	s_waitcnt lgkmcnt(0)
	v_lshlrev_b32_e32 v11, 16, v9
	v_lshlrev_b32_e32 v10, 16, v10
	v_pk_mul_f32 v[10:11], v[8:9], v[10:11] op_sel_hi:[0,1]
	v_lshlrev_b32_e32 v15, 16, v14
	v_lshlrev_b32_e32 v14, 16, v16
	ds_read_u16 v9, v53 offset:4608
	ds_read_u16 v16, v52 offset:4608
	ds_read_u16 v18, v53 offset:6912
	ds_read_u16 v20, v52 offset:6912
	s_waitcnt lgkmcnt(0)
	v_lshlrev_b32_e32 v17, 16, v9
	v_lshlrev_b32_e32 v16, 16, v16
	v_lshlrev_b32_e32 v19, 16, v18
	v_lshlrev_b32_e32 v18, 16, v20
	v_pk_mul_f32 v[14:15], v[8:9], v[14:15] op_sel_hi:[0,1] neg_lo:[0,1] neg_hi:[0,1]
	v_pk_mul_f32 v[16:17], v[8:9], v[16:17] op_sel_hi:[0,1]
	v_pk_mul_f32 v[18:19], v[8:9], v[18:19] op_sel_hi:[0,1] neg_lo:[0,1] neg_hi:[0,1]
	v_cvt_pk_bf16_f32 v8, v10, v11
	v_cvt_pk_bf16_f32 v9, v16, v17
	v_cvt_pk_bf16_f32 v10, v14, v15
	v_cvt_pk_bf16_f32 v11, v18, v19
	global_store_dwordx4 v[12:13], v[8:11], off offset:2048
	ds_read_u16 v9, v51 offset:4640
	ds_read_u16 v10, v50 offset:4640
	ds_read_b32 v8, v23 offset:16000
	ds_read_u16 v14, v51 offset:6944
	ds_read_u16 v16, v50 offset:6944
	s_waitcnt lgkmcnt(0)
	v_lshlrev_b32_e32 v11, 16, v9
	v_lshlrev_b32_e32 v10, 16, v10
	v_pk_mul_f32 v[10:11], v[8:9], v[10:11] op_sel_hi:[0,1]
	v_lshlrev_b32_e32 v15, 16, v14
	v_lshlrev_b32_e32 v14, 16, v16
	ds_read_u16 v9, v53 offset:4640
	ds_read_u16 v16, v54 offset:4640
	ds_read_u16 v18, v53 offset:6944
	ds_read_u16 v20, v54 offset:6944
	s_waitcnt lgkmcnt(0)
	v_lshlrev_b32_e32 v17, 16, v9
	v_lshlrev_b32_e32 v16, 16, v16
	v_lshlrev_b32_e32 v19, 16, v18
	v_lshlrev_b32_e32 v18, 16, v20
	v_pk_mul_f32 v[14:15], v[8:9], v[14:15] op_sel_hi:[0,1] neg_lo:[0,1] neg_hi:[0,1]
	v_pk_mul_f32 v[16:17], v[8:9], v[16:17] op_sel_hi:[0,1]
	v_pk_mul_f32 v[18:19], v[8:9], v[18:19] op_sel_hi:[0,1] neg_lo:[0,1] neg_hi:[0,1]
	v_cvt_pk_bf16_f32 v8, v10, v11
	v_cvt_pk_bf16_f32 v9, v16, v17
	v_cvt_pk_bf16_f32 v10, v14, v15
	v_cvt_pk_bf16_f32 v11, v18, v19
	global_store_dwordx4 v[12:13], v[8:11], off offset:3072
	ds_read_u16 v9, v51 offset:4672
	ds_read_u16 v10, v50 offset:4672
	ds_read_b32 v8, v23 offset:16064
	ds_read_u16 v12, v51 offset:6976
	ds_read_u16 v14, v50 offset:6976
	s_waitcnt lgkmcnt(0)
	v_lshlrev_b32_e32 v11, 16, v9
	v_lshlrev_b32_e32 v10, 16, v10
	v_pk_mul_f32 v[10:11], v[8:9], v[10:11] op_sel_hi:[0,1]
	v_lshlrev_b32_e32 v13, 16, v12
	v_lshlrev_b32_e32 v12, 16, v14
	ds_read_u16 v9, v53 offset:4672
	ds_read_u16 v14, v54 offset:4672
	ds_read_u16 v16, v53 offset:6976
	ds_read_u16 v18, v54 offset:6976
	s_waitcnt lgkmcnt(0)
	v_pk_mul_f32 v[12:13], v[8:9], v[12:13] op_sel_hi:[0,1] neg_lo:[0,1] neg_hi:[0,1]
	v_lshlrev_b32_e32 v15, 16, v9
	v_lshlrev_b32_e32 v14, 16, v14
	v_lshlrev_b32_e32 v17, 16, v16
	v_lshlrev_b32_e32 v16, 16, v18
	v_pk_mul_f32 v[14:15], v[8:9], v[14:15] op_sel_hi:[0,1]
	v_pk_mul_f32 v[16:17], v[8:9], v[16:17] op_sel_hi:[0,1] neg_lo:[0,1] neg_hi:[0,1]
	v_cvt_pk_bf16_f32 v8, v10, v11
	v_cvt_pk_bf16_f32 v10, v12, v13
	v_add_co_u32_e32 v12, vcc, s0, v6
	v_cvt_pk_bf16_f32 v9, v14, v15
	v_cvt_pk_bf16_f32 v11, v16, v17
	v_addc_co_u32_e32 v13, vcc, 0, v7, vcc
	global_store_dwordx4 v[12:13], v[8:11], off
	ds_read_u16 v7, v56 offset:4608
	ds_read_u16 v8, v25 offset:4608
	ds_read_b32 v6, v55 offset:15936
	ds_read_u16 v10, v56 offset:6912
	ds_read_u16 v14, v25 offset:6912
	s_waitcnt lgkmcnt(0)
	v_lshlrev_b32_e32 v9, 16, v7
	v_lshlrev_b32_e32 v8, 16, v8
	v_pk_mul_f32 v[8:9], v[6:7], v[8:9] op_sel_hi:[0,1]
	v_lshlrev_b32_e32 v11, 16, v10
	v_lshlrev_b32_e32 v10, 16, v14
	ds_read_u16 v7, v58 offset:4608
	ds_read_u16 v14, v57 offset:4608
	ds_read_u16 v16, v58 offset:6912
	ds_read_u16 v18, v57 offset:6912
	v_readlane_b32 s0, v254, 9
	v_readlane_b32 s1, v254, 10
	s_waitcnt lgkmcnt(0)
	v_lshlrev_b32_e32 v15, 16, v7
	v_lshlrev_b32_e32 v14, 16, v14
	v_lshlrev_b32_e32 v17, 16, v16
	v_lshlrev_b32_e32 v16, 16, v18
	v_pk_mul_f32 v[10:11], v[6:7], v[10:11] op_sel_hi:[0,1] neg_lo:[0,1] neg_hi:[0,1]
	v_pk_mul_f32 v[14:15], v[6:7], v[14:15] op_sel_hi:[0,1]
	v_pk_mul_f32 v[16:17], v[6:7], v[16:17] op_sel_hi:[0,1] neg_lo:[0,1] neg_hi:[0,1]
	v_cvt_pk_bf16_f32 v6, v8, v9
	v_cvt_pk_bf16_f32 v7, v14, v15
	v_cvt_pk_bf16_f32 v8, v10, v11
	v_cvt_pk_bf16_f32 v9, v16, v17
	global_store_dwordx4 v[12:13], v[6:9], off offset:1024
	v_lshl_add_u64 v[2:3], v[2:3], 0, s[0:1]
	s_nop 0
	v_lshl_add_u64 v[6:7], s[88:89], 0, v[0:1]
	global_store_dword v[6:7], v61, off
	s_waitcnt lgkmcnt(0)
	v_lshl_add_u64 v[0:1], v[0:1], 0, s[0:1]
	v_readlane_b32 s0, v254, 42
	v_readlane_b32 s1, v254, 43
	s_nop 1
	v_lshl_add_u64 v[4:5], v[4:5], 0, s[0:1]
	s_cbranch_scc1 .LBB0_313
; __device__ __forceinline__ void pc_phase(LAS unsigned char* lds, const bf16* Pp_, const bf16* LO, const float* mu, const float* w0, const float* a0, const float* k_k, const float* k_a, const float* r_k, ...
;     ...
;     for (int item = bid * NWAVES + wave; item < 16384; item += G * NWAVES) {
;         const size_t ib = (size_t)item * 16;
;         const int bh = item >> 8, c = item & 255, b = bh >> 4, h = bh & 15, ch = h * 64 + lane; const int m0 = b * SEQ + c * 16;
;         const float mu_r = mu[ch], mu_k = mu[1024 + ch], mu_v = mu[2048 + ch], w0c = w0[ch], a0c = a0[ch], kkc = k_k[ch], kac = k_a[ch], rkc = r_k[ch];
;         unsigned short sr_[17], sk_[17], sv_[17], slw[16], sla[16];
;         { const bf16* pp = Pp_ + (size_t)(c > 0 ? m0 - 1 : m0) * EV_IN_P + 3072 + ch; sr_[0] = pp[0]; sk_[0] = pp[1024]; sv_[0] = pp[2048]; }
; #pragma unroll
;         for (int t = 0; t < 16; ++t) { const bf16* pr = Pp_ + (size_t)(m0 + t) * EV_IN_P + 3072 + ch; sr_[t + 1] = pr[0]; sk_[t + 1] = pr[1024]; sv_[t + 1] = pr[2048];
;             const bf16* lo = LO + (size_t)(m0 + t) * LORA_N + ch; slw[t] = lo[0]; sla[t] = lo[1024]; }
.LBB0_281:
	s_and_b32 s1, s11, 0xff
	s_bfe_u32 s0, s11, 0x40008
	s_and_b32 s2, s11, 0xfffff000
	s_lshl_b32 s4, s1, 4
	v_lshl_or_b32 v16, s0, 6, v185
	s_or_b32 s56, s4, s2
	v_readlane_b32 s4, v255, 13
	v_lshlrev_b32_e32 v96, 2, v16
	v_readlane_b32 s5, v255, 14
	s_add_i32 s6, s56, -1
	s_cmp_eq_u32 s1, 0
	v_lshl_add_u64 v[6:7], s[4:5], 0, v[96:97]
	v_add_co_u32_e32 v8, vcc, 0x1000, v6
	global_load_dword v10, v[6:7], off
	s_nop 0
	v_addc_co_u32_e32 v9, vcc, 0, v7, vcc
	global_load_dword v9, v[8:9], off
	v_add_co_u32_e32 v6, vcc, 0x2000, v6
	v_readlane_b32 s4, v255, 15
	s_nop 0
	v_addc_co_u32_e32 v7, vcc, 0, v7, vcc
	v_readlane_b32 s5, v255, 16
	global_load_dword v12, v[6:7], off
	s_cselect_b64 s[94:95], -1, 0
	v_lshl_add_u64 v[6:7], s[4:5], 0, v[96:97]
	v_readlane_b32 s4, v255, 20
	v_readlane_b32 s5, v255, 21
	global_load_dword v8, v[6:7], off
	v_readlane_b32 s8, v254, 63
	v_lshl_add_u64 v[6:7], s[4:5], 0, v[96:97]
	v_readlane_b32 s4, v255, 22
	v_readlane_b32 s5, v255, 23
	global_load_dword v15, v[6:7], off
	v_readlane_b32 s9, v255, 0
	v_lshl_add_u64 v[6:7], s[4:5], 0, v[96:97]
	v_readlane_b32 s4, v255, 24
	v_readlane_b32 s5, v255, 25
	global_load_dword v14, v[6:7], off
	s_nop 0
	v_lshl_add_u64 v[6:7], s[4:5], 0, v[96:97]
	v_readlane_b32 s4, v255, 26
	v_readlane_b32 s5, v255, 27
	global_load_dword v13, v[6:7], off
	s_nop 0
	v_lshl_add_u64 v[6:7], s[4:5], 0, v[96:97]
	s_and_b64 s[4:5], s[94:95], exec
	s_cselect_b32 s1, s2, s6
	s_mul_hi_i32 s2, s1, 0x3400
	s_mulk_i32 s1, 0x3400
	s_add_u32 s4, s8, s1
	s_addc_u32 s5, s9, s2
	v_lshlrev_b32_e32 v96, 1, v16
	v_lshl_add_u64 v[16:17], s[4:5], 0, v[96:97]
	v_readlane_b32 s4, v255, 1
	v_readlane_b32 s5, v255, 2
	s_mul_i32 s2, s56, 0x3400
	global_load_dword v11, v[6:7], off
	v_lshl_add_u64 v[6:7], s[4:5], 0, v[96:97]
	s_mul_hi_i32 s1, s56, 0x3400
	s_add_u32 s4, s8, s2
	s_addc_u32 s5, s9, s1
	s_or_b32 s86, s56, 1
	v_lshl_add_u64 v[20:21], s[4:5], 0, v[96:97]
	s_waitcnt vmcnt(0)
	v_mad_i64_i32 v[140:141], s[4:5], s56, v226, v[6:7]
	s_mul_i32 s2, s86, 0x3400
	s_mul_hi_i32 s1, s86, 0x3400
	s_add_u32 s4, s8, s2
	s_addc_u32 s5, s9, s1
	v_lshl_add_u64 v[64:65], s[4:5], 0, v[96:97]
	v_add_co_u32_e32 v68, vcc, s55, v64
	s_mov_b64 s[6:7], 0x1800
	s_nop 0
	v_addc_co_u32_e32 v69, vcc, 0, v65, vcc
	v_lshl_add_u64 v[66:67], v[64:65], 0, s[6:7]
	v_add_co_u32_e32 v64, vcc, s13, v64
	s_or_b32 s34, s56, 2
	s_nop 0
	v_addc_co_u32_e32 v65, vcc, 0, v65, vcc
	global_load_ushort v132, v[140:141], off
	global_load_ushort v129, v[68:69], off offset:2048
	global_load_ushort v130, v[66:67], off offset:2048
	global_load_ushort v131, v[64:65], off offset:2048
	v_mad_i64_i32 v[64:65], s[4:5], s86, v226, v[6:7]
	s_mul_i32 s2, s34, 0x3400
	s_mul_hi_i32 s1, s34, 0x3400
	s_add_u32 s4, s8, s2
	s_addc_u32 s5, s9, s1
	global_load_ushort v127, v[64:65], off
	global_load_ushort v128, v[64:65], off offset:2048
	v_lshl_add_u64 v[64:65], s[4:5], 0, v[96:97]
	v_add_co_u32_e32 v68, vcc, s55, v64
	v_lshl_add_u64 v[66:67], v[64:65], 0, s[6:7]
	s_nop 0
	v_addc_co_u32_e32 v69, vcc, 0, v65, vcc
	v_add_co_u32_e32 v64, vcc, s13, v64
	s_or_b32 s40, s56, 3
	s_nop 0
	v_addc_co_u32_e32 v65, vcc, 0, v65, vcc
	global_load_ushort v124, v[68:69], off offset:2048
	global_load_ushort v125, v[66:67], off offset:2048
	global_load_ushort v126, v[64:65], off offset:2048
	v_mad_i64_i32 v[64:65], s[4:5], s34, v226, v[6:7]
	s_mul_i32 s2, s40, 0x3400
	s_mul_hi_i32 s1, s40, 0x3400
	s_add_u32 s4, s8, s2
	s_addc_u32 s5, s9, s1
	global_load_ushort v122, v[64:65], off
	global_load_ushort v123, v[64:65], off offset:2048
	v_lshl_add_u64 v[64:65], s[4:5], 0, v[96:97]
	v_add_co_u32_e32 v68, vcc, s55, v64
	v_lshl_add_u64 v[66:67], v[64:65], 0, s[6:7]
	s_nop 0
	v_addc_co_u32_e32 v69, vcc, 0, v65, vcc
	v_add_co_u32_e32 v64, vcc, s13, v64
	s_or_b32 s72, s56, 4
	s_nop 0
	v_addc_co_u32_e32 v65, vcc, 0, v65, vcc
	global_load_ushort v119, v[68:69], off offset:2048
	global_load_ushort v120, v[66:67], off offset:2048
	global_load_ushort v121, v[64:65], off offset:2048
	v_mad_i64_i32 v[64:65], s[4:5], s40, v226, v[6:7]
	s_mul_i32 s2, s72, 0x3400
	s_mul_hi_i32 s1, s72, 0x3400
	s_add_u32 s4, s8, s2
	s_addc_u32 s5, s9, s1
	global_load_ushort v117, v[64:65], off
	global_load_ushort v118, v[64:65], off offset:2048
	v_lshl_add_u64 v[64:65], s[4:5], 0, v[96:97]
	v_add_co_u32_e32 v68, vcc, s55, v64
	v_lshl_add_u64 v[66:67], v[64:65], 0, s[6:7]
	s_nop 0
	v_addc_co_u32_e32 v69, vcc, 0, v65, vcc
	v_add_co_u32_e32 v64, vcc, s13, v64
	s_or_b32 s68, s56, 5
	s_nop 0
	v_addc_co_u32_e32 v65, vcc, 0, v65, vcc
	global_load_ushort v114, v[68:69], off offset:2048
	global_load_ushort v115, v[66:67], off offset:2048
	global_load_ushort v116, v[64:65], off offset:2048
	v_mad_i64_i32 v[64:65], s[4:5], s72, v226, v[6:7]
	s_mul_i32 s2, s68, 0x3400
	s_mul_hi_i32 s1, s68, 0x3400
	s_add_u32 s4, s8, s2
	s_addc_u32 s5, s9, s1
	global_load_ushort v112, v[64:65], off
	global_load_ushort v113, v[64:65], off offset:2048
	v_lshl_add_u64 v[64:65], s[4:5], 0, v[96:97]
	v_add_co_u32_e32 v68, vcc, s55, v64
	v_lshl_add_u64 v[66:67], v[64:65], 0, s[6:7]
	s_nop 0
	v_addc_co_u32_e32 v69, vcc, 0, v65, vcc
	v_add_co_u32_e32 v64, vcc, s13, v64
	s_or_b32 s66, s56, 6
	s_nop 0
	v_addc_co_u32_e32 v65, vcc, 0, v65, vcc
	global_load_ushort v109, v[68:69], off offset:2048
	global_load_ushort v110, v[66:67], off offset:2048
	global_load_ushort v111, v[64:65], off offset:2048
	v_mad_i64_i32 v[64:65], s[4:5], s68, v226, v[6:7]
	s_mul_i32 s2, s66, 0x3400
	s_mul_hi_i32 s1, s66, 0x3400
	s_add_u32 s4, s8, s2
	s_addc_u32 s5, s9, s1
	global_load_ushort v107, v[64:65], off
	global_load_ushort v108, v[64:65], off offset:2048
	v_lshl_add_u64 v[64:65], s[4:5], 0, v[96:97]
; __device__ __forceinline__ void pc_phase(LAS unsigned char* lds, const bf16* Pp_, const bf16* LO, const float* mu, const float* w0, const float* a0, const float* k_k, const float* k_a, const float* r_k, ...
;     ...
;         { const bf16* pp = Pp_ + (size_t)(c > 0 ? m0 - 1 : m0) * EV_IN_P + 3072 + ch; sr_[0] = pp[0]; sk_[0] = pp[1024]; sv_[0] = pp[2048]; }
; #pragma unroll
;         for (int t = 0; t < 16; ++t) { const bf16* pr = Pp_ + (size_t)(m0 + t) * EV_IN_P + 3072 + ch; sr_[t + 1] = pr[0]; sk_[t + 1] = pr[1024]; sv_[t + 1] = pr[2048];
;             const bf16* lo = LO + (size_t)(m0 + t) * LORA_N + ch; slw[t] = lo[0]; sla[t] = lo[1024]; }
	v_add_co_u32_e32 v68, vcc, s55, v64
	v_lshl_add_u64 v[66:67], v[64:65], 0, s[6:7]
	s_nop 0
	v_addc_co_u32_e32 v69, vcc, 0, v65, vcc
	v_add_co_u32_e32 v64, vcc, s13, v64
	s_or_b32 s64, s56, 7
	s_nop 0
	v_addc_co_u32_e32 v65, vcc, 0, v65, vcc
	global_load_ushort v104, v[68:69], off offset:2048
	global_load_ushort v105, v[66:67], off offset:2048
	global_load_ushort v106, v[64:65], off offset:2048
	v_mad_i64_i32 v[64:65], s[4:5], s66, v226, v[6:7]
	s_mul_i32 s2, s64, 0x3400
	s_mul_hi_i32 s1, s64, 0x3400
	s_add_u32 s4, s8, s2
	s_addc_u32 s5, s9, s1
	global_load_ushort v102, v[64:65], off
	global_load_ushort v103, v[64:65], off offset:2048
	v_lshl_add_u64 v[64:65], s[4:5], 0, v[96:97]
	v_add_co_u32_e32 v68, vcc, s55, v64
	v_lshl_add_u64 v[66:67], v[64:65], 0, s[6:7]
	s_nop 0
	v_addc_co_u32_e32 v69, vcc, 0, v65, vcc
	v_add_co_u32_e32 v64, vcc, s13, v64
	s_or_b32 s62, s56, 8
	s_nop 0
	v_addc_co_u32_e32 v65, vcc, 0, v65, vcc
	global_load_ushort v99, v[68:69], off offset:2048
	global_load_ushort v100, v[66:67], off offset:2048
	global_load_ushort v101, v[64:65], off offset:2048
	v_mad_i64_i32 v[64:65], s[4:5], s64, v226, v[6:7]
	s_mul_i32 s2, s62, 0x3400
	s_mul_hi_i32 s1, s62, 0x3400
	s_add_u32 s4, s8, s2
	s_addc_u32 s5, s9, s1
	global_load_ushort v95, v[64:65], off
	global_load_ushort v98, v[64:65], off offset:2048
	v_lshl_add_u64 v[64:65], s[4:5], 0, v[96:97]
	v_add_co_u32_e32 v68, vcc, s55, v64
	v_lshl_add_u64 v[66:67], v[64:65], 0, s[6:7]
	s_nop 0
	v_addc_co_u32_e32 v69, vcc, 0, v65, vcc
	v_add_co_u32_e32 v64, vcc, s13, v64
	s_or_b32 s36, s56, 9
	s_nop 0
	v_addc_co_u32_e32 v65, vcc, 0, v65, vcc
	global_load_ushort v92, v[68:69], off offset:2048
	global_load_ushort v93, v[66:67], off offset:2048
	global_load_ushort v94, v[64:65], off offset:2048
	v_mad_i64_i32 v[64:65], s[4:5], s62, v226, v[6:7]
	s_mul_i32 s2, s36, 0x3400
	s_mul_hi_i32 s1, s36, 0x3400
	s_add_u32 s4, s8, s2
	s_addc_u32 s5, s9, s1
	global_load_ushort v90, v[64:65], off
	global_load_ushort v91, v[64:65], off offset:2048
	v_lshl_add_u64 v[64:65], s[4:5], 0, v[96:97]
	v_add_co_u32_e32 v68, vcc, s55, v64
	v_lshl_add_u64 v[66:67], v[64:65], 0, s[6:7]
	s_nop 0
	v_addc_co_u32_e32 v69, vcc, 0, v65, vcc
	v_add_co_u32_e32 v64, vcc, s13, v64
	s_or_b32 s84, s56, 10
	s_nop 0
	v_addc_co_u32_e32 v65, vcc, 0, v65, vcc
	global_load_ushort v87, v[68:69], off offset:2048
	global_load_ushort v88, v[66:67], off offset:2048
	global_load_ushort v89, v[64:65], off offset:2048
	v_mad_i64_i32 v[64:65], s[4:5], s36, v226, v[6:7]
	s_mul_i32 s2, s84, 0x3400
	s_mul_hi_i32 s1, s84, 0x3400
	s_add_u32 s4, s8, s2
	s_addc_u32 s5, s9, s1
	global_load_ushort v85, v[64:65], off
	global_load_ushort v86, v[64:65], off offset:2048
	v_lshl_add_u64 v[64:65], s[4:5], 0, v[96:97]
	v_add_co_u32_e32 v68, vcc, s55, v64
	v_lshl_add_u64 v[66:67], v[64:65], 0, s[6:7]
	s_nop 0
	v_addc_co_u32_e32 v69, vcc, 0, v65, vcc
	v_add_co_u32_e32 v64, vcc, s13, v64
	s_or_b32 s82, s56, 11
	s_nop 0
	v_addc_co_u32_e32 v65, vcc, 0, v65, vcc
	global_load_ushort v82, v[68:69], off offset:2048
	global_load_ushort v83, v[66:67], off offset:2048
	global_load_ushort v84, v[64:65], off offset:2048
	v_mad_i64_i32 v[64:65], s[4:5], s84, v226, v[6:7]
	s_mul_i32 s2, s82, 0x3400
	s_mul_hi_i32 s1, s82, 0x3400
	s_add_u32 s4, s8, s2
	s_addc_u32 s5, s9, s1
	global_load_ushort v80, v[64:65], off
	global_load_ushort v81, v[64:65], off offset:2048
	v_lshl_add_u64 v[64:65], s[4:5], 0, v[96:97]
	v_add_co_u32_e32 v68, vcc, s55, v64
	v_lshl_add_u64 v[66:67], v[64:65], 0, s[6:7]
	s_nop 0
	v_addc_co_u32_e32 v69, vcc, 0, v65, vcc
	v_add_co_u32_e32 v64, vcc, s13, v64
	s_or_b32 s80, s56, 12
	s_nop 0
	v_addc_co_u32_e32 v65, vcc, 0, v65, vcc
	global_load_ushort v77, v[68:69], off offset:2048
	global_load_ushort v78, v[66:67], off offset:2048
	global_load_ushort v79, v[64:65], off offset:2048
	v_mad_i64_i32 v[64:65], s[4:5], s82, v226, v[6:7]
	s_mul_i32 s2, s80, 0x3400
	s_mul_hi_i32 s1, s80, 0x3400
	s_add_u32 s4, s8, s2
	s_addc_u32 s5, s9, s1
	global_load_ushort v75, v[64:65], off
	global_load_ushort v76, v[64:65], off offset:2048
	v_lshl_add_u64 v[64:65], s[4:5], 0, v[96:97]
	v_add_co_u32_e32 v68, vcc, s55, v64
	v_lshl_add_u64 v[66:67], v[64:65], 0, s[6:7]
	s_nop 0
	v_addc_co_u32_e32 v69, vcc, 0, v65, vcc
	v_add_co_u32_e32 v64, vcc, s13, v64
	s_or_b32 s78, s56, 13
	s_nop 0
	v_addc_co_u32_e32 v65, vcc, 0, v65, vcc
	global_load_ushort v72, v[68:69], off offset:2048
	global_load_ushort v73, v[66:67], off offset:2048
	global_load_ushort v74, v[64:65], off offset:2048
	v_mad_i64_i32 v[64:65], s[4:5], s80, v226, v[6:7]
	s_mul_i32 s2, s78, 0x3400
	s_mul_hi_i32 s1, s78, 0x3400
	s_add_u32 s4, s8, s2
	s_addc_u32 s5, s9, s1
	global_load_ushort v70, v[64:65], off
	global_load_ushort v71, v[64:65], off offset:2048
	v_lshl_add_u64 v[64:65], s[4:5], 0, v[96:97]
	v_add_co_u32_e32 v66, vcc, s55, v64
	v_lshl_add_u64 v[68:69], v[64:65], 0, s[6:7]
	s_nop 0
	v_addc_co_u32_e32 v67, vcc, 0, v65, vcc
	v_add_co_u32_e32 v64, vcc, s13, v64
	global_load_ushort v66, v[66:67], off offset:2048
	s_nop 0
	global_load_ushort v67, v[68:69], off offset:2048
	v_addc_co_u32_e32 v65, vcc, 0, v65, vcc
	global_load_ushort v68, v[64:65], off offset:2048
	v_add_co_u32_e32 v64, vcc, s55, v16
	v_lshl_add_u64 v[18:19], v[16:17], 0, s[6:7]
	s_nop 0
	v_addc_co_u32_e32 v65, vcc, 0, v17, vcc
	v_add_co_u32_e32 v16, vcc, s13, v16
	global_load_ushort v134, v[64:65], off offset:2048
	global_load_ushort v135, v[18:19], off offset:2048
	v_addc_co_u32_e32 v17, vcc, 0, v17, vcc
	global_load_ushort v138, v[16:17], off offset:2048
	v_add_co_u32_e32 v16, vcc, s55, v20
	v_lshl_add_u64 v[62:63], v[20:21], 0, s[6:7]
	s_nop 0
; __device__ __forceinline__ float bf2f(bf16 b) { return __uint_as_float((unsigned)b << 16); }
; __device__ __forceinline__ bf16 f2bf(float f) { return (bf16)(pk_bf16(f, 0.f) & 0xffffu); }
; __device__ __forceinline__ float fexp(float x) { return __builtin_amdgcn_exp2f(x * 1.4426950408889634f); }
; __device__ __forceinline__ float flog(float x) { return __builtin_amdgcn_logf(x) * 0.6931471805599453f; }
; __device__ __forceinline__ float fsigmoid(float x) { return __builtin_amdgcn_rcpf(1.0f + fexp(-x)); }
; __device__ __forceinline__ void pc_phase(LAS unsigned char* lds, const bf16* Pp_, const bf16* LO, const float* mu, const float* w0, const float* a0, const float* k_k, const float* k_a, const float* r_k, ...
;     ...
;         { const bf16* pp = Pp_ + (size_t)(c > 0 ? m0 - 1 : m0) * EV_IN_P + 3072 + ch; sr_[0] = pp[0]; sk_[0] = pp[1024]; sv_[0] = pp[2048]; }
; #pragma unroll
;         for (int t = 0; t < 16; ++t) { const bf16* pr = Pp_ + (size_t)(m0 + t) * EV_IN_P + 3072 + ch; sr_[t + 1] = pr[0]; sk_[t + 1] = pr[1024]; sv_[t + 1] = pr[2048];
;             const bf16* lo = LO + (size_t)(m0 + t) * LORA_N + ch; slw[t] = lo[0]; sla[t] = lo[1024]; }
;         const float z1 = (c > 0) ? 1.0f : 0.0f;
;         float P = 1.0f, r1 = bf2f(sr_[0]) * z1, k1 = bf2f(sk_[0]) * z1, v1 = bf2f(sv_[0]) * z1;
; #pragma unroll
;         for (int t = 0; t < 16; ++t) {
;             const float r0 = bf2f(sr_[t + 1]), k0 = bf2f(sk_[t + 1]), v0 = bf2f(sv_[t + 1]);
;             const float r = r0 + (r1 - r0) * mu_r, k = k0 + (k1 - k0) * mu_k, v = v0 + (v1 - v0) * mu_v; r1 = r0; k1 = k0; v1 = v0;
;             const float z = -(w0c + bf2f(slw[t])); const float sp = fmaxf(z, 0.f) + flog(1.0f + fexp(-fabsf(z))); const float w = -sp - 0.5f;
;             const float dec = fexp(-fexp(w)); const float a = fsigmoid(a0c + bf2f(sla[t]));
;             float kk = k * kkc; const float n2 = wsum_dpp(kk * kk); kk = kk / fmaxf(sqrtf(n2), 1e-12f);
;             const float kp = bf2f(f2bf(k * (1.0f + (a - 1.0f) * kac))), bb = bf2f(f2bf(kk * a)), rr = bf2f(f2bf(r)); kk = bf2f(f2bf(kk));
;             const float coef = wsum_dpp(rr * kp * rkc);
;             SV[(ib + t) * 64 + lane] = f2bf(v);
;             if (lane == 0) COEF[(size_t)(m0 + t) * 16 + h] = coef;
	v_addc_co_u32_e32 v17, vcc, 0, v21, vcc
	global_load_ushort v136, v[16:17], off offset:2048
	global_load_ushort v137, v[62:63], off offset:2048
	v_add_co_u32_e32 v16, vcc, s13, v20
	s_or_b32 s76, s56, 14
	s_nop 0
	v_addc_co_u32_e32 v17, vcc, 0, v21, vcc
	global_load_ushort v139, v[16:17], off offset:2048
	v_mad_i64_i32 v[16:17], s[4:5], s78, v226, v[6:7]
	global_load_ushort v65, v[16:17], off
	global_load_ushort v133, v[140:141], off offset:2048
	global_load_ushort v69, v[16:17], off offset:2048
	s_mul_i32 s2, s76, 0x3400
	s_mul_hi_i32 s1, s76, 0x3400
	s_add_u32 s4, s8, s2
	s_addc_u32 s5, s9, s1
	v_lshl_add_u64 v[16:17], s[4:5], 0, v[96:97]
	v_add_co_u32_e32 v20, vcc, s55, v16
	v_lshl_add_u64 v[18:19], v[16:17], 0, s[6:7]
	s_nop 0
	v_addc_co_u32_e32 v21, vcc, 0, v17, vcc
	v_add_co_u32_e32 v16, vcc, s13, v16
	s_or_b32 s74, s56, 15
	s_nop 0
	v_addc_co_u32_e32 v17, vcc, 0, v17, vcc
	global_load_ushort v62, v[20:21], off offset:2048
	global_load_ushort v63, v[18:19], off offset:2048
	global_load_ushort v64, v[16:17], off offset:2048
	v_mad_i64_i32 v[16:17], s[4:5], s76, v226, v[6:7]
	s_mul_i32 s2, s74, 0x3400
	s_mul_hi_i32 s1, s74, 0x3400
	s_add_u32 s4, s8, s2
	s_addc_u32 s5, s9, s1
	global_load_ushort v21, v[16:17], off
	global_load_ushort v61, v[16:17], off offset:2048
	v_lshl_add_u64 v[16:17], s[4:5], 0, v[96:97]
	v_add_co_u32_e32 v18, vcc, s55, v16
	v_lshl_add_u64 v[140:141], v[16:17], 0, s[6:7]
	s_nop 0
	v_addc_co_u32_e32 v19, vcc, 0, v17, vcc
	v_add_co_u32_e32 v16, vcc, s13, v16
	v_mad_i64_i32 v[6:7], s[4:5], s74, v226, v[6:7]
	s_nop 0
	v_addc_co_u32_e32 v17, vcc, 0, v17, vcc
	global_load_ushort v18, v[18:19], off offset:2048
	s_nop 0
	global_load_ushort v19, v[140:141], off offset:2048
	global_load_ushort v20, v[16:17], off offset:2048
	s_nop 0
	global_load_ushort v16, v[6:7], off
	global_load_ushort v17, v[6:7], off offset:2048
	v_cndmask_b32_e64 v96, 1.0, 0, s[94:95]
	s_lshl_b32 s0, s0, 2
	v_lshl_add_u64 v[6:7], s[88:89], 0, v[4:5]
	s_add_u32 s2, s49, s0
	s_addc_u32 s14, s35, 0
	s_waitcnt vmcnt(0) lgkmcnt(0)
	v_lshlrev_b32_e32 v140, 16, v134
	v_lshlrev_b32_e32 v141, 16, v135
	v_lshlrev_b32_e32 v138, 16, v138
	v_lshlrev_b32_e32 v136, 16, v136
	v_lshlrev_b32_e32 v135, 16, v137
	v_fma_f32 v137, v96, v140, -v136
	v_fma_f32 v137, v10, v137, v136
	v_cvt_pk_bf16_f32 v137, v137, s0
	v_lshlrev_b32_e32 v137, 16, v137
	v_lshlrev_b32_e32 v134, 16, v139
	v_fma_f32 v139, v96, v141, -v135
	v_lshlrev_b32_e32 v133, 16, v133
	v_add_f32_e32 v133, v15, v133
	v_mul_f32_e32 v133, 0xbfb8aa3b, v133
	v_exp_f32_e32 v133, v133
	v_fma_f32 v140, v9, v139, v135
	v_mul_f32_e32 v139, v14, v140
	v_fma_f32 v96, v96, v138, -v134
	v_add_f32_e32 v133, 1.0, v133
	v_rcp_f32_e32 v138, v133
	v_mul_f32_e32 v133, v139, v139
	v_fma_f32 v96, v12, v96, v134
	s_nop 0
	v_mov_b32_dpp v133, v133 quad_perm:[1,0,3,2] row_mask:0xf bank_mask:0xf bound_ctrl:1
	v_fmac_f32_e32 v133, v139, v139
	s_nop 1
	v_add_f32_dpp v133, v133, v133 quad_perm:[2,3,0,1] row_mask:0xf bank_mask:0xf bound_ctrl:1
	s_nop 1
	v_add_f32_dpp v133, v133, v133 row_ror:4 row_mask:0xf bank_mask:0xf bound_ctrl:1
	s_nop 1
	v_add_f32_dpp v133, v133, v133 row_ror:8 row_mask:0xf bank_mask:0xf bound_ctrl:1
	s_nop 0
	v_readlane_b32 s7, v133, 0
	v_readlane_b32 s8, v133, 16
	v_readlane_b32 s6, v133, 32
	v_readlane_b32 s9, v133, 48
	v_add_f32_e32 v133, -1.0, v138
	v_fma_f32 v133, v13, v133, 1.0
	v_mul_f32_e32 v133, v140, v133
	v_cvt_pk_bf16_f32 v133, v133, s0
	v_lshlrev_b32_e32 v133, 16, v133
	v_mul_f32_e32 v140, v137, v133
	v_mul_f32_e32 v141, v11, v140
	s_nop 1
	v_mov_b32_dpp v141, v141 quad_perm:[1,0,3,2] row_mask:0xf bank_mask:0xf bound_ctrl:1
	v_fmac_f32_e32 v141, v11, v140
	s_nop 1
	v_add_f32_dpp v140, v141, v141 quad_perm:[2,3,0,1] row_mask:0xf bank_mask:0xf bound_ctrl:1
	s_nop 1
	v_add_f32_dpp v140, v140, v140 row_ror:4 row_mask:0xf bank_mask:0xf bound_ctrl:1
	s_nop 1
	v_add_f32_dpp v140, v140, v140 row_ror:8 row_mask:0xf bank_mask:0xf bound_ctrl:1
	s_nop 0
	v_readlane_b32 s0, v140, 0
	v_readlane_b32 s15, v140, 16
	v_readlane_b32 s1, v140, 32
	v_readlane_b32 s17, v140, 48
	v_add_co_u32_e32 v140, vcc, 0x33600000, v6
	v_cvt_pk_bf16_f32 v96, v96, s0
	s_nop 0
	v_addc_co_u32_e32 v141, vcc, 0, v7, vcc
	global_store_short v[140:141], v96, off
	s_and_saveexec_b64 s[4:5], s[38:39]
	s_cbranch_execz .LBB0_283
	s_ashr_i32 s57, s56, 31
	s_lshl_b64 s[30:31], s[56:57], 6
	s_add_u32 s30, s2, s30
	v_mov_b32_e32 v140, s15
	v_mov_b32_e32 v141, s17
	s_addc_u32 s31, s14, s31
	v_pk_add_f32 v[140:141], s[0:1], v[140:141]
	s_nop 0
	v_add_f32_e32 v96, v140, v141
	v_mov_b64_e32 v[140:141], s[30:31]
	global_store_dword v[140:141], v96, off
; __device__ __forceinline__ float bf2f(bf16 b) { return __uint_as_float((unsigned)b << 16); }
; __device__ __forceinline__ bf16 f2bf(float f) { return (bf16)(pk_bf16(f, 0.f) & 0xffffu); }
; __device__ __forceinline__ float fexp(float x) { return __builtin_amdgcn_exp2f(x * 1.4426950408889634f); }
; __device__ __forceinline__ float flog(float x) { return __builtin_amdgcn_logf(x) * 0.6931471805599453f; }
; __device__ __forceinline__ float fsigmoid(float x) { return __builtin_amdgcn_rcpf(1.0f + fexp(-x)); }
; __device__ __forceinline__ void pc_phase(LAS unsigned char* lds, const bf16* Pp_, const bf16* LO, const float* mu, const float* w0, const float* a0, const float* k_k, const float* k_a, const float* r_k, ...
;     ...
;         for (int t = 0; t < 16; ++t) {
;             const float r0 = bf2f(sr_[t + 1]), k0 = bf2f(sk_[t + 1]), v0 = bf2f(sv_[t + 1]);
;             const float r = r0 + (r1 - r0) * mu_r, k = k0 + (k1 - k0) * mu_k, v = v0 + (v1 - v0) * mu_v; r1 = r0; k1 = k0; v1 = v0;
;             const float z = -(w0c + bf2f(slw[t])); const float sp = fmaxf(z, 0.f) + flog(1.0f + fexp(-fabsf(z))); const float w = -sp - 0.5f;
;             const float dec = fexp(-fexp(w)); const float a = fsigmoid(a0c + bf2f(sla[t]));
;             float kk = k * kkc; const float n2 = wsum_dpp(kk * kk); kk = kk / fmaxf(sqrtf(n2), 1e-12f);
;             const float kp = bf2f(f2bf(k * (1.0f + (a - 1.0f) * kac))), bb = bf2f(f2bf(kk * a)), rr = bf2f(f2bf(r)); kk = bf2f(f2bf(kk));
;             const float coef = wsum_dpp(rr * kp * rkc);
;             SV[(ib + t) * 64 + lane] = f2bf(v);
;             if (lane == 0) COEF[(size_t)(m0 + t) * 16 + h] = coef;
;             const float Pp = P; P *= dec; const float inv = 1.0f / P;
;             XKK[t * 72 + lane] = f2bf(kk * Pp); XR[t * 72 + lane] = f2bf(rr * P); XK[t * 72 + lane] = f2bf(kp * inv); XB[t * 72 + lane] = f2bf(bb * inv); }
.LBB0_283:
	s_or_b64 exec, exec, s[4:5]
	v_lshlrev_b32_e32 v96, 16, v132
	v_add_f32_e32 v96, v8, v96
	v_mul_f32_e64 v132, |v96|, s19
	v_exp_f32_e32 v132, v132
	v_mov_b32_e32 v140, s8
	v_mov_b32_e32 v141, s9
	v_add_f32_e32 v140, s7, v140
	v_add_f32_e32 v132, 1.0, v132
	v_log_f32_e32 v132, v132
	v_add_f32_e32 v141, s6, v141
	v_max_f32_e64 v96, -v96, 0
	v_add_f32_e32 v140, v140, v141
	v_fmac_f32_e32 v96, 0x3f317218, v132
	v_mul_f32_e32 v132, 0x4f800000, v140
	v_cmp_gt_f32_e32 vcc, s33, v140
	v_sub_f32_e32 v96, -0.5, v96
	v_mul_f32_e32 v96, 0x3fb8aa3b, v96
	v_cndmask_b32_e32 v132, v140, v132, vcc
	v_sqrt_f32_e32 v140, v132
	v_exp_f32_e32 v96, v96
	v_lshlrev_b32_e32 v128, 16, v128
	v_add_f32_e32 v128, v15, v128
	v_add_u32_e32 v141, -1, v140
	v_fma_f32 v142, -v141, v140, v132
	v_cmp_ge_f32_e64 s[56:57], 0, v142
	v_add_u32_e32 v142, 1, v140
	v_mul_f32_e32 v96, 0xbfb8aa3b, v96
	v_cndmask_b32_e64 v141, v140, v141, s[56:57]
	v_fma_f32 v140, -v142, v140, v132
	v_cmp_lt_f32_e64 s[56:57], 0, v140
	v_exp_f32_e32 v96, v96
	v_mul_f32_e32 v128, 0xbfb8aa3b, v128
	v_cndmask_b32_e64 v140, v141, v142, s[56:57]
	v_mul_f32_e32 v141, 0x37800000, v140
	v_cndmask_b32_e32 v140, v140, v141, vcc
	v_cmp_class_f32_e32 vcc, v132, v219
	v_exp_f32_e32 v128, v128
	v_lshlrev_b32_e32 v130, 16, v130
	v_cndmask_b32_e32 v132, v140, v132, vcc
	v_max_f32_e32 v132, 0x2b8cbccc, v132
	v_div_scale_f32 v140, s[0:1], v132, v132, v139
	v_rcp_f32_e32 v141, v140
	v_add_f32_e32 v128, 1.0, v128
	v_fma_f32 v142, -v140, v141, 1.0
	v_fmac_f32_e32 v141, v142, v141
	v_div_scale_f32 v142, vcc, v139, v132, v139
	v_mul_f32_e32 v143, v142, v141
	v_fma_f32 v144, -v140, v143, v142
	v_fmac_f32_e32 v143, v144, v141
	v_fma_f32 v140, -v140, v143, v142
	v_div_fmas_f32 v140, v140, v141, v143
	v_div_fixup_f32 v132, v140, v132, v139
	v_mul_f32_e32 v138, v138, v132
	v_cvt_pk_bf16_f32 v138, v138, s0
	v_div_scale_f32 v139, s[0:1], v96, v96, 1.0
	v_rcp_f32_e32 v140, v139
	s_nop 0
	v_cvt_pk_bf16_f32 v132, v132, s0
	v_lshlrev_b32_e32 v132, 16, v132
	v_cvt_pk_bf16_f32 v132, v132, s0
	v_fma_f32 v141, -v139, v140, 1.0
	v_fmac_f32_e32 v140, v141, v140
	v_div_scale_f32 v141, vcc, 1.0, v96, 1.0
	v_mul_f32_e32 v142, v141, v140
	v_fma_f32 v143, -v139, v142, v141
	v_fmac_f32_e32 v142, v143, v140
	v_fma_f32 v139, -v139, v142, v141
	v_div_fmas_f32 v139, v139, v140, v142
	ds_write_b16 v27, v132
	v_mul_f32_e32 v132, v96, v137
	v_div_fixup_f32 v139, v139, v96, 1.0
	v_cvt_pk_bf16_f32 v132, v132, s0
	ds_write_b16 v27, v132 offset:2304
	v_mul_f32_e32 v132, v139, v133
	v_lshlrev_b32_e32 v138, 16, v138
	v_cvt_pk_bf16_f32 v132, v132, s0
	ds_write_b16 v27, v132 offset:4608
	v_mul_f32_e32 v132, v139, v138
	v_cvt_pk_bf16_f32 v132, v132, s0
	v_sub_f32_e32 v133, v135, v130
	ds_write_b16 v27, v132 offset:6912
	v_lshlrev_b32_e32 v132, 16, v129
	v_lshlrev_b32_e32 v129, 16, v131
	v_fma_f32 v135, v9, v133, v130
	v_sub_f32_e32 v133, v134, v129
	v_mul_f32_e32 v134, v14, v135
	v_sub_f32_e32 v131, v136, v132
	v_fma_f32 v136, v12, v133, v129
	v_rcp_f32_e32 v133, v128
	v_mul_f32_e32 v128, v134, v134
	v_fma_f32 v131, v10, v131, v132
	v_cvt_pk_bf16_f32 v131, v131, s0
	v_mov_b32_dpp v128, v128 quad_perm:[1,0,3,2] row_mask:0xf bank_mask:0xf bound_ctrl:1
	v_fmac_f32_e32 v128, v134, v134
	v_lshlrev_b32_e32 v131, 16, v131
	s_nop 0
	v_add_f32_dpp v128, v128, v128 quad_perm:[2,3,0,1] row_mask:0xf bank_mask:0xf bound_ctrl:1
	s_nop 1
	v_add_f32_dpp v128, v128, v128 row_ror:4 row_mask:0xf bank_mask:0xf bound_ctrl:1
	s_nop 1
	v_add_f32_dpp v128, v128, v128 row_ror:8 row_mask:0xf bank_mask:0xf bound_ctrl:1
	s_nop 0
	v_readlane_b32 s7, v128, 0
	v_readlane_b32 s8, v128, 16
	v_readlane_b32 s6, v128, 32
	v_readlane_b32 s9, v128, 48
	v_add_f32_e32 v128, -1.0, v133
	v_fma_f32 v128, v13, v128, 1.0
	v_mul_f32_e32 v128, v135, v128
	v_cvt_pk_bf16_f32 v128, v128, s0
	v_lshlrev_b32_e32 v128, 16, v128
	v_mul_f32_e32 v135, v131, v128
	v_mul_f32_e32 v137, v11, v135
	s_nop 1
	v_mov_b32_dpp v137, v137 quad_perm:[1,0,3,2] row_mask:0xf bank_mask:0xf bound_ctrl:1
	v_fmac_f32_e32 v137, v11, v135
	s_nop 1
	v_add_f32_dpp v135, v137, v137 quad_perm:[2,3,0,1] row_mask:0xf bank_mask:0xf bound_ctrl:1
	s_nop 1
	v_add_f32_dpp v135, v135, v135 row_ror:4 row_mask:0xf bank_mask:0xf bound_ctrl:1
	s_nop 1
	v_add_f32_dpp v135, v135, v135 row_ror:8 row_mask:0xf bank_mask:0xf bound_ctrl:1
	s_nop 0
	v_readlane_b32 s0, v135, 0
	v_readlane_b32 s15, v135, 16
	v_readlane_b32 s1, v135, 32
	v_readlane_b32 s17, v135, 48
	v_cvt_pk_bf16_f32 v135, v136, s0
	v_add_co_u32_e32 v136, vcc, 0x33600000, v6
	s_nop 1
	v_addc_co_u32_e32 v137, vcc, 0, v7, vcc
	global_store_short v[136:137], v135, off offset:128
	s_and_saveexec_b64 s[4:5], s[38:39]
	s_cbranch_execz .LBB0_285
	s_ashr_i32 s87, s86, 31
	s_lshl_b64 s[30:31], s[86:87], 6
	s_add_u32 s30, s2, s30
	v_mov_b32_e32 v136, s15
	v_mov_b32_e32 v137, s17
	s_addc_u32 s31, s14, s31
	v_pk_add_f32 v[136:137], s[0:1], v[136:137]
	s_nop 0
	v_add_f32_e32 v135, v136, v137
	v_mov_b64_e32 v[136:137], s[30:31]
	global_store_dword v[136:137], v135, off
; __device__ __forceinline__ float bf2f(bf16 b) { return __uint_as_float((unsigned)b << 16); }
; __device__ __forceinline__ bf16 f2bf(float f) { return (bf16)(pk_bf16(f, 0.f) & 0xffffu); }
; __device__ __forceinline__ float fexp(float x) { return __builtin_amdgcn_exp2f(x * 1.4426950408889634f); }
; __device__ __forceinline__ float flog(float x) { return __builtin_amdgcn_logf(x) * 0.6931471805599453f; }
; __device__ __forceinline__ float fsigmoid(float x) { return __builtin_amdgcn_rcpf(1.0f + fexp(-x)); }
; __device__ __forceinline__ void pc_phase(LAS unsigned char* lds, const bf16* Pp_, const bf16* LO, const float* mu, const float* w0, const float* a0, const float* k_k, const float* k_a, const float* r_k, ...
;     ...
;         for (int t = 0; t < 16; ++t) {
;             const float r0 = bf2f(sr_[t + 1]), k0 = bf2f(sk_[t + 1]), v0 = bf2f(sv_[t + 1]);
;             const float r = r0 + (r1 - r0) * mu_r, k = k0 + (k1 - k0) * mu_k, v = v0 + (v1 - v0) * mu_v; r1 = r0; k1 = k0; v1 = v0;
;             const float z = -(w0c + bf2f(slw[t])); const float sp = fmaxf(z, 0.f) + flog(1.0f + fexp(-fabsf(z))); const float w = -sp - 0.5f;
;             const float dec = fexp(-fexp(w)); const float a = fsigmoid(a0c + bf2f(sla[t]));
;             float kk = k * kkc; const float n2 = wsum_dpp(kk * kk); kk = kk / fmaxf(sqrtf(n2), 1e-12f);
;             const float kp = bf2f(f2bf(k * (1.0f + (a - 1.0f) * kac))), bb = bf2f(f2bf(kk * a)), rr = bf2f(f2bf(r)); kk = bf2f(f2bf(kk));
;             const float coef = wsum_dpp(rr * kp * rkc);
;             SV[(ib + t) * 64 + lane] = f2bf(v);
;             if (lane == 0) COEF[(size_t)(m0 + t) * 16 + h] = coef;
;             const float Pp = P; P *= dec; const float inv = 1.0f / P;
;             XKK[t * 72 + lane] = f2bf(kk * Pp); XR[t * 72 + lane] = f2bf(rr * P); XK[t * 72 + lane] = f2bf(kp * inv); XB[t * 72 + lane] = f2bf(bb * inv); }
.LBB0_285:
	s_or_b64 exec, exec, s[4:5]
	v_lshlrev_b32_e32 v127, 16, v127
	v_add_f32_e32 v127, v8, v127
	v_mul_f32_e64 v135, |v127|, s19
	v_exp_f32_e32 v135, v135
	v_mov_b32_e32 v136, s8
	v_mov_b32_e32 v137, s9
	v_add_f32_e32 v136, s7, v136
	v_add_f32_e32 v135, 1.0, v135
	v_log_f32_e32 v135, v135
	v_add_f32_e32 v137, s6, v137
	v_max_f32_e64 v127, -v127, 0
	v_add_f32_e32 v136, v136, v137
	v_fmac_f32_e32 v127, 0x3f317218, v135
	v_mul_f32_e32 v135, 0x4f800000, v136
	v_cmp_gt_f32_e32 vcc, s33, v136
	v_sub_f32_e32 v127, -0.5, v127
	v_mul_f32_e32 v127, 0x3fb8aa3b, v127
	v_cndmask_b32_e32 v135, v136, v135, vcc
	v_sqrt_f32_e32 v136, v135
	v_exp_f32_e32 v127, v127
	v_lshlrev_b32_e32 v123, 16, v123
	v_add_f32_e32 v123, v15, v123
	v_add_u32_e32 v137, -1, v136
	v_fma_f32 v138, -v137, v136, v135
	v_cmp_ge_f32_e64 s[56:57], 0, v138
	v_add_u32_e32 v138, 1, v136
	v_mul_f32_e32 v127, 0xbfb8aa3b, v127
	v_cndmask_b32_e64 v137, v136, v137, s[56:57]
	v_fma_f32 v136, -v138, v136, v135
	v_cmp_lt_f32_e64 s[56:57], 0, v136
	v_exp_f32_e32 v127, v127
	v_mul_f32_e32 v123, 0xbfb8aa3b, v123
	v_cndmask_b32_e64 v136, v137, v138, s[56:57]
	v_mul_f32_e32 v137, 0x37800000, v136
	v_cndmask_b32_e32 v136, v136, v137, vcc
	v_cmp_class_f32_e32 vcc, v135, v219
	v_mul_f32_e32 v127, v96, v127
	v_lshlrev_b32_e32 v125, 16, v125
	v_cndmask_b32_e32 v135, v136, v135, vcc
	v_max_f32_e32 v135, 0x2b8cbccc, v135
	v_div_scale_f32 v136, s[0:1], v135, v135, v134
	v_rcp_f32_e32 v137, v136
	v_exp_f32_e32 v123, v123
	v_fma_f32 v138, -v136, v137, 1.0
	v_fmac_f32_e32 v137, v138, v137
	v_div_scale_f32 v138, vcc, v134, v135, v134
	v_mul_f32_e32 v139, v138, v137
	v_fma_f32 v140, -v136, v139, v138
	v_fmac_f32_e32 v139, v140, v137
	v_fma_f32 v136, -v136, v139, v138
	v_div_fmas_f32 v136, v136, v137, v139
	v_div_fixup_f32 v134, v136, v135, v134
	v_mul_f32_e32 v133, v133, v134
	v_cvt_pk_bf16_f32 v133, v133, s0
	v_div_scale_f32 v135, s[0:1], v127, v127, 1.0
	v_rcp_f32_e32 v136, v135
	s_nop 0
	v_cvt_pk_bf16_f32 v134, v134, s0
	v_lshlrev_b32_e32 v134, 16, v134
	v_mul_f32_e32 v96, v96, v134
	v_fma_f32 v137, -v135, v136, 1.0
	v_fmac_f32_e32 v136, v137, v136
	v_div_scale_f32 v137, vcc, 1.0, v127, 1.0
	v_mul_f32_e32 v138, v137, v136
	v_fma_f32 v139, -v135, v138, v137
	v_fmac_f32_e32 v138, v139, v136
	v_fma_f32 v135, -v135, v138, v137
	v_cvt_pk_bf16_f32 v96, v96, s0
	v_div_fmas_f32 v135, v135, v136, v138
	ds_write_b16 v27, v96 offset:144
	v_mul_f32_e32 v96, v127, v131
	v_div_fixup_f32 v135, v135, v127, 1.0
	v_cvt_pk_bf16_f32 v96, v96, s0
	ds_write_b16 v27, v96 offset:2448
	v_mul_f32_e32 v96, v135, v128
	v_lshlrev_b32_e32 v133, 16, v133
	v_cvt_pk_bf16_f32 v96, v96, s0
	ds_write_b16 v27, v96 offset:4752
	v_mul_f32_e32 v96, v135, v133
	v_cvt_pk_bf16_f32 v96, v96, s0
	v_lshlrev_b32_e32 v128, 16, v124
	ds_write_b16 v27, v96 offset:7056
	v_sub_f32_e32 v96, v132, v128
	v_lshlrev_b32_e32 v124, 16, v126
	v_fma_f32 v126, v10, v96, v128
	v_sub_f32_e32 v96, v130, v125
	v_fma_f32 v130, v9, v96, v125
	v_sub_f32_e32 v96, v129, v124
	v_mul_f32_e32 v129, v14, v130
	v_fma_f32 v131, v12, v96, v124
	v_add_f32_e32 v96, 1.0, v123
	v_mul_f32_e32 v123, v129, v129
	v_rcp_f32_e32 v96, v96
	v_cvt_pk_bf16_f32 v126, v126, s0
	v_mov_b32_dpp v123, v123 quad_perm:[1,0,3,2] row_mask:0xf bank_mask:0xf bound_ctrl:1
	v_fmac_f32_e32 v123, v129, v129
	v_lshlrev_b32_e32 v126, 16, v126
	s_nop 0
	v_add_f32_dpp v123, v123, v123 quad_perm:[2,3,0,1] row_mask:0xf bank_mask:0xf bound_ctrl:1
	s_nop 1
	v_add_f32_dpp v123, v123, v123 row_ror:4 row_mask:0xf bank_mask:0xf bound_ctrl:1
	s_nop 1
	v_add_f32_dpp v123, v123, v123 row_ror:8 row_mask:0xf bank_mask:0xf bound_ctrl:1
	s_nop 0
	v_readlane_b32 s7, v123, 0
	v_readlane_b32 s8, v123, 16
	v_readlane_b32 s6, v123, 32
	v_readlane_b32 s9, v123, 48
	v_add_f32_e32 v123, -1.0, v96
	v_fma_f32 v123, v13, v123, 1.0
	v_mul_f32_e32 v123, v130, v123
	v_cvt_pk_bf16_f32 v123, v123, s0
	v_lshlrev_b32_e32 v123, 16, v123
	v_mul_f32_e32 v130, v126, v123
	v_mul_f32_e32 v132, v11, v130
	s_nop 1
	v_mov_b32_dpp v132, v132 quad_perm:[1,0,3,2] row_mask:0xf bank_mask:0xf bound_ctrl:1
	v_fmac_f32_e32 v132, v11, v130
	s_nop 1
	v_add_f32_dpp v130, v132, v132 quad_perm:[2,3,0,1] row_mask:0xf bank_mask:0xf bound_ctrl:1
	s_nop 1
	v_add_f32_dpp v130, v130, v130 row_ror:4 row_mask:0xf bank_mask:0xf bound_ctrl:1
	s_nop 1
	v_add_f32_dpp v130, v130, v130 row_ror:8 row_mask:0xf bank_mask:0xf bound_ctrl:1
	s_nop 0
	v_readlane_b32 s0, v130, 0
	v_readlane_b32 s15, v130, 16
	v_readlane_b32 s1, v130, 32
	v_readlane_b32 s17, v130, 48
	v_add_co_u32_e32 v130, vcc, 0x33600000, v6
	v_cvt_pk_bf16_f32 v132, v131, s0
	s_nop 0
	v_addc_co_u32_e32 v131, vcc, 0, v7, vcc
	global_store_short v[130:131], v132, off offset:256
	s_and_saveexec_b64 s[4:5], s[38:39]
	s_cbranch_execz .LBB0_287
	s_mov_b32 s37, s35
	s_ashr_i32 s35, s34, 31
	s_lshl_b64 s[30:31], s[34:35], 6
	s_add_u32 s30, s2, s30
	v_mov_b32_e32 v130, s15
	v_mov_b32_e32 v131, s17
	s_addc_u32 s31, s14, s31
	v_pk_add_f32 v[130:131], s[0:1], v[130:131]
	s_mov_b32 s35, s37
	v_add_f32_e32 v132, v130, v131
	v_mov_b64_e32 v[130:131], s[30:31]
	global_store_dword v[130:131], v132, off
; __device__ __forceinline__ float bf2f(bf16 b) { return __uint_as_float((unsigned)b << 16); }
; __device__ __forceinline__ bf16 f2bf(float f) { return (bf16)(pk_bf16(f, 0.f) & 0xffffu); }
; __device__ __forceinline__ float fexp(float x) { return __builtin_amdgcn_exp2f(x * 1.4426950408889634f); }
; __device__ __forceinline__ float flog(float x) { return __builtin_amdgcn_logf(x) * 0.6931471805599453f; }
; __device__ __forceinline__ float fsigmoid(float x) { return __builtin_amdgcn_rcpf(1.0f + fexp(-x)); }
; __device__ __forceinline__ void pc_phase(LAS unsigned char* lds, const bf16* Pp_, const bf16* LO, const float* mu, const float* w0, const float* a0, const float* k_k, const float* k_a, const float* r_k, ...
;     ...
;         for (int t = 0; t < 16; ++t) {
;             const float r0 = bf2f(sr_[t + 1]), k0 = bf2f(sk_[t + 1]), v0 = bf2f(sv_[t + 1]);
;             const float r = r0 + (r1 - r0) * mu_r, k = k0 + (k1 - k0) * mu_k, v = v0 + (v1 - v0) * mu_v; r1 = r0; k1 = k0; v1 = v0;
;             const float z = -(w0c + bf2f(slw[t])); const float sp = fmaxf(z, 0.f) + flog(1.0f + fexp(-fabsf(z))); const float w = -sp - 0.5f;
;             const float dec = fexp(-fexp(w)); const float a = fsigmoid(a0c + bf2f(sla[t]));
;             float kk = k * kkc; const float n2 = wsum_dpp(kk * kk); kk = kk / fmaxf(sqrtf(n2), 1e-12f);
;             const float kp = bf2f(f2bf(k * (1.0f + (a - 1.0f) * kac))), bb = bf2f(f2bf(kk * a)), rr = bf2f(f2bf(r)); kk = bf2f(f2bf(kk));
;             const float coef = wsum_dpp(rr * kp * rkc);
;             SV[(ib + t) * 64 + lane] = f2bf(v);
;             if (lane == 0) COEF[(size_t)(m0 + t) * 16 + h] = coef;
;             const float Pp = P; P *= dec; const float inv = 1.0f / P;
;             XKK[t * 72 + lane] = f2bf(kk * Pp); XR[t * 72 + lane] = f2bf(rr * P); XK[t * 72 + lane] = f2bf(kp * inv); XB[t * 72 + lane] = f2bf(bb * inv); }
.LBB0_287:
	s_or_b64 exec, exec, s[4:5]
	v_lshlrev_b32_e32 v122, 16, v122
	v_add_f32_e32 v122, v8, v122
	v_mul_f32_e64 v130, |v122|, s19
	v_exp_f32_e32 v130, v130
	v_mov_b32_e32 v131, s8
	v_mov_b32_e32 v132, s9
	v_add_f32_e32 v131, s7, v131
	v_add_f32_e32 v130, 1.0, v130
	v_log_f32_e32 v130, v130
	v_add_f32_e32 v132, s6, v132
	v_max_f32_e64 v122, -v122, 0
	v_add_f32_e32 v131, v131, v132
	v_fmac_f32_e32 v122, 0x3f317218, v130
	v_mul_f32_e32 v130, 0x4f800000, v131
	v_cmp_gt_f32_e32 vcc, s33, v131
	v_sub_f32_e32 v122, -0.5, v122
	v_mul_f32_e32 v122, 0x3fb8aa3b, v122
	v_cndmask_b32_e32 v130, v131, v130, vcc
	v_sqrt_f32_e32 v131, v130
	v_exp_f32_e32 v122, v122
	v_lshlrev_b32_e32 v118, 16, v118
	v_add_f32_e32 v118, v15, v118
	v_add_u32_e32 v132, -1, v131
	v_fma_f32 v133, -v132, v131, v130
	v_cmp_ge_f32_e64 s[56:57], 0, v133
	v_add_u32_e32 v133, 1, v131
	v_mul_f32_e32 v122, 0xbfb8aa3b, v122
	v_cndmask_b32_e64 v132, v131, v132, s[56:57]
	v_fma_f32 v131, -v133, v131, v130
	v_cmp_lt_f32_e64 s[56:57], 0, v131
	v_exp_f32_e32 v122, v122
	v_mul_f32_e32 v118, 0xbfb8aa3b, v118
	v_cndmask_b32_e64 v131, v132, v133, s[56:57]
	v_mul_f32_e32 v132, 0x37800000, v131
	v_cndmask_b32_e32 v131, v131, v132, vcc
	v_cmp_class_f32_e32 vcc, v130, v219
	v_exp_f32_e32 v118, v118
	v_lshlrev_b32_e32 v120, 16, v120
	v_cndmask_b32_e32 v130, v131, v130, vcc
	v_max_f32_e32 v130, 0x2b8cbccc, v130
	v_div_scale_f32 v131, s[0:1], v130, v130, v129
	v_rcp_f32_e32 v132, v131
	v_add_f32_e32 v118, 1.0, v118
	v_fma_f32 v133, -v131, v132, 1.0
	v_fmac_f32_e32 v132, v133, v132
	v_div_scale_f32 v133, vcc, v129, v130, v129
	v_mul_f32_e32 v134, v133, v132
	v_fma_f32 v135, -v131, v134, v133
	v_fmac_f32_e32 v134, v135, v132
	v_fma_f32 v131, -v131, v134, v133
	v_div_fmas_f32 v131, v131, v132, v134
	v_div_fixup_f32 v129, v131, v130, v129
	v_mul_f32_e32 v96, v96, v129
	v_cvt_pk_bf16_f32 v130, v96, s0
	v_mul_f32_e32 v96, v127, v122
	v_div_scale_f32 v122, s[0:1], v96, v96, 1.0
	v_rcp_f32_e32 v131, v122
	v_lshlrev_b32_e32 v130, 16, v130
	v_mul_f32_e32 v126, v96, v126
	v_cvt_pk_bf16_f32 v126, v126, s0
	v_fma_f32 v132, -v122, v131, 1.0
	v_fmac_f32_e32 v131, v132, v131
	v_div_scale_f32 v132, vcc, 1.0, v96, 1.0
	v_mul_f32_e32 v133, v132, v131
	v_fma_f32 v134, -v122, v133, v132
	v_fmac_f32_e32 v133, v134, v131
	v_fma_f32 v122, -v122, v133, v132
	v_div_fmas_f32 v122, v122, v131, v133
	v_div_fixup_f32 v122, v122, v96, 1.0
	v_mul_f32_e32 v123, v122, v123
	v_cvt_pk_bf16_f32 v123, v123, s0
	v_mul_f32_e32 v122, v122, v130
	ds_write_b16 v27, v123 offset:4896
	v_cvt_pk_bf16_f32 v122, v122, s0
	v_sub_f32_e32 v123, v125, v120
	ds_write_b16 v27, v122 offset:7200
	v_lshlrev_b32_e32 v122, 16, v119
	v_lshlrev_b32_e32 v119, 16, v121
	v_fma_f32 v125, v9, v123, v120
	v_sub_f32_e32 v123, v124, v119
	v_mul_f32_e32 v124, v14, v125
	ds_write_b16 v27, v126 offset:2592
	v_fma_f32 v126, v12, v123, v119
	v_rcp_f32_e32 v123, v118
	v_mul_f32_e32 v118, v124, v124
	v_sub_f32_e32 v121, v128, v122
	v_cvt_pk_bf16_f32 v129, v129, s0
	v_mov_b32_dpp v118, v118 quad_perm:[1,0,3,2] row_mask:0xf bank_mask:0xf bound_ctrl:1
	v_fmac_f32_e32 v118, v124, v124
	v_fma_f32 v121, v10, v121, v122
	v_lshlrev_b32_e32 v129, 16, v129
	v_add_f32_dpp v118, v118, v118 quad_perm:[2,3,0,1] row_mask:0xf bank_mask:0xf bound_ctrl:1
	v_cvt_pk_bf16_f32 v121, v121, s0
	v_mul_f32_e32 v127, v127, v129
	v_add_f32_dpp v118, v118, v118 row_ror:4 row_mask:0xf bank_mask:0xf bound_ctrl:1
	v_lshlrev_b32_e32 v121, 16, v121
	v_cvt_pk_bf16_f32 v127, v127, s0
	v_add_f32_dpp v118, v118, v118 row_ror:8 row_mask:0xf bank_mask:0xf bound_ctrl:1
	ds_write_b16 v27, v127 offset:288
	v_readlane_b32 s7, v118, 0
	v_readlane_b32 s8, v118, 16
	v_readlane_b32 s6, v118, 32
	v_readlane_b32 s9, v118, 48
	v_add_f32_e32 v118, -1.0, v123
	v_fma_f32 v118, v13, v118, 1.0
	v_mul_f32_e32 v118, v125, v118
	v_cvt_pk_bf16_f32 v118, v118, s0
	v_lshlrev_b32_e32 v118, 16, v118
	v_mul_f32_e32 v125, v121, v118
	v_mul_f32_e32 v127, v11, v125
	s_nop 1
	v_mov_b32_dpp v127, v127 quad_perm:[1,0,3,2] row_mask:0xf bank_mask:0xf bound_ctrl:1
	v_fmac_f32_e32 v127, v11, v125
	s_nop 1
	v_add_f32_dpp v125, v127, v127 quad_perm:[2,3,0,1] row_mask:0xf bank_mask:0xf bound_ctrl:1
	s_nop 1
	v_add_f32_dpp v125, v125, v125 row_ror:4 row_mask:0xf bank_mask:0xf bound_ctrl:1
	s_nop 1
	v_add_f32_dpp v125, v125, v125 row_ror:8 row_mask:0xf bank_mask:0xf bound_ctrl:1
	s_nop 0
	v_readlane_b32 s0, v125, 0
	v_readlane_b32 s15, v125, 16
	v_readlane_b32 s1, v125, 32
	v_readlane_b32 s17, v125, 48
	v_cvt_pk_bf16_f32 v125, v126, s0
	v_add_co_u32_e32 v126, vcc, 0x33600000, v6
	s_nop 1
	v_addc_co_u32_e32 v127, vcc, 0, v7, vcc
	global_store_short v[126:127], v125, off offset:384
	s_and_saveexec_b64 s[4:5], s[38:39]
	s_cbranch_execz .LBB0_289
	s_ashr_i32 s41, s40, 31
	s_lshl_b64 s[30:31], s[40:41], 6
	s_add_u32 s30, s2, s30
	v_mov_b32_e32 v126, s15
	v_mov_b32_e32 v127, s17
	s_addc_u32 s31, s14, s31
	v_pk_add_f32 v[126:127], s[0:1], v[126:127]
	s_nop 0
	v_add_f32_e32 v125, v126, v127
	v_mov_b64_e32 v[126:127], s[30:31]
	global_store_dword v[126:127], v125, off
; __device__ __forceinline__ float bf2f(bf16 b) { return __uint_as_float((unsigned)b << 16); }
; __device__ __forceinline__ bf16 f2bf(float f) { return (bf16)(pk_bf16(f, 0.f) & 0xffffu); }
; __device__ __forceinline__ float fexp(float x) { return __builtin_amdgcn_exp2f(x * 1.4426950408889634f); }
; __device__ __forceinline__ float flog(float x) { return __builtin_amdgcn_logf(x) * 0.6931471805599453f; }
; __device__ __forceinline__ float fsigmoid(float x) { return __builtin_amdgcn_rcpf(1.0f + fexp(-x)); }
; __device__ __forceinline__ void pc_phase(LAS unsigned char* lds, const bf16* Pp_, const bf16* LO, const float* mu, const float* w0, const float* a0, const float* k_k, const float* k_a, const float* r_k, ...
;     ...
;         for (int t = 0; t < 16; ++t) {
;             const float r0 = bf2f(sr_[t + 1]), k0 = bf2f(sk_[t + 1]), v0 = bf2f(sv_[t + 1]);
;             const float r = r0 + (r1 - r0) * mu_r, k = k0 + (k1 - k0) * mu_k, v = v0 + (v1 - v0) * mu_v; r1 = r0; k1 = k0; v1 = v0;
;             const float z = -(w0c + bf2f(slw[t])); const float sp = fmaxf(z, 0.f) + flog(1.0f + fexp(-fabsf(z))); const float w = -sp - 0.5f;
;             const float dec = fexp(-fexp(w)); const float a = fsigmoid(a0c + bf2f(sla[t]));
;             float kk = k * kkc; const float n2 = wsum_dpp(kk * kk); kk = kk / fmaxf(sqrtf(n2), 1e-12f);
;             const float kp = bf2f(f2bf(k * (1.0f + (a - 1.0f) * kac))), bb = bf2f(f2bf(kk * a)), rr = bf2f(f2bf(r)); kk = bf2f(f2bf(kk));
;             const float coef = wsum_dpp(rr * kp * rkc);
;             SV[(ib + t) * 64 + lane] = f2bf(v);
;             if (lane == 0) COEF[(size_t)(m0 + t) * 16 + h] = coef;
;             const float Pp = P; P *= dec; const float inv = 1.0f / P;
;             XKK[t * 72 + lane] = f2bf(kk * Pp); XR[t * 72 + lane] = f2bf(rr * P); XK[t * 72 + lane] = f2bf(kp * inv); XB[t * 72 + lane] = f2bf(bb * inv); }
.LBB0_289:
	s_or_b64 exec, exec, s[4:5]
	v_lshlrev_b32_e32 v117, 16, v117
	v_add_f32_e32 v117, v8, v117
	v_mul_f32_e64 v125, |v117|, s19
	v_exp_f32_e32 v125, v125
	v_mov_b32_e32 v126, s8
	v_mov_b32_e32 v127, s9
	v_add_f32_e32 v126, s7, v126
	v_add_f32_e32 v125, 1.0, v125
	v_log_f32_e32 v125, v125
	v_add_f32_e32 v127, s6, v127
	v_max_f32_e64 v117, -v117, 0
	v_add_f32_e32 v126, v126, v127
	v_fmac_f32_e32 v117, 0x3f317218, v125
	v_mul_f32_e32 v125, 0x4f800000, v126
	v_cmp_gt_f32_e32 vcc, s33, v126
	v_sub_f32_e32 v117, -0.5, v117
	v_mul_f32_e32 v117, 0x3fb8aa3b, v117
	v_cndmask_b32_e32 v125, v126, v125, vcc
	v_sqrt_f32_e32 v126, v125
	v_exp_f32_e32 v117, v117
	v_lshlrev_b32_e32 v113, 16, v113
	v_add_f32_e32 v113, v15, v113
	v_add_u32_e32 v127, -1, v126
	v_fma_f32 v128, -v127, v126, v125
	v_cmp_ge_f32_e64 s[56:57], 0, v128
	v_add_u32_e32 v128, 1, v126
	v_mul_f32_e32 v117, 0xbfb8aa3b, v117
	v_cndmask_b32_e64 v127, v126, v127, s[56:57]
	v_fma_f32 v126, -v128, v126, v125
	v_cmp_lt_f32_e64 s[56:57], 0, v126
	v_exp_f32_e32 v117, v117
	v_mul_f32_e32 v113, 0xbfb8aa3b, v113
	v_cndmask_b32_e64 v126, v127, v128, s[56:57]
	v_mul_f32_e32 v127, 0x37800000, v126
	v_cndmask_b32_e32 v126, v126, v127, vcc
	v_cmp_class_f32_e32 vcc, v125, v219
	v_mul_f32_e32 v117, v96, v117
	v_lshlrev_b32_e32 v115, 16, v115
	v_cndmask_b32_e32 v125, v126, v125, vcc
	v_max_f32_e32 v125, 0x2b8cbccc, v125
	v_div_scale_f32 v126, s[0:1], v125, v125, v124
	v_rcp_f32_e32 v127, v126
	v_exp_f32_e32 v113, v113
	v_fma_f32 v128, -v126, v127, 1.0
	v_fmac_f32_e32 v127, v128, v127
	v_div_scale_f32 v128, vcc, v124, v125, v124
	v_mul_f32_e32 v129, v128, v127
	v_fma_f32 v130, -v126, v129, v128
	v_fmac_f32_e32 v129, v130, v127
	v_fma_f32 v126, -v126, v129, v128
	v_div_fmas_f32 v126, v126, v127, v129
	v_div_fixup_f32 v124, v126, v125, v124
	v_mul_f32_e32 v123, v123, v124
	v_cvt_pk_bf16_f32 v123, v123, s0
	v_div_scale_f32 v125, s[0:1], v117, v117, 1.0
	v_rcp_f32_e32 v126, v125
	s_nop 0
	v_cvt_pk_bf16_f32 v124, v124, s0
	v_lshlrev_b32_e32 v124, 16, v124
	v_mul_f32_e32 v96, v96, v124
	v_fma_f32 v127, -v125, v126, 1.0
	v_fmac_f32_e32 v126, v127, v126
	v_div_scale_f32 v127, vcc, 1.0, v117, 1.0
	v_mul_f32_e32 v128, v127, v126
	v_fma_f32 v129, -v125, v128, v127
	v_fmac_f32_e32 v128, v129, v126
	v_fma_f32 v125, -v125, v128, v127
	v_cvt_pk_bf16_f32 v96, v96, s0
	v_div_fmas_f32 v125, v125, v126, v128
	ds_write_b16 v27, v96 offset:432
	v_mul_f32_e32 v96, v117, v121
	v_div_fixup_f32 v125, v125, v117, 1.0
	v_cvt_pk_bf16_f32 v96, v96, s0
	ds_write_b16 v27, v96 offset:2736
	v_mul_f32_e32 v96, v125, v118
	v_lshlrev_b32_e32 v123, 16, v123
	v_cvt_pk_bf16_f32 v96, v96, s0
	ds_write_b16 v27, v96 offset:5040
	v_mul_f32_e32 v96, v125, v123
	v_cvt_pk_bf16_f32 v96, v96, s0
	v_lshlrev_b32_e32 v118, 16, v114
	ds_write_b16 v27, v96 offset:7344
	v_sub_f32_e32 v96, v122, v118
	v_lshlrev_b32_e32 v114, 16, v116
	v_fma_f32 v116, v10, v96, v118
	v_sub_f32_e32 v96, v120, v115
	v_fma_f32 v120, v9, v96, v115
	v_sub_f32_e32 v96, v119, v114
	v_mul_f32_e32 v119, v14, v120
	v_fma_f32 v121, v12, v96, v114
	v_add_f32_e32 v96, 1.0, v113
	v_mul_f32_e32 v113, v119, v119
	v_rcp_f32_e32 v96, v96
	v_cvt_pk_bf16_f32 v116, v116, s0
	v_mov_b32_dpp v113, v113 quad_perm:[1,0,3,2] row_mask:0xf bank_mask:0xf bound_ctrl:1
	v_fmac_f32_e32 v113, v119, v119
	v_lshlrev_b32_e32 v116, 16, v116
	s_nop 0
	v_add_f32_dpp v113, v113, v113 quad_perm:[2,3,0,1] row_mask:0xf bank_mask:0xf bound_ctrl:1
	s_nop 1
	v_add_f32_dpp v113, v113, v113 row_ror:4 row_mask:0xf bank_mask:0xf bound_ctrl:1
	s_nop 1
	v_add_f32_dpp v113, v113, v113 row_ror:8 row_mask:0xf bank_mask:0xf bound_ctrl:1
	s_nop 0
	v_readlane_b32 s7, v113, 0
	v_readlane_b32 s8, v113, 16
	v_readlane_b32 s6, v113, 32
	v_readlane_b32 s9, v113, 48
	v_add_f32_e32 v113, -1.0, v96
	v_fma_f32 v113, v13, v113, 1.0
	v_mul_f32_e32 v113, v120, v113
	v_cvt_pk_bf16_f32 v113, v113, s0
	v_lshlrev_b32_e32 v113, 16, v113
	v_mul_f32_e32 v120, v116, v113
	v_mul_f32_e32 v122, v11, v120
	s_nop 1
	v_mov_b32_dpp v122, v122 quad_perm:[1,0,3,2] row_mask:0xf bank_mask:0xf bound_ctrl:1
	v_fmac_f32_e32 v122, v11, v120
	s_nop 1
	v_add_f32_dpp v120, v122, v122 quad_perm:[2,3,0,1] row_mask:0xf bank_mask:0xf bound_ctrl:1
	s_nop 1
	v_add_f32_dpp v120, v120, v120 row_ror:4 row_mask:0xf bank_mask:0xf bound_ctrl:1
	s_nop 1
	v_add_f32_dpp v120, v120, v120 row_ror:8 row_mask:0xf bank_mask:0xf bound_ctrl:1
	s_nop 0
	v_readlane_b32 s0, v120, 0
	v_readlane_b32 s15, v120, 16
	v_readlane_b32 s1, v120, 32
	v_readlane_b32 s17, v120, 48
	v_add_co_u32_e32 v120, vcc, 0x33600000, v6
	v_cvt_pk_bf16_f32 v122, v121, s0
	s_nop 0
	v_addc_co_u32_e32 v121, vcc, 0, v7, vcc
	global_store_short v[120:121], v122, off offset:512
	s_and_saveexec_b64 s[4:5], s[38:39]
	s_cbranch_execz .LBB0_291
	s_ashr_i32 s73, s72, 31
	s_lshl_b64 s[30:31], s[72:73], 6
	s_add_u32 s30, s2, s30
	v_mov_b32_e32 v120, s15
	v_mov_b32_e32 v121, s17
	s_addc_u32 s31, s14, s31
	v_pk_add_f32 v[120:121], s[0:1], v[120:121]
	s_nop 0
	v_add_f32_e32 v122, v120, v121
	v_mov_b64_e32 v[120:121], s[30:31]
	global_store_dword v[120:121], v122, off
; __device__ __forceinline__ float bf2f(bf16 b) { return __uint_as_float((unsigned)b << 16); }
; __device__ __forceinline__ bf16 f2bf(float f) { return (bf16)(pk_bf16(f, 0.f) & 0xffffu); }
; __device__ __forceinline__ float fexp(float x) { return __builtin_amdgcn_exp2f(x * 1.4426950408889634f); }
; __device__ __forceinline__ float flog(float x) { return __builtin_amdgcn_logf(x) * 0.6931471805599453f; }
; __device__ __forceinline__ float fsigmoid(float x) { return __builtin_amdgcn_rcpf(1.0f + fexp(-x)); }
; __device__ __forceinline__ void pc_phase(LAS unsigned char* lds, const bf16* Pp_, const bf16* LO, const float* mu, const float* w0, const float* a0, const float* k_k, const float* k_a, const float* r_k, ...
;     ...
;         for (int t = 0; t < 16; ++t) {
;             const float r0 = bf2f(sr_[t + 1]), k0 = bf2f(sk_[t + 1]), v0 = bf2f(sv_[t + 1]);
;             const float r = r0 + (r1 - r0) * mu_r, k = k0 + (k1 - k0) * mu_k, v = v0 + (v1 - v0) * mu_v; r1 = r0; k1 = k0; v1 = v0;
;             const float z = -(w0c + bf2f(slw[t])); const float sp = fmaxf(z, 0.f) + flog(1.0f + fexp(-fabsf(z))); const float w = -sp - 0.5f;
;             const float dec = fexp(-fexp(w)); const float a = fsigmoid(a0c + bf2f(sla[t]));
;             float kk = k * kkc; const float n2 = wsum_dpp(kk * kk); kk = kk / fmaxf(sqrtf(n2), 1e-12f);
;             const float kp = bf2f(f2bf(k * (1.0f + (a - 1.0f) * kac))), bb = bf2f(f2bf(kk * a)), rr = bf2f(f2bf(r)); kk = bf2f(f2bf(kk));
;             const float coef = wsum_dpp(rr * kp * rkc);
;             SV[(ib + t) * 64 + lane] = f2bf(v);
;             if (lane == 0) COEF[(size_t)(m0 + t) * 16 + h] = coef;
;             const float Pp = P; P *= dec; const float inv = 1.0f / P;
;             XKK[t * 72 + lane] = f2bf(kk * Pp); XR[t * 72 + lane] = f2bf(rr * P); XK[t * 72 + lane] = f2bf(kp * inv); XB[t * 72 + lane] = f2bf(bb * inv); }
.LBB0_291:
	s_or_b64 exec, exec, s[4:5]
	v_lshlrev_b32_e32 v112, 16, v112
	v_add_f32_e32 v112, v8, v112
	v_mul_f32_e64 v120, |v112|, s19
	v_exp_f32_e32 v120, v120
	v_mov_b32_e32 v121, s8
	v_mov_b32_e32 v122, s9
	v_add_f32_e32 v121, s7, v121
	v_add_f32_e32 v120, 1.0, v120
	v_log_f32_e32 v120, v120
	v_add_f32_e32 v122, s6, v122
	v_max_f32_e64 v112, -v112, 0
	v_add_f32_e32 v121, v121, v122
	v_fmac_f32_e32 v112, 0x3f317218, v120
	v_mul_f32_e32 v120, 0x4f800000, v121
	v_cmp_gt_f32_e32 vcc, s33, v121
	v_sub_f32_e32 v112, -0.5, v112
	v_mul_f32_e32 v112, 0x3fb8aa3b, v112
	v_cndmask_b32_e32 v120, v121, v120, vcc
	v_sqrt_f32_e32 v121, v120
	v_exp_f32_e32 v112, v112
	v_lshlrev_b32_e32 v108, 16, v108
	v_add_f32_e32 v108, v15, v108
	v_add_u32_e32 v122, -1, v121
	v_fma_f32 v123, -v122, v121, v120
	v_cmp_ge_f32_e64 s[56:57], 0, v123
	v_add_u32_e32 v123, 1, v121
	v_mul_f32_e32 v112, 0xbfb8aa3b, v112
	v_cndmask_b32_e64 v122, v121, v122, s[56:57]
	v_fma_f32 v121, -v123, v121, v120
	v_cmp_lt_f32_e64 s[56:57], 0, v121
	v_exp_f32_e32 v112, v112
	v_mul_f32_e32 v108, 0xbfb8aa3b, v108
	v_cndmask_b32_e64 v121, v122, v123, s[56:57]
	v_mul_f32_e32 v122, 0x37800000, v121
	v_cndmask_b32_e32 v121, v121, v122, vcc
	v_cmp_class_f32_e32 vcc, v120, v219
	v_exp_f32_e32 v108, v108
	v_lshlrev_b32_e32 v110, 16, v110
	v_cndmask_b32_e32 v120, v121, v120, vcc
	v_max_f32_e32 v120, 0x2b8cbccc, v120
	v_div_scale_f32 v121, s[0:1], v120, v120, v119
	v_rcp_f32_e32 v122, v121
	v_add_f32_e32 v108, 1.0, v108
	v_fma_f32 v123, -v121, v122, 1.0
	v_fmac_f32_e32 v122, v123, v122
	v_div_scale_f32 v123, vcc, v119, v120, v119
	v_mul_f32_e32 v124, v123, v122
	v_fma_f32 v125, -v121, v124, v123
	v_fmac_f32_e32 v124, v125, v122
	v_fma_f32 v121, -v121, v124, v123
	v_div_fmas_f32 v121, v121, v122, v124
	v_div_fixup_f32 v119, v121, v120, v119
	v_mul_f32_e32 v96, v96, v119
	v_cvt_pk_bf16_f32 v120, v96, s0
	v_mul_f32_e32 v96, v117, v112
	v_div_scale_f32 v112, s[0:1], v96, v96, 1.0
	v_rcp_f32_e32 v121, v112
	v_lshlrev_b32_e32 v120, 16, v120
	v_mul_f32_e32 v116, v96, v116
	v_cvt_pk_bf16_f32 v116, v116, s0
	v_fma_f32 v122, -v112, v121, 1.0
	v_fmac_f32_e32 v121, v122, v121
	v_div_scale_f32 v122, vcc, 1.0, v96, 1.0
	v_mul_f32_e32 v123, v122, v121
	v_fma_f32 v124, -v112, v123, v122
	v_fmac_f32_e32 v123, v124, v121
	v_fma_f32 v112, -v112, v123, v122
	v_div_fmas_f32 v112, v112, v121, v123
	v_div_fixup_f32 v112, v112, v96, 1.0
	v_mul_f32_e32 v113, v112, v113
	v_cvt_pk_bf16_f32 v113, v113, s0
	v_mul_f32_e32 v112, v112, v120
	ds_write_b16 v27, v113 offset:5184
	v_cvt_pk_bf16_f32 v112, v112, s0
	v_sub_f32_e32 v113, v115, v110
	ds_write_b16 v27, v112 offset:7488
	v_lshlrev_b32_e32 v112, 16, v109
	v_lshlrev_b32_e32 v109, 16, v111
	v_fma_f32 v115, v9, v113, v110
	v_sub_f32_e32 v113, v114, v109
	v_mul_f32_e32 v114, v14, v115
	ds_write_b16 v27, v116 offset:2880
	v_fma_f32 v116, v12, v113, v109
	v_rcp_f32_e32 v113, v108
	v_mul_f32_e32 v108, v114, v114
	v_sub_f32_e32 v111, v118, v112
	v_cvt_pk_bf16_f32 v119, v119, s0
	v_mov_b32_dpp v108, v108 quad_perm:[1,0,3,2] row_mask:0xf bank_mask:0xf bound_ctrl:1
	v_fmac_f32_e32 v108, v114, v114
	v_fma_f32 v111, v10, v111, v112
	v_lshlrev_b32_e32 v119, 16, v119
	v_add_f32_dpp v108, v108, v108 quad_perm:[2,3,0,1] row_mask:0xf bank_mask:0xf bound_ctrl:1
	v_cvt_pk_bf16_f32 v111, v111, s0
	v_mul_f32_e32 v117, v117, v119
	v_add_f32_dpp v108, v108, v108 row_ror:4 row_mask:0xf bank_mask:0xf bound_ctrl:1
	v_lshlrev_b32_e32 v111, 16, v111
	v_cvt_pk_bf16_f32 v117, v117, s0
	v_add_f32_dpp v108, v108, v108 row_ror:8 row_mask:0xf bank_mask:0xf bound_ctrl:1
	ds_write_b16 v27, v117 offset:576
	v_readlane_b32 s7, v108, 0
	v_readlane_b32 s8, v108, 16
	v_readlane_b32 s6, v108, 32
	v_readlane_b32 s9, v108, 48
	v_add_f32_e32 v108, -1.0, v113
	v_fma_f32 v108, v13, v108, 1.0
	v_mul_f32_e32 v108, v115, v108
	v_cvt_pk_bf16_f32 v108, v108, s0
	v_lshlrev_b32_e32 v108, 16, v108
	v_mul_f32_e32 v115, v111, v108
	v_mul_f32_e32 v117, v11, v115
	s_nop 1
	v_mov_b32_dpp v117, v117 quad_perm:[1,0,3,2] row_mask:0xf bank_mask:0xf bound_ctrl:1
	v_fmac_f32_e32 v117, v11, v115
	s_nop 1
	v_add_f32_dpp v115, v117, v117 quad_perm:[2,3,0,1] row_mask:0xf bank_mask:0xf bound_ctrl:1
	s_nop 1
	v_add_f32_dpp v115, v115, v115 row_ror:4 row_mask:0xf bank_mask:0xf bound_ctrl:1
	s_nop 1
	v_add_f32_dpp v115, v115, v115 row_ror:8 row_mask:0xf bank_mask:0xf bound_ctrl:1
	s_nop 0
	v_readlane_b32 s0, v115, 0
	v_readlane_b32 s15, v115, 16
	v_readlane_b32 s1, v115, 32
	v_readlane_b32 s17, v115, 48
	v_cvt_pk_bf16_f32 v115, v116, s0
	v_add_co_u32_e32 v116, vcc, 0x33600000, v6
	s_nop 1
	v_addc_co_u32_e32 v117, vcc, 0, v7, vcc
	global_store_short v[116:117], v115, off offset:640
	s_and_saveexec_b64 s[4:5], s[38:39]
	s_cbranch_execz .LBB0_293
	s_ashr_i32 s69, s68, 31
	s_lshl_b64 s[30:31], s[68:69], 6
	s_add_u32 s30, s2, s30
	v_mov_b32_e32 v116, s15
	v_mov_b32_e32 v117, s17
	s_addc_u32 s31, s14, s31
	v_pk_add_f32 v[116:117], s[0:1], v[116:117]
	s_nop 0
	v_add_f32_e32 v115, v116, v117
	v_mov_b64_e32 v[116:117], s[30:31]
	global_store_dword v[116:117], v115, off
; __device__ __forceinline__ float bf2f(bf16 b) { return __uint_as_float((unsigned)b << 16); }
; __device__ __forceinline__ bf16 f2bf(float f) { return (bf16)(pk_bf16(f, 0.f) & 0xffffu); }
; __device__ __forceinline__ float fexp(float x) { return __builtin_amdgcn_exp2f(x * 1.4426950408889634f); }
; __device__ __forceinline__ float flog(float x) { return __builtin_amdgcn_logf(x) * 0.6931471805599453f; }
; __device__ __forceinline__ float fsigmoid(float x) { return __builtin_amdgcn_rcpf(1.0f + fexp(-x)); }
; __device__ __forceinline__ void pc_phase(LAS unsigned char* lds, const bf16* Pp_, const bf16* LO, const float* mu, const float* w0, const float* a0, const float* k_k, const float* k_a, const float* r_k, ...
;     ...
;         for (int t = 0; t < 16; ++t) {
;             const float r0 = bf2f(sr_[t + 1]), k0 = bf2f(sk_[t + 1]), v0 = bf2f(sv_[t + 1]);
;             const float r = r0 + (r1 - r0) * mu_r, k = k0 + (k1 - k0) * mu_k, v = v0 + (v1 - v0) * mu_v; r1 = r0; k1 = k0; v1 = v0;
;             const float z = -(w0c + bf2f(slw[t])); const float sp = fmaxf(z, 0.f) + flog(1.0f + fexp(-fabsf(z))); const float w = -sp - 0.5f;
;             const float dec = fexp(-fexp(w)); const float a = fsigmoid(a0c + bf2f(sla[t]));
;             float kk = k * kkc; const float n2 = wsum_dpp(kk * kk); kk = kk / fmaxf(sqrtf(n2), 1e-12f);
;             const float kp = bf2f(f2bf(k * (1.0f + (a - 1.0f) * kac))), bb = bf2f(f2bf(kk * a)), rr = bf2f(f2bf(r)); kk = bf2f(f2bf(kk));
;             const float coef = wsum_dpp(rr * kp * rkc);
;             SV[(ib + t) * 64 + lane] = f2bf(v);
;             if (lane == 0) COEF[(size_t)(m0 + t) * 16 + h] = coef;
;             const float Pp = P; P *= dec; const float inv = 1.0f / P;
;             XKK[t * 72 + lane] = f2bf(kk * Pp); XR[t * 72 + lane] = f2bf(rr * P); XK[t * 72 + lane] = f2bf(kp * inv); XB[t * 72 + lane] = f2bf(bb * inv); }
.LBB0_293:
	s_or_b64 exec, exec, s[4:5]
	v_lshlrev_b32_e32 v107, 16, v107
	v_add_f32_e32 v107, v8, v107
	v_mul_f32_e64 v115, |v107|, s19
	v_exp_f32_e32 v115, v115
	v_mov_b32_e32 v116, s8
	v_mov_b32_e32 v117, s9
	v_add_f32_e32 v116, s7, v116
	v_add_f32_e32 v115, 1.0, v115
	v_log_f32_e32 v115, v115
	v_add_f32_e32 v117, s6, v117
	v_max_f32_e64 v107, -v107, 0
	v_add_f32_e32 v116, v116, v117
	v_fmac_f32_e32 v107, 0x3f317218, v115
	v_mul_f32_e32 v115, 0x4f800000, v116
	v_cmp_gt_f32_e32 vcc, s33, v116
	v_sub_f32_e32 v107, -0.5, v107
	v_mul_f32_e32 v107, 0x3fb8aa3b, v107
	v_cndmask_b32_e32 v115, v116, v115, vcc
	v_sqrt_f32_e32 v116, v115
	v_exp_f32_e32 v107, v107
	v_lshlrev_b32_e32 v103, 16, v103
	v_add_f32_e32 v103, v15, v103
	v_add_u32_e32 v117, -1, v116
	v_fma_f32 v118, -v117, v116, v115
	v_cmp_ge_f32_e64 s[56:57], 0, v118
	v_add_u32_e32 v118, 1, v116
	v_mul_f32_e32 v107, 0xbfb8aa3b, v107
	v_cndmask_b32_e64 v117, v116, v117, s[56:57]
	v_fma_f32 v116, -v118, v116, v115
	v_cmp_lt_f32_e64 s[56:57], 0, v116
	v_exp_f32_e32 v107, v107
	v_mul_f32_e32 v103, 0xbfb8aa3b, v103
	v_cndmask_b32_e64 v116, v117, v118, s[56:57]
	v_mul_f32_e32 v117, 0x37800000, v116
	v_cndmask_b32_e32 v116, v116, v117, vcc
	v_cmp_class_f32_e32 vcc, v115, v219
	v_mul_f32_e32 v107, v96, v107
	v_lshlrev_b32_e32 v105, 16, v105
	v_cndmask_b32_e32 v115, v116, v115, vcc
	v_max_f32_e32 v115, 0x2b8cbccc, v115
	v_div_scale_f32 v116, s[0:1], v115, v115, v114
	v_rcp_f32_e32 v117, v116
	v_exp_f32_e32 v103, v103
	v_fma_f32 v118, -v116, v117, 1.0
	v_fmac_f32_e32 v117, v118, v117
	v_div_scale_f32 v118, vcc, v114, v115, v114
	v_mul_f32_e32 v119, v118, v117
	v_fma_f32 v120, -v116, v119, v118
	v_fmac_f32_e32 v119, v120, v117
	v_fma_f32 v116, -v116, v119, v118
	v_div_fmas_f32 v116, v116, v117, v119
	v_div_fixup_f32 v114, v116, v115, v114
	v_mul_f32_e32 v113, v113, v114
	v_cvt_pk_bf16_f32 v113, v113, s0
	v_div_scale_f32 v115, s[0:1], v107, v107, 1.0
	v_rcp_f32_e32 v116, v115
	s_nop 0
	v_cvt_pk_bf16_f32 v114, v114, s0
	v_lshlrev_b32_e32 v114, 16, v114
	v_mul_f32_e32 v96, v96, v114
	v_fma_f32 v117, -v115, v116, 1.0
	v_fmac_f32_e32 v116, v117, v116
	v_div_scale_f32 v117, vcc, 1.0, v107, 1.0
	v_mul_f32_e32 v118, v117, v116
	v_fma_f32 v119, -v115, v118, v117
	v_fmac_f32_e32 v118, v119, v116
	v_fma_f32 v115, -v115, v118, v117
	v_cvt_pk_bf16_f32 v96, v96, s0
	v_div_fmas_f32 v115, v115, v116, v118
	ds_write_b16 v27, v96 offset:720
	v_mul_f32_e32 v96, v107, v111
	v_div_fixup_f32 v115, v115, v107, 1.0
	v_cvt_pk_bf16_f32 v96, v96, s0
	ds_write_b16 v27, v96 offset:3024
	v_mul_f32_e32 v96, v115, v108
	v_lshlrev_b32_e32 v113, 16, v113
	v_cvt_pk_bf16_f32 v96, v96, s0
	ds_write_b16 v27, v96 offset:5328
	v_mul_f32_e32 v96, v115, v113
	v_cvt_pk_bf16_f32 v96, v96, s0
	v_lshlrev_b32_e32 v108, 16, v104
	ds_write_b16 v27, v96 offset:7632
	v_sub_f32_e32 v96, v112, v108
	v_lshlrev_b32_e32 v104, 16, v106
	v_fma_f32 v106, v10, v96, v108
	v_sub_f32_e32 v96, v110, v105
	v_fma_f32 v110, v9, v96, v105
	v_sub_f32_e32 v96, v109, v104
	v_mul_f32_e32 v109, v14, v110
	v_fma_f32 v111, v12, v96, v104
	v_add_f32_e32 v96, 1.0, v103
	v_mul_f32_e32 v103, v109, v109
	v_rcp_f32_e32 v96, v96
	v_cvt_pk_bf16_f32 v106, v106, s0
	v_mov_b32_dpp v103, v103 quad_perm:[1,0,3,2] row_mask:0xf bank_mask:0xf bound_ctrl:1
	v_fmac_f32_e32 v103, v109, v109
	v_lshlrev_b32_e32 v106, 16, v106
	s_nop 0
	v_add_f32_dpp v103, v103, v103 quad_perm:[2,3,0,1] row_mask:0xf bank_mask:0xf bound_ctrl:1
	s_nop 1
	v_add_f32_dpp v103, v103, v103 row_ror:4 row_mask:0xf bank_mask:0xf bound_ctrl:1
	s_nop 1
	v_add_f32_dpp v103, v103, v103 row_ror:8 row_mask:0xf bank_mask:0xf bound_ctrl:1
	s_nop 0
	v_readlane_b32 s7, v103, 0
	v_readlane_b32 s8, v103, 16
	v_readlane_b32 s6, v103, 32
	v_readlane_b32 s9, v103, 48
	v_add_f32_e32 v103, -1.0, v96
	v_fma_f32 v103, v13, v103, 1.0
	v_mul_f32_e32 v103, v110, v103
	v_cvt_pk_bf16_f32 v103, v103, s0
	v_lshlrev_b32_e32 v103, 16, v103
	v_mul_f32_e32 v110, v106, v103
	v_mul_f32_e32 v112, v11, v110
	s_nop 1
	v_mov_b32_dpp v112, v112 quad_perm:[1,0,3,2] row_mask:0xf bank_mask:0xf bound_ctrl:1
	v_fmac_f32_e32 v112, v11, v110
	s_nop 1
	v_add_f32_dpp v110, v112, v112 quad_perm:[2,3,0,1] row_mask:0xf bank_mask:0xf bound_ctrl:1
	s_nop 1
	v_add_f32_dpp v110, v110, v110 row_ror:4 row_mask:0xf bank_mask:0xf bound_ctrl:1
	s_nop 1
	v_add_f32_dpp v110, v110, v110 row_ror:8 row_mask:0xf bank_mask:0xf bound_ctrl:1
	s_nop 0
	v_readlane_b32 s0, v110, 0
	v_readlane_b32 s15, v110, 16
	v_readlane_b32 s1, v110, 32
	v_readlane_b32 s17, v110, 48
	v_add_co_u32_e32 v110, vcc, 0x33600000, v6
	v_cvt_pk_bf16_f32 v112, v111, s0
	s_nop 0
	v_addc_co_u32_e32 v111, vcc, 0, v7, vcc
	global_store_short v[110:111], v112, off offset:768
	s_and_saveexec_b64 s[4:5], s[38:39]
	s_cbranch_execz .LBB0_295
	s_ashr_i32 s67, s66, 31
	s_lshl_b64 s[30:31], s[66:67], 6
	s_add_u32 s30, s2, s30
	v_mov_b32_e32 v110, s15
	v_mov_b32_e32 v111, s17
	s_addc_u32 s31, s14, s31
	v_pk_add_f32 v[110:111], s[0:1], v[110:111]
	s_nop 0
	v_add_f32_e32 v112, v110, v111
	v_mov_b64_e32 v[110:111], s[30:31]
	global_store_dword v[110:111], v112, off
; __device__ __forceinline__ float bf2f(bf16 b) { return __uint_as_float((unsigned)b << 16); }
; __device__ __forceinline__ bf16 f2bf(float f) { return (bf16)(pk_bf16(f, 0.f) & 0xffffu); }
; __device__ __forceinline__ float fexp(float x) { return __builtin_amdgcn_exp2f(x * 1.4426950408889634f); }
; __device__ __forceinline__ float flog(float x) { return __builtin_amdgcn_logf(x) * 0.6931471805599453f; }
; __device__ __forceinline__ float fsigmoid(float x) { return __builtin_amdgcn_rcpf(1.0f + fexp(-x)); }
; __device__ __forceinline__ void pc_phase(LAS unsigned char* lds, const bf16* Pp_, const bf16* LO, const float* mu, const float* w0, const float* a0, const float* k_k, const float* k_a, const float* r_k, ...
;     ...
;         for (int t = 0; t < 16; ++t) {
;             const float r0 = bf2f(sr_[t + 1]), k0 = bf2f(sk_[t + 1]), v0 = bf2f(sv_[t + 1]);
;             const float r = r0 + (r1 - r0) * mu_r, k = k0 + (k1 - k0) * mu_k, v = v0 + (v1 - v0) * mu_v; r1 = r0; k1 = k0; v1 = v0;
;             const float z = -(w0c + bf2f(slw[t])); const float sp = fmaxf(z, 0.f) + flog(1.0f + fexp(-fabsf(z))); const float w = -sp - 0.5f;
;             const float dec = fexp(-fexp(w)); const float a = fsigmoid(a0c + bf2f(sla[t]));
;             float kk = k * kkc; const float n2 = wsum_dpp(kk * kk); kk = kk / fmaxf(sqrtf(n2), 1e-12f);
;             const float kp = bf2f(f2bf(k * (1.0f + (a - 1.0f) * kac))), bb = bf2f(f2bf(kk * a)), rr = bf2f(f2bf(r)); kk = bf2f(f2bf(kk));
;             const float coef = wsum_dpp(rr * kp * rkc);
;             SV[(ib + t) * 64 + lane] = f2bf(v);
;             if (lane == 0) COEF[(size_t)(m0 + t) * 16 + h] = coef;
;             const float Pp = P; P *= dec; const float inv = 1.0f / P;
;             XKK[t * 72 + lane] = f2bf(kk * Pp); XR[t * 72 + lane] = f2bf(rr * P); XK[t * 72 + lane] = f2bf(kp * inv); XB[t * 72 + lane] = f2bf(bb * inv); }
.LBB0_295:
	s_or_b64 exec, exec, s[4:5]
	v_lshlrev_b32_e32 v102, 16, v102
	v_add_f32_e32 v102, v8, v102
	v_mul_f32_e64 v110, |v102|, s19
	v_exp_f32_e32 v110, v110
	v_mov_b32_e32 v111, s8
	v_mov_b32_e32 v112, s9
	v_add_f32_e32 v111, s7, v111
	v_add_f32_e32 v110, 1.0, v110
	v_log_f32_e32 v110, v110
	v_add_f32_e32 v112, s6, v112
	v_max_f32_e64 v102, -v102, 0
	v_add_f32_e32 v111, v111, v112
	v_fmac_f32_e32 v102, 0x3f317218, v110
	v_mul_f32_e32 v110, 0x4f800000, v111
	v_cmp_gt_f32_e32 vcc, s33, v111
	v_sub_f32_e32 v102, -0.5, v102
	v_mul_f32_e32 v102, 0x3fb8aa3b, v102
	v_cndmask_b32_e32 v110, v111, v110, vcc
	v_sqrt_f32_e32 v111, v110
	v_exp_f32_e32 v102, v102
	v_lshlrev_b32_e32 v98, 16, v98
	v_add_f32_e32 v98, v15, v98
	v_add_u32_e32 v112, -1, v111
	v_fma_f32 v113, -v112, v111, v110
	v_cmp_ge_f32_e64 s[56:57], 0, v113
	v_add_u32_e32 v113, 1, v111
	v_mul_f32_e32 v102, 0xbfb8aa3b, v102
	v_cndmask_b32_e64 v112, v111, v112, s[56:57]
	v_fma_f32 v111, -v113, v111, v110
	v_cmp_lt_f32_e64 s[56:57], 0, v111
	v_exp_f32_e32 v102, v102
	v_mul_f32_e32 v98, 0xbfb8aa3b, v98
	v_cndmask_b32_e64 v111, v112, v113, s[56:57]
	v_mul_f32_e32 v112, 0x37800000, v111
	v_cndmask_b32_e32 v111, v111, v112, vcc
	v_cmp_class_f32_e32 vcc, v110, v219
	v_exp_f32_e32 v98, v98
	v_lshlrev_b32_e32 v100, 16, v100
	v_cndmask_b32_e32 v110, v111, v110, vcc
	v_max_f32_e32 v110, 0x2b8cbccc, v110
	v_div_scale_f32 v111, s[0:1], v110, v110, v109
	v_rcp_f32_e32 v112, v111
	v_add_f32_e32 v98, 1.0, v98
	v_fma_f32 v113, -v111, v112, 1.0
	v_fmac_f32_e32 v112, v113, v112
	v_div_scale_f32 v113, vcc, v109, v110, v109
	v_mul_f32_e32 v114, v113, v112
	v_fma_f32 v115, -v111, v114, v113
	v_fmac_f32_e32 v114, v115, v112
	v_fma_f32 v111, -v111, v114, v113
	v_div_fmas_f32 v111, v111, v112, v114
	v_div_fixup_f32 v109, v111, v110, v109
	v_mul_f32_e32 v96, v96, v109
	v_cvt_pk_bf16_f32 v110, v96, s0
	v_mul_f32_e32 v96, v107, v102
	v_div_scale_f32 v102, s[0:1], v96, v96, 1.0
	v_rcp_f32_e32 v111, v102
	v_lshlrev_b32_e32 v110, 16, v110
	v_mul_f32_e32 v106, v96, v106
	v_cvt_pk_bf16_f32 v106, v106, s0
	v_fma_f32 v112, -v102, v111, 1.0
	v_fmac_f32_e32 v111, v112, v111
	v_div_scale_f32 v112, vcc, 1.0, v96, 1.0
	v_mul_f32_e32 v113, v112, v111
	v_fma_f32 v114, -v102, v113, v112
	v_fmac_f32_e32 v113, v114, v111
	v_fma_f32 v102, -v102, v113, v112
	v_div_fmas_f32 v102, v102, v111, v113
	v_div_fixup_f32 v102, v102, v96, 1.0
	v_mul_f32_e32 v103, v102, v103
	v_cvt_pk_bf16_f32 v103, v103, s0
	v_mul_f32_e32 v102, v102, v110
	ds_write_b16 v27, v103 offset:5472
	v_cvt_pk_bf16_f32 v102, v102, s0
	v_sub_f32_e32 v103, v105, v100
	ds_write_b16 v27, v102 offset:7776
	v_lshlrev_b32_e32 v102, 16, v99
	v_lshlrev_b32_e32 v99, 16, v101
	v_fma_f32 v105, v9, v103, v100
	v_sub_f32_e32 v103, v104, v99
	v_mul_f32_e32 v104, v14, v105
	ds_write_b16 v27, v106 offset:3168
	v_fma_f32 v106, v12, v103, v99
	v_rcp_f32_e32 v103, v98
	v_mul_f32_e32 v98, v104, v104
	v_sub_f32_e32 v101, v108, v102
	v_cvt_pk_bf16_f32 v109, v109, s0
	v_mov_b32_dpp v98, v98 quad_perm:[1,0,3,2] row_mask:0xf bank_mask:0xf bound_ctrl:1
	v_fmac_f32_e32 v98, v104, v104
	v_fma_f32 v101, v10, v101, v102
	v_lshlrev_b32_e32 v109, 16, v109
	v_add_f32_dpp v98, v98, v98 quad_perm:[2,3,0,1] row_mask:0xf bank_mask:0xf bound_ctrl:1
	v_cvt_pk_bf16_f32 v101, v101, s0
	v_mul_f32_e32 v107, v107, v109
	v_add_f32_dpp v98, v98, v98 row_ror:4 row_mask:0xf bank_mask:0xf bound_ctrl:1
	v_lshlrev_b32_e32 v101, 16, v101
	v_cvt_pk_bf16_f32 v107, v107, s0
	v_add_f32_dpp v98, v98, v98 row_ror:8 row_mask:0xf bank_mask:0xf bound_ctrl:1
	ds_write_b16 v27, v107 offset:864
	v_readlane_b32 s7, v98, 0
	v_readlane_b32 s8, v98, 16
	v_readlane_b32 s6, v98, 32
	v_readlane_b32 s9, v98, 48
	v_add_f32_e32 v98, -1.0, v103
	v_fma_f32 v98, v13, v98, 1.0
	v_mul_f32_e32 v98, v105, v98
	v_cvt_pk_bf16_f32 v98, v98, s0
	v_lshlrev_b32_e32 v98, 16, v98
	v_mul_f32_e32 v105, v101, v98
	v_mul_f32_e32 v107, v11, v105
	s_nop 1
	v_mov_b32_dpp v107, v107 quad_perm:[1,0,3,2] row_mask:0xf bank_mask:0xf bound_ctrl:1
	v_fmac_f32_e32 v107, v11, v105
	s_nop 1
	v_add_f32_dpp v105, v107, v107 quad_perm:[2,3,0,1] row_mask:0xf bank_mask:0xf bound_ctrl:1
	s_nop 1
	v_add_f32_dpp v105, v105, v105 row_ror:4 row_mask:0xf bank_mask:0xf bound_ctrl:1
	s_nop 1
	v_add_f32_dpp v105, v105, v105 row_ror:8 row_mask:0xf bank_mask:0xf bound_ctrl:1
	s_nop 0
	v_readlane_b32 s0, v105, 0
	v_readlane_b32 s15, v105, 16
	v_readlane_b32 s1, v105, 32
	v_readlane_b32 s17, v105, 48
	v_cvt_pk_bf16_f32 v105, v106, s0
	v_add_co_u32_e32 v106, vcc, 0x33600000, v6
	s_nop 1
	v_addc_co_u32_e32 v107, vcc, 0, v7, vcc
	global_store_short v[106:107], v105, off offset:896
	s_and_saveexec_b64 s[4:5], s[38:39]
	s_cbranch_execz .LBB0_297
	s_ashr_i32 s65, s64, 31
	s_lshl_b64 s[30:31], s[64:65], 6
	s_add_u32 s30, s2, s30
	v_mov_b32_e32 v106, s15
	v_mov_b32_e32 v107, s17
	s_addc_u32 s31, s14, s31
	v_pk_add_f32 v[106:107], s[0:1], v[106:107]
	s_nop 0
	v_add_f32_e32 v105, v106, v107
	v_mov_b64_e32 v[106:107], s[30:31]
	global_store_dword v[106:107], v105, off
; __device__ __forceinline__ float bf2f(bf16 b) { return __uint_as_float((unsigned)b << 16); }
; __device__ __forceinline__ bf16 f2bf(float f) { return (bf16)(pk_bf16(f, 0.f) & 0xffffu); }
; __device__ __forceinline__ float fexp(float x) { return __builtin_amdgcn_exp2f(x * 1.4426950408889634f); }
; __device__ __forceinline__ float flog(float x) { return __builtin_amdgcn_logf(x) * 0.6931471805599453f; }
; __device__ __forceinline__ float fsigmoid(float x) { return __builtin_amdgcn_rcpf(1.0f + fexp(-x)); }
; __device__ __forceinline__ void pc_phase(LAS unsigned char* lds, const bf16* Pp_, const bf16* LO, const float* mu, const float* w0, const float* a0, const float* k_k, const float* k_a, const float* r_k, ...
;     ...
;         for (int t = 0; t < 16; ++t) {
;             const float r0 = bf2f(sr_[t + 1]), k0 = bf2f(sk_[t + 1]), v0 = bf2f(sv_[t + 1]);
;             const float r = r0 + (r1 - r0) * mu_r, k = k0 + (k1 - k0) * mu_k, v = v0 + (v1 - v0) * mu_v; r1 = r0; k1 = k0; v1 = v0;
;             const float z = -(w0c + bf2f(slw[t])); const float sp = fmaxf(z, 0.f) + flog(1.0f + fexp(-fabsf(z))); const float w = -sp - 0.5f;
;             const float dec = fexp(-fexp(w)); const float a = fsigmoid(a0c + bf2f(sla[t]));
;             float kk = k * kkc; const float n2 = wsum_dpp(kk * kk); kk = kk / fmaxf(sqrtf(n2), 1e-12f);
;             const float kp = bf2f(f2bf(k * (1.0f + (a - 1.0f) * kac))), bb = bf2f(f2bf(kk * a)), rr = bf2f(f2bf(r)); kk = bf2f(f2bf(kk));
;             const float coef = wsum_dpp(rr * kp * rkc);
;             SV[(ib + t) * 64 + lane] = f2bf(v);
;             if (lane == 0) COEF[(size_t)(m0 + t) * 16 + h] = coef;
;             const float Pp = P; P *= dec; const float inv = 1.0f / P;
;             XKK[t * 72 + lane] = f2bf(kk * Pp); XR[t * 72 + lane] = f2bf(rr * P); XK[t * 72 + lane] = f2bf(kp * inv); XB[t * 72 + lane] = f2bf(bb * inv); }
.LBB0_297:
	s_or_b64 exec, exec, s[4:5]
	v_lshlrev_b32_e32 v95, 16, v95
	v_add_f32_e32 v95, v8, v95
	v_mul_f32_e64 v105, |v95|, s19
	v_exp_f32_e32 v105, v105
	v_mov_b32_e32 v106, s8
	v_mov_b32_e32 v107, s9
	v_add_f32_e32 v106, s7, v106
	v_add_f32_e32 v105, 1.0, v105
	v_log_f32_e32 v105, v105
	v_add_f32_e32 v107, s6, v107
	v_max_f32_e64 v95, -v95, 0
	v_add_f32_e32 v106, v106, v107
	v_fmac_f32_e32 v95, 0x3f317218, v105
	v_mul_f32_e32 v105, 0x4f800000, v106
	v_cmp_gt_f32_e32 vcc, s33, v106
	v_sub_f32_e32 v95, -0.5, v95
	v_mul_f32_e32 v95, 0x3fb8aa3b, v95
	v_cndmask_b32_e32 v105, v106, v105, vcc
	v_sqrt_f32_e32 v106, v105
	v_exp_f32_e32 v95, v95
	v_lshlrev_b32_e32 v91, 16, v91
	v_add_f32_e32 v91, v15, v91
	v_add_u32_e32 v107, -1, v106
	v_fma_f32 v108, -v107, v106, v105
	v_cmp_ge_f32_e64 s[56:57], 0, v108
	v_add_u32_e32 v108, 1, v106
	v_mul_f32_e32 v95, 0xbfb8aa3b, v95
	v_cndmask_b32_e64 v107, v106, v107, s[56:57]
	v_fma_f32 v106, -v108, v106, v105
	v_cmp_lt_f32_e64 s[56:57], 0, v106
	v_exp_f32_e32 v95, v95
	v_mul_f32_e32 v91, 0xbfb8aa3b, v91
	v_cndmask_b32_e64 v106, v107, v108, s[56:57]
	v_mul_f32_e32 v107, 0x37800000, v106
	v_cndmask_b32_e32 v106, v106, v107, vcc
	v_cmp_class_f32_e32 vcc, v105, v219
	v_mul_f32_e32 v95, v96, v95
	v_exp_f32_e32 v91, v91
	v_cndmask_b32_e32 v105, v106, v105, vcc
	v_max_f32_e32 v105, 0x2b8cbccc, v105
	v_div_scale_f32 v106, s[0:1], v105, v105, v104
	v_rcp_f32_e32 v107, v106
	v_lshlrev_b32_e32 v93, 16, v93
	v_add_f32_e32 v91, 1.0, v91
	v_fma_f32 v108, -v106, v107, 1.0
	v_fmac_f32_e32 v107, v108, v107
	v_div_scale_f32 v108, vcc, v104, v105, v104
	v_mul_f32_e32 v109, v108, v107
	v_fma_f32 v110, -v106, v109, v108
	v_fmac_f32_e32 v109, v110, v107
	v_fma_f32 v106, -v106, v109, v108
	v_div_fmas_f32 v106, v106, v107, v109
	v_div_fixup_f32 v104, v106, v105, v104
	v_mul_f32_e32 v103, v103, v104
	v_cvt_pk_bf16_f32 v103, v103, s0
	v_div_scale_f32 v105, s[0:1], v95, v95, 1.0
	v_rcp_f32_e32 v106, v105
	s_nop 0
	v_cvt_pk_bf16_f32 v104, v104, s0
	v_lshlrev_b32_e32 v104, 16, v104
	v_mul_f32_e32 v96, v96, v104
	v_fma_f32 v107, -v105, v106, 1.0
	v_fmac_f32_e32 v106, v107, v106
	v_div_scale_f32 v107, vcc, 1.0, v95, 1.0
	v_mul_f32_e32 v108, v107, v106
	v_fma_f32 v109, -v105, v108, v107
	v_fmac_f32_e32 v108, v109, v106
	v_fma_f32 v105, -v105, v108, v107
	v_cvt_pk_bf16_f32 v96, v96, s0
	v_div_fmas_f32 v105, v105, v106, v108
	ds_write_b16 v27, v96 offset:1008
	v_mul_f32_e32 v96, v95, v101
	v_div_fixup_f32 v105, v105, v95, 1.0
	v_cvt_pk_bf16_f32 v96, v96, s0
	ds_write_b16 v27, v96 offset:3312
	v_mul_f32_e32 v96, v105, v98
	v_lshlrev_b32_e32 v103, 16, v103
	v_cvt_pk_bf16_f32 v96, v96, s0
	ds_write_b16 v27, v96 offset:5616
	v_mul_f32_e32 v96, v105, v103
	v_cvt_pk_bf16_f32 v96, v96, s0
	v_sub_f32_e32 v98, v100, v93
	ds_write_b16 v27, v96 offset:7920
	v_lshlrev_b32_e32 v96, 16, v92
	v_lshlrev_b32_e32 v92, 16, v94
	v_fma_f32 v100, v9, v98, v93
	v_sub_f32_e32 v98, v99, v92
	v_mul_f32_e32 v99, v14, v100
	v_fma_f32 v101, v12, v98, v92
	v_rcp_f32_e32 v98, v91
	v_mul_f32_e32 v91, v99, v99
	v_sub_f32_e32 v94, v102, v96
	v_fma_f32 v94, v10, v94, v96
	v_mov_b32_dpp v91, v91 quad_perm:[1,0,3,2] row_mask:0xf bank_mask:0xf bound_ctrl:1
	v_fmac_f32_e32 v91, v99, v99
	v_cvt_pk_bf16_f32 v94, v94, s0
	v_lshlrev_b32_e32 v94, 16, v94
	v_add_f32_dpp v91, v91, v91 quad_perm:[2,3,0,1] row_mask:0xf bank_mask:0xf bound_ctrl:1
	s_nop 1
	v_add_f32_dpp v91, v91, v91 row_ror:4 row_mask:0xf bank_mask:0xf bound_ctrl:1
	s_nop 1
	v_add_f32_dpp v91, v91, v91 row_ror:8 row_mask:0xf bank_mask:0xf bound_ctrl:1
	s_nop 0
	v_readlane_b32 s7, v91, 0
	v_readlane_b32 s8, v91, 16
	v_readlane_b32 s6, v91, 32
	v_readlane_b32 s9, v91, 48
	v_add_f32_e32 v91, -1.0, v98
	v_fma_f32 v91, v13, v91, 1.0
	v_mul_f32_e32 v91, v100, v91
	v_cvt_pk_bf16_f32 v91, v91, s0
	v_lshlrev_b32_e32 v91, 16, v91
	v_mul_f32_e32 v100, v94, v91
	v_mul_f32_e32 v102, v11, v100
	s_nop 1
	v_mov_b32_dpp v102, v102 quad_perm:[1,0,3,2] row_mask:0xf bank_mask:0xf bound_ctrl:1
	v_fmac_f32_e32 v102, v11, v100
	s_nop 1
	v_add_f32_dpp v100, v102, v102 quad_perm:[2,3,0,1] row_mask:0xf bank_mask:0xf bound_ctrl:1
	s_nop 1
	v_add_f32_dpp v100, v100, v100 row_ror:4 row_mask:0xf bank_mask:0xf bound_ctrl:1
	s_nop 1
	v_add_f32_dpp v100, v100, v100 row_ror:8 row_mask:0xf bank_mask:0xf bound_ctrl:1
	s_nop 0
	v_readlane_b32 s0, v100, 0
	v_readlane_b32 s15, v100, 16
	v_readlane_b32 s1, v100, 32
	v_readlane_b32 s17, v100, 48
	v_add_co_u32_e32 v100, vcc, 0x33600000, v6
	v_cvt_pk_bf16_f32 v102, v101, s0
	s_nop 0
	v_addc_co_u32_e32 v101, vcc, 0, v7, vcc
	global_store_short v[100:101], v102, off offset:1024
	s_and_saveexec_b64 s[4:5], s[38:39]
	s_cbranch_execz .LBB0_299
	s_ashr_i32 s63, s62, 31
	s_lshl_b64 s[30:31], s[62:63], 6
	s_add_u32 s30, s2, s30
	v_mov_b32_e32 v100, s15
	v_mov_b32_e32 v101, s17
	s_addc_u32 s31, s14, s31
	v_pk_add_f32 v[100:101], s[0:1], v[100:101]
	v_readlane_b32 s63, v254, 44
	v_add_f32_e32 v102, v100, v101
	v_mov_b64_e32 v[100:101], s[30:31]
	global_store_dword v[100:101], v102, off
; __device__ __forceinline__ float bf2f(bf16 b) { return __uint_as_float((unsigned)b << 16); }
; __device__ __forceinline__ bf16 f2bf(float f) { return (bf16)(pk_bf16(f, 0.f) & 0xffffu); }
; __device__ __forceinline__ float fexp(float x) { return __builtin_amdgcn_exp2f(x * 1.4426950408889634f); }
; __device__ __forceinline__ float flog(float x) { return __builtin_amdgcn_logf(x) * 0.6931471805599453f; }
; __device__ __forceinline__ float fsigmoid(float x) { return __builtin_amdgcn_rcpf(1.0f + fexp(-x)); }
; __device__ __forceinline__ void pc_phase(LAS unsigned char* lds, const bf16* Pp_, const bf16* LO, const float* mu, const float* w0, const float* a0, const float* k_k, const float* k_a, const float* r_k, ...
;     ...
;         for (int t = 0; t < 16; ++t) {
;             const float r0 = bf2f(sr_[t + 1]), k0 = bf2f(sk_[t + 1]), v0 = bf2f(sv_[t + 1]);
;             const float r = r0 + (r1 - r0) * mu_r, k = k0 + (k1 - k0) * mu_k, v = v0 + (v1 - v0) * mu_v; r1 = r0; k1 = k0; v1 = v0;
;             const float z = -(w0c + bf2f(slw[t])); const float sp = fmaxf(z, 0.f) + flog(1.0f + fexp(-fabsf(z))); const float w = -sp - 0.5f;
;             const float dec = fexp(-fexp(w)); const float a = fsigmoid(a0c + bf2f(sla[t]));
;             float kk = k * kkc; const float n2 = wsum_dpp(kk * kk); kk = kk / fmaxf(sqrtf(n2), 1e-12f);
;             const float kp = bf2f(f2bf(k * (1.0f + (a - 1.0f) * kac))), bb = bf2f(f2bf(kk * a)), rr = bf2f(f2bf(r)); kk = bf2f(f2bf(kk));
;             const float coef = wsum_dpp(rr * kp * rkc);
;             SV[(ib + t) * 64 + lane] = f2bf(v);
;             if (lane == 0) COEF[(size_t)(m0 + t) * 16 + h] = coef;
;             const float Pp = P; P *= dec; const float inv = 1.0f / P;
;             XKK[t * 72 + lane] = f2bf(kk * Pp); XR[t * 72 + lane] = f2bf(rr * P); XK[t * 72 + lane] = f2bf(kp * inv); XB[t * 72 + lane] = f2bf(bb * inv); }
.LBB0_299:
	s_or_b64 exec, exec, s[4:5]
	v_lshlrev_b32_e32 v90, 16, v90
	v_add_f32_e32 v90, v8, v90
	v_mul_f32_e64 v100, |v90|, s19
	v_exp_f32_e32 v100, v100
	v_mov_b32_e32 v101, s8
	v_mov_b32_e32 v102, s9
	v_add_f32_e32 v101, s7, v101
	v_add_f32_e32 v100, 1.0, v100
	v_log_f32_e32 v100, v100
	v_add_f32_e32 v102, s6, v102
	v_max_f32_e64 v90, -v90, 0
	v_add_f32_e32 v101, v101, v102
	v_fmac_f32_e32 v90, 0x3f317218, v100
	v_mul_f32_e32 v100, 0x4f800000, v101
	v_cmp_gt_f32_e32 vcc, s33, v101
	v_sub_f32_e32 v90, -0.5, v90
	v_mul_f32_e32 v90, 0x3fb8aa3b, v90
	v_cndmask_b32_e32 v100, v101, v100, vcc
	v_sqrt_f32_e32 v101, v100
	v_exp_f32_e32 v90, v90
	v_lshlrev_b32_e32 v86, 16, v86
	v_add_f32_e32 v86, v15, v86
	v_add_u32_e32 v102, -1, v101
	v_fma_f32 v103, -v102, v101, v100
	v_cmp_ge_f32_e64 s[56:57], 0, v103
	v_add_u32_e32 v103, 1, v101
	v_mul_f32_e32 v90, 0xbfb8aa3b, v90
	v_cndmask_b32_e64 v102, v101, v102, s[56:57]
	v_fma_f32 v101, -v103, v101, v100
	v_cmp_lt_f32_e64 s[56:57], 0, v101
	v_exp_f32_e32 v90, v90
	v_mul_f32_e32 v86, 0xbfb8aa3b, v86
	v_cndmask_b32_e64 v101, v102, v103, s[56:57]
	v_mul_f32_e32 v102, 0x37800000, v101
	v_cndmask_b32_e32 v101, v101, v102, vcc
	v_cmp_class_f32_e32 vcc, v100, v219
	v_mul_f32_e32 v90, v95, v90
	v_exp_f32_e32 v86, v86
	v_cndmask_b32_e32 v100, v101, v100, vcc
	v_max_f32_e32 v100, 0x2b8cbccc, v100
	v_div_scale_f32 v101, s[0:1], v100, v100, v99
	v_rcp_f32_e32 v102, v101
	v_mul_f32_e32 v94, v90, v94
	v_lshlrev_b32_e32 v88, 16, v88
	v_sub_f32_e32 v93, v93, v88
	v_fma_f32 v103, -v101, v102, 1.0
	v_fmac_f32_e32 v102, v103, v102
	v_div_scale_f32 v103, vcc, v99, v100, v99
	v_mul_f32_e32 v104, v103, v102
	v_fma_f32 v105, -v101, v104, v103
	v_fmac_f32_e32 v104, v105, v102
	v_fma_f32 v101, -v101, v104, v103
	v_div_fmas_f32 v101, v101, v102, v104
	v_div_fixup_f32 v99, v101, v100, v99
	v_mul_f32_e32 v98, v98, v99
	v_cvt_pk_bf16_f32 v98, v98, s0
	v_div_scale_f32 v100, s[0:1], v90, v90, 1.0
	v_rcp_f32_e32 v101, v100
	v_lshlrev_b32_e32 v98, 16, v98
	v_cvt_pk_bf16_f32 v99, v99, s0
	v_lshlrev_b32_e32 v99, 16, v99
	v_fma_f32 v102, -v100, v101, 1.0
	v_fmac_f32_e32 v101, v102, v101
	v_div_scale_f32 v102, vcc, 1.0, v90, 1.0
	v_mul_f32_e32 v103, v102, v101
	v_fma_f32 v104, -v100, v103, v102
	v_fmac_f32_e32 v103, v104, v101
	v_fma_f32 v100, -v100, v103, v102
	v_div_fmas_f32 v100, v100, v101, v103
	v_div_fixup_f32 v100, v100, v90, 1.0
	v_mul_f32_e32 v91, v100, v91
	v_cvt_pk_bf16_f32 v91, v91, s0
	ds_write_b16 v27, v91 offset:5760
	v_mul_f32_e32 v91, v100, v98
	v_cvt_pk_bf16_f32 v94, v94, s0
	v_cvt_pk_bf16_f32 v91, v91, s0
	v_mul_f32_e32 v95, v95, v99
	ds_write_b16 v27, v94 offset:3456
	ds_write_b16 v27, v91 offset:8064
	v_lshlrev_b32_e32 v91, 16, v87
	v_lshlrev_b32_e32 v87, 16, v89
	v_fma_f32 v94, v9, v93, v88
	v_cvt_pk_bf16_f32 v95, v95, s0
	v_sub_f32_e32 v92, v92, v87
	v_add_f32_e32 v86, 1.0, v86
	v_mul_f32_e32 v93, v14, v94
	ds_write_b16 v27, v95 offset:1152
	v_fma_f32 v95, v12, v92, v87
	v_rcp_f32_e32 v92, v86
	v_mul_f32_e32 v86, v93, v93
	v_sub_f32_e32 v89, v96, v91
	v_fma_f32 v89, v10, v89, v91
	v_mov_b32_dpp v86, v86 quad_perm:[1,0,3,2] row_mask:0xf bank_mask:0xf bound_ctrl:1
	v_fmac_f32_e32 v86, v93, v93
	v_cvt_pk_bf16_f32 v89, v89, s0
	v_lshlrev_b32_e32 v89, 16, v89
	v_add_f32_dpp v86, v86, v86 quad_perm:[2,3,0,1] row_mask:0xf bank_mask:0xf bound_ctrl:1
	s_nop 1
	v_add_f32_dpp v86, v86, v86 row_ror:4 row_mask:0xf bank_mask:0xf bound_ctrl:1
	s_nop 1
	v_add_f32_dpp v86, v86, v86 row_ror:8 row_mask:0xf bank_mask:0xf bound_ctrl:1
	s_nop 0
	v_readlane_b32 s7, v86, 0
	v_readlane_b32 s8, v86, 16
	v_readlane_b32 s6, v86, 32
	v_readlane_b32 s9, v86, 48
	v_add_f32_e32 v86, -1.0, v92
	v_fma_f32 v86, v13, v86, 1.0
	v_mul_f32_e32 v86, v94, v86
	v_cvt_pk_bf16_f32 v86, v86, s0
	v_lshlrev_b32_e32 v86, 16, v86
	v_mul_f32_e32 v94, v89, v86
	v_mul_f32_e32 v96, v11, v94
	s_nop 1
	v_mov_b32_dpp v96, v96 quad_perm:[1,0,3,2] row_mask:0xf bank_mask:0xf bound_ctrl:1
	v_fmac_f32_e32 v96, v11, v94
	s_nop 1
	v_add_f32_dpp v94, v96, v96 quad_perm:[2,3,0,1] row_mask:0xf bank_mask:0xf bound_ctrl:1
	s_nop 1
	v_add_f32_dpp v94, v94, v94 row_ror:4 row_mask:0xf bank_mask:0xf bound_ctrl:1
	s_nop 1
	v_add_f32_dpp v94, v94, v94 row_ror:8 row_mask:0xf bank_mask:0xf bound_ctrl:1
	s_nop 0
	v_readlane_b32 s0, v94, 0
	v_readlane_b32 s15, v94, 16
	v_readlane_b32 s1, v94, 32
	v_readlane_b32 s17, v94, 48
	v_add_co_u32_e32 v94, vcc, 0x33600000, v6
	v_cvt_pk_bf16_f32 v96, v95, s0
	s_nop 0
	v_addc_co_u32_e32 v95, vcc, 0, v7, vcc
	global_store_short v[94:95], v96, off offset:1152
	s_and_saveexec_b64 s[4:5], s[38:39]
	s_cbranch_execz .LBB0_301
	s_ashr_i32 s37, s36, 31
	s_lshl_b64 s[30:31], s[36:37], 6
	s_add_u32 s30, s2, s30
	v_mov_b32_e32 v94, s15
	v_mov_b32_e32 v95, s17
	s_addc_u32 s31, s14, s31
	v_pk_add_f32 v[94:95], s[0:1], v[94:95]
	s_nop 0
	v_add_f32_e32 v96, v94, v95
	v_mov_b64_e32 v[94:95], s[30:31]
	global_store_dword v[94:95], v96, off
; __device__ __forceinline__ float bf2f(bf16 b) { return __uint_as_float((unsigned)b << 16); }
; __device__ __forceinline__ bf16 f2bf(float f) { return (bf16)(pk_bf16(f, 0.f) & 0xffffu); }
; __device__ __forceinline__ float fexp(float x) { return __builtin_amdgcn_exp2f(x * 1.4426950408889634f); }
; __device__ __forceinline__ float flog(float x) { return __builtin_amdgcn_logf(x) * 0.6931471805599453f; }
; __device__ __forceinline__ float fsigmoid(float x) { return __builtin_amdgcn_rcpf(1.0f + fexp(-x)); }
; __device__ __forceinline__ void pc_phase(LAS unsigned char* lds, const bf16* Pp_, const bf16* LO, const float* mu, const float* w0, const float* a0, const float* k_k, const float* k_a, const float* r_k, ...
;     ...
;         for (int t = 0; t < 16; ++t) {
;             const float r0 = bf2f(sr_[t + 1]), k0 = bf2f(sk_[t + 1]), v0 = bf2f(sv_[t + 1]);
;             const float r = r0 + (r1 - r0) * mu_r, k = k0 + (k1 - k0) * mu_k, v = v0 + (v1 - v0) * mu_v; r1 = r0; k1 = k0; v1 = v0;
;             const float z = -(w0c + bf2f(slw[t])); const float sp = fmaxf(z, 0.f) + flog(1.0f + fexp(-fabsf(z))); const float w = -sp - 0.5f;
;             const float dec = fexp(-fexp(w)); const float a = fsigmoid(a0c + bf2f(sla[t]));
;             float kk = k * kkc; const float n2 = wsum_dpp(kk * kk); kk = kk / fmaxf(sqrtf(n2), 1e-12f);
;             const float kp = bf2f(f2bf(k * (1.0f + (a - 1.0f) * kac))), bb = bf2f(f2bf(kk * a)), rr = bf2f(f2bf(r)); kk = bf2f(f2bf(kk));
;             const float coef = wsum_dpp(rr * kp * rkc);
;             SV[(ib + t) * 64 + lane] = f2bf(v);
;             if (lane == 0) COEF[(size_t)(m0 + t) * 16 + h] = coef;
;             const float Pp = P; P *= dec; const float inv = 1.0f / P;
;             XKK[t * 72 + lane] = f2bf(kk * Pp); XR[t * 72 + lane] = f2bf(rr * P); XK[t * 72 + lane] = f2bf(kp * inv); XB[t * 72 + lane] = f2bf(bb * inv); }
.LBB0_301:
	s_or_b64 exec, exec, s[4:5]
	v_lshlrev_b32_e32 v85, 16, v85
	v_add_f32_e32 v85, v8, v85
	v_mul_f32_e64 v94, |v85|, s19
	v_exp_f32_e32 v94, v94
	v_mov_b32_e32 v95, s8
	v_mov_b32_e32 v96, s9
	v_add_f32_e32 v95, s7, v95
	v_add_f32_e32 v94, 1.0, v94
	v_log_f32_e32 v94, v94
	v_add_f32_e32 v96, s6, v96
	v_max_f32_e64 v85, -v85, 0
	v_add_f32_e32 v95, v95, v96
	v_fmac_f32_e32 v85, 0x3f317218, v94
	v_mul_f32_e32 v94, 0x4f800000, v95
	v_cmp_gt_f32_e32 vcc, s33, v95
	v_sub_f32_e32 v85, -0.5, v85
	v_mul_f32_e32 v85, 0x3fb8aa3b, v85
	v_cndmask_b32_e32 v94, v95, v94, vcc
	v_sqrt_f32_e32 v95, v94
	v_exp_f32_e32 v85, v85
	v_lshlrev_b32_e32 v81, 16, v81
	v_add_f32_e32 v81, v15, v81
	v_add_u32_e32 v96, -1, v95
	v_fma_f32 v98, -v96, v95, v94
	v_cmp_ge_f32_e64 s[56:57], 0, v98
	v_add_u32_e32 v98, 1, v95
	v_mul_f32_e32 v85, 0xbfb8aa3b, v85
	v_cndmask_b32_e64 v96, v95, v96, s[56:57]
	v_fma_f32 v95, -v98, v95, v94
	v_cmp_lt_f32_e64 s[56:57], 0, v95
	v_exp_f32_e32 v85, v85
	v_mul_f32_e32 v81, 0xbfb8aa3b, v81
	v_cndmask_b32_e64 v95, v96, v98, s[56:57]
	v_mul_f32_e32 v96, 0x37800000, v95
	v_cndmask_b32_e32 v95, v95, v96, vcc
	v_cmp_class_f32_e32 vcc, v94, v219
	v_mul_f32_e32 v85, v90, v85
	v_exp_f32_e32 v81, v81
	v_cndmask_b32_e32 v94, v95, v94, vcc
	v_max_f32_e32 v94, 0x2b8cbccc, v94
	v_div_scale_f32 v95, s[0:1], v94, v94, v93
	v_rcp_f32_e32 v96, v95
	v_mul_f32_e32 v89, v85, v89
	v_lshlrev_b32_e32 v83, 16, v83
	v_sub_f32_e32 v88, v88, v83
	v_fma_f32 v98, -v95, v96, 1.0
	v_fmac_f32_e32 v96, v98, v96
	v_div_scale_f32 v98, vcc, v93, v94, v93
	v_mul_f32_e32 v99, v98, v96
	v_fma_f32 v100, -v95, v99, v98
	v_fmac_f32_e32 v99, v100, v96
	v_fma_f32 v95, -v95, v99, v98
	v_div_fmas_f32 v95, v95, v96, v99
	v_div_fixup_f32 v93, v95, v94, v93
	v_mul_f32_e32 v92, v92, v93
	v_cvt_pk_bf16_f32 v92, v92, s0
	v_div_scale_f32 v94, s[0:1], v85, v85, 1.0
	v_rcp_f32_e32 v95, v94
	v_lshlrev_b32_e32 v92, 16, v92
	v_cvt_pk_bf16_f32 v93, v93, s0
	v_lshlrev_b32_e32 v93, 16, v93
	v_fma_f32 v96, -v94, v95, 1.0
	v_fmac_f32_e32 v95, v96, v95
	v_div_scale_f32 v96, vcc, 1.0, v85, 1.0
	v_mul_f32_e32 v98, v96, v95
	v_fma_f32 v99, -v94, v98, v96
	v_fmac_f32_e32 v98, v99, v95
	v_fma_f32 v94, -v94, v98, v96
	v_div_fmas_f32 v94, v94, v95, v98
	v_div_fixup_f32 v94, v94, v85, 1.0
	v_mul_f32_e32 v86, v94, v86
	v_cvt_pk_bf16_f32 v86, v86, s0
	ds_write_b16 v27, v86 offset:5904
	v_mul_f32_e32 v86, v94, v92
	v_cvt_pk_bf16_f32 v89, v89, s0
	v_cvt_pk_bf16_f32 v86, v86, s0
	v_mul_f32_e32 v90, v90, v93
	ds_write_b16 v27, v89 offset:3600
	ds_write_b16 v27, v86 offset:8208
	v_lshlrev_b32_e32 v86, 16, v82
	v_lshlrev_b32_e32 v82, 16, v84
	v_fma_f32 v89, v9, v88, v83
	v_cvt_pk_bf16_f32 v90, v90, s0
	v_sub_f32_e32 v87, v87, v82
	v_add_f32_e32 v81, 1.0, v81
	v_mul_f32_e32 v88, v14, v89
	ds_write_b16 v27, v90 offset:1296
	v_fma_f32 v90, v12, v87, v82
	v_rcp_f32_e32 v87, v81
	v_mul_f32_e32 v81, v88, v88
	v_sub_f32_e32 v84, v91, v86
	v_fma_f32 v84, v10, v84, v86
	v_mov_b32_dpp v81, v81 quad_perm:[1,0,3,2] row_mask:0xf bank_mask:0xf bound_ctrl:1
	v_fmac_f32_e32 v81, v88, v88
	v_cvt_pk_bf16_f32 v84, v84, s0
	v_lshlrev_b32_e32 v84, 16, v84
	v_add_f32_dpp v81, v81, v81 quad_perm:[2,3,0,1] row_mask:0xf bank_mask:0xf bound_ctrl:1
	s_nop 1
	v_add_f32_dpp v81, v81, v81 row_ror:4 row_mask:0xf bank_mask:0xf bound_ctrl:1
	s_nop 1
	v_add_f32_dpp v81, v81, v81 row_ror:8 row_mask:0xf bank_mask:0xf bound_ctrl:1
	s_nop 0
	v_readlane_b32 s7, v81, 0
	v_readlane_b32 s8, v81, 16
	v_readlane_b32 s6, v81, 32
	v_readlane_b32 s9, v81, 48
	v_add_f32_e32 v81, -1.0, v87
	v_fma_f32 v81, v13, v81, 1.0
	v_mul_f32_e32 v81, v89, v81
	v_cvt_pk_bf16_f32 v81, v81, s0
	v_lshlrev_b32_e32 v81, 16, v81
	v_mul_f32_e32 v89, v84, v81
	v_mul_f32_e32 v91, v11, v89
	s_nop 1
	v_mov_b32_dpp v91, v91 quad_perm:[1,0,3,2] row_mask:0xf bank_mask:0xf bound_ctrl:1
	v_fmac_f32_e32 v91, v11, v89
	s_nop 1
	v_add_f32_dpp v89, v91, v91 quad_perm:[2,3,0,1] row_mask:0xf bank_mask:0xf bound_ctrl:1
	s_nop 1
	v_add_f32_dpp v89, v89, v89 row_ror:4 row_mask:0xf bank_mask:0xf bound_ctrl:1
	s_nop 1
	v_add_f32_dpp v89, v89, v89 row_ror:8 row_mask:0xf bank_mask:0xf bound_ctrl:1
	s_nop 0
	v_readlane_b32 s0, v89, 0
	v_readlane_b32 s15, v89, 16
	v_readlane_b32 s1, v89, 32
	v_readlane_b32 s17, v89, 48
	v_cvt_pk_bf16_f32 v89, v90, s0
	v_add_co_u32_e32 v90, vcc, 0x33600000, v6
	s_nop 1
	v_addc_co_u32_e32 v91, vcc, 0, v7, vcc
	global_store_short v[90:91], v89, off offset:1280
	s_and_saveexec_b64 s[4:5], s[38:39]
	s_cbranch_execz .LBB0_303
	s_ashr_i32 s85, s84, 31
	s_lshl_b64 s[30:31], s[84:85], 6
	s_add_u32 s30, s2, s30
	v_mov_b32_e32 v90, s15
	v_mov_b32_e32 v91, s17
	s_addc_u32 s31, s14, s31
	v_pk_add_f32 v[90:91], s[0:1], v[90:91]
	s_nop 0
	v_add_f32_e32 v89, v90, v91
	v_mov_b64_e32 v[90:91], s[30:31]
	global_store_dword v[90:91], v89, off
; __device__ __forceinline__ float bf2f(bf16 b) { return __uint_as_float((unsigned)b << 16); }
; __device__ __forceinline__ bf16 f2bf(float f) { return (bf16)(pk_bf16(f, 0.f) & 0xffffu); }
; __device__ __forceinline__ float fexp(float x) { return __builtin_amdgcn_exp2f(x * 1.4426950408889634f); }
; __device__ __forceinline__ float flog(float x) { return __builtin_amdgcn_logf(x) * 0.6931471805599453f; }
; __device__ __forceinline__ float fsigmoid(float x) { return __builtin_amdgcn_rcpf(1.0f + fexp(-x)); }
; __device__ __forceinline__ void pc_phase(LAS unsigned char* lds, const bf16* Pp_, const bf16* LO, const float* mu, const float* w0, const float* a0, const float* k_k, const float* k_a, const float* r_k, ...
;     ...
;         for (int t = 0; t < 16; ++t) {
;             const float r0 = bf2f(sr_[t + 1]), k0 = bf2f(sk_[t + 1]), v0 = bf2f(sv_[t + 1]);
;             const float r = r0 + (r1 - r0) * mu_r, k = k0 + (k1 - k0) * mu_k, v = v0 + (v1 - v0) * mu_v; r1 = r0; k1 = k0; v1 = v0;
;             const float z = -(w0c + bf2f(slw[t])); const float sp = fmaxf(z, 0.f) + flog(1.0f + fexp(-fabsf(z))); const float w = -sp - 0.5f;
;             const float dec = fexp(-fexp(w)); const float a = fsigmoid(a0c + bf2f(sla[t]));
;             float kk = k * kkc; const float n2 = wsum_dpp(kk * kk); kk = kk / fmaxf(sqrtf(n2), 1e-12f);
;             const float kp = bf2f(f2bf(k * (1.0f + (a - 1.0f) * kac))), bb = bf2f(f2bf(kk * a)), rr = bf2f(f2bf(r)); kk = bf2f(f2bf(kk));
;             const float coef = wsum_dpp(rr * kp * rkc);
;             SV[(ib + t) * 64 + lane] = f2bf(v);
;             if (lane == 0) COEF[(size_t)(m0 + t) * 16 + h] = coef;
;             const float Pp = P; P *= dec; const float inv = 1.0f / P;
;             XKK[t * 72 + lane] = f2bf(kk * Pp); XR[t * 72 + lane] = f2bf(rr * P); XK[t * 72 + lane] = f2bf(kp * inv); XB[t * 72 + lane] = f2bf(bb * inv); }
.LBB0_303:
	s_or_b64 exec, exec, s[4:5]
	v_lshlrev_b32_e32 v80, 16, v80
	v_add_f32_e32 v80, v8, v80
	v_mul_f32_e64 v89, |v80|, s19
	v_exp_f32_e32 v89, v89
	v_mov_b32_e32 v90, s8
	v_mov_b32_e32 v91, s9
	v_add_f32_e32 v90, s7, v90
	v_add_f32_e32 v89, 1.0, v89
	v_log_f32_e32 v89, v89
	v_add_f32_e32 v91, s6, v91
	v_max_f32_e64 v80, -v80, 0
	v_add_f32_e32 v90, v90, v91
	v_fmac_f32_e32 v80, 0x3f317218, v89
	v_mul_f32_e32 v89, 0x4f800000, v90
	v_cmp_gt_f32_e32 vcc, s33, v90
	v_sub_f32_e32 v80, -0.5, v80
	v_mul_f32_e32 v80, 0x3fb8aa3b, v80
	v_cndmask_b32_e32 v89, v90, v89, vcc
	v_sqrt_f32_e32 v90, v89
	v_exp_f32_e32 v80, v80
	v_lshlrev_b32_e32 v76, 16, v76
	v_add_f32_e32 v76, v15, v76
	v_add_u32_e32 v91, -1, v90
	v_fma_f32 v92, -v91, v90, v89
	v_cmp_ge_f32_e64 s[56:57], 0, v92
	v_add_u32_e32 v92, 1, v90
	v_mul_f32_e32 v80, 0xbfb8aa3b, v80
	v_cndmask_b32_e64 v91, v90, v91, s[56:57]
	v_fma_f32 v90, -v92, v90, v89
	v_cmp_lt_f32_e64 s[56:57], 0, v90
	v_exp_f32_e32 v80, v80
	v_mul_f32_e32 v76, 0xbfb8aa3b, v76
	v_cndmask_b32_e64 v90, v91, v92, s[56:57]
	v_mul_f32_e32 v91, 0x37800000, v90
	v_cndmask_b32_e32 v90, v90, v91, vcc
	v_cmp_class_f32_e32 vcc, v89, v219
	v_mul_f32_e32 v80, v85, v80
	v_exp_f32_e32 v76, v76
	v_cndmask_b32_e32 v89, v90, v89, vcc
	v_max_f32_e32 v89, 0x2b8cbccc, v89
	v_div_scale_f32 v90, s[0:1], v89, v89, v88
	v_rcp_f32_e32 v91, v90
	v_mul_f32_e32 v84, v80, v84
	v_lshlrev_b32_e32 v78, 16, v78
	v_sub_f32_e32 v83, v83, v78
	v_fma_f32 v92, -v90, v91, 1.0
	v_fmac_f32_e32 v91, v92, v91
	v_div_scale_f32 v92, vcc, v88, v89, v88
	v_mul_f32_e32 v93, v92, v91
	v_fma_f32 v94, -v90, v93, v92
	v_fmac_f32_e32 v93, v94, v91
	v_fma_f32 v90, -v90, v93, v92
	v_div_fmas_f32 v90, v90, v91, v93
	v_div_fixup_f32 v88, v90, v89, v88
	v_mul_f32_e32 v87, v87, v88
	v_cvt_pk_bf16_f32 v87, v87, s0
	v_div_scale_f32 v89, s[0:1], v80, v80, 1.0
	v_rcp_f32_e32 v90, v89
	v_lshlrev_b32_e32 v87, 16, v87
	v_cvt_pk_bf16_f32 v88, v88, s0
	v_lshlrev_b32_e32 v88, 16, v88
	v_fma_f32 v91, -v89, v90, 1.0
	v_fmac_f32_e32 v90, v91, v90
	v_div_scale_f32 v91, vcc, 1.0, v80, 1.0
	v_mul_f32_e32 v92, v91, v90
	v_fma_f32 v93, -v89, v92, v91
	v_fmac_f32_e32 v92, v93, v90
	v_fma_f32 v89, -v89, v92, v91
	v_div_fmas_f32 v89, v89, v90, v92
	v_div_fixup_f32 v89, v89, v80, 1.0
	v_mul_f32_e32 v81, v89, v81
	v_cvt_pk_bf16_f32 v81, v81, s0
	ds_write_b16 v27, v81 offset:6048
	v_mul_f32_e32 v81, v89, v87
	v_cvt_pk_bf16_f32 v84, v84, s0
	v_cvt_pk_bf16_f32 v81, v81, s0
	v_mul_f32_e32 v85, v85, v88
	ds_write_b16 v27, v84 offset:3744
	ds_write_b16 v27, v81 offset:8352
	v_lshlrev_b32_e32 v81, 16, v77
	v_lshlrev_b32_e32 v77, 16, v79
	v_fma_f32 v84, v9, v83, v78
	v_cvt_pk_bf16_f32 v85, v85, s0
	v_sub_f32_e32 v82, v82, v77
	v_add_f32_e32 v76, 1.0, v76
	v_mul_f32_e32 v83, v14, v84
	ds_write_b16 v27, v85 offset:1440
	v_fma_f32 v85, v12, v82, v77
	v_rcp_f32_e32 v82, v76
	v_mul_f32_e32 v76, v83, v83
	v_sub_f32_e32 v79, v86, v81
	v_fma_f32 v79, v10, v79, v81
	v_mov_b32_dpp v76, v76 quad_perm:[1,0,3,2] row_mask:0xf bank_mask:0xf bound_ctrl:1
	v_fmac_f32_e32 v76, v83, v83
	v_cvt_pk_bf16_f32 v79, v79, s0
	v_lshlrev_b32_e32 v79, 16, v79
	v_add_f32_dpp v76, v76, v76 quad_perm:[2,3,0,1] row_mask:0xf bank_mask:0xf bound_ctrl:1
	s_nop 1
	v_add_f32_dpp v76, v76, v76 row_ror:4 row_mask:0xf bank_mask:0xf bound_ctrl:1
	s_nop 1
	v_add_f32_dpp v76, v76, v76 row_ror:8 row_mask:0xf bank_mask:0xf bound_ctrl:1
	s_nop 0
	v_readlane_b32 s7, v76, 0
	v_readlane_b32 s8, v76, 16
	v_readlane_b32 s6, v76, 32
	v_readlane_b32 s9, v76, 48
	v_add_f32_e32 v76, -1.0, v82
	v_fma_f32 v76, v13, v76, 1.0
	v_mul_f32_e32 v76, v84, v76
	v_cvt_pk_bf16_f32 v76, v76, s0
	v_lshlrev_b32_e32 v76, 16, v76
	v_mul_f32_e32 v84, v79, v76
	v_mul_f32_e32 v86, v11, v84
	s_nop 1
	v_mov_b32_dpp v86, v86 quad_perm:[1,0,3,2] row_mask:0xf bank_mask:0xf bound_ctrl:1
	v_fmac_f32_e32 v86, v11, v84
	s_nop 1
	v_add_f32_dpp v84, v86, v86 quad_perm:[2,3,0,1] row_mask:0xf bank_mask:0xf bound_ctrl:1
	s_nop 1
	v_add_f32_dpp v84, v84, v84 row_ror:4 row_mask:0xf bank_mask:0xf bound_ctrl:1
	s_nop 1
	v_add_f32_dpp v84, v84, v84 row_ror:8 row_mask:0xf bank_mask:0xf bound_ctrl:1
	s_nop 0
	v_readlane_b32 s0, v84, 0
	v_readlane_b32 s15, v84, 16
	v_readlane_b32 s1, v84, 32
	v_readlane_b32 s17, v84, 48
	v_add_co_u32_e32 v84, vcc, 0x33600000, v6
	v_cvt_pk_bf16_f32 v86, v85, s0
	s_nop 0
	v_addc_co_u32_e32 v85, vcc, 0, v7, vcc
	global_store_short v[84:85], v86, off offset:1408
	s_and_saveexec_b64 s[4:5], s[38:39]
	s_cbranch_execz .LBB0_305
	s_ashr_i32 s83, s82, 31
	s_lshl_b64 s[30:31], s[82:83], 6
	s_add_u32 s30, s2, s30
	v_mov_b32_e32 v84, s15
	v_mov_b32_e32 v85, s17
	s_addc_u32 s31, s14, s31
	v_pk_add_f32 v[84:85], s[0:1], v[84:85]
	s_nop 0
	v_add_f32_e32 v86, v84, v85
	v_mov_b64_e32 v[84:85], s[30:31]
	global_store_dword v[84:85], v86, off
; __device__ __forceinline__ float bf2f(bf16 b) { return __uint_as_float((unsigned)b << 16); }
; __device__ __forceinline__ bf16 f2bf(float f) { return (bf16)(pk_bf16(f, 0.f) & 0xffffu); }
; __device__ __forceinline__ float fexp(float x) { return __builtin_amdgcn_exp2f(x * 1.4426950408889634f); }
; __device__ __forceinline__ float flog(float x) { return __builtin_amdgcn_logf(x) * 0.6931471805599453f; }
; __device__ __forceinline__ float fsigmoid(float x) { return __builtin_amdgcn_rcpf(1.0f + fexp(-x)); }
; __device__ __forceinline__ float wsum_dpp(float x) { x = red16(x);
;     return (__builtin_bit_cast(float, __builtin_amdgcn_readlane(__builtin_bit_cast(int, x), 0)) + __builtin_bit_cast(float, __builtin_amdgcn_readlane(__builtin_bit_cast(int, x), 16)))
;          + (__builtin_bit_cast(float, __builtin_amdgcn_readlane(__builtin_bit_cast(int, x), 32)) + __builtin_bit_cast(float, __builtin_amdgcn_readlane(__builtin_bit_cast(int, x), 48))); }
; __device__ __forceinline__ void pc_phase(LAS unsigned char* lds, const bf16* Pp_, const bf16* LO, const float* mu, const float* w0, const float* a0, const float* k_k, const float* k_a, const float* r_k, ...
;     ...
;         for (int t = 0; t < 16; ++t) {
;             const float r0 = bf2f(sr_[t + 1]), k0 = bf2f(sk_[t + 1]), v0 = bf2f(sv_[t + 1]);
;             const float r = r0 + (r1 - r0) * mu_r, k = k0 + (k1 - k0) * mu_k, v = v0 + (v1 - v0) * mu_v; r1 = r0; k1 = k0; v1 = v0;
;             const float z = -(w0c + bf2f(slw[t])); const float sp = fmaxf(z, 0.f) + flog(1.0f + fexp(-fabsf(z))); const float w = -sp - 0.5f;
;             const float dec = fexp(-fexp(w)); const float a = fsigmoid(a0c + bf2f(sla[t]));
;             float kk = k * kkc; const float n2 = wsum_dpp(kk * kk); kk = kk / fmaxf(sqrtf(n2), 1e-12f);
;             const float kp = bf2f(f2bf(k * (1.0f + (a - 1.0f) * kac))), bb = bf2f(f2bf(kk * a)), rr = bf2f(f2bf(r)); kk = bf2f(f2bf(kk));
;             const float coef = wsum_dpp(rr * kp * rkc);
;             SV[(ib + t) * 64 + lane] = f2bf(v);
;             if (lane == 0) COEF[(size_t)(m0 + t) * 16 + h] = coef;
;             const float Pp = P; P *= dec; const float inv = 1.0f / P;
;             XKK[t * 72 + lane] = f2bf(kk * Pp); XR[t * 72 + lane] = f2bf(rr * P); XK[t * 72 + lane] = f2bf(kp * inv); XB[t * 72 + lane] = f2bf(bb * inv); }
.LBB0_305:
	s_or_b64 exec, exec, s[4:5]
	v_lshlrev_b32_e32 v75, 16, v75
	v_add_f32_e32 v75, v8, v75
	v_mul_f32_e64 v84, |v75|, s19
	v_exp_f32_e32 v84, v84
	v_mov_b32_e32 v85, s8
	v_mov_b32_e32 v86, s9
	v_add_f32_e32 v85, s7, v85
	v_add_f32_e32 v84, 1.0, v84
	v_log_f32_e32 v84, v84
	v_add_f32_e32 v86, s6, v86
	v_max_f32_e64 v75, -v75, 0
	v_add_f32_e32 v85, v85, v86
	v_fmac_f32_e32 v75, 0x3f317218, v84
	v_mul_f32_e32 v84, 0x4f800000, v85
	v_cmp_gt_f32_e32 vcc, s33, v85
	v_sub_f32_e32 v75, -0.5, v75
	v_mul_f32_e32 v75, 0x3fb8aa3b, v75
	v_cndmask_b32_e32 v84, v85, v84, vcc
	v_sqrt_f32_e32 v85, v84
	v_exp_f32_e32 v75, v75
	v_lshlrev_b32_e32 v71, 16, v71
	v_add_f32_e32 v71, v15, v71
	v_add_u32_e32 v86, -1, v85
	v_fma_f32 v87, -v86, v85, v84
	v_cmp_ge_f32_e64 s[56:57], 0, v87
	v_add_u32_e32 v87, 1, v85
	v_mul_f32_e32 v75, 0xbfb8aa3b, v75
	v_cndmask_b32_e64 v86, v85, v86, s[56:57]
	v_fma_f32 v85, -v87, v85, v84
	v_cmp_lt_f32_e64 s[56:57], 0, v85
	v_exp_f32_e32 v75, v75
	v_mul_f32_e32 v71, 0xbfb8aa3b, v71
	v_cndmask_b32_e64 v85, v86, v87, s[56:57]
	v_mul_f32_e32 v86, 0x37800000, v85
	v_cndmask_b32_e32 v85, v85, v86, vcc
	v_cmp_class_f32_e32 vcc, v84, v219
	v_mul_f32_e32 v75, v80, v75
	v_exp_f32_e32 v71, v71
	v_cndmask_b32_e32 v84, v85, v84, vcc
	v_max_f32_e32 v84, 0x2b8cbccc, v84
	v_div_scale_f32 v85, s[0:1], v84, v84, v83
	v_rcp_f32_e32 v86, v85
	v_mul_f32_e32 v79, v75, v79
	v_lshlrev_b32_e32 v73, 16, v73
	v_sub_f32_e32 v78, v78, v73
	v_fma_f32 v87, -v85, v86, 1.0
	v_fmac_f32_e32 v86, v87, v86
	v_div_scale_f32 v87, vcc, v83, v84, v83
	v_mul_f32_e32 v88, v87, v86
	v_fma_f32 v89, -v85, v88, v87
	v_fmac_f32_e32 v88, v89, v86
	v_fma_f32 v85, -v85, v88, v87
	v_div_fmas_f32 v85, v85, v86, v88
	v_div_fixup_f32 v83, v85, v84, v83
	v_mul_f32_e32 v82, v82, v83
	v_cvt_pk_bf16_f32 v82, v82, s0
	v_div_scale_f32 v84, s[0:1], v75, v75, 1.0
	v_rcp_f32_e32 v85, v84
	v_lshlrev_b32_e32 v82, 16, v82
	v_cvt_pk_bf16_f32 v83, v83, s0
	v_lshlrev_b32_e32 v83, 16, v83
	v_fma_f32 v86, -v84, v85, 1.0
	v_fmac_f32_e32 v85, v86, v85
	v_div_scale_f32 v86, vcc, 1.0, v75, 1.0
	v_mul_f32_e32 v87, v86, v85
	v_fma_f32 v88, -v84, v87, v86
	v_fmac_f32_e32 v87, v88, v85
	v_fma_f32 v84, -v84, v87, v86
	v_div_fmas_f32 v84, v84, v85, v87
	v_div_fixup_f32 v84, v84, v75, 1.0
	v_mul_f32_e32 v76, v84, v76
	v_cvt_pk_bf16_f32 v76, v76, s0
	ds_write_b16 v27, v76 offset:6192
	v_mul_f32_e32 v76, v84, v82
	v_cvt_pk_bf16_f32 v79, v79, s0
	v_cvt_pk_bf16_f32 v76, v76, s0
	v_mul_f32_e32 v80, v80, v83
	ds_write_b16 v27, v79 offset:3888
	ds_write_b16 v27, v76 offset:8496
	v_lshlrev_b32_e32 v76, 16, v72
	v_lshlrev_b32_e32 v72, 16, v74
	v_fma_f32 v79, v9, v78, v73
	v_cvt_pk_bf16_f32 v80, v80, s0
	v_sub_f32_e32 v77, v77, v72
	v_add_f32_e32 v71, 1.0, v71
	v_mul_f32_e32 v78, v14, v79
	ds_write_b16 v27, v80 offset:1584
	v_fma_f32 v80, v12, v77, v72
	v_rcp_f32_e32 v77, v71
	v_mul_f32_e32 v71, v78, v78
	v_sub_f32_e32 v74, v81, v76
	v_fma_f32 v74, v10, v74, v76
	v_mov_b32_dpp v71, v71 quad_perm:[1,0,3,2] row_mask:0xf bank_mask:0xf bound_ctrl:1
	v_fmac_f32_e32 v71, v78, v78
	v_cvt_pk_bf16_f32 v74, v74, s0
	v_lshlrev_b32_e32 v74, 16, v74
	v_add_f32_dpp v71, v71, v71 quad_perm:[2,3,0,1] row_mask:0xf bank_mask:0xf bound_ctrl:1
	s_nop 1
	v_add_f32_dpp v71, v71, v71 row_ror:4 row_mask:0xf bank_mask:0xf bound_ctrl:1
	s_nop 1
	v_add_f32_dpp v71, v71, v71 row_ror:8 row_mask:0xf bank_mask:0xf bound_ctrl:1
	s_nop 0
	v_readlane_b32 s7, v71, 0
	v_readlane_b32 s8, v71, 16
	v_readlane_b32 s6, v71, 32
	v_readlane_b32 s9, v71, 48
	v_add_f32_e32 v71, -1.0, v77
	v_fma_f32 v71, v13, v71, 1.0
	v_mul_f32_e32 v71, v79, v71
	v_cvt_pk_bf16_f32 v71, v71, s0
	v_lshlrev_b32_e32 v71, 16, v71
	v_mul_f32_e32 v79, v74, v71
	v_mul_f32_e32 v81, v11, v79
	s_nop 1
	v_mov_b32_dpp v81, v81 quad_perm:[1,0,3,2] row_mask:0xf bank_mask:0xf bound_ctrl:1
	v_fmac_f32_e32 v81, v11, v79
	s_nop 1
	v_add_f32_dpp v79, v81, v81 quad_perm:[2,3,0,1] row_mask:0xf bank_mask:0xf bound_ctrl:1
	s_nop 1
	v_add_f32_dpp v79, v79, v79 row_ror:4 row_mask:0xf bank_mask:0xf bound_ctrl:1
	s_nop 1
	v_add_f32_dpp v79, v79, v79 row_ror:8 row_mask:0xf bank_mask:0xf bound_ctrl:1
	s_nop 0
	v_readlane_b32 s0, v79, 0
	v_readlane_b32 s15, v79, 16
	v_readlane_b32 s1, v79, 32
	v_readlane_b32 s17, v79, 48
	v_cvt_pk_bf16_f32 v79, v80, s0
	v_add_co_u32_e32 v80, vcc, 0x33600000, v6
	s_nop 1
	v_addc_co_u32_e32 v81, vcc, 0, v7, vcc
	global_store_short v[80:81], v79, off offset:1536
	s_and_saveexec_b64 s[4:5], s[38:39]
	s_cbranch_execz .LBB0_307
	s_ashr_i32 s81, s80, 31
	s_lshl_b64 s[30:31], s[80:81], 6
	s_add_u32 s30, s2, s30
	v_mov_b32_e32 v80, s15
	v_mov_b32_e32 v81, s17
	s_addc_u32 s31, s14, s31
	v_pk_add_f32 v[80:81], s[0:1], v[80:81]
	s_nop 0
	v_add_f32_e32 v79, v80, v81
	v_mov_b64_e32 v[80:81], s[30:31]
	global_store_dword v[80:81], v79, off
; __device__ __forceinline__ float bf2f(bf16 b) { return __uint_as_float((unsigned)b << 16); }
; __device__ __forceinline__ bf16 f2bf(float f) { return (bf16)(pk_bf16(f, 0.f) & 0xffffu); }
; __device__ __forceinline__ float fexp(float x) { return __builtin_amdgcn_exp2f(x * 1.4426950408889634f); }
; __device__ __forceinline__ float flog(float x) { return __builtin_amdgcn_logf(x) * 0.6931471805599453f; }
; __device__ __forceinline__ float fsigmoid(float x) { return __builtin_amdgcn_rcpf(1.0f + fexp(-x)); }
; __device__ __forceinline__ float wsum_dpp(float x) { x = red16(x);
;     return (__builtin_bit_cast(float, __builtin_amdgcn_readlane(__builtin_bit_cast(int, x), 0)) + __builtin_bit_cast(float, __builtin_amdgcn_readlane(__builtin_bit_cast(int, x), 16)))
;          + (__builtin_bit_cast(float, __builtin_amdgcn_readlane(__builtin_bit_cast(int, x), 32)) + __builtin_bit_cast(float, __builtin_amdgcn_readlane(__builtin_bit_cast(int, x), 48))); }
; __device__ __forceinline__ void pc_phase(LAS unsigned char* lds, const bf16* Pp_, const bf16* LO, const float* mu, const float* w0, const float* a0, const float* k_k, const float* k_a, const float* r_k, ...
;     ...
;         for (int t = 0; t < 16; ++t) {
;             const float r0 = bf2f(sr_[t + 1]), k0 = bf2f(sk_[t + 1]), v0 = bf2f(sv_[t + 1]);
;             const float r = r0 + (r1 - r0) * mu_r, k = k0 + (k1 - k0) * mu_k, v = v0 + (v1 - v0) * mu_v; r1 = r0; k1 = k0; v1 = v0;
;             const float z = -(w0c + bf2f(slw[t])); const float sp = fmaxf(z, 0.f) + flog(1.0f + fexp(-fabsf(z))); const float w = -sp - 0.5f;
;             const float dec = fexp(-fexp(w)); const float a = fsigmoid(a0c + bf2f(sla[t]));
;             float kk = k * kkc; const float n2 = wsum_dpp(kk * kk); kk = kk / fmaxf(sqrtf(n2), 1e-12f);
;             const float kp = bf2f(f2bf(k * (1.0f + (a - 1.0f) * kac))), bb = bf2f(f2bf(kk * a)), rr = bf2f(f2bf(r)); kk = bf2f(f2bf(kk));
;             const float coef = wsum_dpp(rr * kp * rkc);
;             SV[(ib + t) * 64 + lane] = f2bf(v);
;             if (lane == 0) COEF[(size_t)(m0 + t) * 16 + h] = coef;
;             const float Pp = P; P *= dec; const float inv = 1.0f / P;
;             XKK[t * 72 + lane] = f2bf(kk * Pp); XR[t * 72 + lane] = f2bf(rr * P); XK[t * 72 + lane] = f2bf(kp * inv); XB[t * 72 + lane] = f2bf(bb * inv); }
.LBB0_307:
	s_or_b64 exec, exec, s[4:5]
	v_lshlrev_b32_e32 v70, 16, v70
	v_add_f32_e32 v70, v8, v70
	v_mul_f32_e64 v79, |v70|, s19
	v_exp_f32_e32 v79, v79
	v_mov_b32_e32 v80, s8
	v_mov_b32_e32 v81, s9
	v_add_f32_e32 v80, s7, v80
	v_add_f32_e32 v79, 1.0, v79
	v_log_f32_e32 v79, v79
	v_add_f32_e32 v81, s6, v81
	v_max_f32_e64 v70, -v70, 0
	v_add_f32_e32 v80, v80, v81
	v_fmac_f32_e32 v70, 0x3f317218, v79
	v_mul_f32_e32 v79, 0x4f800000, v80
	v_cmp_gt_f32_e32 vcc, s33, v80
	v_sub_f32_e32 v70, -0.5, v70
	v_mul_f32_e32 v70, 0x3fb8aa3b, v70
	v_cndmask_b32_e32 v79, v80, v79, vcc
	v_sqrt_f32_e32 v80, v79
	v_exp_f32_e32 v70, v70
	v_lshlrev_b32_e32 v69, 16, v69
	v_add_f32_e32 v69, v15, v69
	v_add_u32_e32 v81, -1, v80
	v_fma_f32 v82, -v81, v80, v79
	v_cmp_ge_f32_e64 s[56:57], 0, v82
	v_add_u32_e32 v82, 1, v80
	v_mul_f32_e32 v70, 0xbfb8aa3b, v70
	v_cndmask_b32_e64 v81, v80, v81, s[56:57]
	v_fma_f32 v80, -v82, v80, v79
	v_cmp_lt_f32_e64 s[56:57], 0, v80
	v_exp_f32_e32 v70, v70
	v_mul_f32_e32 v69, 0xbfb8aa3b, v69
	v_cndmask_b32_e64 v80, v81, v82, s[56:57]
	v_mul_f32_e32 v81, 0x37800000, v80
	v_cndmask_b32_e32 v80, v80, v81, vcc
	v_cmp_class_f32_e32 vcc, v79, v219
	v_mul_f32_e32 v70, v75, v70
	v_mul_f32_e32 v74, v70, v74
	v_cndmask_b32_e32 v79, v80, v79, vcc
	v_max_f32_e32 v79, 0x2b8cbccc, v79
	v_div_scale_f32 v80, s[0:1], v79, v79, v78
	v_rcp_f32_e32 v81, v80
	v_exp_f32_e32 v69, v69
	v_lshlrev_b32_e32 v67, 16, v67
	v_fma_f32 v82, -v80, v81, 1.0
	v_fmac_f32_e32 v81, v82, v81
	v_div_scale_f32 v82, vcc, v78, v79, v78
	v_mul_f32_e32 v83, v82, v81
	v_fma_f32 v84, -v80, v83, v82
	v_fmac_f32_e32 v83, v84, v81
	v_fma_f32 v80, -v80, v83, v82
	v_div_fmas_f32 v80, v80, v81, v83
	v_div_fixup_f32 v78, v80, v79, v78
	v_mul_f32_e32 v77, v77, v78
	v_cvt_pk_bf16_f32 v77, v77, s0
	v_div_scale_f32 v79, s[0:1], v70, v70, 1.0
	v_rcp_f32_e32 v80, v79
	v_lshlrev_b32_e32 v77, 16, v77
	v_cvt_pk_bf16_f32 v78, v78, s0
	v_cvt_pk_bf16_f32 v74, v74, s0
	v_fma_f32 v81, -v79, v80, 1.0
	v_fmac_f32_e32 v80, v81, v80
	v_div_scale_f32 v81, vcc, 1.0, v70, 1.0
	v_mul_f32_e32 v82, v81, v80
	v_fma_f32 v83, -v79, v82, v81
	v_fmac_f32_e32 v82, v83, v80
	v_fma_f32 v79, -v79, v82, v81
	v_div_fmas_f32 v79, v79, v80, v82
	v_div_fixup_f32 v79, v79, v70, 1.0
	v_mul_f32_e32 v71, v79, v71
	v_cvt_pk_bf16_f32 v71, v71, s0
	ds_write_b16 v27, v71 offset:6336
	v_mul_f32_e32 v71, v79, v77
	v_cvt_pk_bf16_f32 v71, v71, s0
	ds_write_b16 v27, v71 offset:8640
	v_lshlrev_b32_e32 v71, 16, v66
	v_lshlrev_b32_e32 v66, 16, v68
	v_sub_f32_e32 v68, v76, v71
	v_lshlrev_b32_e32 v78, 16, v78
	ds_write_b16 v27, v74 offset:4032
	v_fma_f32 v74, v10, v68, v71
	v_sub_f32_e32 v68, v73, v67
	v_mul_f32_e32 v75, v75, v78
	v_fma_f32 v68, v9, v68, v67
	v_cvt_pk_bf16_f32 v75, v75, s0
	v_sub_f32_e32 v72, v72, v66
	v_add_f32_e32 v69, 1.0, v69
	v_mul_f32_e32 v73, v14, v68
	ds_write_b16 v27, v75 offset:1728
	v_fma_f32 v75, v12, v72, v66
	v_rcp_f32_e32 v72, v69
	v_mul_f32_e32 v69, v73, v73
	s_nop 1
	v_mov_b32_dpp v69, v69 quad_perm:[1,0,3,2] row_mask:0xf bank_mask:0xf bound_ctrl:1
	v_fmac_f32_e32 v69, v73, v73
	s_nop 1
	v_add_f32_dpp v69, v69, v69 quad_perm:[2,3,0,1] row_mask:0xf bank_mask:0xf bound_ctrl:1
	s_nop 1
	v_add_f32_dpp v69, v69, v69 row_ror:4 row_mask:0xf bank_mask:0xf bound_ctrl:1
	s_nop 1
	v_add_f32_dpp v69, v69, v69 row_ror:8 row_mask:0xf bank_mask:0xf bound_ctrl:1
	s_nop 0
	v_readlane_b32 s7, v69, 0
	v_readlane_b32 s8, v69, 16
	v_readlane_b32 s6, v69, 32
	v_readlane_b32 s9, v69, 48
	v_add_f32_e32 v69, -1.0, v72
	v_fma_f32 v69, v13, v69, 1.0
	v_mul_f32_e32 v68, v68, v69
	v_cvt_pk_bf16_f32 v68, v68, s0
	v_cvt_pk_bf16_f32 v69, v74, s0
	v_lshlrev_b32_e32 v68, 16, v68
	v_lshlrev_b32_e32 v69, 16, v69
	v_mul_f32_e32 v74, v69, v68
	v_mul_f32_e32 v76, v11, v74
	s_nop 1
	v_mov_b32_dpp v76, v76 quad_perm:[1,0,3,2] row_mask:0xf bank_mask:0xf bound_ctrl:1
	v_fmac_f32_e32 v76, v11, v74
	s_nop 1
	v_add_f32_dpp v74, v76, v76 quad_perm:[2,3,0,1] row_mask:0xf bank_mask:0xf bound_ctrl:1
	s_nop 1
	v_add_f32_dpp v74, v74, v74 row_ror:4 row_mask:0xf bank_mask:0xf bound_ctrl:1
	s_nop 1
	v_add_f32_dpp v74, v74, v74 row_ror:8 row_mask:0xf bank_mask:0xf bound_ctrl:1
	s_nop 0
	v_readlane_b32 s0, v74, 0
	v_readlane_b32 s15, v74, 16
	v_readlane_b32 s1, v74, 32
	v_readlane_b32 s17, v74, 48
	v_add_co_u32_e32 v74, vcc, 0x33600000, v6
	v_cvt_pk_bf16_f32 v76, v75, s0
	s_nop 0
	v_addc_co_u32_e32 v75, vcc, 0, v7, vcc
	global_store_short v[74:75], v76, off offset:1664
	s_and_saveexec_b64 s[4:5], s[38:39]
	s_cbranch_execz .LBB0_309
	s_mov_b32 s34, s79
	s_ashr_i32 s79, s78, 31
	s_lshl_b64 s[30:31], s[78:79], 6
	s_add_u32 s30, s2, s30
	v_mov_b32_e32 v74, s15
	v_mov_b32_e32 v75, s17
	s_addc_u32 s31, s14, s31
	v_pk_add_f32 v[74:75], s[0:1], v[74:75]
	s_mov_b32 s79, s34
	v_add_f32_e32 v76, v74, v75
	v_mov_b64_e32 v[74:75], s[30:31]
	global_store_dword v[74:75], v76, off
; __device__ __forceinline__ float bf2f(bf16 b) { return __uint_as_float((unsigned)b << 16); }
; __device__ __forceinline__ bf16 f2bf(float f) { return (bf16)(pk_bf16(f, 0.f) & 0xffffu); }
; __device__ __forceinline__ float fexp(float x) { return __builtin_amdgcn_exp2f(x * 1.4426950408889634f); }
; __device__ __forceinline__ float flog(float x) { return __builtin_amdgcn_logf(x) * 0.6931471805599453f; }
; __device__ __forceinline__ float fsigmoid(float x) { return __builtin_amdgcn_rcpf(1.0f + fexp(-x)); }
; __device__ __forceinline__ float wsum_dpp(float x) { x = red16(x);
;     return (__builtin_bit_cast(float, __builtin_amdgcn_readlane(__builtin_bit_cast(int, x), 0)) + __builtin_bit_cast(float, __builtin_amdgcn_readlane(__builtin_bit_cast(int, x), 16)))
;          + (__builtin_bit_cast(float, __builtin_amdgcn_readlane(__builtin_bit_cast(int, x), 32)) + __builtin_bit_cast(float, __builtin_amdgcn_readlane(__builtin_bit_cast(int, x), 48))); }
; __device__ __forceinline__ void pc_phase(LAS unsigned char* lds, const bf16* Pp_, const bf16* LO, const float* mu, const float* w0, const float* a0, const float* k_k, const float* k_a, const float* r_k, ...
;     ...
;         for (int t = 0; t < 16; ++t) {
;             const float r0 = bf2f(sr_[t + 1]), k0 = bf2f(sk_[t + 1]), v0 = bf2f(sv_[t + 1]);
;             const float r = r0 + (r1 - r0) * mu_r, k = k0 + (k1 - k0) * mu_k, v = v0 + (v1 - v0) * mu_v; r1 = r0; k1 = k0; v1 = v0;
;             const float z = -(w0c + bf2f(slw[t])); const float sp = fmaxf(z, 0.f) + flog(1.0f + fexp(-fabsf(z))); const float w = -sp - 0.5f;
;             const float dec = fexp(-fexp(w)); const float a = fsigmoid(a0c + bf2f(sla[t]));
;             float kk = k * kkc; const float n2 = wsum_dpp(kk * kk); kk = kk / fmaxf(sqrtf(n2), 1e-12f);
;             const float kp = bf2f(f2bf(k * (1.0f + (a - 1.0f) * kac))), bb = bf2f(f2bf(kk * a)), rr = bf2f(f2bf(r)); kk = bf2f(f2bf(kk));
;             const float coef = wsum_dpp(rr * kp * rkc);
;             SV[(ib + t) * 64 + lane] = f2bf(v);
;             if (lane == 0) COEF[(size_t)(m0 + t) * 16 + h] = coef;
;             const float Pp = P; P *= dec; const float inv = 1.0f / P;
;             XKK[t * 72 + lane] = f2bf(kk * Pp); XR[t * 72 + lane] = f2bf(rr * P); XK[t * 72 + lane] = f2bf(kp * inv); XB[t * 72 + lane] = f2bf(bb * inv); }
.LBB0_309:
	s_or_b64 exec, exec, s[4:5]
	v_lshlrev_b32_e32 v65, 16, v65
	v_add_f32_e32 v65, v8, v65
	v_mul_f32_e64 v74, |v65|, s19
	v_exp_f32_e32 v74, v74
	v_mov_b32_e32 v75, s8
	v_mov_b32_e32 v76, s9
	v_add_f32_e32 v75, s7, v75
	v_add_f32_e32 v74, 1.0, v74
	v_log_f32_e32 v74, v74
	v_add_f32_e32 v76, s6, v76
	v_max_f32_e64 v65, -v65, 0
	v_add_f32_e32 v75, v75, v76
	v_fmac_f32_e32 v65, 0x3f317218, v74
	v_mul_f32_e32 v74, 0x4f800000, v75
	v_cmp_gt_f32_e32 vcc, s33, v75
	v_sub_f32_e32 v65, -0.5, v65
	v_mul_f32_e32 v65, 0x3fb8aa3b, v65
	v_cndmask_b32_e32 v74, v75, v74, vcc
	v_sqrt_f32_e32 v75, v74
	v_exp_f32_e32 v65, v65
	v_lshlrev_b32_e32 v61, 16, v61
	v_add_f32_e32 v61, v15, v61
	v_add_u32_e32 v76, -1, v75
	v_fma_f32 v77, -v76, v75, v74
	v_cmp_ge_f32_e64 s[56:57], 0, v77
	v_add_u32_e32 v77, 1, v75
	v_mul_f32_e32 v65, 0xbfb8aa3b, v65
	v_cndmask_b32_e64 v76, v75, v76, s[56:57]
	v_fma_f32 v75, -v77, v75, v74
	v_cmp_lt_f32_e64 s[56:57], 0, v75
	v_exp_f32_e32 v65, v65
	v_mul_f32_e32 v61, 0xbfb8aa3b, v61
	v_cndmask_b32_e64 v75, v76, v77, s[56:57]
	v_mul_f32_e32 v76, 0x37800000, v75
	v_cndmask_b32_e32 v75, v75, v76, vcc
	v_cmp_class_f32_e32 vcc, v74, v219
	v_mul_f32_e32 v65, v70, v65
	v_exp_f32_e32 v61, v61
	v_cndmask_b32_e32 v74, v75, v74, vcc
	v_max_f32_e32 v74, 0x2b8cbccc, v74
	v_div_scale_f32 v75, s[0:1], v74, v74, v73
	v_rcp_f32_e32 v76, v75
	v_mul_f32_e32 v69, v65, v69
	v_lshlrev_b32_e32 v63, 16, v63
	v_sub_f32_e32 v67, v67, v63
	v_fma_f32 v77, -v75, v76, 1.0
	v_fmac_f32_e32 v76, v77, v76
	v_div_scale_f32 v77, vcc, v73, v74, v73
	v_mul_f32_e32 v78, v77, v76
	v_fma_f32 v79, -v75, v78, v77
	v_fmac_f32_e32 v78, v79, v76
	v_fma_f32 v75, -v75, v78, v77
	v_div_fmas_f32 v75, v75, v76, v78
	v_div_fixup_f32 v73, v75, v74, v73
	v_mul_f32_e32 v72, v72, v73
	v_cvt_pk_bf16_f32 v72, v72, s0
	v_div_scale_f32 v74, s[0:1], v65, v65, 1.0
	v_rcp_f32_e32 v75, v74
	v_lshlrev_b32_e32 v72, 16, v72
	v_cvt_pk_bf16_f32 v73, v73, s0
	v_lshlrev_b32_e32 v73, 16, v73
	v_fma_f32 v76, -v74, v75, 1.0
	v_fmac_f32_e32 v75, v76, v75
	v_div_scale_f32 v76, vcc, 1.0, v65, 1.0
	v_mul_f32_e32 v77, v76, v75
	v_fma_f32 v78, -v74, v77, v76
	v_fmac_f32_e32 v77, v78, v75
	v_fma_f32 v74, -v74, v77, v76
	v_div_fmas_f32 v74, v74, v75, v77
	v_div_fixup_f32 v74, v74, v65, 1.0
	v_mul_f32_e32 v68, v74, v68
	v_cvt_pk_bf16_f32 v68, v68, s0
	ds_write_b16 v27, v68 offset:6480
	v_mul_f32_e32 v68, v74, v72
	v_cvt_pk_bf16_f32 v69, v69, s0
	v_cvt_pk_bf16_f32 v68, v68, s0
	v_mul_f32_e32 v70, v70, v73
	ds_write_b16 v27, v69 offset:4176
	ds_write_b16 v27, v68 offset:8784
	v_lshlrev_b32_e32 v68, 16, v62
	v_lshlrev_b32_e32 v62, 16, v64
	v_fma_f32 v69, v9, v67, v63
	v_cvt_pk_bf16_f32 v70, v70, s0
	v_sub_f32_e32 v66, v66, v62
	v_add_f32_e32 v61, 1.0, v61
	v_mul_f32_e32 v67, v14, v69
	ds_write_b16 v27, v70 offset:1872
	v_fma_f32 v70, v12, v66, v62
	v_rcp_f32_e32 v66, v61
	v_mul_f32_e32 v61, v67, v67
	v_sub_f32_e32 v64, v71, v68
	v_fma_f32 v64, v10, v64, v68
	v_mov_b32_dpp v61, v61 quad_perm:[1,0,3,2] row_mask:0xf bank_mask:0xf bound_ctrl:1
	v_fmac_f32_e32 v61, v67, v67
	v_cvt_pk_bf16_f32 v64, v64, s0
	v_lshlrev_b32_e32 v64, 16, v64
	v_add_f32_dpp v61, v61, v61 quad_perm:[2,3,0,1] row_mask:0xf bank_mask:0xf bound_ctrl:1
	s_nop 1
	v_add_f32_dpp v61, v61, v61 row_ror:4 row_mask:0xf bank_mask:0xf bound_ctrl:1
	s_nop 1
	v_add_f32_dpp v61, v61, v61 row_ror:8 row_mask:0xf bank_mask:0xf bound_ctrl:1
	s_nop 0
	v_readlane_b32 s7, v61, 0
	v_readlane_b32 s8, v61, 16
	v_readlane_b32 s6, v61, 32
	v_readlane_b32 s9, v61, 48
	v_add_f32_e32 v61, -1.0, v66
	v_fma_f32 v61, v13, v61, 1.0
	v_mul_f32_e32 v61, v69, v61
	v_cvt_pk_bf16_f32 v61, v61, s0
	v_lshlrev_b32_e32 v61, 16, v61
	v_mul_f32_e32 v69, v64, v61
	v_mul_f32_e32 v71, v11, v69
	s_nop 1
	v_mov_b32_dpp v71, v71 quad_perm:[1,0,3,2] row_mask:0xf bank_mask:0xf bound_ctrl:1
	v_fmac_f32_e32 v71, v11, v69
	s_nop 1
	v_add_f32_dpp v69, v71, v71 quad_perm:[2,3,0,1] row_mask:0xf bank_mask:0xf bound_ctrl:1
	s_nop 1
	v_add_f32_dpp v69, v69, v69 row_ror:4 row_mask:0xf bank_mask:0xf bound_ctrl:1
	s_nop 1
	v_add_f32_dpp v69, v69, v69 row_ror:8 row_mask:0xf bank_mask:0xf bound_ctrl:1
	s_nop 0
	v_readlane_b32 s0, v69, 0
	v_readlane_b32 s15, v69, 16
	v_readlane_b32 s1, v69, 32
	v_readlane_b32 s17, v69, 48
	v_cvt_pk_bf16_f32 v69, v70, s0
	v_add_co_u32_e32 v70, vcc, 0x33600000, v6
	s_nop 1
	v_addc_co_u32_e32 v71, vcc, 0, v7, vcc
	global_store_short v[70:71], v69, off offset:1792
	s_and_saveexec_b64 s[4:5], s[38:39]
	s_cbranch_execz .LBB0_311
	s_ashr_i32 s77, s76, 31
	s_lshl_b64 s[30:31], s[76:77], 6
	s_add_u32 s30, s2, s30
	v_mov_b32_e32 v70, s15
	v_mov_b32_e32 v71, s17
	s_addc_u32 s31, s14, s31
	v_pk_add_f32 v[70:71], s[0:1], v[70:71]
	v_readlane_b32 s77, v254, 56
	v_add_f32_e32 v69, v70, v71
	v_mov_b64_e32 v[70:71], s[30:31]
	global_store_dword v[70:71], v69, off
; __device__ __forceinline__ float bf2f(bf16 b) { return __uint_as_float((unsigned)b << 16); }
; __device__ __forceinline__ bf16 f2bf(float f) { return (bf16)(pk_bf16(f, 0.f) & 0xffffu); }
; __device__ __forceinline__ float fexp(float x) { return __builtin_amdgcn_exp2f(x * 1.4426950408889634f); }
; __device__ __forceinline__ float flog(float x) { return __builtin_amdgcn_logf(x) * 0.6931471805599453f; }
; __device__ __forceinline__ float fsigmoid(float x) { return __builtin_amdgcn_rcpf(1.0f + fexp(-x)); }
; __device__ __forceinline__ float wsum_dpp(float x) { x = red16(x);
;     return (__builtin_bit_cast(float, __builtin_amdgcn_readlane(__builtin_bit_cast(int, x), 0)) + __builtin_bit_cast(float, __builtin_amdgcn_readlane(__builtin_bit_cast(int, x), 16)))
;          + (__builtin_bit_cast(float, __builtin_amdgcn_readlane(__builtin_bit_cast(int, x), 32)) + __builtin_bit_cast(float, __builtin_amdgcn_readlane(__builtin_bit_cast(int, x), 48))); }
; __device__ __forceinline__ void pc_phase(LAS unsigned char* lds, const bf16* Pp_, const bf16* LO, const float* mu, const float* w0, const float* a0, const float* k_k, const float* k_a, const float* r_k, ...
;     ...
;         for (int t = 0; t < 16; ++t) {
;             const float r0 = bf2f(sr_[t + 1]), k0 = bf2f(sk_[t + 1]), v0 = bf2f(sv_[t + 1]);
;             const float r = r0 + (r1 - r0) * mu_r, k = k0 + (k1 - k0) * mu_k, v = v0 + (v1 - v0) * mu_v; r1 = r0; k1 = k0; v1 = v0;
;             const float z = -(w0c + bf2f(slw[t])); const float sp = fmaxf(z, 0.f) + flog(1.0f + fexp(-fabsf(z))); const float w = -sp - 0.5f;
;             const float dec = fexp(-fexp(w)); const float a = fsigmoid(a0c + bf2f(sla[t]));
;             float kk = k * kkc; const float n2 = wsum_dpp(kk * kk); kk = kk / fmaxf(sqrtf(n2), 1e-12f);
;             const float kp = bf2f(f2bf(k * (1.0f + (a - 1.0f) * kac))), bb = bf2f(f2bf(kk * a)), rr = bf2f(f2bf(r)); kk = bf2f(f2bf(kk));
;             const float coef = wsum_dpp(rr * kp * rkc);
;             SV[(ib + t) * 64 + lane] = f2bf(v);
;             if (lane == 0) COEF[(size_t)(m0 + t) * 16 + h] = coef;
;             const float Pp = P; P *= dec; const float inv = 1.0f / P;
;             XKK[t * 72 + lane] = f2bf(kk * Pp); XR[t * 72 + lane] = f2bf(rr * P); XK[t * 72 + lane] = f2bf(kp * inv); XB[t * 72 + lane] = f2bf(bb * inv); }
.LBB0_311:
	s_or_b64 exec, exec, s[4:5]
	v_lshlrev_b32_e32 v21, 16, v21
	v_add_f32_e32 v21, v8, v21
	v_mul_f32_e64 v69, |v21|, s19
	v_exp_f32_e32 v69, v69
	v_mov_b32_e32 v70, s8
	v_mov_b32_e32 v71, s9
	v_add_f32_e32 v70, s7, v70
	v_add_f32_e32 v69, 1.0, v69
	v_log_f32_e32 v69, v69
	v_add_f32_e32 v71, s6, v71
	v_max_f32_e64 v21, -v21, 0
	v_add_f32_e32 v70, v70, v71
	v_fmac_f32_e32 v21, 0x3f317218, v69
	v_mul_f32_e32 v69, 0x4f800000, v70
	v_cmp_gt_f32_e32 vcc, s33, v70
	v_sub_f32_e32 v21, -0.5, v21
	v_mul_f32_e32 v21, 0x3fb8aa3b, v21
	v_cndmask_b32_e32 v69, v70, v69, vcc
	v_sqrt_f32_e32 v70, v69
	v_exp_f32_e32 v21, v21
	v_lshlrev_b32_e32 v17, 16, v17
	v_add_f32_e32 v15, v15, v17
	v_add_u32_e32 v71, -1, v70
	v_fma_f32 v72, -v71, v70, v69
	v_cmp_ge_f32_e64 s[56:57], 0, v72
	v_add_u32_e32 v72, 1, v70
	v_mul_f32_e32 v21, 0xbfb8aa3b, v21
	v_cndmask_b32_e64 v71, v70, v71, s[56:57]
	v_fma_f32 v70, -v72, v70, v69
	v_cmp_lt_f32_e64 s[56:57], 0, v70
	v_exp_f32_e32 v21, v21
	v_mul_f32_e32 v15, 0xbfb8aa3b, v15
	v_cndmask_b32_e64 v70, v71, v72, s[56:57]
	v_mul_f32_e32 v71, 0x37800000, v70
	v_cndmask_b32_e32 v70, v70, v71, vcc
	v_cmp_class_f32_e32 vcc, v69, v219
	v_mul_f32_e32 v21, v65, v21
	v_lshlrev_b32_e32 v18, 16, v18
	v_cndmask_b32_e32 v69, v70, v69, vcc
	v_max_f32_e32 v69, 0x2b8cbccc, v69
	v_div_scale_f32 v70, s[0:1], v69, v69, v67
	v_rcp_f32_e32 v71, v70
	v_exp_f32_e32 v15, v15
	v_lshlrev_b32_e32 v19, 16, v19
	v_lshlrev_b32_e32 v20, 16, v20
	v_fma_f32 v72, -v70, v71, 1.0
	v_fmac_f32_e32 v71, v72, v71
	v_div_scale_f32 v72, vcc, v67, v69, v67
	v_mul_f32_e32 v73, v72, v71
	v_fma_f32 v74, -v70, v73, v72
	v_fmac_f32_e32 v73, v74, v71
	v_fma_f32 v70, -v70, v73, v72
	v_div_fmas_f32 v70, v70, v71, v73
	v_div_fixup_f32 v67, v70, v69, v67
	v_mul_f32_e32 v66, v66, v67
	v_cvt_pk_bf16_f32 v66, v66, s0
	v_div_scale_f32 v69, s[0:1], v21, v21, 1.0
	v_rcp_f32_e32 v70, v69
	v_lshlrev_b32_e32 v66, 16, v66
	v_cvt_pk_bf16_f32 v67, v67, s0
	v_lshlrev_b32_e32 v67, 16, v67
	v_fma_f32 v71, -v69, v70, 1.0
	v_fmac_f32_e32 v70, v71, v70
	v_div_scale_f32 v71, vcc, 1.0, v21, 1.0
	v_mul_f32_e32 v72, v71, v70
	v_fma_f32 v73, -v69, v72, v71
	v_fmac_f32_e32 v72, v73, v70
	v_fma_f32 v69, -v69, v72, v71
	v_div_fmas_f32 v69, v69, v70, v72
	v_div_fixup_f32 v69, v69, v21, 1.0
	v_mul_f32_e32 v61, v69, v61
	v_cvt_pk_bf16_f32 v61, v61, s0
	ds_write_b16 v27, v61 offset:6624
	v_mul_f32_e32 v61, v69, v66
	v_cvt_pk_bf16_f32 v61, v61, s0
	ds_write_b16 v27, v61 offset:8928
	v_sub_f32_e32 v61, v68, v18
	v_fmac_f32_e32 v18, v10, v61
	v_sub_f32_e32 v10, v63, v19
	v_fmac_f32_e32 v19, v9, v10
	v_sub_f32_e32 v9, v62, v20
	v_fmac_f32_e32 v20, v12, v9
	v_add_f32_e32 v9, 1.0, v15
	v_mul_f32_e32 v14, v14, v19
	v_rcp_f32_e32 v12, v9
	v_mul_f32_e32 v9, v14, v14
	v_cvt_pk_bf16_f32 v10, v18, s0
	v_lshlrev_b32_e32 v10, 16, v10
	v_mov_b32_dpp v9, v9 quad_perm:[1,0,3,2] row_mask:0xf bank_mask:0xf bound_ctrl:1
	v_fmac_f32_e32 v9, v14, v14
	v_mul_f32_e32 v65, v65, v67
	v_mul_f32_e32 v64, v21, v64
	v_add_f32_dpp v9, v9, v9 quad_perm:[2,3,0,1] row_mask:0xf bank_mask:0xf bound_ctrl:1
	v_cvt_pk_bf16_f32 v65, v65, s0
	v_cvt_pk_bf16_f32 v64, v64, s0
	v_add_f32_dpp v9, v9, v9 row_ror:4 row_mask:0xf bank_mask:0xf bound_ctrl:1
	v_add_co_u32_e32 v6, vcc, 0x33600000, v6
	s_nop 0
	v_add_f32_dpp v9, v9, v9 row_ror:8 row_mask:0xf bank_mask:0xf bound_ctrl:1
	v_addc_co_u32_e32 v7, vcc, 0, v7, vcc
	v_readlane_b32 s7, v9, 0
	v_readlane_b32 s9, v9, 16
	v_readlane_b32 s6, v9, 32
	v_readlane_b32 s8, v9, 48
	v_add_f32_e32 v9, -1.0, v12
	v_fma_f32 v9, v13, v9, 1.0
	v_mul_f32_e32 v9, v19, v9
	v_cvt_pk_bf16_f32 v9, v9, s0
	v_lshlrev_b32_e32 v9, 16, v9
	v_mul_f32_e32 v13, v10, v9
	v_mul_f32_e32 v15, v11, v13
	ds_write_b16 v27, v65 offset:2016
	ds_write_b16 v27, v64 offset:4320
	v_mov_b32_dpp v15, v15 quad_perm:[1,0,3,2] row_mask:0xf bank_mask:0xf bound_ctrl:1
	v_fmac_f32_e32 v15, v11, v13
	s_nop 1
	v_add_f32_dpp v11, v15, v15 quad_perm:[2,3,0,1] row_mask:0xf bank_mask:0xf bound_ctrl:1
	s_nop 1
	v_add_f32_dpp v11, v11, v11 row_ror:4 row_mask:0xf bank_mask:0xf bound_ctrl:1
	s_nop 1
	v_add_f32_dpp v11, v11, v11 row_ror:8 row_mask:0xf bank_mask:0xf bound_ctrl:1
	s_nop 0
	v_readlane_b32 s0, v11, 0
	v_readlane_b32 s15, v11, 16
	v_readlane_b32 s1, v11, 32
	v_readlane_b32 s17, v11, 48
	v_cvt_pk_bf16_f32 v11, v20, s0
	global_store_short v[6:7], v11, off offset:1920
	s_and_saveexec_b64 s[4:5], s[38:39]
	s_cbranch_execz .LBB0_280
	s_mov_b32 s34, s75
	s_ashr_i32 s75, s74, 31
	s_lshl_b64 s[30:31], s[74:75], 6
	s_add_u32 s30, s2, s30
	v_mov_b32_e32 v6, s15
	v_mov_b32_e32 v7, s17
	s_addc_u32 s31, s14, s31
	v_pk_add_f32 v[6:7], s[0:1], v[6:7]
	s_mov_b32 s75, s34
	v_add_f32_e32 v11, v6, v7
	v_mov_b64_e32 v[6:7], s[30:31]
	global_store_dword v[6:7], v11, off
	s_branch .LBB0_280

; __device__ __forceinline__ void unpack8(const u32x4 w, float (&f)[8]) { f[0] = bflo(w.x); f[1] = bfhi(w.x); f[2] = bflo(w.y); f[3] = bfhi(w.y); f[4] = bflo(w.z); f[5] = bfhi(w.z); f[6] = bflo(w.w); f[7] = bfhi(w.w); }
; __device__ __forceinline__ u32x4 pack8(const float (&f)[8]) { u32x4 w; w.x = pk_bf16(f[0], f[1]); w.y = pk_bf16(f[2], f[3]); w.z = pk_bf16(f[4], f[5]); w.w = pk_bf16(f[6], f[7]); return w; }
; __device__ __forceinline__ float sum8(float x) { x += __shfl_xor(x, 1); x += __shfl_xor(x, 2); x += __shfl_xor(x, 4); return x; }
; __device__ __forceinline__ void e6_phase(const bf16* LO, const float* COEF, const bf16* SV, const float* ln_w, const float* ln_b, bf16* mix, int gw, int ngw, int lane) {
;     const int hf = gw & 1, c = hf * 512 + lane * 8, h = c >> 6, cl = (lane & 7) * 8;
;     float lw[8], lb[8]; ld8f(ln_w + c, lw); ld8f(ln_b + c, lb);
;     for (int m = gw >> 1; m < T; m += ngw >> 1) { const int t = m & (SEQ - 1), b = m >> 12;
;         bf16* yp = mix + (size_t)m * D + 1024 + c;
;         const size_t idx = (size_t)(b * 16 + h) * SEQ + t;
;         float y[8], v[8], g[8];
;         unpack8(*(const u32x4*)yp, y); unpack8(*(const u32x4*)(SV + idx * 64 + cl), v); unpack8(*(const u32x4*)(LO + (size_t)m * LORA_N + 2048 + c), g);
;         const float bs = COEF[(size_t)m * 16 + h];
;         float s = 0.f;
; #pragma unroll
;         for (int e = 0; e < 8; ++e) s += y[e];
;         s = sum8(s);
;         const float mean = s * (1.0f / 64.0f); float q = 0.f;
; #pragma unroll
;         for (int e = 0; e < 8; ++e) { y[e] -= mean; q += y[e] * y[e]; }
;         q = sum8(q); const float rs = rsqrtf(q * (1.0f / 64.0f) + GN_EPS);
;         float o[8];
; #pragma unroll
;         for (int e = 0; e < 8; ++e) o[e] = (y[e] * rs * lw[e] + lb[e] + bs * v[e]) * g[e];
;         *(u32x4*)yp = pack8(o);
;     }
.LBB0_315:
	s_andn2_b64 vcc, exec, s[0:1]
	s_cbranch_vccnz .LBB0_320
	s_cmp_eq_u32 s77, 5
	s_cbranch_scc0 .LBB0_320
	s_add_i32 s0, s92, 0
	s_waitcnt vmcnt(0)
	v_mov_b32_e32 v2, s0
	s_waitcnt lgkmcnt(0)
	ds_read_b64 v[0:1], v2 offset:112
	s_ashr_i32 s34, s10, 1
	s_cmpk_gt_i32 s34, 0x3fff
	s_waitcnt lgkmcnt(0)
	v_readfirstlane_b32 s0, v1
	v_readfirstlane_b32 s1, v0
	ds_read_b64 v[0:1], v2 offset:120
	s_waitcnt lgkmcnt(0)
	v_readfirstlane_b32 s2, v1
	v_readfirstlane_b32 s4, v0
	s_cbranch_scc1 .LBB0_320
	s_lshl_b32 s5, s52, 9
	s_and_b32 s5, s5, 0x200
	v_lshlrev_b32_e32 v16, 3, v185
	s_lshl_b32 s6, s96, 12
	v_or_b32_e32 v17, s5, v16
	s_add_u32 s4, s4, s6
	s_addc_u32 s5, s2, 0
	v_lshlrev_b32_e32 v96, 2, v17
	v_lshl_add_u64 v[4:5], s[4:5], 0, v[96:97]
	s_add_u32 s4, s1, s6
	s_addc_u32 s5, s0, 0
	v_lshl_add_u64 v[12:13], s[4:5], 0, v[96:97]
	global_load_dwordx4 v[0:3], v[4:5], off offset:16
	s_nop 0
	global_load_dwordx4 v[4:7], v[4:5], off
	s_nop 0
	global_load_dwordx4 v[8:11], v[12:13], off offset:16
	s_nop 0
	global_load_dwordx4 v[12:15], v[12:13], off
	v_and_b32_e32 v19, 64, v220
	v_xor_b32_e32 v18, 1, v220
	v_add_u32_e32 v19, 64, v19
	v_cmp_lt_i32_e32 vcc, v18, v19
	s_ashr_i32 s35, s34, 31
	s_lshl_b32 s0, s34, 6
	v_cndmask_b32_e32 v18, v220, v18, vcc
	v_lshlrev_b32_e32 v28, 2, v18
	v_xor_b32_e32 v18, 2, v220
	v_cmp_lt_i32_e32 vcc, v18, v19
	s_lshl_b64 s[4:5], s[34:35], 6
	s_add_u32 s4, s88, s4
	v_cndmask_b32_e32 v18, v220, v18, vcc
	v_lshlrev_b32_e32 v29, 2, v18
	v_xor_b32_e32 v18, 4, v220
	v_cmp_lt_i32_e32 vcc, v18, v19
	s_addc_u32 s5, s89, s5
	s_mul_i32 s2, s34, 0x1800
	v_cndmask_b32_e32 v18, v220, v18, vcc
	v_lshlrev_b32_e32 v30, 2, v18
	v_lshrrev_b32_e32 v18, 4, v17
	v_and_b32_e32 v96, 60, v18
	v_lshl_add_u64 v[18:19], s[4:5], 0, v[96:97]
	s_mov_b64 s[4:5], 0x31e00000
	v_lshl_add_u64 v[20:21], v[18:19], 0, s[4:5]
	s_mul_hi_i32 s1, s34, 0x1800
	s_add_u32 s4, s88, s2
	v_lshlrev_b32_e32 v96, 1, v17
	s_addc_u32 s5, s89, s1
	v_lshl_add_u64 v[18:19], s[4:5], 0, v[96:97]
	s_mov_b64 s[4:5], 0x20a01000
	v_lshl_add_u64 v[22:23], v[18:19], 0, s[4:5]
	s_lshl_b64 s[4:5], s[34:35], 12
	v_readlane_b32 s6, v254, 57
	v_readlane_b32 s7, v254, 58
	s_add_u32 s4, s6, s4
	s_addc_u32 s5, s7, s5
	v_lshl_add_u64 v[18:19], s[4:5], 0, v[96:97]
	s_mov_b64 s[4:5], 0x800
	v_and_b32_e32 v16, 56, v16
	v_lshl_add_u64 v[24:25], v[18:19], 0, s[4:5]
	v_readlane_b32 s4, v254, 3
	v_readlane_b32 s6, v254, 5
	v_readlane_b32 s8, v254, 7
	v_lshrrev_b32_e32 v27, 6, v17
	v_lshlrev_b32_e32 v96, 1, v16
	v_readlane_b32 s5, v254, 4
	v_readlane_b32 s7, v254, 6
	v_readlane_b32 s9, v254, 8
.LBB0_319:
	global_load_dwordx4 v[32:35], v[24:25], off
	global_load_dwordx4 v[36:39], v[22:23], off
	s_ashr_i32 s1, s34, 8
	v_and_or_b32 v16, s1, -16, v27
	v_ashrrev_i32_e32 v17, 31, v16
	s_and_b32 s2, s0, 0x3ffc0
	v_lshlrev_b64 v[16:17], 19, v[16:17]
	s_lshl_b32 s28, s2, 1
	v_lshl_add_u64 v[16:17], s[80:81], 0, v[16:17]
	v_lshl_add_u64 v[16:17], v[16:17], 0, s[28:29]
	v_lshl_add_u64 v[16:17], v[16:17], 0, v[96:97]
	global_load_dwordx4 v[16:19], v[16:17], off
	s_nop 0
	global_load_dword v26, v[20:21], off
	s_add_i32 s34, s34, s93
	s_add_i32 s0, s0, s41
	v_lshl_add_u64 v[20:21], v[20:21], 0, s[6:7]
	v_lshl_add_u64 v[22:23], v[22:23], 0, s[4:5]
	s_cmpk_gt_i32 s34, 0x3fff
	s_waitcnt vmcnt(0) lgkmcnt(0)
	v_lshlrev_b32_e32 v44, 16, v32
	v_and_b32_e32 v45, 0xffff0000, v32
	v_add_f32_e32 v31, 0, v44
	v_lshlrev_b32_e32 v42, 16, v34
	v_and_b32_e32 v43, 0xffff0000, v34
	v_lshlrev_b32_e32 v34, 16, v33
	v_add_f32_e32 v31, v31, v45
	v_lshlrev_b32_e32 v40, 16, v35
	v_and_b32_e32 v41, 0xffff0000, v35
	v_and_b32_e32 v35, 0xffff0000, v33
	v_add_f32_e32 v31, v31, v34
	v_add_f32_e32 v31, v31, v35
	v_add_f32_e32 v31, v31, v42
	v_add_f32_e32 v31, v31, v43
	v_add_f32_e32 v31, v31, v40
	v_add_f32_e32 v31, v31, v41
	ds_bpermute_b32 v32, v28, v31
	s_waitcnt lgkmcnt(0)
	v_add_f32_e32 v31, v31, v32
	ds_bpermute_b32 v32, v29, v31
	s_waitcnt lgkmcnt(0)
	v_add_f32_e32 v31, v31, v32
	ds_bpermute_b32 v33, v30, v31
	v_lshlrev_b32_e32 v32, 16, v39
	s_waitcnt lgkmcnt(0)
	v_add_f32_e32 v31, v31, v33
	v_mul_f32_e32 v46, 0x3c800000, v31
	v_pk_add_f32 v[44:45], v[44:45], v[46:47] op_sel_hi:[1,0] neg_lo:[0,1] neg_hi:[0,1]
	v_pk_add_f32 v[34:35], v[34:35], v[46:47] op_sel_hi:[1,0] neg_lo:[0,1] neg_hi:[0,1]
	v_pk_add_f32 v[42:43], v[42:43], v[46:47] op_sel_hi:[1,0] neg_lo:[0,1] neg_hi:[0,1]
	v_pk_add_f32 v[40:41], v[40:41], v[46:47] op_sel_hi:[1,0] neg_lo:[0,1] neg_hi:[0,1]
	v_pk_mul_f32 v[46:47], v[44:45], v[44:45]
	v_pk_mul_f32 v[48:49], v[34:35], v[34:35]
	v_add_f32_e32 v31, v46, v47
	v_add_f32_e32 v31, v48, v31
	v_pk_mul_f32 v[50:51], v[42:43], v[42:43]
	v_add_f32_e32 v31, v49, v31
	v_add_f32_e32 v31, v50, v31
	v_pk_mul_f32 v[52:53], v[40:41], v[40:41]
	v_add_f32_e32 v31, v51, v31
	v_add_f32_e32 v31, v52, v31
	v_add_f32_e32 v31, v53, v31
	ds_bpermute_b32 v48, v28, v31
	v_and_b32_e32 v33, 0xffff0000, v39
	v_lshlrev_b32_e32 v46, 16, v38
	v_and_b32_e32 v47, 0xffff0000, v38
	v_lshlrev_b32_e32 v38, 16, v37
	s_waitcnt lgkmcnt(0)
	v_add_f32_e32 v31, v31, v48
	ds_bpermute_b32 v50, v29, v31
	v_and_b32_e32 v39, 0xffff0000, v37
	v_lshlrev_b32_e32 v48, 16, v36
	v_and_b32_e32 v49, 0xffff0000, v36
	v_lshlrev_b32_e32 v36, 16, v19
	s_waitcnt lgkmcnt(0)
	v_add_f32_e32 v31, v31, v50
	ds_bpermute_b32 v52, v30, v31
	v_and_b32_e32 v37, 0xffff0000, v19
	v_and_b32_e32 v53, 0xffff0000, v16
	v_lshlrev_b32_e32 v50, 16, v18
	v_and_b32_e32 v51, 0xffff0000, v18
	s_waitcnt lgkmcnt(0)
	v_add_f32_e32 v19, v31, v52
	v_mov_b32_e32 v31, 0x3a27c5ac
	v_fmamk_f32 v19, v19, 0x3c800000, v31
	v_mul_f32_e32 v31, 0x4b800000, v19
	v_cmp_gt_f32_e32 vcc, s12, v19
	v_lshlrev_b32_e32 v52, 16, v16
	v_lshlrev_b32_e32 v18, 16, v17
	v_cndmask_b32_e32 v19, v19, v31, vcc
	v_rsq_f32_e32 v31, v19
	v_and_b32_e32 v19, 0xffff0000, v17
	v_mul_f32_e32 v16, 0x45800000, v31
	v_cndmask_b32_e32 v16, v31, v16, vcc
	v_pk_mul_f32 v[44:45], v[44:45], v[16:17] op_sel_hi:[1,0]
	v_pk_mul_f32 v[34:35], v[34:35], v[16:17] op_sel_hi:[1,0]
	v_pk_mul_f32 v[42:43], v[42:43], v[16:17] op_sel_hi:[1,0]
	v_pk_mul_f32 v[16:17], v[40:41], v[16:17] op_sel_hi:[1,0]
	v_pk_fma_f32 v[40:41], v[12:13], v[44:45], v[4:5]
	v_pk_fma_f32 v[34:35], v[14:15], v[34:35], v[6:7]
	v_pk_fma_f32 v[42:43], v[8:9], v[42:43], v[0:1]
	v_pk_fma_f32 v[16:17], v[10:11], v[16:17], v[2:3]
	v_pk_fma_f32 v[40:41], v[26:27], v[52:53], v[40:41] op_sel_hi:[0,1,1]
	v_pk_fma_f32 v[18:19], v[26:27], v[18:19], v[34:35] op_sel_hi:[0,1,1]
	v_pk_fma_f32 v[34:35], v[26:27], v[50:51], v[42:43] op_sel_hi:[0,1,1]
	v_pk_fma_f32 v[16:17], v[26:27], v[36:37], v[16:17] op_sel_hi:[0,1,1]
	v_pk_mul_f32 v[36:37], v[40:41], v[48:49]
	v_pk_mul_f32 v[18:19], v[18:19], v[38:39]
	v_pk_mul_f32 v[34:35], v[34:35], v[46:47]
	v_pk_mul_f32 v[32:33], v[16:17], v[32:33]
	v_cvt_pk_bf16_f32 v16, v36, v37
	v_cvt_pk_bf16_f32 v17, v18, v19
	v_cvt_pk_bf16_f32 v18, v34, v35
	v_cvt_pk_bf16_f32 v19, v32, v33
	global_store_dwordx4 v[24:25], v[16:19], off
	v_lshl_add_u64 v[24:25], v[24:25], 0, s[8:9]
	s_cbranch_scc0 .LBB0_319

; __device__ __forceinline__ unsigned pk_bf16(float lo, float hi) { f32x2e v = {lo, hi}; bf16x2e b = __builtin_convertvector(v, bf16x2e); return __builtin_bit_cast(unsigned, b); }
; #define LAS __attribute__((address_space(3)))
; __device__ __forceinline__ void tr_item(const float* W, int Ksrc, int N, int k0, int n0, bf16* dst, int ldt, int drow0, int dcol0, LAS float* scr, int lane, const float* nscale = nullptr, const float* kscale = nullptr) {
;     ...
;     for (int i = 0; i < 8; ++i) { const int kk = 8 * i + kr_; const int kr = (k0 + kk < Ksrc) ? (k0 + kk) : (Ksrc - 1); tv[i] = __builtin_nontemporal_load((const f32x4*)(W + (size_t)kr * N + n0 + 4 * nq_)); }
; #pragma unroll
;     for (int i = 0; i < 8; ++i) { const int kk = 8 * i + kr_; const bool ok = (k0 + kk < Ksrc); LAS float* d_ = scr + kk * 33 + 4 * nq_;
;         const float ks_ = (ok && kscale) ? kscale[k0 + kk] : 1.0f;
;         d_[0] = ok ? tv[i].x * ks_ : 0.f; d_[1] = ok ? tv[i].y * ks_ : 0.f; d_[2] = ok ? tv[i].z * ks_ : 0.f; d_[3] = ok ? tv[i].w * ks_ : 0.f; }
;     asm volatile("s_waitcnt lgkmcnt(0)" ::: "memory");
;     const int c = lane & 7;
; #pragma unroll
;     for (int j = 0; j < 4; ++j) { const int n = (lane >> 3) + 8 * j; const LAS float* s = scr + (8 * c) * 33 + n;
;         const float sc = nscale ? nscale[n0 + n] : 1.0f;
;         u32x4 o; o.x = pk_bf16(s[0 * 33] * sc, s[1 * 33] * sc); o.y = pk_bf16(s[2 * 33] * sc, s[3 * 33] * sc); o.z = pk_bf16(s[4 * 33] * sc, s[5 * 33] * sc); o.w = pk_bf16(s[6 * 33] * sc, s[7 * 33] * sc);
;         *(u32x4*)(dst + (size_t)(drow0 + n) * ldt + dcol0 + k0 + 8 * c) = o; }
;     asm volatile("s_waitcnt lgkmcnt(0)" ::: "memory");
; __device__ __forceinline__ void tr_matrix(const float* W, int Ksrc, int N, bf16* dst, int ldt, int dcol0, int rowmode, int drow_off, LAS float* scr, int gw, int ngw, int lane, const float* nscale = nullptr, const float* kscale = nullptr) {
;     ...
;     for (int it = gw; it < items; it += ngw) { const int kb = it / nnb, nb = it - kb * nnb, n0 = nb * 32;
;         const int drow0 = rowmode ? ((n0 >> 7) * 256 + (n0 & 127) + drow_off) : (drow_off + n0);
;         tr_item(W, Ksrc, N, kb * 64, n0, dst, ldt, drow0, dcol0, scr, lane, nscale, kscale); }
.LBB0_329:
	s_or_b64 exec, exec, s[0:1]
	s_waitcnt vmcnt(0) lgkmcnt(0)
	v_mul_f32_e32 v0, v0, v6
	v_mul_f32_e32 v1, v1, v6
	v_cndmask_b32_e32 v0, 0, v0, vcc
	v_cndmask_b32_e32 v1, 0, v1, vcc
	v_add_u32_e32 v7, 0x1080, v16
	ds_write2_b32 v7, v0, v1 offset1:1
	v_mul_f32_e32 v0, v2, v6
	v_mul_f32_e32 v1, v3, v6
	v_cndmask_b32_e32 v0, 0, v0, vcc
	v_cndmask_b32_e32 v1, 0, v1, vcc
	v_add_u32_e32 v2, 0x1088, v16
	ds_write2_b32 v2, v0, v1 offset1:1
	s_waitcnt lgkmcnt(0)
	ds_read_b32 v0, v58
	ds_read_b32 v1, v58 offset:132
	s_mulk_i32 s14, 0xd400
	s_add_i32 s0, s7, s14
	s_and_b32 s0, s0, 0xffffff00
	s_and_b32 s1, s68, 0x60
	s_waitcnt lgkmcnt(0)
	v_cvt_pk_bf16_f32 v0, v0, v1
	ds_read_b32 v1, v58 offset:264
	ds_read_b32 v2, v58 offset:396
	s_or_b32 s0, s1, s0
	v_lshl_add_u64 v[4:5], v[4:5], 1, v[44:45]
	s_add_i32 s8, s8, s19
	s_add_i32 s7, s7, s33
	s_waitcnt lgkmcnt(0)
	v_cvt_pk_bf16_f32 v1, v1, v2
	ds_read_b32 v2, v58 offset:528
	ds_read_b32 v3, v58 offset:660
	s_waitcnt lgkmcnt(0)
	v_cvt_pk_bf16_f32 v2, v2, v3
	ds_read_b32 v3, v58 offset:792
	ds_read_b32 v6, v58 offset:924
	s_waitcnt lgkmcnt(0)
	v_cvt_pk_bf16_f32 v3, v3, v6
	v_or_b32_e32 v6, s0, v32
	v_ashrrev_i32_e32 v7, 31, v6
	v_lshlrev_b64 v[6:7], 12, v[6:7]
	v_lshl_add_u64 v[6:7], v[4:5], 0, v[6:7]
	global_store_dwordx4 v[6:7], v[0:3], off
	ds_read_b32 v0, v58 offset:32
	ds_read_b32 v1, v58 offset:164
	s_waitcnt lgkmcnt(0)
	v_cvt_pk_bf16_f32 v0, v0, v1
	ds_read_b32 v1, v58 offset:296
	ds_read_b32 v2, v58 offset:428
	s_waitcnt lgkmcnt(0)
	v_cvt_pk_bf16_f32 v1, v1, v2
	ds_read_b32 v2, v58 offset:560
	ds_read_b32 v3, v58 offset:692
	s_waitcnt lgkmcnt(0)
	v_cvt_pk_bf16_f32 v2, v2, v3
	ds_read_b32 v3, v58 offset:824
	ds_read_b32 v6, v58 offset:956
	s_waitcnt lgkmcnt(0)
	v_cvt_pk_bf16_f32 v3, v3, v6
	v_or_b32_e32 v6, s0, v48
	v_ashrrev_i32_e32 v7, 31, v6
	v_lshlrev_b64 v[6:7], 12, v[6:7]
	v_lshl_add_u64 v[6:7], v[4:5], 0, v[6:7]
	global_store_dwordx4 v[6:7], v[0:3], off
	ds_read_b32 v0, v58 offset:64
	ds_read_b32 v1, v58 offset:196
	s_waitcnt lgkmcnt(0)
	v_cvt_pk_bf16_f32 v0, v0, v1
	ds_read_b32 v1, v58 offset:328
	ds_read_b32 v2, v58 offset:460
	s_waitcnt lgkmcnt(0)
	v_cvt_pk_bf16_f32 v1, v1, v2
	ds_read_b32 v2, v58 offset:592
	ds_read_b32 v3, v58 offset:724
	s_waitcnt lgkmcnt(0)
	v_cvt_pk_bf16_f32 v2, v2, v3
	ds_read_b32 v3, v58 offset:856
	ds_read_b32 v6, v58 offset:988
	s_waitcnt lgkmcnt(0)
	v_cvt_pk_bf16_f32 v3, v3, v6
	v_or_b32_e32 v6, s0, v50
	v_ashrrev_i32_e32 v7, 31, v6
	v_lshlrev_b64 v[6:7], 12, v[6:7]
	v_lshl_add_u64 v[6:7], v[4:5], 0, v[6:7]
	global_store_dwordx4 v[6:7], v[0:3], off
	ds_read_b32 v0, v58 offset:96
	ds_read_b32 v1, v58 offset:228
	s_waitcnt lgkmcnt(0)
	v_cvt_pk_bf16_f32 v0, v0, v1
	ds_read_b32 v1, v58 offset:360
	ds_read_b32 v2, v58 offset:492
	s_waitcnt lgkmcnt(0)
	v_cvt_pk_bf16_f32 v1, v1, v2
	ds_read_b32 v2, v58 offset:624
	ds_read_b32 v3, v58 offset:756
	s_waitcnt lgkmcnt(0)
	v_cvt_pk_bf16_f32 v2, v2, v3
	ds_read_b32 v3, v58 offset:888
	ds_read_b32 v6, v58 offset:1020
	s_waitcnt lgkmcnt(0)
	v_cvt_pk_bf16_f32 v3, v3, v6
	v_or_b32_e32 v6, s0, v52
	v_ashrrev_i32_e32 v7, 31, v6
	v_lshlrev_b64 v[6:7], 12, v[6:7]
	v_lshl_add_u64 v[4:5], v[4:5], 0, v[6:7]
	global_store_dwordx4 v[4:5], v[0:3], off
	s_waitcnt lgkmcnt(0)
	v_readlane_b32 s0, v253, 48
	s_add_i32 s9, s9, s0
	s_cmpk_lt_i32 s9, 0x1600
	s_cbranch_scc0 .LBB0_348
.LBB0_330:
	s_mul_hi_i32 s0, s9, 0x2e8ba2e9
	s_lshr_b32 s1, s0, 31
	s_ashr_i32 s14, s0, 5
	s_add_i32 s14, s14, s1
	s_mul_i32 s0, s14, 0xffffea00
	s_lshl_b32 s72, s14, 6
	s_add_i32 s68, s8, s0
	v_or_b32_e32 v46, s72, v32
	s_ashr_i32 s69, s68, 31
	v_or_b32_e32 v4, 8, v46
	v_lshl_add_u64 v[0:1], s[68:69], 2, v[42:43]
	v_min_i32_e32 v2, 0x7ff, v46
	s_movk_i32 s15, 0x5800
	v_min_i32_e32 v4, 0x7ff, v4
	v_mad_i64_i32 v[2:3], s[0:1], v2, s15, v[0:1]
	v_mad_i64_i32 v[4:5], s[0:1], v4, s15, v[0:1]
	global_load_dwordx4 v[28:31], v[2:3], off nt
	global_load_dwordx4 v[24:27], v[4:5], off nt
	v_or_b32_e32 v2, 16, v46
	v_or_b32_e32 v4, 24, v46
	v_min_i32_e32 v2, 0x7ff, v2
	v_min_i32_e32 v4, 0x7ff, v4
	v_mad_i64_i32 v[2:3], s[0:1], v2, s15, v[0:1]
	v_mad_i64_i32 v[4:5], s[0:1], v4, s15, v[0:1]
	global_load_dwordx4 v[20:23], v[2:3], off nt
	global_load_dwordx4 v[16:19], v[4:5], off nt
	v_or_b32_e32 v2, 32, v46
	v_or_b32_e32 v4, 40, v46
	v_min_i32_e32 v2, 0x7ff, v2
	v_min_i32_e32 v4, 0x7ff, v4
	v_mad_i64_i32 v[2:3], s[0:1], v2, s15, v[0:1]
	v_mad_i64_i32 v[4:5], s[0:1], v4, s15, v[0:1]
	global_load_dwordx4 v[12:15], v[2:3], off nt
	global_load_dwordx4 v[8:11], v[4:5], off nt
	v_or_b32_e32 v2, 48, v46
	v_or_b32_e32 v4, 56, v46
	v_min_i32_e32 v2, 0x7ff, v2
	v_min_i32_e32 v4, 0x7ff, v4
	v_mad_i64_i32 v[2:3], s[0:1], v2, s15, v[0:1]
	v_mad_i64_i32 v[0:1], s[0:1], v4, s15, v[0:1]
	global_load_dwordx4 v[4:7], v[2:3], off nt
	s_nop 0
	global_load_dwordx4 v[0:3], v[0:1], off nt
	v_cmp_gt_i32_e32 vcc, s61, v46
	s_and_b64 s[30:31], s[66:67], vcc
	v_mov_b32_e32 v41, 1.0
	v_mov_b32_e32 v47, 1.0
	s_and_saveexec_b64 s[0:1], s[30:31]
	s_cbranch_execz .LBB0_332
	v_ashrrev_i32_e32 v47, 31, v46
	v_lshl_add_u64 v[46:47], v[46:47], 2, s[64:65]
	global_load_dword v47, v[46:47], off
; #define LAS __attribute__((address_space(3)))
; __device__ __forceinline__ void tr_item(const float* W, int Ksrc, int N, int k0, int n0, bf16* dst, int ldt, int drow0, int dcol0, LAS float* scr, int lane, const float* nscale = nullptr, const float* kscale = nullptr) {
;     ...
;     for (int i = 0; i < 8; ++i) { const int kk = 8 * i + kr_; const bool ok = (k0 + kk < Ksrc); LAS float* d_ = scr + kk * 33 + 4 * nq_;
;         const float ks_ = (ok && kscale) ? kscale[k0 + kk] : 1.0f;
;         d_[0] = ok ? tv[i].x * ks_ : 0.f; d_[1] = ok ? tv[i].y * ks_ : 0.f; d_[2] = ok ? tv[i].z * ks_ : 0.f; d_[3] = ok ? tv[i].w * ks_ : 0.f; }
.LBB0_332:
	s_or_b64 exec, exec, s[0:1]
	s_waitcnt vmcnt(0) lgkmcnt(0)
	v_mul_f32_e32 v28, v28, v47
	v_mul_f32_e32 v29, v29, v47
	v_cndmask_b32_e32 v28, 0, v28, vcc
	v_cndmask_b32_e32 v29, 0, v29, vcc
	v_add_u32_e32 v46, v35, v37
	ds_write2_b32 v46, v28, v29 offset1:1
	v_mul_f32_e32 v28, v30, v47
	v_mul_f32_e32 v29, v31, v47
	v_cndmask_b32_e32 v28, 0, v28, vcc
	v_cndmask_b32_e32 v29, 0, v29, vcc
	ds_write2_b32 v46, v28, v29 offset0:2 offset1:3
	v_or_b32_e32 v28, s72, v48
	v_cmp_gt_i32_e32 vcc, s61, v28
	s_and_b64 s[30:31], s[66:67], vcc
	s_and_saveexec_b64 s[0:1], s[30:31]
	s_cbranch_execz .LBB0_334
	s_ashr_i32 s73, s72, 31
	v_lshl_add_u64 v[28:29], s[72:73], 0, v[32:33]
	v_lshl_add_u64 v[28:29], v[28:29], 2, s[64:65]
	global_load_dword v41, v[28:29], off offset:32
.LBB0_334:
	s_or_b64 exec, exec, s[0:1]
	s_waitcnt vmcnt(0) lgkmcnt(0)
	v_mul_f32_e32 v24, v24, v41
	v_mul_f32_e32 v25, v25, v41
	v_cndmask_b32_e32 v24, 0, v24, vcc
	v_cndmask_b32_e32 v25, 0, v25, vcc
	v_add_u32_e32 v28, v35, v49
	ds_write2_b32 v28, v24, v25 offset1:1
	v_mul_f32_e32 v24, v26, v41
	v_mul_f32_e32 v25, v27, v41
	v_cndmask_b32_e32 v24, 0, v24, vcc
	v_cndmask_b32_e32 v25, 0, v25, vcc
	ds_write2_b32 v28, v24, v25 offset0:2 offset1:3
	v_or_b32_e32 v24, s72, v50
	v_cmp_gt_i32_e32 vcc, s61, v24
	s_and_b64 s[30:31], s[66:67], vcc
	v_mov_b32_e32 v24, 1.0
	v_mov_b32_e32 v25, 1.0
	s_and_saveexec_b64 s[0:1], s[30:31]
	s_cbranch_execz .LBB0_336
	s_ashr_i32 s73, s72, 31
	v_lshl_add_u64 v[26:27], s[72:73], 0, v[32:33]
	v_lshl_add_u64 v[26:27], v[26:27], 2, s[64:65]
	global_load_dword v25, v[26:27], off offset:64
.LBB0_336:
	s_or_b64 exec, exec, s[0:1]
	s_waitcnt vmcnt(0) lgkmcnt(0)
	v_mul_f32_e32 v20, v20, v25
	v_mul_f32_e32 v21, v21, v25
	v_cndmask_b32_e32 v20, 0, v20, vcc
	v_cndmask_b32_e32 v21, 0, v21, vcc
	v_add_u32_e32 v26, v35, v51
	ds_write2_b32 v26, v20, v21 offset1:1
	v_mul_f32_e32 v20, v22, v25
	v_mul_f32_e32 v21, v23, v25
	v_cndmask_b32_e32 v20, 0, v20, vcc
	v_cndmask_b32_e32 v21, 0, v21, vcc
	ds_write2_b32 v26, v20, v21 offset0:2 offset1:3
	v_or_b32_e32 v20, s72, v52
	v_cmp_gt_i32_e32 vcc, s61, v20
	s_and_b64 s[30:31], s[66:67], vcc
	s_and_saveexec_b64 s[0:1], s[30:31]
	s_cbranch_execz .LBB0_338
	s_ashr_i32 s73, s72, 31
	v_lshl_add_u64 v[20:21], s[72:73], 0, v[32:33]
	v_lshl_add_u64 v[20:21], v[20:21], 2, s[64:65]
	global_load_dword v24, v[20:21], off offset:96
.LBB0_338:
	s_or_b64 exec, exec, s[0:1]
	s_waitcnt vmcnt(0) lgkmcnt(0)
	v_mul_f32_e32 v16, v16, v24
	v_mul_f32_e32 v17, v17, v24
	v_cndmask_b32_e32 v20, 0, v16, vcc
	v_cndmask_b32_e32 v17, 0, v17, vcc
	v_add_u32_e32 v16, v35, v53
	ds_write2_b32 v16, v20, v17 offset1:1
	v_mul_f32_e32 v17, v18, v24
	v_mul_f32_e32 v18, v19, v24
	v_cndmask_b32_e32 v17, 0, v17, vcc
	v_cndmask_b32_e32 v18, 0, v18, vcc
	ds_write2_b32 v16, v17, v18 offset0:2 offset1:3
	v_or_b32_e32 v17, s72, v54
	v_cmp_gt_i32_e32 vcc, s61, v17
	s_and_b64 s[30:31], s[66:67], vcc
	v_mov_b32_e32 v17, 1.0
	v_mov_b32_e32 v18, 1.0
	s_and_saveexec_b64 s[0:1], s[30:31]
	s_cbranch_execz .LBB0_340
	s_ashr_i32 s73, s72, 31
	v_lshl_add_u64 v[18:19], s[72:73], 0, v[32:33]
	v_lshl_add_u64 v[18:19], v[18:19], 2, s[64:65]
	global_load_dword v18, v[18:19], off offset:128
.LBB0_340:
	s_or_b64 exec, exec, s[0:1]
	s_waitcnt vmcnt(0) lgkmcnt(0)
	v_mul_f32_e32 v12, v12, v18
	v_mul_f32_e32 v13, v13, v18
	v_cndmask_b32_e32 v12, 0, v12, vcc
	v_cndmask_b32_e32 v13, 0, v13, vcc
	v_add_u32_e32 v19, 0x420, v16
	ds_write2_b32 v19, v12, v13 offset1:1
	v_mul_f32_e32 v12, v14, v18
	v_mul_f32_e32 v13, v15, v18
	v_cndmask_b32_e32 v12, 0, v12, vcc
	v_cndmask_b32_e32 v13, 0, v13, vcc
	v_add_u32_e32 v14, 0x428, v16
	ds_write2_b32 v14, v12, v13 offset1:1
	v_or_b32_e32 v12, s72, v55
	v_cmp_gt_i32_e32 vcc, s61, v12
	s_and_b64 s[30:31], s[66:67], vcc
	s_and_saveexec_b64 s[0:1], s[30:31]
	s_cbranch_execz .LBB0_342
	s_ashr_i32 s73, s72, 31
	v_lshl_add_u64 v[12:13], s[72:73], 0, v[32:33]
	v_lshl_add_u64 v[12:13], v[12:13], 2, s[64:65]
	global_load_dword v17, v[12:13], off offset:160
.LBB0_342:
	s_or_b64 exec, exec, s[0:1]
	s_waitcnt vmcnt(0) lgkmcnt(0)
	v_mul_f32_e32 v8, v8, v17
	v_mul_f32_e32 v9, v9, v17
	v_cndmask_b32_e32 v8, 0, v8, vcc
	v_cndmask_b32_e32 v9, 0, v9, vcc
	v_add_u32_e32 v12, 0x840, v16
	ds_write2_b32 v12, v8, v9 offset1:1
	v_mul_f32_e32 v8, v10, v17
	v_mul_f32_e32 v9, v11, v17
	v_cndmask_b32_e32 v8, 0, v8, vcc
	v_cndmask_b32_e32 v9, 0, v9, vcc
	v_add_u32_e32 v10, 0x848, v16
	ds_write2_b32 v10, v8, v9 offset1:1
	v_or_b32_e32 v8, s72, v56
	v_cmp_gt_i32_e32 vcc, s61, v8
	s_and_b64 s[30:31], s[66:67], vcc
	v_mov_b32_e32 v8, 1.0
	s_and_saveexec_b64 s[0:1], s[30:31]
	s_cbranch_execz .LBB0_344
	s_ashr_i32 s73, s72, 31
	v_lshl_add_u64 v[8:9], s[72:73], 0, v[32:33]
	v_lshl_add_u64 v[8:9], v[8:9], 2, s[64:65]
	global_load_dword v8, v[8:9], off offset:192
.LBB0_344:
	s_or_b64 exec, exec, s[0:1]
	s_waitcnt vmcnt(0) lgkmcnt(0)
	v_mul_f32_e32 v4, v4, v8
	v_mul_f32_e32 v5, v5, v8
	v_cndmask_b32_e32 v4, 0, v4, vcc
	v_cndmask_b32_e32 v5, 0, v5, vcc
	v_add_u32_e32 v9, 0xc60, v16
	ds_write2_b32 v9, v4, v5 offset1:1
	v_mul_f32_e32 v4, v6, v8
	v_mul_f32_e32 v5, v7, v8
	v_cndmask_b32_e32 v4, 0, v4, vcc
	v_cndmask_b32_e32 v5, 0, v5, vcc
	v_add_u32_e32 v6, 0xc68, v16
	ds_write2_b32 v6, v4, v5 offset1:1
	v_or_b32_e32 v4, s72, v57
	v_cmp_gt_i32_e32 vcc, s61, v4
	s_and_b64 s[0:1], s[66:67], vcc
	s_xor_b64 s[0:1], s[0:1], -1
	s_and_saveexec_b64 s[30:31], s[0:1]
	s_xor_b64 s[0:1], exec, s[30:31]
	s_ashr_i32 s73, s72, 31
	s_or_saveexec_b64 s[0:1], s[0:1]
	v_mov_b32_e32 v6, 1.0
	v_mov_b64_e32 v[4:5], s[72:73]
	s_xor_b64 exec, exec, s[0:1]
	s_cbranch_execz .LBB0_329
	s_ashr_i32 s73, s72, 31
	v_lshl_add_u64 v[4:5], s[72:73], 0, v[32:33]
	v_lshl_add_u64 v[4:5], v[4:5], 2, s[64:65]
	global_load_dword v6, v[4:5], off offset:224
	v_mov_b64_e32 v[4:5], s[72:73]
	s_branch .LBB0_329

; __device__ __forceinline__ unsigned pk_bf16(float lo, float hi) { f32x2e v = {lo, hi}; bf16x2e b = __builtin_convertvector(v, bf16x2e); return __builtin_bit_cast(unsigned, b); }
; #define LAS __attribute__((address_space(3)))
; __device__ __forceinline__ void tr_item(const float* W, int Ksrc, int N, int k0, int n0, bf16* dst, int ldt, int drow0, int dcol0, LAS float* scr, int lane, const float* nscale = nullptr, const float* kscale = nullptr) {
;     ...
;     for (int i = 0; i < 8; ++i) { const int kk = 8 * i + kr_; const int kr = (k0 + kk < Ksrc) ? (k0 + kk) : (Ksrc - 1); tv[i] = __builtin_nontemporal_load((const f32x4*)(W + (size_t)kr * N + n0 + 4 * nq_)); }
; #pragma unroll
;     for (int i = 0; i < 8; ++i) { const int kk = 8 * i + kr_; const bool ok = (k0 + kk < Ksrc); LAS float* d_ = scr + kk * 33 + 4 * nq_;
;         const float ks_ = (ok && kscale) ? kscale[k0 + kk] : 1.0f;
;         d_[0] = ok ? tv[i].x * ks_ : 0.f; d_[1] = ok ? tv[i].y * ks_ : 0.f; d_[2] = ok ? tv[i].z * ks_ : 0.f; d_[3] = ok ? tv[i].w * ks_ : 0.f; }
;     asm volatile("s_waitcnt lgkmcnt(0)" ::: "memory");
;     const int c = lane & 7;
; #pragma unroll
;     for (int j = 0; j < 4; ++j) { const int n = (lane >> 3) + 8 * j; const LAS float* s = scr + (8 * c) * 33 + n;
;         const float sc = nscale ? nscale[n0 + n] : 1.0f;
;         u32x4 o; o.x = pk_bf16(s[0 * 33] * sc, s[1 * 33] * sc); o.y = pk_bf16(s[2 * 33] * sc, s[3 * 33] * sc); o.z = pk_bf16(s[4 * 33] * sc, s[5 * 33] * sc); o.w = pk_bf16(s[6 * 33] * sc, s[7 * 33] * sc);
;         *(u32x4*)(dst + (size_t)(drow0 + n) * ldt + dcol0 + k0 + 8 * c) = o; }
;     asm volatile("s_waitcnt lgkmcnt(0)" ::: "memory");
; __device__ __forceinline__ void tr_matrix(const float* W, int Ksrc, int N, bf16* dst, int ldt, int dcol0, int rowmode, int drow_off, LAS float* scr, int gw, int ngw, int lane, const float* nscale = nullptr, const float* kscale = nullptr) {
;     ...
;     for (int it = gw; it < items; it += ngw) { const int kb = it / nnb, nb = it - kb * nnb, n0 = nb * 32;
;         const int drow0 = rowmode ? ((n0 >> 7) * 256 + (n0 & 127) + drow_off) : (drow_off + n0);
;         tr_item(W, Ksrc, N, kb * 64, n0, dst, ldt, drow0, dcol0, scr, lane, nscale, kscale); }
.LBB0_350:
	s_or_b64 exec, exec, s[0:1]
	s_waitcnt vmcnt(0) lgkmcnt(0)
	v_mul_f32_e32 v0, v0, v6
	v_mul_f32_e32 v1, v1, v6
	v_cndmask_b32_e32 v0, 0, v0, vcc
	v_cndmask_b32_e32 v1, 0, v1, vcc
	v_add_u32_e32 v7, 0x1080, v16
	ds_write2_b32 v7, v0, v1 offset1:1
	v_mul_f32_e32 v0, v2, v6
	v_mul_f32_e32 v1, v3, v6
	v_cndmask_b32_e32 v0, 0, v0, vcc
	v_cndmask_b32_e32 v1, 0, v1, vcc
	v_add_u32_e32 v2, 0x1088, v16
	ds_write2_b32 v2, v0, v1 offset1:1
	s_waitcnt lgkmcnt(0)
	ds_read_b32 v0, v58
	ds_read_b32 v1, v58 offset:132
	s_mulk_i32 s14, 0xd400
	s_add_i32 s0, s7, s14
	s_and_b32 s0, s0, 0xffffff00
	s_and_b32 s1, s42, 0x60
	s_waitcnt lgkmcnt(0)
	v_cvt_pk_bf16_f32 v0, v0, v1
	ds_read_b32 v1, v58 offset:264
	ds_read_b32 v2, v58 offset:396
	s_or_b32 s0, s0, s1
	s_bitset1_b32 s0, 7
	v_lshl_add_u64 v[4:5], v[4:5], 1, v[40:41]
	s_add_i32 s8, s8, s19
	s_waitcnt lgkmcnt(0)
	v_cvt_pk_bf16_f32 v1, v1, v2
	ds_read_b32 v2, v58 offset:528
	ds_read_b32 v3, v58 offset:660
	s_add_i32 s7, s7, s33
	s_waitcnt lgkmcnt(0)
	v_cvt_pk_bf16_f32 v2, v2, v3
	ds_read_b32 v3, v58 offset:792
	ds_read_b32 v6, v58 offset:924
	s_waitcnt lgkmcnt(0)
	v_cvt_pk_bf16_f32 v3, v3, v6
	v_or_b32_e32 v6, s0, v32
	v_ashrrev_i32_e32 v7, 31, v6
	v_lshlrev_b64 v[6:7], 12, v[6:7]
	v_lshl_add_u64 v[6:7], v[4:5], 0, v[6:7]
	global_store_dwordx4 v[6:7], v[0:3], off
	ds_read_b32 v0, v58 offset:32
	ds_read_b32 v1, v58 offset:164
	s_waitcnt lgkmcnt(0)
	v_cvt_pk_bf16_f32 v0, v0, v1
	ds_read_b32 v1, v58 offset:296
	ds_read_b32 v2, v58 offset:428
	s_waitcnt lgkmcnt(0)
	v_cvt_pk_bf16_f32 v1, v1, v2
	ds_read_b32 v2, v58 offset:560
	ds_read_b32 v3, v58 offset:692
	s_waitcnt lgkmcnt(0)
	v_cvt_pk_bf16_f32 v2, v2, v3
	ds_read_b32 v3, v58 offset:824
	ds_read_b32 v6, v58 offset:956
	s_waitcnt lgkmcnt(0)
	v_cvt_pk_bf16_f32 v3, v3, v6
	v_or_b32_e32 v6, s0, v48
	v_ashrrev_i32_e32 v7, 31, v6
	v_lshlrev_b64 v[6:7], 12, v[6:7]
	v_lshl_add_u64 v[6:7], v[4:5], 0, v[6:7]
	global_store_dwordx4 v[6:7], v[0:3], off
	ds_read_b32 v0, v58 offset:64
	ds_read_b32 v1, v58 offset:196
	s_waitcnt lgkmcnt(0)
	v_cvt_pk_bf16_f32 v0, v0, v1
	ds_read_b32 v1, v58 offset:328
	ds_read_b32 v2, v58 offset:460
	s_waitcnt lgkmcnt(0)
	v_cvt_pk_bf16_f32 v1, v1, v2
	ds_read_b32 v2, v58 offset:592
	ds_read_b32 v3, v58 offset:724
	s_waitcnt lgkmcnt(0)
	v_cvt_pk_bf16_f32 v2, v2, v3
	ds_read_b32 v3, v58 offset:856
	ds_read_b32 v6, v58 offset:988
	s_waitcnt lgkmcnt(0)
	v_cvt_pk_bf16_f32 v3, v3, v6
	v_or_b32_e32 v6, s0, v50
	v_ashrrev_i32_e32 v7, 31, v6
	v_lshlrev_b64 v[6:7], 12, v[6:7]
	v_lshl_add_u64 v[6:7], v[4:5], 0, v[6:7]
	global_store_dwordx4 v[6:7], v[0:3], off
	ds_read_b32 v0, v58 offset:96
	ds_read_b32 v1, v58 offset:228
	s_waitcnt lgkmcnt(0)
	v_cvt_pk_bf16_f32 v0, v0, v1
	ds_read_b32 v1, v58 offset:360
	ds_read_b32 v2, v58 offset:492
	s_waitcnt lgkmcnt(0)
	v_cvt_pk_bf16_f32 v1, v1, v2
	ds_read_b32 v2, v58 offset:624
	ds_read_b32 v3, v58 offset:756
	s_waitcnt lgkmcnt(0)
	v_cvt_pk_bf16_f32 v2, v2, v3
	ds_read_b32 v3, v58 offset:888
	ds_read_b32 v6, v58 offset:1020
	s_waitcnt lgkmcnt(0)
	v_cvt_pk_bf16_f32 v3, v3, v6
	v_or_b32_e32 v6, s0, v52
	v_ashrrev_i32_e32 v7, 31, v6
	v_lshlrev_b64 v[6:7], 12, v[6:7]
	v_lshl_add_u64 v[4:5], v[4:5], 0, v[6:7]
	global_store_dwordx4 v[4:5], v[0:3], off
	s_waitcnt lgkmcnt(0)
	v_readlane_b32 s0, v253, 48
	s_add_i32 s9, s9, s0
	s_cmpk_lt_i32 s9, 0x1600
	s_cbranch_scc0 .LBB0_369
.LBB0_351:
	s_mul_hi_i32 s0, s9, 0x2e8ba2e9
	s_lshr_b32 s1, s0, 31
	s_ashr_i32 s14, s0, 5
	s_add_i32 s14, s14, s1
	s_mul_i32 s0, s14, 0xffffea00
	s_lshl_b32 s64, s14, 6
	s_add_i32 s42, s8, s0
	v_or_b32_e32 v44, s64, v32
	s_ashr_i32 s43, s42, 31
	v_or_b32_e32 v4, 8, v44
	v_lshl_add_u64 v[0:1], s[42:43], 2, v[42:43]
	v_min_i32_e32 v2, 0x7ff, v44
	s_movk_i32 s15, 0x5800
	v_min_i32_e32 v4, 0x7ff, v4
	v_mad_i64_i32 v[2:3], s[0:1], v2, s15, v[0:1]
	v_mad_i64_i32 v[4:5], s[0:1], v4, s15, v[0:1]
	global_load_dwordx4 v[28:31], v[2:3], off nt
	global_load_dwordx4 v[24:27], v[4:5], off nt
	v_or_b32_e32 v2, 16, v44
	v_or_b32_e32 v4, 24, v44
	v_min_i32_e32 v2, 0x7ff, v2
	v_min_i32_e32 v4, 0x7ff, v4
	v_mad_i64_i32 v[2:3], s[0:1], v2, s15, v[0:1]
	v_mad_i64_i32 v[4:5], s[0:1], v4, s15, v[0:1]
	global_load_dwordx4 v[20:23], v[2:3], off nt
	global_load_dwordx4 v[16:19], v[4:5], off nt
	v_or_b32_e32 v2, 32, v44
	v_or_b32_e32 v4, 40, v44
	v_min_i32_e32 v2, 0x7ff, v2
	v_min_i32_e32 v4, 0x7ff, v4
	v_mad_i64_i32 v[2:3], s[0:1], v2, s15, v[0:1]
	v_mad_i64_i32 v[4:5], s[0:1], v4, s15, v[0:1]
	global_load_dwordx4 v[12:15], v[2:3], off nt
	global_load_dwordx4 v[8:11], v[4:5], off nt
	v_or_b32_e32 v2, 48, v44
	v_or_b32_e32 v4, 56, v44
	v_min_i32_e32 v2, 0x7ff, v2
	v_min_i32_e32 v4, 0x7ff, v4
	v_mad_i64_i32 v[2:3], s[0:1], v2, s15, v[0:1]
	v_mad_i64_i32 v[0:1], s[0:1], v4, s15, v[0:1]
	global_load_dwordx4 v[4:7], v[2:3], off nt
	s_nop 0
	global_load_dwordx4 v[0:3], v[0:1], off nt
	v_cmp_gt_i32_e32 vcc, s61, v44
	s_and_b64 s[30:31], s[56:57], vcc
	v_mov_b32_e32 v46, 1.0
	v_mov_b32_e32 v45, 1.0
	s_and_saveexec_b64 s[0:1], s[30:31]
	s_cbranch_execz .LBB0_353
	v_ashrrev_i32_e32 v45, 31, v44
	v_lshl_add_u64 v[44:45], v[44:45], 2, s[62:63]
	global_load_dword v45, v[44:45], off
; #define LAS __attribute__((address_space(3)))
; __device__ __forceinline__ void tr_item(const float* W, int Ksrc, int N, int k0, int n0, bf16* dst, int ldt, int drow0, int dcol0, LAS float* scr, int lane, const float* nscale = nullptr, const float* kscale = nullptr) {
;     ...
;     for (int i = 0; i < 8; ++i) { const int kk = 8 * i + kr_; const bool ok = (k0 + kk < Ksrc); LAS float* d_ = scr + kk * 33 + 4 * nq_;
;         const float ks_ = (ok && kscale) ? kscale[k0 + kk] : 1.0f;
;         d_[0] = ok ? tv[i].x * ks_ : 0.f; d_[1] = ok ? tv[i].y * ks_ : 0.f; d_[2] = ok ? tv[i].z * ks_ : 0.f; d_[3] = ok ? tv[i].w * ks_ : 0.f; }
.LBB0_353:
	s_or_b64 exec, exec, s[0:1]
	s_waitcnt vmcnt(0) lgkmcnt(0)
	v_mul_f32_e32 v28, v28, v45
	v_mul_f32_e32 v29, v29, v45
	v_cndmask_b32_e32 v28, 0, v28, vcc
	v_cndmask_b32_e32 v29, 0, v29, vcc
	v_add_u32_e32 v44, v35, v37
	ds_write2_b32 v44, v28, v29 offset1:1
	v_mul_f32_e32 v28, v30, v45
	v_mul_f32_e32 v29, v31, v45
	v_cndmask_b32_e32 v28, 0, v28, vcc
	v_cndmask_b32_e32 v29, 0, v29, vcc
	ds_write2_b32 v44, v28, v29 offset0:2 offset1:3
	v_or_b32_e32 v28, s64, v48
	v_cmp_gt_i32_e32 vcc, s61, v28
	s_and_b64 s[30:31], s[56:57], vcc
	s_and_saveexec_b64 s[0:1], s[30:31]
	s_cbranch_execz .LBB0_355
	s_ashr_i32 s65, s64, 31
	v_lshl_add_u64 v[28:29], s[64:65], 0, v[32:33]
	v_lshl_add_u64 v[28:29], v[28:29], 2, s[62:63]
	global_load_dword v46, v[28:29], off offset:32
.LBB0_355:
	s_or_b64 exec, exec, s[0:1]
	s_waitcnt vmcnt(0) lgkmcnt(0)
	v_mul_f32_e32 v24, v24, v46
	v_mul_f32_e32 v25, v25, v46
	v_cndmask_b32_e32 v24, 0, v24, vcc
	v_cndmask_b32_e32 v25, 0, v25, vcc
	v_add_u32_e32 v28, v35, v49
	ds_write2_b32 v28, v24, v25 offset1:1
	v_mul_f32_e32 v24, v26, v46
	v_mul_f32_e32 v25, v27, v46
	v_cndmask_b32_e32 v24, 0, v24, vcc
	v_cndmask_b32_e32 v25, 0, v25, vcc
	ds_write2_b32 v28, v24, v25 offset0:2 offset1:3
	v_or_b32_e32 v24, s64, v50
	v_cmp_gt_i32_e32 vcc, s61, v24
	s_and_b64 s[30:31], s[56:57], vcc
	v_mov_b32_e32 v24, 1.0
	v_mov_b32_e32 v25, 1.0
	s_and_saveexec_b64 s[0:1], s[30:31]
	s_cbranch_execz .LBB0_357
	s_ashr_i32 s65, s64, 31
	v_lshl_add_u64 v[26:27], s[64:65], 0, v[32:33]
	v_lshl_add_u64 v[26:27], v[26:27], 2, s[62:63]
	global_load_dword v25, v[26:27], off offset:64
.LBB0_357:
	s_or_b64 exec, exec, s[0:1]
	s_waitcnt vmcnt(0) lgkmcnt(0)
	v_mul_f32_e32 v20, v20, v25
	v_mul_f32_e32 v21, v21, v25
	v_cndmask_b32_e32 v20, 0, v20, vcc
	v_cndmask_b32_e32 v21, 0, v21, vcc
	v_add_u32_e32 v26, v35, v51
	ds_write2_b32 v26, v20, v21 offset1:1
	v_mul_f32_e32 v20, v22, v25
	v_mul_f32_e32 v21, v23, v25
	v_cndmask_b32_e32 v20, 0, v20, vcc
	v_cndmask_b32_e32 v21, 0, v21, vcc
	ds_write2_b32 v26, v20, v21 offset0:2 offset1:3
	v_or_b32_e32 v20, s64, v52
	v_cmp_gt_i32_e32 vcc, s61, v20
	s_and_b64 s[30:31], s[56:57], vcc
	s_and_saveexec_b64 s[0:1], s[30:31]
	s_cbranch_execz .LBB0_359
	s_ashr_i32 s65, s64, 31
	v_lshl_add_u64 v[20:21], s[64:65], 0, v[32:33]
	v_lshl_add_u64 v[20:21], v[20:21], 2, s[62:63]
	global_load_dword v24, v[20:21], off offset:96
.LBB0_359:
	s_or_b64 exec, exec, s[0:1]
	s_waitcnt vmcnt(0) lgkmcnt(0)
	v_mul_f32_e32 v16, v16, v24
	v_mul_f32_e32 v17, v17, v24
	v_cndmask_b32_e32 v20, 0, v16, vcc
	v_cndmask_b32_e32 v17, 0, v17, vcc
	v_add_u32_e32 v16, v35, v53
	ds_write2_b32 v16, v20, v17 offset1:1
	v_mul_f32_e32 v17, v18, v24
	v_mul_f32_e32 v18, v19, v24
	v_cndmask_b32_e32 v17, 0, v17, vcc
	v_cndmask_b32_e32 v18, 0, v18, vcc
	ds_write2_b32 v16, v17, v18 offset0:2 offset1:3
	v_or_b32_e32 v17, s64, v54
	v_cmp_gt_i32_e32 vcc, s61, v17
	s_and_b64 s[30:31], s[56:57], vcc
	v_mov_b32_e32 v17, 1.0
	v_mov_b32_e32 v18, 1.0
	s_and_saveexec_b64 s[0:1], s[30:31]
	s_cbranch_execz .LBB0_361
	s_ashr_i32 s65, s64, 31
	v_lshl_add_u64 v[18:19], s[64:65], 0, v[32:33]
	v_lshl_add_u64 v[18:19], v[18:19], 2, s[62:63]
	global_load_dword v18, v[18:19], off offset:128
.LBB0_361:
	s_or_b64 exec, exec, s[0:1]
	s_waitcnt vmcnt(0) lgkmcnt(0)
	v_mul_f32_e32 v12, v12, v18
	v_mul_f32_e32 v13, v13, v18
	v_cndmask_b32_e32 v12, 0, v12, vcc
	v_cndmask_b32_e32 v13, 0, v13, vcc
	v_add_u32_e32 v19, 0x420, v16
	ds_write2_b32 v19, v12, v13 offset1:1
	v_mul_f32_e32 v12, v14, v18
	v_mul_f32_e32 v13, v15, v18
	v_cndmask_b32_e32 v12, 0, v12, vcc
	v_cndmask_b32_e32 v13, 0, v13, vcc
	v_add_u32_e32 v14, 0x428, v16
	ds_write2_b32 v14, v12, v13 offset1:1
	v_or_b32_e32 v12, s64, v55
	v_cmp_gt_i32_e32 vcc, s61, v12
	s_and_b64 s[30:31], s[56:57], vcc
	s_and_saveexec_b64 s[0:1], s[30:31]
	s_cbranch_execz .LBB0_363
	s_ashr_i32 s65, s64, 31
	v_lshl_add_u64 v[12:13], s[64:65], 0, v[32:33]
	v_lshl_add_u64 v[12:13], v[12:13], 2, s[62:63]
	global_load_dword v17, v[12:13], off offset:160
.LBB0_363:
	s_or_b64 exec, exec, s[0:1]
	s_waitcnt vmcnt(0) lgkmcnt(0)
	v_mul_f32_e32 v8, v8, v17
	v_mul_f32_e32 v9, v9, v17
	v_cndmask_b32_e32 v8, 0, v8, vcc
	v_cndmask_b32_e32 v9, 0, v9, vcc
	v_add_u32_e32 v12, 0x840, v16
	ds_write2_b32 v12, v8, v9 offset1:1
	v_mul_f32_e32 v8, v10, v17
	v_mul_f32_e32 v9, v11, v17
	v_cndmask_b32_e32 v8, 0, v8, vcc
	v_cndmask_b32_e32 v9, 0, v9, vcc
	v_add_u32_e32 v10, 0x848, v16
	ds_write2_b32 v10, v8, v9 offset1:1
	v_or_b32_e32 v8, s64, v56
	v_cmp_gt_i32_e32 vcc, s61, v8
	s_and_b64 s[30:31], s[56:57], vcc
	v_mov_b32_e32 v8, 1.0
	s_and_saveexec_b64 s[0:1], s[30:31]
	s_cbranch_execz .LBB0_365
	s_ashr_i32 s65, s64, 31
	v_lshl_add_u64 v[8:9], s[64:65], 0, v[32:33]
	v_lshl_add_u64 v[8:9], v[8:9], 2, s[62:63]
	global_load_dword v8, v[8:9], off offset:192
.LBB0_365:
	s_or_b64 exec, exec, s[0:1]
	s_waitcnt vmcnt(0) lgkmcnt(0)
	v_mul_f32_e32 v4, v4, v8
	v_mul_f32_e32 v5, v5, v8
	v_cndmask_b32_e32 v4, 0, v4, vcc
	v_cndmask_b32_e32 v5, 0, v5, vcc
	v_add_u32_e32 v9, 0xc60, v16
	ds_write2_b32 v9, v4, v5 offset1:1
	v_mul_f32_e32 v4, v6, v8
	v_mul_f32_e32 v5, v7, v8
	v_cndmask_b32_e32 v4, 0, v4, vcc
	v_cndmask_b32_e32 v5, 0, v5, vcc
	v_add_u32_e32 v6, 0xc68, v16
	ds_write2_b32 v6, v4, v5 offset1:1
	v_or_b32_e32 v4, s64, v57
	v_cmp_gt_i32_e32 vcc, s61, v4
	s_and_b64 s[0:1], s[56:57], vcc
	s_xor_b64 s[0:1], s[0:1], -1
	s_and_saveexec_b64 s[30:31], s[0:1]
	s_xor_b64 s[0:1], exec, s[30:31]
	s_ashr_i32 s65, s64, 31
	s_or_saveexec_b64 s[0:1], s[0:1]
	v_mov_b32_e32 v6, 1.0
	v_mov_b64_e32 v[4:5], s[64:65]
	s_xor_b64 exec, exec, s[0:1]
	s_cbranch_execz .LBB0_350
	s_ashr_i32 s65, s64, 31
	v_lshl_add_u64 v[4:5], s[64:65], 0, v[32:33]
	v_lshl_add_u64 v[4:5], v[4:5], 2, s[62:63]
	global_load_dword v6, v[4:5], off offset:224
	v_mov_b64_e32 v[4:5], s[64:65]
	s_branch .LBB0_350

; #define LAS __attribute__((address_space(3)))
; __device__ __forceinline__ void tr_item(const float* W, int Ksrc, int N, int k0, int n0, bf16* dst, int ldt, int drow0, int dcol0, LAS float* scr, int lane, const float* nscale = nullptr, const float* kscale = nullptr) {
;     ...
;     for (int i = 0; i < 8; ++i) { const int kk = 8 * i + kr_; const int kr = (k0 + kk < Ksrc) ? (k0 + kk) : (Ksrc - 1); tv[i] = __builtin_nontemporal_load((const f32x4*)(W + (size_t)kr * N + n0 + 4 * nq_)); }
; #pragma unroll
;     for (int i = 0; i < 8; ++i) { const int kk = 8 * i + kr_; const bool ok = (k0 + kk < Ksrc); LAS float* d_ = scr + kk * 33 + 4 * nq_;
;         const float ks_ = (ok && kscale) ? kscale[k0 + kk] : 1.0f;
;         d_[0] = ok ? tv[i].x * ks_ : 0.f; d_[1] = ok ? tv[i].y * ks_ : 0.f; d_[2] = ok ? tv[i].z * ks_ : 0.f; d_[3] = ok ? tv[i].w * ks_ : 0.f; }
;     asm volatile("s_waitcnt lgkmcnt(0)" ::: "memory");
.LBB0_371:
	s_ashr_i32 s6, s1, 31
	s_lshr_b32 s6, s6, 26
	s_add_i32 s7, s1, s6
	s_lshl_b32 s6, s7, 5
	s_and_b32 s34, s7, 0xffffffc0
	s_and_b32 s6, s6, 0xfffff800
	s_add_i32 s8, s11, s0
	v_or_b32_e32 v45, s34, v32
	s_sub_i32 s8, s8, s6
	v_min_i32_e32 v2, 0x15ff, v45
	s_ashr_i32 s9, s8, 31
	v_ashrrev_i32_e32 v3, 31, v2
	v_lshl_add_u64 v[0:1], s[8:9], 2, v[40:41]
	v_lshlrev_b64 v[2:3], 13, v[2:3]
	v_lshl_add_u64 v[2:3], v[0:1], 0, v[2:3]
	global_load_dwordx4 v[28:31], v[2:3], off nt
	v_or_b32_e32 v2, 8, v45
	v_min_i32_e32 v2, 0x15ff, v2
	v_ashrrev_i32_e32 v3, 31, v2
	v_lshlrev_b64 v[2:3], 13, v[2:3]
	v_lshl_add_u64 v[2:3], v[0:1], 0, v[2:3]
	global_load_dwordx4 v[24:27], v[2:3], off nt
	v_or_b32_e32 v2, 16, v45
	v_min_i32_e32 v2, 0x15ff, v2
	v_ashrrev_i32_e32 v3, 31, v2
	v_lshlrev_b64 v[2:3], 13, v[2:3]
	v_lshl_add_u64 v[2:3], v[0:1], 0, v[2:3]
	global_load_dwordx4 v[20:23], v[2:3], off nt
	v_or_b32_e32 v2, 24, v45
	v_min_i32_e32 v2, 0x15ff, v2
	v_ashrrev_i32_e32 v3, 31, v2
	v_lshlrev_b64 v[2:3], 13, v[2:3]
	v_lshl_add_u64 v[2:3], v[0:1], 0, v[2:3]
	global_load_dwordx4 v[16:19], v[2:3], off nt
	v_or_b32_e32 v2, 32, v45
	v_min_i32_e32 v2, 0x15ff, v2
	v_ashrrev_i32_e32 v3, 31, v2
	v_lshlrev_b64 v[2:3], 13, v[2:3]
	v_lshl_add_u64 v[2:3], v[0:1], 0, v[2:3]
	global_load_dwordx4 v[12:15], v[2:3], off nt
	v_or_b32_e32 v2, 40, v45
	v_min_i32_e32 v2, 0x15ff, v2
	v_ashrrev_i32_e32 v3, 31, v2
	v_lshlrev_b64 v[2:3], 13, v[2:3]
	v_lshl_add_u64 v[2:3], v[0:1], 0, v[2:3]
	global_load_dwordx4 v[8:11], v[2:3], off nt
	v_or_b32_e32 v2, 48, v45
	v_min_i32_e32 v2, 0x15ff, v2
	v_ashrrev_i32_e32 v3, 31, v2
	v_lshlrev_b64 v[2:3], 13, v[2:3]
	v_lshl_add_u64 v[2:3], v[0:1], 0, v[2:3]
	global_load_dwordx4 v[4:7], v[2:3], off nt
	v_or_b32_e32 v2, 56, v45
	v_min_i32_e32 v2, 0x15ff, v2
	v_ashrrev_i32_e32 v3, 31, v2
	v_lshlrev_b64 v[2:3], 13, v[2:3]
	v_lshl_add_u64 v[0:1], v[0:1], 0, v[2:3]
	global_load_dwordx4 v[0:3], v[0:1], off nt
	v_cmp_gt_i32_e32 vcc, s15, v45
	v_add_u32_e32 v45, v35, v37
	s_sub_i32 s6, s11, s6
	s_ashr_i32 s35, s34, 31
	s_add_i32 s1, s1, s14
	s_add_i32 s0, s0, s19
	s_cmpk_lt_i32 s1, 0x1600
	s_waitcnt vmcnt(0) lgkmcnt(0)
	v_cndmask_b32_e32 v28, 0, v28, vcc
	v_cndmask_b32_e32 v29, 0, v29, vcc
	ds_write2_b32 v45, v28, v29 offset1:1
	v_cndmask_b32_e32 v28, 0, v30, vcc
	v_cndmask_b32_e32 v29, 0, v31, vcc
	ds_write2_b32 v45, v28, v29 offset0:2 offset1:3
	v_or_b32_e32 v28, s34, v48
	v_cmp_gt_i32_e32 vcc, s15, v28
	v_add_u32_e32 v28, 0x420, v45
	s_nop 0
	v_cndmask_b32_e32 v24, 0, v24, vcc
	v_cndmask_b32_e32 v25, 0, v25, vcc
	ds_write2_b32 v28, v24, v25 offset1:1
	v_cndmask_b32_e32 v24, 0, v26, vcc
	v_cndmask_b32_e32 v25, 0, v27, vcc
	v_add_u32_e32 v26, 0x428, v45
	ds_write2_b32 v26, v24, v25 offset1:1
	v_or_b32_e32 v24, s34, v50
	v_cmp_gt_i32_e32 vcc, s15, v24
	v_add_u32_e32 v24, 0x840, v45
	s_nop 0
	v_cndmask_b32_e32 v20, 0, v20, vcc
	v_cndmask_b32_e32 v21, 0, v21, vcc
	ds_write2_b32 v24, v20, v21 offset1:1
	v_cndmask_b32_e32 v20, 0, v22, vcc
	v_cndmask_b32_e32 v21, 0, v23, vcc
	v_add_u32_e32 v22, 0x848, v45
	ds_write2_b32 v22, v20, v21 offset1:1
	v_or_b32_e32 v20, s34, v52
	v_cmp_gt_i32_e32 vcc, s15, v20
	v_add_u32_e32 v20, 0xc60, v45
	s_nop 0
	v_cndmask_b32_e32 v16, 0, v16, vcc
	v_cndmask_b32_e32 v17, 0, v17, vcc
	ds_write2_b32 v20, v16, v17 offset1:1
	v_cndmask_b32_e32 v16, 0, v18, vcc
	v_cndmask_b32_e32 v17, 0, v19, vcc
	v_add_u32_e32 v18, 0xc68, v45
	ds_write2_b32 v18, v16, v17 offset1:1
	v_or_b32_e32 v16, s34, v54
	v_cmp_gt_i32_e32 vcc, s15, v16
	v_add_u32_e32 v16, 0x1080, v45
	s_nop 0
	v_cndmask_b32_e32 v12, 0, v12, vcc
	v_cndmask_b32_e32 v13, 0, v13, vcc
	ds_write2_b32 v16, v12, v13 offset1:1
	v_cndmask_b32_e32 v12, 0, v14, vcc
	v_cndmask_b32_e32 v13, 0, v15, vcc
	v_add_u32_e32 v14, 0x1088, v45
	ds_write2_b32 v14, v12, v13 offset1:1
	v_or_b32_e32 v12, s34, v55
	v_cmp_gt_i32_e32 vcc, s15, v12
	v_add_u32_e32 v12, 0x14a0, v45
	s_nop 0
	v_cndmask_b32_e32 v8, 0, v8, vcc
	v_cndmask_b32_e32 v9, 0, v9, vcc
	ds_write2_b32 v12, v8, v9 offset1:1
	v_cndmask_b32_e32 v8, 0, v10, vcc
	v_cndmask_b32_e32 v9, 0, v11, vcc
	v_add_u32_e32 v10, 0x14a8, v45
	ds_write2_b32 v10, v8, v9 offset1:1
	v_or_b32_e32 v8, s34, v56
	v_cmp_gt_i32_e32 vcc, s15, v8
	v_add_u32_e32 v8, 0x18c0, v45
	s_nop 0
	v_cndmask_b32_e32 v4, 0, v4, vcc
	v_cndmask_b32_e32 v5, 0, v5, vcc
	ds_write2_b32 v8, v4, v5 offset1:1
	v_cndmask_b32_e32 v4, 0, v6, vcc
	v_cndmask_b32_e32 v5, 0, v7, vcc
	v_add_u32_e32 v6, 0x18c8, v45
	ds_write2_b32 v6, v4, v5 offset1:1
	v_or_b32_e32 v4, s34, v57
	v_cmp_gt_i32_e32 vcc, s15, v4
	v_add_u32_e32 v4, 0x1ce0, v45
	v_add_u32_e32 v8, s6, v44
	v_cndmask_b32_e32 v0, 0, v0, vcc
	v_cndmask_b32_e32 v1, 0, v1, vcc
	ds_write2_b32 v4, v0, v1 offset1:1
	v_cndmask_b32_e32 v0, 0, v2, vcc
	v_cndmask_b32_e32 v1, 0, v3, vcc
	v_add_u32_e32 v2, 0x1ce8, v45
	ds_write2_b32 v2, v0, v1 offset1:1
	s_waitcnt lgkmcnt(0)
; __device__ __forceinline__ unsigned pk_bf16(float lo, float hi) { f32x2e v = {lo, hi}; bf16x2e b = __builtin_convertvector(v, bf16x2e); return __builtin_bit_cast(unsigned, b); }
; #define LAS __attribute__((address_space(3)))
; __device__ __forceinline__ void tr_item(const float* W, int Ksrc, int N, int k0, int n0, bf16* dst, int ldt, int drow0, int dcol0, LAS float* scr, int lane, const float* nscale = nullptr, const float* kscale = nullptr) {
;     ...
;     const int c = lane & 7;
; #pragma unroll
;     for (int j = 0; j < 4; ++j) { const int n = (lane >> 3) + 8 * j; const LAS float* s = scr + (8 * c) * 33 + n;
;         const float sc = nscale ? nscale[n0 + n] : 1.0f;
;         u32x4 o; o.x = pk_bf16(s[0 * 33] * sc, s[1 * 33] * sc); o.y = pk_bf16(s[2 * 33] * sc, s[3 * 33] * sc); o.z = pk_bf16(s[4 * 33] * sc, s[5 * 33] * sc); o.w = pk_bf16(s[6 * 33] * sc, s[7 * 33] * sc);
;         *(u32x4*)(dst + (size_t)(drow0 + n) * ldt + dcol0 + k0 + 8 * c) = o; }
;     asm volatile("s_waitcnt lgkmcnt(0)" ::: "memory");
	ds_read_b32 v0, v58
	ds_read_b32 v1, v58 offset:132
	v_lshl_add_u64 v[4:5], s[34:35], 1, v[42:43]
	v_add_u32_e32 v44, s19, v44
	s_waitcnt lgkmcnt(0)
	v_cvt_pk_bf16_f32 v0, v0, v1
	ds_read_b32 v1, v58 offset:264
	ds_read_b32 v2, v58 offset:396
	s_waitcnt lgkmcnt(0)
	v_cvt_pk_bf16_f32 v1, v1, v2
	ds_read_b32 v2, v58 offset:528
	ds_read_b32 v3, v58 offset:660
	s_waitcnt lgkmcnt(0)
	v_cvt_pk_bf16_f32 v2, v2, v3
	ds_read_b32 v3, v58 offset:792
	ds_read_b32 v6, v58 offset:924
	s_waitcnt lgkmcnt(0)
	v_cvt_pk_bf16_f32 v3, v3, v6
	v_add_u32_e32 v6, 0xffffc000, v8
	v_mad_i64_i32 v[6:7], s[6:7], v6, s28, v[4:5]
	global_store_dwordx4 v[6:7], v[0:3], off
	ds_read_b32 v0, v58 offset:32
	ds_read_b32 v1, v58 offset:164
	s_waitcnt lgkmcnt(0)
	v_cvt_pk_bf16_f32 v0, v0, v1
	ds_read_b32 v1, v58 offset:296
	ds_read_b32 v2, v58 offset:428
	s_waitcnt lgkmcnt(0)
	v_cvt_pk_bf16_f32 v1, v1, v2
	ds_read_b32 v2, v58 offset:560
	ds_read_b32 v3, v58 offset:692
	s_waitcnt lgkmcnt(0)
	v_cvt_pk_bf16_f32 v2, v2, v3
	ds_read_b32 v3, v58 offset:824
	ds_read_b32 v6, v58 offset:956
	s_waitcnt lgkmcnt(0)
	v_cvt_pk_bf16_f32 v3, v3, v6
	v_add_u32_e32 v6, 0xffffc008, v8
	v_mad_i64_i32 v[6:7], s[6:7], v6, s28, v[4:5]
	global_store_dwordx4 v[6:7], v[0:3], off
	ds_read_b32 v0, v58 offset:64
	ds_read_b32 v1, v58 offset:196
	s_waitcnt lgkmcnt(0)
	v_cvt_pk_bf16_f32 v0, v0, v1
	ds_read_b32 v1, v58 offset:328
	ds_read_b32 v2, v58 offset:460
	s_waitcnt lgkmcnt(0)
	v_cvt_pk_bf16_f32 v1, v1, v2
	ds_read_b32 v2, v58 offset:592
	ds_read_b32 v3, v58 offset:724
	s_waitcnt lgkmcnt(0)
	v_cvt_pk_bf16_f32 v2, v2, v3
	ds_read_b32 v3, v58 offset:856
	ds_read_b32 v6, v58 offset:988
	s_waitcnt lgkmcnt(0)
	v_cvt_pk_bf16_f32 v3, v3, v6
	v_add_u32_e32 v6, 0xffffc010, v8
	v_mad_i64_i32 v[6:7], s[6:7], v6, s28, v[4:5]
	global_store_dwordx4 v[6:7], v[0:3], off
	ds_read_b32 v0, v58 offset:96
	ds_read_b32 v1, v58 offset:228
	s_waitcnt lgkmcnt(0)
	v_cvt_pk_bf16_f32 v0, v0, v1
	ds_read_b32 v1, v58 offset:360
	ds_read_b32 v2, v58 offset:492
	s_waitcnt lgkmcnt(0)
	v_cvt_pk_bf16_f32 v1, v1, v2
	ds_read_b32 v2, v58 offset:624
	ds_read_b32 v3, v58 offset:756
	s_waitcnt lgkmcnt(0)
	v_cvt_pk_bf16_f32 v2, v2, v3
	ds_read_b32 v3, v58 offset:888
	ds_read_b32 v6, v58 offset:1020
	s_waitcnt lgkmcnt(0)
	v_cvt_pk_bf16_f32 v3, v3, v6
	v_add_u32_e32 v6, 0xffffc018, v8
	v_mad_i64_i32 v[4:5], s[6:7], v6, s28, v[4:5]
	global_store_dwordx4 v[4:5], v[0:3], off
	s_waitcnt lgkmcnt(0)
	s_cbranch_scc1 .LBB0_371
	s_branch .LBB0_326

; #define LAS __attribute__((address_space(3)))
; __device__ __forceinline__ void sc2_issue(u32x4 (&R)[SG_NL], const unsigned char* ops, const unsigned char* sv, int grp, int lt) {
;     if (grp > 63) grp = 63;
;     const unsigned char* og = ops + (size_t)grp * SG_OPS; const unsigned char* vg = sv + (size_t)grp * (SG * 2048);
; #pragma unroll
;     for (int i = 0; i < SG_NL; ++i) { int idx = lt + 256 * i; idx = idx < SG_N16 ? idx : SG_N16 - 1;
;         const unsigned char* p = (idx < SG_OPS / 16) ? (og + (size_t)idx * 16) : (vg + (size_t)(idx - SG_OPS / 16) * 16); R[i] = *(const u32x4*)p; }
; }
; __device__ __forceinline__ void sc2_commit(const u32x4 (&R)[SG_NL], LAS unsigned char* buf, int lt) {
; #pragma unroll
;     for (int i = 0; i < SG_NL; ++i) { int idx = lt + 256 * i; idx = idx < SG_N16 ? idx : SG_N16 - 1; *(LAS u32x4*)(buf + idx * 16) = R[i]; }
; }
; __device__ __forceinline__ void scan2_phase(LAS unsigned char* lds, const unsigned char* OPS, const bf16* SV, bf16* mix, int bid, int G, int tid) {
;     ...
;     for (int bh = bid; bh < 64; bh += G) { const int b = bh >> 4, h = bh & 15;
;         const unsigned char* ops = OPS + (size_t)bh * 256 * PCI_BYTES; const unsigned char* sv = (const unsigned char*)(SV + (size_t)bh * SEQ * 64);
;         bf16* ybase = mix + (size_t)(b * SEQ) * D + 1024 + h * 64 + (wid & 3) * 16 + (lane & 15);
;         u32x4 ra[SG_NL], rb[SG_NL]; f32x4 Z[4];
; #pragma unroll
;         for (int kt = 0; kt < 4; ++kt) Z[kt] = (f32x4){0.f, 0.f, 0.f, 0.f};
;         if (loader) { sc2_issue(ra, ops, sv, 0, lt); sc2_issue(rb, ops, sv, 1, lt); sc2_commit(ra, buf0, lt); sc2_issue(ra, ops, sv, 2, lt); }
.LBB0_376:
	s_ashr_i32 s43, s42, 31
	s_mul_i32 s6, s42, 0x290000
	s_lshl_b64 s[0:1], s[42:43], 19
	v_readlane_b32 s30, v255, 5
	s_mul_hi_i32 s5, s42, 0x290000
	v_readlane_b32 s31, v255, 6
	s_add_u32 s56, s30, s6
	s_addc_u32 s57, s31, s5
	s_add_u32 s62, s80, s0
	s_addc_u32 s63, s81, s1
	s_andn2_b64 vcc, exec, s[34:35]
	v_add_u32_e32 v160, 0, v142
	s_cbranch_vccnz .LBB0_378
	s_waitcnt vmcnt(0)
	v_lshl_add_u64 v[0:1], s[56:57], 0, v[140:141]
	v_add_co_u32_e32 v2, vcc, 0x1000, v0
	s_add_u32 s0, s56, 0xa400
	s_nop 0
	v_addc_co_u32_e32 v3, vcc, 0, v1, vcc
	global_load_dwordx4 v[40:43], v[0:1], off
	global_load_dwordx4 v[44:47], v[2:3], off
	v_add_co_u32_e32 v2, vcc, 0x2000, v0
	s_addc_u32 s1, s57, 0
	s_nop 0
	v_addc_co_u32_e32 v3, vcc, 0, v1, vcc
	v_add_co_u32_e32 v4, vcc, 0x3000, v0
	v_lshl_add_u64 v[32:33], s[0:1], 0, v[140:141]
	s_nop 0
	v_addc_co_u32_e32 v5, vcc, 0, v1, vcc
	global_load_dwordx4 v[56:59], v[2:3], off
	global_load_dwordx4 v[64:67], v[4:5], off
	v_add_co_u32_e32 v2, vcc, s11, v0
	s_add_u32 s6, s62, 0x2000
	s_nop 0
	v_addc_co_u32_e32 v3, vcc, 0, v1, vcc
	v_add_co_u32_e32 v4, vcc, 0x5000, v0
	s_addc_u32 s7, s63, 0
	s_nop 0
	v_addc_co_u32_e32 v5, vcc, 0, v1, vcc
	global_load_dwordx4 v[68:71], v[2:3], off
	global_load_dwordx4 v[72:75], v[4:5], off
	v_add_co_u32_e32 v2, vcc, 0x6000, v0
	v_lshl_add_u64 v[54:55], s[6:7], 0, v[142:143]
	s_nop 0
	v_addc_co_u32_e32 v3, vcc, 0, v1, vcc
	v_add_co_u32_e32 v4, vcc, s17, v0
	v_lshl_add_u64 v[48:49], s[0:1], 0, v[146:147]
	s_nop 0
	v_addc_co_u32_e32 v5, vcc, 0, v1, vcc
	global_load_dwordx4 v[76:79], v[2:3], off
	global_load_dwordx4 v[80:83], v[4:5], off
	v_add_co_u32_e32 v2, vcc, s9, v0
	v_lshl_add_u64 v[50:51], s[6:7], 0, v[144:145]
	s_nop 0
	v_addc_co_u32_e32 v3, vcc, 0, v1, vcc
	v_add_co_u32_e32 v0, vcc, 0x9000, v0
	s_add_u32 s0, s56, 0x14800
	s_nop 0
	v_addc_co_u32_e32 v1, vcc, 0, v1, vcc
	global_load_dwordx4 v[84:87], v[2:3], off
	global_load_dwordx4 v[88:91], v[0:1], off
	v_lshl_add_u64 v[0:1], s[56:57], 0, v[146:147]
	v_lshl_add_u64 v[2:3], s[62:63], 0, v[144:145]
	v_cndmask_b32_e64 v1, v3, v1, s[38:39]
	v_cndmask_b32_e64 v0, v2, v0, s[38:39]
	v_lshl_add_u64 v[2:3], s[62:63], 0, v[142:143]
	global_load_dwordx4 v[92:95], v[0:1], off
	v_lshl_add_u64 v[0:1], s[62:63], 0, v[140:141]
	v_add_co_u32_e32 v2, vcc, s28, v2
	v_cndmask_b32_e64 v49, v51, v49, s[38:39]
	s_nop 0
	v_addc_co_u32_e32 v3, vcc, -1, v3, vcc
	global_load_dwordx4 v[98:101], v[0:1], off offset:3072
	global_load_dwordx4 v[102:105], v[2:3], off
	v_add_co_u32_e32 v4, vcc, s55, v32
	v_cndmask_b32_e64 v48, v50, v48, s[38:39]
	s_nop 0
	v_addc_co_u32_e32 v5, vcc, 0, v33, vcc
	v_add_co_u32_e32 v8, vcc, s13, v32
	v_lshl_add_u64 v[52:53], s[6:7], 0, v[140:141]
	s_nop 0
	v_addc_co_u32_e32 v9, vcc, 0, v33, vcc
	v_add_co_u32_e32 v12, vcc, s54, v32
	s_addc_u32 s1, s57, 0
	s_nop 0
	v_addc_co_u32_e32 v13, vcc, 0, v33, vcc
	v_add_co_u32_e32 v16, vcc, s11, v32
	global_load_dwordx4 v[0:3], v[32:33], off
	s_nop 0
	global_load_dwordx4 v[4:7], v[4:5], off
	v_addc_co_u32_e32 v17, vcc, 0, v33, vcc
	v_add_co_u32_e32 v20, vcc, s14, v32
	global_load_dwordx4 v[8:11], v[8:9], off
	s_nop 0
	global_load_dwordx4 v[12:15], v[12:13], off
	v_addc_co_u32_e32 v21, vcc, 0, v33, vcc
	v_add_co_u32_e32 v24, vcc, s15, v32
	global_load_dwordx4 v[16:19], v[16:17], off
	s_nop 0
	global_load_dwordx4 v[20:23], v[20:21], off
	v_addc_co_u32_e32 v25, vcc, 0, v33, vcc
	v_add_co_u32_e32 v28, vcc, s17, v32
	s_add_u32 s6, s62, 0x4000
	s_nop 0
	v_addc_co_u32_e32 v29, vcc, 0, v33, vcc
	v_add_co_u32_e32 v34, vcc, s9, v32
	global_load_dwordx4 v[24:27], v[24:25], off
	s_nop 0
	global_load_dwordx4 v[28:31], v[28:29], off
	v_addc_co_u32_e32 v35, vcc, 0, v33, vcc
	v_add_co_u32_e32 v36, vcc, s19, v32
	s_addc_u32 s7, s63, 0
	s_nop 0
	v_addc_co_u32_e32 v37, vcc, 0, v33, vcc
	v_add_co_u32_e32 v60, vcc, s28, v54
	global_load_dwordx4 v[32:35], v[34:35], off
	s_nop 0
	global_load_dwordx4 v[36:39], v[36:37], off
	v_addc_co_u32_e32 v61, vcc, -1, v55, vcc
	global_load_dwordx4 v[48:51], v[48:49], off
	s_nop 0
	global_load_dwordx4 v[52:55], v[52:53], off offset:3072
	s_nop 0
	global_load_dwordx4 v[60:63], v[60:61], off
	s_waitcnt vmcnt(0) lgkmcnt(0)
	ds_write_b128 v152, v[40:43]
	ds_write_b128 v152, v[44:47] offset:4096
	ds_write_b128 v152, v[56:59] offset:8192
	ds_write_b128 v152, v[64:67] offset:12288
	ds_write_b128 v152, v[68:71] offset:16384
	ds_write_b128 v152, v[72:75] offset:20480
	ds_write_b128 v152, v[76:79] offset:24576
	ds_write_b128 v152, v[80:83] offset:28672
	ds_write_b128 v152, v[84:87] offset:32768
	ds_write_b128 v152, v[88:91] offset:36864
	ds_write_b128 v152, v[92:95] offset:40960
	ds_write_b128 v152, v[98:101] offset:45056
	ds_write_b128 v160, v[102:105]
	v_lshl_add_u64 v[84:85], s[0:1], 0, v[140:141]
	v_add_co_u32_e32 v44, vcc, s55, v84
	v_lshl_add_u64 v[100:101], s[6:7], 0, v[142:143]
	s_nop 0
	v_addc_co_u32_e32 v45, vcc, 0, v85, vcc
	v_add_co_u32_e32 v56, vcc, s13, v84
	v_lshl_add_u64 v[92:93], s[0:1], 0, v[146:147]
	s_nop 0
	v_addc_co_u32_e32 v57, vcc, 0, v85, vcc
	v_add_co_u32_e32 v64, vcc, s54, v84
	v_lshl_add_u64 v[94:95], s[6:7], 0, v[144:145]
	s_nop 0
	v_addc_co_u32_e32 v65, vcc, 0, v85, vcc
	v_add_co_u32_e32 v68, vcc, s11, v84
	v_cndmask_b32_e64 v93, v95, v93, s[38:39]
	s_nop 0
	v_addc_co_u32_e32 v69, vcc, 0, v85, vcc
	v_add_co_u32_e32 v72, vcc, s14, v84
	v_cndmask_b32_e64 v92, v94, v92, s[38:39]
	s_nop 0
	v_addc_co_u32_e32 v73, vcc, 0, v85, vcc
	v_add_co_u32_e32 v76, vcc, s15, v84
	v_lshl_add_u64 v[98:99], s[6:7], 0, v[140:141]
	s_nop 0
	v_addc_co_u32_e32 v77, vcc, 0, v85, vcc
	v_add_co_u32_e32 v80, vcc, s17, v84
	global_load_dwordx4 v[40:43], v[84:85], off
	s_nop 0
	global_load_dwordx4 v[44:47], v[44:45], off
	v_addc_co_u32_e32 v81, vcc, 0, v85, vcc
	v_add_co_u32_e32 v86, vcc, s9, v84
	global_load_dwordx4 v[56:59], v[56:57], off
	s_nop 0
	global_load_dwordx4 v[64:67], v[64:65], off
	v_addc_co_u32_e32 v87, vcc, 0, v85, vcc
	v_add_co_u32_e32 v88, vcc, s19, v84
	global_load_dwordx4 v[68:71], v[68:69], off
	s_nop 0
	global_load_dwordx4 v[72:75], v[72:73], off
	v_addc_co_u32_e32 v89, vcc, 0, v85, vcc
	v_add_co_u32_e32 v104, vcc, 0xffff5c00, v100
	global_load_dwordx4 v[76:79], v[76:77], off
	s_nop 0
	global_load_dwordx4 v[80:83], v[80:81], off
	v_addc_co_u32_e32 v105, vcc, -1, v101, vcc
	global_load_dwordx4 v[84:87], v[86:87], off
	s_nop 0
	global_load_dwordx4 v[88:91], v[88:89], off
	s_nop 0
	global_load_dwordx4 v[92:95], v[92:93], off
	s_nop 0
	global_load_dwordx4 v[100:103], v[98:99], off offset:3072
	s_nop 0
	global_load_dwordx4 v[104:107], v[104:105], off

; #define LAS __attribute__((address_space(3)))
; __device__ __forceinline__ void sc2_compute(f32x4 (&Z)[4], const LAS unsigned char* buf, bf16* yout, int lane, int vq) {
;     ...
;     for (int ci = 0; ci < SG; ++ci) { const LAS unsigned char* ob = buf + ci * PCI_BYTES + lane * 16;
;         const bf16x8 op1_0 = *(const LAS bf16x8*)ob, op1_1 = *(const LAS bf16x8*)(ob + 1024), op3_0 = *(const LAS bf16x8*)(ob + 2048), op3_1 = *(const LAS bf16x8*)(ob + 3072),
;                      op2 = *(const LAS bf16x8*)(ob + 4096), op4 = *(const LAS bf16x8*)(ob + 5120);
;         const LAS unsigned short* vp = (const LAS unsigned short*)(buf + SG_OPS + ((ci * 16 + 4 * g) * 64 + vq * 16 + m) * 2);
;         const short v0 = (short)vp[0], v1 = (short)vp[64], v2 = (short)vp[128], v3 = (short)vp[192];
;         const bf16x8 zb0 = __builtin_bit_cast(bf16x8, pack8v(Z[0], Z[1])), zb1 = __builtin_bit_cast(bf16x8, pack8v(Z[2], Z[3]));
;         f32x4 Gm = __builtin_amdgcn_mfma_f32_16x16x32_bf16(op1_0, zb0, zero, 0, 0, 0); Gm = __builtin_amdgcn_mfma_f32_16x16x32_bf16(op1_1, zb1, Gm, 0, 0, 0);
;         f32x4 Y = __builtin_amdgcn_mfma_f32_16x16x32_bf16(op3_0, zb0, zero, 0, 0, 0); Y = __builtin_amdgcn_mfma_f32_16x16x32_bf16(op3_1, zb1, Y, 0, 0, 0);
;         const unsigned g01 = pk_bf16(Gm.x, Gm.y), g23 = pk_bf16(Gm.z, Gm.w);
;         bf16x8 B2; B2[0] = (short)(g01 & 0xffff); B2[1] = (short)(g01 >> 16); B2[2] = (short)(g23 & 0xffff); B2[3] = (short)(g23 >> 16); B2[4] = v0; B2[5] = v1; B2[6] = v2; B2[7] = v3;
;         const f32x4 U = __builtin_amdgcn_mfma_f32_16x16x32_bf16(op2, B2, zero, 0, 0, 0);
;         const unsigned u01 = pk_bf16(U.x, U.y), u23 = pk_bf16(U.z, U.w);
;         bf16x8 B3; B3[0] = v0; B3[1] = v1; B3[2] = v2; B3[3] = v3; B3[4] = (short)(u01 & 0xffff); B3[5] = (short)(u01 >> 16); B3[6] = (short)(u23 & 0xffff); B3[7] = (short)(u23 >> 16);
;         Y = __builtin_amdgcn_mfma_f32_16x16x32_bf16(op4, B3, Y, 0, 0, 0);
; #pragma unroll
;         for (int kt = 0; kt < 4; ++kt) { const bf16x8 op5 = *(const LAS bf16x8*)(ob + (6 + kt) * 1024); const f32x4 pc = *(const LAS f32x4*)(buf + ci * PCI_BYTES + 10240 + (16 * kt + 4 * g) * 4);
;             Z[kt] = __builtin_amdgcn_mfma_f32_16x16x32_bf16(op5, B3, Z[kt] * pc, 0, 0, 0); }
;         bf16* yp = yout + (size_t)(ci * 16 + 4 * g) * D;
;         yp[0] = f2bf(Y.x); yp[D] = f2bf(Y.y); yp[2 * D] = f2bf(Y.z); yp[3 * D] = f2bf(Y.w); }
.LBB0_381:
	ds_read_b128 v[162:165], v96
	ds_read_b128 v[166:169], v96 offset:1024
	ds_read_b128 v[170:173], v96 offset:2048
	ds_read_b128 v[174:177], v96 offset:3072
	ds_read_b128 v[178:181], v96 offset:4096
	ds_read_b128 v[186:189], v96 offset:5120
	ds_read_u16 v161, v99
	ds_read_u16 v182, v99 offset:128
	ds_read_u16 v183, v99 offset:256
	ds_read_u16 v184, v99 offset:384
	v_cvt_pk_bf16_f32 v190, v124, v125
	v_cvt_pk_bf16_f32 v191, v126, v127
	v_cvt_pk_bf16_f32 v192, v128, v129
	v_cvt_pk_bf16_f32 v193, v130, v131
	v_cvt_pk_bf16_f32 v202, v132, v133
	v_cvt_pk_bf16_f32 v203, v134, v135
	s_waitcnt lgkmcnt(0)
	v_mfma_f32_16x16x32_bf16 v[162:165], v[162:165], v[190:193], 0
	v_cvt_pk_bf16_f32 v204, v136, v137
	v_cvt_pk_bf16_f32 v205, v138, v139
	v_add_u32_e32 v99, 0x800, v99
	s_nop 0
	v_mfma_f32_16x16x32_bf16 v[162:165], v[166:169], v[202:205], v[162:165]
	v_mfma_f32_16x16x32_bf16 v[166:169], v[170:173], v[190:193], 0
	s_nop 6
	v_cvt_pk_bf16_f32 v162, v162, v163
	v_cvt_pk_bf16_f32 v163, v164, v165
	v_perm_b32 v165, v184, v183, s48
	v_perm_b32 v164, v182, v161, s48
	s_nop 1
	v_mfma_f32_16x16x32_bf16 v[170:173], v[178:181], v[162:165], 0
	v_mov_b32_e32 v178, v164
	v_mov_b32_e32 v179, v165
	s_nop 5
	v_cvt_pk_bf16_f32 v180, v170, v171
	v_cvt_pk_bf16_f32 v181, v172, v173
	ds_read_b128 v[162:165], v96 offset:6144
	ds_read_b128 v[170:173], v98
	s_waitcnt lgkmcnt(0)
	v_pk_mul_f32 v[126:127], v[126:127], v[172:173]
	v_pk_mul_f32 v[124:125], v[124:125], v[170:171]
	s_nop 1
	v_mfma_f32_16x16x32_bf16 v[124:127], v[162:165], v[178:181], v[124:127]
	ds_read_b128 v[162:165], v96 offset:7168
	ds_read_b128 v[170:173], v98 offset:64
	s_waitcnt lgkmcnt(0)
	v_pk_mul_f32 v[130:131], v[130:131], v[172:173]
	v_pk_mul_f32 v[128:129], v[128:129], v[170:171]
	s_nop 1
	v_mfma_f32_16x16x32_bf16 v[128:131], v[162:165], v[178:181], v[128:131]
	ds_read_b128 v[162:165], v96 offset:8192
	ds_read_b128 v[170:173], v98 offset:128
	s_waitcnt lgkmcnt(0)
	v_pk_mul_f32 v[134:135], v[134:135], v[172:173]
	v_pk_mul_f32 v[132:133], v[132:133], v[170:171]
	s_nop 1
	v_mfma_f32_16x16x32_bf16 v[132:135], v[162:165], v[178:181], v[132:135]
	ds_read_b128 v[162:165], v96 offset:9216
	ds_read_b128 v[170:173], v98 offset:192
	v_add_u32_e32 v98, 0x2900, v98
	v_add_u32_e32 v96, 0x2900, v96
	s_waitcnt lgkmcnt(0)
	v_pk_mul_f32 v[138:139], v[138:139], v[172:173]
	v_pk_mul_f32 v[136:137], v[136:137], v[170:171]
	s_nop 1
	v_mfma_f32_16x16x32_bf16 v[136:139], v[162:165], v[178:181], v[136:139]
	v_mfma_f32_16x16x32_bf16 v[162:165], v[174:177], v[202:205], v[166:169]
	v_mfma_f32_16x16x32_bf16 v[162:165], v[186:189], v[178:181], v[162:165]
	s_nop 1
	v_lshl_add_u64 v[166:167], v[150:151], 0, s[64:65]
	s_add_u32 s64, s64, 0x10000
	s_addc_u32 s65, s65, 0
	s_cmp_eq_u32 s64, 0x40000
	s_nop 1
	v_cvt_pk_bf16_f32 v161, v162, s0
	v_add_co_u32_e32 v162, vcc, s55, v166
	global_store_short v[166:167], v161, off offset:2048
	v_cvt_pk_bf16_f32 v161, v163, s0
	v_addc_co_u32_e32 v163, vcc, 0, v167, vcc
	global_store_short v[162:163], v161, off offset:2048
	v_add_co_u32_e32 v162, vcc, s13, v166
	v_cvt_pk_bf16_f32 v161, v164, s0
	s_nop 0
	v_addc_co_u32_e32 v163, vcc, 0, v167, vcc
	global_store_short v[162:163], v161, off offset:2048
	v_add_co_u32_e32 v162, vcc, s54, v166
	v_cvt_pk_bf16_f32 v161, v165, s0
	s_nop 0
	v_addc_co_u32_e32 v163, vcc, 0, v167, vcc
	global_store_short v[162:163], v161, off offset:2048
	s_cbranch_scc0 .LBB0_381
	s_mov_b64 s[0:1], 0
.LBB0_383:
	s_and_b64 vcc, exec, s[0:1]
	s_cbranch_vccz .LBB0_385
	s_min_u32 s0, s5, 60
	s_add_i32 s6, s0, 3
	s_mul_i32 s0, s6, 0xa400
	s_add_u32 s0, s56, s0
	s_addc_u32 s1, s57, 0
	s_waitcnt vmcnt(0)
	ds_write_b128 v152, v[0:3] offset:50176
	ds_write_b128 v152, v[4:7] offset:54272
	ds_write_b128 v152, v[8:11] offset:58368
	ds_write_b128 v152, v[12:15] offset:62464
	ds_write_b128 v153, v[16:19] offset:16384
	ds_write_b128 v153, v[20:23] offset:20480
	ds_write_b128 v153, v[24:27] offset:24576
	ds_write_b128 v153, v[28:31] offset:28672
	ds_write_b128 v153, v[32:35] offset:32768
	ds_write_b128 v153, v[36:39] offset:36864
	ds_write_b128 v153, v[48:51] offset:40960
	ds_write_b128 v153, v[52:55] offset:45056
	ds_write_b128 v160, v[60:63] offset:50176
	v_lshl_add_u64 v[32:33], s[0:1], 0, v[140:141]
	v_add_co_u32_e32 v4, vcc, s55, v32
	s_lshl_b32 s6, s6, 13
	s_nop 0
	v_addc_co_u32_e32 v5, vcc, 0, v33, vcc
	v_add_co_u32_e32 v8, vcc, s13, v32
	s_add_u32 s6, s62, s6
	s_nop 0
	v_addc_co_u32_e32 v9, vcc, 0, v33, vcc
	v_add_co_u32_e32 v12, vcc, s54, v32
	s_addc_u32 s7, s63, 0
	s_nop 0
	v_addc_co_u32_e32 v13, vcc, 0, v33, vcc
	v_add_co_u32_e32 v16, vcc, s11, v32
	v_lshl_add_u64 v[54:55], s[6:7], 0, v[142:143]
	s_nop 0
	v_addc_co_u32_e32 v17, vcc, 0, v33, vcc
	v_add_co_u32_e32 v20, vcc, s14, v32
	v_lshl_add_u64 v[48:49], s[0:1], 0, v[146:147]
	s_nop 0
	v_addc_co_u32_e32 v21, vcc, 0, v33, vcc
	v_add_co_u32_e32 v24, vcc, s15, v32
	v_lshl_add_u64 v[50:51], s[6:7], 0, v[144:145]
	s_nop 0
	v_addc_co_u32_e32 v25, vcc, 0, v33, vcc
	v_add_co_u32_e32 v28, vcc, s17, v32
	v_cndmask_b32_e64 v49, v51, v49, s[38:39]
	s_nop 0
	v_addc_co_u32_e32 v29, vcc, 0, v33, vcc
	v_add_co_u32_e32 v34, vcc, s9, v32
	v_cndmask_b32_e64 v48, v50, v48, s[38:39]
	s_nop 0
	v_addc_co_u32_e32 v35, vcc, 0, v33, vcc
	v_add_co_u32_e32 v36, vcc, s19, v32
	v_lshl_add_u64 v[52:53], s[6:7], 0, v[140:141]
	s_nop 0
	v_addc_co_u32_e32 v37, vcc, 0, v33, vcc
	v_add_co_u32_e32 v60, vcc, 0xffff5c00, v54
	global_load_dwordx4 v[0:3], v[32:33], off
	s_nop 0
	global_load_dwordx4 v[4:7], v[4:5], off
	v_addc_co_u32_e32 v61, vcc, -1, v55, vcc
	global_load_dwordx4 v[8:11], v[8:9], off
	s_nop 0
	global_load_dwordx4 v[12:15], v[12:13], off
	s_nop 0
	global_load_dwordx4 v[16:19], v[16:17], off
	s_nop 0
	global_load_dwordx4 v[20:23], v[20:21], off
	s_nop 0
	global_load_dwordx4 v[24:27], v[24:25], off
	s_nop 0
	global_load_dwordx4 v[28:31], v[28:29], off
	s_nop 0
	global_load_dwordx4 v[32:35], v[34:35], off
	s_nop 0
	global_load_dwordx4 v[36:39], v[36:37], off
	s_nop 0
	global_load_dwordx4 v[48:51], v[48:49], off
	s_nop 0
	global_load_dwordx4 v[52:55], v[52:53], off offset:3072
	s_nop 0
	global_load_dwordx4 v[60:63], v[60:61], off
	s_branch .LBB0_386

; #define LAS __attribute__((address_space(3)))
; __device__ __forceinline__ void sc2_compute(f32x4 (&Z)[4], const LAS unsigned char* buf, bf16* yout, int lane, int vq) {
;     ...
;     for (int ci = 0; ci < SG; ++ci) { const LAS unsigned char* ob = buf + ci * PCI_BYTES + lane * 16;
;         const bf16x8 op1_0 = *(const LAS bf16x8*)ob, op1_1 = *(const LAS bf16x8*)(ob + 1024), op3_0 = *(const LAS bf16x8*)(ob + 2048), op3_1 = *(const LAS bf16x8*)(ob + 3072),
;                      op2 = *(const LAS bf16x8*)(ob + 4096), op4 = *(const LAS bf16x8*)(ob + 5120);
;         const LAS unsigned short* vp = (const LAS unsigned short*)(buf + SG_OPS + ((ci * 16 + 4 * g) * 64 + vq * 16 + m) * 2);
;         const short v0 = (short)vp[0], v1 = (short)vp[64], v2 = (short)vp[128], v3 = (short)vp[192];
;         const bf16x8 zb0 = __builtin_bit_cast(bf16x8, pack8v(Z[0], Z[1])), zb1 = __builtin_bit_cast(bf16x8, pack8v(Z[2], Z[3]));
;         f32x4 Gm = __builtin_amdgcn_mfma_f32_16x16x32_bf16(op1_0, zb0, zero, 0, 0, 0); Gm = __builtin_amdgcn_mfma_f32_16x16x32_bf16(op1_1, zb1, Gm, 0, 0, 0);
;         f32x4 Y = __builtin_amdgcn_mfma_f32_16x16x32_bf16(op3_0, zb0, zero, 0, 0, 0); Y = __builtin_amdgcn_mfma_f32_16x16x32_bf16(op3_1, zb1, Y, 0, 0, 0);
;         const unsigned g01 = pk_bf16(Gm.x, Gm.y), g23 = pk_bf16(Gm.z, Gm.w);
;         bf16x8 B2; B2[0] = (short)(g01 & 0xffff); B2[1] = (short)(g01 >> 16); B2[2] = (short)(g23 & 0xffff); B2[3] = (short)(g23 >> 16); B2[4] = v0; B2[5] = v1; B2[6] = v2; B2[7] = v3;
;         const f32x4 U = __builtin_amdgcn_mfma_f32_16x16x32_bf16(op2, B2, zero, 0, 0, 0);
;         const unsigned u01 = pk_bf16(U.x, U.y), u23 = pk_bf16(U.z, U.w);
;         bf16x8 B3; B3[0] = v0; B3[1] = v1; B3[2] = v2; B3[3] = v3; B3[4] = (short)(u01 & 0xffff); B3[5] = (short)(u01 >> 16); B3[6] = (short)(u23 & 0xffff); B3[7] = (short)(u23 >> 16);
;         Y = __builtin_amdgcn_mfma_f32_16x16x32_bf16(op4, B3, Y, 0, 0, 0);
; #pragma unroll
;         for (int kt = 0; kt < 4; ++kt) { const bf16x8 op5 = *(const LAS bf16x8*)(ob + (6 + kt) * 1024); const f32x4 pc = *(const LAS f32x4*)(buf + ci * PCI_BYTES + 10240 + (16 * kt + 4 * g) * 4);
;             Z[kt] = __builtin_amdgcn_mfma_f32_16x16x32_bf16(op5, B3, Z[kt] * pc, 0, 0, 0); }
;         bf16* yp = yout + (size_t)(ci * 16 + 4 * g) * D;
;         yp[0] = f2bf(Y.x); yp[D] = f2bf(Y.y); yp[2 * D] = f2bf(Y.z); yp[3 * D] = f2bf(Y.w); }
.LBB0_388:
	v_add_u32_e32 v182, 0, v98
	v_add_u32_e32 v161, 0, v99
	v_add_u32_e32 v183, 0x16800, v182
	v_add_u32_e32 v184, 0x16880, v182
	v_add_u32_e32 v190, 0x16900, v182
	ds_read_b128 v[162:165], v161
	ds_read_b128 v[166:169], v161 offset:1024
	ds_read_b128 v[170:173], v161 offset:2048
	ds_read_b128 v[174:177], v161 offset:3072
	ds_read_b128 v[178:181], v161 offset:4096
	ds_read_b128 v[186:189], v161 offset:5120
	ds_read_u16 v183, v183
	ds_read_u16 v184, v184
	ds_read_u16 v206, v190
	v_cvt_pk_bf16_f32 v190, v124, v125
	v_cvt_pk_bf16_f32 v191, v126, v127
	v_cvt_pk_bf16_f32 v192, v128, v129
	v_cvt_pk_bf16_f32 v193, v130, v131
	v_add_u32_e32 v182, 0x16980, v182
	ds_read_u16 v182, v182
	s_waitcnt lgkmcnt(0)
	v_mfma_f32_16x16x32_bf16 v[162:165], v[162:165], v[190:193], 0
	v_cvt_pk_bf16_f32 v202, v132, v133
	v_cvt_pk_bf16_f32 v203, v134, v135
	v_cvt_pk_bf16_f32 v204, v136, v137
	v_cvt_pk_bf16_f32 v205, v138, v139
	v_add_u32_e32 v99, 0x2900, v99
	v_add_u32_e32 v98, 0x800, v98
	v_mfma_f32_16x16x32_bf16 v[162:165], v[166:169], v[202:205], v[162:165]
	v_mfma_f32_16x16x32_bf16 v[166:169], v[170:173], v[190:193], 0
	s_nop 6
	v_cvt_pk_bf16_f32 v162, v162, v163
	v_cvt_pk_bf16_f32 v163, v164, v165
	v_perm_b32 v165, v182, v206, s48
	v_perm_b32 v164, v184, v183, s48
	v_add_u32_e32 v182, 0, v96
	v_add_u32_e32 v96, 0x2900, v96
	v_mfma_f32_16x16x32_bf16 v[170:173], v[178:181], v[162:165], 0
	v_mov_b32_e32 v178, v164
	v_mov_b32_e32 v179, v165
	s_nop 5
	v_cvt_pk_bf16_f32 v180, v170, v171
	v_cvt_pk_bf16_f32 v181, v172, v173
	ds_read_b128 v[162:165], v161 offset:6144
	ds_read_b128 v[170:173], v182
	s_waitcnt lgkmcnt(0)
	v_pk_mul_f32 v[126:127], v[126:127], v[172:173]
	v_pk_mul_f32 v[124:125], v[124:125], v[170:171]
	s_nop 1
	v_mfma_f32_16x16x32_bf16 v[124:127], v[162:165], v[178:181], v[124:127]
	ds_read_b128 v[162:165], v161 offset:7168
	ds_read_b128 v[170:173], v182 offset:64
	s_waitcnt lgkmcnt(0)
	v_pk_mul_f32 v[130:131], v[130:131], v[172:173]
	v_pk_mul_f32 v[128:129], v[128:129], v[170:171]
	s_nop 1
	v_mfma_f32_16x16x32_bf16 v[128:131], v[162:165], v[178:181], v[128:131]
	ds_read_b128 v[162:165], v161 offset:8192
	ds_read_b128 v[170:173], v182 offset:128
	s_waitcnt lgkmcnt(0)
	v_pk_mul_f32 v[134:135], v[134:135], v[172:173]
	v_pk_mul_f32 v[132:133], v[132:133], v[170:171]
	s_nop 1
	v_mfma_f32_16x16x32_bf16 v[132:135], v[162:165], v[178:181], v[132:135]
	ds_read_b128 v[162:165], v161 offset:9216
	ds_read_b128 v[170:173], v182 offset:192
	s_waitcnt lgkmcnt(0)
	v_pk_mul_f32 v[138:139], v[138:139], v[172:173]
	v_pk_mul_f32 v[136:137], v[136:137], v[170:171]
	s_nop 1
	v_mfma_f32_16x16x32_bf16 v[136:139], v[162:165], v[178:181], v[136:139]
	v_mfma_f32_16x16x32_bf16 v[162:165], v[174:177], v[202:205], v[166:169]
	v_mfma_f32_16x16x32_bf16 v[162:165], v[186:189], v[178:181], v[162:165]
	s_nop 1
	v_lshl_add_u64 v[166:167], v[150:151], 0, s[40:41]
	s_add_u32 s40, s40, 0x10000
	s_addc_u32 s41, s41, 0
	s_cmp_eq_u32 s40, 0x40000
	s_nop 1
	v_cvt_pk_bf16_f32 v161, v162, s0
	s_mov_b32 s0, 0x40000
	v_add_co_u32_e32 v168, vcc, s0, v166
	s_nop 1
	v_addc_co_u32_e32 v169, vcc, 0, v167, vcc
	global_store_short v[168:169], v161, off offset:2048
	v_cvt_pk_bf16_f32 v161, v163, s0
	s_mov_b32 s0, 0x41000
	v_add_co_u32_e32 v162, vcc, s0, v166
	s_nop 1
	v_addc_co_u32_e32 v163, vcc, 0, v167, vcc
	global_store_short v[162:163], v161, off offset:2048
	v_cvt_pk_bf16_f32 v161, v164, s0
	s_mov_b32 s0, 0x42000
	v_add_co_u32_e32 v162, vcc, s0, v166
	s_nop 1
	v_addc_co_u32_e32 v163, vcc, 0, v167, vcc
	global_store_short v[162:163], v161, off offset:2048
	v_cvt_pk_bf16_f32 v161, v165, s0
	s_mov_b32 s0, 0x43000
	v_add_co_u32_e32 v162, vcc, s0, v166
	s_nop 1
	v_addc_co_u32_e32 v163, vcc, 0, v167, vcc
	global_store_short v[162:163], v161, off offset:2048
	s_cbranch_scc0 .LBB0_388
	s_mov_b64 s[0:1], 0
.LBB0_390:
	s_and_b64 vcc, exec, s[0:1]
	s_cbranch_vccz .LBB0_392
	s_min_u32 s0, s5, 59
	s_add_i32 s6, s0, 4
	s_mul_i32 s0, s6, 0xa400
	s_add_u32 s0, s56, s0
	s_addc_u32 s1, s57, 0
	s_waitcnt vmcnt(0)
	ds_write_b128 v152, v[40:43]
	ds_write_b128 v152, v[44:47] offset:4096
	ds_write_b128 v152, v[56:59] offset:8192
	ds_write_b128 v152, v[64:67] offset:12288
	ds_write_b128 v152, v[68:71] offset:16384
	ds_write_b128 v152, v[72:75] offset:20480
	ds_write_b128 v152, v[76:79] offset:24576
	ds_write_b128 v152, v[80:83] offset:28672
	ds_write_b128 v152, v[84:87] offset:32768
	ds_write_b128 v152, v[88:91] offset:36864
	ds_write_b128 v152, v[92:95] offset:40960
	ds_write_b128 v152, v[100:103] offset:45056
	ds_write_b128 v160, v[104:107]
	v_lshl_add_u64 v[84:85], s[0:1], 0, v[140:141]
	v_add_co_u32_e32 v44, vcc, s55, v84
	s_lshl_b32 s6, s6, 13
	s_nop 0
	v_addc_co_u32_e32 v45, vcc, 0, v85, vcc
	v_add_co_u32_e32 v56, vcc, s13, v84
	s_add_u32 s6, s62, s6
	s_nop 0
	v_addc_co_u32_e32 v57, vcc, 0, v85, vcc
	v_add_co_u32_e32 v64, vcc, s54, v84
	s_addc_u32 s7, s63, 0
	s_nop 0
	v_addc_co_u32_e32 v65, vcc, 0, v85, vcc
	v_add_co_u32_e32 v68, vcc, s11, v84
	v_lshl_add_u64 v[100:101], s[6:7], 0, v[142:143]
	s_nop 0
	v_addc_co_u32_e32 v69, vcc, 0, v85, vcc
	v_add_co_u32_e32 v72, vcc, s14, v84
	v_lshl_add_u64 v[92:93], s[0:1], 0, v[146:147]
	s_nop 0
	v_addc_co_u32_e32 v73, vcc, 0, v85, vcc
	v_add_co_u32_e32 v76, vcc, s15, v84
	v_lshl_add_u64 v[94:95], s[6:7], 0, v[144:145]
	s_nop 0
	v_addc_co_u32_e32 v77, vcc, 0, v85, vcc
	v_add_co_u32_e32 v80, vcc, s17, v84
	v_cndmask_b32_e64 v93, v95, v93, s[38:39]
	s_nop 0
	v_addc_co_u32_e32 v81, vcc, 0, v85, vcc
	v_add_co_u32_e32 v86, vcc, s9, v84
	v_cndmask_b32_e64 v92, v94, v92, s[38:39]
	s_nop 0
	v_addc_co_u32_e32 v87, vcc, 0, v85, vcc
	v_add_co_u32_e32 v88, vcc, s19, v84
	v_lshl_add_u64 v[98:99], s[6:7], 0, v[140:141]
	s_nop 0
	v_addc_co_u32_e32 v89, vcc, 0, v85, vcc
	v_add_co_u32_e32 v104, vcc, 0xffff5c00, v100
	global_load_dwordx4 v[40:43], v[84:85], off
	s_nop 0
	global_load_dwordx4 v[44:47], v[44:45], off
	v_addc_co_u32_e32 v105, vcc, -1, v101, vcc
	global_load_dwordx4 v[56:59], v[56:57], off
	s_nop 0
	global_load_dwordx4 v[64:67], v[64:65], off
	s_nop 0
	global_load_dwordx4 v[68:71], v[68:69], off
	s_nop 0
	global_load_dwordx4 v[72:75], v[72:73], off
	s_nop 0
	global_load_dwordx4 v[76:79], v[76:77], off
	s_nop 0
	global_load_dwordx4 v[80:83], v[80:81], off
	s_nop 0
	global_load_dwordx4 v[84:87], v[86:87], off
	s_nop 0
	global_load_dwordx4 v[88:91], v[88:89], off
	s_nop 0
	global_load_dwordx4 v[92:95], v[92:93], off
	s_nop 0
	global_load_dwordx4 v[100:103], v[98:99], off offset:3072
	s_nop 0
	global_load_dwordx4 v[104:107], v[104:105], off
	s_branch .LBB0_393

; __device__ __forceinline__ void unpack8(const u32x4 w, float (&f)[8]) { f[0] = bflo(w.x); f[1] = bfhi(w.x); f[2] = bflo(w.y); f[3] = bfhi(w.y); f[4] = bflo(w.z); f[5] = bfhi(w.z); f[6] = bflo(w.w); f[7] = bfhi(w.w); }
; __device__ __forceinline__ void e4_phase(const bf16* P, const bf16* LO, const float* mu, const float* w0, const float* a0, const float* k_k, const float* k_a,
;                                          bf16* SI, float* SW, bf16* SV, int gw, int ngw, int lane) {
;     const int hf = gw & 1, c = hf * 512 + lane * 8, h = c >> 6, cl = (lane & 7) * 8;
;     float mu_r[8], mu_k[8], mu_v[8], w0c[8], a0c[8], kkc[8], kac[8];
;     ld8f(mu + c, mu_r); ld8f(mu + 1024 + c, mu_k); ld8f(mu + 2048 + c, mu_v); ld8f(w0 + c, w0c); ld8f(a0 + c, a0c); ld8f(k_k + c, kkc); ld8f(k_a + c, kac);
;     for (int m = gw >> 1; m < T; m += ngw >> 1) { const int t = m & (SEQ - 1), b = m >> 12; const bf16* pr = P + (size_t)m * EV_IN_P + 3072 + c;
;         float r[8], k[8], v[8], r1[8], k1[8], v1[8], lw[8], la[8];
;         unpack8(*(const u32x4*)pr, r); unpack8(*(const u32x4*)(pr + 1024), k); unpack8(*(const u32x4*)(pr + 2048), v);
;         unpack8(*(const u32x4*)(LO + (size_t)m * LORA_N + c), lw); unpack8(*(const u32x4*)(LO + (size_t)m * LORA_N + 1024 + c), la);
;         { const bf16* pp = (t >= 1) ? (pr - EV_IN_P) : pr; const float z1 = (t >= 1) ? 1.0f : 0.0f;
;           unpack8(*(const u32x4*)pp, r1); unpack8(*(const u32x4*)(pp + 1024), k1); unpack8(*(const u32x4*)(pp + 2048), v1);
.LBB0_396:
	s_andn2_b64 vcc, exec, s[0:1]
	s_cbranch_vccnz .LBB0_400
	s_add_i32 s0, s92, 0
	s_waitcnt vmcnt(0)
	v_mov_b32_e32 v2, s0
	s_waitcnt lgkmcnt(0)
	ds_read_b64 v[0:1], v2 offset:40
	s_ashr_i32 s0, s10, 1
	s_cmpk_gt_i32 s0, 0x3fff
	s_waitcnt lgkmcnt(0)
	v_readfirstlane_b32 s1, v1
	v_readfirstlane_b32 s2, v0
	ds_read_b64 v[0:1], v2 offset:48
	s_waitcnt lgkmcnt(0)
	v_readfirstlane_b32 s4, v1
	v_readfirstlane_b32 s5, v0
	ds_read_b64 v[0:1], v2 offset:64
	s_waitcnt lgkmcnt(0)
	v_readfirstlane_b32 s7, v1
	v_readfirstlane_b32 s9, v0
	ds_read_b64 v[0:1], v2 offset:88
	s_waitcnt lgkmcnt(0)
	v_readfirstlane_b32 s6, v1
	v_readfirstlane_b32 s8, v0
	ds_read_b64 v[0:1], v2 offset:96
	s_waitcnt lgkmcnt(0)
	v_readfirstlane_b32 s11, v1
	v_readfirstlane_b32 s14, v0
	s_cbranch_scc1 .LBB0_400
	s_lshl_b32 s15, s96, 12
	s_add_u32 s30, s5, s15
	s_addc_u32 s31, s4, 0
	s_add_u32 s4, s9, s15
	s_addc_u32 s5, s7, 0
	s_lshl_b32 s7, s52, 9
	s_and_b32 s7, s7, 0x200
	v_lshlrev_b32_e32 v56, 3, v185
	v_or_b32_e32 v58, s7, v56
	v_lshlrev_b32_e32 v96, 2, v58
	v_lshl_add_u64 v[12:13], s[4:5], 0, v[96:97]
	s_add_u32 s4, s14, s15
	s_addc_u32 s5, s11, 0
	v_lshl_add_u64 v[20:21], s[4:5], 0, v[96:97]
	s_add_u32 s4, s8, s15
	s_addc_u32 s5, s6, 0
	v_lshl_add_u64 v[28:29], s[4:5], 0, v[96:97]
	s_mul_i32 s4, s96, 0x3480
	s_add_u32 s4, s2, s4
	s_addc_u32 s5, s1, 0
	v_lshl_add_u64 v[52:53], s[4:5], 0, v[96:97]
	v_add_co_u32_e32 v36, vcc, s13, v52
	s_mov_b64 s[4:5], 0x2000
	s_nop 0
	v_addc_co_u32_e32 v37, vcc, 0, v53, vcc
	v_lshl_add_u64 v[32:33], v[52:53], 0, s[4:5]
	s_mov_b64 s[4:5], 0x1000
	v_add_co_u32_e32 v44, vcc, s55, v52
	v_lshl_add_u64 v[4:5], s[30:31], 0, v[96:97]
	v_lshl_add_u64 v[40:41], v[52:53], 0, s[4:5]
	v_addc_co_u32_e32 v45, vcc, 0, v53, vcc
	global_load_dwordx4 v[0:3], v[4:5], off
	s_nop 0
	global_load_dwordx4 v[4:7], v[4:5], off offset:16
	s_nop 0
	global_load_dwordx4 v[8:11], v[12:13], off
	s_nop 0
	global_load_dwordx4 v[12:15], v[12:13], off offset:16
	s_nop 0
	global_load_dwordx4 v[16:19], v[20:21], off offset:16
	s_nop 0
	global_load_dwordx4 v[20:23], v[20:21], off
	s_nop 0
	global_load_dwordx4 v[24:27], v[28:29], off offset:16
	s_nop 0
	global_load_dwordx4 v[28:31], v[28:29], off
	s_nop 0
	global_load_dwordx4 v[32:35], v[32:33], off offset:16
	s_nop 0
	global_load_dwordx4 v[36:39], v[36:37], off
	s_nop 0
	global_load_dwordx4 v[40:43], v[40:41], off offset:16
	s_nop 0
	global_load_dwordx4 v[44:47], v[44:45], off
	s_nop 0
	global_load_dwordx4 v[48:51], v[52:53], off offset:16
	s_nop 0
	global_load_dwordx4 v[52:55], v[52:53], off
	v_and_b32_e32 v59, 64, v220
	v_xor_b32_e32 v57, 1, v220
	v_add_u32_e32 v59, 64, v59
	v_cmp_lt_i32_e32 vcc, v57, v59
	v_and_b32_e32 v56, 56, v56
	v_readlane_b32 s4, v255, 5
	v_cndmask_b32_e32 v57, v220, v57, vcc
	v_lshlrev_b32_e32 v113, 2, v57
	v_xor_b32_e32 v57, 2, v220
	v_cmp_lt_i32_e32 vcc, v57, v59
	s_mul_i32 s2, s0, 0x1800
	v_lshlrev_b32_e32 v96, 1, v56
	v_cndmask_b32_e32 v57, v220, v57, vcc
	v_lshlrev_b32_e32 v114, 2, v57
	v_xor_b32_e32 v57, 4, v220
	v_cmp_lt_i32_e32 vcc, v57, v59
	v_readlane_b32 s5, v255, 6
	s_mul_hi_i32 s1, s0, 0x1800
	s_add_u32 s34, s88, s2
	v_cndmask_b32_e32 v57, v220, v57, vcc
	v_lshl_add_u64 v[76:77], s[4:5], 0, v[96:97]
	v_readlane_b32 s4, v255, 7
	s_addc_u32 s35, s89, s1
	s_mul_i32 s2, s0, 0x3400
	v_lshlrev_b32_e32 v115, 2, v57
	v_lshlrev_b32_e32 v56, 2, v56
	v_mov_b32_e32 v57, v97
	v_readlane_b32 s5, v255, 8
	s_mul_hi_i32 s1, s0, 0x3400
	s_add_u32 s36, s88, s2
	v_readlane_b32 s8, v254, 3
	v_lshrrev_b32_e32 v112, 6, v58
	v_lshl_add_u64 v[78:79], s[4:5], 0, v[56:57]
	v_lshl_add_u64 v[80:81], s[80:81], 0, v[96:97]
	v_lshlrev_b32_e32 v96, 1, v58
	s_addc_u32 s37, s89, s1
	v_readlane_b32 s9, v254, 4
	s_mov_b32 s11, 0xbfb8aa3b
	s_mov_b32 s14, 0xf800000
.LBB0_399:
	v_lshl_add_u64 v[72:73], s[36:37], 0, v[96:97]
	v_add_co_u32_e32 v56, vcc, 0x13a01000, v72
	s_and_b32 s1, s0, 0xfff
	s_nop 0
	v_addc_co_u32_e32 v57, vcc, 0, v73, vcc
	global_load_dwordx4 v[68:71], v[56:57], off offset:2048
	v_add_co_u32_e32 v56, vcc, 0x13a02000, v72
	s_cmp_eq_u32 s1, 0
	s_nop 0
	v_addc_co_u32_e32 v57, vcc, 0, v73, vcc
	global_load_dwordx4 v[64:67], v[56:57], off
	global_load_dwordx4 v[60:63], v[56:57], off offset:2048
	v_lshl_add_u64 v[56:57], s[34:35], 0, v[96:97]
	v_add_co_u32_e32 v74, vcc, 0x20a00000, v56
	s_cselect_b64 s[4:5], -1, 0
	s_nop 0
	v_addc_co_u32_e32 v75, vcc, 0, v57, vcc
	global_load_dwordx4 v[56:59], v[74:75], off
	s_and_b64 s[6:7], s[4:5], exec
	s_cselect_b32 s7, 0, -1
	s_cselect_b32 s6, 0, 0xffffcc00
	s_mov_b32 s2, 0x13a02000
	v_cndmask_b32_e64 v94, 1.0, 0, s[4:5]
	s_waitcnt vmcnt(0) lgkmcnt(0)
	v_lshlrev_b32_e32 v82, 16, v56
	v_and_b32_e32 v86, 0xffff0000, v56
	v_lshlrev_b32_e32 v87, 16, v57
	v_and_b32_e32 v92, 0xffff0000, v57
	v_lshlrev_b32_e32 v93, 16, v58
	v_and_b32_e32 v95, 0xffff0000, v58
	v_lshlrev_b32_e32 v104, 16, v59
	v_and_b32_e32 v105, 0xffff0000, v59
	global_load_dwordx4 v[56:59], v[74:75], off offset:2048
	s_waitcnt vmcnt(0) lgkmcnt(0)
; __device__ __forceinline__ void unpack8(const u32x4 w, float (&f)[8]) { f[0] = bflo(w.x); f[1] = bfhi(w.x); f[2] = bflo(w.y); f[3] = bfhi(w.y); f[4] = bflo(w.z); f[5] = bfhi(w.z); f[6] = bflo(w.w); f[7] = bfhi(w.w); }
; __device__ __forceinline__ float fexp(float x) { return __builtin_amdgcn_exp2f(x * 1.4426950408889634f); }
; __device__ __forceinline__ float flog(float x) { return __builtin_amdgcn_logf(x) * 0.6931471805599453f; }
; __device__ __forceinline__ float fsigmoid(float x) { return __builtin_amdgcn_rcpf(1.0f + fexp(-x)); }
; __device__ __forceinline__ void e4_phase(const bf16* P, const bf16* LO, const float* mu, const float* w0, const float* a0, const float* k_k, const float* k_a,
;                                          bf16* SI, float* SW, bf16* SV, int gw, int ngw, int lane) {
;     ...
;     for (int m = gw >> 1; m < T; m += ngw >> 1) { const int t = m & (SEQ - 1), b = m >> 12; const bf16* pr = P + (size_t)m * EV_IN_P + 3072 + c;
;         float r[8], k[8], v[8], r1[8], k1[8], v1[8], lw[8], la[8];
;         unpack8(*(const u32x4*)pr, r); unpack8(*(const u32x4*)(pr + 1024), k); unpack8(*(const u32x4*)(pr + 2048), v);
;         unpack8(*(const u32x4*)(LO + (size_t)m * LORA_N + c), lw); unpack8(*(const u32x4*)(LO + (size_t)m * LORA_N + 1024 + c), la);
;         { const bf16* pp = (t >= 1) ? (pr - EV_IN_P) : pr; const float z1 = (t >= 1) ? 1.0f : 0.0f;
;           unpack8(*(const u32x4*)pp, r1); unpack8(*(const u32x4*)(pp + 1024), k1); unpack8(*(const u32x4*)(pp + 2048), v1);
; #pragma unroll
;           for (int e = 0; e < 8; ++e) { r1[e] *= z1; k1[e] *= z1; v1[e] *= z1; } }
;         float kk[8], kp[8], bb[8], dec[8]; float n2 = 0.f;
; #pragma unroll
;         for (int e = 0; e < 8; ++e) { r[e] += (r1[e] - r[e]) * mu_r[e]; k[e] += (k1[e] - k[e]) * mu_k[e]; v[e] += (v1[e] - v[e]) * mu_v[e];
;             const float z = -(w0c[e] + lw[e]); const float sp = fmaxf(z, 0.f) + flog(1.0f + fexp(-fabsf(z))); const float w = -sp - 0.5f;
;             dec[e] = fexp(-fexp(w));
;             const float a = fsigmoid(a0c[e] + la[e]);
;             kk[e] = k[e] * kkc[e]; n2 += kk[e] * kk[e];
;             kp[e] = k[e] * (1.0f + (a - 1.0f) * kac[e]); bb[e] = a; }
	v_lshlrev_b32_e32 v83, 16, v56
	v_and_b32_e32 v99, 0xffff0000, v56
	v_lshlrev_b32_e32 v106, 16, v57
	v_and_b32_e32 v107, 0xffff0000, v57
	v_lshl_add_u64 v[56:57], v[72:73], 0, s[6:7]
	v_lshlrev_b32_e32 v110, 16, v58
	v_and_b32_e32 v111, 0xffff0000, v58
	v_add_co_u32_e32 v58, vcc, s49, v56
	v_lshlrev_b32_e32 v116, 16, v59
	v_and_b32_e32 v117, 0xffff0000, v59
	v_addc_co_u32_e32 v59, vcc, 0, v57, vcc
	global_load_dwordx4 v[72:75], v[58:59], off offset:2048
	v_add_co_u32_e32 v56, vcc, s2, v56
	v_lshlrev_b32_e32 v58, 16, v68
	s_nop 0
	v_addc_co_u32_e32 v57, vcc, 0, v57, vcc
	global_load_dwordx4 v[100:103], v[56:57], off
	global_load_dwordx4 v[88:91], v[56:57], off offset:2048
	v_add_f32_e32 v56, v0, v82
	v_max_f32_e64 v57, -v56, 0
	v_mul_f32_e64 v56, |v56|, s11
	v_exp_f32_e32 v56, v56
	v_and_b32_e32 v59, 0xffff0000, v68
	v_lshlrev_b32_e32 v68, 16, v69
	v_and_b32_e32 v69, 0xffff0000, v69
	v_add_f32_e32 v56, 1.0, v56
	v_log_f32_e32 v56, v56
	s_ashr_i32 s2, s0, 8
	s_add_i32 s0, s0, s93
	s_add_u32 s34, s34, s8
	v_fmac_f32_e32 v57, 0x3f317218, v56
	v_sub_f32_e32 v56, -0.5, v57
	v_add_f32_e32 v57, v8, v83
	v_mul_f32_e32 v57, 0xbfb8aa3b, v57
	v_exp_f32_e32 v57, v57
	v_mul_f32_e32 v56, 0x3fb8aa3b, v56
	v_exp_f32_e32 v56, v56
	s_addc_u32 s35, s35, s9
	v_add_f32_e32 v57, 1.0, v57
	v_rcp_f32_e32 v98, v57
	v_add_f32_e32 v57, v1, v86
	v_lshlrev_b32_e32 v86, 16, v70
	v_mul_f32_e32 v56, 0xbfb8aa3b, v56
	v_exp_f32_e32 v56, v56
	s_add_u32 s36, s36, s40
	s_addc_u32 s37, s37, s33
	s_cmpk_gt_i32 s0, 0x3fff
	s_waitcnt vmcnt(0) lgkmcnt(0)
	v_lshlrev_b32_e32 v82, 16, v72
	v_and_b32_e32 v83, 0xffff0000, v72
	v_pk_fma_f32 v[82:83], v[94:95], v[82:83], v[58:59] op_sel_hi:[0,1,1] neg_lo:[0,0,1] neg_hi:[0,0,1]
	v_pk_fma_f32 v[84:85], v[52:53], v[82:83], v[58:59]
	v_lshlrev_b32_e32 v58, 16, v60
	v_and_b32_e32 v59, 0xffff0000, v60
	v_lshlrev_b32_e32 v82, 16, v88
	v_and_b32_e32 v83, 0xffff0000, v88
	v_pk_fma_f32 v[82:83], v[94:95], v[82:83], v[58:59] op_sel_hi:[0,1,1] neg_lo:[0,0,1] neg_hi:[0,0,1]
	v_pk_fma_f32 v[82:83], v[36:37], v[82:83], v[58:59]
	v_max_f32_e64 v58, -v57, 0
	v_mul_f32_e64 v57, |v57|, s11
	v_exp_f32_e32 v57, v57
	v_lshlrev_b32_e32 v72, 16, v73
	v_and_b32_e32 v73, 0xffff0000, v73
	v_pk_fma_f32 v[72:73], v[94:95], v[72:73], v[68:69] op_sel_hi:[0,1,1] neg_lo:[0,0,1] neg_hi:[0,0,1]
	v_add_f32_e32 v57, 1.0, v57
	v_log_f32_e32 v57, v57
	v_pk_fma_f32 v[72:73], v[54:55], v[72:73], v[68:69]
	v_lshlrev_b32_e32 v60, 16, v61
	v_and_b32_e32 v61, 0xffff0000, v61
	v_fmac_f32_e32 v58, 0x3f317218, v57
	v_sub_f32_e32 v57, -0.5, v58
	v_add_f32_e32 v58, v9, v99
	v_mul_f32_e32 v58, 0xbfb8aa3b, v58
	v_exp_f32_e32 v58, v58
	v_lshlrev_b32_e32 v68, 16, v89
	v_and_b32_e32 v69, 0xffff0000, v89
	v_pk_fma_f32 v[68:69], v[94:95], v[68:69], v[60:61] op_sel_hi:[0,1,1] neg_lo:[0,0,1] neg_hi:[0,0,1]
	v_add_f32_e32 v58, 1.0, v58
	v_rcp_f32_e32 v99, v58
	v_add_f32_e32 v58, v2, v87
	v_max_f32_e64 v59, -v58, 0
	v_mul_f32_e64 v58, |v58|, s11
	v_exp_f32_e32 v58, v58
	v_pk_fma_f32 v[68:69], v[38:39], v[68:69], v[60:61]
	v_and_b32_e32 v87, 0xffff0000, v70
	v_lshlrev_b32_e32 v88, 16, v74
	v_add_f32_e32 v58, 1.0, v58
	v_log_f32_e32 v58, v58
	v_and_b32_e32 v89, 0xffff0000, v74
	v_pk_fma_f32 v[88:89], v[94:95], v[88:89], v[86:87] op_sel_hi:[0,1,1] neg_lo:[0,0,1] neg_hi:[0,0,1]
	v_pk_fma_f32 v[88:89], v[48:49], v[88:89], v[86:87]
	v_fmac_f32_e32 v59, 0x3f317218, v58
	v_sub_f32_e32 v58, -0.5, v59
	v_add_f32_e32 v59, v10, v106
	v_mul_f32_e32 v59, 0xbfb8aa3b, v59
	v_exp_f32_e32 v59, v59
	v_lshlrev_b32_e32 v86, 16, v62
	v_and_b32_e32 v87, 0xffff0000, v62
	v_lshlrev_b32_e32 v74, 16, v75
	v_add_f32_e32 v59, 1.0, v59
	v_rcp_f32_e32 v108, v59
	v_add_f32_e32 v59, v3, v92
	v_max_f32_e64 v60, -v59, 0
	v_mul_f32_e64 v59, |v59|, s11
	v_exp_f32_e32 v59, v59
	v_and_b32_e32 v75, 0xffff0000, v75
	v_lshlrev_b32_e32 v92, 16, v90
	v_lshlrev_b32_e32 v120, 16, v101
	v_add_f32_e32 v59, 1.0, v59
	v_log_f32_e32 v59, v59
	v_and_b32_e32 v121, 0xffff0000, v101
	v_mul_f32_e32 v57, 0x3fb8aa3b, v57
	v_mul_f32_e32 v58, 0x3fb8aa3b, v58
	v_fmac_f32_e32 v60, 0x3f317218, v59
	v_sub_f32_e32 v59, -0.5, v60
	v_add_f32_e32 v60, v11, v107
	v_mul_f32_e32 v60, 0xbfb8aa3b, v60
	v_exp_f32_e32 v60, v60
	v_mul_f32_e32 v59, 0x3fb8aa3b, v59
	v_exp_f32_e32 v57, v57
	v_exp_f32_e32 v58, v58
	v_add_f32_e32 v60, 1.0, v60
	v_rcp_f32_e32 v109, v60
	v_add_f32_e32 v60, v4, v93
	v_max_f32_e64 v61, -v60, 0
	v_mul_f32_e64 v60, |v60|, s11
	v_exp_f32_e32 v60, v60
	v_and_b32_e32 v93, 0xffff0000, v90
	v_lshlrev_b32_e32 v90, 16, v91
	v_and_b32_e32 v91, 0xffff0000, v91
	v_add_f32_e32 v60, 1.0, v60
	v_log_f32_e32 v60, v60
	v_pk_fma_f32 v[92:93], v[94:95], v[92:93], v[86:87] op_sel_hi:[0,1,1] neg_lo:[0,0,1] neg_hi:[0,0,1]
	v_pk_fma_f32 v[86:87], v[32:33], v[92:93], v[86:87]
	v_lshlrev_b32_e32 v92, 16, v103
	v_fmac_f32_e32 v61, 0x3f317218, v60
	v_sub_f32_e32 v60, -0.5, v61
	v_add_f32_e32 v61, v12, v110
	v_mul_f32_e32 v61, 0xbfb8aa3b, v61
	v_exp_f32_e32 v61, v61
	v_and_b32_e32 v93, 0xffff0000, v103
	v_pk_add_f32 v[124:125], v[108:109], -1.0 op_sel_hi:[1,0]
	v_exp_f32_e32 v59, v59
	v_add_f32_e32 v61, 1.0, v61
	v_rcp_f32_e32 v110, v61
	v_add_f32_e32 v61, v5, v95
	v_max_f32_e64 v62, -v61, 0
	v_mul_f32_e64 v61, |v61|, s11
	v_exp_f32_e32 v61, v61
	v_pk_fma_f32 v[124:125], v[22:23], v[124:125], 1.0 op_sel_hi:[1,1,0]
	v_mul_f32_e32 v60, 0x3fb8aa3b, v60
	v_exp_f32_e32 v60, v60
	v_add_f32_e32 v61, 1.0, v61
	v_log_f32_e32 v61, v61
	v_mul_f32_e32 v57, 0xbfb8aa3b, v57
	v_mul_f32_e32 v58, 0xbfb8aa3b, v58
	v_mul_f32_e32 v59, 0xbfb8aa3b, v59
	v_fmac_f32_e32 v62, 0x3f317218, v61
	v_sub_f32_e32 v61, -0.5, v62
	v_add_f32_e32 v62, v13, v111
	v_mul_f32_e32 v62, 0xbfb8aa3b, v62
; __device__ __forceinline__ float fexp(float x) { return __builtin_amdgcn_exp2f(x * 1.4426950408889634f); }
; __device__ __forceinline__ float flog(float x) { return __builtin_amdgcn_logf(x) * 0.6931471805599453f; }
; __device__ __forceinline__ float fsigmoid(float x) { return __builtin_amdgcn_rcpf(1.0f + fexp(-x)); }
; __device__ __forceinline__ void e4_phase(const bf16* P, const bf16* LO, const float* mu, const float* w0, const float* a0, const float* k_k, const float* k_a,
;                                          bf16* SI, float* SW, bf16* SV, int gw, int ngw, int lane) {
;     ...
;         for (int e = 0; e < 8; ++e) { r[e] += (r1[e] - r[e]) * mu_r[e]; k[e] += (k1[e] - k[e]) * mu_k[e]; v[e] += (v1[e] - v[e]) * mu_v[e];
;             const float z = -(w0c[e] + lw[e]); const float sp = fmaxf(z, 0.f) + flog(1.0f + fexp(-fabsf(z))); const float w = -sp - 0.5f;
;             dec[e] = fexp(-fexp(w));
;             const float a = fsigmoid(a0c[e] + la[e]);
;             kk[e] = k[e] * kkc[e]; n2 += kk[e] * kk[e];
;             kp[e] = k[e] * (1.0f + (a - 1.0f) * kac[e]); bb[e] = a; }
	v_exp_f32_e32 v62, v62
	v_mul_f32_e32 v61, 0x3fb8aa3b, v61
	v_exp_f32_e32 v61, v61
	v_exp_f32_e32 v57, v57
	v_add_f32_e32 v62, 1.0, v62
	v_rcp_f32_e32 v111, v62
	v_add_f32_e32 v62, v6, v104
	v_max_f32_e64 v70, -v62, 0
	v_mul_f32_e64 v62, |v62|, s11
	v_exp_f32_e32 v62, v62
	v_exp_f32_e32 v58, v58
	v_exp_f32_e32 v59, v59
	v_mul_f32_e32 v60, 0xbfb8aa3b, v60
	v_add_f32_e32 v62, 1.0, v62
	v_log_f32_e32 v62, v62
	v_mul_f32_e32 v61, 0xbfb8aa3b, v61
	v_exp_f32_e32 v60, v60
	v_exp_f32_e32 v61, v61
	v_fmac_f32_e32 v70, 0x3f317218, v62
	v_sub_f32_e32 v62, -0.5, v70
	v_add_f32_e32 v70, v14, v116
	v_mul_f32_e32 v70, 0xbfb8aa3b, v70
	v_exp_f32_e32 v70, v70
	v_mul_f32_e32 v62, 0x3fb8aa3b, v62
	v_exp_f32_e32 v62, v62
	v_add_f32_e32 v70, 1.0, v70
	v_rcp_f32_e32 v116, v70
	v_lshlrev_b32_e32 v70, 16, v71
	v_and_b32_e32 v71, 0xffff0000, v71
	v_pk_fma_f32 v[74:75], v[94:95], v[74:75], v[70:71] op_sel_hi:[0,1,1] neg_lo:[0,0,1] neg_hi:[0,0,1]
	v_pk_fma_f32 v[74:75], v[50:51], v[74:75], v[70:71]
	v_lshlrev_b32_e32 v70, 16, v63
	v_and_b32_e32 v71, 0xffff0000, v63
	v_pk_fma_f32 v[90:91], v[94:95], v[90:91], v[70:71] op_sel_hi:[0,1,1] neg_lo:[0,0,1] neg_hi:[0,0,1]
	v_add_f32_e32 v63, v7, v105
	v_pk_fma_f32 v[70:71], v[34:35], v[90:91], v[70:71]
	v_max_f32_e64 v90, -v63, 0
	v_mul_f32_e64 v63, |v63|, s11
	v_exp_f32_e32 v63, v63
	v_and_b32_e32 v91, 0xffff0000, v67
	v_mul_f32_e32 v62, 0xbfb8aa3b, v62
	v_exp_f32_e32 v62, v62
	v_add_f32_e32 v63, 1.0, v63
	v_log_f32_e32 v63, v63
	s_nop 0
	v_fmac_f32_e32 v90, 0x3f317218, v63
	v_sub_f32_e32 v63, -0.5, v90
	v_add_f32_e32 v90, v15, v117
	v_mul_f32_e32 v90, 0xbfb8aa3b, v90
	v_exp_f32_e32 v90, v90
	v_mul_f32_e32 v63, 0x3fb8aa3b, v63
	v_exp_f32_e32 v63, v63
	v_add_f32_e32 v90, 1.0, v90
	v_rcp_f32_e32 v117, v90
	v_lshlrev_b32_e32 v90, 16, v67
	v_pk_fma_f32 v[92:93], v[94:95], v[92:93], v[90:91] op_sel_hi:[0,1,1] neg_lo:[0,0,1] neg_hi:[0,0,1]
	v_pk_fma_f32 v[90:91], v[42:43], v[92:93], v[90:91]
	v_pk_add_f32 v[92:93], v[116:117], -1.0 op_sel_hi:[1,0]
	v_pk_mul_f32 v[118:119], v[26:27], v[90:91]
	v_pk_fma_f32 v[92:93], v[18:19], v[92:93], 1.0 op_sel_hi:[1,1,0]
	v_and_b32_e32 v67, 0xffff0000, v102
	v_pk_mul_f32 v[90:91], v[90:91], v[92:93]
	v_lshlrev_b32_e32 v92, 16, v66
	v_and_b32_e32 v93, 0xffff0000, v66
	v_lshlrev_b32_e32 v66, 16, v102
	v_pk_fma_f32 v[66:67], v[94:95], v[66:67], v[92:93] op_sel_hi:[0,1,1] neg_lo:[0,0,1] neg_hi:[0,0,1]
	v_pk_fma_f32 v[66:67], v[40:41], v[66:67], v[92:93]
	v_pk_add_f32 v[92:93], v[110:111], -1.0 op_sel_hi:[1,0]
	v_pk_mul_f32 v[102:103], v[24:25], v[66:67]
	v_pk_fma_f32 v[92:93], v[16:17], v[92:93], 1.0 op_sel_hi:[1,1,0]
	v_pk_mul_f32 v[106:107], v[102:103], v[102:103]
	v_pk_mul_f32 v[66:67], v[66:67], v[92:93]
	v_lshlrev_b32_e32 v92, 16, v65
	v_and_b32_e32 v93, 0xffff0000, v65
	v_pk_fma_f32 v[120:121], v[94:95], v[120:121], v[92:93] op_sel_hi:[0,1,1] neg_lo:[0,0,1] neg_hi:[0,0,1]
	v_pk_fma_f32 v[92:93], v[46:47], v[120:121], v[92:93]
	v_and_b32_e32 v65, 0xffff0000, v100
	v_pk_mul_f32 v[120:121], v[30:31], v[92:93]
	v_pk_mul_f32 v[92:93], v[92:93], v[124:125]
	v_lshlrev_b32_e32 v124, 16, v64
	v_and_b32_e32 v125, 0xffff0000, v64
	v_lshlrev_b32_e32 v64, 16, v100
	v_pk_fma_f32 v[64:65], v[94:95], v[64:65], v[124:125] op_sel_hi:[0,1,1] neg_lo:[0,0,1] neg_hi:[0,0,1]
	v_pk_fma_f32 v[64:65], v[44:45], v[64:65], v[124:125]
	v_pk_mul_f32 v[122:123], v[120:121], v[120:121]
	v_pk_mul_f32 v[94:95], v[28:29], v[64:65]
	v_pk_mul_f32 v[104:105], v[118:119], v[118:119]
	v_pk_mul_f32 v[100:101], v[94:95], v[94:95]
	v_pk_add_f32 v[124:125], v[98:99], -1.0 op_sel_hi:[1,0]
	v_add_f32_e32 v100, v100, v101
	v_add_f32_e32 v100, v122, v100
	v_add_f32_e32 v100, v123, v100
	v_add_f32_e32 v100, v106, v100
	v_add_f32_e32 v100, v107, v100
	v_add_f32_e32 v100, v104, v100
	v_add_f32_e32 v100, v105, v100
	ds_bpermute_b32 v101, v113, v100
	v_pk_fma_f32 v[124:125], v[20:21], v[124:125], 1.0 op_sel_hi:[1,1,0]
	v_cvt_pk_bf16_f32 v66, v66, v67
	v_pk_mul_f32 v[64:65], v[64:65], v[124:125]
	v_cvt_pk_bf16_f32 v67, v90, v91
	s_waitcnt lgkmcnt(0)
; __device__ __forceinline__ u32x4 pack8(const float (&f)[8]) { u32x4 w; w.x = pk_bf16(f[0], f[1]); w.y = pk_bf16(f[2], f[3]); w.z = pk_bf16(f[4], f[5]); w.w = pk_bf16(f[6], f[7]); return w; }
; __device__ __forceinline__ float sum8(float x) { x += __shfl_xor(x, 1); x += __shfl_xor(x, 2); x += __shfl_xor(x, 4); return x; }
; __device__ __forceinline__ void e4_phase(const bf16* P, const bf16* LO, const float* mu, const float* w0, const float* a0, const float* k_k, const float* k_a,
;                                          bf16* SI, float* SW, bf16* SV, int gw, int ngw, int lane) {
;     ...
;         n2 = sum8(n2); const float inn = 1.0f / fmaxf(sqrtf(n2), 1e-12f);
; #pragma unroll
;         for (int e = 0; e < 8; ++e) { kk[e] *= inn; bb[e] *= kk[e]; }
;         const size_t idx = (size_t)(b * 16 + h) * SEQ + t;
;         bf16* si = SI + idx * 256 + cl;
;         *(u32x4*)si = pack8(kp); *(u32x4*)(si + 64) = pack8(kk); *(u32x4*)(si + 128) = pack8(bb); *(u32x4*)(si + 192) = pack8(r);
;         *(f32x4*)(SW + idx * 64 + cl) = (f32x4){dec[0], dec[1], dec[2], dec[3]}; *(f32x4*)(SW + idx * 64 + cl + 4) = (f32x4){dec[4], dec[5], dec[6], dec[7]};
;         *(u32x4*)(SV + idx * 64 + cl) = pack8(v);
	v_add_f32_e32 v100, v100, v101
	ds_bpermute_b32 v101, v114, v100
	v_cvt_pk_bf16_f32 v64, v64, v65
	v_cvt_pk_bf16_f32 v65, v92, v93
	v_mul_f32_e32 v63, 0xbfb8aa3b, v63
	v_exp_f32_e32 v63, v63
	s_waitcnt lgkmcnt(0)
	v_add_f32_e32 v100, v100, v101
	ds_bpermute_b32 v101, v115, v100
	s_waitcnt lgkmcnt(0)
	v_add_f32_e32 v100, v100, v101
	v_cmp_gt_f32_e32 vcc, s14, v100
	v_mul_f32_e32 v101, 0x4f800000, v100
	s_nop 0
	v_cndmask_b32_e32 v100, v100, v101, vcc
	v_sqrt_f32_e32 v101, v100
	s_nop 0
	v_add_u32_e32 v104, -1, v101
	v_fma_f32 v105, -v104, v101, v100
	v_cmp_ge_f32_e64 s[38:39], 0, v105
	v_add_u32_e32 v105, 1, v101
	s_nop 0
	v_cndmask_b32_e64 v104, v101, v104, s[38:39]
	v_fma_f32 v101, -v105, v101, v100
	v_cmp_lt_f32_e64 s[38:39], 0, v101
	s_nop 1
	v_cndmask_b32_e64 v101, v104, v105, s[38:39]
	v_mul_f32_e32 v104, 0x37800000, v101
	v_cndmask_b32_e32 v101, v101, v104, vcc
	v_cmp_class_f32_e32 vcc, v100, v219
	s_nop 1
	v_cndmask_b32_e32 v100, v101, v100, vcc
	v_max_f32_e32 v100, 0x2b8cbccc, v100
	v_div_scale_f32 v101, s[4:5], v100, v100, 1.0
	v_rcp_f32_e32 v104, v101
	s_nop 0
	v_fma_f32 v105, -v101, v104, 1.0
	v_fmac_f32_e32 v104, v105, v104
	v_div_scale_f32 v105, vcc, 1.0, v100, 1.0
	v_mul_f32_e32 v106, v105, v104
	v_fma_f32 v107, -v101, v106, v105
	v_fmac_f32_e32 v106, v107, v104
	v_fma_f32 v101, -v101, v106, v105
	v_div_fmas_f32 v101, v101, v104, v106
	v_div_fixup_f32 v122, v101, v100, 1.0
	v_pk_mul_f32 v[104:105], v[94:95], v[122:123] op_sel_hi:[1,0]
	v_pk_mul_f32 v[106:107], v[120:121], v[122:123] op_sel_hi:[1,0]
	v_pk_mul_f32 v[94:95], v[98:99], v[104:105]
	v_pk_mul_f32 v[98:99], v[108:109], v[106:107]
	v_pk_mul_f32 v[108:109], v[102:103], v[122:123] op_sel_hi:[1,0]
	s_nop 0
	v_pk_mul_f32 v[100:101], v[110:111], v[108:109]
	v_pk_mul_f32 v[110:111], v[118:119], v[122:123] op_sel_hi:[1,0]
	s_nop 0
	v_pk_mul_f32 v[102:103], v[116:117], v[110:111]
	v_and_or_b32 v116, s2, -16, v112
	v_ashrrev_i32_e32 v117, 31, v116
	v_lshlrev_b64 v[116:117], 12, v[116:117]
	v_or_b32_e32 v116, s1, v116
	v_lshlrev_b64 v[118:119], 9, v[116:117]
	v_lshl_add_u64 v[118:119], v[76:77], 0, v[118:119]
	global_store_dwordx4 v[118:119], v[64:67], off
	s_nop 1
	v_cvt_pk_bf16_f32 v64, v104, v105
	v_cvt_pk_bf16_f32 v65, v106, v107
	v_cvt_pk_bf16_f32 v66, v108, v109
	v_cvt_pk_bf16_f32 v67, v110, v111
	global_store_dwordx4 v[118:119], v[64:67], off offset:128
	s_nop 1
	v_cvt_pk_bf16_f32 v64, v94, v95
	v_cvt_pk_bf16_f32 v65, v98, v99
	v_cvt_pk_bf16_f32 v66, v100, v101
	v_cvt_pk_bf16_f32 v67, v102, v103
	global_store_dwordx4 v[118:119], v[64:67], off offset:256
	s_nop 1
	v_cvt_pk_bf16_f32 v64, v84, v85
	v_cvt_pk_bf16_f32 v65, v72, v73
	v_cvt_pk_bf16_f32 v66, v88, v89
	v_cvt_pk_bf16_f32 v67, v74, v75
	global_store_dwordx4 v[118:119], v[64:67], off offset:384
	s_nop 1
	v_lshlrev_b64 v[64:65], 8, v[116:117]
	v_lshl_add_u64 v[64:65], v[78:79], 0, v[64:65]
	global_store_dwordx4 v[64:65], v[56:59], off
	global_store_dwordx4 v[64:65], v[60:63], off offset:16
	s_nop 0
	v_cvt_pk_bf16_f32 v56, v82, v83
	v_lshlrev_b64 v[60:61], 7, v[116:117]
	v_cvt_pk_bf16_f32 v57, v68, v69
	v_cvt_pk_bf16_f32 v58, v86, v87
	v_cvt_pk_bf16_f32 v59, v70, v71
	v_lshl_add_u64 v[60:61], v[80:81], 0, v[60:61]
	global_store_dwordx4 v[60:61], v[56:59], off
	s_cbranch_scc0 .LBB0_399

; __device__ __forceinline__ void unpack8(const u32x4 w, float (&f)[8]) { f[0] = bflo(w.x); f[1] = bfhi(w.x); f[2] = bflo(w.y); f[3] = bfhi(w.y); f[4] = bflo(w.z); f[5] = bfhi(w.z); f[6] = bflo(w.w); f[7] = bfhi(w.w); }
; __device__ __forceinline__ void e2_phase(const bf16* P, const float* convw, const float* mu, bf16* mix, bf16* alora, int gw, int ngw, int lane) {
;     ...
;         for (int i = 0; i < 2; ++i) { const int c = (lane + 64 * i) * 8;
;             float bg[8], u0[8], u1[8], u2[8], tmp[8];
;             unpack8(*(const u32x4*)(pr + c), bg);
;             unpack8(*(const u32x4*)(pr + 1024 + c), u0); unpack8(*(const u32x4*)(pr + 2048 + c), tmp);
; #pragma unroll
;             for (int e = 0; e < 8; ++e) u0[e] *= tmp[e];
;             { const bf16* p1 = (t >= 1) ? pr - EV_IN_P : pr; const bf16* p2 = (t >= 2) ? pr - 2 * EV_IN_P : pr; const float z1 = (t >= 1) ? 1.f : 0.f, z2 = (t >= 2) ? 1.f : 0.f;
;               float t2[8];
;               unpack8(*(const u32x4*)(p1 + 1024 + c), u1); unpack8(*(const u32x4*)(p1 + 2048 + c), tmp); unpack8(*(const u32x4*)(p2 + 1024 + c), u2); unpack8(*(const u32x4*)(p2 + 2048 + c), t2);
; #pragma unroll
;               for (int e = 0; e < 8; ++e) { u1[e] *= tmp[e] * z1; u2[e] *= t2[e] * z2; } }
;             float o[8]; const float* cw = convw + c * 3;
; #pragma unroll
;             for (int e = 0; e < 8; ++e) o[e] = bg[e] * (cw[3 * e + 2] * u0[e] + cw[3 * e + 1] * u1[e] + cw[3 * e] * u2[e]);
.LBB0_405:
	s_and_b32 s2, s10, 0xfff
	s_cmp_gt_u32 s2, 1
	s_cselect_b64 s[4:5], -1, 0
	s_and_b64 s[6:7], s[4:5], exec
	s_cselect_b32 s11, 0xffff9800, 0
	s_cselect_b32 s14, -1, 0
	s_cmp_eq_u32 s2, 0
	s_cselect_b64 s[6:7], -1, 0
	s_and_b64 s[8:9], s[6:7], exec
	v_lshl_add_u64 v[8:9], s[88:89], 0, v[46:47]
	s_cselect_b32 s9, 0, 0xffffcc00
	v_add_co_u32_e64 v56, s[38:39], s15, v8
	s_cselect_b32 s8, 0, -1
	v_cndmask_b32_e64 v54, 0, 1.0, s[4:5]
	v_addc_co_u32_e64 v57, s[38:39], 0, v9, s[38:39]
	s_cselect_b32 s2, 0, 0xffffe600
	s_add_u32 s4, s88, s9
	v_add_co_u32_e64 v58, s[38:39], s49, v8
	s_addc_u32 s5, s89, s8
	s_nop 0
	v_addc_co_u32_e64 v59, s[38:39], 0, v9, s[38:39]
	v_lshl_add_u64 v[16:17], s[4:5], 0, v[46:47]
	v_add_co_u32_e64 v60, s[38:39], s15, v16
	s_add_u32 s4, s88, s11
	s_nop 0
	v_addc_co_u32_e64 v61, s[38:39], 0, v17, s[38:39]
	v_add_co_u32_e64 v62, s[38:39], s49, v16
	s_addc_u32 s5, s89, s14
	s_nop 0
	v_addc_co_u32_e64 v63, s[38:39], 0, v17, s[38:39]
	v_lshl_add_u64 v[24:25], s[4:5], 0, v[46:47]
	v_add_co_u32_e64 v64, s[38:39], s15, v24
	global_load_dwordx4 v[4:7], v[56:57], off
	global_load_dwordx4 v[0:3], v[56:57], off offset:2048
	v_addc_co_u32_e64 v65, s[38:39], 0, v25, s[38:39]
	global_load_dwordx4 v[8:11], v[58:59], off
	global_load_dwordx4 v[12:15], v[60:61], off offset:2048
	v_add_co_u32_e64 v66, s[38:39], s49, v24
	global_load_dwordx4 v[16:19], v[62:63], off
	global_load_dwordx4 v[20:23], v[64:65], off offset:2048
	v_addc_co_u32_e64 v67, s[38:39], 0, v25, s[38:39]
	global_load_dwordx4 v[24:27], v[66:67], off
	v_cndmask_b32_e64 v52, 1.0, 0, s[6:7]
	s_add_u32 s34, s88, s0
	s_addc_u32 s35, s89, s1
	s_mov_b32 s4, 0x13a03000
	s_add_i32 s10, s10, s16
	v_lshl_add_u64 v[46:47], v[46:47], 0, s[36:37]
	s_waitcnt vmcnt(0) lgkmcnt(0)
	v_lshlrev_b32_e32 v68, 16, v4
	v_lshlrev_b32_e32 v74, 16, v0
	v_and_b32_e32 v75, 0xffff0000, v0
	v_lshlrev_b32_e32 v0, 16, v1
	v_lshlrev_b32_e32 v76, 16, v8
	v_and_b32_e32 v77, 0xffff0000, v8
	v_pk_mul_f32 v[78:79], v[74:75], v[76:77]
	v_lshlrev_b32_e32 v74, 16, v12
	v_lshlrev_b32_e32 v76, 16, v16
	v_and_b32_e32 v77, 0xffff0000, v16
	v_and_b32_e32 v75, 0xffff0000, v12
	v_pk_mul_f32 v[76:77], v[52:53], v[76:77] op_sel_hi:[0,1]
	v_lshlrev_b32_e32 v82, 16, v24
	v_and_b32_e32 v83, 0xffff0000, v24
	v_lshlrev_b32_e32 v80, 16, v20
	v_and_b32_e32 v81, 0xffff0000, v20
	v_pk_mul_f32 v[84:85], v[76:77], v[74:75]
	v_pk_mul_f32 v[74:75], v[54:55], v[82:83] op_sel_hi:[0,1]
	v_pk_mul_f32 v[80:81], v[74:75], v[80:81]
	global_load_dwordx2 v[82:83], v[28:29], off offset:16
	global_load_dwordx4 v[74:77], v[28:29], off
	v_and_b32_e32 v1, 0xffff0000, v1
	v_lshlrev_b32_e32 v8, 16, v9
	v_and_b32_e32 v9, 0xffff0000, v9
	v_pk_mul_f32 v[0:1], v[0:1], v[8:9]
	v_lshlrev_b32_e32 v8, 16, v13
	v_and_b32_e32 v9, 0xffff0000, v13
	v_lshlrev_b32_e32 v12, 16, v17
	v_and_b32_e32 v13, 0xffff0000, v17
	v_lshlrev_b32_e32 v16, 16, v21
	v_and_b32_e32 v17, 0xffff0000, v21
	v_lshlrev_b32_e32 v20, 16, v25
	v_and_b32_e32 v21, 0xffff0000, v25
	v_pk_mul_f32 v[12:13], v[52:53], v[12:13] op_sel_hi:[0,1]
	v_and_b32_e32 v69, 0xffff0000, v4
	v_pk_mul_f32 v[8:9], v[12:13], v[8:9]
	v_pk_mul_f32 v[12:13], v[54:55], v[20:21] op_sel_hi:[0,1]
	v_pk_mul_f32 v[12:13], v[12:13], v[16:17]
	v_lshlrev_b32_e32 v24, 16, v26
	v_and_b32_e32 v25, 0xffff0000, v26
	v_lshlrev_b32_e32 v4, 16, v5
	v_and_b32_e32 v5, 0xffff0000, v5
	s_waitcnt vmcnt(0) lgkmcnt(0)
	v_mov_b32_e32 v87, v83
	v_pk_mov_b32 v[82:83], v[74:75], v[82:83] op_sel:[1,0]
	v_mov_b32_e32 v86, v76
	v_pk_mul_f32 v[82:83], v[82:83], v[84:85]
	v_mov_b32_e32 v75, v77
	v_pk_fma_f32 v[78:79], v[78:79], v[86:87], v[82:83]
	s_nop 0
	v_pk_fma_f32 v[74:75], v[74:75], v[80:81], v[78:79]
	s_nop 0
	v_pk_mul_f32 v[68:69], v[74:75], v[68:69]
	global_load_dwordx2 v[16:17], v[28:29], off offset:40
	global_load_dwordx4 v[74:77], v[28:29], off offset:24
	s_waitcnt vmcnt(0) lgkmcnt(0)
	v_mov_b32_e32 v21, v17
	v_pk_mov_b32 v[16:17], v[74:75], v[16:17] op_sel:[1,0]
	v_mov_b32_e32 v20, v76
	v_pk_mul_f32 v[8:9], v[8:9], v[16:17]
	v_mov_b32_e32 v75, v77
	v_pk_fma_f32 v[0:1], v[0:1], v[20:21], v[8:9]
	v_lshlrev_b32_e32 v8, 16, v2
	v_pk_fma_f32 v[0:1], v[12:13], v[74:75], v[0:1]
	v_and_b32_e32 v9, 0xffff0000, v2
	v_lshlrev_b32_e32 v12, 16, v10
	v_and_b32_e32 v13, 0xffff0000, v10
	v_lshlrev_b32_e32 v16, 16, v18
	v_and_b32_e32 v17, 0xffff0000, v18
	v_pk_mul_f32 v[8:9], v[8:9], v[12:13]
	v_lshlrev_b32_e32 v12, 16, v14
	v_and_b32_e32 v13, 0xffff0000, v14
	v_pk_mul_f32 v[16:17], v[52:53], v[16:17] op_sel_hi:[0,1]
	v_lshlrev_b32_e32 v20, 16, v22
	v_and_b32_e32 v21, 0xffff0000, v22
	v_pk_mul_f32 v[12:13], v[16:17], v[12:13]
	v_pk_mul_f32 v[16:17], v[54:55], v[24:25] op_sel_hi:[0,1]
	v_pk_mul_f32 v[16:17], v[16:17], v[20:21]
	global_load_dwordx2 v[20:21], v[28:29], off offset:64
	global_load_dwordx4 v[74:77], v[28:29], off offset:48
	v_pk_mul_f32 v[0:1], v[0:1], v[4:5]
	v_lshlrev_b32_e32 v4, 16, v6
	v_and_b32_e32 v5, 0xffff0000, v6
	v_lshlrev_b32_e32 v2, 16, v3
	v_and_b32_e32 v3, 0xffff0000, v3
	v_lshlrev_b32_e32 v14, 16, v27
	v_lshlrev_b32_e32 v6, 16, v7
	v_and_b32_e32 v7, 0xffff0000, v7
	s_waitcnt vmcnt(0) lgkmcnt(0)
	v_mov_b32_e32 v25, v21
	v_pk_mov_b32 v[20:21], v[74:75], v[20:21] op_sel:[1,0]
	v_mov_b32_e32 v24, v76
	v_pk_mul_f32 v[12:13], v[12:13], v[20:21]
	v_mov_b32_e32 v75, v77
	v_pk_fma_f32 v[8:9], v[8:9], v[24:25], v[12:13]
	v_lshlrev_b32_e32 v12, 16, v23
	v_pk_fma_f32 v[8:9], v[16:17], v[74:75], v[8:9]
	v_and_b32_e32 v13, 0xffff0000, v23
	v_pk_mul_f32 v[8:9], v[8:9], v[4:5]
	v_lshlrev_b32_e32 v4, 16, v11
	v_and_b32_e32 v5, 0xffff0000, v11
	v_pk_mul_f32 v[10:11], v[2:3], v[4:5]
	v_lshlrev_b32_e32 v4, 16, v19
	v_and_b32_e32 v5, 0xffff0000, v19
	v_lshlrev_b32_e32 v2, 16, v15
	v_and_b32_e32 v3, 0xffff0000, v15
	v_and_b32_e32 v15, 0xffff0000, v27
	v_pk_mul_f32 v[4:5], v[52:53], v[4:5] op_sel_hi:[0,1]
	v_pk_mul_f32 v[16:17], v[4:5], v[2:3]
	v_pk_mul_f32 v[2:3], v[54:55], v[14:15] op_sel_hi:[0,1]
	v_pk_mul_f32 v[12:13], v[2:3], v[12:13]
	global_load_dwordx2 v[14:15], v[28:29], off offset:88
	global_load_dwordx4 v[2:5], v[28:29], off offset:72
	s_waitcnt vmcnt(0) lgkmcnt(0)
; __device__ __forceinline__ void unpack8(const u32x4 w, float (&f)[8]) { f[0] = bflo(w.x); f[1] = bfhi(w.x); f[2] = bflo(w.y); f[3] = bfhi(w.y); f[4] = bflo(w.z); f[5] = bfhi(w.z); f[6] = bflo(w.w); f[7] = bfhi(w.w); }
; __device__ __forceinline__ u32x4 pack8(const float (&f)[8]) { u32x4 w; w.x = pk_bf16(f[0], f[1]); w.y = pk_bf16(f[2], f[3]); w.z = pk_bf16(f[4], f[5]); w.w = pk_bf16(f[6], f[7]); return w; }
; __device__ __forceinline__ void e2_phase(const bf16* P, const float* convw, const float* mu, bf16* mix, bf16* alora, int gw, int ngw, int lane) {
;     ...
;         for (int i = 0; i < 2; ++i) { const int c = (lane + 64 * i) * 8;
;             float bg[8], u0[8], u1[8], u2[8], tmp[8];
;             unpack8(*(const u32x4*)(pr + c), bg);
;             unpack8(*(const u32x4*)(pr + 1024 + c), u0); unpack8(*(const u32x4*)(pr + 2048 + c), tmp);
; #pragma unroll
;             for (int e = 0; e < 8; ++e) u0[e] *= tmp[e];
;             { const bf16* p1 = (t >= 1) ? pr - EV_IN_P : pr; const bf16* p2 = (t >= 2) ? pr - 2 * EV_IN_P : pr; const float z1 = (t >= 1) ? 1.f : 0.f, z2 = (t >= 2) ? 1.f : 0.f;
;               float t2[8];
;               unpack8(*(const u32x4*)(p1 + 1024 + c), u1); unpack8(*(const u32x4*)(p1 + 2048 + c), tmp); unpack8(*(const u32x4*)(p2 + 1024 + c), u2); unpack8(*(const u32x4*)(p2 + 2048 + c), t2);
; #pragma unroll
;               for (int e = 0; e < 8; ++e) { u1[e] *= tmp[e] * z1; u2[e] *= t2[e] * z2; } }
;             float o[8]; const float* cw = convw + c * 3;
; #pragma unroll
;             for (int e = 0; e < 8; ++e) o[e] = bg[e] * (cw[3 * e + 2] * u0[e] + cw[3 * e + 1] * u1[e] + cw[3 * e] * u2[e]);
;             *(u32x4*)(mix + (size_t)m * D + c) = pack8(o); }
	v_mov_b32_e32 v19, v15
	v_pk_mov_b32 v[14:15], v[2:3], v[14:15] op_sel:[1,0]
	v_mov_b32_e32 v18, v4
	v_pk_mul_f32 v[14:15], v[16:17], v[14:15]
	v_mov_b32_e32 v3, v5
	v_pk_fma_f32 v[10:11], v[10:11], v[18:19], v[14:15]
	v_cvt_pk_bf16_f32 v4, v8, v9
	v_pk_fma_f32 v[2:3], v[12:13], v[2:3], v[10:11]
	s_nop 0
	v_pk_mul_f32 v[6:7], v[2:3], v[6:7]
	v_cvt_pk_bf16_f32 v2, v68, v69
	v_cvt_pk_bf16_f32 v3, v0, v1
	v_cvt_pk_bf16_f32 v5, v6, v7
	global_store_dwordx4 v[44:45], v[2:5], off
	global_load_dwordx4 v[0:3], v[56:57], off offset:1024
	s_nop 0
	global_load_dwordx4 v[4:7], v[56:57], off offset:3072
	global_load_dwordx4 v[8:11], v[58:59], off offset:1024
	global_load_dwordx4 v[12:15], v[60:61], off offset:3072
	global_load_dwordx4 v[16:19], v[62:63], off offset:1024
	global_load_dwordx4 v[20:23], v[64:65], off offset:3072
	global_load_dwordx4 v[24:27], v[66:67], off offset:1024
	s_waitcnt vmcnt(0) lgkmcnt(0)
	v_lshlrev_b32_e32 v60, 16, v0
	v_lshlrev_b32_e32 v56, 16, v4
	v_and_b32_e32 v57, 0xffff0000, v4
	v_lshlrev_b32_e32 v58, 16, v8
	v_and_b32_e32 v59, 0xffff0000, v8
	v_pk_mul_f32 v[62:63], v[56:57], v[58:59]
	v_lshlrev_b32_e32 v58, 16, v16
	v_and_b32_e32 v59, 0xffff0000, v16
	v_lshlrev_b32_e32 v56, 16, v12
	v_and_b32_e32 v57, 0xffff0000, v12
	v_lshlrev_b32_e32 v66, 16, v24
	v_and_b32_e32 v67, 0xffff0000, v24
	v_pk_mul_f32 v[58:59], v[52:53], v[58:59] op_sel_hi:[0,1]
	v_lshlrev_b32_e32 v64, 16, v20
	v_and_b32_e32 v65, 0xffff0000, v20
	v_pk_mul_f32 v[68:69], v[58:59], v[56:57]
	v_pk_mul_f32 v[56:57], v[54:55], v[66:67] op_sel_hi:[0,1]
	v_pk_mul_f32 v[64:65], v[56:57], v[64:65]
	global_load_dwordx2 v[66:67], v[30:31], off offset:16
	global_load_dwordx4 v[56:59], v[30:31], off
	v_lshlrev_b32_e32 v4, 16, v5
	v_and_b32_e32 v5, 0xffff0000, v5
	v_lshlrev_b32_e32 v8, 16, v9
	v_and_b32_e32 v9, 0xffff0000, v9
	v_pk_mul_f32 v[4:5], v[4:5], v[8:9]
	v_lshlrev_b32_e32 v8, 16, v13
	v_and_b32_e32 v9, 0xffff0000, v13
	v_lshlrev_b32_e32 v12, 16, v17
	v_and_b32_e32 v13, 0xffff0000, v17
	v_lshlrev_b32_e32 v16, 16, v21
	v_and_b32_e32 v17, 0xffff0000, v21
	v_lshlrev_b32_e32 v20, 16, v25
	v_and_b32_e32 v21, 0xffff0000, v25
	v_pk_mul_f32 v[12:13], v[52:53], v[12:13] op_sel_hi:[0,1]
	v_and_b32_e32 v61, 0xffff0000, v0
	v_pk_mul_f32 v[8:9], v[12:13], v[8:9]
	v_pk_mul_f32 v[12:13], v[54:55], v[20:21] op_sel_hi:[0,1]
	v_pk_mul_f32 v[12:13], v[12:13], v[16:17]
	v_lshlrev_b32_e32 v24, 16, v26
	v_and_b32_e32 v25, 0xffff0000, v26
	v_lshlrev_b32_e32 v0, 16, v1
	v_and_b32_e32 v1, 0xffff0000, v1
	s_waitcnt vmcnt(0) lgkmcnt(0)
	v_mov_b32_e32 v75, v67
	v_pk_mov_b32 v[66:67], v[56:57], v[66:67] op_sel:[1,0]
	v_mov_b32_e32 v74, v58
	v_pk_mul_f32 v[66:67], v[66:67], v[68:69]
	v_mov_b32_e32 v57, v59
	v_pk_fma_f32 v[62:63], v[62:63], v[74:75], v[66:67]
	s_nop 0
	v_pk_fma_f32 v[56:57], v[56:57], v[64:65], v[62:63]
	s_nop 0
	v_pk_mul_f32 v[60:61], v[56:57], v[60:61]
	global_load_dwordx2 v[16:17], v[30:31], off offset:40
	global_load_dwordx4 v[56:59], v[30:31], off offset:24
	s_waitcnt vmcnt(0) lgkmcnt(0)
	v_mov_b32_e32 v21, v17
	v_pk_mov_b32 v[16:17], v[56:57], v[16:17] op_sel:[1,0]
	v_mov_b32_e32 v20, v58
	v_pk_mul_f32 v[8:9], v[8:9], v[16:17]
	v_mov_b32_e32 v57, v59
	v_pk_fma_f32 v[4:5], v[4:5], v[20:21], v[8:9]
	v_lshlrev_b32_e32 v8, 16, v6
	v_pk_fma_f32 v[4:5], v[12:13], v[56:57], v[4:5]
	v_and_b32_e32 v9, 0xffff0000, v6
	v_lshlrev_b32_e32 v12, 16, v10
	v_and_b32_e32 v13, 0xffff0000, v10
	v_lshlrev_b32_e32 v16, 16, v18
	v_and_b32_e32 v17, 0xffff0000, v18
	v_pk_mul_f32 v[8:9], v[8:9], v[12:13]
	v_lshlrev_b32_e32 v12, 16, v14
	v_and_b32_e32 v13, 0xffff0000, v14
	v_pk_mul_f32 v[16:17], v[52:53], v[16:17] op_sel_hi:[0,1]
	v_lshlrev_b32_e32 v20, 16, v22
	v_and_b32_e32 v21, 0xffff0000, v22
	v_pk_mul_f32 v[12:13], v[16:17], v[12:13]
	v_pk_mul_f32 v[16:17], v[54:55], v[24:25] op_sel_hi:[0,1]
	v_pk_mul_f32 v[16:17], v[16:17], v[20:21]
	global_load_dwordx2 v[20:21], v[30:31], off offset:64
	global_load_dwordx4 v[56:59], v[30:31], off offset:48
	v_pk_mul_f32 v[4:5], v[4:5], v[0:1]
	v_lshlrev_b32_e32 v0, 16, v2
	v_and_b32_e32 v1, 0xffff0000, v2
	v_lshlrev_b32_e32 v2, 16, v11
	v_lshlrev_b32_e32 v14, 16, v27
	v_lshlrev_b32_e32 v10, 16, v23
	s_waitcnt vmcnt(0) lgkmcnt(0)
; __device__ __forceinline__ float bf2f(bf16 b) { return __uint_as_float((unsigned)b << 16); }
; __device__ __forceinline__ bf16 f2bf(float f) { return (bf16)(pk_bf16(f, 0.f) & 0xffffu); }
; __device__ __forceinline__ u32x4 pack8(const float (&f)[8]) { u32x4 w; w.x = pk_bf16(f[0], f[1]); w.y = pk_bf16(f[2], f[3]); w.z = pk_bf16(f[4], f[5]); w.w = pk_bf16(f[6], f[7]); return w; }
; __device__ __forceinline__ float fsigmoid(float x) { return __builtin_amdgcn_rcpf(1.0f + fexp(-x)); }
; __device__ __forceinline__ float ftanh(float x) { return 1.0f - 2.0f * __builtin_amdgcn_rcpf(1.0f + fexp(2.0f * x)); }
; __device__ __forceinline__ void e2_phase(const bf16* P, const float* convw, const float* mu, bf16* mix, bf16* alora, int gw, int ngw, int lane) {
;     ...
;             *(u32x4*)(mix + (size_t)m * D + c) = pack8(o); }
; #pragma unroll
;         for (int i = 0; i < 6; ++i) { const int idx = lane + 64 * i; float val = 0.f;
;             { const int ic = idx < 288 ? idx : 287; const float pt = bf2f(pr[6144 + ic]); const float pp = bf2f(pr[6144 + ic - ((t >= 1) ? EV_IN_P : 0)]) * ((t >= 1) ? 1.f : 0.f);
;                 const float xs = pt + (pp - pt) * mu[3072 + ic];
;                 val = idx < 64 ? ftanh(xs) : (idx < 128 ? xs : (idx < 288 ? fsigmoid(xs) : 0.f)); }
;             alora[(size_t)m * LORA_K + idx] = f2bf(val); }
	v_mov_b32_e32 v25, v21
	v_pk_mov_b32 v[20:21], v[56:57], v[20:21] op_sel:[1,0]
	v_mov_b32_e32 v24, v58
	v_pk_mul_f32 v[12:13], v[12:13], v[20:21]
	v_mov_b32_e32 v57, v59
	v_pk_fma_f32 v[8:9], v[8:9], v[24:25], v[12:13]
	v_lshlrev_b32_e32 v12, 16, v3
	v_pk_fma_f32 v[8:9], v[16:17], v[56:57], v[8:9]
	v_and_b32_e32 v13, 0xffff0000, v3
	v_pk_mul_f32 v[8:9], v[8:9], v[0:1]
	v_lshlrev_b32_e32 v0, 16, v7
	v_and_b32_e32 v1, 0xffff0000, v7
	v_and_b32_e32 v3, 0xffff0000, v11
	v_pk_mul_f32 v[6:7], v[0:1], v[2:3]
	v_lshlrev_b32_e32 v2, 16, v19
	v_and_b32_e32 v3, 0xffff0000, v19
	v_lshlrev_b32_e32 v0, 16, v15
	v_and_b32_e32 v1, 0xffff0000, v15
	v_and_b32_e32 v15, 0xffff0000, v27
	v_pk_mul_f32 v[2:3], v[52:53], v[2:3] op_sel_hi:[0,1]
	v_and_b32_e32 v11, 0xffff0000, v23
	v_pk_mul_f32 v[16:17], v[2:3], v[0:1]
	v_pk_mul_f32 v[0:1], v[54:55], v[14:15] op_sel_hi:[0,1]
	v_pk_mul_f32 v[10:11], v[0:1], v[10:11]
	global_load_dwordx2 v[14:15], v[30:31], off offset:88
	global_load_dwordx4 v[0:3], v[30:31], off offset:72
	s_waitcnt vmcnt(0) lgkmcnt(0)
	v_mov_b32_e32 v19, v15
	v_pk_mov_b32 v[14:15], v[0:1], v[14:15] op_sel:[1,0]
	v_mov_b32_e32 v18, v2
	v_pk_mul_f32 v[14:15], v[16:17], v[14:15]
	v_mov_b32_e32 v1, v3
	v_pk_fma_f32 v[6:7], v[6:7], v[18:19], v[14:15]
	v_cvt_pk_bf16_f32 v2, v8, v9
	v_pk_fma_f32 v[0:1], v[10:11], v[0:1], v[6:7]
	s_nop 0
	v_pk_mul_f32 v[6:7], v[0:1], v[12:13]
	v_cvt_pk_bf16_f32 v0, v60, v61
	v_cvt_pk_bf16_f32 v1, v4, v5
	v_cvt_pk_bf16_f32 v3, v6, v7
	global_store_dwordx4 v[44:45], v[0:3], off offset:1024
	global_load_dword v2, v[32:33], off
	v_lshl_add_u64 v[44:45], v[44:45], 0, s[42:43]
	v_or_b32_e32 v0, s2, v53
	v_ashrrev_i32_e32 v1, 31, v0
	v_lshl_add_u64 v[0:1], v[0:1], 1, s[34:35]
	global_load_ushort v0, v[0:1], off
	s_waitcnt vmcnt(0) lgkmcnt(0)
	v_lshlrev_b32_e32 v3, 16, v0
	v_lshl_add_u64 v[0:1], s[88:89], 0, v[50:51]
	v_add_co_u32_e64 v0, s[38:39], s4, v0
	global_load_dword v6, v[34:35], off
	s_nop 0
	v_addc_co_u32_e64 v1, s[38:39], 0, v1, s[38:39]
	global_load_ushort v4, v[0:1], off
	s_mov_b32 s4, 0x26a00000
	v_lshl_add_u64 v[50:51], v[50:51], 0, s[36:37]
	s_waitcnt vmcnt(0) lgkmcnt(0)
	v_lshlrev_b32_e32 v4, 16, v4
	v_fma_f32 v3, v52, v3, -v4
	v_fmac_f32_e32 v4, v2, v3
	v_add_f32_e32 v2, v4, v4
	v_mul_f32_e32 v2, 0x3fb8aa3b, v2
	v_exp_f32_e32 v2, v2
	s_nop 0
	v_add_f32_e32 v2, 1.0, v2
	v_rcp_f32_e32 v2, v2
	s_nop 0
	v_fma_f32 v2, v2, -2.0, 1.0
	v_cvt_pk_bf16_f32 v4, v2, s0
	v_lshl_add_u64 v[2:3], s[88:89], 0, v[42:43]
	v_add_co_u32_e64 v2, s[38:39], s4, v2
	v_lshl_add_u64 v[42:43], v[42:43], 0, s[30:31]
	s_nop 0
	v_addc_co_u32_e64 v3, s[38:39], 0, v3, s[38:39]
	global_store_short v[2:3], v4, off
	v_or_b32_e32 v4, s2, v55
	v_ashrrev_i32_e32 v5, 31, v4
	v_lshl_add_u64 v[4:5], v[4:5], 1, s[34:35]
	global_load_ushort v4, v[4:5], off
	s_waitcnt vmcnt(0) lgkmcnt(0)
	v_lshlrev_b32_e32 v4, 16, v4
	global_load_ushort v5, v[0:1], off offset:128
	s_waitcnt vmcnt(0) lgkmcnt(0)
	v_lshlrev_b32_e32 v5, 16, v5
	v_fma_f32 v4, v52, v4, -v5
	v_fmac_f32_e32 v5, v6, v4
	v_cvt_pk_bf16_f32 v4, v5, s0
	global_store_short v[2:3], v4, off offset:128
	v_or_b32_e32 v4, s2, v70
	v_ashrrev_i32_e32 v5, 31, v4
	v_lshl_add_u64 v[4:5], v[4:5], 1, s[34:35]
	global_load_ushort v4, v[4:5], off
	s_waitcnt vmcnt(0) lgkmcnt(0)
	v_lshlrev_b32_e32 v4, 16, v4
	global_load_ushort v5, v[0:1], off offset:256
	global_load_dword v6, v[36:37], off
	s_waitcnt vmcnt(0) lgkmcnt(0)
	v_lshlrev_b32_e32 v5, 16, v5
	v_fma_f32 v4, v52, v4, -v5
	v_fmac_f32_e32 v5, v6, v4
	v_mul_f32_e32 v4, 0xbfb8aa3b, v5
	v_exp_f32_e32 v4, v4
	global_load_dword v6, v[38:39], off
	v_add_f32_e32 v4, 1.0, v4
	v_rcp_f32_e32 v4, v4
	s_nop 0
	v_cvt_pk_bf16_f32 v4, v4, s0
	global_store_short v[2:3], v4, off offset:256
	v_or_b32_e32 v4, s2, v71
	v_ashrrev_i32_e32 v5, 31, v4
	v_lshl_add_u64 v[4:5], v[4:5], 1, s[34:35]
	global_load_ushort v4, v[4:5], off
	s_nop 0
	global_load_ushort v0, v[0:1], off offset:384
	s_waitcnt vmcnt(0) lgkmcnt(0)
	v_lshlrev_b32_e32 v4, 16, v4
	v_lshlrev_b32_e32 v0, 16, v0
	v_fma_f32 v1, v52, v4, -v0
	global_load_dword v4, v[40:41], off
	v_fmac_f32_e32 v0, v6, v1
	v_mul_f32_e32 v0, 0xbfb8aa3b, v0
	v_exp_f32_e32 v0, v0
	s_nop 0
	v_add_f32_e32 v0, 1.0, v0
	v_rcp_f32_e32 v0, v0
	s_nop 0
	v_cvt_pk_bf16_f32 v0, v0, s0
	global_store_short v[2:3], v0, off offset:384
	v_or_b32_e32 v0, s2, v72
	v_ashrrev_i32_e32 v1, 31, v0
	v_lshl_add_u64 v[0:1], v[0:1], 1, s[34:35]
	global_load_ushort v0, v[0:1], off
	s_waitcnt vmcnt(0) lgkmcnt(0)
	v_lshlrev_b32_e32 v5, 16, v0
	v_lshl_add_u64 v[0:1], s[88:89], 0, v[48:49]
	global_load_ushort v0, v[0:1], off
	v_lshl_add_u64 v[48:49], v[48:49], 0, s[36:37]
	s_waitcnt vmcnt(0) lgkmcnt(0)
	v_lshlrev_b32_e32 v0, 16, v0
	v_fma_f32 v1, v52, v5, -v0
	v_fmac_f32_e32 v0, v4, v1
	v_mul_f32_e32 v0, 0xbfb8aa3b, v0
	v_exp_f32_e32 v0, v0
	s_nop 0
	v_add_f32_e32 v0, 1.0, v0
	v_rcp_f32_e32 v0, v0
	s_nop 0
	v_cvt_pk_bf16_f32 v0, v0, s0
	s_add_u32 s0, s0, s36
	s_addc_u32 s1, s1, s37
	v_cndmask_b32_e32 v0, 0, v0, vcc
	s_cmpk_gt_i32 s10, 0x3fff
	global_store_short v[2:3], v0, off offset:512
	global_store_short v[2:3], v97, off offset:640
	s_cbranch_scc0 .LBB0_405

; __device__ __forceinline__ void tile_rstd(float (&rs)[2][4], const float* ssp, int rowtile, int wr, int fr, int fq) {
;     const int lane = fq * 16 + fr; f32x4 pa[2][4][2];
; #pragma unroll
;     for (int ai = 0; ai < 2; ++ai)
; #pragma unroll
;         for (int m = 0; m < 4; ++m) { const f32x4* p = (const f32x4*)(ssp + (size_t)(rowtile + wr * 64 + ai * HALF + m * 16 + (lane >> 2)) * 32 + (lane & 3) * 8); pa[ai][m][0] = p[0]; pa[ai][m][1] = p[1]; }
; #pragma unroll
;     for (int ai = 0; ai < 2; ++ai)
; #pragma unroll
;         for (int m = 0; m < 4; ++m) { const f32x4 a = pa[ai][m][0], b = pa[ai][m][1];
;             float t = ((a.x + a.y) + (a.z + a.w)) + ((b.x + b.y) + (b.z + b.w));
;             t += __shfl_xor(t, 1); t += __shfl_xor(t, 2);
;             rs[ai][m] = __shfl(rsqrtf(t * (1.0f / 2048.0f) + 1e-6f), fr * 4); }
.LBB0_420:
	s_lshl_b32 s0, s6, 8
	s_add_i32 s0, s0, s73
	v_or_b32_e32 v130, s0, v206
	v_ashrrev_i32_e32 v131, 31, v130
	v_lshlrev_b64 v[132:133], 7, v[130:131]
	v_lshl_add_u64 v[132:133], v[184:185], 0, v[132:133]
	global_load_dwordx4 v[232:235], v[132:133], off
	global_load_dwordx4 v[242:245], v[132:133], off offset:16
	v_or_b32_e32 v132, 16, v130
	v_ashrrev_i32_e32 v133, 31, v132
	v_lshlrev_b64 v[132:133], 7, v[132:133]
	v_lshl_add_u64 v[132:133], v[184:185], 0, v[132:133]
	global_load_dwordx4 v[246:249], v[132:133], off
	global_load_dwordx4 v[228:231], v[132:133], off offset:16
	v_or_b32_e32 v132, 32, v130
	v_ashrrev_i32_e32 v133, 31, v132
	v_lshlrev_b64 v[132:133], 7, v[132:133]
	v_lshl_add_u64 v[132:133], v[184:185], 0, v[132:133]
	global_load_dwordx4 v[170:173], v[132:133], off
	global_load_dwordx4 v[174:177], v[132:133], off offset:16
	v_or_b32_e32 v132, 48, v130
	v_ashrrev_i32_e32 v133, 31, v132
	v_lshlrev_b64 v[132:133], 7, v[132:133]
	v_lshl_add_u64 v[132:133], v[184:185], 0, v[132:133]
	global_load_dwordx4 v[166:169], v[132:133], off
	global_load_dwordx4 v[162:165], v[132:133], off offset:16
	v_add_u32_e32 v132, 0x80, v130
	v_ashrrev_i32_e32 v133, 31, v132
	v_lshlrev_b64 v[132:133], 7, v[132:133]
	v_lshl_add_u64 v[132:133], v[184:185], 0, v[132:133]
	global_load_dwordx4 v[158:161], v[132:133], off
	global_load_dwordx4 v[154:157], v[132:133], off offset:16
	v_add_u32_e32 v132, 0x90, v130
	v_ashrrev_i32_e32 v133, 31, v132
	v_lshlrev_b64 v[132:133], 7, v[132:133]
	v_lshl_add_u64 v[132:133], v[184:185], 0, v[132:133]
	global_load_dwordx4 v[150:153], v[132:133], off
	global_load_dwordx4 v[146:149], v[132:133], off offset:16
	v_add_u32_e32 v132, 0xa0, v130
	v_ashrrev_i32_e32 v133, 31, v132
	v_lshlrev_b64 v[132:133], 7, v[132:133]
	v_add_u32_e32 v130, 0xb0, v130
	v_lshl_add_u64 v[132:133], v[184:185], 0, v[132:133]
	v_ashrrev_i32_e32 v131, 31, v130
	global_load_dwordx4 v[142:145], v[132:133], off
	global_load_dwordx4 v[138:141], v[132:133], off offset:16
	v_lshlrev_b64 v[130:131], 7, v[130:131]
	v_lshl_add_u64 v[130:131], v[184:185], 0, v[130:131]
	global_load_dwordx4 v[134:137], v[130:131], off
	s_nop 0
	global_load_dwordx4 v[130:133], v[130:131], off offset:16
	v_and_b32_e32 v192, 64, v220
	v_xor_b32_e32 v191, 1, v220
	v_add_u32_e32 v192, 64, v192
	v_cmp_lt_i32_e32 vcc, v191, v192
	v_or_b32_e32 v210, s0, v193
	v_readlane_b32 s0, v254, 63
	v_cndmask_b32_e32 v191, v220, v191, vcc
	v_lshlrev_b32_e32 v212, 2, v191
	v_xor_b32_e32 v191, 2, v220
	v_cmp_lt_i32_e32 vcc, v191, v192
	v_lshl_or_b32 v190, s2, 7, v208
	v_readlane_b32 s1, v255, 0
	v_cndmask_b32_e32 v191, v220, v191, vcc
	v_lshlrev_b32_e32 v211, 2, v191
	v_lshlrev_b32_e32 v191, 2, v220
	v_and_or_b32 v191, v191, s25, v207
	s_movk_i32 s2, 0x2c00
	s_waitcnt vmcnt(0) lgkmcnt(0)
	v_mov_b32_e32 v204, v232
	v_mov_b32_e32 v205, v242
	v_mov_b32_e32 v242, v233
	v_mov_b32_e32 v214, v234
	v_mov_b32_e32 v215, v244
	v_mov_b32_e32 v244, v235
	v_pk_add_f32 v[204:205], v[204:205], v[242:243]
	v_pk_add_f32 v[214:215], v[214:215], v[244:245]
	s_nop 0
	v_pk_add_f32 v[204:205], v[204:205], v[214:215]
	v_mov_b32_e32 v214, v246
	v_mov_b32_e32 v215, v228
	v_mov_b32_e32 v228, v247
	v_pk_add_f32 v[214:215], v[214:215], v[228:229]
	v_mov_b32_e32 v228, v248
	v_mov_b32_e32 v229, v230
	v_mov_b32_e32 v230, v249
	v_pk_add_f32 v[228:229], v[228:229], v[230:231]
	s_nop 0
	v_pk_add_f32 v[214:215], v[214:215], v[228:229]
	v_mov_b32_e32 v229, v204
	v_mov_b32_e32 v228, v214
	v_mov_b32_e32 v204, v215
	v_pk_add_f32 v[204:205], v[228:229], v[204:205]
	ds_bpermute_b32 v215, v212, v205
	ds_bpermute_b32 v214, v212, v204
	s_waitcnt lgkmcnt(0)
	v_pk_add_f32 v[204:205], v[204:205], v[214:215]
	ds_bpermute_b32 v215, v211, v205
	ds_bpermute_b32 v214, v211, v204
	s_waitcnt lgkmcnt(0)
	v_pk_add_f32 v[214:215], v[204:205], v[214:215]
	v_mov_b64_e32 v[204:205], s[24:25]
	v_pk_fma_f32 v[214:215], v[214:215], s[18:19], v[204:205] op_sel_hi:[1,0,0]
	s_nop 0
	v_mul_f32_e32 v192, 0x4b800000, v215
	v_cmp_gt_f32_e64 s[40:41], s12, v215
	v_cmp_gt_f32_e32 vcc, s12, v214
	s_nop 0
	v_cndmask_b32_e64 v192, v215, v192, s[40:41]
	v_rsq_f32_e32 v192, v192
	v_mov_b32_e32 v215, v174
	v_mov_b32_e32 v174, v171
	v_mul_f32_e32 v202, 0x45800000, v192
	v_cndmask_b32_e64 v192, v192, v202, s[40:41]
	ds_bpermute_b32 v202, v191, v192
	v_mul_f32_e32 v192, 0x4b800000, v214
	v_cndmask_b32_e32 v192, v214, v192, vcc
	v_mov_b32_e32 v214, v170
	v_pk_add_f32 v[170:171], v[214:215], v[174:175]
	v_mov_b32_e32 v174, v172
	v_mov_b32_e32 v175, v176
	v_mov_b32_e32 v176, v173
	v_pk_add_f32 v[172:173], v[174:175], v[176:177]
	s_waitcnt lgkmcnt(0)
; __device__ __forceinline__ unsigned pk_bf16(float lo, float hi) { f32x2e v = {lo, hi}; bf16x2e b = __builtin_convertvector(v, bf16x2e); return __builtin_bit_cast(unsigned, b); }
; __device__ __forceinline__ float silu_mul(float g, float u) { return g * __builtin_amdgcn_rcpf(1.0f + __builtin_amdgcn_exp2f(-1.4426950408889634f * g)) * u; }
; __device__ __forceinline__ void tile_rstd(float (&rs)[2][4], const float* ssp, int rowtile, int wr, int fr, int fq) {
;     ...
;         for (int m = 0; m < 4; ++m) { const f32x4 a = pa[ai][m][0], b = pa[ai][m][1];
;             float t = ((a.x + a.y) + (a.z + a.w)) + ((b.x + b.y) + (b.z + b.w));
;             t += __shfl_xor(t, 1); t += __shfl_xor(t, 2);
;             rs[ai][m] = __shfl(rsqrtf(t * (1.0f / 2048.0f) + 1e-6f), fr * 4); }
;     __device__ __forceinline__ void operator()(const f32x4 (&acc)[2][2][4][2], const Unit& u, int wr, int wc, int fr, int fq) const {
;     ...
;             for (int m = 0; m < 4; ++m) { bf16_t* rowp = O + (size_t)(row0 + ai * HALF + m * 16) * ldc + col0;
;                 const float rs = rsa[ai][m];
;                 const f32x4 g0 = acc[ai][0][m][0] * rs, g1 = acc[ai][0][m][1] * rs, u0 = acc[ai][1][m][0] * rs, u1 = acc[ai][1][m][1] * rs;
;                 u32x4 w; w.x = pk_bf16(silu_mul(g0[0], u0[0]), silu_mul(g0[1], u0[1])); w.y = pk_bf16(silu_mul(g0[2], u0[2]), silu_mul(g0[3], u0[3]));
;                 w.z = pk_bf16(silu_mul(g1[0], u1[0]), silu_mul(g1[1], u1[1])); w.w = pk_bf16(silu_mul(g1[2], u1[2]), silu_mul(g1[3], u1[3]));
	v_pk_mul_f32 v[126:127], v[126:127], v[202:203] op_sel_hi:[1,0]
	v_pk_add_f32 v[170:171], v[170:171], v[172:173]
	v_mov_b32_e32 v172, v166
	v_mov_b32_e32 v173, v162
	v_mov_b32_e32 v162, v167
	v_mov_b32_e32 v166, v168
	v_mov_b32_e32 v167, v164
	v_mov_b32_e32 v164, v169
	v_pk_add_f32 v[164:165], v[166:167], v[164:165]
	v_mov_b32_e32 v166, v158
	v_mov_b32_e32 v167, v154
	v_mov_b32_e32 v154, v159
	v_mov_b32_e32 v158, v160
	v_mov_b32_e32 v159, v156
	v_mov_b32_e32 v156, v161
	v_pk_add_f32 v[154:155], v[166:167], v[154:155]
	v_pk_add_f32 v[156:157], v[158:159], v[156:157]
	v_pk_mul_f32 v[118:119], v[118:119], v[202:203] op_sel_hi:[1,0]
	v_pk_add_f32 v[154:155], v[154:155], v[156:157]
	v_mov_b32_e32 v156, v150
	v_mov_b32_e32 v157, v146
	v_mov_b32_e32 v146, v151
	v_mov_b32_e32 v150, v152
	v_mov_b32_e32 v151, v148
	v_mov_b32_e32 v148, v153
	v_pk_add_f32 v[148:149], v[150:151], v[148:149]
	v_mov_b32_e32 v150, v142
	v_mov_b32_e32 v151, v138
	v_mov_b32_e32 v138, v143
	v_mov_b32_e32 v142, v144
	v_mov_b32_e32 v143, v140
	v_mov_b32_e32 v140, v145
	v_pk_add_f32 v[138:139], v[150:151], v[138:139]
	v_pk_add_f32 v[140:141], v[142:143], v[140:141]
	v_pk_add_f32 v[162:163], v[172:173], v[162:163]
	v_pk_add_f32 v[138:139], v[138:139], v[140:141]
	v_mov_b32_e32 v140, v134
	v_mov_b32_e32 v141, v130
	v_mov_b32_e32 v130, v135
	v_pk_add_f32 v[130:131], v[140:141], v[130:131]
	v_pk_mul_f32 v[140:141], v[116:117], v[202:203] op_sel_hi:[1,0]
	v_pk_mul_f32 v[116:117], v[114:115], v[202:203] op_sel_hi:[1,0]
	v_mul_f32_e32 v114, 0xbfb8aa3b, v126
	v_mul_f32_e32 v115, 0xbfb8aa3b, v127
	v_exp_f32_e32 v114, v114
	v_exp_f32_e32 v115, v115
	v_pk_mul_f32 v[128:129], v[128:129], v[202:203] op_sel_hi:[1,0]
	v_pk_add_f32 v[162:163], v[162:163], v[164:165]
	v_add_f32_e32 v114, 1.0, v114
	v_add_f32_e32 v115, 1.0, v115
	v_rcp_f32_e32 v114, v114
	v_rcp_f32_e32 v115, v115
	v_mov_b32_e32 v164, v162
	v_mov_b32_e32 v165, v170
	v_mov_b32_e32 v170, v163
	v_pk_mul_f32 v[114:115], v[126:127], v[114:115]
	v_pk_add_f32 v[162:163], v[164:165], v[170:171]
	v_pk_mul_f32 v[114:115], v[118:119], v[114:115]
	ds_bpermute_b32 v165, v212, v163
	v_cvt_pk_bf16_f32 v114, v114, v115
	v_mul_f32_e32 v115, 0xbfb8aa3b, v128
	v_exp_f32_e32 v115, v115
	ds_bpermute_b32 v164, v212, v162
	v_pk_add_f32 v[146:147], v[156:157], v[146:147]
	v_mov_b32_e32 v134, v136
	v_add_f32_e32 v115, 1.0, v115
	v_rcp_f32_e32 v118, v115
	v_mul_f32_e32 v115, 0xbfb8aa3b, v129
	v_pk_add_f32 v[146:147], v[146:147], v[148:149]
	v_exp_f32_e32 v115, v115
	s_waitcnt lgkmcnt(0)
	v_pk_add_f32 v[162:163], v[162:163], v[164:165]
	v_mov_b32_e32 v148, v146
	v_mov_b32_e32 v149, v154
	v_mov_b32_e32 v154, v147
	ds_bpermute_b32 v165, v211, v163
	ds_bpermute_b32 v164, v211, v162
	v_pk_add_f32 v[146:147], v[148:149], v[154:155]
	ds_bpermute_b32 v149, v212, v147
	ds_bpermute_b32 v148, v212, v146
	v_add_f32_e32 v115, 1.0, v115
	v_mov_b32_e32 v135, v132
	v_mov_b32_e32 v132, v137
	v_rcp_f32_e32 v119, v115
	v_pk_add_f32 v[132:133], v[134:135], v[132:133]
	s_waitcnt lgkmcnt(2)
	v_pk_add_f32 v[162:163], v[162:163], v[164:165]
	v_pk_add_f32 v[130:131], v[130:131], v[132:133]
	v_pk_fma_f32 v[162:163], v[162:163], s[18:19], v[204:205] op_sel_hi:[1,0,0]
	s_waitcnt lgkmcnt(0)
	v_pk_add_f32 v[146:147], v[146:147], v[148:149]
	v_mov_b32_e32 v132, v130
	v_mov_b32_e32 v133, v138
	v_mov_b32_e32 v138, v131
	v_mul_f32_e32 v164, 0x4b800000, v163
	v_cmp_gt_f32_e64 s[40:41], s12, v163
	ds_bpermute_b32 v149, v211, v147
	ds_bpermute_b32 v148, v211, v146
	v_pk_add_f32 v[130:131], v[132:133], v[138:139]
	v_pk_mul_f32 v[120:121], v[120:121], v[202:203] op_sel_hi:[1,0]
	v_pk_mul_f32 v[118:119], v[128:129], v[118:119]
	v_cndmask_b32_e64 v163, v163, v164, s[40:41]
	ds_bpermute_b32 v133, v212, v131
	ds_bpermute_b32 v132, v212, v130
	v_pk_mul_f32 v[122:123], v[122:123], v[202:203] op_sel_hi:[1,0]
	v_pk_mul_f32 v[118:119], v[120:121], v[118:119]
	v_rsq_f32_e32 v163, v163
	v_cvt_pk_bf16_f32 v115, v118, v119
	v_mul_f32_e32 v118, 0xbfb8aa3b, v122
	v_mul_f32_e32 v119, 0xbfb8aa3b, v123
	v_rsq_f32_e32 v192, v192
	v_exp_f32_e32 v118, v118
	v_exp_f32_e32 v119, v119
	s_waitcnt lgkmcnt(2)
	v_pk_add_f32 v[146:147], v[146:147], v[148:149]
	v_mul_f32_e32 v164, 0x45800000, v163
	v_pk_fma_f32 v[146:147], v[146:147], s[18:19], v[204:205] op_sel_hi:[1,0,0]
	s_waitcnt lgkmcnt(0)
	v_pk_add_f32 v[130:131], v[130:131], v[132:133]
	v_mul_f32_e32 v213, 0x45800000, v192
	v_cndmask_b32_e64 v163, v163, v164, s[40:41]
	v_mul_f32_e32 v148, 0x4b800000, v147
	v_cmp_gt_f32_e64 s[40:41], s12, v147
	ds_bpermute_b32 v133, v211, v131
	ds_bpermute_b32 v132, v211, v130
	v_add_f32_e32 v118, 1.0, v118
	v_add_f32_e32 v119, 1.0, v119
	v_cndmask_b32_e32 v192, v192, v213, vcc
	v_cmp_gt_f32_e32 vcc, s12, v162
	ds_bpermute_b32 v164, v191, v163
	v_mul_f32_e32 v163, 0x4b800000, v162
	v_cndmask_b32_e64 v147, v147, v148, s[40:41]
	v_rcp_f32_e32 v118, v118
	v_rcp_f32_e32 v119, v119
	v_cndmask_b32_e32 v162, v162, v163, vcc
	v_rsq_f32_e32 v147, v147
	v_rsq_f32_e32 v162, v162
	s_waitcnt lgkmcnt(1)
; __device__ __forceinline__ unsigned pk_bf16(float lo, float hi) { f32x2e v = {lo, hi}; bf16x2e b = __builtin_convertvector(v, bf16x2e); return __builtin_bit_cast(unsigned, b); }
; __device__ __forceinline__ float silu_mul(float g, float u) { return g * __builtin_amdgcn_rcpf(1.0f + __builtin_amdgcn_exp2f(-1.4426950408889634f * g)) * u; }
; __device__ __forceinline__ void tile_rstd(float (&rs)[2][4], const float* ssp, int rowtile, int wr, int fr, int fq) {
;     ...
;         for (int m = 0; m < 4; ++m) { const f32x4 a = pa[ai][m][0], b = pa[ai][m][1];
;             float t = ((a.x + a.y) + (a.z + a.w)) + ((b.x + b.y) + (b.z + b.w));
;             t += __shfl_xor(t, 1); t += __shfl_xor(t, 2);
;             rs[ai][m] = __shfl(rsqrtf(t * (1.0f / 2048.0f) + 1e-6f), fr * 4); }
;     __device__ __forceinline__ void operator()(const f32x4 (&acc)[2][2][4][2], const Unit& u, int wr, int wc, int fr, int fq) const {
;     ...
;             for (int m = 0; m < 4; ++m) { bf16_t* rowp = O + (size_t)(row0 + ai * HALF + m * 16) * ldc + col0;
;                 const float rs = rsa[ai][m];
;                 const f32x4 g0 = acc[ai][0][m][0] * rs, g1 = acc[ai][0][m][1] * rs, u0 = acc[ai][1][m][0] * rs, u1 = acc[ai][1][m][1] * rs;
;                 u32x4 w; w.x = pk_bf16(silu_mul(g0[0], u0[0]), silu_mul(g0[1], u0[1])); w.y = pk_bf16(silu_mul(g0[2], u0[2]), silu_mul(g0[3], u0[3]));
;                 w.z = pk_bf16(silu_mul(g1[0], u1[0]), silu_mul(g1[1], u1[1])); w.w = pk_bf16(silu_mul(g1[2], u1[2]), silu_mul(g1[3], u1[3]));
;                 *(u32x4*)rowp = w; }
	v_pk_add_f32 v[130:131], v[130:131], v[132:133]
	v_pk_mul_f32 v[118:119], v[122:123], v[118:119]
	v_mul_f32_e32 v148, 0x45800000, v147
	v_pk_fma_f32 v[130:131], v[130:131], s[18:19], v[204:205] op_sel_hi:[1,0,0]
	v_pk_mul_f32 v[124:125], v[124:125], v[202:203] op_sel_hi:[1,0]
	v_pk_mul_f32 v[116:117], v[116:117], v[118:119]
	v_mul_f32_e32 v163, 0x45800000, v162
	v_cndmask_b32_e64 v147, v147, v148, s[40:41]
	v_mul_f32_e32 v132, 0x4b800000, v131
	v_cmp_gt_f32_e64 s[40:41], s12, v131
	v_cvt_pk_bf16_f32 v116, v116, v117
	v_mul_f32_e32 v117, 0xbfb8aa3b, v124
	v_cndmask_b32_e32 v162, v162, v163, vcc
	v_cmp_gt_f32_e32 vcc, s12, v146
	ds_bpermute_b32 v148, v191, v147
	v_mul_f32_e32 v147, 0x4b800000, v146
	v_cndmask_b32_e64 v131, v131, v132, s[40:41]
	v_exp_f32_e32 v117, v117
	v_cndmask_b32_e32 v146, v146, v147, vcc
	v_rsq_f32_e32 v131, v131
	v_rsq_f32_e32 v146, v146
	v_add_f32_e32 v117, 1.0, v117
	v_rcp_f32_e32 v118, v117
	v_mul_f32_e32 v132, 0x45800000, v131
	v_mul_f32_e32 v117, 0xbfb8aa3b, v125
	v_mul_f32_e32 v147, 0x45800000, v146
	v_cndmask_b32_e64 v131, v131, v132, s[40:41]
	v_exp_f32_e32 v117, v117
	v_cndmask_b32_e32 v146, v146, v147, vcc
	v_cmp_gt_f32_e32 vcc, s12, v130
	ds_bpermute_b32 v136, v191, v131
	v_mul_f32_e32 v131, 0x4b800000, v130
	v_cndmask_b32_e32 v130, v130, v131, vcc
	v_rsq_f32_e32 v130, v130
	v_add_f32_e32 v117, 1.0, v117
	v_rcp_f32_e32 v119, v117
	ds_bpermute_b32 v192, v191, v192
	v_mul_f32_e32 v131, 0x45800000, v130
	v_cndmask_b32_e32 v130, v130, v131, vcc
	ds_bpermute_b32 v162, v191, v162
	ds_bpermute_b32 v146, v191, v146
	ds_bpermute_b32 v130, v191, v130
	v_ashrrev_i32_e32 v191, 31, v190
	v_mov_b64_e32 v[132:133], s[0:1]
	v_pk_mul_f32 v[118:119], v[124:125], v[118:119]
	v_mad_i64_i32 v[138:139], s[0:1], v210, s2, v[132:133]
	v_lshlrev_b64 v[134:135], 1, v[190:191]
	v_pk_mul_f32 v[118:119], v[140:141], v[118:119]
	v_lshl_add_u64 v[138:139], v[138:139], 0, v[134:135]
	v_cvt_pk_bf16_f32 v117, v118, v119
	s_waitcnt lgkmcnt(3)
	v_pk_mul_f32 v[110:111], v[110:111], v[192:193] op_sel_hi:[1,0]
	global_store_dwordx4 v[138:139], v[114:117], off
	v_pk_mul_f32 v[102:103], v[102:103], v[192:193] op_sel_hi:[1,0]
	v_pk_mul_f32 v[112:113], v[112:113], v[192:193] op_sel_hi:[1,0]
	v_pk_mul_f32 v[116:117], v[100:101], v[192:193] op_sel_hi:[1,0]
	v_pk_mul_f32 v[100:101], v[98:99], v[192:193] op_sel_hi:[1,0]
	v_mul_f32_e32 v98, 0xbfb8aa3b, v110
	v_mul_f32_e32 v99, 0xbfb8aa3b, v111
	v_exp_f32_e32 v98, v98
	v_exp_f32_e32 v99, v99
	v_pk_mul_f32 v[104:105], v[104:105], v[192:193] op_sel_hi:[1,0]
	v_pk_mul_f32 v[106:107], v[106:107], v[192:193] op_sel_hi:[1,0]
	v_add_f32_e32 v98, 1.0, v98
	v_add_f32_e32 v99, 1.0, v99
	v_rcp_f32_e32 v98, v98
	v_rcp_f32_e32 v99, v99
	v_pk_mul_f32 v[108:109], v[108:109], v[192:193] op_sel_hi:[1,0]
	v_or_b32_e32 v114, 16, v210
	v_mad_i64_i32 v[114:115], s[0:1], v114, s2, v[132:133]
	v_pk_mul_f32 v[98:99], v[110:111], v[98:99]
	v_lshl_add_u64 v[114:115], v[114:115], 0, v[134:135]
	v_pk_mul_f32 v[98:99], v[102:103], v[98:99]
	v_pk_mul_f32 v[92:93], v[92:93], v[164:165] op_sel_hi:[1,0]
	v_cvt_pk_bf16_f32 v98, v98, v99
	v_mul_f32_e32 v99, 0xbfb8aa3b, v112
	v_exp_f32_e32 v99, v99
	v_pk_mul_f32 v[84:85], v[84:85], v[164:165] op_sel_hi:[1,0]
	v_pk_mul_f32 v[94:95], v[94:95], v[164:165] op_sel_hi:[1,0]
	v_pk_mul_f32 v[86:87], v[86:87], v[164:165] op_sel_hi:[1,0]
	v_add_f32_e32 v99, 1.0, v99
	v_rcp_f32_e32 v102, v99
	v_mul_f32_e32 v99, 0xbfb8aa3b, v113
	v_exp_f32_e32 v99, v99
	v_pk_mul_f32 v[88:89], v[88:89], v[164:165] op_sel_hi:[1,0]
	v_pk_mul_f32 v[90:91], v[90:91], v[164:165] op_sel_hi:[1,0]
	s_waitcnt lgkmcnt(0)
	v_pk_mul_f32 v[76:77], v[76:77], v[162:163] op_sel_hi:[1,0]
	v_add_f32_e32 v99, 1.0, v99
	v_rcp_f32_e32 v103, v99
	v_pk_mul_f32 v[68:69], v[68:69], v[162:163] op_sel_hi:[1,0]
	v_pk_mul_f32 v[78:79], v[78:79], v[162:163] op_sel_hi:[1,0]
	v_pk_mul_f32 v[70:71], v[70:71], v[162:163] op_sel_hi:[1,0]
	v_pk_mul_f32 v[102:103], v[112:113], v[102:103]
	v_pk_mul_f32 v[72:73], v[72:73], v[162:163] op_sel_hi:[1,0]
	v_pk_mul_f32 v[102:103], v[104:105], v[102:103]
	v_pk_mul_f32 v[74:75], v[74:75], v[162:163] op_sel_hi:[1,0]
	v_cvt_pk_bf16_f32 v99, v102, v103
	v_mul_f32_e32 v102, 0xbfb8aa3b, v106
	v_mul_f32_e32 v103, 0xbfb8aa3b, v107
	v_exp_f32_e32 v102, v102
	v_exp_f32_e32 v103, v103
	v_pk_mul_f32 v[60:61], v[60:61], v[148:149] op_sel_hi:[1,0]
	v_pk_mul_f32 v[52:53], v[52:53], v[148:149] op_sel_hi:[1,0]
	v_add_f32_e32 v102, 1.0, v102
	v_add_f32_e32 v103, 1.0, v103
	v_rcp_f32_e32 v102, v102
	v_rcp_f32_e32 v103, v103
	v_pk_mul_f32 v[62:63], v[62:63], v[148:149] op_sel_hi:[1,0]
	v_pk_mul_f32 v[54:55], v[54:55], v[148:149] op_sel_hi:[1,0]
	v_pk_mul_f32 v[56:57], v[56:57], v[148:149] op_sel_hi:[1,0]
	v_pk_mul_f32 v[102:103], v[106:107], v[102:103]
	v_pk_mul_f32 v[58:59], v[58:59], v[148:149] op_sel_hi:[1,0]
	v_pk_mul_f32 v[100:101], v[100:101], v[102:103]
	v_pk_mul_f32 v[44:45], v[44:45], v[146:147] op_sel_hi:[1,0]
	v_cvt_pk_bf16_f32 v100, v100, v101
	v_mul_f32_e32 v101, 0xbfb8aa3b, v108
	v_exp_f32_e32 v101, v101
	v_pk_mul_f32 v[36:37], v[36:37], v[146:147] op_sel_hi:[1,0]
	v_pk_mul_f32 v[46:47], v[46:47], v[146:147] op_sel_hi:[1,0]
	v_pk_mul_f32 v[38:39], v[38:39], v[146:147] op_sel_hi:[1,0]
	v_add_f32_e32 v101, 1.0, v101
	v_rcp_f32_e32 v102, v101
	v_mul_f32_e32 v101, 0xbfb8aa3b, v109
	v_exp_f32_e32 v101, v101
	v_pk_mul_f32 v[40:41], v[40:41], v[146:147] op_sel_hi:[1,0]
	v_pk_mul_f32 v[42:43], v[42:43], v[146:147] op_sel_hi:[1,0]
	v_pk_mul_f32 v[28:29], v[28:29], v[136:137] op_sel_hi:[1,0]
	v_add_f32_e32 v101, 1.0, v101
	v_rcp_f32_e32 v103, v101
	v_pk_mul_f32 v[20:21], v[20:21], v[136:137] op_sel_hi:[1,0]
; __device__ __forceinline__ unsigned pk_bf16(float lo, float hi) { f32x2e v = {lo, hi}; bf16x2e b = __builtin_convertvector(v, bf16x2e); return __builtin_bit_cast(unsigned, b); }
; __device__ __forceinline__ float silu_mul(float g, float u) { return g * __builtin_amdgcn_rcpf(1.0f + __builtin_amdgcn_exp2f(-1.4426950408889634f * g)) * u; }
;     __device__ __forceinline__ void operator()(const f32x4 (&acc)[2][2][4][2], const Unit& u, int wr, int wc, int fr, int fq) const {
;     ...
;             for (int m = 0; m < 4; ++m) { bf16_t* rowp = O + (size_t)(row0 + ai * HALF + m * 16) * ldc + col0;
;                 const float rs = rsa[ai][m];
;                 const f32x4 g0 = acc[ai][0][m][0] * rs, g1 = acc[ai][0][m][1] * rs, u0 = acc[ai][1][m][0] * rs, u1 = acc[ai][1][m][1] * rs;
;                 u32x4 w; w.x = pk_bf16(silu_mul(g0[0], u0[0]), silu_mul(g0[1], u0[1])); w.y = pk_bf16(silu_mul(g0[2], u0[2]), silu_mul(g0[3], u0[3]));
;                 w.z = pk_bf16(silu_mul(g1[0], u1[0]), silu_mul(g1[1], u1[1])); w.w = pk_bf16(silu_mul(g1[2], u1[2]), silu_mul(g1[3], u1[3]));
;                 *(u32x4*)rowp = w; }
	v_pk_mul_f32 v[30:31], v[30:31], v[136:137] op_sel_hi:[1,0]
	v_pk_mul_f32 v[22:23], v[22:23], v[136:137] op_sel_hi:[1,0]
	v_pk_mul_f32 v[102:103], v[108:109], v[102:103]
	v_pk_mul_f32 v[24:25], v[24:25], v[136:137] op_sel_hi:[1,0]
	v_pk_mul_f32 v[102:103], v[116:117], v[102:103]
	v_pk_mul_f32 v[26:27], v[26:27], v[136:137] op_sel_hi:[1,0]
	v_cvt_pk_bf16_f32 v101, v102, v103
	global_store_dwordx4 v[114:115], v[98:101], off
	v_pk_mul_f32 v[12:13], v[12:13], v[130:131] op_sel_hi:[1,0]
	v_pk_mul_f32 v[4:5], v[4:5], v[130:131] op_sel_hi:[1,0]
	v_pk_mul_f32 v[100:101], v[82:83], v[164:165] op_sel_hi:[1,0]
	v_pk_mul_f32 v[82:83], v[80:81], v[164:165] op_sel_hi:[1,0]
	v_mul_f32_e32 v80, 0xbfb8aa3b, v92
	v_mul_f32_e32 v81, 0xbfb8aa3b, v93
	v_exp_f32_e32 v80, v80
	v_exp_f32_e32 v81, v81
	v_or_b32_e32 v98, 32, v210
	v_mad_i64_i32 v[98:99], s[0:1], v98, s2, v[132:133]
	v_add_f32_e32 v80, 1.0, v80
	v_add_f32_e32 v81, 1.0, v81
	v_rcp_f32_e32 v80, v80
	v_rcp_f32_e32 v81, v81
	v_lshl_add_u64 v[98:99], v[98:99], 0, v[134:135]
	v_pk_mul_f32 v[14:15], v[14:15], v[130:131] op_sel_hi:[1,0]
	v_pk_mul_f32 v[6:7], v[6:7], v[130:131] op_sel_hi:[1,0]
	v_pk_mul_f32 v[80:81], v[92:93], v[80:81]
	v_pk_mul_f32 v[8:9], v[8:9], v[130:131] op_sel_hi:[1,0]
	v_pk_mul_f32 v[80:81], v[84:85], v[80:81]
	v_pk_mul_f32 v[10:11], v[10:11], v[130:131] op_sel_hi:[1,0]
	v_cvt_pk_bf16_f32 v80, v80, v81
	v_mul_f32_e32 v81, 0xbfb8aa3b, v94
	v_exp_f32_e32 v81, v81
	s_andn2_b64 vcc, exec, s[38:39]
	v_add_f32_e32 v81, 1.0, v81
	v_rcp_f32_e32 v84, v81
	v_mul_f32_e32 v81, 0xbfb8aa3b, v95
	v_exp_f32_e32 v81, v81
	s_nop 0
	v_add_f32_e32 v81, 1.0, v81
	v_rcp_f32_e32 v85, v81
	s_nop 0
	v_pk_mul_f32 v[84:85], v[94:95], v[84:85]
	s_nop 0
	v_pk_mul_f32 v[84:85], v[86:87], v[84:85]
	s_nop 0
	v_cvt_pk_bf16_f32 v81, v84, v85
	v_mul_f32_e32 v84, 0xbfb8aa3b, v88
	v_mul_f32_e32 v85, 0xbfb8aa3b, v89
	v_exp_f32_e32 v84, v84
	v_exp_f32_e32 v85, v85
	v_add_f32_e32 v84, 1.0, v84
	v_add_f32_e32 v85, 1.0, v85
	v_rcp_f32_e32 v84, v84
	v_rcp_f32_e32 v85, v85
	s_nop 0
	v_pk_mul_f32 v[84:85], v[88:89], v[84:85]
	s_nop 0
	v_pk_mul_f32 v[82:83], v[82:83], v[84:85]
	s_nop 0
	v_cvt_pk_bf16_f32 v82, v82, v83
	v_mul_f32_e32 v83, 0xbfb8aa3b, v90
	v_exp_f32_e32 v83, v83
	s_nop 0
	v_add_f32_e32 v83, 1.0, v83
	v_rcp_f32_e32 v84, v83
	v_mul_f32_e32 v83, 0xbfb8aa3b, v91
	v_exp_f32_e32 v83, v83
	s_nop 0
	v_add_f32_e32 v83, 1.0, v83
	v_rcp_f32_e32 v85, v83
	s_nop 0
	v_pk_mul_f32 v[84:85], v[90:91], v[84:85]
	s_nop 0
	v_pk_mul_f32 v[84:85], v[100:101], v[84:85]
	s_nop 0
	v_cvt_pk_bf16_f32 v83, v84, v85
	global_store_dwordx4 v[98:99], v[80:83], off
	s_nop 1
	v_pk_mul_f32 v[82:83], v[66:67], v[162:163] op_sel_hi:[1,0]
	v_pk_mul_f32 v[66:67], v[64:65], v[162:163] op_sel_hi:[1,0]
	v_mul_f32_e32 v64, 0xbfb8aa3b, v76
	v_mul_f32_e32 v65, 0xbfb8aa3b, v77
	v_exp_f32_e32 v64, v64
	v_exp_f32_e32 v65, v65
	v_or_b32_e32 v80, 48, v210
	v_mad_i64_i32 v[80:81], s[0:1], v80, s2, v[132:133]
	v_add_f32_e32 v64, 1.0, v64
	v_add_f32_e32 v65, 1.0, v65
	v_rcp_f32_e32 v64, v64
	v_rcp_f32_e32 v65, v65
	v_lshl_add_u64 v[80:81], v[80:81], 0, v[134:135]
	v_pk_mul_f32 v[64:65], v[76:77], v[64:65]
	s_nop 0
	v_pk_mul_f32 v[64:65], v[68:69], v[64:65]
	s_nop 0
	v_cvt_pk_bf16_f32 v64, v64, v65
	v_mul_f32_e32 v65, 0xbfb8aa3b, v78
	v_exp_f32_e32 v65, v65
	s_nop 0
	v_add_f32_e32 v65, 1.0, v65
	v_rcp_f32_e32 v68, v65
	v_mul_f32_e32 v65, 0xbfb8aa3b, v79
	v_exp_f32_e32 v65, v65
	s_nop 0
	v_add_f32_e32 v65, 1.0, v65
	v_rcp_f32_e32 v69, v65
	s_nop 0
	v_pk_mul_f32 v[68:69], v[78:79], v[68:69]
	s_nop 0
	v_pk_mul_f32 v[68:69], v[70:71], v[68:69]
	s_nop 0
	v_cvt_pk_bf16_f32 v65, v68, v69
	v_mul_f32_e32 v68, 0xbfb8aa3b, v72
	v_mul_f32_e32 v69, 0xbfb8aa3b, v73
	v_exp_f32_e32 v68, v68
	v_exp_f32_e32 v69, v69
	v_add_f32_e32 v68, 1.0, v68
	v_add_f32_e32 v69, 1.0, v69
	v_rcp_f32_e32 v68, v68
	v_rcp_f32_e32 v69, v69
	s_nop 0
	v_pk_mul_f32 v[68:69], v[72:73], v[68:69]
	s_nop 0
	v_pk_mul_f32 v[66:67], v[66:67], v[68:69]
	s_nop 0
	v_cvt_pk_bf16_f32 v66, v66, v67
	v_mul_f32_e32 v67, 0xbfb8aa3b, v74
	v_exp_f32_e32 v67, v67
	s_nop 0
	v_add_f32_e32 v67, 1.0, v67
	v_rcp_f32_e32 v68, v67
	v_mul_f32_e32 v67, 0xbfb8aa3b, v75
	v_exp_f32_e32 v67, v67
	s_nop 0
	v_add_f32_e32 v67, 1.0, v67
	v_rcp_f32_e32 v69, v67
	s_nop 0
	v_pk_mul_f32 v[68:69], v[74:75], v[68:69]
	s_nop 0
	v_pk_mul_f32 v[68:69], v[82:83], v[68:69]
	s_nop 0
	v_cvt_pk_bf16_f32 v67, v68, v69
	global_store_dwordx4 v[80:81], v[64:67], off
	s_nop 1
	v_pk_mul_f32 v[66:67], v[50:51], v[148:149] op_sel_hi:[1,0]
	v_pk_mul_f32 v[50:51], v[48:49], v[148:149] op_sel_hi:[1,0]
	v_mul_f32_e32 v48, 0xbfb8aa3b, v60
	v_mul_f32_e32 v49, 0xbfb8aa3b, v61
	v_exp_f32_e32 v48, v48
	v_exp_f32_e32 v49, v49
	v_add_u32_e32 v64, 0x80, v210
	v_mad_i64_i32 v[64:65], s[0:1], v64, s2, v[132:133]
	v_add_f32_e32 v48, 1.0, v48
	v_add_f32_e32 v49, 1.0, v49
	v_rcp_f32_e32 v48, v48
	v_rcp_f32_e32 v49, v49
	v_lshl_add_u64 v[64:65], v[64:65], 0, v[134:135]
	v_pk_mul_f32 v[48:49], v[60:61], v[48:49]
	s_nop 0
	v_pk_mul_f32 v[48:49], v[52:53], v[48:49]
	s_nop 0
	v_cvt_pk_bf16_f32 v48, v48, v49
	v_mul_f32_e32 v49, 0xbfb8aa3b, v62
	v_exp_f32_e32 v49, v49
	s_nop 0
	v_add_f32_e32 v49, 1.0, v49
	v_rcp_f32_e32 v52, v49
	v_mul_f32_e32 v49, 0xbfb8aa3b, v63
	v_exp_f32_e32 v49, v49
	s_nop 0
	v_add_f32_e32 v49, 1.0, v49
	v_rcp_f32_e32 v53, v49
	s_nop 0
	v_pk_mul_f32 v[52:53], v[62:63], v[52:53]
	s_nop 0
	v_pk_mul_f32 v[52:53], v[54:55], v[52:53]
	s_nop 0
	v_cvt_pk_bf16_f32 v49, v52, v53
	v_mul_f32_e32 v52, 0xbfb8aa3b, v56
	v_mul_f32_e32 v53, 0xbfb8aa3b, v57
	v_exp_f32_e32 v52, v52
	v_exp_f32_e32 v53, v53
	v_add_f32_e32 v52, 1.0, v52
	v_add_f32_e32 v53, 1.0, v53
	v_rcp_f32_e32 v52, v52
; __device__ __forceinline__ unsigned pk_bf16(float lo, float hi) { f32x2e v = {lo, hi}; bf16x2e b = __builtin_convertvector(v, bf16x2e); return __builtin_bit_cast(unsigned, b); }
; __device__ __forceinline__ float silu_mul(float g, float u) { return g * __builtin_amdgcn_rcpf(1.0f + __builtin_amdgcn_exp2f(-1.4426950408889634f * g)) * u; }
;     __device__ __forceinline__ void operator()(const f32x4 (&acc)[2][2][4][2], const Unit& u, int wr, int wc, int fr, int fq) const {
;     ...
;             for (int m = 0; m < 4; ++m) { bf16_t* rowp = O + (size_t)(row0 + ai * HALF + m * 16) * ldc + col0;
;                 const float rs = rsa[ai][m];
;                 const f32x4 g0 = acc[ai][0][m][0] * rs, g1 = acc[ai][0][m][1] * rs, u0 = acc[ai][1][m][0] * rs, u1 = acc[ai][1][m][1] * rs;
;                 u32x4 w; w.x = pk_bf16(silu_mul(g0[0], u0[0]), silu_mul(g0[1], u0[1])); w.y = pk_bf16(silu_mul(g0[2], u0[2]), silu_mul(g0[3], u0[3]));
;                 w.z = pk_bf16(silu_mul(g1[0], u1[0]), silu_mul(g1[1], u1[1])); w.w = pk_bf16(silu_mul(g1[2], u1[2]), silu_mul(g1[3], u1[3]));
;                 *(u32x4*)rowp = w; }
	v_rcp_f32_e32 v53, v53
	s_nop 0
	v_pk_mul_f32 v[52:53], v[56:57], v[52:53]
	s_nop 0
	v_pk_mul_f32 v[50:51], v[50:51], v[52:53]
	s_nop 0
	v_cvt_pk_bf16_f32 v50, v50, v51
	v_mul_f32_e32 v51, 0xbfb8aa3b, v58
	v_exp_f32_e32 v51, v51
	s_nop 0
	v_add_f32_e32 v51, 1.0, v51
	v_rcp_f32_e32 v52, v51
	v_mul_f32_e32 v51, 0xbfb8aa3b, v59
	v_exp_f32_e32 v51, v51
	s_nop 0
	v_add_f32_e32 v51, 1.0, v51
	v_rcp_f32_e32 v53, v51
	s_nop 0
	v_pk_mul_f32 v[52:53], v[58:59], v[52:53]
	s_nop 0
	v_pk_mul_f32 v[52:53], v[66:67], v[52:53]
	s_nop 0
	v_cvt_pk_bf16_f32 v51, v52, v53
	global_store_dwordx4 v[64:65], v[48:51], off
	s_nop 1
	v_pk_mul_f32 v[50:51], v[34:35], v[146:147] op_sel_hi:[1,0]
	v_pk_mul_f32 v[34:35], v[32:33], v[146:147] op_sel_hi:[1,0]
	v_mul_f32_e32 v32, 0xbfb8aa3b, v44
	v_mul_f32_e32 v33, 0xbfb8aa3b, v45
	v_exp_f32_e32 v32, v32
	v_exp_f32_e32 v33, v33
	v_add_u32_e32 v48, 0x90, v210
	v_mad_i64_i32 v[48:49], s[0:1], v48, s2, v[132:133]
	v_add_f32_e32 v32, 1.0, v32
	v_add_f32_e32 v33, 1.0, v33
	v_rcp_f32_e32 v32, v32
	v_rcp_f32_e32 v33, v33
	v_lshl_add_u64 v[48:49], v[48:49], 0, v[134:135]
	v_pk_mul_f32 v[32:33], v[44:45], v[32:33]
	s_nop 0
	v_pk_mul_f32 v[32:33], v[36:37], v[32:33]
	s_nop 0
	v_cvt_pk_bf16_f32 v32, v32, v33
	v_mul_f32_e32 v33, 0xbfb8aa3b, v46
	v_exp_f32_e32 v33, v33
	s_nop 0
	v_add_f32_e32 v33, 1.0, v33
	v_rcp_f32_e32 v36, v33
	v_mul_f32_e32 v33, 0xbfb8aa3b, v47
	v_exp_f32_e32 v33, v33
	s_nop 0
	v_add_f32_e32 v33, 1.0, v33
	v_rcp_f32_e32 v37, v33
	s_nop 0
	v_pk_mul_f32 v[36:37], v[46:47], v[36:37]
	s_nop 0
	v_pk_mul_f32 v[36:37], v[38:39], v[36:37]
	s_nop 0
	v_cvt_pk_bf16_f32 v33, v36, v37
	v_mul_f32_e32 v36, 0xbfb8aa3b, v40
	v_mul_f32_e32 v37, 0xbfb8aa3b, v41
	v_exp_f32_e32 v36, v36
	v_exp_f32_e32 v37, v37
	v_add_f32_e32 v36, 1.0, v36
	v_add_f32_e32 v37, 1.0, v37
	v_rcp_f32_e32 v36, v36
	v_rcp_f32_e32 v37, v37
	s_nop 0
	v_pk_mul_f32 v[36:37], v[40:41], v[36:37]
	s_nop 0
	v_pk_mul_f32 v[34:35], v[34:35], v[36:37]
	s_nop 0
	v_cvt_pk_bf16_f32 v34, v34, v35
	v_mul_f32_e32 v35, 0xbfb8aa3b, v42
	v_exp_f32_e32 v35, v35
	s_nop 0
	v_add_f32_e32 v35, 1.0, v35
	v_rcp_f32_e32 v36, v35
	v_mul_f32_e32 v35, 0xbfb8aa3b, v43
	v_exp_f32_e32 v35, v35
	s_nop 0
	v_add_f32_e32 v35, 1.0, v35
	v_rcp_f32_e32 v37, v35
	s_nop 0
	v_pk_mul_f32 v[36:37], v[42:43], v[36:37]
	s_nop 0
	v_pk_mul_f32 v[36:37], v[50:51], v[36:37]
	s_nop 0
	v_cvt_pk_bf16_f32 v35, v36, v37
	global_store_dwordx4 v[48:49], v[32:35], off
	s_nop 1
	v_pk_mul_f32 v[34:35], v[18:19], v[136:137] op_sel_hi:[1,0]
	v_pk_mul_f32 v[18:19], v[16:17], v[136:137] op_sel_hi:[1,0]
	v_mul_f32_e32 v16, 0xbfb8aa3b, v28
	v_mul_f32_e32 v17, 0xbfb8aa3b, v29
	v_exp_f32_e32 v16, v16
	v_exp_f32_e32 v17, v17
	v_add_u32_e32 v32, 0xa0, v210
	v_mad_i64_i32 v[32:33], s[0:1], v32, s2, v[132:133]
	v_add_f32_e32 v16, 1.0, v16
	v_add_f32_e32 v17, 1.0, v17
	v_rcp_f32_e32 v16, v16
	v_rcp_f32_e32 v17, v17
	v_lshl_add_u64 v[32:33], v[32:33], 0, v[134:135]
	v_pk_mul_f32 v[16:17], v[28:29], v[16:17]
	s_nop 0
	v_pk_mul_f32 v[16:17], v[20:21], v[16:17]
	s_nop 0
	v_cvt_pk_bf16_f32 v16, v16, v17
	v_mul_f32_e32 v17, 0xbfb8aa3b, v30
	v_exp_f32_e32 v17, v17
	s_nop 0
	v_add_f32_e32 v17, 1.0, v17
	v_rcp_f32_e32 v20, v17
	v_mul_f32_e32 v17, 0xbfb8aa3b, v31
	v_exp_f32_e32 v17, v17
	s_nop 0
	v_add_f32_e32 v17, 1.0, v17
	v_rcp_f32_e32 v21, v17
	s_nop 0
	v_pk_mul_f32 v[20:21], v[30:31], v[20:21]
	s_nop 0
	v_pk_mul_f32 v[20:21], v[22:23], v[20:21]
	s_nop 0
	v_cvt_pk_bf16_f32 v17, v20, v21
	v_mul_f32_e32 v20, 0xbfb8aa3b, v24
	v_mul_f32_e32 v21, 0xbfb8aa3b, v25
	v_exp_f32_e32 v20, v20
	v_exp_f32_e32 v21, v21
	v_add_f32_e32 v20, 1.0, v20
	v_add_f32_e32 v21, 1.0, v21
	v_rcp_f32_e32 v20, v20
	v_rcp_f32_e32 v21, v21
	s_nop 0
	v_pk_mul_f32 v[20:21], v[24:25], v[20:21]
	s_nop 0
	v_pk_mul_f32 v[18:19], v[18:19], v[20:21]
	s_nop 0
	v_cvt_pk_bf16_f32 v18, v18, v19
	v_mul_f32_e32 v19, 0xbfb8aa3b, v26
	v_exp_f32_e32 v19, v19
	s_nop 0
	v_add_f32_e32 v19, 1.0, v19
	v_rcp_f32_e32 v20, v19
	v_mul_f32_e32 v19, 0xbfb8aa3b, v27
	v_exp_f32_e32 v19, v19
	s_nop 0
	v_add_f32_e32 v19, 1.0, v19
	v_rcp_f32_e32 v21, v19
	s_nop 0
	v_pk_mul_f32 v[20:21], v[26:27], v[20:21]
	s_nop 0
	v_pk_mul_f32 v[20:21], v[34:35], v[20:21]
	s_nop 0
	v_cvt_pk_bf16_f32 v19, v20, v21
	global_store_dwordx4 v[32:33], v[16:19], off
	s_nop 1
	v_pk_mul_f32 v[18:19], v[2:3], v[130:131] op_sel_hi:[1,0]
	v_pk_mul_f32 v[2:3], v[0:1], v[130:131] op_sel_hi:[1,0]
	v_mul_f32_e32 v0, 0xbfb8aa3b, v12
	v_mul_f32_e32 v1, 0xbfb8aa3b, v13
	v_exp_f32_e32 v0, v0
	v_exp_f32_e32 v1, v1
	v_add_u32_e32 v16, 0xb0, v210
	v_mad_i64_i32 v[16:17], s[0:1], v16, s2, v[132:133]
	v_add_f32_e32 v0, 1.0, v0
	v_add_f32_e32 v1, 1.0, v1
	v_rcp_f32_e32 v0, v0
	v_rcp_f32_e32 v1, v1
	v_lshl_add_u64 v[16:17], v[16:17], 0, v[134:135]
	s_mov_b64 s[0:1], -1
	v_pk_mul_f32 v[0:1], v[12:13], v[0:1]
	s_nop 0
	v_pk_mul_f32 v[0:1], v[4:5], v[0:1]
	s_nop 0
	v_cvt_pk_bf16_f32 v0, v0, v1
	v_mul_f32_e32 v1, 0xbfb8aa3b, v14
	v_exp_f32_e32 v1, v1
	s_nop 0
	v_add_f32_e32 v1, 1.0, v1
	v_rcp_f32_e32 v4, v1
	v_mul_f32_e32 v1, 0xbfb8aa3b, v15
	v_exp_f32_e32 v1, v1
	s_nop 0
	v_add_f32_e32 v1, 1.0, v1
	v_rcp_f32_e32 v5, v1
	s_nop 0
	v_pk_mul_f32 v[4:5], v[14:15], v[4:5]
	s_nop 0
	v_pk_mul_f32 v[4:5], v[6:7], v[4:5]
	s_nop 0
	v_cvt_pk_bf16_f32 v1, v4, v5
	v_mul_f32_e32 v4, 0xbfb8aa3b, v8
	v_mul_f32_e32 v5, 0xbfb8aa3b, v9
	v_exp_f32_e32 v4, v4
	v_exp_f32_e32 v5, v5
	v_add_f32_e32 v4, 1.0, v4
	v_add_f32_e32 v5, 1.0, v5
	v_rcp_f32_e32 v4, v4
	v_rcp_f32_e32 v5, v5
	s_nop 0
	v_pk_mul_f32 v[4:5], v[8:9], v[4:5]
	s_nop 0
	v_pk_mul_f32 v[2:3], v[2:3], v[4:5]
	s_nop 0
	v_cvt_pk_bf16_f32 v2, v2, v3
	v_mul_f32_e32 v3, 0xbfb8aa3b, v10
	v_exp_f32_e32 v3, v3
	s_nop 0
	v_add_f32_e32 v3, 1.0, v3
	v_rcp_f32_e32 v4, v3
	v_mul_f32_e32 v3, 0xbfb8aa3b, v11
	v_exp_f32_e32 v3, v3
	s_nop 0
	v_add_f32_e32 v3, 1.0, v3
	v_rcp_f32_e32 v5, v3
	s_nop 0
	v_pk_mul_f32 v[4:5], v[10:11], v[4:5]
	s_nop 0
	v_pk_mul_f32 v[4:5], v[18:19], v[4:5]
	s_nop 0
	v_cvt_pk_bf16_f32 v3, v4, v5
	global_store_dwordx4 v[16:17], v[0:3], off
	s_cbranch_vccnz .LBB0_413
	s_andn2_b64 vcc, exec, s[10:11]
	s_cbranch_vccnz .LBB0_412
	s_barrier
	s_branch .LBB0_412

; __device__ __forceinline__ unsigned pk_bf16(float lo, float hi) { f32x2e v = {lo, hi}; bf16x2e b = __builtin_convertvector(v, bf16x2e); return __builtin_bit_cast(unsigned, b); }
;     __device__ __forceinline__ void operator()(const f32x4 (&acc)[2][2][4][2], const Unit& u, int wr, int wc, int fr, int fq) const {
;         const int col0 = u.pn * BM + wc * 32 + 8 * fq;
;         bf16_t* base = H + (size_t)(u.pm * BM + wr * 64 + fr) * ldc + col0;
;         u32x4 r[2][4][2];
; #pragma unroll
;         for (int ai = 0; ai < 2; ++ai)
; #pragma unroll
;             for (int m = 0; m < 4; ++m)
; #pragma unroll
;                 for (int bj = 0; bj < 2; ++bj) r[ai][m][bj] = *(const u32x4*)(base + (size_t)(ai * HALF + m * 16) * ldc + bj * HALF);
; #pragma unroll
;         for (int ai = 0; ai < 2; ++ai)
; #pragma unroll
;             for (int m = 0; m < 4; ++m) { const int row = u.pm * BM + ai * HALF + wr * 64 + m * 16 + fr; bf16_t* rowp = base + (size_t)(ai * HALF + m * 16) * ldc;
;                 float qs = 0.f;
; #pragma unroll
;                 for (int bj = 0; bj < 2; ++bj) { const f32x4 a0 = acc[ai][bj][m][0], a1 = acc[ai][bj][m][1]; const u32x4 q = r[ai][m][bj]; u32x4 w;
;                     w.x = pk_bf16(__uint_as_float(q.x << 16) + a0.x, __uint_as_float(q.x & 0xffff0000u) + a0.y);
;                     w.y = pk_bf16(__uint_as_float(q.y << 16) + a0.z, __uint_as_float(q.y & 0xffff0000u) + a0.w);
;                     w.z = pk_bf16(__uint_as_float(q.z << 16) + a1.x, __uint_as_float(q.z & 0xffff0000u) + a1.y);
;                     w.w = pk_bf16(__uint_as_float(q.w << 16) + a1.z, __uint_as_float(q.w & 0xffff0000u) + a1.w);
;                     *(u32x4*)(rowp + bj * HALF) = w;
; #pragma unroll
;                     for (int e = 0; e < 4; ++e) { const float h0 = __uint_as_float(w[e] << 16), h1 = __uint_as_float(w[e] & 0xffff0000u); qs += h0 * h0 + h1 * h1; } }
;                 qs += __shfl_xor(qs, 16); qs += __shfl_xor(qs, 32);
;                 if (fq == 0) ss[(size_t)row * 32 + u.pn * 4 + wc] = qs; }
.LBB0_450:
	v_lshl_add_u32 v212, s7, 8, v231
	v_ashrrev_i32_e32 v213, 31, v212
	v_readlane_b32 s0, v254, 59
	v_lshl_or_b32 v98, s6, 8, v233
	v_lshlrev_b64 v[100:101], 12, v[212:213]
	v_readlane_b32 s1, v254, 60
	v_ashrrev_i32_e32 v99, 31, v98
	v_and_b32_e32 v229, 64, v220
	v_lshl_add_u64 v[100:101], s[0:1], 0, v[100:101]
	v_lshl_add_u64 v[214:215], v[98:99], 1, v[100:101]
	global_load_dwordx4 v[190:193], v[214:215], off
	global_load_dwordx4 v[186:189], v[214:215], off offset:256
	s_mov_b32 s0, 0x10000
	v_add_co_u32_e32 v98, vcc, s0, v214
	s_mov_b32 s0, 0x20000
	s_nop 0
	v_addc_co_u32_e32 v99, vcc, 0, v215, vcc
	global_load_dwordx4 v[182:185], v[98:99], off
	global_load_dwordx4 v[178:181], v[98:99], off offset:256
	v_add_co_u32_e32 v98, vcc, s0, v214
	s_mov_b32 s0, 0x30000
	s_nop 0
	v_addc_co_u32_e32 v99, vcc, 0, v215, vcc
	global_load_dwordx4 v[174:177], v[98:99], off
	global_load_dwordx4 v[170:173], v[98:99], off offset:256
	v_add_co_u32_e32 v98, vcc, s0, v214
	s_mov_b32 s0, 0x80000
	s_nop 0
	v_addc_co_u32_e32 v99, vcc, 0, v215, vcc
	global_load_dwordx4 v[166:169], v[98:99], off
	global_load_dwordx4 v[162:165], v[98:99], off offset:256
	v_add_co_u32_e32 v98, vcc, s0, v214
	s_mov_b32 s0, 0x90000
	s_nop 0
	v_addc_co_u32_e32 v99, vcc, 0, v215, vcc
	global_load_dwordx4 v[158:161], v[98:99], off
	global_load_dwordx4 v[150:153], v[98:99], off offset:256
	v_add_co_u32_e32 v98, vcc, s0, v214
	s_mov_b32 s0, 0xa0000
	s_nop 0
	v_addc_co_u32_e32 v99, vcc, 0, v215, vcc
	global_load_dwordx4 v[142:145], v[98:99], off
	global_load_dwordx4 v[138:141], v[98:99], off offset:256
	v_add_co_u32_e32 v98, vcc, s0, v214
	s_mov_b32 s0, 0xb0000
	s_nop 0
	v_addc_co_u32_e32 v99, vcc, 0, v215, vcc
	global_load_dwordx4 v[126:129], v[98:99], off
	global_load_dwordx4 v[118:121], v[98:99], off offset:256
	v_add_co_u32_e32 v98, vcc, s0, v214
	v_xor_b32_e32 v228, 16, v220
	s_nop 0
	v_addc_co_u32_e32 v99, vcc, 0, v215, vcc
	global_load_dwordx4 v[106:109], v[98:99], off
	s_nop 0
	global_load_dwordx4 v[98:101], v[98:99], off offset:256
	v_add_u32_e32 v229, 64, v229
	v_cmp_lt_i32_e32 vcc, v228, v229
	s_lshl_b32 s66, s6, 2
	s_ashr_i32 s67, s66, 31
	v_cndmask_b32_e32 v228, v220, v228, vcc
	v_lshlrev_b32_e32 v235, 2, v228
	v_xor_b32_e32 v228, 32, v220
	v_cmp_lt_i32_e32 vcc, v228, v229
	s_waitcnt vmcnt(0) lgkmcnt(0)
	v_and_b32_e32 v229, 0xffff0000, v190
	v_cndmask_b32_e32 v228, v220, v228, vcc
	v_lshlrev_b32_e32 v236, 2, v228
	v_lshlrev_b32_e32 v228, 16, v190
	v_lshlrev_b32_e32 v190, 16, v191
	v_and_b32_e32 v191, 0xffff0000, v191
	v_pk_add_f32 v[154:155], v[154:155], v[228:229]
	v_pk_add_f32 v[156:157], v[156:157], v[190:191]
	v_cvt_pk_bf16_f32 v154, v154, v155
	v_cvt_pk_bf16_f32 v155, v156, v157
	v_lshlrev_b32_e32 v156, 16, v192
	v_and_b32_e32 v157, 0xffff0000, v192
	v_pk_add_f32 v[146:147], v[146:147], v[156:157]
	s_nop 0
	v_cvt_pk_bf16_f32 v156, v146, v147
	v_lshlrev_b32_e32 v146, 16, v193
	v_and_b32_e32 v147, 0xffff0000, v193
	v_pk_add_f32 v[146:147], v[148:149], v[146:147]
	v_and_b32_e32 v148, 0xffff0000, v155
	v_cvt_pk_bf16_f32 v157, v146, v147
	v_and_b32_e32 v147, 0xffff0000, v154
	v_lshlrev_b32_e32 v146, 16, v154
	v_mul_f32_e32 v147, v147, v147
	v_fmac_f32_e32 v147, v146, v146
	v_lshlrev_b32_e32 v146, 16, v155
	v_mul_f32_e32 v148, v148, v148
	v_fmac_f32_e32 v148, v146, v146
	v_add_f32_e32 v146, v147, v148
	v_and_b32_e32 v148, 0xffff0000, v156
	v_lshlrev_b32_e32 v147, 16, v156
	v_mul_f32_e32 v148, v148, v148
	v_fmac_f32_e32 v148, v147, v147
	v_add_f32_e32 v146, v148, v146
	v_and_b32_e32 v148, 0xffff0000, v157
	v_lshlrev_b32_e32 v147, 16, v157
	v_mul_f32_e32 v148, v148, v148
	v_fmac_f32_e32 v148, v147, v147
	v_add_f32_e32 v148, v148, v146
	v_lshlrev_b32_e32 v146, 16, v186
	v_and_b32_e32 v147, 0xffff0000, v186
	v_pk_add_f32 v[134:135], v[134:135], v[146:147]
	v_lshlrev_b32_e32 v146, 16, v187
	v_and_b32_e32 v147, 0xffff0000, v187
	v_pk_add_f32 v[136:137], v[136:137], v[146:147]
	v_cvt_pk_bf16_f32 v134, v134, v135
	v_cvt_pk_bf16_f32 v135, v136, v137
	v_lshlrev_b32_e32 v136, 16, v188
	v_and_b32_e32 v137, 0xffff0000, v188
	v_pk_add_f32 v[130:131], v[130:131], v[136:137]
	global_store_dwordx4 v[214:215], v[154:157], off
	v_cvt_pk_bf16_f32 v136, v130, v131
	v_lshlrev_b32_e32 v130, 16, v189
	v_and_b32_e32 v131, 0xffff0000, v189
	v_pk_add_f32 v[130:131], v[132:133], v[130:131]
	v_and_b32_e32 v132, 0xffff0000, v135
	v_cvt_pk_bf16_f32 v137, v130, v131
	v_and_b32_e32 v131, 0xffff0000, v134
	v_lshlrev_b32_e32 v130, 16, v134
	v_mul_f32_e32 v131, v131, v131
	v_fmac_f32_e32 v131, v130, v130
	v_add_f32_e32 v130, v131, v148
	v_lshlrev_b32_e32 v131, 16, v135
	v_mul_f32_e32 v132, v132, v132
	v_fmac_f32_e32 v132, v131, v131
	v_add_f32_e32 v130, v132, v130
	v_and_b32_e32 v132, 0xffff0000, v136
	v_lshlrev_b32_e32 v131, 16, v136
	v_mul_f32_e32 v132, v132, v132
	v_fmac_f32_e32 v132, v131, v131
	v_add_f32_e32 v130, v132, v130
	v_and_b32_e32 v132, 0xffff0000, v137
	v_lshlrev_b32_e32 v131, 16, v137
	v_mul_f32_e32 v132, v132, v132
	v_fmac_f32_e32 v132, v131, v131
	v_add_f32_e32 v130, v132, v130
	ds_bpermute_b32 v131, v235, v130
	global_store_dwordx4 v[214:215], v[134:137], off offset:256
	s_waitcnt lgkmcnt(0)
	v_add_f32_e32 v130, v130, v131
	ds_bpermute_b32 v131, v236, v130
	s_and_saveexec_b64 s[0:1], s[38:39]
	s_cbranch_execz .LBB0_452
	v_lshlrev_b64 v[132:133], 7, v[212:213]
	v_lshl_add_u64 v[132:133], s[44:45], 0, v[132:133]
	v_lshl_add_u64 v[132:133], s[66:67], 2, v[132:133]
	s_lshl_b32 s28, s47, 2
	v_lshl_add_u64 v[132:133], v[132:133], 0, s[28:29]
	s_waitcnt lgkmcnt(0)
	v_add_f32_e32 v130, v130, v131
	global_store_dword v[132:133], v130, off
; __device__ __forceinline__ unsigned pk_bf16(float lo, float hi) { f32x2e v = {lo, hi}; bf16x2e b = __builtin_convertvector(v, bf16x2e); return __builtin_bit_cast(unsigned, b); }
;     __device__ __forceinline__ void operator()(const f32x4 (&acc)[2][2][4][2], const Unit& u, int wr, int wc, int fr, int fq) const {
;     ...
;             for (int m = 0; m < 4; ++m) { const int row = u.pm * BM + ai * HALF + wr * 64 + m * 16 + fr; bf16_t* rowp = base + (size_t)(ai * HALF + m * 16) * ldc;
;                 float qs = 0.f;
; #pragma unroll
;                 for (int bj = 0; bj < 2; ++bj) { const f32x4 a0 = acc[ai][bj][m][0], a1 = acc[ai][bj][m][1]; const u32x4 q = r[ai][m][bj]; u32x4 w;
;                     w.x = pk_bf16(__uint_as_float(q.x << 16) + a0.x, __uint_as_float(q.x & 0xffff0000u) + a0.y);
;                     w.y = pk_bf16(__uint_as_float(q.y << 16) + a0.z, __uint_as_float(q.y & 0xffff0000u) + a0.w);
;                     w.z = pk_bf16(__uint_as_float(q.z << 16) + a1.x, __uint_as_float(q.z & 0xffff0000u) + a1.y);
;                     w.w = pk_bf16(__uint_as_float(q.w << 16) + a1.z, __uint_as_float(q.w & 0xffff0000u) + a1.w);
;                     *(u32x4*)(rowp + bj * HALF) = w;
; #pragma unroll
;                     for (int e = 0; e < 4; ++e) { const float h0 = __uint_as_float(w[e] << 16), h1 = __uint_as_float(w[e] & 0xffff0000u); qs += h0 * h0 + h1 * h1; } }
;                 qs += __shfl_xor(qs, 16); qs += __shfl_xor(qs, 32);
;                 if (fq == 0) ss[(size_t)row * 32 + u.pn * 4 + wc] = qs; }
.LBB0_452:
	s_or_b64 exec, exec, s[0:1]
	v_lshlrev_b32_e32 v130, 16, v182
	s_waitcnt lgkmcnt(0)
	v_and_b32_e32 v131, 0xffff0000, v182
	v_pk_add_f32 v[122:123], v[122:123], v[130:131]
	v_lshlrev_b32_e32 v130, 16, v183
	v_and_b32_e32 v131, 0xffff0000, v183
	v_pk_add_f32 v[124:125], v[124:125], v[130:131]
	v_cvt_pk_bf16_f32 v122, v122, v123
	v_cvt_pk_bf16_f32 v123, v124, v125
	v_lshlrev_b32_e32 v124, 16, v184
	v_and_b32_e32 v125, 0xffff0000, v184
	v_pk_add_f32 v[114:115], v[114:115], v[124:125]
	s_mov_b64 s[0:1], 0x10000
	v_cvt_pk_bf16_f32 v124, v114, v115
	v_lshlrev_b32_e32 v114, 16, v185
	v_and_b32_e32 v115, 0xffff0000, v185
	v_pk_add_f32 v[114:115], v[116:117], v[114:115]
	v_and_b32_e32 v116, 0xffff0000, v123
	v_cvt_pk_bf16_f32 v125, v114, v115
	v_and_b32_e32 v115, 0xffff0000, v122
	v_lshlrev_b32_e32 v114, 16, v122
	v_mul_f32_e32 v115, v115, v115
	v_fmac_f32_e32 v115, v114, v114
	v_lshlrev_b32_e32 v114, 16, v123
	v_mul_f32_e32 v116, v116, v116
	v_fmac_f32_e32 v116, v114, v114
	v_add_f32_e32 v114, v115, v116
	v_and_b32_e32 v116, 0xffff0000, v124
	v_lshlrev_b32_e32 v115, 16, v124
	v_mul_f32_e32 v116, v116, v116
	v_fmac_f32_e32 v116, v115, v115
	v_add_f32_e32 v114, v116, v114
	v_and_b32_e32 v116, 0xffff0000, v125
	v_lshlrev_b32_e32 v115, 16, v125
	v_mul_f32_e32 v116, v116, v116
	v_fmac_f32_e32 v116, v115, v115
	v_add_f32_e32 v116, v116, v114
	v_lshlrev_b32_e32 v114, 16, v178
	v_and_b32_e32 v115, 0xffff0000, v178
	v_pk_add_f32 v[110:111], v[110:111], v[114:115]
	v_lshlrev_b32_e32 v114, 16, v179
	v_and_b32_e32 v115, 0xffff0000, v179
	v_pk_add_f32 v[112:113], v[112:113], v[114:115]
	v_cvt_pk_bf16_f32 v110, v110, v111
	v_cvt_pk_bf16_f32 v111, v112, v113
	v_lshlrev_b32_e32 v112, 16, v180
	v_and_b32_e32 v113, 0xffff0000, v180
	v_pk_add_f32 v[102:103], v[102:103], v[112:113]
	s_nop 0
	v_cvt_pk_bf16_f32 v112, v102, v103
	v_lshlrev_b32_e32 v102, 16, v181
	v_and_b32_e32 v103, 0xffff0000, v181
	v_pk_add_f32 v[102:103], v[104:105], v[102:103]
	v_and_b32_e32 v104, 0xffff0000, v111
	v_cvt_pk_bf16_f32 v113, v102, v103
	v_and_b32_e32 v103, 0xffff0000, v110
	v_lshlrev_b32_e32 v102, 16, v110
	v_mul_f32_e32 v103, v103, v103
	v_fmac_f32_e32 v103, v102, v102
	v_add_f32_e32 v102, v103, v116
	v_lshlrev_b32_e32 v103, 16, v111
	v_mul_f32_e32 v104, v104, v104
	v_fmac_f32_e32 v104, v103, v103
	v_add_f32_e32 v102, v104, v102
	v_and_b32_e32 v104, 0xffff0000, v112
	v_lshlrev_b32_e32 v103, 16, v112
	v_mul_f32_e32 v104, v104, v104
	v_fmac_f32_e32 v104, v103, v103
	v_add_f32_e32 v102, v104, v102
	v_and_b32_e32 v104, 0xffff0000, v113
	v_lshlrev_b32_e32 v103, 16, v113
	v_mul_f32_e32 v104, v104, v104
	v_fmac_f32_e32 v104, v103, v103
	v_add_f32_e32 v102, v104, v102
	ds_bpermute_b32 v103, v235, v102
	v_lshl_add_u64 v[104:105], v[214:215], 0, s[0:1]
	s_mov_b64 s[0:1], 0x10100
	v_lshl_add_u64 v[114:115], v[214:215], 0, s[0:1]
	global_store_dwordx4 v[104:105], v[122:125], off
	global_store_dwordx4 v[114:115], v[110:113], off
	s_waitcnt lgkmcnt(0)
	v_add_f32_e32 v102, v102, v103
	ds_bpermute_b32 v103, v236, v102
	s_and_saveexec_b64 s[0:1], s[38:39]
	s_cbranch_execz .LBB0_454
	v_or_b32_e32 v104, 16, v212
	v_ashrrev_i32_e32 v105, 31, v104
	s_waitcnt lgkmcnt(0)
	v_add_f32_e32 v110, v102, v103
	v_lshlrev_b64 v[102:103], 7, v[104:105]
	v_lshl_add_u64 v[102:103], s[44:45], 0, v[102:103]
	v_lshl_add_u64 v[102:103], s[66:67], 2, v[102:103]
	s_lshl_b32 s28, s47, 2
	v_lshl_add_u64 v[102:103], v[102:103], 0, s[28:29]
	global_store_dword v[102:103], v110, off
.LBB0_454:
	s_or_b64 exec, exec, s[0:1]
	v_lshlrev_b32_e32 v102, 16, v174
	s_waitcnt lgkmcnt(0)
	v_and_b32_e32 v103, 0xffff0000, v174
	v_pk_add_f32 v[92:93], v[92:93], v[102:103]
	v_lshlrev_b32_e32 v102, 16, v175
	v_and_b32_e32 v103, 0xffff0000, v175
	v_pk_add_f32 v[94:95], v[94:95], v[102:103]
	v_cvt_pk_bf16_f32 v92, v92, v93
	v_cvt_pk_bf16_f32 v93, v94, v95
	v_lshlrev_b32_e32 v94, 16, v176
	v_and_b32_e32 v95, 0xffff0000, v176
	v_pk_add_f32 v[88:89], v[88:89], v[94:95]
	s_mov_b64 s[0:1], 0x20000
	v_cvt_pk_bf16_f32 v94, v88, v89
	v_lshlrev_b32_e32 v88, 16, v177
	v_and_b32_e32 v89, 0xffff0000, v177
	v_pk_add_f32 v[88:89], v[90:91], v[88:89]
	v_and_b32_e32 v90, 0xffff0000, v93
	v_cvt_pk_bf16_f32 v95, v88, v89
	v_and_b32_e32 v89, 0xffff0000, v92
	v_lshlrev_b32_e32 v88, 16, v92
	v_mul_f32_e32 v89, v89, v89
	v_fmac_f32_e32 v89, v88, v88
	v_lshlrev_b32_e32 v88, 16, v93
	v_mul_f32_e32 v90, v90, v90
	v_fmac_f32_e32 v90, v88, v88
	v_add_f32_e32 v88, v89, v90
	v_and_b32_e32 v90, 0xffff0000, v94
	v_lshlrev_b32_e32 v89, 16, v94
	v_mul_f32_e32 v90, v90, v90
	v_fmac_f32_e32 v90, v89, v89
	v_add_f32_e32 v88, v90, v88
	v_and_b32_e32 v90, 0xffff0000, v95
	v_lshlrev_b32_e32 v89, 16, v95
	v_mul_f32_e32 v90, v90, v90
	v_fmac_f32_e32 v90, v89, v89
	v_add_f32_e32 v90, v90, v88
	v_lshlrev_b32_e32 v88, 16, v170
	v_and_b32_e32 v89, 0xffff0000, v170
	v_pk_add_f32 v[84:85], v[84:85], v[88:89]
	v_lshlrev_b32_e32 v88, 16, v171
	v_and_b32_e32 v89, 0xffff0000, v171
	v_pk_add_f32 v[86:87], v[86:87], v[88:89]
	v_cvt_pk_bf16_f32 v84, v84, v85
	v_cvt_pk_bf16_f32 v85, v86, v87
	v_lshlrev_b32_e32 v86, 16, v172
	v_and_b32_e32 v87, 0xffff0000, v172
	v_pk_add_f32 v[80:81], v[80:81], v[86:87]
	s_nop 0
	v_cvt_pk_bf16_f32 v86, v80, v81
	v_lshlrev_b32_e32 v80, 16, v173
	v_and_b32_e32 v81, 0xffff0000, v173
	v_pk_add_f32 v[80:81], v[82:83], v[80:81]
	v_and_b32_e32 v82, 0xffff0000, v85
	v_cvt_pk_bf16_f32 v87, v80, v81
	v_and_b32_e32 v81, 0xffff0000, v84
	v_lshlrev_b32_e32 v80, 16, v84
	v_mul_f32_e32 v81, v81, v81
	v_fmac_f32_e32 v81, v80, v80
	v_add_f32_e32 v80, v81, v90
	v_lshlrev_b32_e32 v81, 16, v85
	v_mul_f32_e32 v82, v82, v82
	v_fmac_f32_e32 v82, v81, v81
	v_add_f32_e32 v80, v82, v80
	v_and_b32_e32 v82, 0xffff0000, v86
	v_lshlrev_b32_e32 v81, 16, v86
	v_mul_f32_e32 v82, v82, v82
	v_fmac_f32_e32 v82, v81, v81
	v_add_f32_e32 v80, v82, v80
	v_and_b32_e32 v82, 0xffff0000, v87
	v_lshlrev_b32_e32 v81, 16, v87
	v_mul_f32_e32 v82, v82, v82
	v_fmac_f32_e32 v82, v81, v81
	v_add_f32_e32 v80, v82, v80
	ds_bpermute_b32 v81, v235, v80
	v_lshl_add_u64 v[82:83], v[214:215], 0, s[0:1]
	s_mov_b64 s[0:1], 0x20100
	v_lshl_add_u64 v[88:89], v[214:215], 0, s[0:1]
	global_store_dwordx4 v[82:83], v[92:95], off
	global_store_dwordx4 v[88:89], v[84:87], off
	s_waitcnt lgkmcnt(0)
	v_add_f32_e32 v80, v80, v81
	ds_bpermute_b32 v81, v236, v80
	s_and_saveexec_b64 s[0:1], s[38:39]
	s_cbranch_execz .LBB0_456
	v_or_b32_e32 v82, 32, v212
	v_ashrrev_i32_e32 v83, 31, v82
	s_waitcnt lgkmcnt(0)
	v_add_f32_e32 v84, v80, v81
	v_lshlrev_b64 v[80:81], 7, v[82:83]
	v_lshl_add_u64 v[80:81], s[44:45], 0, v[80:81]
	v_lshl_add_u64 v[80:81], s[66:67], 2, v[80:81]
	s_lshl_b32 s28, s47, 2
	v_lshl_add_u64 v[80:81], v[80:81], 0, s[28:29]
	global_store_dword v[80:81], v84, off
; __device__ __forceinline__ unsigned pk_bf16(float lo, float hi) { f32x2e v = {lo, hi}; bf16x2e b = __builtin_convertvector(v, bf16x2e); return __builtin_bit_cast(unsigned, b); }
;     __device__ __forceinline__ void operator()(const f32x4 (&acc)[2][2][4][2], const Unit& u, int wr, int wc, int fr, int fq) const {
;     ...
;             for (int m = 0; m < 4; ++m) { const int row = u.pm * BM + ai * HALF + wr * 64 + m * 16 + fr; bf16_t* rowp = base + (size_t)(ai * HALF + m * 16) * ldc;
;                 float qs = 0.f;
; #pragma unroll
;                 for (int bj = 0; bj < 2; ++bj) { const f32x4 a0 = acc[ai][bj][m][0], a1 = acc[ai][bj][m][1]; const u32x4 q = r[ai][m][bj]; u32x4 w;
;                     w.x = pk_bf16(__uint_as_float(q.x << 16) + a0.x, __uint_as_float(q.x & 0xffff0000u) + a0.y);
;                     w.y = pk_bf16(__uint_as_float(q.y << 16) + a0.z, __uint_as_float(q.y & 0xffff0000u) + a0.w);
;                     w.z = pk_bf16(__uint_as_float(q.z << 16) + a1.x, __uint_as_float(q.z & 0xffff0000u) + a1.y);
;                     w.w = pk_bf16(__uint_as_float(q.w << 16) + a1.z, __uint_as_float(q.w & 0xffff0000u) + a1.w);
;                     *(u32x4*)(rowp + bj * HALF) = w;
; #pragma unroll
;                     for (int e = 0; e < 4; ++e) { const float h0 = __uint_as_float(w[e] << 16), h1 = __uint_as_float(w[e] & 0xffff0000u); qs += h0 * h0 + h1 * h1; } }
;                 qs += __shfl_xor(qs, 16); qs += __shfl_xor(qs, 32);
;                 if (fq == 0) ss[(size_t)row * 32 + u.pn * 4 + wc] = qs; }
.LBB0_456:
	s_or_b64 exec, exec, s[0:1]
	v_lshlrev_b32_e32 v80, 16, v166
	s_waitcnt lgkmcnt(0)
	v_and_b32_e32 v81, 0xffff0000, v166
	v_pk_add_f32 v[76:77], v[76:77], v[80:81]
	v_lshlrev_b32_e32 v80, 16, v167
	v_and_b32_e32 v81, 0xffff0000, v167
	v_pk_add_f32 v[78:79], v[78:79], v[80:81]
	v_cvt_pk_bf16_f32 v76, v76, v77
	v_cvt_pk_bf16_f32 v77, v78, v79
	v_lshlrev_b32_e32 v78, 16, v168
	v_and_b32_e32 v79, 0xffff0000, v168
	v_pk_add_f32 v[72:73], v[72:73], v[78:79]
	s_mov_b64 s[0:1], 0x30000
	v_cvt_pk_bf16_f32 v78, v72, v73
	v_lshlrev_b32_e32 v72, 16, v169
	v_and_b32_e32 v73, 0xffff0000, v169
	v_pk_add_f32 v[72:73], v[74:75], v[72:73]
	v_and_b32_e32 v74, 0xffff0000, v77
	v_cvt_pk_bf16_f32 v79, v72, v73
	v_and_b32_e32 v73, 0xffff0000, v76
	v_lshlrev_b32_e32 v72, 16, v76
	v_mul_f32_e32 v73, v73, v73
	v_fmac_f32_e32 v73, v72, v72
	v_lshlrev_b32_e32 v72, 16, v77
	v_mul_f32_e32 v74, v74, v74
	v_fmac_f32_e32 v74, v72, v72
	v_add_f32_e32 v72, v73, v74
	v_and_b32_e32 v74, 0xffff0000, v78
	v_lshlrev_b32_e32 v73, 16, v78
	v_mul_f32_e32 v74, v74, v74
	v_fmac_f32_e32 v74, v73, v73
	v_add_f32_e32 v72, v74, v72
	v_and_b32_e32 v74, 0xffff0000, v79
	v_lshlrev_b32_e32 v73, 16, v79
	v_mul_f32_e32 v74, v74, v74
	v_fmac_f32_e32 v74, v73, v73
	v_add_f32_e32 v74, v74, v72
	v_lshlrev_b32_e32 v72, 16, v162
	v_and_b32_e32 v73, 0xffff0000, v162
	v_pk_add_f32 v[68:69], v[68:69], v[72:73]
	v_lshlrev_b32_e32 v72, 16, v163
	v_and_b32_e32 v73, 0xffff0000, v163
	v_pk_add_f32 v[70:71], v[70:71], v[72:73]
	v_cvt_pk_bf16_f32 v68, v68, v69
	v_cvt_pk_bf16_f32 v69, v70, v71
	v_lshlrev_b32_e32 v70, 16, v164
	v_and_b32_e32 v71, 0xffff0000, v164
	v_pk_add_f32 v[64:65], v[64:65], v[70:71]
	s_nop 0
	v_cvt_pk_bf16_f32 v70, v64, v65
	v_lshlrev_b32_e32 v64, 16, v165
	v_and_b32_e32 v65, 0xffff0000, v165
	v_pk_add_f32 v[64:65], v[66:67], v[64:65]
	v_and_b32_e32 v66, 0xffff0000, v69
	v_cvt_pk_bf16_f32 v71, v64, v65
	v_and_b32_e32 v65, 0xffff0000, v68
	v_lshlrev_b32_e32 v64, 16, v68
	v_mul_f32_e32 v65, v65, v65
	v_fmac_f32_e32 v65, v64, v64
	v_add_f32_e32 v64, v65, v74
	v_lshlrev_b32_e32 v65, 16, v69
	v_mul_f32_e32 v66, v66, v66
	v_fmac_f32_e32 v66, v65, v65
	v_add_f32_e32 v64, v66, v64
	v_and_b32_e32 v66, 0xffff0000, v70
	v_lshlrev_b32_e32 v65, 16, v70
	v_mul_f32_e32 v66, v66, v66
	v_fmac_f32_e32 v66, v65, v65
	v_add_f32_e32 v64, v66, v64
	v_and_b32_e32 v66, 0xffff0000, v71
	v_lshlrev_b32_e32 v65, 16, v71
	v_mul_f32_e32 v66, v66, v66
	v_fmac_f32_e32 v66, v65, v65
	v_add_f32_e32 v64, v66, v64
	ds_bpermute_b32 v65, v235, v64
	v_lshl_add_u64 v[66:67], v[214:215], 0, s[0:1]
	s_mov_b64 s[0:1], 0x30100
	v_lshl_add_u64 v[72:73], v[214:215], 0, s[0:1]
	global_store_dwordx4 v[66:67], v[76:79], off
	global_store_dwordx4 v[72:73], v[68:71], off
	s_waitcnt lgkmcnt(0)
	v_add_f32_e32 v64, v64, v65
	ds_bpermute_b32 v65, v236, v64
	s_and_saveexec_b64 s[0:1], s[38:39]
	s_cbranch_execz .LBB0_458
	v_or_b32_e32 v66, 48, v212
	v_ashrrev_i32_e32 v67, 31, v66
	s_waitcnt lgkmcnt(0)
	v_add_f32_e32 v68, v64, v65
	v_lshlrev_b64 v[64:65], 7, v[66:67]
	v_lshl_add_u64 v[64:65], s[44:45], 0, v[64:65]
	v_lshl_add_u64 v[64:65], s[66:67], 2, v[64:65]
	s_lshl_b32 s28, s47, 2
	v_lshl_add_u64 v[64:65], v[64:65], 0, s[28:29]
	global_store_dword v[64:65], v68, off
.LBB0_458:
	s_or_b64 exec, exec, s[0:1]
	v_lshlrev_b32_e32 v64, 16, v158
	s_waitcnt lgkmcnt(0)
	v_and_b32_e32 v65, 0xffff0000, v158
	v_pk_add_f32 v[60:61], v[60:61], v[64:65]
	v_lshlrev_b32_e32 v64, 16, v159
	v_and_b32_e32 v65, 0xffff0000, v159
	v_pk_add_f32 v[62:63], v[62:63], v[64:65]
	v_cvt_pk_bf16_f32 v60, v60, v61
	v_cvt_pk_bf16_f32 v61, v62, v63
	v_lshlrev_b32_e32 v62, 16, v160
	v_and_b32_e32 v63, 0xffff0000, v160
	v_pk_add_f32 v[56:57], v[56:57], v[62:63]
	s_mov_b64 s[0:1], 0x80000
	v_cvt_pk_bf16_f32 v62, v56, v57
	v_lshlrev_b32_e32 v56, 16, v161
	v_and_b32_e32 v57, 0xffff0000, v161
	v_pk_add_f32 v[56:57], v[58:59], v[56:57]
	v_and_b32_e32 v58, 0xffff0000, v61
	v_cvt_pk_bf16_f32 v63, v56, v57
	v_and_b32_e32 v57, 0xffff0000, v60
	v_lshlrev_b32_e32 v56, 16, v60
	v_mul_f32_e32 v57, v57, v57
	v_fmac_f32_e32 v57, v56, v56
	v_lshlrev_b32_e32 v56, 16, v61
	v_mul_f32_e32 v58, v58, v58
	v_fmac_f32_e32 v58, v56, v56
	v_add_f32_e32 v56, v57, v58
	v_and_b32_e32 v58, 0xffff0000, v62
	v_lshlrev_b32_e32 v57, 16, v62
	v_mul_f32_e32 v58, v58, v58
	v_fmac_f32_e32 v58, v57, v57
	v_add_f32_e32 v56, v58, v56
	v_and_b32_e32 v58, 0xffff0000, v63
	v_lshlrev_b32_e32 v57, 16, v63
	v_mul_f32_e32 v58, v58, v58
	v_fmac_f32_e32 v58, v57, v57
	v_add_f32_e32 v58, v58, v56
	v_lshlrev_b32_e32 v56, 16, v150
	v_and_b32_e32 v57, 0xffff0000, v150
	v_pk_add_f32 v[52:53], v[52:53], v[56:57]
	v_lshlrev_b32_e32 v56, 16, v151
	v_and_b32_e32 v57, 0xffff0000, v151
	v_pk_add_f32 v[54:55], v[54:55], v[56:57]
	v_cvt_pk_bf16_f32 v52, v52, v53
	v_cvt_pk_bf16_f32 v53, v54, v55
	v_lshlrev_b32_e32 v54, 16, v152
	v_and_b32_e32 v55, 0xffff0000, v152
	v_pk_add_f32 v[48:49], v[48:49], v[54:55]
	s_nop 0
	v_cvt_pk_bf16_f32 v54, v48, v49
	v_lshlrev_b32_e32 v48, 16, v153
	v_and_b32_e32 v49, 0xffff0000, v153
	v_pk_add_f32 v[48:49], v[50:51], v[48:49]
	v_and_b32_e32 v50, 0xffff0000, v53
	v_cvt_pk_bf16_f32 v55, v48, v49
	v_and_b32_e32 v49, 0xffff0000, v52
	v_lshlrev_b32_e32 v48, 16, v52
	v_mul_f32_e32 v49, v49, v49
	v_fmac_f32_e32 v49, v48, v48
	v_add_f32_e32 v48, v49, v58
	v_lshlrev_b32_e32 v49, 16, v53
	v_mul_f32_e32 v50, v50, v50
	v_fmac_f32_e32 v50, v49, v49
	v_add_f32_e32 v48, v50, v48
	v_and_b32_e32 v50, 0xffff0000, v54
	v_lshlrev_b32_e32 v49, 16, v54
	v_mul_f32_e32 v50, v50, v50
	v_fmac_f32_e32 v50, v49, v49
	v_add_f32_e32 v48, v50, v48
	v_and_b32_e32 v50, 0xffff0000, v55
	v_lshlrev_b32_e32 v49, 16, v55
	v_mul_f32_e32 v50, v50, v50
	v_fmac_f32_e32 v50, v49, v49
	v_add_f32_e32 v48, v50, v48
	ds_bpermute_b32 v49, v235, v48
	v_lshl_add_u64 v[50:51], v[214:215], 0, s[0:1]
	s_mov_b64 s[0:1], 0x80100
	v_lshl_add_u64 v[56:57], v[214:215], 0, s[0:1]
	global_store_dwordx4 v[50:51], v[60:63], off
	global_store_dwordx4 v[56:57], v[52:55], off
	s_waitcnt lgkmcnt(0)
	v_add_f32_e32 v48, v48, v49
	ds_bpermute_b32 v49, v236, v48
	s_and_saveexec_b64 s[0:1], s[38:39]
	s_cbranch_execz .LBB0_460
	v_add_u32_e32 v50, 0x80, v212
	v_ashrrev_i32_e32 v51, 31, v50
	s_waitcnt lgkmcnt(0)
	v_add_f32_e32 v52, v48, v49
	v_lshlrev_b64 v[48:49], 7, v[50:51]
	v_lshl_add_u64 v[48:49], s[44:45], 0, v[48:49]
	v_lshl_add_u64 v[48:49], s[66:67], 2, v[48:49]
	s_lshl_b32 s28, s47, 2
	v_lshl_add_u64 v[48:49], v[48:49], 0, s[28:29]
	global_store_dword v[48:49], v52, off
; __device__ __forceinline__ unsigned pk_bf16(float lo, float hi) { f32x2e v = {lo, hi}; bf16x2e b = __builtin_convertvector(v, bf16x2e); return __builtin_bit_cast(unsigned, b); }
;     __device__ __forceinline__ void operator()(const f32x4 (&acc)[2][2][4][2], const Unit& u, int wr, int wc, int fr, int fq) const {
;     ...
;             for (int m = 0; m < 4; ++m) { const int row = u.pm * BM + ai * HALF + wr * 64 + m * 16 + fr; bf16_t* rowp = base + (size_t)(ai * HALF + m * 16) * ldc;
;                 float qs = 0.f;
; #pragma unroll
;                 for (int bj = 0; bj < 2; ++bj) { const f32x4 a0 = acc[ai][bj][m][0], a1 = acc[ai][bj][m][1]; const u32x4 q = r[ai][m][bj]; u32x4 w;
;                     w.x = pk_bf16(__uint_as_float(q.x << 16) + a0.x, __uint_as_float(q.x & 0xffff0000u) + a0.y);
;                     w.y = pk_bf16(__uint_as_float(q.y << 16) + a0.z, __uint_as_float(q.y & 0xffff0000u) + a0.w);
;                     w.z = pk_bf16(__uint_as_float(q.z << 16) + a1.x, __uint_as_float(q.z & 0xffff0000u) + a1.y);
;                     w.w = pk_bf16(__uint_as_float(q.w << 16) + a1.z, __uint_as_float(q.w & 0xffff0000u) + a1.w);
;                     *(u32x4*)(rowp + bj * HALF) = w;
; #pragma unroll
;                     for (int e = 0; e < 4; ++e) { const float h0 = __uint_as_float(w[e] << 16), h1 = __uint_as_float(w[e] & 0xffff0000u); qs += h0 * h0 + h1 * h1; } }
;                 qs += __shfl_xor(qs, 16); qs += __shfl_xor(qs, 32);
;                 if (fq == 0) ss[(size_t)row * 32 + u.pn * 4 + wc] = qs; }
.LBB0_460:
	s_or_b64 exec, exec, s[0:1]
	v_lshlrev_b32_e32 v48, 16, v142
	s_waitcnt lgkmcnt(0)
	v_and_b32_e32 v49, 0xffff0000, v142
	v_pk_add_f32 v[44:45], v[44:45], v[48:49]
	v_lshlrev_b32_e32 v48, 16, v143
	v_and_b32_e32 v49, 0xffff0000, v143
	v_pk_add_f32 v[46:47], v[46:47], v[48:49]
	v_cvt_pk_bf16_f32 v44, v44, v45
	v_cvt_pk_bf16_f32 v45, v46, v47
	v_lshlrev_b32_e32 v46, 16, v144
	v_and_b32_e32 v47, 0xffff0000, v144
	v_pk_add_f32 v[40:41], v[40:41], v[46:47]
	s_mov_b64 s[0:1], 0x90000
	v_cvt_pk_bf16_f32 v46, v40, v41
	v_lshlrev_b32_e32 v40, 16, v145
	v_and_b32_e32 v41, 0xffff0000, v145
	v_pk_add_f32 v[40:41], v[42:43], v[40:41]
	v_and_b32_e32 v42, 0xffff0000, v45
	v_cvt_pk_bf16_f32 v47, v40, v41
	v_and_b32_e32 v41, 0xffff0000, v44
	v_lshlrev_b32_e32 v40, 16, v44
	v_mul_f32_e32 v41, v41, v41
	v_fmac_f32_e32 v41, v40, v40
	v_lshlrev_b32_e32 v40, 16, v45
	v_mul_f32_e32 v42, v42, v42
	v_fmac_f32_e32 v42, v40, v40
	v_add_f32_e32 v40, v41, v42
	v_and_b32_e32 v42, 0xffff0000, v46
	v_lshlrev_b32_e32 v41, 16, v46
	v_mul_f32_e32 v42, v42, v42
	v_fmac_f32_e32 v42, v41, v41
	v_add_f32_e32 v40, v42, v40
	v_and_b32_e32 v42, 0xffff0000, v47
	v_lshlrev_b32_e32 v41, 16, v47
	v_mul_f32_e32 v42, v42, v42
	v_fmac_f32_e32 v42, v41, v41
	v_add_f32_e32 v42, v42, v40
	v_lshlrev_b32_e32 v40, 16, v138
	v_and_b32_e32 v41, 0xffff0000, v138
	v_pk_add_f32 v[36:37], v[36:37], v[40:41]
	v_lshlrev_b32_e32 v40, 16, v139
	v_and_b32_e32 v41, 0xffff0000, v139
	v_pk_add_f32 v[38:39], v[38:39], v[40:41]
	v_cvt_pk_bf16_f32 v36, v36, v37
	v_cvt_pk_bf16_f32 v37, v38, v39
	v_lshlrev_b32_e32 v38, 16, v140
	v_and_b32_e32 v39, 0xffff0000, v140
	v_pk_add_f32 v[32:33], v[32:33], v[38:39]
	s_nop 0
	v_cvt_pk_bf16_f32 v38, v32, v33
	v_lshlrev_b32_e32 v32, 16, v141
	v_and_b32_e32 v33, 0xffff0000, v141
	v_pk_add_f32 v[32:33], v[34:35], v[32:33]
	v_and_b32_e32 v34, 0xffff0000, v37
	v_cvt_pk_bf16_f32 v39, v32, v33
	v_and_b32_e32 v33, 0xffff0000, v36
	v_lshlrev_b32_e32 v32, 16, v36
	v_mul_f32_e32 v33, v33, v33
	v_fmac_f32_e32 v33, v32, v32
	v_add_f32_e32 v32, v33, v42
	v_lshlrev_b32_e32 v33, 16, v37
	v_mul_f32_e32 v34, v34, v34
	v_fmac_f32_e32 v34, v33, v33
	v_add_f32_e32 v32, v34, v32
	v_and_b32_e32 v34, 0xffff0000, v38
	v_lshlrev_b32_e32 v33, 16, v38
	v_mul_f32_e32 v34, v34, v34
	v_fmac_f32_e32 v34, v33, v33
	v_add_f32_e32 v32, v34, v32
	v_and_b32_e32 v34, 0xffff0000, v39
	v_lshlrev_b32_e32 v33, 16, v39
	v_mul_f32_e32 v34, v34, v34
	v_fmac_f32_e32 v34, v33, v33
	v_add_f32_e32 v32, v34, v32
	ds_bpermute_b32 v33, v235, v32
	v_lshl_add_u64 v[34:35], v[214:215], 0, s[0:1]
	s_mov_b64 s[0:1], 0x90100
	v_lshl_add_u64 v[40:41], v[214:215], 0, s[0:1]
	global_store_dwordx4 v[34:35], v[44:47], off
	global_store_dwordx4 v[40:41], v[36:39], off
	s_waitcnt lgkmcnt(0)
	v_add_f32_e32 v32, v32, v33
	ds_bpermute_b32 v33, v236, v32
	s_and_saveexec_b64 s[0:1], s[38:39]
	s_cbranch_execz .LBB0_462
	v_add_u32_e32 v34, 0x90, v212
	v_ashrrev_i32_e32 v35, 31, v34
	s_waitcnt lgkmcnt(0)
	v_add_f32_e32 v36, v32, v33
	v_lshlrev_b64 v[32:33], 7, v[34:35]
	v_lshl_add_u64 v[32:33], s[44:45], 0, v[32:33]
	v_lshl_add_u64 v[32:33], s[66:67], 2, v[32:33]
	s_lshl_b32 s28, s47, 2
	v_lshl_add_u64 v[32:33], v[32:33], 0, s[28:29]
	global_store_dword v[32:33], v36, off
; __device__ __forceinline__ unsigned pk_bf16(float lo, float hi) { f32x2e v = {lo, hi}; bf16x2e b = __builtin_convertvector(v, bf16x2e); return __builtin_bit_cast(unsigned, b); }
;     __device__ __forceinline__ void operator()(const f32x4 (&acc)[2][2][4][2], const Unit& u, int wr, int wc, int fr, int fq) const {
;     ...
;             for (int m = 0; m < 4; ++m) { const int row = u.pm * BM + ai * HALF + wr * 64 + m * 16 + fr; bf16_t* rowp = base + (size_t)(ai * HALF + m * 16) * ldc;
;                 float qs = 0.f;
; #pragma unroll
;                 for (int bj = 0; bj < 2; ++bj) { const f32x4 a0 = acc[ai][bj][m][0], a1 = acc[ai][bj][m][1]; const u32x4 q = r[ai][m][bj]; u32x4 w;
;                     w.x = pk_bf16(__uint_as_float(q.x << 16) + a0.x, __uint_as_float(q.x & 0xffff0000u) + a0.y);
;                     w.y = pk_bf16(__uint_as_float(q.y << 16) + a0.z, __uint_as_float(q.y & 0xffff0000u) + a0.w);
;                     w.z = pk_bf16(__uint_as_float(q.z << 16) + a1.x, __uint_as_float(q.z & 0xffff0000u) + a1.y);
;                     w.w = pk_bf16(__uint_as_float(q.w << 16) + a1.z, __uint_as_float(q.w & 0xffff0000u) + a1.w);
;                     *(u32x4*)(rowp + bj * HALF) = w;
; #pragma unroll
;                     for (int e = 0; e < 4; ++e) { const float h0 = __uint_as_float(w[e] << 16), h1 = __uint_as_float(w[e] & 0xffff0000u); qs += h0 * h0 + h1 * h1; } }
;                 qs += __shfl_xor(qs, 16); qs += __shfl_xor(qs, 32);
;                 if (fq == 0) ss[(size_t)row * 32 + u.pn * 4 + wc] = qs; }
.LBB0_462:
	s_or_b64 exec, exec, s[0:1]
	v_lshlrev_b32_e32 v32, 16, v126
	s_waitcnt lgkmcnt(0)
	v_and_b32_e32 v33, 0xffff0000, v126
	v_pk_add_f32 v[28:29], v[28:29], v[32:33]
	v_lshlrev_b32_e32 v32, 16, v127
	v_and_b32_e32 v33, 0xffff0000, v127
	v_pk_add_f32 v[30:31], v[30:31], v[32:33]
	v_cvt_pk_bf16_f32 v28, v28, v29
	v_cvt_pk_bf16_f32 v29, v30, v31
	v_lshlrev_b32_e32 v30, 16, v128
	v_and_b32_e32 v31, 0xffff0000, v128
	v_pk_add_f32 v[24:25], v[24:25], v[30:31]
	s_mov_b64 s[0:1], 0xa0000
	v_cvt_pk_bf16_f32 v30, v24, v25
	v_lshlrev_b32_e32 v24, 16, v129
	v_and_b32_e32 v25, 0xffff0000, v129
	v_pk_add_f32 v[24:25], v[26:27], v[24:25]
	v_and_b32_e32 v26, 0xffff0000, v29
	v_cvt_pk_bf16_f32 v31, v24, v25
	v_and_b32_e32 v25, 0xffff0000, v28
	v_lshlrev_b32_e32 v24, 16, v28
	v_mul_f32_e32 v25, v25, v25
	v_fmac_f32_e32 v25, v24, v24
	v_lshlrev_b32_e32 v24, 16, v29
	v_mul_f32_e32 v26, v26, v26
	v_fmac_f32_e32 v26, v24, v24
	v_add_f32_e32 v24, v25, v26
	v_and_b32_e32 v26, 0xffff0000, v30
	v_lshlrev_b32_e32 v25, 16, v30
	v_mul_f32_e32 v26, v26, v26
	v_fmac_f32_e32 v26, v25, v25
	v_add_f32_e32 v24, v26, v24
	v_and_b32_e32 v26, 0xffff0000, v31
	v_lshlrev_b32_e32 v25, 16, v31
	v_mul_f32_e32 v26, v26, v26
	v_fmac_f32_e32 v26, v25, v25
	v_add_f32_e32 v26, v26, v24
	v_lshlrev_b32_e32 v24, 16, v118
	v_and_b32_e32 v25, 0xffff0000, v118
	v_pk_add_f32 v[20:21], v[20:21], v[24:25]
	v_lshlrev_b32_e32 v24, 16, v119
	v_and_b32_e32 v25, 0xffff0000, v119
	v_pk_add_f32 v[22:23], v[22:23], v[24:25]
	v_cvt_pk_bf16_f32 v20, v20, v21
	v_cvt_pk_bf16_f32 v21, v22, v23
	v_lshlrev_b32_e32 v22, 16, v120
	v_and_b32_e32 v23, 0xffff0000, v120
	v_pk_add_f32 v[16:17], v[16:17], v[22:23]
	s_nop 0
	v_cvt_pk_bf16_f32 v22, v16, v17
	v_lshlrev_b32_e32 v16, 16, v121
	v_and_b32_e32 v17, 0xffff0000, v121
	v_pk_add_f32 v[16:17], v[18:19], v[16:17]
	v_and_b32_e32 v18, 0xffff0000, v21
	v_cvt_pk_bf16_f32 v23, v16, v17
	v_and_b32_e32 v17, 0xffff0000, v20
	v_lshlrev_b32_e32 v16, 16, v20
	v_mul_f32_e32 v17, v17, v17
	v_fmac_f32_e32 v17, v16, v16
	v_add_f32_e32 v16, v17, v26
	v_lshlrev_b32_e32 v17, 16, v21
	v_mul_f32_e32 v18, v18, v18
	v_fmac_f32_e32 v18, v17, v17
	v_add_f32_e32 v16, v18, v16
	v_and_b32_e32 v18, 0xffff0000, v22
	v_lshlrev_b32_e32 v17, 16, v22
	v_mul_f32_e32 v18, v18, v18
	v_fmac_f32_e32 v18, v17, v17
	v_add_f32_e32 v16, v18, v16
	v_and_b32_e32 v18, 0xffff0000, v23
	v_lshlrev_b32_e32 v17, 16, v23
	v_mul_f32_e32 v18, v18, v18
	v_fmac_f32_e32 v18, v17, v17
	v_add_f32_e32 v16, v18, v16
	ds_bpermute_b32 v17, v235, v16
	v_lshl_add_u64 v[18:19], v[214:215], 0, s[0:1]
	s_mov_b64 s[0:1], 0xa0100
	v_lshl_add_u64 v[24:25], v[214:215], 0, s[0:1]
	global_store_dwordx4 v[18:19], v[28:31], off
	global_store_dwordx4 v[24:25], v[20:23], off
	s_waitcnt lgkmcnt(0)
	v_add_f32_e32 v16, v16, v17
	ds_bpermute_b32 v17, v236, v16
	s_and_saveexec_b64 s[0:1], s[38:39]
	s_cbranch_execz .LBB0_464
	v_add_u32_e32 v18, 0xa0, v212
	v_ashrrev_i32_e32 v19, 31, v18
	s_waitcnt lgkmcnt(0)
	v_add_f32_e32 v20, v16, v17
	v_lshlrev_b64 v[16:17], 7, v[18:19]
	v_lshl_add_u64 v[16:17], s[44:45], 0, v[16:17]
	v_lshl_add_u64 v[16:17], s[66:67], 2, v[16:17]
	s_lshl_b32 s28, s47, 2
	v_lshl_add_u64 v[16:17], v[16:17], 0, s[28:29]
	global_store_dword v[16:17], v20, off
.LBB0_464:
	s_or_b64 exec, exec, s[0:1]
	v_lshlrev_b32_e32 v16, 16, v106
	s_waitcnt lgkmcnt(0)
	v_and_b32_e32 v17, 0xffff0000, v106
	v_pk_add_f32 v[12:13], v[12:13], v[16:17]
	v_lshlrev_b32_e32 v16, 16, v107
	v_and_b32_e32 v17, 0xffff0000, v107
	v_pk_add_f32 v[14:15], v[14:15], v[16:17]
	v_cvt_pk_bf16_f32 v12, v12, v13
	v_cvt_pk_bf16_f32 v13, v14, v15
	v_lshlrev_b32_e32 v14, 16, v108
	v_and_b32_e32 v15, 0xffff0000, v108
	v_pk_add_f32 v[8:9], v[8:9], v[14:15]
	s_mov_b64 s[0:1], 0xb0000
	v_cvt_pk_bf16_f32 v14, v8, v9
	v_lshlrev_b32_e32 v8, 16, v109
	v_and_b32_e32 v9, 0xffff0000, v109
	v_pk_add_f32 v[8:9], v[10:11], v[8:9]
	v_and_b32_e32 v10, 0xffff0000, v13
	v_cvt_pk_bf16_f32 v15, v8, v9
	v_and_b32_e32 v9, 0xffff0000, v12
	v_lshlrev_b32_e32 v8, 16, v12
	v_mul_f32_e32 v9, v9, v9
	v_fmac_f32_e32 v9, v8, v8
	v_lshlrev_b32_e32 v8, 16, v13
	v_mul_f32_e32 v10, v10, v10
	v_fmac_f32_e32 v10, v8, v8
	v_add_f32_e32 v8, v9, v10
	v_and_b32_e32 v10, 0xffff0000, v14
	v_lshlrev_b32_e32 v9, 16, v14
	v_mul_f32_e32 v10, v10, v10
	v_fmac_f32_e32 v10, v9, v9
	v_add_f32_e32 v8, v10, v8
	v_and_b32_e32 v10, 0xffff0000, v15
	v_lshlrev_b32_e32 v9, 16, v15
	v_mul_f32_e32 v10, v10, v10
	v_fmac_f32_e32 v10, v9, v9
	v_add_f32_e32 v10, v10, v8
	v_lshlrev_b32_e32 v8, 16, v98
	v_and_b32_e32 v9, 0xffff0000, v98
	v_pk_add_f32 v[4:5], v[4:5], v[8:9]
	v_lshlrev_b32_e32 v8, 16, v99
	v_and_b32_e32 v9, 0xffff0000, v99
	v_pk_add_f32 v[6:7], v[6:7], v[8:9]
	v_cvt_pk_bf16_f32 v4, v4, v5
	v_cvt_pk_bf16_f32 v5, v6, v7
	v_lshlrev_b32_e32 v6, 16, v100
	v_and_b32_e32 v7, 0xffff0000, v100
	v_pk_add_f32 v[0:1], v[0:1], v[6:7]
	s_nop 0
	v_cvt_pk_bf16_f32 v6, v0, v1
	v_lshlrev_b32_e32 v0, 16, v101
	v_and_b32_e32 v1, 0xffff0000, v101
	v_pk_add_f32 v[0:1], v[2:3], v[0:1]
	v_and_b32_e32 v2, 0xffff0000, v5
	v_cvt_pk_bf16_f32 v7, v0, v1
	v_and_b32_e32 v1, 0xffff0000, v4
	v_lshlrev_b32_e32 v0, 16, v4
	v_mul_f32_e32 v1, v1, v1
	v_fmac_f32_e32 v1, v0, v0
	v_add_f32_e32 v0, v1, v10
	v_lshlrev_b32_e32 v1, 16, v5
	v_mul_f32_e32 v2, v2, v2
	v_fmac_f32_e32 v2, v1, v1
	v_add_f32_e32 v0, v2, v0
	v_and_b32_e32 v2, 0xffff0000, v6
	v_lshlrev_b32_e32 v1, 16, v6
	v_mul_f32_e32 v2, v2, v2
	v_fmac_f32_e32 v2, v1, v1
	v_add_f32_e32 v0, v2, v0
	v_and_b32_e32 v2, 0xffff0000, v7
	v_lshlrev_b32_e32 v1, 16, v7
	v_mul_f32_e32 v2, v2, v2
	v_fmac_f32_e32 v2, v1, v1
	v_add_f32_e32 v0, v2, v0
	ds_bpermute_b32 v1, v235, v0
	v_lshl_add_u64 v[2:3], v[214:215], 0, s[0:1]
	s_mov_b64 s[0:1], 0xb0100
	v_lshl_add_u64 v[8:9], v[214:215], 0, s[0:1]
	global_store_dwordx4 v[2:3], v[12:15], off
	global_store_dwordx4 v[8:9], v[4:7], off
	s_waitcnt lgkmcnt(0)
	v_add_f32_e32 v0, v0, v1
	ds_bpermute_b32 v1, v236, v0
	s_and_saveexec_b64 s[0:1], s[38:39]
	s_cbranch_execz .LBB0_466
	v_add_u32_e32 v2, 0xb0, v212
	v_ashrrev_i32_e32 v3, 31, v2
	s_waitcnt lgkmcnt(0)
	v_add_f32_e32 v4, v0, v1
	v_lshlrev_b64 v[0:1], 7, v[2:3]
	v_lshl_add_u64 v[0:1], s[44:45], 0, v[0:1]
	v_lshl_add_u64 v[0:1], s[66:67], 2, v[0:1]
	s_lshl_b32 s28, s47, 2
	v_lshl_add_u64 v[0:1], v[0:1], 0, s[28:29]
	global_store_dword v[0:1], v4, off

; __device__ __forceinline__ void tile_rstd(float (&rs)[2][4], const float* ssp, int rowtile, int wr, int fr, int fq) {
;     const int lane = fq * 16 + fr; f32x4 pa[2][4][2];
; #pragma unroll
;     for (int ai = 0; ai < 2; ++ai)
; #pragma unroll
;         for (int m = 0; m < 4; ++m) { const f32x4* p = (const f32x4*)(ssp + (size_t)(rowtile + wr * 64 + ai * HALF + m * 16 + (lane >> 2)) * 32 + (lane & 3) * 8); pa[ai][m][0] = p[0]; pa[ai][m][1] = p[1]; }
; #pragma unroll
;     for (int ai = 0; ai < 2; ++ai)
; #pragma unroll
;         for (int m = 0; m < 4; ++m) { const f32x4 a = pa[ai][m][0], b = pa[ai][m][1];
;             float t = ((a.x + a.y) + (a.z + a.w)) + ((b.x + b.y) + (b.z + b.w));
;             t += __shfl_xor(t, 1); t += __shfl_xor(t, 2);
;             rs[ai][m] = __shfl(rsqrtf(t * (1.0f / 2048.0f) + 1e-6f), fr * 4); }
.LBB0_513:
	s_lshl_b32 s0, s52, 8
	s_andn2_b64 vcc, exec, s[84:85]
	s_add_i32 s0, s0, s6
	s_cbranch_vccnz .LBB0_515
	v_or_b32_e32 v130, s0, v204
	v_ashrrev_i32_e32 v131, 31, v130
	v_lshlrev_b64 v[132:133], 7, v[130:131]
	v_lshl_add_u64 v[132:133], v[184:185], 0, v[132:133]
	global_load_dwordx4 v[212:215], v[132:133], off
	global_load_dwordx4 v[232:235], v[132:133], off offset:16
	v_or_b32_e32 v132, 16, v130
	v_ashrrev_i32_e32 v133, 31, v132
	v_lshlrev_b64 v[132:133], 7, v[132:133]
	v_lshl_add_u64 v[132:133], v[184:185], 0, v[132:133]
	global_load_dwordx4 v[242:245], v[132:133], off
	global_load_dwordx4 v[246:249], v[132:133], off offset:16
	v_or_b32_e32 v132, 32, v130
	v_ashrrev_i32_e32 v133, 31, v132
	v_lshlrev_b64 v[132:133], 7, v[132:133]
	v_lshl_add_u64 v[132:133], v[184:185], 0, v[132:133]
	global_load_dwordx4 v[170:173], v[132:133], off
	global_load_dwordx4 v[174:177], v[132:133], off offset:16
	v_or_b32_e32 v132, 48, v130
	v_ashrrev_i32_e32 v133, 31, v132
	v_lshlrev_b64 v[132:133], 7, v[132:133]
	v_lshl_add_u64 v[132:133], v[184:185], 0, v[132:133]
	global_load_dwordx4 v[166:169], v[132:133], off
	global_load_dwordx4 v[162:165], v[132:133], off offset:16
	v_add_u32_e32 v132, 0x80, v130
	v_ashrrev_i32_e32 v133, 31, v132
	v_lshlrev_b64 v[132:133], 7, v[132:133]
	v_lshl_add_u64 v[132:133], v[184:185], 0, v[132:133]
	global_load_dwordx4 v[158:161], v[132:133], off
	global_load_dwordx4 v[154:157], v[132:133], off offset:16
	v_add_u32_e32 v132, 0x90, v130
	v_ashrrev_i32_e32 v133, 31, v132
	v_lshlrev_b64 v[132:133], 7, v[132:133]
	v_lshl_add_u64 v[132:133], v[184:185], 0, v[132:133]
	global_load_dwordx4 v[150:153], v[132:133], off
	global_load_dwordx4 v[146:149], v[132:133], off offset:16
	v_add_u32_e32 v132, 0xa0, v130
	v_ashrrev_i32_e32 v133, 31, v132
	v_lshlrev_b64 v[132:133], 7, v[132:133]
	v_add_u32_e32 v130, 0xb0, v130
	v_lshl_add_u64 v[132:133], v[184:185], 0, v[132:133]
	v_ashrrev_i32_e32 v131, 31, v130
	global_load_dwordx4 v[142:145], v[132:133], off
	global_load_dwordx4 v[138:141], v[132:133], off offset:16
	v_lshlrev_b64 v[130:131], 7, v[130:131]
	v_lshl_add_u64 v[130:131], v[184:185], 0, v[130:131]
	global_load_dwordx4 v[134:137], v[130:131], off
	s_nop 0
	global_load_dwordx4 v[130:133], v[130:131], off offset:16
	v_and_b32_e32 v192, 64, v220
	v_xor_b32_e32 v190, 1, v220
	v_add_u32_e32 v192, 64, v192
	v_cmp_lt_i32_e32 vcc, v190, v192
	s_waitcnt vmcnt(0) lgkmcnt(0)
	v_mov_b32_e32 v202, v212
	v_mov_b32_e32 v203, v232
	v_mov_b32_e32 v232, v213
	v_mov_b32_e32 v212, v214
	v_mov_b32_e32 v213, v234
	v_mov_b32_e32 v234, v215
	v_pk_add_f32 v[202:203], v[202:203], v[232:233]
	v_pk_add_f32 v[212:213], v[212:213], v[234:235]
	v_mov_b32_e32 v214, v244
	v_pk_add_f32 v[202:203], v[202:203], v[212:213]
	v_mov_b32_e32 v212, v242
	v_mov_b32_e32 v213, v246
	v_mov_b32_e32 v246, v243
	v_mov_b32_e32 v215, v248
	v_mov_b32_e32 v248, v245
	v_pk_add_f32 v[212:213], v[212:213], v[246:247]
	v_pk_add_f32 v[214:215], v[214:215], v[248:249]
	v_cndmask_b32_e32 v190, v220, v190, vcc
	v_pk_add_f32 v[212:213], v[212:213], v[214:215]
	v_mov_b32_e32 v215, v202
	v_mov_b32_e32 v214, v212
	v_mov_b32_e32 v202, v213
	v_lshlrev_b32_e32 v210, 2, v190
	v_pk_add_f32 v[202:203], v[214:215], v[202:203]
	ds_bpermute_b32 v213, v210, v203
	ds_bpermute_b32 v212, v210, v202
	v_xor_b32_e32 v190, 2, v220
	v_cmp_lt_i32_e32 vcc, v190, v192
	s_waitcnt lgkmcnt(0)
	v_pk_add_f32 v[202:203], v[202:203], v[212:213]
	v_cndmask_b32_e32 v190, v220, v190, vcc
	v_lshlrev_b32_e32 v209, 2, v190
	ds_bpermute_b32 v213, v209, v203
	ds_bpermute_b32 v212, v209, v202
	v_lshlrev_b32_e32 v190, 2, v220
	v_and_or_b32 v208, v190, s25, v205
	s_waitcnt lgkmcnt(0)
	v_pk_add_f32 v[212:213], v[202:203], v[212:213]
	v_mov_b64_e32 v[202:203], s[24:25]
	v_pk_fma_f32 v[212:213], v[212:213], s[18:19], v[202:203] op_sel_hi:[1,0,0]
	s_nop 0
	v_mul_f32_e32 v190, 0x4b800000, v213
	v_cmp_gt_f32_e64 s[40:41], s12, v213
	v_cmp_gt_f32_e32 vcc, s12, v212
	s_nop 0
	v_cndmask_b32_e64 v190, v213, v190, s[40:41]
	v_rsq_f32_e32 v190, v190
	v_mov_b32_e32 v213, v174
	v_mov_b32_e32 v174, v171
	v_mul_f32_e32 v192, 0x45800000, v190
	v_cndmask_b32_e64 v190, v190, v192, s[40:41]
	ds_bpermute_b32 v192, v208, v190
	v_mul_f32_e32 v190, 0x4b800000, v212
	v_cndmask_b32_e32 v190, v212, v190, vcc
	v_mov_b32_e32 v212, v170
	v_pk_add_f32 v[170:171], v[212:213], v[174:175]
	v_mov_b32_e32 v174, v172
	v_mov_b32_e32 v175, v176
	v_mov_b32_e32 v176, v173
	v_pk_add_f32 v[172:173], v[174:175], v[176:177]
	v_rsq_f32_e32 v190, v190
	v_pk_add_f32 v[170:171], v[170:171], v[172:173]
	v_mov_b32_e32 v172, v166
	v_mov_b32_e32 v173, v162
	v_mov_b32_e32 v162, v167
	v_mov_b32_e32 v166, v168
	v_mov_b32_e32 v167, v164
	v_mov_b32_e32 v164, v169
	v_pk_add_f32 v[162:163], v[172:173], v[162:163]
	v_pk_add_f32 v[164:165], v[166:167], v[164:165]
	v_mov_b32_e32 v166, v158
	v_pk_add_f32 v[162:163], v[162:163], v[164:165]
	v_mov_b32_e32 v165, v170
	v_mov_b32_e32 v164, v162
	v_mov_b32_e32 v170, v163
	v_pk_add_f32 v[162:163], v[164:165], v[170:171]
	ds_bpermute_b32 v165, v210, v163
	ds_bpermute_b32 v164, v210, v162
	v_mov_b32_e32 v167, v154
	v_mov_b32_e32 v154, v159
	v_mov_b32_e32 v158, v160
	v_mov_b32_e32 v159, v156
	v_mov_b32_e32 v156, v161
	v_pk_add_f32 v[154:155], v[166:167], v[154:155]
	v_pk_add_f32 v[156:157], v[158:159], v[156:157]
	s_waitcnt lgkmcnt(0)
; __device__ __forceinline__ void tile_rstd(float (&rs)[2][4], const float* ssp, int rowtile, int wr, int fr, int fq) {
;     ...
;         for (int m = 0; m < 4; ++m) { const f32x4 a = pa[ai][m][0], b = pa[ai][m][1];
;             float t = ((a.x + a.y) + (a.z + a.w)) + ((b.x + b.y) + (b.z + b.w));
;             t += __shfl_xor(t, 1); t += __shfl_xor(t, 2);
;             rs[ai][m] = __shfl(rsqrtf(t * (1.0f / 2048.0f) + 1e-6f), fr * 4); }
	v_pk_add_f32 v[162:163], v[162:163], v[164:165]
	v_pk_add_f32 v[154:155], v[154:155], v[156:157]
	v_mov_b32_e32 v156, v150
	v_mov_b32_e32 v157, v146
	v_mov_b32_e32 v146, v151
	v_mov_b32_e32 v150, v152
	v_mov_b32_e32 v151, v148
	v_mov_b32_e32 v148, v153
	v_pk_add_f32 v[146:147], v[156:157], v[146:147]
	v_pk_add_f32 v[148:149], v[150:151], v[148:149]
	ds_bpermute_b32 v165, v209, v163
	v_pk_add_f32 v[146:147], v[146:147], v[148:149]
	v_mov_b32_e32 v149, v154
	v_mov_b32_e32 v148, v146
	v_mov_b32_e32 v154, v147
	ds_bpermute_b32 v164, v209, v162
	v_pk_add_f32 v[146:147], v[148:149], v[154:155]
	ds_bpermute_b32 v149, v210, v147
	ds_bpermute_b32 v148, v210, v146
	v_mov_b32_e32 v150, v142
	v_mov_b32_e32 v151, v138
	v_mov_b32_e32 v138, v143
	v_mov_b32_e32 v142, v144
	v_mov_b32_e32 v143, v140
	v_mov_b32_e32 v140, v145
	v_pk_add_f32 v[138:139], v[150:151], v[138:139]
	v_pk_add_f32 v[140:141], v[142:143], v[140:141]
	s_waitcnt lgkmcnt(2)
	v_pk_add_f32 v[162:163], v[162:163], v[164:165]
	v_pk_add_f32 v[138:139], v[138:139], v[140:141]
	v_mov_b32_e32 v140, v134
	v_mov_b32_e32 v141, v130
	v_mov_b32_e32 v130, v135
	v_mov_b32_e32 v134, v136
	v_mov_b32_e32 v135, v132
	v_mov_b32_e32 v132, v137
	v_pk_add_f32 v[130:131], v[140:141], v[130:131]
	v_pk_add_f32 v[132:133], v[134:135], v[132:133]
	v_pk_fma_f32 v[162:163], v[162:163], s[18:19], v[202:203] op_sel_hi:[1,0,0]
	v_pk_add_f32 v[130:131], v[130:131], v[132:133]
	s_waitcnt lgkmcnt(0)
	v_pk_add_f32 v[146:147], v[146:147], v[148:149]
	v_mov_b32_e32 v132, v130
	v_mov_b32_e32 v133, v138
	v_mov_b32_e32 v138, v131
	v_mul_f32_e32 v164, 0x4b800000, v163
	v_cmp_gt_f32_e64 s[40:41], s12, v163
	ds_bpermute_b32 v149, v209, v147
	ds_bpermute_b32 v148, v209, v146
	v_pk_add_f32 v[130:131], v[132:133], v[138:139]
	v_cndmask_b32_e64 v163, v163, v164, s[40:41]
	ds_bpermute_b32 v133, v210, v131
	ds_bpermute_b32 v132, v210, v130
	v_rsq_f32_e32 v163, v163
	s_waitcnt lgkmcnt(2)
	v_pk_add_f32 v[146:147], v[146:147], v[148:149]
	v_mul_f32_e32 v211, 0x45800000, v190
	v_pk_fma_f32 v[146:147], v[146:147], s[18:19], v[202:203] op_sel_hi:[1,0,0]
	v_mul_f32_e32 v164, 0x45800000, v163
	s_waitcnt lgkmcnt(0)
	v_pk_add_f32 v[130:131], v[130:131], v[132:133]
	v_cndmask_b32_e64 v163, v163, v164, s[40:41]
	v_mul_f32_e32 v148, 0x4b800000, v147
	v_cmp_gt_f32_e64 s[40:41], s12, v147
	ds_bpermute_b32 v133, v209, v131
	ds_bpermute_b32 v132, v209, v130
	v_cndmask_b32_e32 v190, v190, v211, vcc
	v_cmp_gt_f32_e32 vcc, s12, v162
	ds_bpermute_b32 v164, v208, v163
	v_mul_f32_e32 v163, 0x4b800000, v162
	v_cndmask_b32_e64 v147, v147, v148, s[40:41]
	v_cndmask_b32_e32 v162, v162, v163, vcc
	v_rsq_f32_e32 v147, v147
	v_rsq_f32_e32 v162, v162
	s_waitcnt lgkmcnt(1)
	v_pk_add_f32 v[130:131], v[130:131], v[132:133]
	ds_bpermute_b32 v190, v208, v190
	v_mul_f32_e32 v148, 0x45800000, v147
	v_pk_fma_f32 v[130:131], v[130:131], s[18:19], v[202:203] op_sel_hi:[1,0,0]
	v_mul_f32_e32 v163, 0x45800000, v162
	v_cndmask_b32_e64 v147, v147, v148, s[40:41]
	v_mul_f32_e32 v132, 0x4b800000, v131
	v_cmp_gt_f32_e64 s[40:41], s12, v131
	v_cndmask_b32_e32 v162, v162, v163, vcc
	v_cmp_gt_f32_e32 vcc, s12, v146
	ds_bpermute_b32 v148, v208, v147
	v_mul_f32_e32 v147, 0x4b800000, v146
	v_cndmask_b32_e64 v131, v131, v132, s[40:41]
	v_cndmask_b32_e32 v146, v146, v147, vcc
	v_rsq_f32_e32 v131, v131
	v_rsq_f32_e32 v146, v146
	ds_bpermute_b32 v162, v208, v162
	v_mul_f32_e32 v132, 0x45800000, v131
	v_mul_f32_e32 v147, 0x45800000, v146
	v_cndmask_b32_e64 v131, v131, v132, s[40:41]
	v_cndmask_b32_e32 v146, v146, v147, vcc
	v_cmp_gt_f32_e32 vcc, s12, v130
	ds_bpermute_b32 v132, v208, v131
	v_mul_f32_e32 v131, 0x4b800000, v130
	v_cndmask_b32_e32 v130, v130, v131, vcc
	v_rsq_f32_e32 v130, v130
	ds_bpermute_b32 v146, v208, v146
	v_mul_f32_e32 v131, 0x45800000, v130
	v_cndmask_b32_e32 v130, v130, v131, vcc
	ds_bpermute_b32 v130, v208, v130
	s_branch .LBB0_516

; __device__ __forceinline__ unsigned pk_bf16(float lo, float hi) { f32x2e v = {lo, hi}; bf16x2e b = __builtin_convertvector(v, bf16x2e); return __builtin_bit_cast(unsigned, b); }
;     __device__ __forceinline__ void operator()(const f32x4 (&acc)[2][2][4][2], const Unit& u, int wr, int wc, int fr, int fq) const {
;     ...
;             for (int m = 0; m < 4; ++m) { bf16_t* rowp = O + (size_t)(row0 + ai * HALF + m * 16) * ldc + col0;
;                 const float rs = rsa[ai][m];
; #pragma unroll
;                 for (int bj = 0; bj < 2; ++bj) { const f32x4 v0 = acc[ai][bj][m][0] * rs, v1 = acc[ai][bj][m][1] * rs;
;                     u32x4 w; w.x = pk_bf16(v0[0], v0[1]); w.y = pk_bf16(v0[2], v0[3]); w.z = pk_bf16(v1[0], v1[1]); w.w = pk_bf16(v1[2], v1[3]);
;                     *(u32x4*)(rowp + bj * HALF) = w; } }
.LBB0_516:
	v_or_b32_e32 v131, s0, v191
	s_ashr_i32 s0, s0, 31
	v_lshl_or_b32 v134, s31, 8, v206
	v_mul_lo_u32 v133, s67, v131
	s_mul_i32 s31, s66, s0
	v_mad_u64_u32 v[136:137], s[0:1], s66, v131, 0
	v_ashrrev_i32_e32 v135, 31, v134
	v_add3_u32 v137, v137, s31, v133
	v_lshl_add_u64 v[136:137], v[136:137], 1, s[74:75]
	v_lshlrev_b64 v[134:135], 1, v[134:135]
	v_pk_mul_f32 v[128:129], v[128:129], v[192:193] op_sel_hi:[1,0]
	v_pk_mul_f32 v[126:127], v[126:127], v[192:193] op_sel_hi:[1,0]
	v_pk_mul_f32 v[138:139], v[124:125], v[192:193] op_sel_hi:[1,0]
	v_pk_mul_f32 v[124:125], v[122:123], v[192:193] op_sel_hi:[1,0]
	v_lshl_add_u64 v[136:137], v[136:137], 0, v[134:135]
	v_cvt_pk_bf16_f32 v122, v126, v127
	v_cvt_pk_bf16_f32 v123, v128, v129
	v_cvt_pk_bf16_f32 v124, v124, v125
	v_cvt_pk_bf16_f32 v125, v138, v139
	global_store_dwordx4 v[136:137], v[122:125], off
	v_pk_mul_f32 v[120:121], v[120:121], v[192:193] op_sel_hi:[1,0]
	v_pk_mul_f32 v[118:119], v[118:119], v[192:193] op_sel_hi:[1,0]
	v_pk_mul_f32 v[122:123], v[112:113], v[192:193] op_sel_hi:[1,0]
	v_pk_mul_f32 v[112:113], v[110:111], v[192:193] op_sel_hi:[1,0]
	v_cvt_pk_bf16_f32 v110, v118, v119
	v_cvt_pk_bf16_f32 v111, v120, v121
	v_cvt_pk_bf16_f32 v112, v112, v113
	v_cvt_pk_bf16_f32 v113, v122, v123
	global_store_dwordx4 v[136:137], v[110:113], off offset:256
	s_waitcnt lgkmcnt(0)
	v_pk_mul_f32 v[114:115], v[114:115], v[190:191] op_sel_hi:[1,0]
	v_pk_mul_f32 v[104:105], v[104:105], v[190:191] op_sel_hi:[1,0]
	v_or_b32_e32 v110, 16, v131
	v_mul_lo_u32 v112, s67, v110
	v_mad_u64_u32 v[110:111], s[0:1], s66, v110, 0
	v_add3_u32 v111, v111, s31, v112
	v_lshl_add_u64 v[110:111], v[110:111], 1, s[74:75]
	v_pk_mul_f32 v[112:113], v[116:117], v[190:191] op_sel_hi:[1,0]
	v_pk_mul_f32 v[116:117], v[108:109], v[190:191] op_sel_hi:[1,0]
	v_pk_mul_f32 v[108:109], v[106:107], v[190:191] op_sel_hi:[1,0]
	v_lshl_add_u64 v[110:111], v[110:111], 0, v[134:135]
	v_cvt_pk_bf16_f32 v106, v114, v115
	v_cvt_pk_bf16_f32 v107, v112, v113
	v_cvt_pk_bf16_f32 v108, v108, v109
	v_cvt_pk_bf16_f32 v109, v116, v117
	global_store_dwordx4 v[110:111], v[106:109], off
	v_pk_mul_f32 v[102:103], v[102:103], v[190:191] op_sel_hi:[1,0]
	v_pk_mul_f32 v[98:99], v[98:99], v[164:165] op_sel_hi:[1,0]
	v_pk_mul_f32 v[106:107], v[94:95], v[190:191] op_sel_hi:[1,0]
	v_pk_mul_f32 v[94:95], v[92:93], v[190:191] op_sel_hi:[1,0]
	v_cvt_pk_bf16_f32 v92, v102, v103
	v_cvt_pk_bf16_f32 v93, v104, v105
	v_cvt_pk_bf16_f32 v94, v94, v95
	v_cvt_pk_bf16_f32 v95, v106, v107
	global_store_dwordx4 v[110:111], v[92:95], off offset:256
	v_pk_mul_f32 v[86:87], v[86:87], v[164:165] op_sel_hi:[1,0]
	v_pk_mul_f32 v[84:85], v[84:85], v[164:165] op_sel_hi:[1,0]
	v_or_b32_e32 v92, 32, v131
	v_mul_lo_u32 v94, s67, v92
	v_mad_u64_u32 v[92:93], s[0:1], s66, v92, 0
	v_add3_u32 v93, v93, s31, v94
	v_lshl_add_u64 v[92:93], v[92:93], 1, s[74:75]
	v_pk_mul_f32 v[94:95], v[100:101], v[164:165] op_sel_hi:[1,0]
	v_pk_mul_f32 v[100:101], v[90:91], v[164:165] op_sel_hi:[1,0]
	v_pk_mul_f32 v[90:91], v[88:89], v[164:165] op_sel_hi:[1,0]
	v_lshl_add_u64 v[92:93], v[92:93], 0, v[134:135]
	v_cvt_pk_bf16_f32 v88, v98, v99
	v_cvt_pk_bf16_f32 v89, v94, v95
	v_cvt_pk_bf16_f32 v90, v90, v91
	v_cvt_pk_bf16_f32 v91, v100, v101
	global_store_dwordx4 v[92:93], v[88:91], off
	v_pk_mul_f32 v[80:81], v[80:81], v[162:163] op_sel_hi:[1,0]
	v_pk_mul_f32 v[70:71], v[70:71], v[162:163] op_sel_hi:[1,0]
	v_pk_mul_f32 v[88:89], v[78:79], v[164:165] op_sel_hi:[1,0]
	v_pk_mul_f32 v[78:79], v[76:77], v[164:165] op_sel_hi:[1,0]
	v_cvt_pk_bf16_f32 v76, v84, v85
	v_cvt_pk_bf16_f32 v77, v86, v87
	v_cvt_pk_bf16_f32 v78, v78, v79
	v_cvt_pk_bf16_f32 v79, v88, v89
	global_store_dwordx4 v[92:93], v[76:79], off offset:256
	v_pk_mul_f32 v[68:69], v[68:69], v[162:163] op_sel_hi:[1,0]
	v_pk_mul_f32 v[62:63], v[62:63], v[148:149] op_sel_hi:[1,0]
	v_or_b32_e32 v76, 48, v131
	v_mul_lo_u32 v78, s67, v76
	v_mad_u64_u32 v[76:77], s[0:1], s66, v76, 0
	v_add3_u32 v77, v77, s31, v78
	v_lshl_add_u64 v[76:77], v[76:77], 1, s[74:75]
	v_pk_mul_f32 v[78:79], v[82:83], v[162:163] op_sel_hi:[1,0]
	v_pk_mul_f32 v[82:83], v[74:75], v[162:163] op_sel_hi:[1,0]
	v_pk_mul_f32 v[74:75], v[72:73], v[162:163] op_sel_hi:[1,0]
	v_lshl_add_u64 v[76:77], v[76:77], 0, v[134:135]
	v_cvt_pk_bf16_f32 v72, v80, v81
	v_cvt_pk_bf16_f32 v73, v78, v79
	v_cvt_pk_bf16_f32 v74, v74, v75
	v_cvt_pk_bf16_f32 v75, v82, v83
	global_store_dwordx4 v[76:77], v[72:75], off
	v_pk_mul_f32 v[60:61], v[60:61], v[148:149] op_sel_hi:[1,0]
	v_pk_mul_f32 v[54:55], v[54:55], v[148:149] op_sel_hi:[1,0]
	v_pk_mul_f32 v[72:73], v[66:67], v[162:163] op_sel_hi:[1,0]
	v_pk_mul_f32 v[66:67], v[64:65], v[162:163] op_sel_hi:[1,0]
	v_cvt_pk_bf16_f32 v64, v68, v69
; __device__ __forceinline__ unsigned pk_bf16(float lo, float hi) { f32x2e v = {lo, hi}; bf16x2e b = __builtin_convertvector(v, bf16x2e); return __builtin_bit_cast(unsigned, b); }
;     __device__ __forceinline__ void operator()(const f32x4 (&acc)[2][2][4][2], const Unit& u, int wr, int wc, int fr, int fq) const {
;     ...
;             for (int m = 0; m < 4; ++m) { bf16_t* rowp = O + (size_t)(row0 + ai * HALF + m * 16) * ldc + col0;
;                 const float rs = rsa[ai][m];
; #pragma unroll
;                 for (int bj = 0; bj < 2; ++bj) { const f32x4 v0 = acc[ai][bj][m][0] * rs, v1 = acc[ai][bj][m][1] * rs;
;                     u32x4 w; w.x = pk_bf16(v0[0], v0[1]); w.y = pk_bf16(v0[2], v0[3]); w.z = pk_bf16(v1[0], v1[1]); w.w = pk_bf16(v1[2], v1[3]);
;                     *(u32x4*)(rowp + bj * HALF) = w; } }
	v_cvt_pk_bf16_f32 v65, v70, v71
	v_cvt_pk_bf16_f32 v66, v66, v67
	v_cvt_pk_bf16_f32 v67, v72, v73
	global_store_dwordx4 v[76:77], v[64:67], off offset:256
	v_pk_mul_f32 v[52:53], v[52:53], v[148:149] op_sel_hi:[1,0]
	v_pk_mul_f32 v[48:49], v[48:49], v[146:147] op_sel_hi:[1,0]
	v_add_u32_e32 v64, 0x80, v131
	v_ashrrev_i32_e32 v65, 31, v64
	v_mul_lo_u32 v66, s66, v65
	v_mul_lo_u32 v67, s67, v64
	v_mad_u64_u32 v[64:65], s[0:1], s66, v64, 0
	v_add3_u32 v65, v65, v66, v67
	v_lshl_add_u64 v[64:65], v[64:65], 1, s[74:75]
	v_pk_mul_f32 v[66:67], v[58:59], v[148:149] op_sel_hi:[1,0]
	v_pk_mul_f32 v[58:59], v[56:57], v[148:149] op_sel_hi:[1,0]
	v_lshl_add_u64 v[64:65], v[64:65], 0, v[134:135]
	v_cvt_pk_bf16_f32 v56, v60, v61
	v_cvt_pk_bf16_f32 v57, v62, v63
	v_cvt_pk_bf16_f32 v58, v58, v59
	v_cvt_pk_bf16_f32 v59, v66, v67
	global_store_dwordx4 v[64:65], v[56:59], off
	v_pk_mul_f32 v[38:39], v[38:39], v[146:147] op_sel_hi:[1,0]
	v_pk_mul_f32 v[36:37], v[36:37], v[146:147] op_sel_hi:[1,0]
	v_pk_mul_f32 v[56:57], v[46:47], v[148:149] op_sel_hi:[1,0]
	v_pk_mul_f32 v[46:47], v[44:45], v[148:149] op_sel_hi:[1,0]
	v_cvt_pk_bf16_f32 v44, v52, v53
	v_cvt_pk_bf16_f32 v45, v54, v55
	v_cvt_pk_bf16_f32 v46, v46, v47
	v_cvt_pk_bf16_f32 v47, v56, v57
	global_store_dwordx4 v[64:65], v[44:47], off offset:256
	v_pk_mul_f32 v[32:33], v[32:33], v[132:133] op_sel_hi:[1,0]
	v_pk_mul_f32 v[22:23], v[22:23], v[132:133] op_sel_hi:[1,0]
	v_add_u32_e32 v44, 0x90, v131
	v_ashrrev_i32_e32 v45, 31, v44
	v_mul_lo_u32 v46, s66, v45
	v_mul_lo_u32 v47, s67, v44
	v_mad_u64_u32 v[44:45], s[0:1], s66, v44, 0
	v_add3_u32 v45, v45, v46, v47
	v_lshl_add_u64 v[44:45], v[44:45], 1, s[74:75]
	v_pk_mul_f32 v[46:47], v[50:51], v[146:147] op_sel_hi:[1,0]
	v_pk_mul_f32 v[50:51], v[42:43], v[146:147] op_sel_hi:[1,0]
	v_pk_mul_f32 v[42:43], v[40:41], v[146:147] op_sel_hi:[1,0]
	v_lshl_add_u64 v[44:45], v[44:45], 0, v[134:135]
	v_cvt_pk_bf16_f32 v40, v48, v49
	v_cvt_pk_bf16_f32 v41, v46, v47
	v_cvt_pk_bf16_f32 v42, v42, v43
	v_cvt_pk_bf16_f32 v43, v50, v51
	global_store_dwordx4 v[44:45], v[40:43], off
	v_pk_mul_f32 v[20:21], v[20:21], v[132:133] op_sel_hi:[1,0]
	v_pk_mul_f32 v[16:17], v[16:17], v[130:131] op_sel_hi:[1,0]
	v_pk_mul_f32 v[40:41], v[30:31], v[146:147] op_sel_hi:[1,0]
	v_pk_mul_f32 v[30:31], v[28:29], v[146:147] op_sel_hi:[1,0]
	v_cvt_pk_bf16_f32 v28, v36, v37
	v_cvt_pk_bf16_f32 v29, v38, v39
	v_cvt_pk_bf16_f32 v30, v30, v31
	v_cvt_pk_bf16_f32 v31, v40, v41
	global_store_dwordx4 v[44:45], v[28:31], off offset:256
	v_pk_mul_f32 v[6:7], v[6:7], v[130:131] op_sel_hi:[1,0]
	v_pk_mul_f32 v[4:5], v[4:5], v[130:131] op_sel_hi:[1,0]
	v_add_u32_e32 v28, 0xa0, v131
	v_ashrrev_i32_e32 v29, 31, v28
	v_mul_lo_u32 v30, s66, v29
	v_mul_lo_u32 v31, s67, v28
	v_mad_u64_u32 v[28:29], s[0:1], s66, v28, 0
	v_add3_u32 v29, v29, v30, v31
	v_lshl_add_u64 v[28:29], v[28:29], 1, s[74:75]
	v_pk_mul_f32 v[30:31], v[34:35], v[132:133] op_sel_hi:[1,0]
	v_pk_mul_f32 v[34:35], v[26:27], v[132:133] op_sel_hi:[1,0]
	v_pk_mul_f32 v[26:27], v[24:25], v[132:133] op_sel_hi:[1,0]
	v_lshl_add_u64 v[28:29], v[28:29], 0, v[134:135]
	v_cvt_pk_bf16_f32 v24, v32, v33
	v_cvt_pk_bf16_f32 v25, v30, v31
	v_cvt_pk_bf16_f32 v26, v26, v27
	v_cvt_pk_bf16_f32 v27, v34, v35
	global_store_dwordx4 v[28:29], v[24:27], off
	s_and_b64 vcc, exec, s[38:39]
	s_nop 0
	v_pk_mul_f32 v[24:25], v[14:15], v[132:133] op_sel_hi:[1,0]
	v_pk_mul_f32 v[14:15], v[12:13], v[132:133] op_sel_hi:[1,0]
	v_cvt_pk_bf16_f32 v12, v20, v21
	v_cvt_pk_bf16_f32 v13, v22, v23
	v_cvt_pk_bf16_f32 v14, v14, v15
	v_cvt_pk_bf16_f32 v15, v24, v25
	global_store_dwordx4 v[28:29], v[12:15], off offset:256
	s_nop 1
	v_add_u32_e32 v12, 0xb0, v131
	v_ashrrev_i32_e32 v13, 31, v12
	v_mul_lo_u32 v14, s66, v13
	v_mul_lo_u32 v15, s67, v12
	v_mad_u64_u32 v[12:13], s[0:1], s66, v12, 0
	v_add3_u32 v13, v13, v14, v15
	v_lshl_add_u64 v[12:13], v[12:13], 1, s[74:75]
	v_pk_mul_f32 v[14:15], v[18:19], v[130:131] op_sel_hi:[1,0]
	v_pk_mul_f32 v[18:19], v[10:11], v[130:131] op_sel_hi:[1,0]
	v_pk_mul_f32 v[10:11], v[8:9], v[130:131] op_sel_hi:[1,0]
	v_lshl_add_u64 v[12:13], v[12:13], 0, v[134:135]
	v_cvt_pk_bf16_f32 v8, v16, v17
	v_cvt_pk_bf16_f32 v9, v14, v15
	v_cvt_pk_bf16_f32 v10, v10, v11
	v_cvt_pk_bf16_f32 v11, v18, v19
	global_store_dwordx4 v[12:13], v[8:11], off
	s_mov_b64 s[0:1], -1
	s_nop 0
	v_pk_mul_f32 v[8:9], v[2:3], v[130:131] op_sel_hi:[1,0]
	v_pk_mul_f32 v[2:3], v[0:1], v[130:131] op_sel_hi:[1,0]
	v_cvt_pk_bf16_f32 v0, v4, v5
	v_cvt_pk_bf16_f32 v1, v6, v7
	v_cvt_pk_bf16_f32 v2, v2, v3
	v_cvt_pk_bf16_f32 v3, v8, v9
	global_store_dwordx4 v[12:13], v[0:3], off offset:256
	s_cbranch_vccnz .LBB0_502
	s_andn2_b64 vcc, exec, s[80:81]
	s_cbranch_vccnz .LBB0_501
	s_barrier
	s_branch .LBB0_501
